# GEMM K-loops: redundant mid-segment setprio 0/1 pair and already-satisfied lgkmcnt(0) wait removed from every 32-MFMA segment (on v17)
# speedup vs baseline: 1.0078x; 1.0078x over previous
; #define PG8_STAGE(bufoff, gbase, voff) do { _Pragma("unroll") for (int _i = 0; _i < 2; ++_i) \
;         __builtin_amdgcn_global_load_lds((const unsigned*)((const char*)(gbase) + (voff)[_i]), (LAS unsigned*)(lds + (bufoff) + ldsw + _i * 8192), 16, 0, 0); } while (0)
; #define PG8_LDA(dst, b, h) do { _Pragma("unroll") for (int m = 0; m < 4; ++m) _Pragma("unroll") for (int k = 0; k < 2; ++k) dst[m][k] = *(const LAS bf16x8*)(lds + PG8_SA(b, h) + aoff + m * 2048 + k * 1024); } while (0)
; #define PG8_LDB(dst, b, h) do { _Pragma("unroll") for (int n = 0; n < 2; ++n) _Pragma("unroll") for (int k = 0; k < 2; ++k) dst[n][k] = *(const LAS bf16x8*)(lds + PG8_SB(b, h) + boff + n * 2048 + k * 1024); } while (0)
; #define PG8_MMA(ai, bj, At, Bt) do { __builtin_amdgcn_s_setprio(1); _Pragma("unroll") for (int m = 0; m < 4; ++m) _Pragma("unroll") for (int n = 0; n < 2; ++n) _Pragma("unroll") for (int k = 0; k < 2; ++k) \
;         acc[ai][bj][m][n] = __builtin_amdgcn_mfma_f32_16x16x32_bf16(Bt[n][k], At[m][k], acc[ai][bj][m][n], 0, 0, 0); __builtin_amdgcn_s_setprio(0); } while (0)
; template <class Epi>
; DI void gemm_phase(LAS unsigned char* lds, const int wid, const Gemm g, const Order& S, const Epi& E) {
;     ...
;         const bool has_next = S.next(ui + 1, nxt);
;         const char* nA = has_next ? (const char*)(g.A + (size_t)nxt.g * g.gsA + (size_t)nxt.pm * BM * g.lda) : cA;
;         const char* nB = has_next ? (const char*)(g.Bt + (size_t)nxt.g * g.gsB + (size_t)nxt.pn * BM * g.ldb) : cB;
;         for (int t = 0; t < nt; t += 2) {
;             const bool last = (t == nt - 2);
;             const char* a1 = cA + (size_t)(t + 1) * kstep;
;             const char* a2 = last ? nA : cA + (size_t)(t + 2) * kstep; const char* b2 = last ? nB : cB + (size_t)(t + 2) * kstep;
;             const char* a3 = a2 + kstep; const char* b3 = b2 + kstep;
;             PG8_LDB(B0, 0, 0); PG8_LDB(B1, 0, 1); PG8_SCHED; PG8_LDA(At, 0, 0); PG8_STAGE(PG8_SA(1, 1), a1 + hstepA, voffA);
;             PG8_WAIT_V(8); PG8_WAIT_L(0); PG8_BAR; PG8_MMA(0, 0, At, B0); PG8_MMA(0, 1, At, B1); PG8_BAR; PG8_SCHED;
;             PG8_LDA(At, 0, 1); PG8_STAGE(PG8_SB(0, 0), b2, voffB); PG8_STAGE(PG8_SB(0, 1), b2 + hstepB, voffB); PG8_STAGE(PG8_SA(0, 0), a2, voffA);
;             PG8_WAIT_V(8); PG8_WAIT_L(0); PG8_BAR; PG8_MMA(1, 0, At, B0); PG8_MMA(1, 1, At, B1); PG8_BAR; PG8_SCHED;
.LBB0_227:
	s_ashr_i32 s31, s30, 31
	s_lshl_b64 s[36:37], s[30:31], 19
	s_add_u32 s36, s21, s36
	s_addc_u32 s37, s25, s37
	s_and_b64 s[38:39], s[6:7], exec
	s_cselect_b32 s31, s37, s43
	s_cselect_b32 s59, s36, s42
	s_ashr_i32 s35, s34, 31
	s_lshl_b64 s[38:39], s[34:35], 19
	s_add_u32 s38, s8, s38
	s_addc_u32 s39, s9, s39
	s_and_b64 s[46:47], s[6:7], exec
	s_cselect_b32 s35, s39, s45
	s_cselect_b32 s60, s38, s44
	s_add_u32 s42, s42, 0x40080
	s_addc_u32 s43, s43, 0
	s_add_u32 s61, s44, 0x100
	v_mov_b32_e32 v0, 0
	s_addc_u32 s62, s45, 0
	s_mov_b32 s63, -2
	ds_read_b128 v[164:167], v151
	ds_read_b128 v[168:171], v151 offset:1024
	ds_read_b128 v[172:175], v151 offset:2048
	ds_read_b128 v[176:179], v151 offset:3072
	ds_read_b128 v[180:183], v155
	ds_read_b128 v[184:187], v155 offset:1024
	ds_read_b128 v[188:191], v155 offset:2048
	ds_read_b128 v[192:195], v155 offset:3072
	s_add_u32 s44, s42, 0xfffc0080
	s_addc_u32 s45, s43, -1
	s_cmp_eq_u32 s63, 12
	s_cselect_b32 s47, s31, s45
	s_cselect_b32 s46, s59, s44
	s_cselect_b32 s45, s35, s62
	s_cselect_b32 s44, s60, s61
	v_lshl_add_u64 v[144:145], s[42:43], 0, v[136:137]
	s_add_i32 m0, s27, 0xc000
	ds_read_b128 v[196:199], v159
	ds_read_b128 v[200:203], v159 offset:1024
	ds_read_b128 v[204:207], v159 offset:2048
	ds_read_b128 v[208:211], v159 offset:3072
	ds_read_b128 v[216:219], v159 offset:4096
	ds_read_b128 v[220:223], v159 offset:5120
	ds_read_b128 v[224:227], v159 offset:6144
	ds_read_b128 v[228:231], v159 offset:7168
	global_load_lds_dwordx4 v[144:145], off
	v_lshl_add_u64 v[144:145], s[42:43], 0, v[138:139]
	s_add_i32 m0, s27, 0xe000
	s_nop 0
	global_load_lds_dwordx4 v[144:145], off
	s_waitcnt vmcnt(8)
	s_waitcnt lgkmcnt(0)
	s_barrier
	s_setprio 1
	v_mfma_f32_16x16x32_bf16 v[124:127], v[164:167], v[196:199], 0
	v_mfma_f32_16x16x32_bf16 v[120:123], v[172:175], v[196:199], 0
	v_mfma_f32_16x16x32_bf16 v[108:111], v[164:167], v[204:207], 0
	v_mfma_f32_16x16x32_bf16 v[104:107], v[172:175], v[204:207], 0
	v_mfma_f32_16x16x32_bf16 v[92:95], v[164:167], v[216:219], 0
	v_mfma_f32_16x16x32_bf16 v[88:91], v[172:175], v[216:219], 0
	v_mfma_f32_16x16x32_bf16 v[76:79], v[164:167], v[224:227], 0
	v_mfma_f32_16x16x32_bf16 v[72:75], v[172:175], v[224:227], 0
	v_mfma_f32_16x16x32_bf16 v[124:127], v[168:171], v[200:203], v[124:127]
	v_mfma_f32_16x16x32_bf16 v[120:123], v[176:179], v[200:203], v[120:123]
	v_mfma_f32_16x16x32_bf16 v[108:111], v[168:171], v[208:211], v[108:111]
	v_mfma_f32_16x16x32_bf16 v[104:107], v[176:179], v[208:211], v[104:107]
	v_mfma_f32_16x16x32_bf16 v[92:95], v[168:171], v[220:223], v[92:95]
	v_mfma_f32_16x16x32_bf16 v[88:91], v[176:179], v[220:223], v[88:91]
	v_mfma_f32_16x16x32_bf16 v[76:79], v[168:171], v[228:231], v[76:79]
	v_mfma_f32_16x16x32_bf16 v[72:75], v[176:179], v[228:231], v[72:75]
	v_mfma_f32_16x16x32_bf16 v[116:119], v[180:183], v[196:199], 0
	v_mfma_f32_16x16x32_bf16 v[112:115], v[188:191], v[196:199], 0
	v_mfma_f32_16x16x32_bf16 v[100:103], v[180:183], v[204:207], 0
	v_mfma_f32_16x16x32_bf16 v[96:99], v[188:191], v[204:207], 0
	v_mfma_f32_16x16x32_bf16 v[84:87], v[180:183], v[216:219], 0
	v_mfma_f32_16x16x32_bf16 v[80:83], v[188:191], v[216:219], 0
	v_mfma_f32_16x16x32_bf16 v[68:71], v[180:183], v[224:227], 0
	v_mfma_f32_16x16x32_bf16 v[64:67], v[188:191], v[224:227], 0
	v_mfma_f32_16x16x32_bf16 v[116:119], v[184:187], v[200:203], v[116:119]
	v_mfma_f32_16x16x32_bf16 v[112:115], v[192:195], v[200:203], v[112:115]
	v_mfma_f32_16x16x32_bf16 v[100:103], v[184:187], v[208:211], v[100:103]
	v_mfma_f32_16x16x32_bf16 v[96:99], v[192:195], v[208:211], v[96:99]
	v_mfma_f32_16x16x32_bf16 v[84:87], v[184:187], v[220:223], v[84:87]
	v_mfma_f32_16x16x32_bf16 v[80:83], v[192:195], v[220:223], v[80:83]
	v_mfma_f32_16x16x32_bf16 v[68:71], v[184:187], v[228:231], v[68:71]
	v_mfma_f32_16x16x32_bf16 v[64:67], v[192:195], v[228:231], v[64:67]
	s_setprio 0
	s_barrier
	s_add_i32 s64, s56, s94
	v_lshl_add_u64 v[144:145], s[44:45], 0, v[132:133]
	s_mov_b32 m0, s64
	ds_read_b128 v[196:199], v159 offset:16384
	ds_read_b128 v[200:203], v159 offset:17408
	ds_read_b128 v[204:207], v159 offset:18432
	ds_read_b128 v[208:211], v159 offset:19456
	ds_read_b128 v[216:219], v159 offset:20480
	ds_read_b128 v[220:223], v159 offset:21504
	ds_read_b128 v[224:227], v159 offset:22528
	ds_read_b128 v[228:231], v159 offset:23552
	global_load_lds_dwordx4 v[144:145], off
	s_add_i32 m0, s64, 0x2000
	s_add_u32 s64, s44, 0x40000
	v_lshl_add_u64 v[148:149], s[44:45], 0, v[128:129]
	s_addc_u32 s65, s45, 0
	s_add_i32 s66, s57, s94
	global_load_lds_dwordx4 v[148:149], off
	v_lshl_add_u64 v[152:153], s[64:65], 0, v[132:133]
	s_mov_b32 m0, s66
	v_lshl_add_u64 v[156:157], s[46:47], 0, v[130:131]
	global_load_lds_dwordx4 v[152:153], off
	v_lshl_add_u64 v[152:153], s[64:65], 0, v[128:129]
	s_add_i32 m0, s66, 0x2000
	s_nop 0
	global_load_lds_dwordx4 v[152:153], off
	v_lshl_add_u64 v[152:153], s[46:47], 0, v[134:135]
	s_mov_b32 m0, s27
	s_nop 0
	global_load_lds_dwordx4 v[152:153], off
	s_mov_b32 m0, s41
	s_nop 0
	global_load_lds_dwordx4 v[156:157], off
	s_waitcnt vmcnt(8)
	s_waitcnt lgkmcnt(0)
	s_barrier
; #define PG8_STAGE(bufoff, gbase, voff) do { _Pragma("unroll") for (int _i = 0; _i < 2; ++_i) \
;         __builtin_amdgcn_global_load_lds((const unsigned*)((const char*)(gbase) + (voff)[_i]), (LAS unsigned*)(lds + (bufoff) + ldsw + _i * 8192), 16, 0, 0); } while (0)
; #define PG8_LDA(dst, b, h) do { _Pragma("unroll") for (int m = 0; m < 4; ++m) _Pragma("unroll") for (int k = 0; k < 2; ++k) dst[m][k] = *(const LAS bf16x8*)(lds + PG8_SA(b, h) + aoff + m * 2048 + k * 1024); } while (0)
; #define PG8_LDB(dst, b, h) do { _Pragma("unroll") for (int n = 0; n < 2; ++n) _Pragma("unroll") for (int k = 0; k < 2; ++k) dst[n][k] = *(const LAS bf16x8*)(lds + PG8_SB(b, h) + boff + n * 2048 + k * 1024); } while (0)
; #define PG8_MMA(ai, bj, At, Bt) do { __builtin_amdgcn_s_setprio(1); _Pragma("unroll") for (int m = 0; m < 4; ++m) _Pragma("unroll") for (int n = 0; n < 2; ++n) _Pragma("unroll") for (int k = 0; k < 2; ++k) \
;         acc[ai][bj][m][n] = __builtin_amdgcn_mfma_f32_16x16x32_bf16(Bt[n][k], At[m][k], acc[ai][bj][m][n], 0, 0, 0); __builtin_amdgcn_s_setprio(0); } while (0)
; #define PG8_WAIT_V(n) asm volatile("s_waitcnt vmcnt(" #n ")" ::: "memory")
; #define PG8_WAIT_L(n) asm volatile("s_waitcnt lgkmcnt(" #n ")" ::: "memory")
; #define PG8_BAR __builtin_amdgcn_s_barrier()
; #define PG8_SCHED __builtin_amdgcn_sched_barrier(0)
; template <class Epi>
; DI void gemm_phase(LAS unsigned char* lds, const int wid, const Gemm g, const Order& S, const Epi& E) {
;     ...
;             PG8_WAIT_V(8); PG8_WAIT_L(0); PG8_BAR; PG8_MMA(0, 0, At, B0); PG8_MMA(0, 1, At, B1); PG8_BAR; PG8_SCHED;
;             PG8_LDA(At, 0, 1); PG8_STAGE(PG8_SB(0, 0), b2, voffB); PG8_STAGE(PG8_SB(0, 1), b2 + hstepB, voffB); PG8_STAGE(PG8_SA(0, 0), a2, voffA);
;             PG8_WAIT_V(8); PG8_WAIT_L(0); PG8_BAR; PG8_MMA(1, 0, At, B0); PG8_MMA(1, 1, At, B1); PG8_BAR; PG8_SCHED;
;             PG8_LDB(B0, 1, 0); PG8_LDB(B1, 1, 1); PG8_SCHED; PG8_LDA(At, 1, 0); PG8_STAGE(PG8_SA(0, 1), a2 + hstepA, voffA);
;             PG8_WAIT_V(8); PG8_WAIT_L(0); PG8_BAR; PG8_MMA(0, 0, At, B0); PG8_MMA(0, 1, At, B1); PG8_BAR; PG8_SCHED;
	s_setprio 1
	v_mfma_f32_16x16x32_bf16 v[60:63], v[164:167], v[196:199], 0
	v_mfma_f32_16x16x32_bf16 v[56:59], v[172:175], v[196:199], 0
	v_mfma_f32_16x16x32_bf16 v[44:47], v[164:167], v[204:207], 0
	v_mfma_f32_16x16x32_bf16 v[40:43], v[172:175], v[204:207], 0
	v_mfma_f32_16x16x32_bf16 v[28:31], v[164:167], v[216:219], 0
	v_mfma_f32_16x16x32_bf16 v[24:27], v[172:175], v[216:219], 0
	v_mfma_f32_16x16x32_bf16 v[12:15], v[164:167], v[224:227], 0
	v_mfma_f32_16x16x32_bf16 v[8:11], v[172:175], v[224:227], 0
	v_mfma_f32_16x16x32_bf16 v[60:63], v[168:171], v[200:203], v[60:63]
	v_mfma_f32_16x16x32_bf16 v[56:59], v[176:179], v[200:203], v[56:59]
	v_mfma_f32_16x16x32_bf16 v[44:47], v[168:171], v[208:211], v[44:47]
	v_mfma_f32_16x16x32_bf16 v[40:43], v[176:179], v[208:211], v[40:43]
	v_mfma_f32_16x16x32_bf16 v[28:31], v[168:171], v[220:223], v[28:31]
	v_mfma_f32_16x16x32_bf16 v[24:27], v[176:179], v[220:223], v[24:27]
	v_mfma_f32_16x16x32_bf16 v[12:15], v[168:171], v[228:231], v[12:15]
	v_mfma_f32_16x16x32_bf16 v[8:11], v[176:179], v[228:231], v[8:11]
	v_mfma_f32_16x16x32_bf16 v[52:55], v[180:183], v[196:199], 0
	v_mfma_f32_16x16x32_bf16 v[48:51], v[188:191], v[196:199], 0
	v_mfma_f32_16x16x32_bf16 v[36:39], v[180:183], v[204:207], 0
	v_mfma_f32_16x16x32_bf16 v[32:35], v[188:191], v[204:207], 0
	v_mfma_f32_16x16x32_bf16 v[20:23], v[180:183], v[216:219], 0
	v_mfma_f32_16x16x32_bf16 v[16:19], v[188:191], v[216:219], 0
	v_mfma_f32_16x16x32_bf16 v[4:7], v[180:183], v[224:227], 0
	v_mfma_f32_16x16x32_bf16 v[0:3], v[188:191], v[224:227], 0
	v_mfma_f32_16x16x32_bf16 v[52:55], v[184:187], v[200:203], v[52:55]
	v_mfma_f32_16x16x32_bf16 v[48:51], v[192:195], v[200:203], v[48:51]
	v_mfma_f32_16x16x32_bf16 v[36:39], v[184:187], v[208:211], v[36:39]
	v_mfma_f32_16x16x32_bf16 v[32:35], v[192:195], v[208:211], v[32:35]
	v_mfma_f32_16x16x32_bf16 v[20:23], v[184:187], v[220:223], v[20:23]
	v_mfma_f32_16x16x32_bf16 v[16:19], v[192:195], v[220:223], v[16:19]
	v_mfma_f32_16x16x32_bf16 v[4:7], v[184:187], v[228:231], v[4:7]
	v_mfma_f32_16x16x32_bf16 v[0:3], v[192:195], v[228:231], v[0:3]
	s_setprio 0
	s_barrier
	s_add_i32 s64, 0, 0x18000
	v_add_u32_e32 v146, s64, v147
	s_add_i32 s65, 0, 0x1c000
	ds_read_b128 v[164:167], v146
	ds_read_b128 v[168:171], v146 offset:1024
	ds_read_b128 v[172:175], v146 offset:2048
	ds_read_b128 v[176:179], v146 offset:3072
	v_add_u32_e32 v146, s65, v147
	ds_read_b128 v[180:183], v146
	ds_read_b128 v[184:187], v146 offset:1024
	ds_read_b128 v[188:191], v146 offset:2048
	ds_read_b128 v[192:195], v146 offset:3072
	s_add_u32 s46, s46, 0x40000
	s_addc_u32 s47, s47, 0
	s_mov_b32 m0, s48
	v_lshl_add_u64 v[160:161], s[46:47], 0, v[134:135]
	ds_read_b128 v[196:199], v159 offset:32768
	ds_read_b128 v[200:203], v159 offset:33792
	ds_read_b128 v[204:207], v159 offset:34816
	ds_read_b128 v[208:211], v159 offset:35840
	ds_read_b128 v[216:219], v159 offset:36864
	ds_read_b128 v[220:223], v159 offset:37888
	ds_read_b128 v[224:227], v159 offset:38912
	ds_read_b128 v[228:231], v159 offset:39936
	global_load_lds_dwordx4 v[160:161], off
	v_lshl_add_u64 v[160:161], s[46:47], 0, v[130:131]
	s_mov_b32 m0, s49
	s_nop 0
	global_load_lds_dwordx4 v[160:161], off
	s_waitcnt vmcnt(8)
	s_waitcnt lgkmcnt(0)
	s_barrier
	s_setprio 1
	v_mfma_f32_16x16x32_bf16 v[124:127], v[164:167], v[196:199], v[124:127]
	v_mfma_f32_16x16x32_bf16 v[120:123], v[172:175], v[196:199], v[120:123]
	v_mfma_f32_16x16x32_bf16 v[108:111], v[164:167], v[204:207], v[108:111]
	v_mfma_f32_16x16x32_bf16 v[104:107], v[172:175], v[204:207], v[104:107]
	v_mfma_f32_16x16x32_bf16 v[92:95], v[164:167], v[216:219], v[92:95]
	v_mfma_f32_16x16x32_bf16 v[88:91], v[172:175], v[216:219], v[88:91]
	v_mfma_f32_16x16x32_bf16 v[76:79], v[164:167], v[224:227], v[76:79]
	v_mfma_f32_16x16x32_bf16 v[72:75], v[172:175], v[224:227], v[72:75]
	v_mfma_f32_16x16x32_bf16 v[124:127], v[168:171], v[200:203], v[124:127]
	v_mfma_f32_16x16x32_bf16 v[120:123], v[176:179], v[200:203], v[120:123]
	v_mfma_f32_16x16x32_bf16 v[108:111], v[168:171], v[208:211], v[108:111]
	v_mfma_f32_16x16x32_bf16 v[104:107], v[176:179], v[208:211], v[104:107]
	v_mfma_f32_16x16x32_bf16 v[92:95], v[168:171], v[220:223], v[92:95]
	v_mfma_f32_16x16x32_bf16 v[88:91], v[176:179], v[220:223], v[88:91]
	v_mfma_f32_16x16x32_bf16 v[76:79], v[168:171], v[228:231], v[76:79]
	v_mfma_f32_16x16x32_bf16 v[72:75], v[176:179], v[228:231], v[72:75]
	v_mfma_f32_16x16x32_bf16 v[116:119], v[180:183], v[196:199], v[116:119]
	v_mfma_f32_16x16x32_bf16 v[112:115], v[188:191], v[196:199], v[112:115]
	v_mfma_f32_16x16x32_bf16 v[100:103], v[180:183], v[204:207], v[100:103]
	v_mfma_f32_16x16x32_bf16 v[96:99], v[188:191], v[204:207], v[96:99]
	v_mfma_f32_16x16x32_bf16 v[84:87], v[180:183], v[216:219], v[84:87]
	v_mfma_f32_16x16x32_bf16 v[80:83], v[188:191], v[216:219], v[80:83]
	v_mfma_f32_16x16x32_bf16 v[68:71], v[180:183], v[224:227], v[68:71]
	v_mfma_f32_16x16x32_bf16 v[64:67], v[188:191], v[224:227], v[64:67]
	v_mfma_f32_16x16x32_bf16 v[116:119], v[184:187], v[200:203], v[116:119]
	v_mfma_f32_16x16x32_bf16 v[112:115], v[192:195], v[200:203], v[112:115]
	v_mfma_f32_16x16x32_bf16 v[100:103], v[184:187], v[208:211], v[100:103]
	v_mfma_f32_16x16x32_bf16 v[96:99], v[192:195], v[208:211], v[96:99]
	v_mfma_f32_16x16x32_bf16 v[84:87], v[184:187], v[220:223], v[84:87]
	v_mfma_f32_16x16x32_bf16 v[80:83], v[192:195], v[220:223], v[80:83]
	v_mfma_f32_16x16x32_bf16 v[68:71], v[184:187], v[228:231], v[68:71]
	v_mfma_f32_16x16x32_bf16 v[64:67], v[192:195], v[228:231], v[64:67]
	s_setprio 0
	s_barrier
; #define PG8_STAGE(bufoff, gbase, voff) do { _Pragma("unroll") for (int _i = 0; _i < 2; ++_i) \
;         __builtin_amdgcn_global_load_lds((const unsigned*)((const char*)(gbase) + (voff)[_i]), (LAS unsigned*)(lds + (bufoff) + ldsw + _i * 8192), 16, 0, 0); } while (0)
; #define PG8_LDA(dst, b, h) do { _Pragma("unroll") for (int m = 0; m < 4; ++m) _Pragma("unroll") for (int k = 0; k < 2; ++k) dst[m][k] = *(const LAS bf16x8*)(lds + PG8_SA(b, h) + aoff + m * 2048 + k * 1024); } while (0)
; #define PG8_LDB(dst, b, h) do { _Pragma("unroll") for (int n = 0; n < 2; ++n) _Pragma("unroll") for (int k = 0; k < 2; ++k) dst[n][k] = *(const LAS bf16x8*)(lds + PG8_SB(b, h) + boff + n * 2048 + k * 1024); } while (0)
; #define PG8_MMA(ai, bj, At, Bt) do { __builtin_amdgcn_s_setprio(1); _Pragma("unroll") for (int m = 0; m < 4; ++m) _Pragma("unroll") for (int n = 0; n < 2; ++n) _Pragma("unroll") for (int k = 0; k < 2; ++k) \
;         acc[ai][bj][m][n] = __builtin_amdgcn_mfma_f32_16x16x32_bf16(Bt[n][k], At[m][k], acc[ai][bj][m][n], 0, 0, 0); __builtin_amdgcn_s_setprio(0); } while (0)
; #define PG8_WAIT_V(n) asm volatile("s_waitcnt vmcnt(" #n ")" ::: "memory")
; #define PG8_WAIT_L(n) asm volatile("s_waitcnt lgkmcnt(" #n ")" ::: "memory")
; template <class Epi>
; DI void gemm_phase(LAS unsigned char* lds, const int wid, const Gemm g, const Order& S, const Epi& E) {
;     ...
;             PG8_LDB(B0, 0, 0); PG8_LDB(B1, 0, 1); PG8_SCHED; PG8_LDA(At, 0, 0); PG8_STAGE(PG8_SA(1, 1), a1 + hstepA, voffA);
;             PG8_WAIT_V(8); PG8_WAIT_L(0); PG8_BAR; PG8_MMA(0, 0, At, B0); PG8_MMA(0, 1, At, B1); PG8_BAR; PG8_SCHED;
;             PG8_LDA(At, 0, 1); PG8_STAGE(PG8_SB(0, 0), b2, voffB); PG8_STAGE(PG8_SB(0, 1), b2 + hstepB, voffB); PG8_STAGE(PG8_SA(0, 0), a2, voffA);
;             PG8_WAIT_V(8); PG8_WAIT_L(0); PG8_BAR; PG8_MMA(1, 0, At, B0); PG8_MMA(1, 1, At, B1); PG8_BAR; PG8_SCHED;
;             PG8_LDB(B0, 1, 0); PG8_LDB(B1, 1, 1); PG8_SCHED; PG8_LDA(At, 1, 0); PG8_STAGE(PG8_SA(0, 1), a2 + hstepA, voffA);
;             PG8_WAIT_V(8); PG8_WAIT_L(0); PG8_BAR; PG8_MMA(0, 0, At, B0); PG8_MMA(0, 1, At, B1); PG8_BAR; PG8_SCHED;
;             PG8_LDA(At, 1, 1); PG8_STAGE(PG8_SB(1, 0), b3, voffB); PG8_STAGE(PG8_SB(1, 1), b3 + hstepB, voffB); PG8_STAGE(PG8_SA(1, 0), a3, voffA);
;             PG8_WAIT_V(8); PG8_WAIT_L(0); PG8_BAR; PG8_MMA(1, 0, At, B0); PG8_MMA(1, 1, At, B1); PG8_BAR; PG8_SCHED;
	s_add_i32 s46, s64, s94
	v_lshl_add_u64 v[144:145], v[144:145], 0, s[16:17]
	s_mov_b32 m0, s46
	ds_read_b128 v[196:199], v159 offset:49152
	ds_read_b128 v[200:203], v159 offset:50176
	ds_read_b128 v[204:207], v159 offset:51200
	ds_read_b128 v[208:211], v159 offset:52224
	ds_read_b128 v[216:219], v159 offset:53248
	ds_read_b128 v[220:223], v159 offset:54272
	ds_read_b128 v[224:227], v159 offset:55296
	ds_read_b128 v[228:231], v159 offset:56320
	global_load_lds_dwordx4 v[144:145], off
	s_add_i32 m0, s46, 0x2000
	s_add_u32 s44, s44, 0x40080
	v_lshl_add_u64 v[144:145], v[148:149], 0, s[16:17]
	s_addc_u32 s45, s45, 0
	s_add_i32 s46, s65, s94
	global_load_lds_dwordx4 v[144:145], off
	v_lshl_add_u64 v[144:145], s[44:45], 0, v[132:133]
	s_mov_b32 m0, s46
	s_nop 0
	global_load_lds_dwordx4 v[144:145], off
	v_lshl_add_u64 v[144:145], s[44:45], 0, v[128:129]
	s_add_i32 m0, s46, 0x2000
	s_nop 0
	global_load_lds_dwordx4 v[144:145], off
	v_lshl_add_u64 v[144:145], v[152:153], 0, s[16:17]
	s_mov_b32 m0, s51
	s_nop 0
	global_load_lds_dwordx4 v[144:145], off
	v_lshl_add_u64 v[144:145], v[156:157], 0, s[16:17]
	s_mov_b32 m0, s52
	s_nop 0
	global_load_lds_dwordx4 v[144:145], off
	s_waitcnt vmcnt(8)
	s_waitcnt lgkmcnt(0)
	s_barrier
	s_setprio 1
	v_mfma_f32_16x16x32_bf16 v[60:63], v[164:167], v[196:199], v[60:63]
	v_mfma_f32_16x16x32_bf16 v[56:59], v[172:175], v[196:199], v[56:59]
	v_mfma_f32_16x16x32_bf16 v[44:47], v[164:167], v[204:207], v[44:47]
	v_mfma_f32_16x16x32_bf16 v[40:43], v[172:175], v[204:207], v[40:43]
	v_mfma_f32_16x16x32_bf16 v[28:31], v[164:167], v[216:219], v[28:31]
	v_mfma_f32_16x16x32_bf16 v[24:27], v[172:175], v[216:219], v[24:27]
	v_mfma_f32_16x16x32_bf16 v[12:15], v[164:167], v[224:227], v[12:15]
	v_mfma_f32_16x16x32_bf16 v[8:11], v[172:175], v[224:227], v[8:11]
	v_mfma_f32_16x16x32_bf16 v[60:63], v[168:171], v[200:203], v[60:63]
	v_mfma_f32_16x16x32_bf16 v[56:59], v[176:179], v[200:203], v[56:59]
	v_mfma_f32_16x16x32_bf16 v[44:47], v[168:171], v[208:211], v[44:47]
	v_mfma_f32_16x16x32_bf16 v[40:43], v[176:179], v[208:211], v[40:43]
	v_mfma_f32_16x16x32_bf16 v[28:31], v[168:171], v[220:223], v[28:31]
	v_mfma_f32_16x16x32_bf16 v[24:27], v[176:179], v[220:223], v[24:27]
	v_mfma_f32_16x16x32_bf16 v[12:15], v[168:171], v[228:231], v[12:15]
	v_mfma_f32_16x16x32_bf16 v[8:11], v[176:179], v[228:231], v[8:11]
	v_mfma_f32_16x16x32_bf16 v[52:55], v[180:183], v[196:199], v[52:55]
	v_mfma_f32_16x16x32_bf16 v[48:51], v[188:191], v[196:199], v[48:51]
	v_mfma_f32_16x16x32_bf16 v[36:39], v[180:183], v[204:207], v[36:39]
	v_mfma_f32_16x16x32_bf16 v[32:35], v[188:191], v[204:207], v[32:35]
	v_mfma_f32_16x16x32_bf16 v[20:23], v[180:183], v[216:219], v[20:23]
	v_mfma_f32_16x16x32_bf16 v[16:19], v[188:191], v[216:219], v[16:19]
	v_mfma_f32_16x16x32_bf16 v[4:7], v[180:183], v[224:227], v[4:7]
	v_mfma_f32_16x16x32_bf16 v[0:3], v[188:191], v[224:227], v[0:3]
	v_mfma_f32_16x16x32_bf16 v[52:55], v[184:187], v[200:203], v[52:55]
	v_mfma_f32_16x16x32_bf16 v[48:51], v[192:195], v[200:203], v[48:51]
	v_mfma_f32_16x16x32_bf16 v[36:39], v[184:187], v[208:211], v[36:39]
	v_mfma_f32_16x16x32_bf16 v[32:35], v[192:195], v[208:211], v[32:35]
	v_mfma_f32_16x16x32_bf16 v[20:23], v[184:187], v[220:223], v[20:23]
	v_mfma_f32_16x16x32_bf16 v[16:19], v[192:195], v[220:223], v[16:19]
	v_mfma_f32_16x16x32_bf16 v[4:7], v[184:187], v[228:231], v[4:7]
	v_mfma_f32_16x16x32_bf16 v[0:3], v[192:195], v[228:231], v[0:3]
	s_setprio 0
	s_barrier
	s_add_i32 s63, s63, 2
	s_add_u32 s42, s42, 0x100
	s_addc_u32 s43, s43, 0
	s_add_u32 s61, s61, 0x100
	s_addc_u32 s62, s62, 0
	s_cmp_gt_u32 s63, 13
	s_cbranch_scc0 .LBB0_228
	s_branch .Lpeel_exit_0
.LBB0_228:
	ds_read_b128 v[164:167], v151
	ds_read_b128 v[168:171], v151 offset:1024
	ds_read_b128 v[172:175], v151 offset:2048
	ds_read_b128 v[176:179], v151 offset:3072
	ds_read_b128 v[180:183], v155
	ds_read_b128 v[184:187], v155 offset:1024
	ds_read_b128 v[188:191], v155 offset:2048
	ds_read_b128 v[192:195], v155 offset:3072
	s_add_u32 s44, s42, 0xfffc0080
	s_addc_u32 s45, s43, -1
	s_cmp_eq_u32 s63, 12
	s_cselect_b32 s47, s31, s45
	s_cselect_b32 s46, s59, s44
	s_cselect_b32 s45, s35, s62
	s_cselect_b32 s44, s60, s61
	v_lshl_add_u64 v[144:145], s[42:43], 0, v[136:137]
	s_add_i32 m0, s27, 0xc000
	ds_read_b128 v[196:199], v159
	ds_read_b128 v[200:203], v159 offset:1024
	ds_read_b128 v[204:207], v159 offset:2048
	ds_read_b128 v[208:211], v159 offset:3072
	ds_read_b128 v[216:219], v159 offset:4096
	ds_read_b128 v[220:223], v159 offset:5120
	ds_read_b128 v[224:227], v159 offset:6144
	ds_read_b128 v[228:231], v159 offset:7168
	global_load_lds_dwordx4 v[144:145], off
	v_lshl_add_u64 v[144:145], s[42:43], 0, v[138:139]
	s_add_i32 m0, s27, 0xe000
	s_nop 0
	global_load_lds_dwordx4 v[144:145], off
	s_waitcnt vmcnt(8)
	s_waitcnt lgkmcnt(0)
	s_barrier
; #define PG8_STAGE(bufoff, gbase, voff) do { _Pragma("unroll") for (int _i = 0; _i < 2; ++_i) \
;         __builtin_amdgcn_global_load_lds((const unsigned*)((const char*)(gbase) + (voff)[_i]), (LAS unsigned*)(lds + (bufoff) + ldsw + _i * 8192), 16, 0, 0); } while (0)
; #define PG8_LDA(dst, b, h) do { _Pragma("unroll") for (int m = 0; m < 4; ++m) _Pragma("unroll") for (int k = 0; k < 2; ++k) dst[m][k] = *(const LAS bf16x8*)(lds + PG8_SA(b, h) + aoff + m * 2048 + k * 1024); } while (0)
; #define PG8_MMA(ai, bj, At, Bt) do { __builtin_amdgcn_s_setprio(1); _Pragma("unroll") for (int m = 0; m < 4; ++m) _Pragma("unroll") for (int n = 0; n < 2; ++n) _Pragma("unroll") for (int k = 0; k < 2; ++k) \
;         acc[ai][bj][m][n] = __builtin_amdgcn_mfma_f32_16x16x32_bf16(Bt[n][k], At[m][k], acc[ai][bj][m][n], 0, 0, 0); __builtin_amdgcn_s_setprio(0); } while (0)
; #define PG8_WAIT_V(n) asm volatile("s_waitcnt vmcnt(" #n ")" ::: "memory")
; #define PG8_WAIT_L(n) asm volatile("s_waitcnt lgkmcnt(" #n ")" ::: "memory")
; #define PG8_BAR __builtin_amdgcn_s_barrier()
; #define PG8_SCHED __builtin_amdgcn_sched_barrier(0)
; template <class Epi>
; DI void gemm_phase(LAS unsigned char* lds, const int wid, const Gemm g, const Order& S, const Epi& E) {
;     ...
;             PG8_WAIT_V(8); PG8_WAIT_L(0); PG8_BAR; PG8_MMA(0, 0, At, B0); PG8_MMA(0, 1, At, B1); PG8_BAR; PG8_SCHED;
;             PG8_LDA(At, 0, 1); PG8_STAGE(PG8_SB(0, 0), b2, voffB); PG8_STAGE(PG8_SB(0, 1), b2 + hstepB, voffB); PG8_STAGE(PG8_SA(0, 0), a2, voffA);
;             PG8_WAIT_V(8); PG8_WAIT_L(0); PG8_BAR; PG8_MMA(1, 0, At, B0); PG8_MMA(1, 1, At, B1); PG8_BAR; PG8_SCHED;
	s_setprio 1
	v_mfma_f32_16x16x32_bf16 v[124:127], v[164:167], v[196:199], v[124:127]
	v_mfma_f32_16x16x32_bf16 v[120:123], v[172:175], v[196:199], v[120:123]
	v_mfma_f32_16x16x32_bf16 v[108:111], v[164:167], v[204:207], v[108:111]
	v_mfma_f32_16x16x32_bf16 v[104:107], v[172:175], v[204:207], v[104:107]
	v_mfma_f32_16x16x32_bf16 v[92:95], v[164:167], v[216:219], v[92:95]
	v_mfma_f32_16x16x32_bf16 v[88:91], v[172:175], v[216:219], v[88:91]
	v_mfma_f32_16x16x32_bf16 v[76:79], v[164:167], v[224:227], v[76:79]
	v_mfma_f32_16x16x32_bf16 v[72:75], v[172:175], v[224:227], v[72:75]
	v_mfma_f32_16x16x32_bf16 v[124:127], v[168:171], v[200:203], v[124:127]
	v_mfma_f32_16x16x32_bf16 v[120:123], v[176:179], v[200:203], v[120:123]
	v_mfma_f32_16x16x32_bf16 v[108:111], v[168:171], v[208:211], v[108:111]
	v_mfma_f32_16x16x32_bf16 v[104:107], v[176:179], v[208:211], v[104:107]
	v_mfma_f32_16x16x32_bf16 v[92:95], v[168:171], v[220:223], v[92:95]
	v_mfma_f32_16x16x32_bf16 v[88:91], v[176:179], v[220:223], v[88:91]
	v_mfma_f32_16x16x32_bf16 v[76:79], v[168:171], v[228:231], v[76:79]
	v_mfma_f32_16x16x32_bf16 v[72:75], v[176:179], v[228:231], v[72:75]
	v_mfma_f32_16x16x32_bf16 v[116:119], v[180:183], v[196:199], v[116:119]
	v_mfma_f32_16x16x32_bf16 v[112:115], v[188:191], v[196:199], v[112:115]
	v_mfma_f32_16x16x32_bf16 v[100:103], v[180:183], v[204:207], v[100:103]
	v_mfma_f32_16x16x32_bf16 v[96:99], v[188:191], v[204:207], v[96:99]
	v_mfma_f32_16x16x32_bf16 v[84:87], v[180:183], v[216:219], v[84:87]
	v_mfma_f32_16x16x32_bf16 v[80:83], v[188:191], v[216:219], v[80:83]
	v_mfma_f32_16x16x32_bf16 v[68:71], v[180:183], v[224:227], v[68:71]
	v_mfma_f32_16x16x32_bf16 v[64:67], v[188:191], v[224:227], v[64:67]
	v_mfma_f32_16x16x32_bf16 v[116:119], v[184:187], v[200:203], v[116:119]
	v_mfma_f32_16x16x32_bf16 v[112:115], v[192:195], v[200:203], v[112:115]
	v_mfma_f32_16x16x32_bf16 v[100:103], v[184:187], v[208:211], v[100:103]
	v_mfma_f32_16x16x32_bf16 v[96:99], v[192:195], v[208:211], v[96:99]
	v_mfma_f32_16x16x32_bf16 v[84:87], v[184:187], v[220:223], v[84:87]
	v_mfma_f32_16x16x32_bf16 v[80:83], v[192:195], v[220:223], v[80:83]
	v_mfma_f32_16x16x32_bf16 v[68:71], v[184:187], v[228:231], v[68:71]
	v_mfma_f32_16x16x32_bf16 v[64:67], v[192:195], v[228:231], v[64:67]
	s_setprio 0
	s_barrier
	s_add_i32 s64, s56, s94
	v_lshl_add_u64 v[144:145], s[44:45], 0, v[132:133]
	s_mov_b32 m0, s64
	ds_read_b128 v[196:199], v159 offset:16384
	ds_read_b128 v[200:203], v159 offset:17408
	ds_read_b128 v[204:207], v159 offset:18432
	ds_read_b128 v[208:211], v159 offset:19456
	ds_read_b128 v[216:219], v159 offset:20480
	ds_read_b128 v[220:223], v159 offset:21504
	ds_read_b128 v[224:227], v159 offset:22528
	ds_read_b128 v[228:231], v159 offset:23552
	global_load_lds_dwordx4 v[144:145], off
	s_add_i32 m0, s64, 0x2000
	s_add_u32 s64, s44, 0x40000
	v_lshl_add_u64 v[148:149], s[44:45], 0, v[128:129]
	s_addc_u32 s65, s45, 0
	s_add_i32 s66, s57, s94
	global_load_lds_dwordx4 v[148:149], off
	v_lshl_add_u64 v[152:153], s[64:65], 0, v[132:133]
	s_mov_b32 m0, s66
	v_lshl_add_u64 v[156:157], s[46:47], 0, v[130:131]
	global_load_lds_dwordx4 v[152:153], off
	v_lshl_add_u64 v[152:153], s[64:65], 0, v[128:129]
	s_add_i32 m0, s66, 0x2000
	s_nop 0
	global_load_lds_dwordx4 v[152:153], off
	v_lshl_add_u64 v[152:153], s[46:47], 0, v[134:135]
	s_mov_b32 m0, s27
	s_nop 0
	global_load_lds_dwordx4 v[152:153], off
	s_mov_b32 m0, s41
	s_nop 0
	global_load_lds_dwordx4 v[156:157], off
	s_waitcnt vmcnt(8)
	s_waitcnt lgkmcnt(0)
	s_barrier
	s_setprio 1
	v_mfma_f32_16x16x32_bf16 v[60:63], v[164:167], v[196:199], v[60:63]
	v_mfma_f32_16x16x32_bf16 v[56:59], v[172:175], v[196:199], v[56:59]
	v_mfma_f32_16x16x32_bf16 v[44:47], v[164:167], v[204:207], v[44:47]
	v_mfma_f32_16x16x32_bf16 v[40:43], v[172:175], v[204:207], v[40:43]
	v_mfma_f32_16x16x32_bf16 v[28:31], v[164:167], v[216:219], v[28:31]
	v_mfma_f32_16x16x32_bf16 v[24:27], v[172:175], v[216:219], v[24:27]
	v_mfma_f32_16x16x32_bf16 v[12:15], v[164:167], v[224:227], v[12:15]
	v_mfma_f32_16x16x32_bf16 v[8:11], v[172:175], v[224:227], v[8:11]
	v_mfma_f32_16x16x32_bf16 v[60:63], v[168:171], v[200:203], v[60:63]
	v_mfma_f32_16x16x32_bf16 v[56:59], v[176:179], v[200:203], v[56:59]
	v_mfma_f32_16x16x32_bf16 v[44:47], v[168:171], v[208:211], v[44:47]
	v_mfma_f32_16x16x32_bf16 v[40:43], v[176:179], v[208:211], v[40:43]
	v_mfma_f32_16x16x32_bf16 v[28:31], v[168:171], v[220:223], v[28:31]
	v_mfma_f32_16x16x32_bf16 v[24:27], v[176:179], v[220:223], v[24:27]
	v_mfma_f32_16x16x32_bf16 v[12:15], v[168:171], v[228:231], v[12:15]
	v_mfma_f32_16x16x32_bf16 v[8:11], v[176:179], v[228:231], v[8:11]
	v_mfma_f32_16x16x32_bf16 v[52:55], v[180:183], v[196:199], v[52:55]
	v_mfma_f32_16x16x32_bf16 v[48:51], v[188:191], v[196:199], v[48:51]
	v_mfma_f32_16x16x32_bf16 v[36:39], v[180:183], v[204:207], v[36:39]
	v_mfma_f32_16x16x32_bf16 v[32:35], v[188:191], v[204:207], v[32:35]
	v_mfma_f32_16x16x32_bf16 v[20:23], v[180:183], v[216:219], v[20:23]
	v_mfma_f32_16x16x32_bf16 v[16:19], v[188:191], v[216:219], v[16:19]
	v_mfma_f32_16x16x32_bf16 v[4:7], v[180:183], v[224:227], v[4:7]
	v_mfma_f32_16x16x32_bf16 v[0:3], v[188:191], v[224:227], v[0:3]
	v_mfma_f32_16x16x32_bf16 v[52:55], v[184:187], v[200:203], v[52:55]
	v_mfma_f32_16x16x32_bf16 v[48:51], v[192:195], v[200:203], v[48:51]
	v_mfma_f32_16x16x32_bf16 v[36:39], v[184:187], v[208:211], v[36:39]
	v_mfma_f32_16x16x32_bf16 v[32:35], v[192:195], v[208:211], v[32:35]
	v_mfma_f32_16x16x32_bf16 v[20:23], v[184:187], v[220:223], v[20:23]
	v_mfma_f32_16x16x32_bf16 v[16:19], v[192:195], v[220:223], v[16:19]
	v_mfma_f32_16x16x32_bf16 v[4:7], v[184:187], v[228:231], v[4:7]
	v_mfma_f32_16x16x32_bf16 v[0:3], v[192:195], v[228:231], v[0:3]
	s_setprio 0
	s_barrier
; #define PG8_STAGE(bufoff, gbase, voff) do { _Pragma("unroll") for (int _i = 0; _i < 2; ++_i) \
;         __builtin_amdgcn_global_load_lds((const unsigned*)((const char*)(gbase) + (voff)[_i]), (LAS unsigned*)(lds + (bufoff) + ldsw + _i * 8192), 16, 0, 0); } while (0)
; #define PG8_LDA(dst, b, h) do { _Pragma("unroll") for (int m = 0; m < 4; ++m) _Pragma("unroll") for (int k = 0; k < 2; ++k) dst[m][k] = *(const LAS bf16x8*)(lds + PG8_SA(b, h) + aoff + m * 2048 + k * 1024); } while (0)
; #define PG8_LDB(dst, b, h) do { _Pragma("unroll") for (int n = 0; n < 2; ++n) _Pragma("unroll") for (int k = 0; k < 2; ++k) dst[n][k] = *(const LAS bf16x8*)(lds + PG8_SB(b, h) + boff + n * 2048 + k * 1024); } while (0)
; #define PG8_MMA(ai, bj, At, Bt) do { __builtin_amdgcn_s_setprio(1); _Pragma("unroll") for (int m = 0; m < 4; ++m) _Pragma("unroll") for (int n = 0; n < 2; ++n) _Pragma("unroll") for (int k = 0; k < 2; ++k) \
;         acc[ai][bj][m][n] = __builtin_amdgcn_mfma_f32_16x16x32_bf16(Bt[n][k], At[m][k], acc[ai][bj][m][n], 0, 0, 0); __builtin_amdgcn_s_setprio(0); } while (0)
; #define PG8_WAIT_V(n) asm volatile("s_waitcnt vmcnt(" #n ")" ::: "memory")
; #define PG8_WAIT_L(n) asm volatile("s_waitcnt lgkmcnt(" #n ")" ::: "memory")
; #define PG8_BAR __builtin_amdgcn_s_barrier()
; #define PG8_SCHED __builtin_amdgcn_sched_barrier(0)
; template <class Epi>
; DI void gemm_phase(LAS unsigned char* lds, const int wid, const Gemm g, const Order& S, const Epi& E) {
;     ...
;             PG8_LDB(B0, 1, 0); PG8_LDB(B1, 1, 1); PG8_SCHED; PG8_LDA(At, 1, 0); PG8_STAGE(PG8_SA(0, 1), a2 + hstepA, voffA);
;             PG8_WAIT_V(8); PG8_WAIT_L(0); PG8_BAR; PG8_MMA(0, 0, At, B0); PG8_MMA(0, 1, At, B1); PG8_BAR; PG8_SCHED;
	s_add_i32 s64, 0, 0x18000
	v_add_u32_e32 v146, s64, v147
	s_add_i32 s65, 0, 0x1c000
	ds_read_b128 v[164:167], v146
	ds_read_b128 v[168:171], v146 offset:1024
	ds_read_b128 v[172:175], v146 offset:2048
	ds_read_b128 v[176:179], v146 offset:3072
	v_add_u32_e32 v146, s65, v147
	ds_read_b128 v[180:183], v146
	ds_read_b128 v[184:187], v146 offset:1024
	ds_read_b128 v[188:191], v146 offset:2048
	ds_read_b128 v[192:195], v146 offset:3072
	s_add_u32 s46, s46, 0x40000
	s_addc_u32 s47, s47, 0
	s_mov_b32 m0, s48
	v_lshl_add_u64 v[160:161], s[46:47], 0, v[134:135]
	ds_read_b128 v[196:199], v159 offset:32768
	ds_read_b128 v[200:203], v159 offset:33792
	ds_read_b128 v[204:207], v159 offset:34816
	ds_read_b128 v[208:211], v159 offset:35840
	ds_read_b128 v[216:219], v159 offset:36864
	ds_read_b128 v[220:223], v159 offset:37888
	ds_read_b128 v[224:227], v159 offset:38912
	ds_read_b128 v[228:231], v159 offset:39936
	global_load_lds_dwordx4 v[160:161], off
	v_lshl_add_u64 v[160:161], s[46:47], 0, v[130:131]
	s_mov_b32 m0, s49
	s_nop 0
	global_load_lds_dwordx4 v[160:161], off
	s_waitcnt vmcnt(8)
	s_waitcnt lgkmcnt(0)
	s_barrier
	s_setprio 1
	v_mfma_f32_16x16x32_bf16 v[124:127], v[164:167], v[196:199], v[124:127]
	v_mfma_f32_16x16x32_bf16 v[120:123], v[172:175], v[196:199], v[120:123]
	v_mfma_f32_16x16x32_bf16 v[108:111], v[164:167], v[204:207], v[108:111]
	v_mfma_f32_16x16x32_bf16 v[104:107], v[172:175], v[204:207], v[104:107]
	v_mfma_f32_16x16x32_bf16 v[92:95], v[164:167], v[216:219], v[92:95]
	v_mfma_f32_16x16x32_bf16 v[88:91], v[172:175], v[216:219], v[88:91]
	v_mfma_f32_16x16x32_bf16 v[76:79], v[164:167], v[224:227], v[76:79]
	v_mfma_f32_16x16x32_bf16 v[72:75], v[172:175], v[224:227], v[72:75]
	v_mfma_f32_16x16x32_bf16 v[124:127], v[168:171], v[200:203], v[124:127]
	v_mfma_f32_16x16x32_bf16 v[120:123], v[176:179], v[200:203], v[120:123]
	v_mfma_f32_16x16x32_bf16 v[108:111], v[168:171], v[208:211], v[108:111]
	v_mfma_f32_16x16x32_bf16 v[104:107], v[176:179], v[208:211], v[104:107]
	v_mfma_f32_16x16x32_bf16 v[92:95], v[168:171], v[220:223], v[92:95]
	v_mfma_f32_16x16x32_bf16 v[88:91], v[176:179], v[220:223], v[88:91]
	v_mfma_f32_16x16x32_bf16 v[76:79], v[168:171], v[228:231], v[76:79]
	v_mfma_f32_16x16x32_bf16 v[72:75], v[176:179], v[228:231], v[72:75]
	v_mfma_f32_16x16x32_bf16 v[116:119], v[180:183], v[196:199], v[116:119]
	v_mfma_f32_16x16x32_bf16 v[112:115], v[188:191], v[196:199], v[112:115]
	v_mfma_f32_16x16x32_bf16 v[100:103], v[180:183], v[204:207], v[100:103]
	v_mfma_f32_16x16x32_bf16 v[96:99], v[188:191], v[204:207], v[96:99]
	v_mfma_f32_16x16x32_bf16 v[84:87], v[180:183], v[216:219], v[84:87]
	v_mfma_f32_16x16x32_bf16 v[80:83], v[188:191], v[216:219], v[80:83]
	v_mfma_f32_16x16x32_bf16 v[68:71], v[180:183], v[224:227], v[68:71]
	v_mfma_f32_16x16x32_bf16 v[64:67], v[188:191], v[224:227], v[64:67]
	v_mfma_f32_16x16x32_bf16 v[116:119], v[184:187], v[200:203], v[116:119]
	v_mfma_f32_16x16x32_bf16 v[112:115], v[192:195], v[200:203], v[112:115]
	v_mfma_f32_16x16x32_bf16 v[100:103], v[184:187], v[208:211], v[100:103]
	v_mfma_f32_16x16x32_bf16 v[96:99], v[192:195], v[208:211], v[96:99]
	v_mfma_f32_16x16x32_bf16 v[84:87], v[184:187], v[220:223], v[84:87]
	v_mfma_f32_16x16x32_bf16 v[80:83], v[192:195], v[220:223], v[80:83]
	v_mfma_f32_16x16x32_bf16 v[68:71], v[184:187], v[228:231], v[68:71]
	v_mfma_f32_16x16x32_bf16 v[64:67], v[192:195], v[228:231], v[64:67]
	s_setprio 0
	s_barrier
; #define PG8_STAGE(bufoff, gbase, voff) do { _Pragma("unroll") for (int _i = 0; _i < 2; ++_i) \
;         __builtin_amdgcn_global_load_lds((const unsigned*)((const char*)(gbase) + (voff)[_i]), (LAS unsigned*)(lds + (bufoff) + ldsw + _i * 8192), 16, 0, 0); } while (0)
; #define PG8_LDA(dst, b, h) do { _Pragma("unroll") for (int m = 0; m < 4; ++m) _Pragma("unroll") for (int k = 0; k < 2; ++k) dst[m][k] = *(const LAS bf16x8*)(lds + PG8_SA(b, h) + aoff + m * 2048 + k * 1024); } while (0)
; #define PG8_MMA(ai, bj, At, Bt) do { __builtin_amdgcn_s_setprio(1); _Pragma("unroll") for (int m = 0; m < 4; ++m) _Pragma("unroll") for (int n = 0; n < 2; ++n) _Pragma("unroll") for (int k = 0; k < 2; ++k) \
;         acc[ai][bj][m][n] = __builtin_amdgcn_mfma_f32_16x16x32_bf16(Bt[n][k], At[m][k], acc[ai][bj][m][n], 0, 0, 0); __builtin_amdgcn_s_setprio(0); } while (0)
; #define PG8_WAIT_V(n) asm volatile("s_waitcnt vmcnt(" #n ")" ::: "memory")
; #define PG8_WAIT_L(n) asm volatile("s_waitcnt lgkmcnt(" #n ")" ::: "memory")
; #define PG8_BAR __builtin_amdgcn_s_barrier()
; #define PG8_SCHED __builtin_amdgcn_sched_barrier(0)
; template <class Epi>
; DI void gemm_phase(LAS unsigned char* lds, const int wid, const Gemm g, const Order& S, const Epi& E) {
;     ...
;             PG8_LDA(At, 1, 1); PG8_STAGE(PG8_SB(1, 0), b3, voffB); PG8_STAGE(PG8_SB(1, 1), b3 + hstepB, voffB); PG8_STAGE(PG8_SA(1, 0), a3, voffA);
;             PG8_WAIT_V(8); PG8_WAIT_L(0); PG8_BAR; PG8_MMA(1, 0, At, B0); PG8_MMA(1, 1, At, B1); PG8_BAR; PG8_SCHED;
;         }
	s_add_i32 s46, s64, s94
	v_lshl_add_u64 v[144:145], v[144:145], 0, s[16:17]
	s_mov_b32 m0, s46
	ds_read_b128 v[196:199], v159 offset:49152
	ds_read_b128 v[200:203], v159 offset:50176
	ds_read_b128 v[204:207], v159 offset:51200
	ds_read_b128 v[208:211], v159 offset:52224
	ds_read_b128 v[216:219], v159 offset:53248
	ds_read_b128 v[220:223], v159 offset:54272
	ds_read_b128 v[224:227], v159 offset:55296
	ds_read_b128 v[228:231], v159 offset:56320
	global_load_lds_dwordx4 v[144:145], off
	s_add_i32 m0, s46, 0x2000
	s_add_u32 s44, s44, 0x40080
	v_lshl_add_u64 v[144:145], v[148:149], 0, s[16:17]
	s_addc_u32 s45, s45, 0
	s_add_i32 s46, s65, s94
	global_load_lds_dwordx4 v[144:145], off
	v_lshl_add_u64 v[144:145], s[44:45], 0, v[132:133]
	s_mov_b32 m0, s46
	s_nop 0
	global_load_lds_dwordx4 v[144:145], off
	v_lshl_add_u64 v[144:145], s[44:45], 0, v[128:129]
	s_add_i32 m0, s46, 0x2000
	s_nop 0
	global_load_lds_dwordx4 v[144:145], off
	v_lshl_add_u64 v[144:145], v[152:153], 0, s[16:17]
	s_mov_b32 m0, s51
	s_nop 0
	global_load_lds_dwordx4 v[144:145], off
	v_lshl_add_u64 v[144:145], v[156:157], 0, s[16:17]
	s_mov_b32 m0, s52
	s_nop 0
	global_load_lds_dwordx4 v[144:145], off
	s_waitcnt vmcnt(8)
	s_waitcnt lgkmcnt(0)
	s_barrier
	s_setprio 1
	v_mfma_f32_16x16x32_bf16 v[60:63], v[164:167], v[196:199], v[60:63]
	v_mfma_f32_16x16x32_bf16 v[56:59], v[172:175], v[196:199], v[56:59]
	v_mfma_f32_16x16x32_bf16 v[44:47], v[164:167], v[204:207], v[44:47]
	v_mfma_f32_16x16x32_bf16 v[40:43], v[172:175], v[204:207], v[40:43]
	v_mfma_f32_16x16x32_bf16 v[28:31], v[164:167], v[216:219], v[28:31]
	v_mfma_f32_16x16x32_bf16 v[24:27], v[172:175], v[216:219], v[24:27]
	v_mfma_f32_16x16x32_bf16 v[12:15], v[164:167], v[224:227], v[12:15]
	v_mfma_f32_16x16x32_bf16 v[8:11], v[172:175], v[224:227], v[8:11]
	v_mfma_f32_16x16x32_bf16 v[60:63], v[168:171], v[200:203], v[60:63]
	v_mfma_f32_16x16x32_bf16 v[56:59], v[176:179], v[200:203], v[56:59]
	v_mfma_f32_16x16x32_bf16 v[44:47], v[168:171], v[208:211], v[44:47]
	v_mfma_f32_16x16x32_bf16 v[40:43], v[176:179], v[208:211], v[40:43]
	v_mfma_f32_16x16x32_bf16 v[28:31], v[168:171], v[220:223], v[28:31]
	v_mfma_f32_16x16x32_bf16 v[24:27], v[176:179], v[220:223], v[24:27]
	v_mfma_f32_16x16x32_bf16 v[12:15], v[168:171], v[228:231], v[12:15]
	v_mfma_f32_16x16x32_bf16 v[8:11], v[176:179], v[228:231], v[8:11]
	v_mfma_f32_16x16x32_bf16 v[52:55], v[180:183], v[196:199], v[52:55]
	v_mfma_f32_16x16x32_bf16 v[48:51], v[188:191], v[196:199], v[48:51]
	v_mfma_f32_16x16x32_bf16 v[36:39], v[180:183], v[204:207], v[36:39]
	v_mfma_f32_16x16x32_bf16 v[32:35], v[188:191], v[204:207], v[32:35]
	v_mfma_f32_16x16x32_bf16 v[20:23], v[180:183], v[216:219], v[20:23]
	v_mfma_f32_16x16x32_bf16 v[16:19], v[188:191], v[216:219], v[16:19]
	v_mfma_f32_16x16x32_bf16 v[4:7], v[180:183], v[224:227], v[4:7]
	v_mfma_f32_16x16x32_bf16 v[0:3], v[188:191], v[224:227], v[0:3]
	v_mfma_f32_16x16x32_bf16 v[52:55], v[184:187], v[200:203], v[52:55]
	v_mfma_f32_16x16x32_bf16 v[48:51], v[192:195], v[200:203], v[48:51]
	v_mfma_f32_16x16x32_bf16 v[36:39], v[184:187], v[208:211], v[36:39]
	v_mfma_f32_16x16x32_bf16 v[32:35], v[192:195], v[208:211], v[32:35]
	v_mfma_f32_16x16x32_bf16 v[20:23], v[184:187], v[220:223], v[20:23]
	v_mfma_f32_16x16x32_bf16 v[16:19], v[192:195], v[220:223], v[16:19]
	v_mfma_f32_16x16x32_bf16 v[4:7], v[184:187], v[228:231], v[4:7]
	v_mfma_f32_16x16x32_bf16 v[0:3], v[192:195], v[228:231], v[0:3]
	s_setprio 0
	s_barrier
	s_add_i32 s63, s63, 2
	s_add_u32 s42, s42, 0x100
	s_addc_u32 s43, s43, 0
	s_add_u32 s61, s61, 0x100
	s_addc_u32 s62, s62, 0
	s_cmp_gt_u32 s63, 13
	s_cbranch_scc0 .LBB0_228

; #define PG8_STAGE(bufoff, gbase, voff) do { _Pragma("unroll") for (int _i = 0; _i < 2; ++_i) \
;         __builtin_amdgcn_global_load_lds((const unsigned*)((const char*)(gbase) + (voff)[_i]), (LAS unsigned*)(lds + (bufoff) + ldsw + _i * 8192), 16, 0, 0); } while (0)
; #define PG8_LDA(dst, b, h) do { _Pragma("unroll") for (int m = 0; m < 4; ++m) _Pragma("unroll") for (int k = 0; k < 2; ++k) dst[m][k] = *(const LAS bf16x8*)(lds + PG8_SA(b, h) + aoff + m * 2048 + k * 1024); } while (0)
; #define PG8_LDB(dst, b, h) do { _Pragma("unroll") for (int n = 0; n < 2; ++n) _Pragma("unroll") for (int k = 0; k < 2; ++k) dst[n][k] = *(const LAS bf16x8*)(lds + PG8_SB(b, h) + boff + n * 2048 + k * 1024); } while (0)
; #define PG8_MMA(ai, bj, At, Bt) do { __builtin_amdgcn_s_setprio(1); _Pragma("unroll") for (int m = 0; m < 4; ++m) _Pragma("unroll") for (int n = 0; n < 2; ++n) _Pragma("unroll") for (int k = 0; k < 2; ++k) \
;         acc[ai][bj][m][n] = __builtin_amdgcn_mfma_f32_16x16x32_bf16(Bt[n][k], At[m][k], acc[ai][bj][m][n], 0, 0, 0); __builtin_amdgcn_s_setprio(0); } while (0)
; template <class Epi>
; DI void gemm_phase(LAS unsigned char* lds, const int wid, const Gemm g, const Order& S, const Epi& E) {
;     ...
;         const bool has_next = S.next(ui + 1, nxt);
;         const char* nA = has_next ? (const char*)(g.A + (size_t)nxt.g * g.gsA + (size_t)nxt.pm * BM * g.lda) : cA;
;         const char* nB = has_next ? (const char*)(g.Bt + (size_t)nxt.g * g.gsB + (size_t)nxt.pn * BM * g.ldb) : cB;
;         for (int t = 0; t < nt; t += 2) {
;             const bool last = (t == nt - 2);
;             const char* a1 = cA + (size_t)(t + 1) * kstep;
;             const char* a2 = last ? nA : cA + (size_t)(t + 2) * kstep; const char* b2 = last ? nB : cB + (size_t)(t + 2) * kstep;
;             const char* a3 = a2 + kstep; const char* b3 = b2 + kstep;
;             PG8_LDB(B0, 0, 0); PG8_LDB(B1, 0, 1); PG8_SCHED; PG8_LDA(At, 0, 0); PG8_STAGE(PG8_SA(1, 1), a1 + hstepA, voffA);
;             PG8_WAIT_V(8); PG8_WAIT_L(0); PG8_BAR; PG8_MMA(0, 0, At, B0); PG8_MMA(0, 1, At, B1); PG8_BAR; PG8_SCHED;
;             PG8_LDA(At, 0, 1); PG8_STAGE(PG8_SB(0, 0), b2, voffB); PG8_STAGE(PG8_SB(0, 1), b2 + hstepB, voffB); PG8_STAGE(PG8_SA(0, 0), a2, voffA);
;             PG8_WAIT_V(8); PG8_WAIT_L(0); PG8_BAR; PG8_MMA(1, 0, At, B0); PG8_MMA(1, 1, At, B1); PG8_BAR; PG8_SCHED;
.LBB0_311:
	s_add_u32 s61, s44, 0x100
	v_mov_b32_e32 v0, 0
	s_addc_u32 s62, s45, 0
	s_mov_b32 s63, -2
	s_waitcnt lgkmcnt(0)
	ds_read_b128 v[128:131], v209
	ds_read_b128 v[132:135], v209 offset:1024
	ds_read_b128 v[136:139], v209 offset:2048
	ds_read_b128 v[140:143], v209 offset:3072
	ds_read_b128 v[144:147], v210
	ds_read_b128 v[148:151], v210 offset:1024
	ds_read_b128 v[152:155], v210 offset:2048
	ds_read_b128 v[156:159], v210 offset:3072
	s_add_u32 s10, s42, 0x100
	s_addc_u32 s11, s43, 0
	s_cmp_eq_u32 s63, 40
	s_cselect_b32 s47, s39, s11
	s_cselect_b32 s46, s38, s10
	s_cselect_b32 s45, s41, s62
	s_cselect_b32 s44, s40, s61
	v_lshl_add_u64 v[214:215], s[42:43], 0, v[184:185]
	s_add_i32 m0, s26, 0xc000
	ds_read_b128 v[160:163], v211
	ds_read_b128 v[164:167], v211 offset:1024
	ds_read_b128 v[168:171], v211 offset:2048
	ds_read_b128 v[172:175], v211 offset:3072
	ds_read_b128 v[192:195], v211 offset:4096
	ds_read_b128 v[196:199], v211 offset:5120
	ds_read_b128 v[200:203], v211 offset:6144
	ds_read_b128 v[204:207], v211 offset:7168
	global_load_lds_dwordx4 v[214:215], off
	v_lshl_add_u64 v[214:215], s[42:43], 0, v[186:187]
	s_add_i32 m0, s26, 0xe000
	s_nop 0
	global_load_lds_dwordx4 v[214:215], off
	s_waitcnt vmcnt(8)
	s_waitcnt lgkmcnt(0)
	s_barrier
	s_setprio 1
	v_mfma_f32_16x16x32_bf16 v[124:127], v[128:131], v[160:163], 0
	v_mfma_f32_16x16x32_bf16 v[120:123], v[136:139], v[160:163], 0
	v_mfma_f32_16x16x32_bf16 v[108:111], v[128:131], v[168:171], 0
	v_mfma_f32_16x16x32_bf16 v[104:107], v[136:139], v[168:171], 0
	v_mfma_f32_16x16x32_bf16 v[92:95], v[128:131], v[192:195], 0
	v_mfma_f32_16x16x32_bf16 v[88:91], v[136:139], v[192:195], 0
	v_mfma_f32_16x16x32_bf16 v[76:79], v[128:131], v[200:203], 0
	v_mfma_f32_16x16x32_bf16 v[72:75], v[136:139], v[200:203], 0
	v_mfma_f32_16x16x32_bf16 v[124:127], v[132:135], v[164:167], v[124:127]
	v_mfma_f32_16x16x32_bf16 v[120:123], v[140:143], v[164:167], v[120:123]
	v_mfma_f32_16x16x32_bf16 v[108:111], v[132:135], v[172:175], v[108:111]
	v_mfma_f32_16x16x32_bf16 v[104:107], v[140:143], v[172:175], v[104:107]
	v_mfma_f32_16x16x32_bf16 v[92:95], v[132:135], v[196:199], v[92:95]
	v_mfma_f32_16x16x32_bf16 v[88:91], v[140:143], v[196:199], v[88:91]
	v_mfma_f32_16x16x32_bf16 v[76:79], v[132:135], v[204:207], v[76:79]
	v_mfma_f32_16x16x32_bf16 v[72:75], v[140:143], v[204:207], v[72:75]
	v_mfma_f32_16x16x32_bf16 v[116:119], v[144:147], v[160:163], 0
	v_mfma_f32_16x16x32_bf16 v[112:115], v[152:155], v[160:163], 0
	v_mfma_f32_16x16x32_bf16 v[100:103], v[144:147], v[168:171], 0
	v_mfma_f32_16x16x32_bf16 v[96:99], v[152:155], v[168:171], 0
	v_mfma_f32_16x16x32_bf16 v[84:87], v[144:147], v[192:195], 0
	v_mfma_f32_16x16x32_bf16 v[80:83], v[152:155], v[192:195], 0
	v_mfma_f32_16x16x32_bf16 v[68:71], v[144:147], v[200:203], 0
	v_mfma_f32_16x16x32_bf16 v[64:67], v[152:155], v[200:203], 0
	v_mfma_f32_16x16x32_bf16 v[116:119], v[148:151], v[164:167], v[116:119]
	v_mfma_f32_16x16x32_bf16 v[112:115], v[156:159], v[164:167], v[112:115]
	v_mfma_f32_16x16x32_bf16 v[100:103], v[148:151], v[172:175], v[100:103]
	v_mfma_f32_16x16x32_bf16 v[96:99], v[156:159], v[172:175], v[96:99]
	v_mfma_f32_16x16x32_bf16 v[84:87], v[148:151], v[196:199], v[84:87]
	v_mfma_f32_16x16x32_bf16 v[80:83], v[156:159], v[196:199], v[80:83]
	v_mfma_f32_16x16x32_bf16 v[68:71], v[148:151], v[204:207], v[68:71]
	v_mfma_f32_16x16x32_bf16 v[64:67], v[156:159], v[204:207], v[64:67]
	s_setprio 0
	s_barrier
	s_add_i32 s42, s55, s94
	v_lshl_add_u64 v[214:215], s[44:45], 0, v[178:179]
	s_mov_b32 m0, s42
	ds_read_b128 v[160:163], v211 offset:16384
	ds_read_b128 v[164:167], v211 offset:17408
	ds_read_b128 v[168:171], v211 offset:18432
	ds_read_b128 v[172:175], v211 offset:19456
	ds_read_b128 v[192:195], v211 offset:20480
	ds_read_b128 v[196:199], v211 offset:21504
	ds_read_b128 v[200:203], v211 offset:22528
	ds_read_b128 v[204:207], v211 offset:23552
	global_load_lds_dwordx4 v[214:215], off
	s_add_i32 m0, s42, 0x2000
	s_add_u32 s42, s44, 0xb0000
	v_lshl_add_u64 v[216:217], s[44:45], 0, v[182:183]
	s_addc_u32 s43, s45, 0
	s_add_i32 s64, s56, s94
	global_load_lds_dwordx4 v[216:217], off
	v_lshl_add_u64 v[218:219], s[42:43], 0, v[178:179]
	s_mov_b32 m0, s64
	v_lshl_add_u64 v[220:221], s[46:47], 0, v[180:181]
	global_load_lds_dwordx4 v[218:219], off
	v_lshl_add_u64 v[218:219], s[42:43], 0, v[182:183]
	s_add_i32 m0, s64, 0x2000
	s_nop 0
	global_load_lds_dwordx4 v[218:219], off
	v_lshl_add_u64 v[218:219], s[46:47], 0, v[176:177]
	s_mov_b32 m0, s26
	s_nop 0
	global_load_lds_dwordx4 v[218:219], off
	s_mov_b32 m0, s27
	s_nop 0
	global_load_lds_dwordx4 v[220:221], off
	s_waitcnt vmcnt(8)
	s_waitcnt lgkmcnt(0)
	s_barrier
; #define PG8_STAGE(bufoff, gbase, voff) do { _Pragma("unroll") for (int _i = 0; _i < 2; ++_i) \
;         __builtin_amdgcn_global_load_lds((const unsigned*)((const char*)(gbase) + (voff)[_i]), (LAS unsigned*)(lds + (bufoff) + ldsw + _i * 8192), 16, 0, 0); } while (0)
; #define PG8_LDA(dst, b, h) do { _Pragma("unroll") for (int m = 0; m < 4; ++m) _Pragma("unroll") for (int k = 0; k < 2; ++k) dst[m][k] = *(const LAS bf16x8*)(lds + PG8_SA(b, h) + aoff + m * 2048 + k * 1024); } while (0)
; #define PG8_LDB(dst, b, h) do { _Pragma("unroll") for (int n = 0; n < 2; ++n) _Pragma("unroll") for (int k = 0; k < 2; ++k) dst[n][k] = *(const LAS bf16x8*)(lds + PG8_SB(b, h) + boff + n * 2048 + k * 1024); } while (0)
; #define PG8_MMA(ai, bj, At, Bt) do { __builtin_amdgcn_s_setprio(1); _Pragma("unroll") for (int m = 0; m < 4; ++m) _Pragma("unroll") for (int n = 0; n < 2; ++n) _Pragma("unroll") for (int k = 0; k < 2; ++k) \
;         acc[ai][bj][m][n] = __builtin_amdgcn_mfma_f32_16x16x32_bf16(Bt[n][k], At[m][k], acc[ai][bj][m][n], 0, 0, 0); __builtin_amdgcn_s_setprio(0); } while (0)
; #define PG8_WAIT_V(n) asm volatile("s_waitcnt vmcnt(" #n ")" ::: "memory")
; #define PG8_WAIT_L(n) asm volatile("s_waitcnt lgkmcnt(" #n ")" ::: "memory")
; #define PG8_BAR __builtin_amdgcn_s_barrier()
; #define PG8_SCHED __builtin_amdgcn_sched_barrier(0)
; template <class Epi>
; DI void gemm_phase(LAS unsigned char* lds, const int wid, const Gemm g, const Order& S, const Epi& E) {
;     ...
;             PG8_WAIT_V(8); PG8_WAIT_L(0); PG8_BAR; PG8_MMA(0, 0, At, B0); PG8_MMA(0, 1, At, B1); PG8_BAR; PG8_SCHED;
;             PG8_LDA(At, 0, 1); PG8_STAGE(PG8_SB(0, 0), b2, voffB); PG8_STAGE(PG8_SB(0, 1), b2 + hstepB, voffB); PG8_STAGE(PG8_SA(0, 0), a2, voffA);
;             PG8_WAIT_V(8); PG8_WAIT_L(0); PG8_BAR; PG8_MMA(1, 0, At, B0); PG8_MMA(1, 1, At, B1); PG8_BAR; PG8_SCHED;
;             PG8_LDB(B0, 1, 0); PG8_LDB(B1, 1, 1); PG8_SCHED; PG8_LDA(At, 1, 0); PG8_STAGE(PG8_SA(0, 1), a2 + hstepA, voffA);
;             PG8_WAIT_V(8); PG8_WAIT_L(0); PG8_BAR; PG8_MMA(0, 0, At, B0); PG8_MMA(0, 1, At, B1); PG8_BAR; PG8_SCHED;
	s_setprio 1
	v_mfma_f32_16x16x32_bf16 v[60:63], v[128:131], v[160:163], 0
	v_mfma_f32_16x16x32_bf16 v[56:59], v[136:139], v[160:163], 0
	v_mfma_f32_16x16x32_bf16 v[44:47], v[128:131], v[168:171], 0
	v_mfma_f32_16x16x32_bf16 v[40:43], v[136:139], v[168:171], 0
	v_mfma_f32_16x16x32_bf16 v[28:31], v[128:131], v[192:195], 0
	v_mfma_f32_16x16x32_bf16 v[24:27], v[136:139], v[192:195], 0
	v_mfma_f32_16x16x32_bf16 v[12:15], v[128:131], v[200:203], 0
	v_mfma_f32_16x16x32_bf16 v[8:11], v[136:139], v[200:203], 0
	v_mfma_f32_16x16x32_bf16 v[60:63], v[132:135], v[164:167], v[60:63]
	v_mfma_f32_16x16x32_bf16 v[56:59], v[140:143], v[164:167], v[56:59]
	v_mfma_f32_16x16x32_bf16 v[44:47], v[132:135], v[172:175], v[44:47]
	v_mfma_f32_16x16x32_bf16 v[40:43], v[140:143], v[172:175], v[40:43]
	v_mfma_f32_16x16x32_bf16 v[28:31], v[132:135], v[196:199], v[28:31]
	v_mfma_f32_16x16x32_bf16 v[24:27], v[140:143], v[196:199], v[24:27]
	v_mfma_f32_16x16x32_bf16 v[12:15], v[132:135], v[204:207], v[12:15]
	v_mfma_f32_16x16x32_bf16 v[8:11], v[140:143], v[204:207], v[8:11]
	v_mfma_f32_16x16x32_bf16 v[52:55], v[144:147], v[160:163], 0
	v_mfma_f32_16x16x32_bf16 v[48:51], v[152:155], v[160:163], 0
	v_mfma_f32_16x16x32_bf16 v[36:39], v[144:147], v[168:171], 0
	v_mfma_f32_16x16x32_bf16 v[32:35], v[152:155], v[168:171], 0
	v_mfma_f32_16x16x32_bf16 v[20:23], v[144:147], v[192:195], 0
	v_mfma_f32_16x16x32_bf16 v[16:19], v[152:155], v[192:195], 0
	v_mfma_f32_16x16x32_bf16 v[4:7], v[144:147], v[200:203], 0
	v_mfma_f32_16x16x32_bf16 v[0:3], v[152:155], v[200:203], 0
	v_mfma_f32_16x16x32_bf16 v[52:55], v[148:151], v[164:167], v[52:55]
	v_mfma_f32_16x16x32_bf16 v[48:51], v[156:159], v[164:167], v[48:51]
	v_mfma_f32_16x16x32_bf16 v[36:39], v[148:151], v[172:175], v[36:39]
	v_mfma_f32_16x16x32_bf16 v[32:35], v[156:159], v[172:175], v[32:35]
	v_mfma_f32_16x16x32_bf16 v[20:23], v[148:151], v[196:199], v[20:23]
	v_mfma_f32_16x16x32_bf16 v[16:19], v[156:159], v[196:199], v[16:19]
	v_mfma_f32_16x16x32_bf16 v[4:7], v[148:151], v[204:207], v[4:7]
	v_mfma_f32_16x16x32_bf16 v[0:3], v[156:159], v[204:207], v[0:3]
	s_setprio 0
	s_barrier
	s_add_i32 s64, 0, 0x18000
	s_add_i32 s65, 0, 0x1c000
	v_add_u32_e32 v140, s64, v208
	v_add_u32_e32 v156, s65, v208
	ds_read_b128 v[128:131], v140
	ds_read_b128 v[132:135], v140 offset:1024
	ds_read_b128 v[136:139], v140 offset:2048
	ds_read_b128 v[140:143], v140 offset:3072
	ds_read_b128 v[144:147], v156
	ds_read_b128 v[148:151], v156 offset:1024
	ds_read_b128 v[152:155], v156 offset:2048
	ds_read_b128 v[156:159], v156 offset:3072
	s_add_u32 s42, s46, 0xb0000
	s_addc_u32 s43, s47, 0
	s_mov_b32 m0, s48
	v_lshl_add_u64 v[222:223], s[42:43], 0, v[176:177]
	ds_read_b128 v[160:163], v211 offset:32768
	ds_read_b128 v[164:167], v211 offset:33792
	ds_read_b128 v[168:171], v211 offset:34816
	ds_read_b128 v[172:175], v211 offset:35840
	ds_read_b128 v[192:195], v211 offset:36864
	ds_read_b128 v[196:199], v211 offset:37888
	ds_read_b128 v[200:203], v211 offset:38912
	ds_read_b128 v[204:207], v211 offset:39936
	global_load_lds_dwordx4 v[222:223], off
	v_lshl_add_u64 v[222:223], s[42:43], 0, v[180:181]
	s_mov_b32 m0, s49
	s_nop 0
	global_load_lds_dwordx4 v[222:223], off
	s_waitcnt vmcnt(8)
	s_waitcnt lgkmcnt(0)
	s_barrier
	s_setprio 1
	v_mfma_f32_16x16x32_bf16 v[124:127], v[128:131], v[160:163], v[124:127]
	v_mfma_f32_16x16x32_bf16 v[120:123], v[136:139], v[160:163], v[120:123]
	v_mfma_f32_16x16x32_bf16 v[108:111], v[128:131], v[168:171], v[108:111]
	v_mfma_f32_16x16x32_bf16 v[104:107], v[136:139], v[168:171], v[104:107]
	v_mfma_f32_16x16x32_bf16 v[92:95], v[128:131], v[192:195], v[92:95]
	v_mfma_f32_16x16x32_bf16 v[88:91], v[136:139], v[192:195], v[88:91]
	v_mfma_f32_16x16x32_bf16 v[76:79], v[128:131], v[200:203], v[76:79]
	v_mfma_f32_16x16x32_bf16 v[72:75], v[136:139], v[200:203], v[72:75]
	v_mfma_f32_16x16x32_bf16 v[124:127], v[132:135], v[164:167], v[124:127]
	v_mfma_f32_16x16x32_bf16 v[120:123], v[140:143], v[164:167], v[120:123]
	v_mfma_f32_16x16x32_bf16 v[108:111], v[132:135], v[172:175], v[108:111]
	v_mfma_f32_16x16x32_bf16 v[104:107], v[140:143], v[172:175], v[104:107]
	v_mfma_f32_16x16x32_bf16 v[92:95], v[132:135], v[196:199], v[92:95]
	v_mfma_f32_16x16x32_bf16 v[88:91], v[140:143], v[196:199], v[88:91]
	v_mfma_f32_16x16x32_bf16 v[76:79], v[132:135], v[204:207], v[76:79]
	v_mfma_f32_16x16x32_bf16 v[72:75], v[140:143], v[204:207], v[72:75]
	v_mfma_f32_16x16x32_bf16 v[116:119], v[144:147], v[160:163], v[116:119]
	v_mfma_f32_16x16x32_bf16 v[112:115], v[152:155], v[160:163], v[112:115]
	v_mfma_f32_16x16x32_bf16 v[100:103], v[144:147], v[168:171], v[100:103]
	v_mfma_f32_16x16x32_bf16 v[96:99], v[152:155], v[168:171], v[96:99]
	v_mfma_f32_16x16x32_bf16 v[84:87], v[144:147], v[192:195], v[84:87]
	v_mfma_f32_16x16x32_bf16 v[80:83], v[152:155], v[192:195], v[80:83]
	v_mfma_f32_16x16x32_bf16 v[68:71], v[144:147], v[200:203], v[68:71]
	v_mfma_f32_16x16x32_bf16 v[64:67], v[152:155], v[200:203], v[64:67]
	v_mfma_f32_16x16x32_bf16 v[116:119], v[148:151], v[164:167], v[116:119]
	v_mfma_f32_16x16x32_bf16 v[112:115], v[156:159], v[164:167], v[112:115]
	v_mfma_f32_16x16x32_bf16 v[100:103], v[148:151], v[172:175], v[100:103]
	v_mfma_f32_16x16x32_bf16 v[96:99], v[156:159], v[172:175], v[96:99]
	v_mfma_f32_16x16x32_bf16 v[84:87], v[148:151], v[196:199], v[84:87]
	v_mfma_f32_16x16x32_bf16 v[80:83], v[156:159], v[196:199], v[80:83]
	v_mfma_f32_16x16x32_bf16 v[68:71], v[148:151], v[204:207], v[68:71]
	v_mfma_f32_16x16x32_bf16 v[64:67], v[156:159], v[204:207], v[64:67]
	s_setprio 0
	s_barrier
; #define PG8_STAGE(bufoff, gbase, voff) do { _Pragma("unroll") for (int _i = 0; _i < 2; ++_i) \
;         __builtin_amdgcn_global_load_lds((const unsigned*)((const char*)(gbase) + (voff)[_i]), (LAS unsigned*)(lds + (bufoff) + ldsw + _i * 8192), 16, 0, 0); } while (0)
; #define PG8_LDA(dst, b, h) do { _Pragma("unroll") for (int m = 0; m < 4; ++m) _Pragma("unroll") for (int k = 0; k < 2; ++k) dst[m][k] = *(const LAS bf16x8*)(lds + PG8_SA(b, h) + aoff + m * 2048 + k * 1024); } while (0)
; #define PG8_LDB(dst, b, h) do { _Pragma("unroll") for (int n = 0; n < 2; ++n) _Pragma("unroll") for (int k = 0; k < 2; ++k) dst[n][k] = *(const LAS bf16x8*)(lds + PG8_SB(b, h) + boff + n * 2048 + k * 1024); } while (0)
; #define PG8_MMA(ai, bj, At, Bt) do { __builtin_amdgcn_s_setprio(1); _Pragma("unroll") for (int m = 0; m < 4; ++m) _Pragma("unroll") for (int n = 0; n < 2; ++n) _Pragma("unroll") for (int k = 0; k < 2; ++k) \
;         acc[ai][bj][m][n] = __builtin_amdgcn_mfma_f32_16x16x32_bf16(Bt[n][k], At[m][k], acc[ai][bj][m][n], 0, 0, 0); __builtin_amdgcn_s_setprio(0); } while (0)
; #define PG8_WAIT_V(n) asm volatile("s_waitcnt vmcnt(" #n ")" ::: "memory")
; #define PG8_WAIT_L(n) asm volatile("s_waitcnt lgkmcnt(" #n ")" ::: "memory")
; template <class Epi>
; DI void gemm_phase(LAS unsigned char* lds, const int wid, const Gemm g, const Order& S, const Epi& E) {
;     ...
;             PG8_LDB(B0, 0, 0); PG8_LDB(B1, 0, 1); PG8_SCHED; PG8_LDA(At, 0, 0); PG8_STAGE(PG8_SA(1, 1), a1 + hstepA, voffA);
;             PG8_WAIT_V(8); PG8_WAIT_L(0); PG8_BAR; PG8_MMA(0, 0, At, B0); PG8_MMA(0, 1, At, B1); PG8_BAR; PG8_SCHED;
;             PG8_LDA(At, 0, 1); PG8_STAGE(PG8_SB(0, 0), b2, voffB); PG8_STAGE(PG8_SB(0, 1), b2 + hstepB, voffB); PG8_STAGE(PG8_SA(0, 0), a2, voffA);
;             PG8_WAIT_V(8); PG8_WAIT_L(0); PG8_BAR; PG8_MMA(1, 0, At, B0); PG8_MMA(1, 1, At, B1); PG8_BAR; PG8_SCHED;
;             PG8_LDB(B0, 1, 0); PG8_LDB(B1, 1, 1); PG8_SCHED; PG8_LDA(At, 1, 0); PG8_STAGE(PG8_SA(0, 1), a2 + hstepA, voffA);
;             PG8_WAIT_V(8); PG8_WAIT_L(0); PG8_BAR; PG8_MMA(0, 0, At, B0); PG8_MMA(0, 1, At, B1); PG8_BAR; PG8_SCHED;
;             PG8_LDA(At, 1, 1); PG8_STAGE(PG8_SB(1, 0), b3, voffB); PG8_STAGE(PG8_SB(1, 1), b3 + hstepB, voffB); PG8_STAGE(PG8_SA(1, 0), a3, voffA);
;             PG8_WAIT_V(8); PG8_WAIT_L(0); PG8_BAR; PG8_MMA(1, 0, At, B0); PG8_MMA(1, 1, At, B1); PG8_BAR; PG8_SCHED;
	s_add_i32 s42, s64, s94
	v_lshl_add_u64 v[214:215], v[214:215], 0, s[34:35]
	s_mov_b32 m0, s42
	ds_read_b128 v[160:163], v211 offset:49152
	ds_read_b128 v[164:167], v211 offset:50176
	ds_read_b128 v[168:171], v211 offset:51200
	ds_read_b128 v[172:175], v211 offset:52224
	ds_read_b128 v[192:195], v211 offset:53248
	ds_read_b128 v[196:199], v211 offset:54272
	ds_read_b128 v[200:203], v211 offset:55296
	ds_read_b128 v[204:207], v211 offset:56320
	global_load_lds_dwordx4 v[214:215], off
	s_add_i32 m0, s42, 0x2000
	s_add_u32 s42, s44, 0xb0080
	v_lshl_add_u64 v[214:215], v[216:217], 0, s[34:35]
	s_addc_u32 s43, s45, 0
	s_add_i32 s44, s65, s94
	global_load_lds_dwordx4 v[214:215], off
	v_lshl_add_u64 v[214:215], s[42:43], 0, v[178:179]
	s_mov_b32 m0, s44
	s_nop 0
	global_load_lds_dwordx4 v[214:215], off
	v_lshl_add_u64 v[214:215], s[42:43], 0, v[182:183]
	s_add_i32 m0, s44, 0x2000
	s_nop 0
	global_load_lds_dwordx4 v[214:215], off
	v_lshl_add_u64 v[214:215], v[218:219], 0, s[34:35]
	s_mov_b32 m0, s51
	s_nop 0
	global_load_lds_dwordx4 v[214:215], off
	v_lshl_add_u64 v[214:215], v[220:221], 0, s[34:35]
	s_mov_b32 m0, s52
	s_nop 0
	global_load_lds_dwordx4 v[214:215], off
	s_waitcnt vmcnt(8)
	s_waitcnt lgkmcnt(0)
	s_barrier
	s_setprio 1
	v_mfma_f32_16x16x32_bf16 v[60:63], v[128:131], v[160:163], v[60:63]
	v_mfma_f32_16x16x32_bf16 v[56:59], v[136:139], v[160:163], v[56:59]
	v_mfma_f32_16x16x32_bf16 v[44:47], v[128:131], v[168:171], v[44:47]
	v_mfma_f32_16x16x32_bf16 v[40:43], v[136:139], v[168:171], v[40:43]
	v_mfma_f32_16x16x32_bf16 v[28:31], v[128:131], v[192:195], v[28:31]
	v_mfma_f32_16x16x32_bf16 v[24:27], v[136:139], v[192:195], v[24:27]
	v_mfma_f32_16x16x32_bf16 v[12:15], v[128:131], v[200:203], v[12:15]
	v_mfma_f32_16x16x32_bf16 v[8:11], v[136:139], v[200:203], v[8:11]
	v_mfma_f32_16x16x32_bf16 v[60:63], v[132:135], v[164:167], v[60:63]
	v_mfma_f32_16x16x32_bf16 v[56:59], v[140:143], v[164:167], v[56:59]
	v_mfma_f32_16x16x32_bf16 v[44:47], v[132:135], v[172:175], v[44:47]
	v_mfma_f32_16x16x32_bf16 v[40:43], v[140:143], v[172:175], v[40:43]
	v_mfma_f32_16x16x32_bf16 v[28:31], v[132:135], v[196:199], v[28:31]
	v_mfma_f32_16x16x32_bf16 v[24:27], v[140:143], v[196:199], v[24:27]
	v_mfma_f32_16x16x32_bf16 v[12:15], v[132:135], v[204:207], v[12:15]
	v_mfma_f32_16x16x32_bf16 v[8:11], v[140:143], v[204:207], v[8:11]
	v_mfma_f32_16x16x32_bf16 v[52:55], v[144:147], v[160:163], v[52:55]
	v_mfma_f32_16x16x32_bf16 v[48:51], v[152:155], v[160:163], v[48:51]
	v_mfma_f32_16x16x32_bf16 v[36:39], v[144:147], v[168:171], v[36:39]
	v_mfma_f32_16x16x32_bf16 v[32:35], v[152:155], v[168:171], v[32:35]
	v_mfma_f32_16x16x32_bf16 v[20:23], v[144:147], v[192:195], v[20:23]
	v_mfma_f32_16x16x32_bf16 v[16:19], v[152:155], v[192:195], v[16:19]
	v_mfma_f32_16x16x32_bf16 v[4:7], v[144:147], v[200:203], v[4:7]
	v_mfma_f32_16x16x32_bf16 v[0:3], v[152:155], v[200:203], v[0:3]
	v_mfma_f32_16x16x32_bf16 v[52:55], v[148:151], v[164:167], v[52:55]
	v_mfma_f32_16x16x32_bf16 v[48:51], v[156:159], v[164:167], v[48:51]
	v_mfma_f32_16x16x32_bf16 v[36:39], v[148:151], v[172:175], v[36:39]
	v_mfma_f32_16x16x32_bf16 v[32:35], v[156:159], v[172:175], v[32:35]
	v_mfma_f32_16x16x32_bf16 v[20:23], v[148:151], v[196:199], v[20:23]
	v_mfma_f32_16x16x32_bf16 v[16:19], v[156:159], v[196:199], v[16:19]
	v_mfma_f32_16x16x32_bf16 v[4:7], v[148:151], v[204:207], v[4:7]
	v_mfma_f32_16x16x32_bf16 v[0:3], v[156:159], v[204:207], v[0:3]
	s_setprio 0
	s_barrier
	s_add_i32 s63, s63, 2
	s_add_u32 s61, s61, 0x100
	s_addc_u32 s62, s62, 0
	s_cmp_gt_u32 s63, 41
	s_mov_b64 s[42:43], s[10:11]
	s_cbranch_scc0 .LBB0_312
	s_branch .Lpeel_exit_1
.LBB0_312:
	ds_read_b128 v[128:131], v209
	ds_read_b128 v[132:135], v209 offset:1024
	ds_read_b128 v[136:139], v209 offset:2048
	ds_read_b128 v[140:143], v209 offset:3072
	ds_read_b128 v[144:147], v210
	ds_read_b128 v[148:151], v210 offset:1024
	ds_read_b128 v[152:155], v210 offset:2048
	ds_read_b128 v[156:159], v210 offset:3072
	s_add_u32 s10, s42, 0x100
	s_addc_u32 s11, s43, 0
	s_cmp_eq_u32 s63, 40
	s_cselect_b32 s47, s39, s11
	s_cselect_b32 s46, s38, s10
	s_cselect_b32 s45, s41, s62
	s_cselect_b32 s44, s40, s61
	v_lshl_add_u64 v[214:215], s[42:43], 0, v[184:185]
	s_add_i32 m0, s26, 0xc000
	ds_read_b128 v[160:163], v211
	ds_read_b128 v[164:167], v211 offset:1024
	ds_read_b128 v[168:171], v211 offset:2048
	ds_read_b128 v[172:175], v211 offset:3072
	ds_read_b128 v[192:195], v211 offset:4096
	ds_read_b128 v[196:199], v211 offset:5120
	ds_read_b128 v[200:203], v211 offset:6144
	ds_read_b128 v[204:207], v211 offset:7168
	global_load_lds_dwordx4 v[214:215], off
	v_lshl_add_u64 v[214:215], s[42:43], 0, v[186:187]
	s_add_i32 m0, s26, 0xe000
	s_nop 0
	global_load_lds_dwordx4 v[214:215], off
	s_waitcnt vmcnt(8)
	s_waitcnt lgkmcnt(0)
	s_barrier
; #define PG8_STAGE(bufoff, gbase, voff) do { _Pragma("unroll") for (int _i = 0; _i < 2; ++_i) \
;         __builtin_amdgcn_global_load_lds((const unsigned*)((const char*)(gbase) + (voff)[_i]), (LAS unsigned*)(lds + (bufoff) + ldsw + _i * 8192), 16, 0, 0); } while (0)
; #define PG8_LDA(dst, b, h) do { _Pragma("unroll") for (int m = 0; m < 4; ++m) _Pragma("unroll") for (int k = 0; k < 2; ++k) dst[m][k] = *(const LAS bf16x8*)(lds + PG8_SA(b, h) + aoff + m * 2048 + k * 1024); } while (0)
; #define PG8_MMA(ai, bj, At, Bt) do { __builtin_amdgcn_s_setprio(1); _Pragma("unroll") for (int m = 0; m < 4; ++m) _Pragma("unroll") for (int n = 0; n < 2; ++n) _Pragma("unroll") for (int k = 0; k < 2; ++k) \
;         acc[ai][bj][m][n] = __builtin_amdgcn_mfma_f32_16x16x32_bf16(Bt[n][k], At[m][k], acc[ai][bj][m][n], 0, 0, 0); __builtin_amdgcn_s_setprio(0); } while (0)
; #define PG8_WAIT_V(n) asm volatile("s_waitcnt vmcnt(" #n ")" ::: "memory")
; #define PG8_WAIT_L(n) asm volatile("s_waitcnt lgkmcnt(" #n ")" ::: "memory")
; #define PG8_BAR __builtin_amdgcn_s_barrier()
; #define PG8_SCHED __builtin_amdgcn_sched_barrier(0)
; template <class Epi>
; DI void gemm_phase(LAS unsigned char* lds, const int wid, const Gemm g, const Order& S, const Epi& E) {
;     ...
;             PG8_WAIT_V(8); PG8_WAIT_L(0); PG8_BAR; PG8_MMA(0, 0, At, B0); PG8_MMA(0, 1, At, B1); PG8_BAR; PG8_SCHED;
;             PG8_LDA(At, 0, 1); PG8_STAGE(PG8_SB(0, 0), b2, voffB); PG8_STAGE(PG8_SB(0, 1), b2 + hstepB, voffB); PG8_STAGE(PG8_SA(0, 0), a2, voffA);
;             PG8_WAIT_V(8); PG8_WAIT_L(0); PG8_BAR; PG8_MMA(1, 0, At, B0); PG8_MMA(1, 1, At, B1); PG8_BAR; PG8_SCHED;
	s_setprio 1
	v_mfma_f32_16x16x32_bf16 v[124:127], v[128:131], v[160:163], v[124:127]
	v_mfma_f32_16x16x32_bf16 v[120:123], v[136:139], v[160:163], v[120:123]
	v_mfma_f32_16x16x32_bf16 v[108:111], v[128:131], v[168:171], v[108:111]
	v_mfma_f32_16x16x32_bf16 v[104:107], v[136:139], v[168:171], v[104:107]
	v_mfma_f32_16x16x32_bf16 v[92:95], v[128:131], v[192:195], v[92:95]
	v_mfma_f32_16x16x32_bf16 v[88:91], v[136:139], v[192:195], v[88:91]
	v_mfma_f32_16x16x32_bf16 v[76:79], v[128:131], v[200:203], v[76:79]
	v_mfma_f32_16x16x32_bf16 v[72:75], v[136:139], v[200:203], v[72:75]
	v_mfma_f32_16x16x32_bf16 v[124:127], v[132:135], v[164:167], v[124:127]
	v_mfma_f32_16x16x32_bf16 v[120:123], v[140:143], v[164:167], v[120:123]
	v_mfma_f32_16x16x32_bf16 v[108:111], v[132:135], v[172:175], v[108:111]
	v_mfma_f32_16x16x32_bf16 v[104:107], v[140:143], v[172:175], v[104:107]
	v_mfma_f32_16x16x32_bf16 v[92:95], v[132:135], v[196:199], v[92:95]
	v_mfma_f32_16x16x32_bf16 v[88:91], v[140:143], v[196:199], v[88:91]
	v_mfma_f32_16x16x32_bf16 v[76:79], v[132:135], v[204:207], v[76:79]
	v_mfma_f32_16x16x32_bf16 v[72:75], v[140:143], v[204:207], v[72:75]
	v_mfma_f32_16x16x32_bf16 v[116:119], v[144:147], v[160:163], v[116:119]
	v_mfma_f32_16x16x32_bf16 v[112:115], v[152:155], v[160:163], v[112:115]
	v_mfma_f32_16x16x32_bf16 v[100:103], v[144:147], v[168:171], v[100:103]
	v_mfma_f32_16x16x32_bf16 v[96:99], v[152:155], v[168:171], v[96:99]
	v_mfma_f32_16x16x32_bf16 v[84:87], v[144:147], v[192:195], v[84:87]
	v_mfma_f32_16x16x32_bf16 v[80:83], v[152:155], v[192:195], v[80:83]
	v_mfma_f32_16x16x32_bf16 v[68:71], v[144:147], v[200:203], v[68:71]
	v_mfma_f32_16x16x32_bf16 v[64:67], v[152:155], v[200:203], v[64:67]
	v_mfma_f32_16x16x32_bf16 v[116:119], v[148:151], v[164:167], v[116:119]
	v_mfma_f32_16x16x32_bf16 v[112:115], v[156:159], v[164:167], v[112:115]
	v_mfma_f32_16x16x32_bf16 v[100:103], v[148:151], v[172:175], v[100:103]
	v_mfma_f32_16x16x32_bf16 v[96:99], v[156:159], v[172:175], v[96:99]
	v_mfma_f32_16x16x32_bf16 v[84:87], v[148:151], v[196:199], v[84:87]
	v_mfma_f32_16x16x32_bf16 v[80:83], v[156:159], v[196:199], v[80:83]
	v_mfma_f32_16x16x32_bf16 v[68:71], v[148:151], v[204:207], v[68:71]
	v_mfma_f32_16x16x32_bf16 v[64:67], v[156:159], v[204:207], v[64:67]
	s_setprio 0
	s_barrier
	s_add_i32 s42, s55, s94
	v_lshl_add_u64 v[214:215], s[44:45], 0, v[178:179]
	s_mov_b32 m0, s42
	ds_read_b128 v[160:163], v211 offset:16384
	ds_read_b128 v[164:167], v211 offset:17408
	ds_read_b128 v[168:171], v211 offset:18432
	ds_read_b128 v[172:175], v211 offset:19456
	ds_read_b128 v[192:195], v211 offset:20480
	ds_read_b128 v[196:199], v211 offset:21504
	ds_read_b128 v[200:203], v211 offset:22528
	ds_read_b128 v[204:207], v211 offset:23552
	global_load_lds_dwordx4 v[214:215], off
	s_add_i32 m0, s42, 0x2000
	s_add_u32 s42, s44, 0xb0000
	v_lshl_add_u64 v[216:217], s[44:45], 0, v[182:183]
	s_addc_u32 s43, s45, 0
	s_add_i32 s64, s56, s94
	global_load_lds_dwordx4 v[216:217], off
	v_lshl_add_u64 v[218:219], s[42:43], 0, v[178:179]
	s_mov_b32 m0, s64
	v_lshl_add_u64 v[220:221], s[46:47], 0, v[180:181]
	global_load_lds_dwordx4 v[218:219], off
	v_lshl_add_u64 v[218:219], s[42:43], 0, v[182:183]
	s_add_i32 m0, s64, 0x2000
	s_nop 0
	global_load_lds_dwordx4 v[218:219], off
	v_lshl_add_u64 v[218:219], s[46:47], 0, v[176:177]
	s_mov_b32 m0, s26
	s_nop 0
	global_load_lds_dwordx4 v[218:219], off
	s_mov_b32 m0, s27
	s_nop 0
	global_load_lds_dwordx4 v[220:221], off
	s_waitcnt vmcnt(8)
	s_waitcnt lgkmcnt(0)
	s_barrier
	s_setprio 1
	v_mfma_f32_16x16x32_bf16 v[60:63], v[128:131], v[160:163], v[60:63]
	v_mfma_f32_16x16x32_bf16 v[56:59], v[136:139], v[160:163], v[56:59]
	v_mfma_f32_16x16x32_bf16 v[44:47], v[128:131], v[168:171], v[44:47]
	v_mfma_f32_16x16x32_bf16 v[40:43], v[136:139], v[168:171], v[40:43]
	v_mfma_f32_16x16x32_bf16 v[28:31], v[128:131], v[192:195], v[28:31]
	v_mfma_f32_16x16x32_bf16 v[24:27], v[136:139], v[192:195], v[24:27]
	v_mfma_f32_16x16x32_bf16 v[12:15], v[128:131], v[200:203], v[12:15]
	v_mfma_f32_16x16x32_bf16 v[8:11], v[136:139], v[200:203], v[8:11]
	v_mfma_f32_16x16x32_bf16 v[60:63], v[132:135], v[164:167], v[60:63]
	v_mfma_f32_16x16x32_bf16 v[56:59], v[140:143], v[164:167], v[56:59]
	v_mfma_f32_16x16x32_bf16 v[44:47], v[132:135], v[172:175], v[44:47]
	v_mfma_f32_16x16x32_bf16 v[40:43], v[140:143], v[172:175], v[40:43]
	v_mfma_f32_16x16x32_bf16 v[28:31], v[132:135], v[196:199], v[28:31]
	v_mfma_f32_16x16x32_bf16 v[24:27], v[140:143], v[196:199], v[24:27]
	v_mfma_f32_16x16x32_bf16 v[12:15], v[132:135], v[204:207], v[12:15]
	v_mfma_f32_16x16x32_bf16 v[8:11], v[140:143], v[204:207], v[8:11]
	v_mfma_f32_16x16x32_bf16 v[52:55], v[144:147], v[160:163], v[52:55]
	v_mfma_f32_16x16x32_bf16 v[48:51], v[152:155], v[160:163], v[48:51]
	v_mfma_f32_16x16x32_bf16 v[36:39], v[144:147], v[168:171], v[36:39]
	v_mfma_f32_16x16x32_bf16 v[32:35], v[152:155], v[168:171], v[32:35]
	v_mfma_f32_16x16x32_bf16 v[20:23], v[144:147], v[192:195], v[20:23]
	v_mfma_f32_16x16x32_bf16 v[16:19], v[152:155], v[192:195], v[16:19]
	v_mfma_f32_16x16x32_bf16 v[4:7], v[144:147], v[200:203], v[4:7]
	v_mfma_f32_16x16x32_bf16 v[0:3], v[152:155], v[200:203], v[0:3]
	v_mfma_f32_16x16x32_bf16 v[52:55], v[148:151], v[164:167], v[52:55]
	v_mfma_f32_16x16x32_bf16 v[48:51], v[156:159], v[164:167], v[48:51]
	v_mfma_f32_16x16x32_bf16 v[36:39], v[148:151], v[172:175], v[36:39]
	v_mfma_f32_16x16x32_bf16 v[32:35], v[156:159], v[172:175], v[32:35]
	v_mfma_f32_16x16x32_bf16 v[20:23], v[148:151], v[196:199], v[20:23]
	v_mfma_f32_16x16x32_bf16 v[16:19], v[156:159], v[196:199], v[16:19]
	v_mfma_f32_16x16x32_bf16 v[4:7], v[148:151], v[204:207], v[4:7]
	v_mfma_f32_16x16x32_bf16 v[0:3], v[156:159], v[204:207], v[0:3]
	s_setprio 0
	s_barrier
; #define PG8_STAGE(bufoff, gbase, voff) do { _Pragma("unroll") for (int _i = 0; _i < 2; ++_i) \
;         __builtin_amdgcn_global_load_lds((const unsigned*)((const char*)(gbase) + (voff)[_i]), (LAS unsigned*)(lds + (bufoff) + ldsw + _i * 8192), 16, 0, 0); } while (0)
; #define PG8_LDA(dst, b, h) do { _Pragma("unroll") for (int m = 0; m < 4; ++m) _Pragma("unroll") for (int k = 0; k < 2; ++k) dst[m][k] = *(const LAS bf16x8*)(lds + PG8_SA(b, h) + aoff + m * 2048 + k * 1024); } while (0)
; #define PG8_LDB(dst, b, h) do { _Pragma("unroll") for (int n = 0; n < 2; ++n) _Pragma("unroll") for (int k = 0; k < 2; ++k) dst[n][k] = *(const LAS bf16x8*)(lds + PG8_SB(b, h) + boff + n * 2048 + k * 1024); } while (0)
; #define PG8_MMA(ai, bj, At, Bt) do { __builtin_amdgcn_s_setprio(1); _Pragma("unroll") for (int m = 0; m < 4; ++m) _Pragma("unroll") for (int n = 0; n < 2; ++n) _Pragma("unroll") for (int k = 0; k < 2; ++k) \
;         acc[ai][bj][m][n] = __builtin_amdgcn_mfma_f32_16x16x32_bf16(Bt[n][k], At[m][k], acc[ai][bj][m][n], 0, 0, 0); __builtin_amdgcn_s_setprio(0); } while (0)
; #define PG8_WAIT_V(n) asm volatile("s_waitcnt vmcnt(" #n ")" ::: "memory")
; #define PG8_WAIT_L(n) asm volatile("s_waitcnt lgkmcnt(" #n ")" ::: "memory")
; #define PG8_BAR __builtin_amdgcn_s_barrier()
; #define PG8_SCHED __builtin_amdgcn_sched_barrier(0)
; template <class Epi>
; DI void gemm_phase(LAS unsigned char* lds, const int wid, const Gemm g, const Order& S, const Epi& E) {
;     ...
;         for (int t = 0; t < nt; t += 2) {
;     ...
;             PG8_LDB(B0, 1, 0); PG8_LDB(B1, 1, 1); PG8_SCHED; PG8_LDA(At, 1, 0); PG8_STAGE(PG8_SA(0, 1), a2 + hstepA, voffA);
;             PG8_WAIT_V(8); PG8_WAIT_L(0); PG8_BAR; PG8_MMA(0, 0, At, B0); PG8_MMA(0, 1, At, B1); PG8_BAR; PG8_SCHED;
;             PG8_LDA(At, 1, 1); PG8_STAGE(PG8_SB(1, 0), b3, voffB); PG8_STAGE(PG8_SB(1, 1), b3 + hstepB, voffB); PG8_STAGE(PG8_SA(1, 0), a3, voffA);
;             PG8_WAIT_V(8); PG8_WAIT_L(0); PG8_BAR; PG8_MMA(1, 0, At, B0); PG8_MMA(1, 1, At, B1); PG8_BAR; PG8_SCHED;
	s_add_i32 s64, 0, 0x18000
	s_add_i32 s65, 0, 0x1c000
	v_add_u32_e32 v140, s64, v208
	v_add_u32_e32 v156, s65, v208
	ds_read_b128 v[128:131], v140
	ds_read_b128 v[132:135], v140 offset:1024
	ds_read_b128 v[136:139], v140 offset:2048
	ds_read_b128 v[140:143], v140 offset:3072
	ds_read_b128 v[144:147], v156
	ds_read_b128 v[148:151], v156 offset:1024
	ds_read_b128 v[152:155], v156 offset:2048
	ds_read_b128 v[156:159], v156 offset:3072
	s_add_u32 s42, s46, 0xb0000
	s_addc_u32 s43, s47, 0
	s_mov_b32 m0, s48
	v_lshl_add_u64 v[222:223], s[42:43], 0, v[176:177]
	ds_read_b128 v[160:163], v211 offset:32768
	ds_read_b128 v[164:167], v211 offset:33792
	ds_read_b128 v[168:171], v211 offset:34816
	ds_read_b128 v[172:175], v211 offset:35840
	ds_read_b128 v[192:195], v211 offset:36864
	ds_read_b128 v[196:199], v211 offset:37888
	ds_read_b128 v[200:203], v211 offset:38912
	ds_read_b128 v[204:207], v211 offset:39936
	global_load_lds_dwordx4 v[222:223], off
	v_lshl_add_u64 v[222:223], s[42:43], 0, v[180:181]
	s_mov_b32 m0, s49
	s_nop 0
	global_load_lds_dwordx4 v[222:223], off
	s_waitcnt vmcnt(8)
	s_waitcnt lgkmcnt(0)
	s_barrier
	s_setprio 1
	v_mfma_f32_16x16x32_bf16 v[124:127], v[128:131], v[160:163], v[124:127]
	v_mfma_f32_16x16x32_bf16 v[120:123], v[136:139], v[160:163], v[120:123]
	v_mfma_f32_16x16x32_bf16 v[108:111], v[128:131], v[168:171], v[108:111]
	v_mfma_f32_16x16x32_bf16 v[104:107], v[136:139], v[168:171], v[104:107]
	v_mfma_f32_16x16x32_bf16 v[92:95], v[128:131], v[192:195], v[92:95]
	v_mfma_f32_16x16x32_bf16 v[88:91], v[136:139], v[192:195], v[88:91]
	v_mfma_f32_16x16x32_bf16 v[76:79], v[128:131], v[200:203], v[76:79]
	v_mfma_f32_16x16x32_bf16 v[72:75], v[136:139], v[200:203], v[72:75]
	v_mfma_f32_16x16x32_bf16 v[124:127], v[132:135], v[164:167], v[124:127]
	v_mfma_f32_16x16x32_bf16 v[120:123], v[140:143], v[164:167], v[120:123]
	v_mfma_f32_16x16x32_bf16 v[108:111], v[132:135], v[172:175], v[108:111]
	v_mfma_f32_16x16x32_bf16 v[104:107], v[140:143], v[172:175], v[104:107]
	v_mfma_f32_16x16x32_bf16 v[92:95], v[132:135], v[196:199], v[92:95]
	v_mfma_f32_16x16x32_bf16 v[88:91], v[140:143], v[196:199], v[88:91]
	v_mfma_f32_16x16x32_bf16 v[76:79], v[132:135], v[204:207], v[76:79]
	v_mfma_f32_16x16x32_bf16 v[72:75], v[140:143], v[204:207], v[72:75]
	v_mfma_f32_16x16x32_bf16 v[116:119], v[144:147], v[160:163], v[116:119]
	v_mfma_f32_16x16x32_bf16 v[112:115], v[152:155], v[160:163], v[112:115]
	v_mfma_f32_16x16x32_bf16 v[100:103], v[144:147], v[168:171], v[100:103]
	v_mfma_f32_16x16x32_bf16 v[96:99], v[152:155], v[168:171], v[96:99]
	v_mfma_f32_16x16x32_bf16 v[84:87], v[144:147], v[192:195], v[84:87]
	v_mfma_f32_16x16x32_bf16 v[80:83], v[152:155], v[192:195], v[80:83]
	v_mfma_f32_16x16x32_bf16 v[68:71], v[144:147], v[200:203], v[68:71]
	v_mfma_f32_16x16x32_bf16 v[64:67], v[152:155], v[200:203], v[64:67]
	v_mfma_f32_16x16x32_bf16 v[116:119], v[148:151], v[164:167], v[116:119]
	v_mfma_f32_16x16x32_bf16 v[112:115], v[156:159], v[164:167], v[112:115]
	v_mfma_f32_16x16x32_bf16 v[100:103], v[148:151], v[172:175], v[100:103]
	v_mfma_f32_16x16x32_bf16 v[96:99], v[156:159], v[172:175], v[96:99]
	v_mfma_f32_16x16x32_bf16 v[84:87], v[148:151], v[196:199], v[84:87]
	v_mfma_f32_16x16x32_bf16 v[80:83], v[156:159], v[196:199], v[80:83]
	v_mfma_f32_16x16x32_bf16 v[68:71], v[148:151], v[204:207], v[68:71]
	v_mfma_f32_16x16x32_bf16 v[64:67], v[156:159], v[204:207], v[64:67]
	s_setprio 0
	s_barrier
	s_add_i32 s42, s64, s94
	v_lshl_add_u64 v[214:215], v[214:215], 0, s[34:35]
	s_mov_b32 m0, s42
	ds_read_b128 v[160:163], v211 offset:49152
	ds_read_b128 v[164:167], v211 offset:50176
	ds_read_b128 v[168:171], v211 offset:51200
	ds_read_b128 v[172:175], v211 offset:52224
	ds_read_b128 v[192:195], v211 offset:53248
	ds_read_b128 v[196:199], v211 offset:54272
	ds_read_b128 v[200:203], v211 offset:55296
	ds_read_b128 v[204:207], v211 offset:56320
	global_load_lds_dwordx4 v[214:215], off
	s_add_i32 m0, s42, 0x2000
	s_add_u32 s42, s44, 0xb0080
	v_lshl_add_u64 v[214:215], v[216:217], 0, s[34:35]
	s_addc_u32 s43, s45, 0
	s_add_i32 s44, s65, s94
	global_load_lds_dwordx4 v[214:215], off
	v_lshl_add_u64 v[214:215], s[42:43], 0, v[178:179]
	s_mov_b32 m0, s44
	s_nop 0
	global_load_lds_dwordx4 v[214:215], off
	v_lshl_add_u64 v[214:215], s[42:43], 0, v[182:183]
	s_add_i32 m0, s44, 0x2000
	s_nop 0
	global_load_lds_dwordx4 v[214:215], off
	v_lshl_add_u64 v[214:215], v[218:219], 0, s[34:35]
	s_mov_b32 m0, s51
	s_nop 0
	global_load_lds_dwordx4 v[214:215], off
	v_lshl_add_u64 v[214:215], v[220:221], 0, s[34:35]
	s_mov_b32 m0, s52
	s_nop 0
	global_load_lds_dwordx4 v[214:215], off
	s_waitcnt vmcnt(8)
	s_waitcnt lgkmcnt(0)
	s_barrier
	s_setprio 1
	v_mfma_f32_16x16x32_bf16 v[60:63], v[128:131], v[160:163], v[60:63]
	v_mfma_f32_16x16x32_bf16 v[56:59], v[136:139], v[160:163], v[56:59]
	v_mfma_f32_16x16x32_bf16 v[44:47], v[128:131], v[168:171], v[44:47]
	v_mfma_f32_16x16x32_bf16 v[40:43], v[136:139], v[168:171], v[40:43]
	v_mfma_f32_16x16x32_bf16 v[28:31], v[128:131], v[192:195], v[28:31]
	v_mfma_f32_16x16x32_bf16 v[24:27], v[136:139], v[192:195], v[24:27]
	v_mfma_f32_16x16x32_bf16 v[12:15], v[128:131], v[200:203], v[12:15]
	v_mfma_f32_16x16x32_bf16 v[8:11], v[136:139], v[200:203], v[8:11]
	v_mfma_f32_16x16x32_bf16 v[60:63], v[132:135], v[164:167], v[60:63]
	v_mfma_f32_16x16x32_bf16 v[56:59], v[140:143], v[164:167], v[56:59]
	v_mfma_f32_16x16x32_bf16 v[44:47], v[132:135], v[172:175], v[44:47]
	v_mfma_f32_16x16x32_bf16 v[40:43], v[140:143], v[172:175], v[40:43]
	v_mfma_f32_16x16x32_bf16 v[28:31], v[132:135], v[196:199], v[28:31]
	v_mfma_f32_16x16x32_bf16 v[24:27], v[140:143], v[196:199], v[24:27]
	v_mfma_f32_16x16x32_bf16 v[12:15], v[132:135], v[204:207], v[12:15]
	v_mfma_f32_16x16x32_bf16 v[8:11], v[140:143], v[204:207], v[8:11]
	v_mfma_f32_16x16x32_bf16 v[52:55], v[144:147], v[160:163], v[52:55]
	v_mfma_f32_16x16x32_bf16 v[48:51], v[152:155], v[160:163], v[48:51]
	v_mfma_f32_16x16x32_bf16 v[36:39], v[144:147], v[168:171], v[36:39]
	v_mfma_f32_16x16x32_bf16 v[32:35], v[152:155], v[168:171], v[32:35]
	v_mfma_f32_16x16x32_bf16 v[20:23], v[144:147], v[192:195], v[20:23]
	v_mfma_f32_16x16x32_bf16 v[16:19], v[152:155], v[192:195], v[16:19]
	v_mfma_f32_16x16x32_bf16 v[4:7], v[144:147], v[200:203], v[4:7]
	v_mfma_f32_16x16x32_bf16 v[0:3], v[152:155], v[200:203], v[0:3]
	v_mfma_f32_16x16x32_bf16 v[52:55], v[148:151], v[164:167], v[52:55]
	v_mfma_f32_16x16x32_bf16 v[48:51], v[156:159], v[164:167], v[48:51]
	v_mfma_f32_16x16x32_bf16 v[36:39], v[148:151], v[172:175], v[36:39]
	v_mfma_f32_16x16x32_bf16 v[32:35], v[156:159], v[172:175], v[32:35]
	v_mfma_f32_16x16x32_bf16 v[20:23], v[148:151], v[196:199], v[20:23]
	v_mfma_f32_16x16x32_bf16 v[16:19], v[156:159], v[196:199], v[16:19]
	v_mfma_f32_16x16x32_bf16 v[4:7], v[148:151], v[204:207], v[4:7]
	v_mfma_f32_16x16x32_bf16 v[0:3], v[156:159], v[204:207], v[0:3]
	s_setprio 0
	s_barrier
	s_add_i32 s63, s63, 2
	s_add_u32 s61, s61, 0x100
	s_addc_u32 s62, s62, 0
	s_cmp_gt_u32 s63, 41
	s_mov_b64 s[42:43], s[10:11]
	s_cbranch_scc0 .LBB0_312

; #define PG8_STAGE(bufoff, gbase, voff) do { _Pragma("unroll") for (int _i = 0; _i < 2; ++_i) \
;         __builtin_amdgcn_global_load_lds((const unsigned*)((const char*)(gbase) + (voff)[_i]), (LAS unsigned*)(lds + (bufoff) + ldsw + _i * 8192), 16, 0, 0); } while (0)
; #define PG8_LDA(dst, b, h) do { _Pragma("unroll") for (int m = 0; m < 4; ++m) _Pragma("unroll") for (int k = 0; k < 2; ++k) dst[m][k] = *(const LAS bf16x8*)(lds + PG8_SA(b, h) + aoff + m * 2048 + k * 1024); } while (0)
; #define PG8_LDB(dst, b, h) do { _Pragma("unroll") for (int n = 0; n < 2; ++n) _Pragma("unroll") for (int k = 0; k < 2; ++k) dst[n][k] = *(const LAS bf16x8*)(lds + PG8_SB(b, h) + boff + n * 2048 + k * 1024); } while (0)
; #define PG8_MMA(ai, bj, At, Bt) do { __builtin_amdgcn_s_setprio(1); _Pragma("unroll") for (int m = 0; m < 4; ++m) _Pragma("unroll") for (int n = 0; n < 2; ++n) _Pragma("unroll") for (int k = 0; k < 2; ++k) \
;         acc[ai][bj][m][n] = __builtin_amdgcn_mfma_f32_16x16x32_bf16(Bt[n][k], At[m][k], acc[ai][bj][m][n], 0, 0, 0); __builtin_amdgcn_s_setprio(0); } while (0)
; #define PG8_WAIT_V(n) asm volatile("s_waitcnt vmcnt(" #n ")" ::: "memory")
; #define PG8_BAR __builtin_amdgcn_s_barrier()
; template <class Epi>
; DI void gemm_phase(LAS unsigned char* lds, const int wid, const Gemm g, const Order& S, const Epi& E) {
;     ...
;         const bool has_next = S.next(ui + 1, nxt);
;         const char* nA = has_next ? (const char*)(g.A + (size_t)nxt.g * g.gsA + (size_t)nxt.pm * BM * g.lda) : cA;
;         const char* nB = has_next ? (const char*)(g.Bt + (size_t)nxt.g * g.gsB + (size_t)nxt.pn * BM * g.ldb) : cB;
;         for (int t = 0; t < nt; t += 2) {
;             const bool last = (t == nt - 2);
;             const char* a1 = cA + (size_t)(t + 1) * kstep;
;             const char* a2 = last ? nA : cA + (size_t)(t + 2) * kstep; const char* b2 = last ? nB : cB + (size_t)(t + 2) * kstep;
;             const char* a3 = a2 + kstep; const char* b3 = b2 + kstep;
;             PG8_LDB(B0, 0, 0); PG8_LDB(B1, 0, 1); PG8_SCHED; PG8_LDA(At, 0, 0); PG8_STAGE(PG8_SA(1, 1), a1 + hstepA, voffA);
;             PG8_WAIT_V(8); PG8_WAIT_L(0); PG8_BAR; PG8_MMA(0, 0, At, B0); PG8_MMA(0, 1, At, B1); PG8_BAR; PG8_SCHED;
;             PG8_LDA(At, 0, 1); PG8_STAGE(PG8_SB(0, 0), b2, voffB); PG8_STAGE(PG8_SB(0, 1), b2 + hstepB, voffB); PG8_STAGE(PG8_SA(0, 0), a2, voffA);
.LBB0_399:
	s_ashr_i32 s57, s56, 31
	s_lshl_b64 s[60:61], s[56:57], 19
	s_add_u32 s60, s73, s60
	s_addc_u32 s61, s74, s61
	s_and_b64 s[62:63], s[8:9], exec
	s_cselect_b32 s11, s61, s13
	s_cselect_b32 s16, s60, s12
	s_ashr_i32 s59, s58, 31
	s_lshl_b64 s[62:63], s[58:59], 19
	s_add_u32 s62, s75, s62
	s_addc_u32 s63, s76, s63
	s_and_b64 s[66:67], s[8:9], exec
	s_cselect_b32 s57, s63, s65
	s_cselect_b32 s59, s62, s64
	s_add_u32 s12, s12, 0x40080
	s_addc_u32 s13, s13, 0
	s_add_u32 s68, s64, 0x100
	v_mov_b32_e32 v0, 0
	s_addc_u32 s69, s65, 0
	s_mov_b32 s70, -2
	s_waitcnt lgkmcnt(0)
	ds_read_b128 v[146:149], v163
	ds_read_b128 v[150:153], v163 offset:1024
	ds_read_b128 v[154:157], v163 offset:2048
	ds_read_b128 v[158:161], v163 offset:3072
	ds_read_b128 v[168:171], v164
	ds_read_b128 v[172:175], v164 offset:1024
	ds_read_b128 v[176:179], v164 offset:2048
	ds_read_b128 v[180:183], v164 offset:3072
	s_add_u32 s64, s12, 0xfffc0080
	s_addc_u32 s65, s13, -1
	s_cmp_eq_u32 s70, 12
	s_cselect_b32 s67, s11, s65
	s_cselect_b32 s66, s16, s64
	s_cselect_b32 s65, s57, s69
	s_cselect_b32 s64, s59, s68
	v_lshl_add_u64 v[212:213], s[12:13], 0, v[138:139]
	s_add_i32 m0, s6, 0xc000
	ds_read_b128 v[184:187], v165
	ds_read_b128 v[188:191], v165 offset:1024
	ds_read_b128 v[192:195], v165 offset:2048
	ds_read_b128 v[196:199], v165 offset:3072
	ds_read_b128 v[200:203], v165 offset:4096
	ds_read_b128 v[204:207], v165 offset:5120
	ds_read_b128 v[208:211], v165 offset:6144
	ds_read_b128 v[216:219], v165 offset:7168
	global_load_lds_dwordx4 v[212:213], off
	v_lshl_add_u64 v[212:213], s[12:13], 0, v[140:141]
	s_add_i32 m0, s6, 0xe000
	s_nop 0
	global_load_lds_dwordx4 v[212:213], off
	s_waitcnt vmcnt(8)
	s_waitcnt lgkmcnt(0)
	s_barrier
	s_setprio 1
	v_mfma_f32_16x16x32_bf16 v[124:127], v[146:149], v[184:187], 0
	v_mfma_f32_16x16x32_bf16 v[120:123], v[154:157], v[184:187], 0
	v_mfma_f32_16x16x32_bf16 v[108:111], v[146:149], v[192:195], 0
	v_mfma_f32_16x16x32_bf16 v[104:107], v[154:157], v[192:195], 0
	v_mfma_f32_16x16x32_bf16 v[92:95], v[146:149], v[200:203], 0
	v_mfma_f32_16x16x32_bf16 v[88:91], v[154:157], v[200:203], 0
	v_mfma_f32_16x16x32_bf16 v[76:79], v[146:149], v[208:211], 0
	v_mfma_f32_16x16x32_bf16 v[72:75], v[154:157], v[208:211], 0
	v_mfma_f32_16x16x32_bf16 v[124:127], v[150:153], v[188:191], v[124:127]
	v_mfma_f32_16x16x32_bf16 v[120:123], v[158:161], v[188:191], v[120:123]
	v_mfma_f32_16x16x32_bf16 v[108:111], v[150:153], v[196:199], v[108:111]
	v_mfma_f32_16x16x32_bf16 v[104:107], v[158:161], v[196:199], v[104:107]
	v_mfma_f32_16x16x32_bf16 v[92:95], v[150:153], v[204:207], v[92:95]
	v_mfma_f32_16x16x32_bf16 v[88:91], v[158:161], v[204:207], v[88:91]
	v_mfma_f32_16x16x32_bf16 v[76:79], v[150:153], v[216:219], v[76:79]
	v_mfma_f32_16x16x32_bf16 v[72:75], v[158:161], v[216:219], v[72:75]
	v_mfma_f32_16x16x32_bf16 v[116:119], v[168:171], v[184:187], 0
	v_mfma_f32_16x16x32_bf16 v[112:115], v[176:179], v[184:187], 0
	v_mfma_f32_16x16x32_bf16 v[100:103], v[168:171], v[192:195], 0
	v_mfma_f32_16x16x32_bf16 v[96:99], v[176:179], v[192:195], 0
	v_mfma_f32_16x16x32_bf16 v[84:87], v[168:171], v[200:203], 0
	v_mfma_f32_16x16x32_bf16 v[80:83], v[176:179], v[200:203], 0
	v_mfma_f32_16x16x32_bf16 v[68:71], v[168:171], v[208:211], 0
	v_mfma_f32_16x16x32_bf16 v[64:67], v[176:179], v[208:211], 0
	v_mfma_f32_16x16x32_bf16 v[116:119], v[172:175], v[188:191], v[116:119]
	v_mfma_f32_16x16x32_bf16 v[112:115], v[180:183], v[188:191], v[112:115]
	v_mfma_f32_16x16x32_bf16 v[100:103], v[172:175], v[196:199], v[100:103]
	v_mfma_f32_16x16x32_bf16 v[96:99], v[180:183], v[196:199], v[96:99]
	v_mfma_f32_16x16x32_bf16 v[84:87], v[172:175], v[204:207], v[84:87]
	v_mfma_f32_16x16x32_bf16 v[80:83], v[180:183], v[204:207], v[80:83]
	v_mfma_f32_16x16x32_bf16 v[68:71], v[172:175], v[216:219], v[68:71]
	v_mfma_f32_16x16x32_bf16 v[64:67], v[180:183], v[216:219], v[64:67]
	s_setprio 0
	s_barrier
	s_add_i32 s71, s82, s94
	v_lshl_add_u64 v[212:213], s[64:65], 0, v[130:131]
	s_mov_b32 m0, s71
	ds_read_b128 v[184:187], v165 offset:16384
	ds_read_b128 v[188:191], v165 offset:17408
	ds_read_b128 v[192:195], v165 offset:18432
	ds_read_b128 v[196:199], v165 offset:19456
	ds_read_b128 v[200:203], v165 offset:20480
	ds_read_b128 v[204:207], v165 offset:21504
	ds_read_b128 v[208:211], v165 offset:22528
	ds_read_b128 v[216:219], v165 offset:23552
	global_load_lds_dwordx4 v[212:213], off
	s_add_i32 m0, s71, 0x2000
	s_add_u32 s86, s64, 0x40000
	v_lshl_add_u64 v[214:215], s[64:65], 0, v[134:135]
	s_addc_u32 s87, s65, 0
	s_add_i32 s71, s83, s94
	global_load_lds_dwordx4 v[214:215], off
	v_lshl_add_u64 v[220:221], s[86:87], 0, v[130:131]
	s_mov_b32 m0, s71
	v_lshl_add_u64 v[222:223], s[66:67], 0, v[132:133]
	global_load_lds_dwordx4 v[220:221], off
	v_lshl_add_u64 v[220:221], s[86:87], 0, v[134:135]
	s_add_i32 m0, s71, 0x2000
	s_nop 0
	global_load_lds_dwordx4 v[220:221], off
	v_lshl_add_u64 v[220:221], s[66:67], 0, v[128:129]
	s_mov_b32 m0, s6
	s_nop 0
	global_load_lds_dwordx4 v[220:221], off
	s_mov_b32 m0, s7
	s_nop 0
	global_load_lds_dwordx4 v[222:223], off
	s_waitcnt vmcnt(8)
	s_waitcnt lgkmcnt(0)
	s_barrier
; #define PG8_STAGE(bufoff, gbase, voff) do { _Pragma("unroll") for (int _i = 0; _i < 2; ++_i) \
;         __builtin_amdgcn_global_load_lds((const unsigned*)((const char*)(gbase) + (voff)[_i]), (LAS unsigned*)(lds + (bufoff) + ldsw + _i * 8192), 16, 0, 0); } while (0)
; #define PG8_LDA(dst, b, h) do { _Pragma("unroll") for (int m = 0; m < 4; ++m) _Pragma("unroll") for (int k = 0; k < 2; ++k) dst[m][k] = *(const LAS bf16x8*)(lds + PG8_SA(b, h) + aoff + m * 2048 + k * 1024); } while (0)
; #define PG8_LDB(dst, b, h) do { _Pragma("unroll") for (int n = 0; n < 2; ++n) _Pragma("unroll") for (int k = 0; k < 2; ++k) dst[n][k] = *(const LAS bf16x8*)(lds + PG8_SB(b, h) + boff + n * 2048 + k * 1024); } while (0)
; #define PG8_MMA(ai, bj, At, Bt) do { __builtin_amdgcn_s_setprio(1); _Pragma("unroll") for (int m = 0; m < 4; ++m) _Pragma("unroll") for (int n = 0; n < 2; ++n) _Pragma("unroll") for (int k = 0; k < 2; ++k) \
;         acc[ai][bj][m][n] = __builtin_amdgcn_mfma_f32_16x16x32_bf16(Bt[n][k], At[m][k], acc[ai][bj][m][n], 0, 0, 0); __builtin_amdgcn_s_setprio(0); } while (0)
; #define PG8_WAIT_V(n) asm volatile("s_waitcnt vmcnt(" #n ")" ::: "memory")
; #define PG8_WAIT_L(n) asm volatile("s_waitcnt lgkmcnt(" #n ")" ::: "memory")
; #define PG8_BAR __builtin_amdgcn_s_barrier()
; #define PG8_SCHED __builtin_amdgcn_sched_barrier(0)
; template <class Epi>
; DI void gemm_phase(LAS unsigned char* lds, const int wid, const Gemm g, const Order& S, const Epi& E) {
;     ...
;             PG8_WAIT_V(8); PG8_WAIT_L(0); PG8_BAR; PG8_MMA(1, 0, At, B0); PG8_MMA(1, 1, At, B1); PG8_BAR; PG8_SCHED;
;             PG8_LDB(B0, 1, 0); PG8_LDB(B1, 1, 1); PG8_SCHED; PG8_LDA(At, 1, 0); PG8_STAGE(PG8_SA(0, 1), a2 + hstepA, voffA);
;             PG8_WAIT_V(8); PG8_WAIT_L(0); PG8_BAR; PG8_MMA(0, 0, At, B0); PG8_MMA(0, 1, At, B1); PG8_BAR; PG8_SCHED;
	s_setprio 1
	v_mfma_f32_16x16x32_bf16 v[60:63], v[146:149], v[184:187], 0
	v_mfma_f32_16x16x32_bf16 v[56:59], v[154:157], v[184:187], 0
	v_mfma_f32_16x16x32_bf16 v[44:47], v[146:149], v[192:195], 0
	v_mfma_f32_16x16x32_bf16 v[40:43], v[154:157], v[192:195], 0
	v_mfma_f32_16x16x32_bf16 v[28:31], v[146:149], v[200:203], 0
	v_mfma_f32_16x16x32_bf16 v[24:27], v[154:157], v[200:203], 0
	v_mfma_f32_16x16x32_bf16 v[12:15], v[146:149], v[208:211], 0
	v_mfma_f32_16x16x32_bf16 v[8:11], v[154:157], v[208:211], 0
	v_mfma_f32_16x16x32_bf16 v[60:63], v[150:153], v[188:191], v[60:63]
	v_mfma_f32_16x16x32_bf16 v[56:59], v[158:161], v[188:191], v[56:59]
	v_mfma_f32_16x16x32_bf16 v[44:47], v[150:153], v[196:199], v[44:47]
	v_mfma_f32_16x16x32_bf16 v[40:43], v[158:161], v[196:199], v[40:43]
	v_mfma_f32_16x16x32_bf16 v[28:31], v[150:153], v[204:207], v[28:31]
	v_mfma_f32_16x16x32_bf16 v[24:27], v[158:161], v[204:207], v[24:27]
	v_mfma_f32_16x16x32_bf16 v[12:15], v[150:153], v[216:219], v[12:15]
	v_mfma_f32_16x16x32_bf16 v[8:11], v[158:161], v[216:219], v[8:11]
	v_mfma_f32_16x16x32_bf16 v[52:55], v[168:171], v[184:187], 0
	v_mfma_f32_16x16x32_bf16 v[48:51], v[176:179], v[184:187], 0
	v_mfma_f32_16x16x32_bf16 v[36:39], v[168:171], v[192:195], 0
	v_mfma_f32_16x16x32_bf16 v[32:35], v[176:179], v[192:195], 0
	v_mfma_f32_16x16x32_bf16 v[20:23], v[168:171], v[200:203], 0
	v_mfma_f32_16x16x32_bf16 v[16:19], v[176:179], v[200:203], 0
	v_mfma_f32_16x16x32_bf16 v[4:7], v[168:171], v[208:211], 0
	v_mfma_f32_16x16x32_bf16 v[0:3], v[176:179], v[208:211], 0
	v_mfma_f32_16x16x32_bf16 v[52:55], v[172:175], v[188:191], v[52:55]
	v_mfma_f32_16x16x32_bf16 v[48:51], v[180:183], v[188:191], v[48:51]
	v_mfma_f32_16x16x32_bf16 v[36:39], v[172:175], v[196:199], v[36:39]
	v_mfma_f32_16x16x32_bf16 v[32:35], v[180:183], v[196:199], v[32:35]
	v_mfma_f32_16x16x32_bf16 v[20:23], v[172:175], v[204:207], v[20:23]
	v_mfma_f32_16x16x32_bf16 v[16:19], v[180:183], v[204:207], v[16:19]
	v_mfma_f32_16x16x32_bf16 v[4:7], v[172:175], v[216:219], v[4:7]
	v_mfma_f32_16x16x32_bf16 v[0:3], v[180:183], v[216:219], v[0:3]
	s_setprio 0
	s_barrier
	s_add_i32 s71, 0, 0x18000
	v_add_u32_e32 v136, s71, v162
	s_add_i32 s86, 0, 0x1c000
	ds_read_b128 v[146:149], v136
	ds_read_b128 v[150:153], v136 offset:1024
	ds_read_b128 v[154:157], v136 offset:2048
	ds_read_b128 v[158:161], v136 offset:3072
	v_add_u32_e32 v136, s86, v162
	ds_read_b128 v[168:171], v136
	ds_read_b128 v[172:175], v136 offset:1024
	ds_read_b128 v[176:179], v136 offset:2048
	ds_read_b128 v[180:183], v136 offset:3072
	s_add_u32 s66, s66, 0x40000
	s_addc_u32 s67, s67, 0
	s_mov_b32 m0, s21
	v_lshl_add_u64 v[224:225], s[66:67], 0, v[128:129]
	ds_read_b128 v[184:187], v165 offset:32768
	ds_read_b128 v[188:191], v165 offset:33792
	ds_read_b128 v[192:195], v165 offset:34816
	ds_read_b128 v[196:199], v165 offset:35840
	ds_read_b128 v[200:203], v165 offset:36864
	ds_read_b128 v[204:207], v165 offset:37888
	ds_read_b128 v[208:211], v165 offset:38912
	ds_read_b128 v[216:219], v165 offset:39936
	global_load_lds_dwordx4 v[224:225], off
	v_lshl_add_u64 v[224:225], s[66:67], 0, v[132:133]
	s_mov_b32 m0, s26
	s_nop 0
	global_load_lds_dwordx4 v[224:225], off
	s_waitcnt vmcnt(8)
	s_waitcnt lgkmcnt(0)
	s_barrier
	s_setprio 1
	v_mfma_f32_16x16x32_bf16 v[124:127], v[146:149], v[184:187], v[124:127]
	v_mfma_f32_16x16x32_bf16 v[120:123], v[154:157], v[184:187], v[120:123]
	v_mfma_f32_16x16x32_bf16 v[108:111], v[146:149], v[192:195], v[108:111]
	v_mfma_f32_16x16x32_bf16 v[104:107], v[154:157], v[192:195], v[104:107]
	v_mfma_f32_16x16x32_bf16 v[92:95], v[146:149], v[200:203], v[92:95]
	v_mfma_f32_16x16x32_bf16 v[88:91], v[154:157], v[200:203], v[88:91]
	v_mfma_f32_16x16x32_bf16 v[76:79], v[146:149], v[208:211], v[76:79]
	v_mfma_f32_16x16x32_bf16 v[72:75], v[154:157], v[208:211], v[72:75]
	v_mfma_f32_16x16x32_bf16 v[124:127], v[150:153], v[188:191], v[124:127]
	v_mfma_f32_16x16x32_bf16 v[120:123], v[158:161], v[188:191], v[120:123]
	v_mfma_f32_16x16x32_bf16 v[108:111], v[150:153], v[196:199], v[108:111]
	v_mfma_f32_16x16x32_bf16 v[104:107], v[158:161], v[196:199], v[104:107]
	v_mfma_f32_16x16x32_bf16 v[92:95], v[150:153], v[204:207], v[92:95]
	v_mfma_f32_16x16x32_bf16 v[88:91], v[158:161], v[204:207], v[88:91]
	v_mfma_f32_16x16x32_bf16 v[76:79], v[150:153], v[216:219], v[76:79]
	v_mfma_f32_16x16x32_bf16 v[72:75], v[158:161], v[216:219], v[72:75]
	v_mfma_f32_16x16x32_bf16 v[116:119], v[168:171], v[184:187], v[116:119]
	v_mfma_f32_16x16x32_bf16 v[112:115], v[176:179], v[184:187], v[112:115]
	v_mfma_f32_16x16x32_bf16 v[100:103], v[168:171], v[192:195], v[100:103]
	v_mfma_f32_16x16x32_bf16 v[96:99], v[176:179], v[192:195], v[96:99]
	v_mfma_f32_16x16x32_bf16 v[84:87], v[168:171], v[200:203], v[84:87]
	v_mfma_f32_16x16x32_bf16 v[80:83], v[176:179], v[200:203], v[80:83]
	v_mfma_f32_16x16x32_bf16 v[68:71], v[168:171], v[208:211], v[68:71]
	v_mfma_f32_16x16x32_bf16 v[64:67], v[176:179], v[208:211], v[64:67]
	v_mfma_f32_16x16x32_bf16 v[116:119], v[172:175], v[188:191], v[116:119]
	v_mfma_f32_16x16x32_bf16 v[112:115], v[180:183], v[188:191], v[112:115]
	v_mfma_f32_16x16x32_bf16 v[100:103], v[172:175], v[196:199], v[100:103]
	v_mfma_f32_16x16x32_bf16 v[96:99], v[180:183], v[196:199], v[96:99]
	v_mfma_f32_16x16x32_bf16 v[84:87], v[172:175], v[204:207], v[84:87]
	v_mfma_f32_16x16x32_bf16 v[80:83], v[180:183], v[204:207], v[80:83]
	v_mfma_f32_16x16x32_bf16 v[68:71], v[172:175], v[216:219], v[68:71]
	v_mfma_f32_16x16x32_bf16 v[64:67], v[180:183], v[216:219], v[64:67]
	s_setprio 0
	s_barrier
; #define PG8_STAGE(bufoff, gbase, voff) do { _Pragma("unroll") for (int _i = 0; _i < 2; ++_i) \
;         __builtin_amdgcn_global_load_lds((const unsigned*)((const char*)(gbase) + (voff)[_i]), (LAS unsigned*)(lds + (bufoff) + ldsw + _i * 8192), 16, 0, 0); } while (0)
; #define PG8_LDA(dst, b, h) do { _Pragma("unroll") for (int m = 0; m < 4; ++m) _Pragma("unroll") for (int k = 0; k < 2; ++k) dst[m][k] = *(const LAS bf16x8*)(lds + PG8_SA(b, h) + aoff + m * 2048 + k * 1024); } while (0)
; #define PG8_LDB(dst, b, h) do { _Pragma("unroll") for (int n = 0; n < 2; ++n) _Pragma("unroll") for (int k = 0; k < 2; ++k) dst[n][k] = *(const LAS bf16x8*)(lds + PG8_SB(b, h) + boff + n * 2048 + k * 1024); } while (0)
; #define PG8_WAIT_V(n) asm volatile("s_waitcnt vmcnt(" #n ")" ::: "memory")
; #define PG8_WAIT_L(n) asm volatile("s_waitcnt lgkmcnt(" #n ")" ::: "memory")
; template <class Epi>
; DI void gemm_phase(LAS unsigned char* lds, const int wid, const Gemm g, const Order& S, const Epi& E) {
;     ...
;         for (int t = 0; t < nt; t += 2) {
;             const bool last = (t == nt - 2);
;             const char* a1 = cA + (size_t)(t + 1) * kstep;
;             const char* a2 = last ? nA : cA + (size_t)(t + 2) * kstep; const char* b2 = last ? nB : cB + (size_t)(t + 2) * kstep;
;             const char* a3 = a2 + kstep; const char* b3 = b2 + kstep;
;             PG8_LDB(B0, 0, 0); PG8_LDB(B1, 0, 1); PG8_SCHED; PG8_LDA(At, 0, 0); PG8_STAGE(PG8_SA(1, 1), a1 + hstepA, voffA);
;             PG8_WAIT_V(8); PG8_WAIT_L(0); PG8_BAR; PG8_MMA(0, 0, At, B0); PG8_MMA(0, 1, At, B1); PG8_BAR; PG8_SCHED;
;             PG8_LDA(At, 0, 1); PG8_STAGE(PG8_SB(0, 0), b2, voffB); PG8_STAGE(PG8_SB(0, 1), b2 + hstepB, voffB); PG8_STAGE(PG8_SA(0, 0), a2, voffA);
;             PG8_WAIT_V(8); PG8_WAIT_L(0); PG8_BAR; PG8_MMA(1, 0, At, B0); PG8_MMA(1, 1, At, B1); PG8_BAR; PG8_SCHED;
;             PG8_LDB(B0, 1, 0); PG8_LDB(B1, 1, 1); PG8_SCHED; PG8_LDA(At, 1, 0); PG8_STAGE(PG8_SA(0, 1), a2 + hstepA, voffA);
;             PG8_WAIT_V(8); PG8_WAIT_L(0); PG8_BAR; PG8_MMA(0, 0, At, B0); PG8_MMA(0, 1, At, B1); PG8_BAR; PG8_SCHED;
;             PG8_LDA(At, 1, 1); PG8_STAGE(PG8_SB(1, 0), b3, voffB); PG8_STAGE(PG8_SB(1, 1), b3 + hstepB, voffB); PG8_STAGE(PG8_SA(1, 0), a3, voffA);
;             PG8_WAIT_V(8); PG8_WAIT_L(0); PG8_BAR; PG8_MMA(1, 0, At, B0); PG8_MMA(1, 1, At, B1); PG8_BAR; PG8_SCHED;
	s_add_i32 s66, s71, s94
	v_lshl_add_u64 v[212:213], v[212:213], 0, s[34:35]
	s_mov_b32 m0, s66
	ds_read_b128 v[184:187], v165 offset:49152
	ds_read_b128 v[188:191], v165 offset:50176
	ds_read_b128 v[192:195], v165 offset:51200
	ds_read_b128 v[196:199], v165 offset:52224
	ds_read_b128 v[200:203], v165 offset:53248
	ds_read_b128 v[204:207], v165 offset:54272
	ds_read_b128 v[208:211], v165 offset:55296
	ds_read_b128 v[216:219], v165 offset:56320
	global_load_lds_dwordx4 v[212:213], off
	s_add_i32 m0, s66, 0x2000
	s_add_u32 s64, s64, 0x40080
	v_lshl_add_u64 v[212:213], v[214:215], 0, s[34:35]
	s_addc_u32 s65, s65, 0
	s_add_i32 s66, s86, s94
	global_load_lds_dwordx4 v[212:213], off
	v_lshl_add_u64 v[212:213], s[64:65], 0, v[130:131]
	s_mov_b32 m0, s66
	s_nop 0
	global_load_lds_dwordx4 v[212:213], off
	v_lshl_add_u64 v[212:213], s[64:65], 0, v[134:135]
	s_add_i32 m0, s66, 0x2000
	s_nop 0
	global_load_lds_dwordx4 v[212:213], off
	v_lshl_add_u64 v[212:213], v[220:221], 0, s[34:35]
	s_mov_b32 m0, s27
	s_nop 0
	global_load_lds_dwordx4 v[212:213], off
	v_lshl_add_u64 v[212:213], v[222:223], 0, s[34:35]
	s_mov_b32 m0, s55
	s_nop 0
	global_load_lds_dwordx4 v[212:213], off
	s_waitcnt vmcnt(8)
	s_waitcnt lgkmcnt(0)
	s_barrier
	s_setprio 1
	v_mfma_f32_16x16x32_bf16 v[60:63], v[146:149], v[184:187], v[60:63]
	v_mfma_f32_16x16x32_bf16 v[56:59], v[154:157], v[184:187], v[56:59]
	v_mfma_f32_16x16x32_bf16 v[44:47], v[146:149], v[192:195], v[44:47]
	v_mfma_f32_16x16x32_bf16 v[40:43], v[154:157], v[192:195], v[40:43]
	v_mfma_f32_16x16x32_bf16 v[28:31], v[146:149], v[200:203], v[28:31]
	v_mfma_f32_16x16x32_bf16 v[24:27], v[154:157], v[200:203], v[24:27]
	v_mfma_f32_16x16x32_bf16 v[12:15], v[146:149], v[208:211], v[12:15]
	v_mfma_f32_16x16x32_bf16 v[8:11], v[154:157], v[208:211], v[8:11]
	v_mfma_f32_16x16x32_bf16 v[60:63], v[150:153], v[188:191], v[60:63]
	v_mfma_f32_16x16x32_bf16 v[56:59], v[158:161], v[188:191], v[56:59]
	v_mfma_f32_16x16x32_bf16 v[44:47], v[150:153], v[196:199], v[44:47]
	v_mfma_f32_16x16x32_bf16 v[40:43], v[158:161], v[196:199], v[40:43]
	v_mfma_f32_16x16x32_bf16 v[28:31], v[150:153], v[204:207], v[28:31]
	v_mfma_f32_16x16x32_bf16 v[24:27], v[158:161], v[204:207], v[24:27]
	v_mfma_f32_16x16x32_bf16 v[12:15], v[150:153], v[216:219], v[12:15]
	v_mfma_f32_16x16x32_bf16 v[8:11], v[158:161], v[216:219], v[8:11]
	v_mfma_f32_16x16x32_bf16 v[52:55], v[168:171], v[184:187], v[52:55]
	v_mfma_f32_16x16x32_bf16 v[48:51], v[176:179], v[184:187], v[48:51]
	v_mfma_f32_16x16x32_bf16 v[36:39], v[168:171], v[192:195], v[36:39]
	v_mfma_f32_16x16x32_bf16 v[32:35], v[176:179], v[192:195], v[32:35]
	v_mfma_f32_16x16x32_bf16 v[20:23], v[168:171], v[200:203], v[20:23]
	v_mfma_f32_16x16x32_bf16 v[16:19], v[176:179], v[200:203], v[16:19]
	v_mfma_f32_16x16x32_bf16 v[4:7], v[168:171], v[208:211], v[4:7]
	v_mfma_f32_16x16x32_bf16 v[0:3], v[176:179], v[208:211], v[0:3]
	v_mfma_f32_16x16x32_bf16 v[52:55], v[172:175], v[188:191], v[52:55]
	v_mfma_f32_16x16x32_bf16 v[48:51], v[180:183], v[188:191], v[48:51]
	v_mfma_f32_16x16x32_bf16 v[36:39], v[172:175], v[196:199], v[36:39]
	v_mfma_f32_16x16x32_bf16 v[32:35], v[180:183], v[196:199], v[32:35]
	v_mfma_f32_16x16x32_bf16 v[20:23], v[172:175], v[204:207], v[20:23]
	v_mfma_f32_16x16x32_bf16 v[16:19], v[180:183], v[204:207], v[16:19]
	v_mfma_f32_16x16x32_bf16 v[4:7], v[172:175], v[216:219], v[4:7]
	v_mfma_f32_16x16x32_bf16 v[0:3], v[180:183], v[216:219], v[0:3]
	s_setprio 0
	s_barrier
	s_add_i32 s70, s70, 2
	s_add_u32 s12, s12, 0x100
	s_addc_u32 s13, s13, 0
	s_add_u32 s68, s68, 0x100
	s_addc_u32 s69, s69, 0
	s_cmp_gt_u32 s70, 13
	s_cbranch_scc0 .LBB0_400
	s_branch .Lpeel_exit_2
.LBB0_400:
	ds_read_b128 v[146:149], v163
	ds_read_b128 v[150:153], v163 offset:1024
	ds_read_b128 v[154:157], v163 offset:2048
	ds_read_b128 v[158:161], v163 offset:3072
	ds_read_b128 v[168:171], v164
	ds_read_b128 v[172:175], v164 offset:1024
	ds_read_b128 v[176:179], v164 offset:2048
	ds_read_b128 v[180:183], v164 offset:3072
	s_add_u32 s64, s12, 0xfffc0080
	s_addc_u32 s65, s13, -1
	s_cmp_eq_u32 s70, 12
	s_cselect_b32 s67, s11, s65
	s_cselect_b32 s66, s16, s64
	s_cselect_b32 s65, s57, s69
	s_cselect_b32 s64, s59, s68
	v_lshl_add_u64 v[212:213], s[12:13], 0, v[138:139]
	s_add_i32 m0, s6, 0xc000
	ds_read_b128 v[184:187], v165
	ds_read_b128 v[188:191], v165 offset:1024
	ds_read_b128 v[192:195], v165 offset:2048
	ds_read_b128 v[196:199], v165 offset:3072
	ds_read_b128 v[200:203], v165 offset:4096
	ds_read_b128 v[204:207], v165 offset:5120
	ds_read_b128 v[208:211], v165 offset:6144
	ds_read_b128 v[216:219], v165 offset:7168
	global_load_lds_dwordx4 v[212:213], off
	v_lshl_add_u64 v[212:213], s[12:13], 0, v[140:141]
	s_add_i32 m0, s6, 0xe000
	s_nop 0
	global_load_lds_dwordx4 v[212:213], off
	s_waitcnt vmcnt(8)
	s_waitcnt lgkmcnt(0)
	s_barrier
; #define PG8_STAGE(bufoff, gbase, voff) do { _Pragma("unroll") for (int _i = 0; _i < 2; ++_i) \
;         __builtin_amdgcn_global_load_lds((const unsigned*)((const char*)(gbase) + (voff)[_i]), (LAS unsigned*)(lds + (bufoff) + ldsw + _i * 8192), 16, 0, 0); } while (0)
; #define PG8_LDA(dst, b, h) do { _Pragma("unroll") for (int m = 0; m < 4; ++m) _Pragma("unroll") for (int k = 0; k < 2; ++k) dst[m][k] = *(const LAS bf16x8*)(lds + PG8_SA(b, h) + aoff + m * 2048 + k * 1024); } while (0)
; #define PG8_MMA(ai, bj, At, Bt) do { __builtin_amdgcn_s_setprio(1); _Pragma("unroll") for (int m = 0; m < 4; ++m) _Pragma("unroll") for (int n = 0; n < 2; ++n) _Pragma("unroll") for (int k = 0; k < 2; ++k) \
;         acc[ai][bj][m][n] = __builtin_amdgcn_mfma_f32_16x16x32_bf16(Bt[n][k], At[m][k], acc[ai][bj][m][n], 0, 0, 0); __builtin_amdgcn_s_setprio(0); } while (0)
; #define PG8_WAIT_V(n) asm volatile("s_waitcnt vmcnt(" #n ")" ::: "memory")
; #define PG8_WAIT_L(n) asm volatile("s_waitcnt lgkmcnt(" #n ")" ::: "memory")
; #define PG8_BAR __builtin_amdgcn_s_barrier()
; #define PG8_SCHED __builtin_amdgcn_sched_barrier(0)
; template <class Epi>
; DI void gemm_phase(LAS unsigned char* lds, const int wid, const Gemm g, const Order& S, const Epi& E) {
;     ...
;             PG8_WAIT_V(8); PG8_WAIT_L(0); PG8_BAR; PG8_MMA(0, 0, At, B0); PG8_MMA(0, 1, At, B1); PG8_BAR; PG8_SCHED;
;             PG8_LDA(At, 0, 1); PG8_STAGE(PG8_SB(0, 0), b2, voffB); PG8_STAGE(PG8_SB(0, 1), b2 + hstepB, voffB); PG8_STAGE(PG8_SA(0, 0), a2, voffA);
;             PG8_WAIT_V(8); PG8_WAIT_L(0); PG8_BAR; PG8_MMA(1, 0, At, B0); PG8_MMA(1, 1, At, B1); PG8_BAR; PG8_SCHED;
	s_setprio 1
	v_mfma_f32_16x16x32_bf16 v[124:127], v[146:149], v[184:187], v[124:127]
	v_mfma_f32_16x16x32_bf16 v[120:123], v[154:157], v[184:187], v[120:123]
	v_mfma_f32_16x16x32_bf16 v[108:111], v[146:149], v[192:195], v[108:111]
	v_mfma_f32_16x16x32_bf16 v[104:107], v[154:157], v[192:195], v[104:107]
	v_mfma_f32_16x16x32_bf16 v[92:95], v[146:149], v[200:203], v[92:95]
	v_mfma_f32_16x16x32_bf16 v[88:91], v[154:157], v[200:203], v[88:91]
	v_mfma_f32_16x16x32_bf16 v[76:79], v[146:149], v[208:211], v[76:79]
	v_mfma_f32_16x16x32_bf16 v[72:75], v[154:157], v[208:211], v[72:75]
	v_mfma_f32_16x16x32_bf16 v[124:127], v[150:153], v[188:191], v[124:127]
	v_mfma_f32_16x16x32_bf16 v[120:123], v[158:161], v[188:191], v[120:123]
	v_mfma_f32_16x16x32_bf16 v[108:111], v[150:153], v[196:199], v[108:111]
	v_mfma_f32_16x16x32_bf16 v[104:107], v[158:161], v[196:199], v[104:107]
	v_mfma_f32_16x16x32_bf16 v[92:95], v[150:153], v[204:207], v[92:95]
	v_mfma_f32_16x16x32_bf16 v[88:91], v[158:161], v[204:207], v[88:91]
	v_mfma_f32_16x16x32_bf16 v[76:79], v[150:153], v[216:219], v[76:79]
	v_mfma_f32_16x16x32_bf16 v[72:75], v[158:161], v[216:219], v[72:75]
	v_mfma_f32_16x16x32_bf16 v[116:119], v[168:171], v[184:187], v[116:119]
	v_mfma_f32_16x16x32_bf16 v[112:115], v[176:179], v[184:187], v[112:115]
	v_mfma_f32_16x16x32_bf16 v[100:103], v[168:171], v[192:195], v[100:103]
	v_mfma_f32_16x16x32_bf16 v[96:99], v[176:179], v[192:195], v[96:99]
	v_mfma_f32_16x16x32_bf16 v[84:87], v[168:171], v[200:203], v[84:87]
	v_mfma_f32_16x16x32_bf16 v[80:83], v[176:179], v[200:203], v[80:83]
	v_mfma_f32_16x16x32_bf16 v[68:71], v[168:171], v[208:211], v[68:71]
	v_mfma_f32_16x16x32_bf16 v[64:67], v[176:179], v[208:211], v[64:67]
	v_mfma_f32_16x16x32_bf16 v[116:119], v[172:175], v[188:191], v[116:119]
	v_mfma_f32_16x16x32_bf16 v[112:115], v[180:183], v[188:191], v[112:115]
	v_mfma_f32_16x16x32_bf16 v[100:103], v[172:175], v[196:199], v[100:103]
	v_mfma_f32_16x16x32_bf16 v[96:99], v[180:183], v[196:199], v[96:99]
	v_mfma_f32_16x16x32_bf16 v[84:87], v[172:175], v[204:207], v[84:87]
	v_mfma_f32_16x16x32_bf16 v[80:83], v[180:183], v[204:207], v[80:83]
	v_mfma_f32_16x16x32_bf16 v[68:71], v[172:175], v[216:219], v[68:71]
	v_mfma_f32_16x16x32_bf16 v[64:67], v[180:183], v[216:219], v[64:67]
	s_setprio 0
	s_barrier
	s_add_i32 s71, s82, s94
	v_lshl_add_u64 v[212:213], s[64:65], 0, v[130:131]
	s_mov_b32 m0, s71
	ds_read_b128 v[184:187], v165 offset:16384
	ds_read_b128 v[188:191], v165 offset:17408
	ds_read_b128 v[192:195], v165 offset:18432
	ds_read_b128 v[196:199], v165 offset:19456
	ds_read_b128 v[200:203], v165 offset:20480
	ds_read_b128 v[204:207], v165 offset:21504
	ds_read_b128 v[208:211], v165 offset:22528
	ds_read_b128 v[216:219], v165 offset:23552
	global_load_lds_dwordx4 v[212:213], off
	s_add_i32 m0, s71, 0x2000
	s_add_u32 s86, s64, 0x40000
	v_lshl_add_u64 v[214:215], s[64:65], 0, v[134:135]
	s_addc_u32 s87, s65, 0
	s_add_i32 s71, s83, s94
	global_load_lds_dwordx4 v[214:215], off
	v_lshl_add_u64 v[220:221], s[86:87], 0, v[130:131]
	s_mov_b32 m0, s71
	v_lshl_add_u64 v[222:223], s[66:67], 0, v[132:133]
	global_load_lds_dwordx4 v[220:221], off
	v_lshl_add_u64 v[220:221], s[86:87], 0, v[134:135]
	s_add_i32 m0, s71, 0x2000
	s_nop 0
	global_load_lds_dwordx4 v[220:221], off
	v_lshl_add_u64 v[220:221], s[66:67], 0, v[128:129]
	s_mov_b32 m0, s6
	s_nop 0
	global_load_lds_dwordx4 v[220:221], off
	s_mov_b32 m0, s7
	s_nop 0
	global_load_lds_dwordx4 v[222:223], off
	s_waitcnt vmcnt(8)
	s_waitcnt lgkmcnt(0)
	s_barrier
	s_setprio 1
	v_mfma_f32_16x16x32_bf16 v[60:63], v[146:149], v[184:187], v[60:63]
	v_mfma_f32_16x16x32_bf16 v[56:59], v[154:157], v[184:187], v[56:59]
	v_mfma_f32_16x16x32_bf16 v[44:47], v[146:149], v[192:195], v[44:47]
	v_mfma_f32_16x16x32_bf16 v[40:43], v[154:157], v[192:195], v[40:43]
	v_mfma_f32_16x16x32_bf16 v[28:31], v[146:149], v[200:203], v[28:31]
	v_mfma_f32_16x16x32_bf16 v[24:27], v[154:157], v[200:203], v[24:27]
	v_mfma_f32_16x16x32_bf16 v[12:15], v[146:149], v[208:211], v[12:15]
	v_mfma_f32_16x16x32_bf16 v[8:11], v[154:157], v[208:211], v[8:11]
	v_mfma_f32_16x16x32_bf16 v[60:63], v[150:153], v[188:191], v[60:63]
	v_mfma_f32_16x16x32_bf16 v[56:59], v[158:161], v[188:191], v[56:59]
	v_mfma_f32_16x16x32_bf16 v[44:47], v[150:153], v[196:199], v[44:47]
	v_mfma_f32_16x16x32_bf16 v[40:43], v[158:161], v[196:199], v[40:43]
	v_mfma_f32_16x16x32_bf16 v[28:31], v[150:153], v[204:207], v[28:31]
	v_mfma_f32_16x16x32_bf16 v[24:27], v[158:161], v[204:207], v[24:27]
	v_mfma_f32_16x16x32_bf16 v[12:15], v[150:153], v[216:219], v[12:15]
	v_mfma_f32_16x16x32_bf16 v[8:11], v[158:161], v[216:219], v[8:11]
	v_mfma_f32_16x16x32_bf16 v[52:55], v[168:171], v[184:187], v[52:55]
	v_mfma_f32_16x16x32_bf16 v[48:51], v[176:179], v[184:187], v[48:51]
	v_mfma_f32_16x16x32_bf16 v[36:39], v[168:171], v[192:195], v[36:39]
	v_mfma_f32_16x16x32_bf16 v[32:35], v[176:179], v[192:195], v[32:35]
	v_mfma_f32_16x16x32_bf16 v[20:23], v[168:171], v[200:203], v[20:23]
	v_mfma_f32_16x16x32_bf16 v[16:19], v[176:179], v[200:203], v[16:19]
	v_mfma_f32_16x16x32_bf16 v[4:7], v[168:171], v[208:211], v[4:7]
	v_mfma_f32_16x16x32_bf16 v[0:3], v[176:179], v[208:211], v[0:3]
	v_mfma_f32_16x16x32_bf16 v[52:55], v[172:175], v[188:191], v[52:55]
	v_mfma_f32_16x16x32_bf16 v[48:51], v[180:183], v[188:191], v[48:51]
	v_mfma_f32_16x16x32_bf16 v[36:39], v[172:175], v[196:199], v[36:39]
	v_mfma_f32_16x16x32_bf16 v[32:35], v[180:183], v[196:199], v[32:35]
	v_mfma_f32_16x16x32_bf16 v[20:23], v[172:175], v[204:207], v[20:23]
	v_mfma_f32_16x16x32_bf16 v[16:19], v[180:183], v[204:207], v[16:19]
	v_mfma_f32_16x16x32_bf16 v[4:7], v[172:175], v[216:219], v[4:7]
	v_mfma_f32_16x16x32_bf16 v[0:3], v[180:183], v[216:219], v[0:3]
	s_setprio 0
	s_barrier
; #define PG8_STAGE(bufoff, gbase, voff) do { _Pragma("unroll") for (int _i = 0; _i < 2; ++_i) \
;         __builtin_amdgcn_global_load_lds((const unsigned*)((const char*)(gbase) + (voff)[_i]), (LAS unsigned*)(lds + (bufoff) + ldsw + _i * 8192), 16, 0, 0); } while (0)
; #define PG8_LDA(dst, b, h) do { _Pragma("unroll") for (int m = 0; m < 4; ++m) _Pragma("unroll") for (int k = 0; k < 2; ++k) dst[m][k] = *(const LAS bf16x8*)(lds + PG8_SA(b, h) + aoff + m * 2048 + k * 1024); } while (0)
; #define PG8_LDB(dst, b, h) do { _Pragma("unroll") for (int n = 0; n < 2; ++n) _Pragma("unroll") for (int k = 0; k < 2; ++k) dst[n][k] = *(const LAS bf16x8*)(lds + PG8_SB(b, h) + boff + n * 2048 + k * 1024); } while (0)
; #define PG8_MMA(ai, bj, At, Bt) do { __builtin_amdgcn_s_setprio(1); _Pragma("unroll") for (int m = 0; m < 4; ++m) _Pragma("unroll") for (int n = 0; n < 2; ++n) _Pragma("unroll") for (int k = 0; k < 2; ++k) \
;         acc[ai][bj][m][n] = __builtin_amdgcn_mfma_f32_16x16x32_bf16(Bt[n][k], At[m][k], acc[ai][bj][m][n], 0, 0, 0); __builtin_amdgcn_s_setprio(0); } while (0)
; #define PG8_WAIT_V(n) asm volatile("s_waitcnt vmcnt(" #n ")" ::: "memory")
; #define PG8_WAIT_L(n) asm volatile("s_waitcnt lgkmcnt(" #n ")" ::: "memory")
; #define PG8_BAR __builtin_amdgcn_s_barrier()
; #define PG8_SCHED __builtin_amdgcn_sched_barrier(0)
; template <class Epi>
; DI void gemm_phase(LAS unsigned char* lds, const int wid, const Gemm g, const Order& S, const Epi& E) {
;     ...
;             PG8_LDB(B0, 1, 0); PG8_LDB(B1, 1, 1); PG8_SCHED; PG8_LDA(At, 1, 0); PG8_STAGE(PG8_SA(0, 1), a2 + hstepA, voffA);
;             PG8_WAIT_V(8); PG8_WAIT_L(0); PG8_BAR; PG8_MMA(0, 0, At, B0); PG8_MMA(0, 1, At, B1); PG8_BAR; PG8_SCHED;
	s_add_i32 s71, 0, 0x18000
	v_add_u32_e32 v136, s71, v162
	s_add_i32 s86, 0, 0x1c000
	ds_read_b128 v[146:149], v136
	ds_read_b128 v[150:153], v136 offset:1024
	ds_read_b128 v[154:157], v136 offset:2048
	ds_read_b128 v[158:161], v136 offset:3072
	v_add_u32_e32 v136, s86, v162
	ds_read_b128 v[168:171], v136
	ds_read_b128 v[172:175], v136 offset:1024
	ds_read_b128 v[176:179], v136 offset:2048
	ds_read_b128 v[180:183], v136 offset:3072
	s_add_u32 s66, s66, 0x40000
	s_addc_u32 s67, s67, 0
	s_mov_b32 m0, s21
	v_lshl_add_u64 v[224:225], s[66:67], 0, v[128:129]
	ds_read_b128 v[184:187], v165 offset:32768
	ds_read_b128 v[188:191], v165 offset:33792
	ds_read_b128 v[192:195], v165 offset:34816
	ds_read_b128 v[196:199], v165 offset:35840
	ds_read_b128 v[200:203], v165 offset:36864
	ds_read_b128 v[204:207], v165 offset:37888
	ds_read_b128 v[208:211], v165 offset:38912
	ds_read_b128 v[216:219], v165 offset:39936
	global_load_lds_dwordx4 v[224:225], off
	v_lshl_add_u64 v[224:225], s[66:67], 0, v[132:133]
	s_mov_b32 m0, s26
	s_nop 0
	global_load_lds_dwordx4 v[224:225], off
	s_waitcnt vmcnt(8)
	s_waitcnt lgkmcnt(0)
	s_barrier
	s_setprio 1
	v_mfma_f32_16x16x32_bf16 v[124:127], v[146:149], v[184:187], v[124:127]
	v_mfma_f32_16x16x32_bf16 v[120:123], v[154:157], v[184:187], v[120:123]
	v_mfma_f32_16x16x32_bf16 v[108:111], v[146:149], v[192:195], v[108:111]
	v_mfma_f32_16x16x32_bf16 v[104:107], v[154:157], v[192:195], v[104:107]
	v_mfma_f32_16x16x32_bf16 v[92:95], v[146:149], v[200:203], v[92:95]
	v_mfma_f32_16x16x32_bf16 v[88:91], v[154:157], v[200:203], v[88:91]
	v_mfma_f32_16x16x32_bf16 v[76:79], v[146:149], v[208:211], v[76:79]
	v_mfma_f32_16x16x32_bf16 v[72:75], v[154:157], v[208:211], v[72:75]
	v_mfma_f32_16x16x32_bf16 v[124:127], v[150:153], v[188:191], v[124:127]
	v_mfma_f32_16x16x32_bf16 v[120:123], v[158:161], v[188:191], v[120:123]
	v_mfma_f32_16x16x32_bf16 v[108:111], v[150:153], v[196:199], v[108:111]
	v_mfma_f32_16x16x32_bf16 v[104:107], v[158:161], v[196:199], v[104:107]
	v_mfma_f32_16x16x32_bf16 v[92:95], v[150:153], v[204:207], v[92:95]
	v_mfma_f32_16x16x32_bf16 v[88:91], v[158:161], v[204:207], v[88:91]
	v_mfma_f32_16x16x32_bf16 v[76:79], v[150:153], v[216:219], v[76:79]
	v_mfma_f32_16x16x32_bf16 v[72:75], v[158:161], v[216:219], v[72:75]
	v_mfma_f32_16x16x32_bf16 v[116:119], v[168:171], v[184:187], v[116:119]
	v_mfma_f32_16x16x32_bf16 v[112:115], v[176:179], v[184:187], v[112:115]
	v_mfma_f32_16x16x32_bf16 v[100:103], v[168:171], v[192:195], v[100:103]
	v_mfma_f32_16x16x32_bf16 v[96:99], v[176:179], v[192:195], v[96:99]
	v_mfma_f32_16x16x32_bf16 v[84:87], v[168:171], v[200:203], v[84:87]
	v_mfma_f32_16x16x32_bf16 v[80:83], v[176:179], v[200:203], v[80:83]
	v_mfma_f32_16x16x32_bf16 v[68:71], v[168:171], v[208:211], v[68:71]
	v_mfma_f32_16x16x32_bf16 v[64:67], v[176:179], v[208:211], v[64:67]
	v_mfma_f32_16x16x32_bf16 v[116:119], v[172:175], v[188:191], v[116:119]
	v_mfma_f32_16x16x32_bf16 v[112:115], v[180:183], v[188:191], v[112:115]
	v_mfma_f32_16x16x32_bf16 v[100:103], v[172:175], v[196:199], v[100:103]
	v_mfma_f32_16x16x32_bf16 v[96:99], v[180:183], v[196:199], v[96:99]
	v_mfma_f32_16x16x32_bf16 v[84:87], v[172:175], v[204:207], v[84:87]
	v_mfma_f32_16x16x32_bf16 v[80:83], v[180:183], v[204:207], v[80:83]
	v_mfma_f32_16x16x32_bf16 v[68:71], v[172:175], v[216:219], v[68:71]
	v_mfma_f32_16x16x32_bf16 v[64:67], v[180:183], v[216:219], v[64:67]
	s_setprio 0
	s_barrier
; #define PG8_STAGE(bufoff, gbase, voff) do { _Pragma("unroll") for (int _i = 0; _i < 2; ++_i) \
;         __builtin_amdgcn_global_load_lds((const unsigned*)((const char*)(gbase) + (voff)[_i]), (LAS unsigned*)(lds + (bufoff) + ldsw + _i * 8192), 16, 0, 0); } while (0)
; #define PG8_LDA(dst, b, h) do { _Pragma("unroll") for (int m = 0; m < 4; ++m) _Pragma("unroll") for (int k = 0; k < 2; ++k) dst[m][k] = *(const LAS bf16x8*)(lds + PG8_SA(b, h) + aoff + m * 2048 + k * 1024); } while (0)
; #define PG8_MMA(ai, bj, At, Bt) do { __builtin_amdgcn_s_setprio(1); _Pragma("unroll") for (int m = 0; m < 4; ++m) _Pragma("unroll") for (int n = 0; n < 2; ++n) _Pragma("unroll") for (int k = 0; k < 2; ++k) \
;         acc[ai][bj][m][n] = __builtin_amdgcn_mfma_f32_16x16x32_bf16(Bt[n][k], At[m][k], acc[ai][bj][m][n], 0, 0, 0); __builtin_amdgcn_s_setprio(0); } while (0)
; #define PG8_WAIT_V(n) asm volatile("s_waitcnt vmcnt(" #n ")" ::: "memory")
; #define PG8_WAIT_L(n) asm volatile("s_waitcnt lgkmcnt(" #n ")" ::: "memory")
; #define PG8_BAR __builtin_amdgcn_s_barrier()
; #define PG8_SCHED __builtin_amdgcn_sched_barrier(0)
; template <class Epi>
; DI void gemm_phase(LAS unsigned char* lds, const int wid, const Gemm g, const Order& S, const Epi& E) {
;     ...
;         for (int t = 0; t < nt; t += 2) {
;     ...
;             PG8_LDA(At, 1, 1); PG8_STAGE(PG8_SB(1, 0), b3, voffB); PG8_STAGE(PG8_SB(1, 1), b3 + hstepB, voffB); PG8_STAGE(PG8_SA(1, 0), a3, voffA);
;             PG8_WAIT_V(8); PG8_WAIT_L(0); PG8_BAR; PG8_MMA(1, 0, At, B0); PG8_MMA(1, 1, At, B1); PG8_BAR; PG8_SCHED;
	s_add_i32 s66, s71, s94
	v_lshl_add_u64 v[212:213], v[212:213], 0, s[34:35]
	s_mov_b32 m0, s66
	ds_read_b128 v[184:187], v165 offset:49152
	ds_read_b128 v[188:191], v165 offset:50176
	ds_read_b128 v[192:195], v165 offset:51200
	ds_read_b128 v[196:199], v165 offset:52224
	ds_read_b128 v[200:203], v165 offset:53248
	ds_read_b128 v[204:207], v165 offset:54272
	ds_read_b128 v[208:211], v165 offset:55296
	ds_read_b128 v[216:219], v165 offset:56320
	global_load_lds_dwordx4 v[212:213], off
	s_add_i32 m0, s66, 0x2000
	s_add_u32 s64, s64, 0x40080
	v_lshl_add_u64 v[212:213], v[214:215], 0, s[34:35]
	s_addc_u32 s65, s65, 0
	s_add_i32 s66, s86, s94
	global_load_lds_dwordx4 v[212:213], off
	v_lshl_add_u64 v[212:213], s[64:65], 0, v[130:131]
	s_mov_b32 m0, s66
	s_nop 0
	global_load_lds_dwordx4 v[212:213], off
	v_lshl_add_u64 v[212:213], s[64:65], 0, v[134:135]
	s_add_i32 m0, s66, 0x2000
	s_nop 0
	global_load_lds_dwordx4 v[212:213], off
	v_lshl_add_u64 v[212:213], v[220:221], 0, s[34:35]
	s_mov_b32 m0, s27
	s_nop 0
	global_load_lds_dwordx4 v[212:213], off
	v_lshl_add_u64 v[212:213], v[222:223], 0, s[34:35]
	s_mov_b32 m0, s55
	s_nop 0
	global_load_lds_dwordx4 v[212:213], off
	s_waitcnt vmcnt(8)
	s_waitcnt lgkmcnt(0)
	s_barrier
	s_setprio 1
	v_mfma_f32_16x16x32_bf16 v[60:63], v[146:149], v[184:187], v[60:63]
	v_mfma_f32_16x16x32_bf16 v[56:59], v[154:157], v[184:187], v[56:59]
	v_mfma_f32_16x16x32_bf16 v[44:47], v[146:149], v[192:195], v[44:47]
	v_mfma_f32_16x16x32_bf16 v[40:43], v[154:157], v[192:195], v[40:43]
	v_mfma_f32_16x16x32_bf16 v[28:31], v[146:149], v[200:203], v[28:31]
	v_mfma_f32_16x16x32_bf16 v[24:27], v[154:157], v[200:203], v[24:27]
	v_mfma_f32_16x16x32_bf16 v[12:15], v[146:149], v[208:211], v[12:15]
	v_mfma_f32_16x16x32_bf16 v[8:11], v[154:157], v[208:211], v[8:11]
	v_mfma_f32_16x16x32_bf16 v[60:63], v[150:153], v[188:191], v[60:63]
	v_mfma_f32_16x16x32_bf16 v[56:59], v[158:161], v[188:191], v[56:59]
	v_mfma_f32_16x16x32_bf16 v[44:47], v[150:153], v[196:199], v[44:47]
	v_mfma_f32_16x16x32_bf16 v[40:43], v[158:161], v[196:199], v[40:43]
	v_mfma_f32_16x16x32_bf16 v[28:31], v[150:153], v[204:207], v[28:31]
	v_mfma_f32_16x16x32_bf16 v[24:27], v[158:161], v[204:207], v[24:27]
	v_mfma_f32_16x16x32_bf16 v[12:15], v[150:153], v[216:219], v[12:15]
	v_mfma_f32_16x16x32_bf16 v[8:11], v[158:161], v[216:219], v[8:11]
	v_mfma_f32_16x16x32_bf16 v[52:55], v[168:171], v[184:187], v[52:55]
	v_mfma_f32_16x16x32_bf16 v[48:51], v[176:179], v[184:187], v[48:51]
	v_mfma_f32_16x16x32_bf16 v[36:39], v[168:171], v[192:195], v[36:39]
	v_mfma_f32_16x16x32_bf16 v[32:35], v[176:179], v[192:195], v[32:35]
	v_mfma_f32_16x16x32_bf16 v[20:23], v[168:171], v[200:203], v[20:23]
	v_mfma_f32_16x16x32_bf16 v[16:19], v[176:179], v[200:203], v[16:19]
	v_mfma_f32_16x16x32_bf16 v[4:7], v[168:171], v[208:211], v[4:7]
	v_mfma_f32_16x16x32_bf16 v[0:3], v[176:179], v[208:211], v[0:3]
	v_mfma_f32_16x16x32_bf16 v[52:55], v[172:175], v[188:191], v[52:55]
	v_mfma_f32_16x16x32_bf16 v[48:51], v[180:183], v[188:191], v[48:51]
	v_mfma_f32_16x16x32_bf16 v[36:39], v[172:175], v[196:199], v[36:39]
	v_mfma_f32_16x16x32_bf16 v[32:35], v[180:183], v[196:199], v[32:35]
	v_mfma_f32_16x16x32_bf16 v[20:23], v[172:175], v[204:207], v[20:23]
	v_mfma_f32_16x16x32_bf16 v[16:19], v[180:183], v[204:207], v[16:19]
	v_mfma_f32_16x16x32_bf16 v[4:7], v[172:175], v[216:219], v[4:7]
	v_mfma_f32_16x16x32_bf16 v[0:3], v[180:183], v[216:219], v[0:3]
	s_setprio 0
	s_barrier
	s_add_i32 s70, s70, 2
	s_add_u32 s12, s12, 0x100
	s_addc_u32 s13, s13, 0
	s_add_u32 s68, s68, 0x100
	s_addc_u32 s69, s69, 0
	s_cmp_gt_u32 s70, 13
	s_cbranch_scc0 .LBB0_400

; #define PG8_STAGE(bufoff, gbase, voff) do { _Pragma("unroll") for (int _i = 0; _i < 2; ++_i) \
;         __builtin_amdgcn_global_load_lds((const unsigned*)((const char*)(gbase) + (voff)[_i]), (LAS unsigned*)(lds + (bufoff) + ldsw + _i * 8192), 16, 0, 0); } while (0)
; #define PG8_LDA(dst, b, h) do { _Pragma("unroll") for (int m = 0; m < 4; ++m) _Pragma("unroll") for (int k = 0; k < 2; ++k) dst[m][k] = *(const LAS bf16x8*)(lds + PG8_SA(b, h) + aoff + m * 2048 + k * 1024); } while (0)
; #define PG8_LDB(dst, b, h) do { _Pragma("unroll") for (int n = 0; n < 2; ++n) _Pragma("unroll") for (int k = 0; k < 2; ++k) dst[n][k] = *(const LAS bf16x8*)(lds + PG8_SB(b, h) + boff + n * 2048 + k * 1024); } while (0)
; #define PG8_MMA(ai, bj, At, Bt) do { __builtin_amdgcn_s_setprio(1); _Pragma("unroll") for (int m = 0; m < 4; ++m) _Pragma("unroll") for (int n = 0; n < 2; ++n) _Pragma("unroll") for (int k = 0; k < 2; ++k) \
;         acc[ai][bj][m][n] = __builtin_amdgcn_mfma_f32_16x16x32_bf16(Bt[n][k], At[m][k], acc[ai][bj][m][n], 0, 0, 0); __builtin_amdgcn_s_setprio(0); } while (0)
; #define PG8_WAIT_V(n) asm volatile("s_waitcnt vmcnt(" #n ")" ::: "memory")
; #define PG8_BAR __builtin_amdgcn_s_barrier()
; template <class Epi>
; DI void gemm_phase(LAS unsigned char* lds, const int wid, const Gemm g, const Order& S, const Epi& E) {
;     ...
;         const bool has_next = S.next(ui + 1, nxt);
;         const char* nA = has_next ? (const char*)(g.A + (size_t)nxt.g * g.gsA + (size_t)nxt.pm * BM * g.lda) : cA;
;         const char* nB = has_next ? (const char*)(g.Bt + (size_t)nxt.g * g.gsB + (size_t)nxt.pn * BM * g.ldb) : cB;
;         for (int t = 0; t < nt; t += 2) {
;             const bool last = (t == nt - 2);
;             const char* a1 = cA + (size_t)(t + 1) * kstep;
;             const char* a2 = last ? nA : cA + (size_t)(t + 2) * kstep; const char* b2 = last ? nB : cB + (size_t)(t + 2) * kstep;
;             const char* a3 = a2 + kstep; const char* b3 = b2 + kstep;
;             PG8_LDB(B0, 0, 0); PG8_LDB(B1, 0, 1); PG8_SCHED; PG8_LDA(At, 0, 0); PG8_STAGE(PG8_SA(1, 1), a1 + hstepA, voffA);
;             PG8_WAIT_V(8); PG8_WAIT_L(0); PG8_BAR; PG8_MMA(0, 0, At, B0); PG8_MMA(0, 1, At, B1); PG8_BAR; PG8_SCHED;
;             PG8_LDA(At, 0, 1); PG8_STAGE(PG8_SB(0, 0), b2, voffB); PG8_STAGE(PG8_SB(0, 1), b2 + hstepB, voffB); PG8_STAGE(PG8_SA(0, 0), a2, voffA);
.LBB0_631:
	ds_read_b128 v[0:3], v205
	ds_read_b128 v[4:7], v205 offset:1024
	ds_read_b128 v[8:11], v205 offset:2048
	ds_read_b128 v[12:15], v205 offset:3072
	ds_read_b128 v[16:19], v206
	ds_read_b128 v[20:23], v206 offset:1024
	ds_read_b128 v[24:27], v206 offset:2048
	ds_read_b128 v[28:31], v206 offset:3072
	s_ashr_i32 s41, s40, 31
	s_lshl_b64 s[44:45], s[40:41], 17
	s_add_u32 s44, s6, s44
	s_addc_u32 s45, s7, s45
	s_and_b64 s[46:47], s[8:9], exec
	s_cselect_b32 s59, s45, s53
	s_cselect_b32 s58, s44, s52
	s_ashr_i32 s43, s42, 31
	s_lshl_b64 s[46:47], s[42:43], 17
	s_add_u32 s46, s21, s46
	s_addc_u32 s47, s25, s47
	s_and_b64 s[56:57], s[8:9], exec
	s_cselect_b32 s57, s47, s55
	s_cselect_b32 s56, s46, s54
	s_add_u32 s76, s52, 0x10080
	s_addc_u32 s77, s53, 0
	s_add_i32 s75, s26, 0xc000
	v_lshl_add_u64 v[64:65], s[76:77], 0, v[160:161]
	s_mov_b32 m0, s75
	s_add_i32 s41, s26, 0xe000
	s_waitcnt vmcnt(0)
	ds_read_b128 v[32:35], v207
	ds_read_b128 v[36:39], v207 offset:1024
	ds_read_b128 v[40:43], v207 offset:2048
	ds_read_b128 v[44:47], v207 offset:3072
	ds_read_b128 v[48:51], v207 offset:4096
	ds_read_b128 v[52:55], v207 offset:5120
	ds_read_b128 v[56:59], v207 offset:6144
	ds_read_b128 v[60:63], v207 offset:7168
	global_load_lds_dwordx4 v[64:65], off
	v_lshl_add_u64 v[64:65], s[76:77], 0, v[164:165]
	s_mov_b32 m0, s41
	s_nop 0
	global_load_lds_dwordx4 v[64:65], off
	s_waitcnt vmcnt(8)
	s_waitcnt lgkmcnt(0)
	s_barrier
	s_setprio 1
	v_mfma_f32_16x16x32_bf16 v[64:67], v[0:3], v[32:35], 0
	v_mfma_f32_16x16x32_bf16 v[68:71], v[8:11], v[32:35], 0
	v_mfma_f32_16x16x32_bf16 v[72:75], v[0:3], v[40:43], 0
	v_mfma_f32_16x16x32_bf16 v[76:79], v[8:11], v[40:43], 0
	v_mfma_f32_16x16x32_bf16 v[80:83], v[0:3], v[48:51], 0
	v_mfma_f32_16x16x32_bf16 v[84:87], v[8:11], v[48:51], 0
	v_mfma_f32_16x16x32_bf16 v[88:91], v[0:3], v[56:59], 0
	v_mfma_f32_16x16x32_bf16 v[92:95], v[8:11], v[56:59], 0
	v_mfma_f32_16x16x32_bf16 v[64:67], v[4:7], v[36:39], v[64:67]
	v_mfma_f32_16x16x32_bf16 v[68:71], v[12:15], v[36:39], v[68:71]
	v_mfma_f32_16x16x32_bf16 v[72:75], v[4:7], v[44:47], v[72:75]
	v_mfma_f32_16x16x32_bf16 v[76:79], v[12:15], v[44:47], v[76:79]
	v_mfma_f32_16x16x32_bf16 v[80:83], v[4:7], v[52:55], v[80:83]
	v_mfma_f32_16x16x32_bf16 v[84:87], v[12:15], v[52:55], v[84:87]
	v_mfma_f32_16x16x32_bf16 v[88:91], v[4:7], v[60:63], v[88:91]
	v_mfma_f32_16x16x32_bf16 v[92:95], v[12:15], v[60:63], v[92:95]
	v_mfma_f32_16x16x32_bf16 v[96:99], v[16:19], v[32:35], 0
	v_mfma_f32_16x16x32_bf16 v[32:35], v[24:27], v[32:35], 0
	v_mfma_f32_16x16x32_bf16 v[96:99], v[20:23], v[36:39], v[96:99]
	v_mfma_f32_16x16x32_bf16 v[32:35], v[28:31], v[36:39], v[32:35]
	v_mfma_f32_16x16x32_bf16 v[36:39], v[16:19], v[40:43], 0
	v_mfma_f32_16x16x32_bf16 v[40:43], v[24:27], v[40:43], 0
	v_mfma_f32_16x16x32_bf16 v[36:39], v[20:23], v[44:47], v[36:39]
	v_mfma_f32_16x16x32_bf16 v[40:43], v[28:31], v[44:47], v[40:43]
	v_mfma_f32_16x16x32_bf16 v[44:47], v[16:19], v[48:51], 0
	v_mfma_f32_16x16x32_bf16 v[48:51], v[24:27], v[48:51], 0
	v_mfma_f32_16x16x32_bf16 v[44:47], v[20:23], v[52:55], v[44:47]
	v_mfma_f32_16x16x32_bf16 v[48:51], v[28:31], v[52:55], v[48:51]
	v_mfma_f32_16x16x32_bf16 v[52:55], v[16:19], v[56:59], 0
	v_mfma_f32_16x16x32_bf16 v[56:59], v[24:27], v[56:59], 0
	v_mfma_f32_16x16x32_bf16 v[52:55], v[20:23], v[60:63], v[52:55]
	v_mfma_f32_16x16x32_bf16 v[56:59], v[28:31], v[60:63], v[56:59]
	s_setprio 0
	s_barrier
	s_add_i32 s73, s67, s94
	v_lshl_add_u64 v[170:171], s[54:55], 0, v[162:163]
	s_add_i32 s43, s73, 0x2000
	v_lshl_add_u64 v[128:129], v[170:171], 0, s[36:37]
	s_mov_b32 m0, s73
	v_lshl_add_u64 v[172:173], s[54:55], 0, v[166:167]
	s_add_u32 s76, s54, 0x10100
	ds_read_b128 v[60:63], v207 offset:16384
	ds_read_b128 v[100:103], v207 offset:17408
	ds_read_b128 v[104:107], v207 offset:18432
	ds_read_b128 v[108:111], v207 offset:19456
	ds_read_b128 v[112:115], v207 offset:20480
	ds_read_b128 v[116:119], v207 offset:21504
	ds_read_b128 v[120:123], v207 offset:22528
	ds_read_b128 v[124:127], v207 offset:23552
	global_load_lds_dwordx4 v[128:129], off
	v_lshl_add_u64 v[128:129], v[172:173], 0, s[36:37]
	s_mov_b32 m0, s43
	s_addc_u32 s77, s55, 0
	s_add_i32 s49, s68, s94
	global_load_lds_dwordx4 v[128:129], off
	v_lshl_add_u64 v[128:129], s[76:77], 0, v[162:163]
	s_mov_b32 m0, s49
	s_add_i32 s71, s49, 0x2000
	global_load_lds_dwordx4 v[128:129], off
	v_lshl_add_u64 v[128:129], s[76:77], 0, v[166:167]
	s_mov_b32 m0, s71
	v_lshl_add_u64 v[202:203], s[52:53], 0, v[160:161]
	global_load_lds_dwordx4 v[128:129], off
	v_lshl_add_u64 v[128:129], v[202:203], 0, s[36:37]
	s_mov_b32 m0, s26
	v_lshl_add_u64 v[214:215], s[52:53], 0, v[164:165]
	global_load_lds_dwordx4 v[128:129], off
	v_lshl_add_u64 v[128:129], v[214:215], 0, s[36:37]
	s_mov_b32 m0, s27
	s_nop 0
	global_load_lds_dwordx4 v[128:129], off
	s_waitcnt vmcnt(8)
	s_waitcnt lgkmcnt(0)
	s_barrier
; #define PG8_STAGE(bufoff, gbase, voff) do { _Pragma("unroll") for (int _i = 0; _i < 2; ++_i) \
;         __builtin_amdgcn_global_load_lds((const unsigned*)((const char*)(gbase) + (voff)[_i]), (LAS unsigned*)(lds + (bufoff) + ldsw + _i * 8192), 16, 0, 0); } while (0)
; #define PG8_LDA(dst, b, h) do { _Pragma("unroll") for (int m = 0; m < 4; ++m) _Pragma("unroll") for (int k = 0; k < 2; ++k) dst[m][k] = *(const LAS bf16x8*)(lds + PG8_SA(b, h) + aoff + m * 2048 + k * 1024); } while (0)
; #define PG8_LDB(dst, b, h) do { _Pragma("unroll") for (int n = 0; n < 2; ++n) _Pragma("unroll") for (int k = 0; k < 2; ++k) dst[n][k] = *(const LAS bf16x8*)(lds + PG8_SB(b, h) + boff + n * 2048 + k * 1024); } while (0)
; #define PG8_MMA(ai, bj, At, Bt) do { __builtin_amdgcn_s_setprio(1); _Pragma("unroll") for (int m = 0; m < 4; ++m) _Pragma("unroll") for (int n = 0; n < 2; ++n) _Pragma("unroll") for (int k = 0; k < 2; ++k) \
;         acc[ai][bj][m][n] = __builtin_amdgcn_mfma_f32_16x16x32_bf16(Bt[n][k], At[m][k], acc[ai][bj][m][n], 0, 0, 0); __builtin_amdgcn_s_setprio(0); } while (0)
; #define PG8_WAIT_V(n) asm volatile("s_waitcnt vmcnt(" #n ")" ::: "memory")
; #define PG8_WAIT_L(n) asm volatile("s_waitcnt lgkmcnt(" #n ")" ::: "memory")
; #define PG8_BAR __builtin_amdgcn_s_barrier()
; #define PG8_SCHED __builtin_amdgcn_sched_barrier(0)
; template <class Epi>
; DI void gemm_phase(LAS unsigned char* lds, const int wid, const Gemm g, const Order& S, const Epi& E) {
;     ...
;             PG8_WAIT_V(8); PG8_WAIT_L(0); PG8_BAR; PG8_MMA(1, 0, At, B0); PG8_MMA(1, 1, At, B1); PG8_BAR; PG8_SCHED;
;             PG8_LDB(B0, 1, 0); PG8_LDB(B1, 1, 1); PG8_SCHED; PG8_LDA(At, 1, 0); PG8_STAGE(PG8_SA(0, 1), a2 + hstepA, voffA);
;             PG8_WAIT_V(8); PG8_WAIT_L(0); PG8_BAR; PG8_MMA(0, 0, At, B0); PG8_MMA(0, 1, At, B1); PG8_BAR; PG8_SCHED;
	s_setprio 1
	v_mfma_f32_16x16x32_bf16 v[128:131], v[0:3], v[60:63], 0
	v_mfma_f32_16x16x32_bf16 v[136:139], v[0:3], v[104:107], 0
	v_mfma_f32_16x16x32_bf16 v[144:147], v[0:3], v[112:115], 0
	v_mfma_f32_16x16x32_bf16 v[0:3], v[0:3], v[120:123], 0
	v_mfma_f32_16x16x32_bf16 v[128:131], v[4:7], v[100:103], v[128:131]
	v_mfma_f32_16x16x32_bf16 v[132:135], v[8:11], v[60:63], 0
	v_mfma_f32_16x16x32_bf16 v[136:139], v[4:7], v[108:111], v[136:139]
	v_mfma_f32_16x16x32_bf16 v[144:147], v[4:7], v[116:119], v[144:147]
	v_mfma_f32_16x16x32_bf16 v[0:3], v[4:7], v[124:127], v[0:3]
	v_mfma_f32_16x16x32_bf16 v[4:7], v[8:11], v[120:123], 0
	v_mfma_f32_16x16x32_bf16 v[132:135], v[12:15], v[100:103], v[132:135]
	v_mfma_f32_16x16x32_bf16 v[140:143], v[8:11], v[104:107], 0
	v_mfma_f32_16x16x32_bf16 v[148:151], v[8:11], v[112:115], 0
	v_mfma_f32_16x16x32_bf16 v[4:7], v[12:15], v[124:127], v[4:7]
	v_mfma_f32_16x16x32_bf16 v[140:143], v[12:15], v[108:111], v[140:143]
	v_mfma_f32_16x16x32_bf16 v[148:151], v[12:15], v[116:119], v[148:151]
	v_mfma_f32_16x16x32_bf16 v[8:11], v[16:19], v[60:63], 0
	v_mfma_f32_16x16x32_bf16 v[12:15], v[24:27], v[60:63], 0
	v_mfma_f32_16x16x32_bf16 v[8:11], v[20:23], v[100:103], v[8:11]
	v_mfma_f32_16x16x32_bf16 v[12:15], v[28:31], v[100:103], v[12:15]
	v_mfma_f32_16x16x32_bf16 v[60:63], v[16:19], v[104:107], 0
	v_mfma_f32_16x16x32_bf16 v[100:103], v[24:27], v[104:107], 0
	v_mfma_f32_16x16x32_bf16 v[104:107], v[16:19], v[112:115], 0
	v_mfma_f32_16x16x32_bf16 v[16:19], v[16:19], v[120:123], 0
	v_mfma_f32_16x16x32_bf16 v[60:63], v[20:23], v[108:111], v[60:63]
	v_mfma_f32_16x16x32_bf16 v[100:103], v[28:31], v[108:111], v[100:103]
	v_mfma_f32_16x16x32_bf16 v[104:107], v[20:23], v[116:119], v[104:107]
	v_mfma_f32_16x16x32_bf16 v[108:111], v[24:27], v[112:115], 0
	v_mfma_f32_16x16x32_bf16 v[16:19], v[20:23], v[124:127], v[16:19]
	v_mfma_f32_16x16x32_bf16 v[20:23], v[24:27], v[120:123], 0
	v_mfma_f32_16x16x32_bf16 v[108:111], v[28:31], v[116:119], v[108:111]
	v_mfma_f32_16x16x32_bf16 v[20:23], v[28:31], v[124:127], v[20:23]
	s_setprio 0
	s_barrier
	s_add_i32 s74, 0, 0x18000
	s_add_i32 s80, 0, 0x1c000
	v_add_u32_e32 v168, s74, v204
	v_add_u32_e32 v236, s80, v204
	ds_read_b128 v[24:27], v168
	ds_read_b128 v[28:31], v168 offset:1024
	ds_read_b128 v[112:115], v168 offset:2048
	ds_read_b128 v[116:119], v168 offset:3072
	ds_read_b128 v[120:123], v236
	ds_read_b128 v[124:127], v236 offset:1024
	ds_read_b128 v[152:155], v236 offset:2048
	ds_read_b128 v[156:159], v236 offset:3072
	s_add_u32 s76, s52, 0x10100
	s_addc_u32 s77, s53, 0
	s_mov_b32 m0, s51
	v_lshl_add_u64 v[216:217], s[76:77], 0, v[160:161]
	ds_read_b128 v[174:177], v207 offset:32768
	ds_read_b128 v[178:181], v207 offset:33792
	ds_read_b128 v[182:185], v207 offset:34816
	ds_read_b128 v[186:189], v207 offset:35840
	ds_read_b128 v[190:193], v207 offset:36864
	ds_read_b128 v[194:197], v207 offset:37888
	ds_read_b128 v[198:201], v207 offset:38912
	ds_read_b128 v[210:213], v207 offset:39936
	global_load_lds_dwordx4 v[216:217], off
	v_lshl_add_u64 v[216:217], s[76:77], 0, v[164:165]
	s_mov_b32 m0, s60
	s_nop 0
	global_load_lds_dwordx4 v[216:217], off
	s_waitcnt vmcnt(8)
	s_waitcnt lgkmcnt(0)
	s_barrier
	s_setprio 1
	v_mfma_f32_16x16x32_bf16 v[64:67], v[24:27], v[174:177], v[64:67]
	v_mfma_f32_16x16x32_bf16 v[68:71], v[112:115], v[174:177], v[68:71]
	v_mfma_f32_16x16x32_bf16 v[72:75], v[24:27], v[182:185], v[72:75]
	v_mfma_f32_16x16x32_bf16 v[76:79], v[112:115], v[182:185], v[76:79]
	v_mfma_f32_16x16x32_bf16 v[80:83], v[24:27], v[190:193], v[80:83]
	v_mfma_f32_16x16x32_bf16 v[84:87], v[112:115], v[190:193], v[84:87]
	v_mfma_f32_16x16x32_bf16 v[88:91], v[24:27], v[198:201], v[88:91]
	v_mfma_f32_16x16x32_bf16 v[92:95], v[112:115], v[198:201], v[92:95]
	v_mfma_f32_16x16x32_bf16 v[64:67], v[28:31], v[178:181], v[64:67]
	v_mfma_f32_16x16x32_bf16 v[68:71], v[116:119], v[178:181], v[68:71]
	v_mfma_f32_16x16x32_bf16 v[72:75], v[28:31], v[186:189], v[72:75]
	v_mfma_f32_16x16x32_bf16 v[76:79], v[116:119], v[186:189], v[76:79]
	v_mfma_f32_16x16x32_bf16 v[80:83], v[28:31], v[194:197], v[80:83]
	v_mfma_f32_16x16x32_bf16 v[84:87], v[116:119], v[194:197], v[84:87]
	v_mfma_f32_16x16x32_bf16 v[88:91], v[28:31], v[210:213], v[88:91]
	v_mfma_f32_16x16x32_bf16 v[92:95], v[116:119], v[210:213], v[92:95]
	v_mfma_f32_16x16x32_bf16 v[96:99], v[120:123], v[174:177], v[96:99]
	v_mfma_f32_16x16x32_bf16 v[32:35], v[152:155], v[174:177], v[32:35]
	v_mfma_f32_16x16x32_bf16 v[36:39], v[120:123], v[182:185], v[36:39]
	v_mfma_f32_16x16x32_bf16 v[40:43], v[152:155], v[182:185], v[40:43]
	v_mfma_f32_16x16x32_bf16 v[44:47], v[120:123], v[190:193], v[44:47]
	v_mfma_f32_16x16x32_bf16 v[48:51], v[152:155], v[190:193], v[48:51]
	v_mfma_f32_16x16x32_bf16 v[52:55], v[120:123], v[198:201], v[52:55]
	v_mfma_f32_16x16x32_bf16 v[56:59], v[152:155], v[198:201], v[56:59]
	v_mfma_f32_16x16x32_bf16 v[96:99], v[124:127], v[178:181], v[96:99]
	v_mfma_f32_16x16x32_bf16 v[32:35], v[156:159], v[178:181], v[32:35]
	v_mfma_f32_16x16x32_bf16 v[36:39], v[124:127], v[186:189], v[36:39]
	v_mfma_f32_16x16x32_bf16 v[40:43], v[156:159], v[186:189], v[40:43]
	v_mfma_f32_16x16x32_bf16 v[44:47], v[124:127], v[194:197], v[44:47]
	v_mfma_f32_16x16x32_bf16 v[48:51], v[156:159], v[194:197], v[48:51]
	v_mfma_f32_16x16x32_bf16 v[52:55], v[124:127], v[210:213], v[52:55]
	v_mfma_f32_16x16x32_bf16 v[56:59], v[156:159], v[210:213], v[56:59]
	s_setprio 0
	s_barrier
; #define PG8_STAGE(bufoff, gbase, voff) do { _Pragma("unroll") for (int _i = 0; _i < 2; ++_i) \
;         __builtin_amdgcn_global_load_lds((const unsigned*)((const char*)(gbase) + (voff)[_i]), (LAS unsigned*)(lds + (bufoff) + ldsw + _i * 8192), 16, 0, 0); } while (0)
; #define PG8_LDA(dst, b, h) do { _Pragma("unroll") for (int m = 0; m < 4; ++m) _Pragma("unroll") for (int k = 0; k < 2; ++k) dst[m][k] = *(const LAS bf16x8*)(lds + PG8_SA(b, h) + aoff + m * 2048 + k * 1024); } while (0)
; #define PG8_LDB(dst, b, h) do { _Pragma("unroll") for (int n = 0; n < 2; ++n) _Pragma("unroll") for (int k = 0; k < 2; ++k) dst[n][k] = *(const LAS bf16x8*)(lds + PG8_SB(b, h) + boff + n * 2048 + k * 1024); } while (0)
; #define PG8_MMA(ai, bj, At, Bt) do { __builtin_amdgcn_s_setprio(1); _Pragma("unroll") for (int m = 0; m < 4; ++m) _Pragma("unroll") for (int n = 0; n < 2; ++n) _Pragma("unroll") for (int k = 0; k < 2; ++k) \
;         acc[ai][bj][m][n] = __builtin_amdgcn_mfma_f32_16x16x32_bf16(Bt[n][k], At[m][k], acc[ai][bj][m][n], 0, 0, 0); __builtin_amdgcn_s_setprio(0); } while (0)
; #define PG8_WAIT_V(n) asm volatile("s_waitcnt vmcnt(" #n ")" ::: "memory")
; #define PG8_WAIT_L(n) asm volatile("s_waitcnt lgkmcnt(" #n ")" ::: "memory")
; #define PG8_BAR __builtin_amdgcn_s_barrier()
; #define PG8_SCHED __builtin_amdgcn_sched_barrier(0)
; template <class Epi>
; DI void gemm_phase(LAS unsigned char* lds, const int wid, const Gemm g, const Order& S, const Epi& E) {
;     ...
;             PG8_LDB(B0, 0, 0); PG8_LDB(B1, 0, 1); PG8_SCHED; PG8_LDA(At, 0, 0); PG8_STAGE(PG8_SA(1, 1), a1 + hstepA, voffA);
;             PG8_WAIT_V(8); PG8_WAIT_L(0); PG8_BAR; PG8_MMA(0, 0, At, B0); PG8_MMA(0, 1, At, B1); PG8_BAR; PG8_SCHED;
;     ...
;             PG8_LDA(At, 1, 1); PG8_STAGE(PG8_SB(1, 0), b3, voffB); PG8_STAGE(PG8_SB(1, 1), b3 + hstepB, voffB); PG8_STAGE(PG8_SA(1, 0), a3, voffA);
;             PG8_WAIT_V(8); PG8_WAIT_L(0); PG8_BAR; PG8_MMA(1, 0, At, B0); PG8_MMA(1, 1, At, B1); PG8_BAR; PG8_SCHED;
	s_add_i32 s76, s74, s94
	s_add_i32 s74, s76, 0x2000
	v_lshl_add_u64 v[170:171], v[170:171], 0, s[38:39]
	s_mov_b32 m0, s76
	s_add_u32 s78, s54, 0x10180
	ds_read_b128 v[174:177], v207 offset:49152
	ds_read_b128 v[178:181], v207 offset:50176
	ds_read_b128 v[182:185], v207 offset:51200
	ds_read_b128 v[186:189], v207 offset:52224
	ds_read_b128 v[190:193], v207 offset:53248
	ds_read_b128 v[194:197], v207 offset:54272
	ds_read_b128 v[198:201], v207 offset:55296
	ds_read_b128 v[210:213], v207 offset:56320
	global_load_lds_dwordx4 v[170:171], off
	v_lshl_add_u64 v[170:171], v[172:173], 0, s[38:39]
	s_mov_b32 m0, s74
	s_addc_u32 s79, s55, 0
	s_add_i32 s54, s80, s94
	global_load_lds_dwordx4 v[170:171], off
	v_lshl_add_u64 v[170:171], s[78:79], 0, v[162:163]
	s_mov_b32 m0, s54
	s_add_i32 s55, s54, 0x2000
	global_load_lds_dwordx4 v[170:171], off
	v_lshl_add_u64 v[170:171], s[78:79], 0, v[166:167]
	s_mov_b32 m0, s55
	s_nop 0
	global_load_lds_dwordx4 v[170:171], off
	v_lshl_add_u64 v[170:171], v[202:203], 0, s[38:39]
	s_mov_b32 m0, s61
	s_nop 0
	global_load_lds_dwordx4 v[170:171], off
	v_lshl_add_u64 v[170:171], v[214:215], 0, s[38:39]
	s_mov_b32 m0, s62
	s_nop 0
	global_load_lds_dwordx4 v[170:171], off
	s_waitcnt vmcnt(8)
	s_waitcnt lgkmcnt(0)
	s_barrier
	s_setprio 1
	v_mfma_f32_16x16x32_bf16 v[128:131], v[24:27], v[174:177], v[128:131]
	v_mfma_f32_16x16x32_bf16 v[132:135], v[112:115], v[174:177], v[132:135]
	v_mfma_f32_16x16x32_bf16 v[0:3], v[24:27], v[198:201], v[0:3]
	v_mfma_f32_16x16x32_bf16 v[4:7], v[112:115], v[198:201], v[4:7]
	v_mfma_f32_16x16x32_bf16 v[128:131], v[28:31], v[178:181], v[128:131]
	v_mfma_f32_16x16x32_bf16 v[132:135], v[116:119], v[178:181], v[132:135]
	v_mfma_f32_16x16x32_bf16 v[136:139], v[24:27], v[182:185], v[136:139]
	v_mfma_f32_16x16x32_bf16 v[140:143], v[112:115], v[182:185], v[140:143]
	v_mfma_f32_16x16x32_bf16 v[144:147], v[24:27], v[190:193], v[144:147]
	v_mfma_f32_16x16x32_bf16 v[148:151], v[112:115], v[190:193], v[148:151]
	v_mfma_f32_16x16x32_bf16 v[0:3], v[28:31], v[210:213], v[0:3]
	v_mfma_f32_16x16x32_bf16 v[4:7], v[116:119], v[210:213], v[4:7]
	v_mfma_f32_16x16x32_bf16 v[136:139], v[28:31], v[186:189], v[136:139]
	v_mfma_f32_16x16x32_bf16 v[140:143], v[116:119], v[186:189], v[140:143]
	v_mfma_f32_16x16x32_bf16 v[144:147], v[28:31], v[194:197], v[144:147]
	v_mfma_f32_16x16x32_bf16 v[148:151], v[116:119], v[194:197], v[148:151]
	v_mfma_f32_16x16x32_bf16 v[8:11], v[120:123], v[174:177], v[8:11]
	v_mfma_f32_16x16x32_bf16 v[12:15], v[152:155], v[174:177], v[12:15]
	v_mfma_f32_16x16x32_bf16 v[24:27], v[120:123], v[182:185], v[60:63]
	v_mfma_f32_16x16x32_bf16 v[28:31], v[152:155], v[182:185], v[100:103]
	v_mfma_f32_16x16x32_bf16 v[60:63], v[120:123], v[190:193], v[104:107]
	v_mfma_f32_16x16x32_bf16 v[100:103], v[152:155], v[190:193], v[108:111]
	v_mfma_f32_16x16x32_bf16 v[16:19], v[120:123], v[198:201], v[16:19]
	v_mfma_f32_16x16x32_bf16 v[20:23], v[152:155], v[198:201], v[20:23]
	v_mfma_f32_16x16x32_bf16 v[8:11], v[124:127], v[178:181], v[8:11]
	v_mfma_f32_16x16x32_bf16 v[12:15], v[156:159], v[178:181], v[12:15]
	v_mfma_f32_16x16x32_bf16 v[24:27], v[124:127], v[186:189], v[24:27]
	v_mfma_f32_16x16x32_bf16 v[28:31], v[156:159], v[186:189], v[28:31]
	v_mfma_f32_16x16x32_bf16 v[60:63], v[124:127], v[194:197], v[60:63]
	v_mfma_f32_16x16x32_bf16 v[100:103], v[156:159], v[194:197], v[100:103]
	v_mfma_f32_16x16x32_bf16 v[16:19], v[124:127], v[210:213], v[16:19]
	v_mfma_f32_16x16x32_bf16 v[20:23], v[156:159], v[210:213], v[20:23]
	s_setprio 0
	s_barrier
	ds_read_b128 v[104:107], v205
	ds_read_b128 v[108:111], v205 offset:1024
	ds_read_b128 v[112:115], v205 offset:2048
	ds_read_b128 v[116:119], v205 offset:3072
	ds_read_b128 v[120:123], v206
	ds_read_b128 v[124:127], v206 offset:1024
	ds_read_b128 v[152:155], v206 offset:2048
	ds_read_b128 v[156:159], v206 offset:3072
	s_add_u32 s52, s52, 0x10180
	s_addc_u32 s53, s53, 0
	s_mov_b32 m0, s75
	v_lshl_add_u64 v[170:171], s[52:53], 0, v[160:161]
	ds_read_b128 v[174:177], v207
	ds_read_b128 v[178:181], v207 offset:1024
	ds_read_b128 v[182:185], v207 offset:2048
	ds_read_b128 v[186:189], v207 offset:3072
	ds_read_b128 v[190:193], v207 offset:4096
	ds_read_b128 v[194:197], v207 offset:5120
	ds_read_b128 v[198:201], v207 offset:6144
	ds_read_b128 v[210:213], v207 offset:7168
	global_load_lds_dwordx4 v[170:171], off
	v_lshl_add_u64 v[170:171], s[52:53], 0, v[164:165]
	s_mov_b32 m0, s41
	s_nop 0
	global_load_lds_dwordx4 v[170:171], off
	s_waitcnt vmcnt(8)
	s_waitcnt lgkmcnt(0)
	s_barrier
; #define PG8_STAGE(bufoff, gbase, voff) do { _Pragma("unroll") for (int _i = 0; _i < 2; ++_i) \
;         __builtin_amdgcn_global_load_lds((const unsigned*)((const char*)(gbase) + (voff)[_i]), (LAS unsigned*)(lds + (bufoff) + ldsw + _i * 8192), 16, 0, 0); } while (0)
; #define PG8_LDA(dst, b, h) do { _Pragma("unroll") for (int m = 0; m < 4; ++m) _Pragma("unroll") for (int k = 0; k < 2; ++k) dst[m][k] = *(const LAS bf16x8*)(lds + PG8_SA(b, h) + aoff + m * 2048 + k * 1024); } while (0)
; #define PG8_MMA(ai, bj, At, Bt) do { __builtin_amdgcn_s_setprio(1); _Pragma("unroll") for (int m = 0; m < 4; ++m) _Pragma("unroll") for (int n = 0; n < 2; ++n) _Pragma("unroll") for (int k = 0; k < 2; ++k) \
;         acc[ai][bj][m][n] = __builtin_amdgcn_mfma_f32_16x16x32_bf16(Bt[n][k], At[m][k], acc[ai][bj][m][n], 0, 0, 0); __builtin_amdgcn_s_setprio(0); } while (0)
; #define PG8_WAIT_V(n) asm volatile("s_waitcnt vmcnt(" #n ")" ::: "memory")
; #define PG8_WAIT_L(n) asm volatile("s_waitcnt lgkmcnt(" #n ")" ::: "memory")
; #define PG8_BAR __builtin_amdgcn_s_barrier()
; #define PG8_SCHED __builtin_amdgcn_sched_barrier(0)
; template <class Epi>
; DI void gemm_phase(LAS unsigned char* lds, const int wid, const Gemm g, const Order& S, const Epi& E) {
;     ...
;             PG8_WAIT_V(8); PG8_WAIT_L(0); PG8_BAR; PG8_MMA(0, 0, At, B0); PG8_MMA(0, 1, At, B1); PG8_BAR; PG8_SCHED;
;             PG8_LDA(At, 0, 1); PG8_STAGE(PG8_SB(0, 0), b2, voffB); PG8_STAGE(PG8_SB(0, 1), b2 + hstepB, voffB); PG8_STAGE(PG8_SA(0, 0), a2, voffA);
;             PG8_WAIT_V(8); PG8_WAIT_L(0); PG8_BAR; PG8_MMA(1, 0, At, B0); PG8_MMA(1, 1, At, B1); PG8_BAR; PG8_SCHED;
	s_setprio 1
	v_mfma_f32_16x16x32_bf16 v[64:67], v[104:107], v[174:177], v[64:67]
	v_mfma_f32_16x16x32_bf16 v[68:71], v[112:115], v[174:177], v[68:71]
	v_mfma_f32_16x16x32_bf16 v[72:75], v[104:107], v[182:185], v[72:75]
	v_mfma_f32_16x16x32_bf16 v[76:79], v[112:115], v[182:185], v[76:79]
	v_mfma_f32_16x16x32_bf16 v[80:83], v[104:107], v[190:193], v[80:83]
	v_mfma_f32_16x16x32_bf16 v[84:87], v[112:115], v[190:193], v[84:87]
	v_mfma_f32_16x16x32_bf16 v[88:91], v[104:107], v[198:201], v[88:91]
	v_mfma_f32_16x16x32_bf16 v[92:95], v[112:115], v[198:201], v[92:95]
	v_mfma_f32_16x16x32_bf16 v[64:67], v[108:111], v[178:181], v[64:67]
	v_mfma_f32_16x16x32_bf16 v[68:71], v[116:119], v[178:181], v[68:71]
	v_mfma_f32_16x16x32_bf16 v[72:75], v[108:111], v[186:189], v[72:75]
	v_mfma_f32_16x16x32_bf16 v[76:79], v[116:119], v[186:189], v[76:79]
	v_mfma_f32_16x16x32_bf16 v[80:83], v[108:111], v[194:197], v[80:83]
	v_mfma_f32_16x16x32_bf16 v[84:87], v[116:119], v[194:197], v[84:87]
	v_mfma_f32_16x16x32_bf16 v[88:91], v[108:111], v[210:213], v[88:91]
	v_mfma_f32_16x16x32_bf16 v[92:95], v[116:119], v[210:213], v[92:95]
	v_mfma_f32_16x16x32_bf16 v[48:51], v[152:155], v[190:193], v[48:51]
	v_mfma_f32_16x16x32_bf16 v[96:99], v[120:123], v[174:177], v[96:99]
	v_mfma_f32_16x16x32_bf16 v[32:35], v[152:155], v[174:177], v[32:35]
	v_mfma_f32_16x16x32_bf16 v[36:39], v[120:123], v[182:185], v[36:39]
	v_mfma_f32_16x16x32_bf16 v[40:43], v[152:155], v[182:185], v[40:43]
	v_mfma_f32_16x16x32_bf16 v[44:47], v[120:123], v[190:193], v[44:47]
	v_mfma_f32_16x16x32_bf16 v[174:177], v[156:159], v[194:197], v[48:51]
	v_mfma_f32_16x16x32_bf16 v[48:51], v[120:123], v[198:201], v[52:55]
	v_mfma_f32_16x16x32_bf16 v[216:219], v[124:127], v[178:181], v[96:99]
	v_mfma_f32_16x16x32_bf16 v[32:35], v[156:159], v[178:181], v[32:35]
	v_mfma_f32_16x16x32_bf16 v[36:39], v[124:127], v[186:189], v[36:39]
	v_mfma_f32_16x16x32_bf16 v[40:43], v[156:159], v[186:189], v[40:43]
	v_mfma_f32_16x16x32_bf16 v[44:47], v[124:127], v[194:197], v[44:47]
	v_mfma_f32_16x16x32_bf16 v[178:181], v[124:127], v[210:213], v[48:51]
	v_mfma_f32_16x16x32_bf16 v[48:51], v[152:155], v[198:201], v[56:59]
	v_mfma_f32_16x16x32_bf16 v[182:185], v[156:159], v[210:213], v[48:51]
	s_setprio 0
	s_barrier
	s_mov_b32 m0, s73
	v_lshl_add_u64 v[202:203], s[56:57], 0, v[162:163]
	s_add_u32 s52, s56, 0x10000
	s_nop 1
	ds_read_b128 v[48:51], v207 offset:16384
	ds_read_b128 v[52:55], v207 offset:17408
	ds_read_b128 v[56:59], v207 offset:18432
	ds_read_b128 v[96:99], v207 offset:19456
	ds_read_b128 v[186:189], v207 offset:20480
	ds_read_b128 v[190:193], v207 offset:21504
	ds_read_b128 v[194:197], v207 offset:22528
	ds_read_b128 v[198:201], v207 offset:23552
	global_load_lds_dwordx4 v[202:203], off
	v_lshl_add_u64 v[214:215], s[56:57], 0, v[166:167]
	s_mov_b32 m0, s43
	s_addc_u32 s53, s57, 0
	global_load_lds_dwordx4 v[214:215], off
	v_lshl_add_u64 v[170:171], s[52:53], 0, v[162:163]
	s_mov_b32 m0, s49
	v_lshl_add_u64 v[252:253], s[58:59], 0, v[160:161]
	global_load_lds_dwordx4 v[170:171], off
	v_lshl_add_u64 v[170:171], s[52:53], 0, v[166:167]
	s_mov_b32 m0, s71
	v_lshl_add_u64 v[208:209], s[58:59], 0, v[164:165]
	global_load_lds_dwordx4 v[170:171], off
	s_mov_b32 m0, s26
	s_nop 0
	global_load_lds_dwordx4 v[252:253], off
	s_mov_b32 m0, s27
	s_nop 0
	global_load_lds_dwordx4 v[208:209], off
	s_waitcnt vmcnt(8)
	s_waitcnt lgkmcnt(0)
	s_barrier
	s_setprio 1
	v_mfma_f32_16x16x32_bf16 v[128:131], v[104:107], v[48:51], v[128:131]
	v_mfma_f32_16x16x32_bf16 v[210:213], v[108:111], v[52:55], v[128:131]
	v_mfma_f32_16x16x32_bf16 v[128:131], v[112:115], v[48:51], v[132:135]
	v_mfma_f32_16x16x32_bf16 v[220:223], v[116:119], v[52:55], v[128:131]
	v_mfma_f32_16x16x32_bf16 v[128:131], v[104:107], v[56:59], v[136:139]
	v_mfma_f32_16x16x32_bf16 v[136:139], v[108:111], v[96:99], v[128:131]
	v_mfma_f32_16x16x32_bf16 v[128:131], v[112:115], v[56:59], v[140:143]
	v_mfma_f32_16x16x32_bf16 v[140:143], v[116:119], v[96:99], v[128:131]
	v_mfma_f32_16x16x32_bf16 v[128:131], v[104:107], v[186:189], v[144:147]
	v_mfma_f32_16x16x32_bf16 v[0:3], v[104:107], v[194:197], v[0:3]
	v_mfma_f32_16x16x32_bf16 v[4:7], v[112:115], v[194:197], v[4:7]
	v_mfma_f32_16x16x32_bf16 v[144:147], v[108:111], v[190:193], v[128:131]
	v_mfma_f32_16x16x32_bf16 v[128:131], v[112:115], v[186:189], v[148:151]
	v_mfma_f32_16x16x32_bf16 v[0:3], v[108:111], v[198:201], v[0:3]
	v_mfma_f32_16x16x32_bf16 v[4:7], v[116:119], v[198:201], v[4:7]
	v_mfma_f32_16x16x32_bf16 v[148:151], v[116:119], v[190:193], v[128:131]
	v_mfma_f32_16x16x32_bf16 v[24:27], v[120:123], v[56:59], v[24:27]
	v_mfma_f32_16x16x32_bf16 v[224:227], v[124:127], v[96:99], v[24:27]
	v_mfma_f32_16x16x32_bf16 v[24:27], v[152:155], v[56:59], v[28:31]
	v_mfma_f32_16x16x32_bf16 v[8:11], v[120:123], v[48:51], v[8:11]
	v_mfma_f32_16x16x32_bf16 v[12:15], v[152:155], v[48:51], v[12:15]
	v_mfma_f32_16x16x32_bf16 v[228:231], v[156:159], v[96:99], v[24:27]
	v_mfma_f32_16x16x32_bf16 v[24:27], v[120:123], v[186:189], v[60:63]
	v_mfma_f32_16x16x32_bf16 v[16:19], v[120:123], v[194:197], v[16:19]
	v_mfma_f32_16x16x32_bf16 v[8:11], v[124:127], v[52:55], v[8:11]
	v_mfma_f32_16x16x32_bf16 v[12:15], v[156:159], v[52:55], v[12:15]
	v_mfma_f32_16x16x32_bf16 v[232:235], v[124:127], v[190:193], v[24:27]
	v_mfma_f32_16x16x32_bf16 v[24:27], v[152:155], v[186:189], v[100:103]
	v_mfma_f32_16x16x32_bf16 v[120:123], v[124:127], v[198:201], v[16:19]
	v_mfma_f32_16x16x32_bf16 v[16:19], v[152:155], v[194:197], v[20:23]
	v_mfma_f32_16x16x32_bf16 v[186:189], v[156:159], v[190:193], v[24:27]
	v_mfma_f32_16x16x32_bf16 v[124:127], v[156:159], v[198:201], v[16:19]
	s_setprio 0
	s_barrier
; #define PG8_STAGE(bufoff, gbase, voff) do { _Pragma("unroll") for (int _i = 0; _i < 2; ++_i) \
;         __builtin_amdgcn_global_load_lds((const unsigned*)((const char*)(gbase) + (voff)[_i]), (LAS unsigned*)(lds + (bufoff) + ldsw + _i * 8192), 16, 0, 0); } while (0)
; #define PG8_LDA(dst, b, h) do { _Pragma("unroll") for (int m = 0; m < 4; ++m) _Pragma("unroll") for (int k = 0; k < 2; ++k) dst[m][k] = *(const LAS bf16x8*)(lds + PG8_SA(b, h) + aoff + m * 2048 + k * 1024); } while (0)
; #define PG8_LDB(dst, b, h) do { _Pragma("unroll") for (int n = 0; n < 2; ++n) _Pragma("unroll") for (int k = 0; k < 2; ++k) dst[n][k] = *(const LAS bf16x8*)(lds + PG8_SB(b, h) + boff + n * 2048 + k * 1024); } while (0)
; #define PG8_MMA(ai, bj, At, Bt) do { __builtin_amdgcn_s_setprio(1); _Pragma("unroll") for (int m = 0; m < 4; ++m) _Pragma("unroll") for (int n = 0; n < 2; ++n) _Pragma("unroll") for (int k = 0; k < 2; ++k) \
;         acc[ai][bj][m][n] = __builtin_amdgcn_mfma_f32_16x16x32_bf16(Bt[n][k], At[m][k], acc[ai][bj][m][n], 0, 0, 0); __builtin_amdgcn_s_setprio(0); } while (0)
; #define PG8_WAIT_V(n) asm volatile("s_waitcnt vmcnt(" #n ")" ::: "memory")
; #define PG8_WAIT_L(n) asm volatile("s_waitcnt lgkmcnt(" #n ")" ::: "memory")
; #define PG8_BAR __builtin_amdgcn_s_barrier()
; #define PG8_SCHED __builtin_amdgcn_sched_barrier(0)
; template <class Epi>
; DI void gemm_phase(LAS unsigned char* lds, const int wid, const Gemm g, const Order& S, const Epi& E) {
;     ...
;             PG8_LDB(B0, 1, 0); PG8_LDB(B1, 1, 1); PG8_SCHED; PG8_LDA(At, 1, 0); PG8_STAGE(PG8_SA(0, 1), a2 + hstepA, voffA);
;             PG8_WAIT_V(8); PG8_WAIT_L(0); PG8_BAR; PG8_MMA(0, 0, At, B0); PG8_MMA(0, 1, At, B1); PG8_BAR; PG8_SCHED;
;             PG8_LDA(At, 1, 1); PG8_STAGE(PG8_SB(1, 0), b3, voffB); PG8_STAGE(PG8_SB(1, 1), b3 + hstepB, voffB); PG8_STAGE(PG8_SA(1, 0), a3, voffA);
;             PG8_WAIT_V(8); PG8_WAIT_L(0); PG8_BAR; PG8_MMA(1, 0, At, B0); PG8_MMA(1, 1, At, B1); PG8_BAR; PG8_SCHED;
;         }
;         if (wr == 0) PG8_BAR;
	s_nop 3
	ds_read_b128 v[16:19], v168
	ds_read_b128 v[20:23], v168 offset:1024
	ds_read_b128 v[24:27], v168 offset:2048
	ds_read_b128 v[28:31], v168 offset:3072
	ds_read_b128 v[152:155], v236
	ds_read_b128 v[156:159], v236 offset:1024
	ds_read_b128 v[190:193], v236 offset:2048
	ds_read_b128 v[194:197], v236 offset:3072
	s_add_u32 s52, s58, 0x10000
	s_addc_u32 s53, s59, 0
	s_mov_b32 m0, s51
	v_lshl_add_u64 v[56:57], s[52:53], 0, v[160:161]
	ds_read_b128 v[48:51], v207 offset:32768
	ds_read_b128 v[52:55], v207 offset:33792
	ds_read_b128 v[198:201], v207 offset:34816
	ds_read_b128 v[236:239], v207 offset:35840
	ds_read_b128 v[240:243], v207 offset:36864
	ds_read_b128 v[244:247], v207 offset:37888
	ds_read_b128 v[248:251], v207 offset:38912
	ds_read_b128 v[170:173], v207 offset:39936
	global_load_lds_dwordx4 v[56:57], off
	v_lshl_add_u64 v[56:57], s[52:53], 0, v[164:165]
	s_mov_b32 m0, s60
	s_nop 0
	global_load_lds_dwordx4 v[56:57], off
	s_waitcnt vmcnt(8)
	s_waitcnt lgkmcnt(0)
	s_barrier
	s_setprio 1
	v_mfma_f32_16x16x32_bf16 v[56:59], v[16:19], v[48:51], v[64:67]
	v_mfma_f32_16x16x32_bf16 v[132:135], v[20:23], v[52:55], v[56:59]
	v_mfma_f32_16x16x32_bf16 v[56:59], v[24:27], v[48:51], v[68:71]
	v_mfma_f32_16x16x32_bf16 v[128:131], v[28:31], v[52:55], v[56:59]
	v_mfma_f32_16x16x32_bf16 v[56:59], v[16:19], v[198:201], v[72:75]
	v_mfma_f32_16x16x32_bf16 v[116:119], v[20:23], v[236:239], v[56:59]
	v_mfma_f32_16x16x32_bf16 v[56:59], v[24:27], v[198:201], v[76:79]
	v_mfma_f32_16x16x32_bf16 v[112:115], v[28:31], v[236:239], v[56:59]
	v_mfma_f32_16x16x32_bf16 v[56:59], v[16:19], v[240:243], v[80:83]
	v_mfma_f32_16x16x32_bf16 v[108:111], v[20:23], v[244:247], v[56:59]
	v_mfma_f32_16x16x32_bf16 v[56:59], v[24:27], v[240:243], v[84:87]
	v_mfma_f32_16x16x32_bf16 v[104:107], v[28:31], v[244:247], v[56:59]
	v_mfma_f32_16x16x32_bf16 v[56:59], v[16:19], v[248:251], v[88:91]
	v_mfma_f32_16x16x32_bf16 v[100:103], v[20:23], v[170:173], v[56:59]
	v_mfma_f32_16x16x32_bf16 v[56:59], v[24:27], v[248:251], v[92:95]
	v_mfma_f32_16x16x32_bf16 v[96:99], v[28:31], v[170:173], v[56:59]
	v_mfma_f32_16x16x32_bf16 v[56:59], v[152:155], v[48:51], v[216:219]
	v_mfma_f32_16x16x32_bf16 v[32:35], v[190:193], v[48:51], v[32:35]
	v_mfma_f32_16x16x32_bf16 v[60:63], v[156:159], v[52:55], v[56:59]
	v_mfma_f32_16x16x32_bf16 v[56:59], v[194:197], v[52:55], v[32:35]
	v_mfma_f32_16x16x32_bf16 v[32:35], v[152:155], v[198:201], v[36:39]
	v_mfma_f32_16x16x32_bf16 v[52:55], v[156:159], v[236:239], v[32:35]
	v_mfma_f32_16x16x32_bf16 v[32:35], v[190:193], v[198:201], v[40:43]
	v_mfma_f32_16x16x32_bf16 v[48:51], v[194:197], v[236:239], v[32:35]
	v_mfma_f32_16x16x32_bf16 v[32:35], v[152:155], v[240:243], v[44:47]
	v_mfma_f32_16x16x32_bf16 v[44:47], v[156:159], v[244:247], v[32:35]
	v_mfma_f32_16x16x32_bf16 v[32:35], v[190:193], v[240:243], v[174:177]
	v_mfma_f32_16x16x32_bf16 v[40:43], v[194:197], v[244:247], v[32:35]
	v_mfma_f32_16x16x32_bf16 v[32:35], v[152:155], v[248:251], v[178:181]
	v_mfma_f32_16x16x32_bf16 v[36:39], v[156:159], v[170:173], v[32:35]
	v_mfma_f32_16x16x32_bf16 v[32:35], v[190:193], v[248:251], v[182:185]
	v_mfma_f32_16x16x32_bf16 v[32:35], v[194:197], v[170:173], v[32:35]
	s_setprio 0
	s_barrier
	s_mov_b32 m0, s76
	v_lshl_add_u64 v[64:65], v[202:203], 0, s[28:29]
	s_add_u32 s52, s56, 0x10080
	ds_read_b128 v[170:173], v207 offset:49152
	ds_read_b128 v[174:177], v207 offset:50176
	ds_read_b128 v[178:181], v207 offset:51200
	ds_read_b128 v[182:185], v207 offset:52224
	ds_read_b128 v[198:201], v207 offset:53248
	ds_read_b128 v[216:219], v207 offset:54272
	ds_read_b128 v[236:239], v207 offset:55296
	ds_read_b128 v[240:243], v207 offset:56320
	global_load_lds_dwordx4 v[64:65], off
	v_lshl_add_u64 v[64:65], v[214:215], 0, s[28:29]
	s_mov_b32 m0, s74
	s_addc_u32 s53, s57, 0
	global_load_lds_dwordx4 v[64:65], off
	v_lshl_add_u64 v[64:65], s[52:53], 0, v[162:163]
	s_mov_b32 m0, s54
	s_nop 0
	global_load_lds_dwordx4 v[64:65], off
	v_lshl_add_u64 v[64:65], s[52:53], 0, v[166:167]
	s_mov_b32 m0, s55
	s_nop 0
	global_load_lds_dwordx4 v[64:65], off
	v_lshl_add_u64 v[64:65], v[252:253], 0, s[28:29]
	s_mov_b32 m0, s61
	s_nop 0
	global_load_lds_dwordx4 v[64:65], off
	v_lshl_add_u64 v[64:65], v[208:209], 0, s[28:29]
	s_mov_b32 m0, s62
	s_nop 0
	global_load_lds_dwordx4 v[64:65], off
	s_waitcnt vmcnt(8)
	s_waitcnt lgkmcnt(0)
	s_barrier
	s_setprio 1
	v_mfma_f32_16x16x32_bf16 v[64:67], v[16:19], v[170:173], v[210:213]
	v_mfma_f32_16x16x32_bf16 v[92:95], v[20:23], v[174:177], v[64:67]
	v_mfma_f32_16x16x32_bf16 v[64:67], v[24:27], v[170:173], v[220:223]
	v_mfma_f32_16x16x32_bf16 v[88:91], v[28:31], v[174:177], v[64:67]
	v_mfma_f32_16x16x32_bf16 v[64:67], v[16:19], v[178:181], v[136:139]
	v_mfma_f32_16x16x32_bf16 v[84:87], v[20:23], v[182:185], v[64:67]
	v_mfma_f32_16x16x32_bf16 v[64:67], v[24:27], v[178:181], v[140:143]
	v_mfma_f32_16x16x32_bf16 v[80:83], v[28:31], v[182:185], v[64:67]
	v_mfma_f32_16x16x32_bf16 v[64:67], v[16:19], v[198:201], v[144:147]
	v_mfma_f32_16x16x32_bf16 v[0:3], v[16:19], v[236:239], v[0:3]
	v_mfma_f32_16x16x32_bf16 v[76:79], v[20:23], v[216:219], v[64:67]
	v_mfma_f32_16x16x32_bf16 v[64:67], v[24:27], v[198:201], v[148:151]
	v_mfma_f32_16x16x32_bf16 v[68:71], v[20:23], v[240:243], v[0:3]
	v_mfma_f32_16x16x32_bf16 v[0:3], v[24:27], v[236:239], v[4:7]
	v_mfma_f32_16x16x32_bf16 v[72:75], v[28:31], v[216:219], v[64:67]
	v_mfma_f32_16x16x32_bf16 v[64:67], v[28:31], v[240:243], v[0:3]
	v_mfma_f32_16x16x32_bf16 v[0:3], v[152:155], v[170:173], v[8:11]
	v_mfma_f32_16x16x32_bf16 v[28:31], v[156:159], v[174:177], v[0:3]
	v_mfma_f32_16x16x32_bf16 v[0:3], v[190:193], v[170:173], v[12:15]
	v_mfma_f32_16x16x32_bf16 v[24:27], v[194:197], v[174:177], v[0:3]
	v_mfma_f32_16x16x32_bf16 v[0:3], v[152:155], v[178:181], v[224:227]
	v_mfma_f32_16x16x32_bf16 v[20:23], v[156:159], v[182:185], v[0:3]
	v_mfma_f32_16x16x32_bf16 v[0:3], v[190:193], v[178:181], v[228:231]
	v_mfma_f32_16x16x32_bf16 v[16:19], v[194:197], v[182:185], v[0:3]
	v_mfma_f32_16x16x32_bf16 v[0:3], v[152:155], v[198:201], v[232:235]
	v_mfma_f32_16x16x32_bf16 v[12:15], v[156:159], v[216:219], v[0:3]
	v_mfma_f32_16x16x32_bf16 v[0:3], v[190:193], v[198:201], v[186:189]
	v_mfma_f32_16x16x32_bf16 v[8:11], v[194:197], v[216:219], v[0:3]
	v_mfma_f32_16x16x32_bf16 v[0:3], v[152:155], v[236:239], v[120:123]
	v_mfma_f32_16x16x32_bf16 v[4:7], v[156:159], v[240:243], v[0:3]
	v_mfma_f32_16x16x32_bf16 v[0:3], v[190:193], v[236:239], v[124:127]
	v_mfma_f32_16x16x32_bf16 v[0:3], v[194:197], v[240:243], v[0:3]
	s_setprio 0
	s_barrier
	s_andn2_b64 vcc, exec, s[30:31]
	s_cbranch_vccnz .LBB0_633
	s_barrier

; #define PG8_STAGE(bufoff, gbase, voff) do { _Pragma("unroll") for (int _i = 0; _i < 2; ++_i) \
;         __builtin_amdgcn_global_load_lds((const unsigned*)((const char*)(gbase) + (voff)[_i]), (LAS unsigned*)(lds + (bufoff) + ldsw + _i * 8192), 16, 0, 0); } while (0)
; #define PG8_LDA(dst, b, h) do { _Pragma("unroll") for (int m = 0; m < 4; ++m) _Pragma("unroll") for (int k = 0; k < 2; ++k) dst[m][k] = *(const LAS bf16x8*)(lds + PG8_SA(b, h) + aoff + m * 2048 + k * 1024); } while (0)
; #define PG8_LDB(dst, b, h) do { _Pragma("unroll") for (int n = 0; n < 2; ++n) _Pragma("unroll") for (int k = 0; k < 2; ++k) dst[n][k] = *(const LAS bf16x8*)(lds + PG8_SB(b, h) + boff + n * 2048 + k * 1024); } while (0)
; #define PG8_MMA(ai, bj, At, Bt) do { __builtin_amdgcn_s_setprio(1); _Pragma("unroll") for (int m = 0; m < 4; ++m) _Pragma("unroll") for (int n = 0; n < 2; ++n) _Pragma("unroll") for (int k = 0; k < 2; ++k) \
;         acc[ai][bj][m][n] = __builtin_amdgcn_mfma_f32_16x16x32_bf16(Bt[n][k], At[m][k], acc[ai][bj][m][n], 0, 0, 0); __builtin_amdgcn_s_setprio(0); } while (0)
; template <class Epi>
; DI void gemm_phase(LAS unsigned char* lds, const int wid, const Gemm g, const Order& S, const Epi& E) {
;     ...
;         const bool has_next = S.next(ui + 1, nxt);
;         const char* nA = has_next ? (const char*)(g.A + (size_t)nxt.g * g.gsA + (size_t)nxt.pm * BM * g.lda) : cA;
;         const char* nB = has_next ? (const char*)(g.Bt + (size_t)nxt.g * g.gsB + (size_t)nxt.pn * BM * g.ldb) : cB;
;         for (int t = 0; t < nt; t += 2) {
;             const bool last = (t == nt - 2);
;             const char* a1 = cA + (size_t)(t + 1) * kstep;
;             const char* a2 = last ? nA : cA + (size_t)(t + 2) * kstep; const char* b2 = last ? nB : cB + (size_t)(t + 2) * kstep;
;             const char* a3 = a2 + kstep; const char* b3 = b2 + kstep;
;             PG8_LDB(B0, 0, 0); PG8_LDB(B1, 0, 1); PG8_SCHED; PG8_LDA(At, 0, 0); PG8_STAGE(PG8_SA(1, 1), a1 + hstepA, voffA);
;             PG8_WAIT_V(8); PG8_WAIT_L(0); PG8_BAR; PG8_MMA(0, 0, At, B0); PG8_MMA(0, 1, At, B1); PG8_BAR; PG8_SCHED;
;             PG8_LDA(At, 0, 1); PG8_STAGE(PG8_SB(0, 0), b2, voffB); PG8_STAGE(PG8_SB(0, 1), b2 + hstepB, voffB); PG8_STAGE(PG8_SA(0, 0), a2, voffA);
;             PG8_WAIT_V(8); PG8_WAIT_L(0); PG8_BAR; PG8_MMA(1, 0, At, B0); PG8_MMA(1, 1, At, B1); PG8_BAR; PG8_SCHED;
.LBB0_750:
	s_ashr_i32 s37, s36, 31
	s_lshl_b64 s[40:41], s[36:37], 16
	s_add_u32 s40, s6, s40
	s_addc_u32 s41, s7, s41
	s_and_b64 s[42:43], s[8:9], exec
	s_cselect_b32 s51, s41, s49
	s_cselect_b32 s50, s40, s48
	s_ashr_i32 s39, s38, 31
	s_lshl_b64 s[42:43], s[38:39], 16
	s_add_u32 s42, s21, s42
	s_addc_u32 s43, s25, s43
	s_add_u32 s64, s48, 0x8080
	ds_read_b128 v[0:3], v152
	ds_read_b128 v[4:7], v152 offset:1024
	ds_read_b128 v[8:11], v152 offset:2048
	ds_read_b128 v[12:15], v152 offset:3072
	ds_read_b128 v[16:19], v153
	ds_read_b128 v[20:23], v153 offset:1024
	ds_read_b128 v[24:27], v153 offset:2048
	ds_read_b128 v[28:31], v153 offset:3072
	s_addc_u32 s65, s49, 0
	s_add_u32 s48, s50, 0x8000
	s_addc_u32 s49, s51, 0
	s_and_b64 s[66:67], s[8:9], exec
	s_cselect_b32 s46, s42, s46
	s_cselect_b32 s47, s43, s47
	s_add_u32 s66, s46, 0x8000
	s_addc_u32 s67, s47, 0
	s_mov_b32 m0, s57
	v_lshl_add_u64 v[64:65], s[64:65], 0, v[128:129]
	s_waitcnt vmcnt(0)
	ds_read_b128 v[32:35], v154
	ds_read_b128 v[36:39], v154 offset:1024
	ds_read_b128 v[40:43], v154 offset:2048
	ds_read_b128 v[44:47], v154 offset:3072
	ds_read_b128 v[48:51], v154 offset:4096
	ds_read_b128 v[52:55], v154 offset:5120
	ds_read_b128 v[56:59], v154 offset:6144
	ds_read_b128 v[60:63], v154 offset:7168
	global_load_lds_dwordx4 v[64:65], off
	v_lshl_add_u64 v[64:65], s[64:65], 0, v[132:133]
	s_mov_b32 m0, s58
	s_nop 0
	global_load_lds_dwordx4 v[64:65], off
	s_waitcnt vmcnt(8)
	s_waitcnt lgkmcnt(0)
	s_barrier
	s_setprio 1
	v_mfma_f32_16x16x32_bf16 v[64:67], v[0:3], v[32:35], 0
	v_mfma_f32_16x16x32_bf16 v[68:71], v[8:11], v[32:35], 0
	v_mfma_f32_16x16x32_bf16 v[72:75], v[0:3], v[40:43], 0
	v_mfma_f32_16x16x32_bf16 v[76:79], v[8:11], v[40:43], 0
	v_mfma_f32_16x16x32_bf16 v[80:83], v[0:3], v[48:51], 0
	v_mfma_f32_16x16x32_bf16 v[84:87], v[8:11], v[48:51], 0
	v_mfma_f32_16x16x32_bf16 v[88:91], v[0:3], v[56:59], 0
	v_mfma_f32_16x16x32_bf16 v[92:95], v[8:11], v[56:59], 0
	v_mfma_f32_16x16x32_bf16 v[64:67], v[4:7], v[36:39], v[64:67]
	v_mfma_f32_16x16x32_bf16 v[68:71], v[12:15], v[36:39], v[68:71]
	v_mfma_f32_16x16x32_bf16 v[72:75], v[4:7], v[44:47], v[72:75]
	v_mfma_f32_16x16x32_bf16 v[76:79], v[12:15], v[44:47], v[76:79]
	v_mfma_f32_16x16x32_bf16 v[80:83], v[4:7], v[52:55], v[80:83]
	v_mfma_f32_16x16x32_bf16 v[84:87], v[12:15], v[52:55], v[84:87]
	v_mfma_f32_16x16x32_bf16 v[88:91], v[4:7], v[60:63], v[88:91]
	v_mfma_f32_16x16x32_bf16 v[104:107], v[12:15], v[60:63], v[92:95]
	v_mfma_f32_16x16x32_bf16 v[92:95], v[16:19], v[32:35], 0
	v_mfma_f32_16x16x32_bf16 v[32:35], v[24:27], v[32:35], 0
	v_mfma_f32_16x16x32_bf16 v[108:111], v[20:23], v[36:39], v[92:95]
	v_mfma_f32_16x16x32_bf16 v[32:35], v[28:31], v[36:39], v[32:35]
	v_mfma_f32_16x16x32_bf16 v[36:39], v[16:19], v[40:43], 0
	v_mfma_f32_16x16x32_bf16 v[40:43], v[24:27], v[40:43], 0
	v_mfma_f32_16x16x32_bf16 v[36:39], v[20:23], v[44:47], v[36:39]
	v_mfma_f32_16x16x32_bf16 v[40:43], v[28:31], v[44:47], v[40:43]
	v_mfma_f32_16x16x32_bf16 v[44:47], v[16:19], v[48:51], 0
	v_mfma_f32_16x16x32_bf16 v[48:51], v[24:27], v[48:51], 0
	v_mfma_f32_16x16x32_bf16 v[44:47], v[20:23], v[52:55], v[44:47]
	v_mfma_f32_16x16x32_bf16 v[48:51], v[28:31], v[52:55], v[48:51]
	v_mfma_f32_16x16x32_bf16 v[52:55], v[16:19], v[56:59], 0
	v_mfma_f32_16x16x32_bf16 v[140:143], v[20:23], v[60:63], v[52:55]
	v_mfma_f32_16x16x32_bf16 v[52:55], v[24:27], v[56:59], 0
	v_mfma_f32_16x16x32_bf16 v[144:147], v[28:31], v[60:63], v[52:55]
	s_setprio 0
	s_barrier
	s_mov_b32 m0, s59
	v_lshl_add_u64 v[148:149], s[46:47], 0, v[130:131]
	s_nop 2
	ds_read_b128 v[52:55], v154 offset:16384
	ds_read_b128 v[56:59], v154 offset:17408
	ds_read_b128 v[60:63], v154 offset:18432
	ds_read_b128 v[92:95], v154 offset:19456
	ds_read_b128 v[96:99], v154 offset:20480
	ds_read_b128 v[100:103], v154 offset:21504
	ds_read_b128 v[112:115], v154 offset:22528
	ds_read_b128 v[116:119], v154 offset:23552
	global_load_lds_dwordx4 v[148:149], off
	v_lshl_add_u64 v[212:213], s[46:47], 0, v[134:135]
	s_mov_b32 m0, s60
	v_lshl_add_u64 v[120:121], s[66:67], 0, v[130:131]
	global_load_lds_dwordx4 v[212:213], off
	s_mov_b32 m0, s61
	v_lshl_add_u64 v[214:215], s[50:51], 0, v[128:129]
	global_load_lds_dwordx4 v[120:121], off
	v_lshl_add_u64 v[120:121], s[66:67], 0, v[134:135]
	s_mov_b32 m0, s62
	v_lshl_add_u64 v[252:253], s[50:51], 0, v[132:133]
	global_load_lds_dwordx4 v[120:121], off
	s_mov_b32 m0, s26
	s_nop 0
	global_load_lds_dwordx4 v[214:215], off
	s_mov_b32 m0, s27
	s_nop 0
	global_load_lds_dwordx4 v[252:253], off
	s_waitcnt vmcnt(8)
	s_waitcnt lgkmcnt(0)
	s_barrier
	s_setprio 1
	v_mfma_f32_16x16x32_bf16 v[120:123], v[0:3], v[52:55], 0
	v_mfma_f32_16x16x32_bf16 v[156:159], v[4:7], v[56:59], v[120:123]
	v_mfma_f32_16x16x32_bf16 v[120:123], v[8:11], v[52:55], 0
	v_mfma_f32_16x16x32_bf16 v[160:163], v[12:15], v[56:59], v[120:123]
	v_mfma_f32_16x16x32_bf16 v[120:123], v[0:3], v[60:63], 0
	v_mfma_f32_16x16x32_bf16 v[164:167], v[4:7], v[92:95], v[120:123]
	v_mfma_f32_16x16x32_bf16 v[120:123], v[8:11], v[60:63], 0
	v_mfma_f32_16x16x32_bf16 v[168:171], v[12:15], v[92:95], v[120:123]
	v_mfma_f32_16x16x32_bf16 v[120:123], v[0:3], v[96:99], 0
	v_mfma_f32_16x16x32_bf16 v[0:3], v[0:3], v[112:115], 0
	v_mfma_f32_16x16x32_bf16 v[172:175], v[4:7], v[100:103], v[120:123]
	v_mfma_f32_16x16x32_bf16 v[0:3], v[4:7], v[116:119], v[0:3]
	v_mfma_f32_16x16x32_bf16 v[4:7], v[8:11], v[112:115], 0
	v_mfma_f32_16x16x32_bf16 v[120:123], v[8:11], v[96:99], 0
	v_mfma_f32_16x16x32_bf16 v[4:7], v[12:15], v[116:119], v[4:7]
	v_mfma_f32_16x16x32_bf16 v[176:179], v[12:15], v[100:103], v[120:123]
	v_mfma_f32_16x16x32_bf16 v[12:15], v[24:27], v[52:55], 0
	v_mfma_f32_16x16x32_bf16 v[180:183], v[28:31], v[56:59], v[12:15]
	v_mfma_f32_16x16x32_bf16 v[12:15], v[16:19], v[60:63], 0
	v_mfma_f32_16x16x32_bf16 v[184:187], v[20:23], v[92:95], v[12:15]
	v_mfma_f32_16x16x32_bf16 v[12:15], v[24:27], v[60:63], 0
	v_mfma_f32_16x16x32_bf16 v[188:191], v[28:31], v[92:95], v[12:15]
	v_mfma_f32_16x16x32_bf16 v[12:15], v[16:19], v[96:99], 0
	v_mfma_f32_16x16x32_bf16 v[192:195], v[20:23], v[100:103], v[12:15]
	v_mfma_f32_16x16x32_bf16 v[12:15], v[24:27], v[96:99], 0
	v_mfma_f32_16x16x32_bf16 v[8:11], v[16:19], v[52:55], 0
	v_mfma_f32_16x16x32_bf16 v[196:199], v[28:31], v[100:103], v[12:15]
	v_mfma_f32_16x16x32_bf16 v[12:15], v[16:19], v[112:115], 0
	v_mfma_f32_16x16x32_bf16 v[8:11], v[20:23], v[56:59], v[8:11]
	v_mfma_f32_16x16x32_bf16 v[200:203], v[20:23], v[116:119], v[12:15]
	v_mfma_f32_16x16x32_bf16 v[12:15], v[24:27], v[112:115], 0
	v_mfma_f32_16x16x32_bf16 v[204:207], v[28:31], v[116:119], v[12:15]
	s_setprio 0
	s_barrier
; #define PG8_STAGE(bufoff, gbase, voff) do { _Pragma("unroll") for (int _i = 0; _i < 2; ++_i) \
;         __builtin_amdgcn_global_load_lds((const unsigned*)((const char*)(gbase) + (voff)[_i]), (LAS unsigned*)(lds + (bufoff) + ldsw + _i * 8192), 16, 0, 0); } while (0)
; #define PG8_LDA(dst, b, h) do { _Pragma("unroll") for (int m = 0; m < 4; ++m) _Pragma("unroll") for (int k = 0; k < 2; ++k) dst[m][k] = *(const LAS bf16x8*)(lds + PG8_SA(b, h) + aoff + m * 2048 + k * 1024); } while (0)
; #define PG8_LDB(dst, b, h) do { _Pragma("unroll") for (int n = 0; n < 2; ++n) _Pragma("unroll") for (int k = 0; k < 2; ++k) dst[n][k] = *(const LAS bf16x8*)(lds + PG8_SB(b, h) + boff + n * 2048 + k * 1024); } while (0)
; #define PG8_MMA(ai, bj, At, Bt) do { __builtin_amdgcn_s_setprio(1); _Pragma("unroll") for (int m = 0; m < 4; ++m) _Pragma("unroll") for (int n = 0; n < 2; ++n) _Pragma("unroll") for (int k = 0; k < 2; ++k) \
;         acc[ai][bj][m][n] = __builtin_amdgcn_mfma_f32_16x16x32_bf16(Bt[n][k], At[m][k], acc[ai][bj][m][n], 0, 0, 0); __builtin_amdgcn_s_setprio(0); } while (0)
; #define PG8_WAIT_V(n) asm volatile("s_waitcnt vmcnt(" #n ")" ::: "memory")
; #define PG8_WAIT_L(n) asm volatile("s_waitcnt lgkmcnt(" #n ")" ::: "memory")
; #define PG8_BAR __builtin_amdgcn_s_barrier()
; #define PG8_SCHED __builtin_amdgcn_sched_barrier(0)
; template <class Epi>
; DI void gemm_phase(LAS unsigned char* lds, const int wid, const Gemm g, const Order& S, const Epi& E) {
;     ...
;             PG8_LDB(B0, 1, 0); PG8_LDB(B1, 1, 1); PG8_SCHED; PG8_LDA(At, 1, 0); PG8_STAGE(PG8_SA(0, 1), a2 + hstepA, voffA);
;             PG8_WAIT_V(8); PG8_WAIT_L(0); PG8_BAR; PG8_MMA(0, 0, At, B0); PG8_MMA(0, 1, At, B1); PG8_BAR; PG8_SCHED;
;             PG8_LDA(At, 1, 1); PG8_STAGE(PG8_SB(1, 0), b3, voffB); PG8_STAGE(PG8_SB(1, 1), b3 + hstepB, voffB); PG8_STAGE(PG8_SA(1, 0), a3, voffA);
;             PG8_WAIT_V(8); PG8_WAIT_L(0); PG8_BAR; PG8_MMA(1, 0, At, B0); PG8_MMA(1, 1, At, B1); PG8_BAR; PG8_SCHED;
;         }
;         if (wr == 0) PG8_BAR;
	s_add_i32 s37, 0, 0x18000
	v_add_u32_e32 v20, s37, v151
	s_add_i32 s39, 0, 0x1c000
	s_nop 1
	ds_read_b128 v[12:15], v20
	ds_read_b128 v[16:19], v20 offset:1024
	ds_read_b128 v[24:27], v20 offset:2048
	ds_read_b128 v[208:211], v20 offset:3072
	v_add_u32_e32 v20, s39, v151
	ds_read_b128 v[216:219], v20
	ds_read_b128 v[220:223], v20 offset:1024
	ds_read_b128 v[224:227], v20 offset:2048
	ds_read_b128 v[228:231], v20 offset:3072
	s_mov_b32 m0, s45
	v_lshl_add_u64 v[52:53], s[48:49], 0, v[128:129]
	ds_read_b128 v[20:23], v154 offset:32768
	ds_read_b128 v[28:31], v154 offset:33792
	ds_read_b128 v[56:59], v154 offset:34816
	ds_read_b128 v[232:235], v154 offset:35840
	ds_read_b128 v[236:239], v154 offset:36864
	ds_read_b128 v[240:243], v154 offset:37888
	ds_read_b128 v[244:247], v154 offset:38912
	ds_read_b128 v[248:251], v154 offset:39936
	global_load_lds_dwordx4 v[52:53], off
	v_lshl_add_u64 v[52:53], s[48:49], 0, v[132:133]
	s_mov_b32 m0, s52
	s_nop 0
	global_load_lds_dwordx4 v[52:53], off
	s_waitcnt vmcnt(8)
	s_waitcnt lgkmcnt(0)
	s_barrier
	s_setprio 1
	v_mfma_f32_16x16x32_bf16 v[52:55], v[12:15], v[20:23], v[64:67]
	v_mfma_f32_16x16x32_bf16 v[112:115], v[16:19], v[28:31], v[52:55]
	v_mfma_f32_16x16x32_bf16 v[52:55], v[24:27], v[20:23], v[68:71]
	v_mfma_f32_16x16x32_bf16 v[116:119], v[208:211], v[28:31], v[52:55]
	v_mfma_f32_16x16x32_bf16 v[52:55], v[12:15], v[56:59], v[72:75]
	v_mfma_f32_16x16x32_bf16 v[96:99], v[16:19], v[232:235], v[52:55]
	v_mfma_f32_16x16x32_bf16 v[52:55], v[24:27], v[56:59], v[76:79]
	v_mfma_f32_16x16x32_bf16 v[100:103], v[208:211], v[232:235], v[52:55]
	v_mfma_f32_16x16x32_bf16 v[52:55], v[12:15], v[236:239], v[80:83]
	v_mfma_f32_16x16x32_bf16 v[92:95], v[16:19], v[240:243], v[52:55]
	v_mfma_f32_16x16x32_bf16 v[52:55], v[24:27], v[236:239], v[84:87]
	v_mfma_f32_16x16x32_bf16 v[84:87], v[208:211], v[240:243], v[52:55]
	v_mfma_f32_16x16x32_bf16 v[52:55], v[12:15], v[244:247], v[88:91]
	v_mfma_f32_16x16x32_bf16 v[60:63], v[16:19], v[248:251], v[52:55]
	v_mfma_f32_16x16x32_bf16 v[52:55], v[24:27], v[244:247], v[104:107]
	v_mfma_f32_16x16x32_bf16 v[52:55], v[208:211], v[248:251], v[52:55]
	v_mfma_f32_16x16x32_bf16 v[64:67], v[216:219], v[20:23], v[108:111]
	v_mfma_f32_16x16x32_bf16 v[20:23], v[224:227], v[20:23], v[32:35]
	v_mfma_f32_16x16x32_bf16 v[124:127], v[228:231], v[28:31], v[20:23]
	v_mfma_f32_16x16x32_bf16 v[20:23], v[216:219], v[56:59], v[36:39]
	v_mfma_f32_16x16x32_bf16 v[108:111], v[220:223], v[232:235], v[20:23]
	v_mfma_f32_16x16x32_bf16 v[20:23], v[224:227], v[56:59], v[40:43]
	v_mfma_f32_16x16x32_bf16 v[104:107], v[228:231], v[232:235], v[20:23]
	v_mfma_f32_16x16x32_bf16 v[20:23], v[216:219], v[236:239], v[44:47]
	v_mfma_f32_16x16x32_bf16 v[88:91], v[220:223], v[240:243], v[20:23]
	v_mfma_f32_16x16x32_bf16 v[20:23], v[224:227], v[236:239], v[48:51]
	v_mfma_f32_16x16x32_bf16 v[80:83], v[228:231], v[240:243], v[20:23]
	v_mfma_f32_16x16x32_bf16 v[20:23], v[216:219], v[244:247], v[140:143]
	v_mfma_f32_16x16x32_bf16 v[56:59], v[220:223], v[248:251], v[20:23]
	v_mfma_f32_16x16x32_bf16 v[20:23], v[224:227], v[244:247], v[144:147]
	v_mfma_f32_16x16x32_bf16 v[120:123], v[220:223], v[28:31], v[64:67]
	v_mfma_f32_16x16x32_bf16 v[48:51], v[228:231], v[248:251], v[20:23]
	s_setprio 0
	s_barrier
	s_add_i32 s37, s37, s94
	s_nop 2
	v_lshl_add_u64 v[20:21], v[148:149], 0, s[28:29]
	s_mov_b32 m0, s37
	ds_read_b128 v[32:35], v154 offset:49152
	ds_read_b128 v[40:43], v154 offset:50176
	ds_read_b128 v[140:143], v154 offset:51200
	ds_read_b128 v[144:147], v154 offset:52224
	ds_read_b128 v[232:235], v154 offset:53248
	ds_read_b128 v[236:239], v154 offset:54272
	ds_read_b128 v[240:243], v154 offset:55296
	ds_read_b128 v[244:247], v154 offset:56320
	global_load_lds_dwordx4 v[20:21], off
	s_add_i32 m0, s37, 0x2000
	s_add_u32 s46, s46, 0x8080
	v_lshl_add_u64 v[20:21], v[212:213], 0, s[28:29]
	s_addc_u32 s47, s47, 0
	s_add_i32 s37, s39, s94
	global_load_lds_dwordx4 v[20:21], off
	v_lshl_add_u64 v[20:21], s[46:47], 0, v[130:131]
	s_mov_b32 m0, s37
	s_nop 0
	global_load_lds_dwordx4 v[20:21], off
	v_lshl_add_u64 v[20:21], s[46:47], 0, v[134:135]
	s_add_i32 m0, s37, 0x2000
	s_nop 0
	global_load_lds_dwordx4 v[20:21], off
	v_lshl_add_u64 v[20:21], v[214:215], 0, s[28:29]
	s_mov_b32 m0, s53
	s_nop 0
	global_load_lds_dwordx4 v[20:21], off
	v_lshl_add_u64 v[20:21], v[252:253], 0, s[28:29]
	s_mov_b32 m0, s54
	s_nop 0
	global_load_lds_dwordx4 v[20:21], off
	s_waitcnt vmcnt(8)
	s_waitcnt lgkmcnt(0)
	s_barrier
	s_setprio 1
	v_mfma_f32_16x16x32_bf16 v[20:23], v[12:15], v[32:35], v[156:159]
	v_mfma_f32_16x16x32_bf16 v[76:79], v[16:19], v[40:43], v[20:23]
	v_mfma_f32_16x16x32_bf16 v[20:23], v[24:27], v[32:35], v[160:163]
	v_mfma_f32_16x16x32_bf16 v[68:71], v[208:211], v[40:43], v[20:23]
	v_mfma_f32_16x16x32_bf16 v[20:23], v[12:15], v[140:143], v[164:167]
	v_mfma_f32_16x16x32_bf16 v[44:47], v[16:19], v[144:147], v[20:23]
	v_mfma_f32_16x16x32_bf16 v[20:23], v[24:27], v[140:143], v[168:171]
	v_mfma_f32_16x16x32_bf16 v[36:39], v[208:211], v[144:147], v[20:23]
	v_mfma_f32_16x16x32_bf16 v[20:23], v[12:15], v[232:235], v[172:175]
	v_mfma_f32_16x16x32_bf16 v[0:3], v[12:15], v[240:243], v[0:3]
	v_mfma_f32_16x16x32_bf16 v[28:31], v[16:19], v[236:239], v[20:23]
	v_mfma_f32_16x16x32_bf16 v[20:23], v[24:27], v[232:235], v[176:179]
	v_mfma_f32_16x16x32_bf16 v[12:15], v[16:19], v[244:247], v[0:3]
	v_mfma_f32_16x16x32_bf16 v[0:3], v[24:27], v[240:243], v[4:7]
	v_mfma_f32_16x16x32_bf16 v[20:23], v[208:211], v[236:239], v[20:23]
	v_mfma_f32_16x16x32_bf16 v[4:7], v[208:211], v[244:247], v[0:3]
	v_mfma_f32_16x16x32_bf16 v[0:3], v[216:219], v[32:35], v[8:11]
	v_mfma_f32_16x16x32_bf16 v[72:75], v[220:223], v[40:43], v[0:3]
	v_mfma_f32_16x16x32_bf16 v[0:3], v[224:227], v[32:35], v[180:183]
	v_mfma_f32_16x16x32_bf16 v[64:67], v[228:231], v[40:43], v[0:3]
	v_mfma_f32_16x16x32_bf16 v[0:3], v[216:219], v[140:143], v[184:187]
	v_mfma_f32_16x16x32_bf16 v[40:43], v[220:223], v[144:147], v[0:3]
	v_mfma_f32_16x16x32_bf16 v[0:3], v[224:227], v[140:143], v[188:191]
	v_mfma_f32_16x16x32_bf16 v[32:35], v[228:231], v[144:147], v[0:3]
	v_mfma_f32_16x16x32_bf16 v[0:3], v[216:219], v[232:235], v[192:195]
	v_mfma_f32_16x16x32_bf16 v[24:27], v[220:223], v[236:239], v[0:3]
	v_mfma_f32_16x16x32_bf16 v[0:3], v[224:227], v[232:235], v[196:199]
	v_mfma_f32_16x16x32_bf16 v[16:19], v[228:231], v[236:239], v[0:3]
	v_mfma_f32_16x16x32_bf16 v[0:3], v[216:219], v[240:243], v[200:203]
	v_mfma_f32_16x16x32_bf16 v[8:11], v[220:223], v[244:247], v[0:3]
	v_mfma_f32_16x16x32_bf16 v[0:3], v[224:227], v[240:243], v[204:207]
	v_mfma_f32_16x16x32_bf16 v[0:3], v[228:231], v[244:247], v[0:3]
	s_setprio 0
	s_barrier
	s_andn2_b64 vcc, exec, s[30:31]
	s_cbranch_vccnz .LBB0_752
	s_barrier

; #define PG8_STAGE(bufoff, gbase, voff) do { _Pragma("unroll") for (int _i = 0; _i < 2; ++_i) \
;         __builtin_amdgcn_global_load_lds((const unsigned*)((const char*)(gbase) + (voff)[_i]), (LAS unsigned*)(lds + (bufoff) + ldsw + _i * 8192), 16, 0, 0); } while (0)
; #define PG8_LDA(dst, b, h) do { _Pragma("unroll") for (int m = 0; m < 4; ++m) _Pragma("unroll") for (int k = 0; k < 2; ++k) dst[m][k] = *(const LAS bf16x8*)(lds + PG8_SA(b, h) + aoff + m * 2048 + k * 1024); } while (0)
; #define PG8_LDB(dst, b, h) do { _Pragma("unroll") for (int n = 0; n < 2; ++n) _Pragma("unroll") for (int k = 0; k < 2; ++k) dst[n][k] = *(const LAS bf16x8*)(lds + PG8_SB(b, h) + boff + n * 2048 + k * 1024); } while (0)
; #define PG8_MMA(ai, bj, At, Bt) do { __builtin_amdgcn_s_setprio(1); _Pragma("unroll") for (int m = 0; m < 4; ++m) _Pragma("unroll") for (int n = 0; n < 2; ++n) _Pragma("unroll") for (int k = 0; k < 2; ++k) \
;         acc[ai][bj][m][n] = __builtin_amdgcn_mfma_f32_16x16x32_bf16(Bt[n][k], At[m][k], acc[ai][bj][m][n], 0, 0, 0); __builtin_amdgcn_s_setprio(0); } while (0)
; template <class Epi>
; DI void gemm_phase(LAS unsigned char* lds, const int wid, const Gemm g, const Order& S, const Epi& E) {
;     ...
;         const bool has_next = S.next(ui + 1, nxt);
;         const char* nA = has_next ? (const char*)(g.A + (size_t)nxt.g * g.gsA + (size_t)nxt.pm * BM * g.lda) : cA;
;         const char* nB = has_next ? (const char*)(g.Bt + (size_t)nxt.g * g.gsB + (size_t)nxt.pn * BM * g.ldb) : cB;
;         for (int t = 0; t < nt; t += 2) {
;             const bool last = (t == nt - 2);
;             const char* a1 = cA + (size_t)(t + 1) * kstep;
;             const char* a2 = last ? nA : cA + (size_t)(t + 2) * kstep; const char* b2 = last ? nB : cB + (size_t)(t + 2) * kstep;
;             const char* a3 = a2 + kstep; const char* b3 = b2 + kstep;
;             PG8_LDB(B0, 0, 0); PG8_LDB(B1, 0, 1); PG8_SCHED; PG8_LDA(At, 0, 0); PG8_STAGE(PG8_SA(1, 1), a1 + hstepA, voffA);
;             PG8_WAIT_V(8); PG8_WAIT_L(0); PG8_BAR; PG8_MMA(0, 0, At, B0); PG8_MMA(0, 1, At, B1); PG8_BAR; PG8_SCHED;
;             PG8_LDA(At, 0, 1); PG8_STAGE(PG8_SB(0, 0), b2, voffB); PG8_STAGE(PG8_SB(0, 1), b2 + hstepB, voffB); PG8_STAGE(PG8_SA(0, 0), a2, voffA);
;             PG8_WAIT_V(8); PG8_WAIT_L(0); PG8_BAR; PG8_MMA(1, 0, At, B0); PG8_MMA(1, 1, At, B1); PG8_BAR; PG8_SCHED;
.LBB0_773:
	s_ashr_i32 s37, s36, 31
	s_lshl_b64 s[40:41], s[36:37], 16
	s_add_u32 s40, s6, s40
	s_addc_u32 s41, s7, s41
	s_and_b64 s[42:43], s[10:11], exec
	s_cselect_b32 s49, s41, s47
	s_cselect_b32 s48, s40, s46
	s_ashr_i32 s39, s38, 31
	s_lshl_b64 s[42:43], s[38:39], 16
	s_add_u32 s42, s8, s42
	s_addc_u32 s43, s9, s43
	s_add_u32 s62, s46, 0x8080
	ds_read_b128 v[0:3], v147
	ds_read_b128 v[4:7], v147 offset:1024
	ds_read_b128 v[8:11], v147 offset:2048
	ds_read_b128 v[12:15], v147 offset:3072
	ds_read_b128 v[16:19], v148
	ds_read_b128 v[20:23], v148 offset:1024
	ds_read_b128 v[24:27], v148 offset:2048
	ds_read_b128 v[28:31], v148 offset:3072
	s_addc_u32 s63, s47, 0
	s_add_u32 s46, s48, 0x8000
	s_addc_u32 s47, s49, 0
	s_and_b64 s[64:65], s[10:11], exec
	s_cselect_b32 s44, s42, s44
	s_cselect_b32 s45, s43, s45
	s_add_u32 s64, s44, 0x8000
	s_addc_u32 s65, s45, 0
	s_mov_b32 m0, s54
	v_lshl_add_u64 v[64:65], s[62:63], 0, v[128:129]
	s_waitcnt vmcnt(0)
	ds_read_b128 v[32:35], v149
	ds_read_b128 v[36:39], v149 offset:1024
	ds_read_b128 v[40:43], v149 offset:2048
	ds_read_b128 v[44:47], v149 offset:3072
	ds_read_b128 v[48:51], v149 offset:4096
	ds_read_b128 v[52:55], v149 offset:5120
	ds_read_b128 v[56:59], v149 offset:6144
	ds_read_b128 v[60:63], v149 offset:7168
	global_load_lds_dwordx4 v[64:65], off
	v_lshl_add_u64 v[64:65], s[62:63], 0, v[132:133]
	s_mov_b32 m0, s55
	s_nop 0
	global_load_lds_dwordx4 v[64:65], off
	s_waitcnt vmcnt(8)
	s_waitcnt lgkmcnt(0)
	s_barrier
	s_setprio 1
	v_mfma_f32_16x16x32_bf16 v[80:83], v[0:3], v[48:51], 0
	v_mfma_f32_16x16x32_bf16 v[96:99], v[4:7], v[52:55], v[80:83]
	v_mfma_f32_16x16x32_bf16 v[80:83], v[8:11], v[48:51], 0
	v_mfma_f32_16x16x32_bf16 v[100:103], v[12:15], v[52:55], v[80:83]
	v_mfma_f32_16x16x32_bf16 v[80:83], v[0:3], v[56:59], 0
	v_mfma_f32_16x16x32_bf16 v[64:67], v[0:3], v[32:35], 0
	v_mfma_f32_16x16x32_bf16 v[68:71], v[8:11], v[32:35], 0
	v_mfma_f32_16x16x32_bf16 v[72:75], v[0:3], v[40:43], 0
	v_mfma_f32_16x16x32_bf16 v[76:79], v[8:11], v[40:43], 0
	v_mfma_f32_16x16x32_bf16 v[104:107], v[4:7], v[60:63], v[80:83]
	v_mfma_f32_16x16x32_bf16 v[80:83], v[8:11], v[56:59], 0
	v_mfma_f32_16x16x32_bf16 v[64:67], v[4:7], v[36:39], v[64:67]
	v_mfma_f32_16x16x32_bf16 v[68:71], v[12:15], v[36:39], v[68:71]
	v_mfma_f32_16x16x32_bf16 v[72:75], v[4:7], v[44:47], v[72:75]
	v_mfma_f32_16x16x32_bf16 v[76:79], v[12:15], v[44:47], v[76:79]
	v_mfma_f32_16x16x32_bf16 v[108:111], v[12:15], v[60:63], v[80:83]
	v_mfma_f32_16x16x32_bf16 v[80:83], v[16:19], v[32:35], 0
	v_mfma_f32_16x16x32_bf16 v[32:35], v[24:27], v[32:35], 0
	v_mfma_f32_16x16x32_bf16 v[112:115], v[20:23], v[36:39], v[80:83]
	v_mfma_f32_16x16x32_bf16 v[32:35], v[28:31], v[36:39], v[32:35]
	v_mfma_f32_16x16x32_bf16 v[36:39], v[16:19], v[40:43], 0
	v_mfma_f32_16x16x32_bf16 v[40:43], v[24:27], v[40:43], 0
	v_mfma_f32_16x16x32_bf16 v[36:39], v[20:23], v[44:47], v[36:39]
	v_mfma_f32_16x16x32_bf16 v[40:43], v[28:31], v[44:47], v[40:43]
	v_mfma_f32_16x16x32_bf16 v[44:47], v[16:19], v[48:51], 0
	v_mfma_f32_16x16x32_bf16 v[116:119], v[20:23], v[52:55], v[44:47]
	v_mfma_f32_16x16x32_bf16 v[44:47], v[24:27], v[48:51], 0
	v_mfma_f32_16x16x32_bf16 v[48:51], v[28:31], v[52:55], v[44:47]
	v_mfma_f32_16x16x32_bf16 v[44:47], v[16:19], v[56:59], 0
	v_mfma_f32_16x16x32_bf16 v[52:55], v[20:23], v[60:63], v[44:47]
	v_mfma_f32_16x16x32_bf16 v[44:47], v[24:27], v[56:59], 0
	v_mfma_f32_16x16x32_bf16 v[120:123], v[28:31], v[60:63], v[44:47]
	s_setprio 0
	s_barrier
	s_mov_b32 m0, s56
	v_lshl_add_u64 v[144:145], s[44:45], 0, v[130:131]
	s_nop 2
	ds_read_b128 v[44:47], v149 offset:16384
	ds_read_b128 v[56:59], v149 offset:17408
	ds_read_b128 v[60:63], v149 offset:18432
	ds_read_b128 v[80:83], v149 offset:19456
	ds_read_b128 v[84:87], v149 offset:20480
	ds_read_b128 v[88:91], v149 offset:21504
	ds_read_b128 v[92:95], v149 offset:22528
	ds_read_b128 v[124:127], v149 offset:23552
	global_load_lds_dwordx4 v[144:145], off
	v_lshl_add_u64 v[252:253], s[44:45], 0, v[134:135]
	s_mov_b32 m0, s57
	v_lshl_add_u64 v[140:141], s[64:65], 0, v[130:131]
	global_load_lds_dwordx4 v[252:253], off
	s_mov_b32 m0, s58
	v_lshl_add_u64 v[136:137], s[48:49], 0, v[128:129]
	global_load_lds_dwordx4 v[140:141], off
	v_lshl_add_u64 v[140:141], s[64:65], 0, v[134:135]
	s_mov_b32 m0, s59
	v_lshl_add_u64 v[138:139], s[48:49], 0, v[132:133]
	global_load_lds_dwordx4 v[140:141], off
	s_mov_b32 m0, s21
	s_nop 0
	global_load_lds_dwordx4 v[136:137], off
	s_mov_b32 m0, s25
	s_nop 0
	global_load_lds_dwordx4 v[138:139], off
	s_waitcnt vmcnt(8)
	s_waitcnt lgkmcnt(0)
	s_barrier
	s_setprio 1
	v_mfma_f32_16x16x32_bf16 v[140:143], v[0:3], v[44:47], 0
	v_mfma_f32_16x16x32_bf16 v[156:159], v[0:3], v[60:63], 0
	v_mfma_f32_16x16x32_bf16 v[164:167], v[0:3], v[84:87], 0
	v_mfma_f32_16x16x32_bf16 v[0:3], v[0:3], v[92:95], 0
	v_mfma_f32_16x16x32_bf16 v[172:175], v[4:7], v[124:127], v[0:3]
	v_mfma_f32_16x16x32_bf16 v[0:3], v[8:11], v[92:95], 0
	v_mfma_f32_16x16x32_bf16 v[152:155], v[8:11], v[44:47], 0
	v_mfma_f32_16x16x32_bf16 v[160:163], v[8:11], v[60:63], 0
	v_mfma_f32_16x16x32_bf16 v[168:171], v[8:11], v[84:87], 0
	v_mfma_f32_16x16x32_bf16 v[8:11], v[12:15], v[124:127], v[0:3]
	v_mfma_f32_16x16x32_bf16 v[140:143], v[4:7], v[56:59], v[140:143]
	v_mfma_f32_16x16x32_bf16 v[152:155], v[12:15], v[56:59], v[152:155]
	v_mfma_f32_16x16x32_bf16 v[156:159], v[4:7], v[80:83], v[156:159]
	v_mfma_f32_16x16x32_bf16 v[160:163], v[12:15], v[80:83], v[160:163]
	v_mfma_f32_16x16x32_bf16 v[164:167], v[4:7], v[88:91], v[164:167]
	v_mfma_f32_16x16x32_bf16 v[168:171], v[12:15], v[88:91], v[168:171]
	v_mfma_f32_16x16x32_bf16 v[0:3], v[16:19], v[44:47], 0
	v_mfma_f32_16x16x32_bf16 v[12:15], v[20:23], v[56:59], v[0:3]
	v_mfma_f32_16x16x32_bf16 v[0:3], v[24:27], v[44:47], 0
	v_mfma_f32_16x16x32_bf16 v[176:179], v[28:31], v[56:59], v[0:3]
	v_mfma_f32_16x16x32_bf16 v[0:3], v[16:19], v[60:63], 0
	v_mfma_f32_16x16x32_bf16 v[180:183], v[20:23], v[80:83], v[0:3]
	v_mfma_f32_16x16x32_bf16 v[0:3], v[24:27], v[60:63], 0
	v_mfma_f32_16x16x32_bf16 v[184:187], v[28:31], v[80:83], v[0:3]
	v_mfma_f32_16x16x32_bf16 v[0:3], v[16:19], v[84:87], 0
	v_mfma_f32_16x16x32_bf16 v[188:191], v[20:23], v[88:91], v[0:3]
	v_mfma_f32_16x16x32_bf16 v[0:3], v[24:27], v[84:87], 0
	v_mfma_f32_16x16x32_bf16 v[192:195], v[28:31], v[88:91], v[0:3]
	v_mfma_f32_16x16x32_bf16 v[0:3], v[16:19], v[92:95], 0
	v_mfma_f32_16x16x32_bf16 v[196:199], v[20:23], v[124:127], v[0:3]
	v_mfma_f32_16x16x32_bf16 v[0:3], v[24:27], v[92:95], 0
	v_mfma_f32_16x16x32_bf16 v[200:203], v[28:31], v[124:127], v[0:3]
	s_setprio 0
	s_barrier
; #define PG8_STAGE(bufoff, gbase, voff) do { _Pragma("unroll") for (int _i = 0; _i < 2; ++_i) \
;         __builtin_amdgcn_global_load_lds((const unsigned*)((const char*)(gbase) + (voff)[_i]), (LAS unsigned*)(lds + (bufoff) + ldsw + _i * 8192), 16, 0, 0); } while (0)
; #define PG8_LDA(dst, b, h) do { _Pragma("unroll") for (int m = 0; m < 4; ++m) _Pragma("unroll") for (int k = 0; k < 2; ++k) dst[m][k] = *(const LAS bf16x8*)(lds + PG8_SA(b, h) + aoff + m * 2048 + k * 1024); } while (0)
; #define PG8_LDB(dst, b, h) do { _Pragma("unroll") for (int n = 0; n < 2; ++n) _Pragma("unroll") for (int k = 0; k < 2; ++k) dst[n][k] = *(const LAS bf16x8*)(lds + PG8_SB(b, h) + boff + n * 2048 + k * 1024); } while (0)
; #define PG8_MMA(ai, bj, At, Bt) do { __builtin_amdgcn_s_setprio(1); _Pragma("unroll") for (int m = 0; m < 4; ++m) _Pragma("unroll") for (int n = 0; n < 2; ++n) _Pragma("unroll") for (int k = 0; k < 2; ++k) \
;         acc[ai][bj][m][n] = __builtin_amdgcn_mfma_f32_16x16x32_bf16(Bt[n][k], At[m][k], acc[ai][bj][m][n], 0, 0, 0); __builtin_amdgcn_s_setprio(0); } while (0)
; #define PG8_WAIT_V(n) asm volatile("s_waitcnt vmcnt(" #n ")" ::: "memory")
; #define PG8_WAIT_L(n) asm volatile("s_waitcnt lgkmcnt(" #n ")" ::: "memory")
; #define PG8_BAR __builtin_amdgcn_s_barrier()
; #define PG8_SCHED __builtin_amdgcn_sched_barrier(0)
; template <class Epi>
; DI void gemm_phase(LAS unsigned char* lds, const int wid, const Gemm g, const Order& S, const Epi& E) {
;     ...
;             PG8_LDB(B0, 1, 0); PG8_LDB(B1, 1, 1); PG8_SCHED; PG8_LDA(At, 1, 0); PG8_STAGE(PG8_SA(0, 1), a2 + hstepA, voffA);
;             PG8_WAIT_V(8); PG8_WAIT_L(0); PG8_BAR; PG8_MMA(0, 0, At, B0); PG8_MMA(0, 1, At, B1); PG8_BAR; PG8_SCHED;
;             PG8_LDA(At, 1, 1); PG8_STAGE(PG8_SB(1, 0), b3, voffB); PG8_STAGE(PG8_SB(1, 1), b3 + hstepB, voffB); PG8_STAGE(PG8_SA(1, 0), a3, voffA);
;             PG8_WAIT_V(8); PG8_WAIT_L(0); PG8_BAR; PG8_MMA(1, 0, At, B0); PG8_MMA(1, 1, At, B1); PG8_BAR; PG8_SCHED;
;         }
;         if (wr == 0) PG8_BAR;
	s_add_i32 s37, 0, 0x18000
	s_nop 3
	v_add_u32_e32 v0, s37, v146
	s_add_i32 s39, 0, 0x1c000
	ds_read_b128 v[20:23], v0
	ds_read_b128 v[24:27], v0 offset:1024
	ds_read_b128 v[204:207], v0 offset:2048
	ds_read_b128 v[208:211], v0 offset:3072
	v_add_u32_e32 v0, s39, v146
	ds_read_b128 v[216:219], v0
	ds_read_b128 v[220:223], v0 offset:1024
	ds_read_b128 v[224:227], v0 offset:2048
	ds_read_b128 v[228:231], v0 offset:3072
	s_mov_b32 m0, s26
	v_lshl_add_u64 v[44:45], s[46:47], 0, v[128:129]
	ds_read_b128 v[0:3], v149 offset:32768
	ds_read_b128 v[4:7], v149 offset:33792
	ds_read_b128 v[16:19], v149 offset:34816
	ds_read_b128 v[28:31], v149 offset:35840
	ds_read_b128 v[124:127], v149 offset:36864
	ds_read_b128 v[232:235], v149 offset:37888
	ds_read_b128 v[236:239], v149 offset:38912
	ds_read_b128 v[240:243], v149 offset:39936
	global_load_lds_dwordx4 v[44:45], off
	v_lshl_add_u64 v[44:45], s[46:47], 0, v[132:133]
	s_mov_b32 m0, s27
	s_nop 0
	global_load_lds_dwordx4 v[44:45], off
	s_waitcnt vmcnt(8)
	s_waitcnt lgkmcnt(0)
	s_barrier
	s_setprio 1
	v_mfma_f32_16x16x32_bf16 v[44:47], v[20:23], v[0:3], v[64:67]
	v_mfma_f32_16x16x32_bf16 v[80:83], v[24:27], v[4:7], v[44:47]
	v_mfma_f32_16x16x32_bf16 v[44:47], v[204:207], v[0:3], v[68:71]
	v_mfma_f32_16x16x32_bf16 v[84:87], v[208:211], v[4:7], v[44:47]
	v_mfma_f32_16x16x32_bf16 v[44:47], v[20:23], v[16:19], v[72:75]
	v_mfma_f32_16x16x32_bf16 v[88:91], v[24:27], v[28:31], v[44:47]
	v_mfma_f32_16x16x32_bf16 v[44:47], v[204:207], v[16:19], v[76:79]
	v_mfma_f32_16x16x32_bf16 v[92:95], v[208:211], v[28:31], v[44:47]
	v_mfma_f32_16x16x32_bf16 v[44:47], v[20:23], v[124:127], v[96:99]
	v_mfma_f32_16x16x32_bf16 v[96:99], v[24:27], v[232:235], v[44:47]
	v_mfma_f32_16x16x32_bf16 v[44:47], v[204:207], v[124:127], v[100:103]
	v_mfma_f32_16x16x32_bf16 v[100:103], v[208:211], v[232:235], v[44:47]
	v_mfma_f32_16x16x32_bf16 v[44:47], v[20:23], v[236:239], v[104:107]
	v_mfma_f32_16x16x32_bf16 v[104:107], v[24:27], v[240:243], v[44:47]
	v_mfma_f32_16x16x32_bf16 v[44:47], v[204:207], v[236:239], v[108:111]
	v_mfma_f32_16x16x32_bf16 v[108:111], v[208:211], v[240:243], v[44:47]
	v_mfma_f32_16x16x32_bf16 v[44:47], v[216:219], v[0:3], v[112:115]
	v_mfma_f32_16x16x32_bf16 v[0:3], v[224:227], v[0:3], v[32:35]
	v_mfma_f32_16x16x32_bf16 v[56:59], v[228:231], v[4:7], v[0:3]
	v_mfma_f32_16x16x32_bf16 v[0:3], v[216:219], v[16:19], v[36:39]
	v_mfma_f32_16x16x32_bf16 v[60:63], v[220:223], v[4:7], v[44:47]
	v_mfma_f32_16x16x32_bf16 v[44:47], v[220:223], v[28:31], v[0:3]
	v_mfma_f32_16x16x32_bf16 v[0:3], v[224:227], v[16:19], v[40:43]
	v_mfma_f32_16x16x32_bf16 v[40:43], v[228:231], v[28:31], v[0:3]
	v_mfma_f32_16x16x32_bf16 v[0:3], v[216:219], v[124:127], v[116:119]
	v_mfma_f32_16x16x32_bf16 v[28:31], v[220:223], v[232:235], v[0:3]
	v_mfma_f32_16x16x32_bf16 v[0:3], v[224:227], v[124:127], v[48:51]
	v_mfma_f32_16x16x32_bf16 v[16:19], v[228:231], v[232:235], v[0:3]
	v_mfma_f32_16x16x32_bf16 v[0:3], v[216:219], v[236:239], v[52:55]
	v_mfma_f32_16x16x32_bf16 v[4:7], v[220:223], v[240:243], v[0:3]
	v_mfma_f32_16x16x32_bf16 v[0:3], v[224:227], v[236:239], v[120:123]
	v_mfma_f32_16x16x32_bf16 v[0:3], v[228:231], v[240:243], v[0:3]
	s_setprio 0
	s_barrier
	s_add_i32 s37, s37, s94
	v_lshl_add_u64 v[48:49], v[144:145], 0, s[28:29]
	s_mov_b32 m0, s37
	ds_read_b128 v[32:35], v149 offset:49152
	ds_read_b128 v[36:39], v149 offset:50176
	ds_read_b128 v[232:235], v149 offset:51200
	ds_read_b128 v[236:239], v149 offset:52224
	ds_read_b128 v[240:243], v149 offset:53248
	ds_read_b128 v[244:247], v149 offset:54272
	ds_read_b128 v[248:251], v149 offset:55296
	ds_read_b128 v[212:215], v149 offset:56320
	global_load_lds_dwordx4 v[48:49], off
	s_add_i32 m0, s37, 0x2000
	s_add_u32 s44, s44, 0x8080
	v_lshl_add_u64 v[48:49], v[252:253], 0, s[28:29]
	s_addc_u32 s45, s45, 0
	s_add_i32 s37, s39, s94
	global_load_lds_dwordx4 v[48:49], off
	v_lshl_add_u64 v[48:49], s[44:45], 0, v[130:131]
	s_mov_b32 m0, s37
	s_nop 0
	global_load_lds_dwordx4 v[48:49], off
	v_lshl_add_u64 v[48:49], s[44:45], 0, v[134:135]
	s_add_i32 m0, s37, 0x2000
	s_nop 0
	global_load_lds_dwordx4 v[48:49], off
	v_lshl_add_u64 v[48:49], v[136:137], 0, s[28:29]
	s_mov_b32 m0, s50
	s_nop 0
	global_load_lds_dwordx4 v[48:49], off
	v_lshl_add_u64 v[48:49], v[138:139], 0, s[28:29]
	s_mov_b32 m0, s51
	s_nop 0
	global_load_lds_dwordx4 v[48:49], off
	s_waitcnt vmcnt(8)
	s_waitcnt lgkmcnt(0)
	s_barrier
	s_setprio 1
	v_mfma_f32_16x16x32_bf16 v[48:51], v[20:23], v[32:35], v[140:143]
	v_mfma_f32_16x16x32_bf16 v[124:127], v[24:27], v[36:39], v[48:51]
	v_mfma_f32_16x16x32_bf16 v[48:51], v[204:207], v[32:35], v[152:155]
	v_mfma_f32_16x16x32_bf16 v[120:123], v[208:211], v[36:39], v[48:51]
	v_mfma_f32_16x16x32_bf16 v[48:51], v[20:23], v[232:235], v[156:159]
	v_mfma_f32_16x16x32_bf16 v[116:119], v[24:27], v[236:239], v[48:51]
	v_mfma_f32_16x16x32_bf16 v[48:51], v[204:207], v[232:235], v[160:163]
	v_mfma_f32_16x16x32_bf16 v[112:115], v[208:211], v[236:239], v[48:51]
	v_mfma_f32_16x16x32_bf16 v[48:51], v[20:23], v[240:243], v[164:167]
	v_mfma_f32_16x16x32_bf16 v[76:79], v[24:27], v[244:247], v[48:51]
	v_mfma_f32_16x16x32_bf16 v[48:51], v[204:207], v[240:243], v[168:171]
	v_mfma_f32_16x16x32_bf16 v[20:23], v[20:23], v[248:251], v[172:175]
	v_mfma_f32_16x16x32_bf16 v[8:11], v[204:207], v[248:251], v[8:11]
	v_mfma_f32_16x16x32_bf16 v[72:75], v[208:211], v[244:247], v[48:51]
	v_mfma_f32_16x16x32_bf16 v[68:71], v[24:27], v[212:215], v[20:23]
	v_mfma_f32_16x16x32_bf16 v[64:67], v[208:211], v[212:215], v[8:11]
	v_mfma_f32_16x16x32_bf16 v[8:11], v[216:219], v[32:35], v[12:15]
	v_mfma_f32_16x16x32_bf16 v[52:55], v[220:223], v[36:39], v[8:11]
	v_mfma_f32_16x16x32_bf16 v[8:11], v[224:227], v[32:35], v[176:179]
	v_mfma_f32_16x16x32_bf16 v[48:51], v[228:231], v[36:39], v[8:11]
	v_mfma_f32_16x16x32_bf16 v[8:11], v[216:219], v[232:235], v[180:183]
	v_mfma_f32_16x16x32_bf16 v[36:39], v[220:223], v[236:239], v[8:11]
	v_mfma_f32_16x16x32_bf16 v[8:11], v[224:227], v[232:235], v[184:187]
	v_mfma_f32_16x16x32_bf16 v[32:35], v[228:231], v[236:239], v[8:11]
	v_mfma_f32_16x16x32_bf16 v[8:11], v[216:219], v[240:243], v[188:191]
	v_mfma_f32_16x16x32_bf16 v[24:27], v[220:223], v[244:247], v[8:11]
	v_mfma_f32_16x16x32_bf16 v[8:11], v[224:227], v[240:243], v[192:195]
	v_mfma_f32_16x16x32_bf16 v[20:23], v[228:231], v[244:247], v[8:11]
	v_mfma_f32_16x16x32_bf16 v[8:11], v[216:219], v[248:251], v[196:199]
	v_mfma_f32_16x16x32_bf16 v[12:15], v[220:223], v[212:215], v[8:11]
	v_mfma_f32_16x16x32_bf16 v[8:11], v[224:227], v[248:251], v[200:203]
	v_mfma_f32_16x16x32_bf16 v[8:11], v[228:231], v[212:215], v[8:11]
	s_setprio 0
	s_barrier
	s_andn2_b64 vcc, exec, s[30:31]
	s_cbranch_vccnz .LBB0_775
	s_barrier

; #define PG8_STAGE(bufoff, gbase, voff) do { _Pragma("unroll") for (int _i = 0; _i < 2; ++_i) \
;         __builtin_amdgcn_global_load_lds((const unsigned*)((const char*)(gbase) + (voff)[_i]), (LAS unsigned*)(lds + (bufoff) + ldsw + _i * 8192), 16, 0, 0); } while (0)
; #define PG8_LDA(dst, b, h) do { _Pragma("unroll") for (int m = 0; m < 4; ++m) _Pragma("unroll") for (int k = 0; k < 2; ++k) dst[m][k] = *(const LAS bf16x8*)(lds + PG8_SA(b, h) + aoff + m * 2048 + k * 1024); } while (0)
; #define PG8_LDB(dst, b, h) do { _Pragma("unroll") for (int n = 0; n < 2; ++n) _Pragma("unroll") for (int k = 0; k < 2; ++k) dst[n][k] = *(const LAS bf16x8*)(lds + PG8_SB(b, h) + boff + n * 2048 + k * 1024); } while (0)
; #define PG8_MMA(ai, bj, At, Bt) do { __builtin_amdgcn_s_setprio(1); _Pragma("unroll") for (int m = 0; m < 4; ++m) _Pragma("unroll") for (int n = 0; n < 2; ++n) _Pragma("unroll") for (int k = 0; k < 2; ++k) \
;         acc[ai][bj][m][n] = __builtin_amdgcn_mfma_f32_16x16x32_bf16(Bt[n][k], At[m][k], acc[ai][bj][m][n], 0, 0, 0); __builtin_amdgcn_s_setprio(0); } while (0)
; #define PG8_WAIT_V(n) asm volatile("s_waitcnt vmcnt(" #n ")" ::: "memory")
; #define PG8_BAR __builtin_amdgcn_s_barrier()
; template <class Epi>
; DI void gemm_phase(LAS unsigned char* lds, const int wid, const Gemm g, const Order& S, const Epi& E) {
;     ...
;         const bool has_next = S.next(ui + 1, nxt);
;         const char* nA = has_next ? (const char*)(g.A + (size_t)nxt.g * g.gsA + (size_t)nxt.pm * BM * g.lda) : cA;
;         const char* nB = has_next ? (const char*)(g.Bt + (size_t)nxt.g * g.gsB + (size_t)nxt.pn * BM * g.ldb) : cB;
;         for (int t = 0; t < nt; t += 2) {
;             const bool last = (t == nt - 2);
;             const char* a1 = cA + (size_t)(t + 1) * kstep;
;             const char* a2 = last ? nA : cA + (size_t)(t + 2) * kstep; const char* b2 = last ? nB : cB + (size_t)(t + 2) * kstep;
;             const char* a3 = a2 + kstep; const char* b3 = b2 + kstep;
;             PG8_LDB(B0, 0, 0); PG8_LDB(B1, 0, 1); PG8_SCHED; PG8_LDA(At, 0, 0); PG8_STAGE(PG8_SA(1, 1), a1 + hstepA, voffA);
;             PG8_WAIT_V(8); PG8_WAIT_L(0); PG8_BAR; PG8_MMA(0, 0, At, B0); PG8_MMA(0, 1, At, B1); PG8_BAR; PG8_SCHED;
;             PG8_LDA(At, 0, 1); PG8_STAGE(PG8_SB(0, 0), b2, voffB); PG8_STAGE(PG8_SB(0, 1), b2 + hstepB, voffB); PG8_STAGE(PG8_SA(0, 0), a2, voffA);
.LBB0_789:
	s_lshl_b64 s[42:43], s[36:37], 18
	s_add_u32 s29, s8, s42
	s_addc_u32 s37, s9, s43
	s_ashr_i32 s39, s38, 31
	s_lshl_b64 s[42:43], s[38:39], 18
	s_add_u32 s42, s29, s42
	s_addc_u32 s43, s37, s43
	s_and_b64 s[12:13], s[12:13], exec
	s_cselect_b32 s29, s43, s47
	s_cselect_b32 s37, s42, s46
	s_add_u32 s39, s46, 0x100
	v_mov_b32_e32 v0, 0
	s_addc_u32 s61, s47, 0
	s_mov_b32 s62, -2
	ds_read_b128 v[148:151], v145
	ds_read_b128 v[152:155], v145 offset:1024
	ds_read_b128 v[156:159], v145 offset:2048
	ds_read_b128 v[160:163], v145 offset:3072
	ds_read_b128 v[164:167], v146
	ds_read_b128 v[168:171], v146 offset:1024
	ds_read_b128 v[172:175], v146 offset:2048
	ds_read_b128 v[176:179], v146 offset:3072
	s_add_u32 s12, s44, 0x100
	s_addc_u32 s13, s45, 0
	s_cmp_eq_u32 s62, 4
	s_cselect_b32 s49, s41, s13
	s_cselect_b32 s48, s40, s12
	s_cselect_b32 s47, s29, s61
	s_cselect_b32 s46, s37, s39
	v_lshl_add_u64 v[212:213], s[44:45], 0, v[136:137]
	s_add_i32 m0, s21, 0xc000
	ds_read_b128 v[180:183], v147
	ds_read_b128 v[184:187], v147 offset:1024
	ds_read_b128 v[188:191], v147 offset:2048
	ds_read_b128 v[192:195], v147 offset:3072
	ds_read_b128 v[196:199], v147 offset:4096
	ds_read_b128 v[200:203], v147 offset:5120
	ds_read_b128 v[204:207], v147 offset:6144
	ds_read_b128 v[208:211], v147 offset:7168
	global_load_lds_dwordx4 v[212:213], off
	v_lshl_add_u64 v[212:213], s[44:45], 0, v[138:139]
	s_add_i32 m0, s21, 0xe000
	s_nop 0
	global_load_lds_dwordx4 v[212:213], off
	s_waitcnt vmcnt(8)
	s_waitcnt lgkmcnt(0)
	s_barrier
	s_setprio 1
	v_mfma_f32_16x16x32_bf16 v[124:127], v[148:151], v[180:183], 0
	v_mfma_f32_16x16x32_bf16 v[120:123], v[156:159], v[180:183], 0
	v_mfma_f32_16x16x32_bf16 v[116:119], v[148:151], v[188:191], 0
	v_mfma_f32_16x16x32_bf16 v[112:115], v[156:159], v[188:191], 0
	v_mfma_f32_16x16x32_bf16 v[100:103], v[148:151], v[196:199], 0
	v_mfma_f32_16x16x32_bf16 v[96:99], v[156:159], v[196:199], 0
	v_mfma_f32_16x16x32_bf16 v[84:87], v[148:151], v[204:207], 0
	v_mfma_f32_16x16x32_bf16 v[80:83], v[156:159], v[204:207], 0
	v_mfma_f32_16x16x32_bf16 v[124:127], v[152:155], v[184:187], v[124:127]
	v_mfma_f32_16x16x32_bf16 v[120:123], v[160:163], v[184:187], v[120:123]
	v_mfma_f32_16x16x32_bf16 v[116:119], v[152:155], v[192:195], v[116:119]
	v_mfma_f32_16x16x32_bf16 v[112:115], v[160:163], v[192:195], v[112:115]
	v_mfma_f32_16x16x32_bf16 v[100:103], v[152:155], v[200:203], v[100:103]
	v_mfma_f32_16x16x32_bf16 v[96:99], v[160:163], v[200:203], v[96:99]
	v_mfma_f32_16x16x32_bf16 v[84:87], v[152:155], v[208:211], v[84:87]
	v_mfma_f32_16x16x32_bf16 v[80:83], v[160:163], v[208:211], v[80:83]
	v_mfma_f32_16x16x32_bf16 v[108:111], v[164:167], v[180:183], 0
	v_mfma_f32_16x16x32_bf16 v[104:107], v[172:175], v[180:183], 0
	v_mfma_f32_16x16x32_bf16 v[92:95], v[164:167], v[188:191], 0
	v_mfma_f32_16x16x32_bf16 v[88:91], v[172:175], v[188:191], 0
	v_mfma_f32_16x16x32_bf16 v[76:79], v[164:167], v[196:199], 0
	v_mfma_f32_16x16x32_bf16 v[72:75], v[172:175], v[196:199], 0
	v_mfma_f32_16x16x32_bf16 v[68:71], v[164:167], v[204:207], 0
	v_mfma_f32_16x16x32_bf16 v[64:67], v[172:175], v[204:207], 0
	v_mfma_f32_16x16x32_bf16 v[108:111], v[168:171], v[184:187], v[108:111]
	v_mfma_f32_16x16x32_bf16 v[104:107], v[176:179], v[184:187], v[104:107]
	v_mfma_f32_16x16x32_bf16 v[92:95], v[168:171], v[192:195], v[92:95]
	v_mfma_f32_16x16x32_bf16 v[88:91], v[176:179], v[192:195], v[88:91]
	v_mfma_f32_16x16x32_bf16 v[76:79], v[168:171], v[200:203], v[76:79]
	v_mfma_f32_16x16x32_bf16 v[72:75], v[176:179], v[200:203], v[72:75]
	v_mfma_f32_16x16x32_bf16 v[68:71], v[168:171], v[208:211], v[68:71]
	v_mfma_f32_16x16x32_bf16 v[64:67], v[176:179], v[208:211], v[64:67]
	s_setprio 0
	s_barrier
	s_add_i32 s44, s57, s94
	v_lshl_add_u64 v[212:213], s[46:47], 0, v[132:133]
	s_mov_b32 m0, s44
	ds_read_b128 v[180:183], v147 offset:16384
	ds_read_b128 v[184:187], v147 offset:17408
	ds_read_b128 v[188:191], v147 offset:18432
	ds_read_b128 v[192:195], v147 offset:19456
	ds_read_b128 v[196:199], v147 offset:20480
	ds_read_b128 v[200:203], v147 offset:21504
	ds_read_b128 v[204:207], v147 offset:22528
	ds_read_b128 v[208:211], v147 offset:23552
	global_load_lds_dwordx4 v[212:213], off
	s_add_i32 m0, s44, 0x2000
	s_add_u32 s44, s46, 0x20000
	v_lshl_add_u64 v[214:215], s[46:47], 0, v[128:129]
	s_addc_u32 s45, s47, 0
	s_add_i32 s63, s58, s94
	global_load_lds_dwordx4 v[214:215], off
	v_lshl_add_u64 v[216:217], s[44:45], 0, v[132:133]
	s_mov_b32 m0, s63
	v_lshl_add_u64 v[218:219], s[48:49], 0, v[130:131]
	global_load_lds_dwordx4 v[216:217], off
	v_lshl_add_u64 v[216:217], s[44:45], 0, v[128:129]
	s_add_i32 m0, s63, 0x2000
	s_nop 0
	global_load_lds_dwordx4 v[216:217], off
	v_lshl_add_u64 v[216:217], s[48:49], 0, v[134:135]
	s_mov_b32 m0, s21
	s_nop 0
	global_load_lds_dwordx4 v[216:217], off
	s_mov_b32 m0, s25
	s_nop 0
	global_load_lds_dwordx4 v[218:219], off
	s_waitcnt vmcnt(8)
	s_waitcnt lgkmcnt(0)
	s_barrier
; #define PG8_STAGE(bufoff, gbase, voff) do { _Pragma("unroll") for (int _i = 0; _i < 2; ++_i) \
;         __builtin_amdgcn_global_load_lds((const unsigned*)((const char*)(gbase) + (voff)[_i]), (LAS unsigned*)(lds + (bufoff) + ldsw + _i * 8192), 16, 0, 0); } while (0)
; #define PG8_LDA(dst, b, h) do { _Pragma("unroll") for (int m = 0; m < 4; ++m) _Pragma("unroll") for (int k = 0; k < 2; ++k) dst[m][k] = *(const LAS bf16x8*)(lds + PG8_SA(b, h) + aoff + m * 2048 + k * 1024); } while (0)
; #define PG8_LDB(dst, b, h) do { _Pragma("unroll") for (int n = 0; n < 2; ++n) _Pragma("unroll") for (int k = 0; k < 2; ++k) dst[n][k] = *(const LAS bf16x8*)(lds + PG8_SB(b, h) + boff + n * 2048 + k * 1024); } while (0)
; #define PG8_MMA(ai, bj, At, Bt) do { __builtin_amdgcn_s_setprio(1); _Pragma("unroll") for (int m = 0; m < 4; ++m) _Pragma("unroll") for (int n = 0; n < 2; ++n) _Pragma("unroll") for (int k = 0; k < 2; ++k) \
;         acc[ai][bj][m][n] = __builtin_amdgcn_mfma_f32_16x16x32_bf16(Bt[n][k], At[m][k], acc[ai][bj][m][n], 0, 0, 0); __builtin_amdgcn_s_setprio(0); } while (0)
; #define PG8_WAIT_V(n) asm volatile("s_waitcnt vmcnt(" #n ")" ::: "memory")
; #define PG8_WAIT_L(n) asm volatile("s_waitcnt lgkmcnt(" #n ")" ::: "memory")
; #define PG8_BAR __builtin_amdgcn_s_barrier()
; #define PG8_SCHED __builtin_amdgcn_sched_barrier(0)
; template <class Epi>
; DI void gemm_phase(LAS unsigned char* lds, const int wid, const Gemm g, const Order& S, const Epi& E) {
;     ...
;             PG8_WAIT_V(8); PG8_WAIT_L(0); PG8_BAR; PG8_MMA(1, 0, At, B0); PG8_MMA(1, 1, At, B1); PG8_BAR; PG8_SCHED;
;             PG8_LDB(B0, 1, 0); PG8_LDB(B1, 1, 1); PG8_SCHED; PG8_LDA(At, 1, 0); PG8_STAGE(PG8_SA(0, 1), a2 + hstepA, voffA);
;             PG8_WAIT_V(8); PG8_WAIT_L(0); PG8_BAR; PG8_MMA(0, 0, At, B0); PG8_MMA(0, 1, At, B1); PG8_BAR; PG8_SCHED;
	s_setprio 1
	v_mfma_f32_16x16x32_bf16 v[60:63], v[148:151], v[180:183], 0
	v_mfma_f32_16x16x32_bf16 v[56:59], v[156:159], v[180:183], 0
	v_mfma_f32_16x16x32_bf16 v[52:55], v[148:151], v[188:191], 0
	v_mfma_f32_16x16x32_bf16 v[48:51], v[156:159], v[188:191], 0
	v_mfma_f32_16x16x32_bf16 v[36:39], v[148:151], v[196:199], 0
	v_mfma_f32_16x16x32_bf16 v[32:35], v[156:159], v[196:199], 0
	v_mfma_f32_16x16x32_bf16 v[20:23], v[148:151], v[204:207], 0
	v_mfma_f32_16x16x32_bf16 v[16:19], v[156:159], v[204:207], 0
	v_mfma_f32_16x16x32_bf16 v[60:63], v[152:155], v[184:187], v[60:63]
	v_mfma_f32_16x16x32_bf16 v[56:59], v[160:163], v[184:187], v[56:59]
	v_mfma_f32_16x16x32_bf16 v[52:55], v[152:155], v[192:195], v[52:55]
	v_mfma_f32_16x16x32_bf16 v[48:51], v[160:163], v[192:195], v[48:51]
	v_mfma_f32_16x16x32_bf16 v[36:39], v[152:155], v[200:203], v[36:39]
	v_mfma_f32_16x16x32_bf16 v[32:35], v[160:163], v[200:203], v[32:35]
	v_mfma_f32_16x16x32_bf16 v[20:23], v[152:155], v[208:211], v[20:23]
	v_mfma_f32_16x16x32_bf16 v[16:19], v[160:163], v[208:211], v[16:19]
	v_mfma_f32_16x16x32_bf16 v[44:47], v[164:167], v[180:183], 0
	v_mfma_f32_16x16x32_bf16 v[40:43], v[172:175], v[180:183], 0
	v_mfma_f32_16x16x32_bf16 v[28:31], v[164:167], v[188:191], 0
	v_mfma_f32_16x16x32_bf16 v[24:27], v[172:175], v[188:191], 0
	v_mfma_f32_16x16x32_bf16 v[12:15], v[164:167], v[196:199], 0
	v_mfma_f32_16x16x32_bf16 v[8:11], v[172:175], v[196:199], 0
	v_mfma_f32_16x16x32_bf16 v[4:7], v[164:167], v[204:207], 0
	v_mfma_f32_16x16x32_bf16 v[0:3], v[172:175], v[204:207], 0
	v_mfma_f32_16x16x32_bf16 v[44:47], v[168:171], v[184:187], v[44:47]
	v_mfma_f32_16x16x32_bf16 v[40:43], v[176:179], v[184:187], v[40:43]
	v_mfma_f32_16x16x32_bf16 v[28:31], v[168:171], v[192:195], v[28:31]
	v_mfma_f32_16x16x32_bf16 v[24:27], v[176:179], v[192:195], v[24:27]
	v_mfma_f32_16x16x32_bf16 v[12:15], v[168:171], v[200:203], v[12:15]
	v_mfma_f32_16x16x32_bf16 v[8:11], v[176:179], v[200:203], v[8:11]
	v_mfma_f32_16x16x32_bf16 v[4:7], v[168:171], v[208:211], v[4:7]
	v_mfma_f32_16x16x32_bf16 v[0:3], v[176:179], v[208:211], v[0:3]
	s_setprio 0
	s_barrier
	s_add_i32 s63, 0, 0x18000
	s_add_i32 s64, 0, 0x1c000
	v_add_u32_e32 v160, s63, v144
	v_add_u32_e32 v176, s64, v144
	ds_read_b128 v[148:151], v160
	ds_read_b128 v[152:155], v160 offset:1024
	ds_read_b128 v[156:159], v160 offset:2048
	ds_read_b128 v[160:163], v160 offset:3072
	ds_read_b128 v[164:167], v176
	ds_read_b128 v[168:171], v176 offset:1024
	ds_read_b128 v[172:175], v176 offset:2048
	ds_read_b128 v[176:179], v176 offset:3072
	s_add_u32 s44, s48, 0x30000
	s_addc_u32 s45, s49, 0
	s_mov_b32 m0, s26
	v_lshl_add_u64 v[220:221], s[44:45], 0, v[134:135]
	ds_read_b128 v[180:183], v147 offset:32768
	ds_read_b128 v[184:187], v147 offset:33792
	ds_read_b128 v[188:191], v147 offset:34816
	ds_read_b128 v[192:195], v147 offset:35840
	ds_read_b128 v[196:199], v147 offset:36864
	ds_read_b128 v[200:203], v147 offset:37888
	ds_read_b128 v[204:207], v147 offset:38912
	ds_read_b128 v[208:211], v147 offset:39936
	global_load_lds_dwordx4 v[220:221], off
	v_lshl_add_u64 v[220:221], s[44:45], 0, v[130:131]
	s_mov_b32 m0, s27
	s_nop 0
	global_load_lds_dwordx4 v[220:221], off
	s_waitcnt vmcnt(8)
	s_waitcnt lgkmcnt(0)
	s_barrier
	s_setprio 1
	v_mfma_f32_16x16x32_bf16 v[124:127], v[148:151], v[180:183], v[124:127]
	v_mfma_f32_16x16x32_bf16 v[120:123], v[156:159], v[180:183], v[120:123]
	v_mfma_f32_16x16x32_bf16 v[116:119], v[148:151], v[188:191], v[116:119]
	v_mfma_f32_16x16x32_bf16 v[112:115], v[156:159], v[188:191], v[112:115]
	v_mfma_f32_16x16x32_bf16 v[100:103], v[148:151], v[196:199], v[100:103]
	v_mfma_f32_16x16x32_bf16 v[96:99], v[156:159], v[196:199], v[96:99]
	v_mfma_f32_16x16x32_bf16 v[84:87], v[148:151], v[204:207], v[84:87]
	v_mfma_f32_16x16x32_bf16 v[80:83], v[156:159], v[204:207], v[80:83]
	v_mfma_f32_16x16x32_bf16 v[124:127], v[152:155], v[184:187], v[124:127]
	v_mfma_f32_16x16x32_bf16 v[120:123], v[160:163], v[184:187], v[120:123]
	v_mfma_f32_16x16x32_bf16 v[116:119], v[152:155], v[192:195], v[116:119]
	v_mfma_f32_16x16x32_bf16 v[112:115], v[160:163], v[192:195], v[112:115]
	v_mfma_f32_16x16x32_bf16 v[100:103], v[152:155], v[200:203], v[100:103]
	v_mfma_f32_16x16x32_bf16 v[96:99], v[160:163], v[200:203], v[96:99]
	v_mfma_f32_16x16x32_bf16 v[84:87], v[152:155], v[208:211], v[84:87]
	v_mfma_f32_16x16x32_bf16 v[80:83], v[160:163], v[208:211], v[80:83]
	v_mfma_f32_16x16x32_bf16 v[108:111], v[164:167], v[180:183], v[108:111]
	v_mfma_f32_16x16x32_bf16 v[104:107], v[172:175], v[180:183], v[104:107]
	v_mfma_f32_16x16x32_bf16 v[92:95], v[164:167], v[188:191], v[92:95]
	v_mfma_f32_16x16x32_bf16 v[88:91], v[172:175], v[188:191], v[88:91]
	v_mfma_f32_16x16x32_bf16 v[76:79], v[164:167], v[196:199], v[76:79]
	v_mfma_f32_16x16x32_bf16 v[72:75], v[172:175], v[196:199], v[72:75]
	v_mfma_f32_16x16x32_bf16 v[68:71], v[164:167], v[204:207], v[68:71]
	v_mfma_f32_16x16x32_bf16 v[64:67], v[172:175], v[204:207], v[64:67]
	v_mfma_f32_16x16x32_bf16 v[108:111], v[168:171], v[184:187], v[108:111]
	v_mfma_f32_16x16x32_bf16 v[104:107], v[176:179], v[184:187], v[104:107]
	v_mfma_f32_16x16x32_bf16 v[92:95], v[168:171], v[192:195], v[92:95]
	v_mfma_f32_16x16x32_bf16 v[88:91], v[176:179], v[192:195], v[88:91]
	v_mfma_f32_16x16x32_bf16 v[76:79], v[168:171], v[200:203], v[76:79]
	v_mfma_f32_16x16x32_bf16 v[72:75], v[176:179], v[200:203], v[72:75]
	v_mfma_f32_16x16x32_bf16 v[68:71], v[168:171], v[208:211], v[68:71]
	v_mfma_f32_16x16x32_bf16 v[64:67], v[176:179], v[208:211], v[64:67]
	s_setprio 0
	s_barrier
; #define PG8_STAGE(bufoff, gbase, voff) do { _Pragma("unroll") for (int _i = 0; _i < 2; ++_i) \
;         __builtin_amdgcn_global_load_lds((const unsigned*)((const char*)(gbase) + (voff)[_i]), (LAS unsigned*)(lds + (bufoff) + ldsw + _i * 8192), 16, 0, 0); } while (0)
; #define PG8_LDA(dst, b, h) do { _Pragma("unroll") for (int m = 0; m < 4; ++m) _Pragma("unroll") for (int k = 0; k < 2; ++k) dst[m][k] = *(const LAS bf16x8*)(lds + PG8_SA(b, h) + aoff + m * 2048 + k * 1024); } while (0)
; #define PG8_LDB(dst, b, h) do { _Pragma("unroll") for (int n = 0; n < 2; ++n) _Pragma("unroll") for (int k = 0; k < 2; ++k) dst[n][k] = *(const LAS bf16x8*)(lds + PG8_SB(b, h) + boff + n * 2048 + k * 1024); } while (0)
; #define PG8_MMA(ai, bj, At, Bt) do { __builtin_amdgcn_s_setprio(1); _Pragma("unroll") for (int m = 0; m < 4; ++m) _Pragma("unroll") for (int n = 0; n < 2; ++n) _Pragma("unroll") for (int k = 0; k < 2; ++k) \
;         acc[ai][bj][m][n] = __builtin_amdgcn_mfma_f32_16x16x32_bf16(Bt[n][k], At[m][k], acc[ai][bj][m][n], 0, 0, 0); __builtin_amdgcn_s_setprio(0); } while (0)
; #define PG8_WAIT_V(n) asm volatile("s_waitcnt vmcnt(" #n ")" ::: "memory")
; #define PG8_WAIT_L(n) asm volatile("s_waitcnt lgkmcnt(" #n ")" ::: "memory")
; #define PG8_BAR __builtin_amdgcn_s_barrier()
; #define PG8_SCHED __builtin_amdgcn_sched_barrier(0)
; template <class Epi>
; DI void gemm_phase(LAS unsigned char* lds, const int wid, const Gemm g, const Order& S, const Epi& E) {
;     ...
;         for (int t = 0; t < nt; t += 2) {
;             const bool last = (t == nt - 2);
;             const char* a1 = cA + (size_t)(t + 1) * kstep;
;             const char* a2 = last ? nA : cA + (size_t)(t + 2) * kstep; const char* b2 = last ? nB : cB + (size_t)(t + 2) * kstep;
;             const char* a3 = a2 + kstep; const char* b3 = b2 + kstep;
;             PG8_LDB(B0, 0, 0); PG8_LDB(B1, 0, 1); PG8_SCHED; PG8_LDA(At, 0, 0); PG8_STAGE(PG8_SA(1, 1), a1 + hstepA, voffA);
;             PG8_WAIT_V(8); PG8_WAIT_L(0); PG8_BAR; PG8_MMA(0, 0, At, B0); PG8_MMA(0, 1, At, B1); PG8_BAR; PG8_SCHED;
;     ...
;             PG8_LDA(At, 1, 1); PG8_STAGE(PG8_SB(1, 0), b3, voffB); PG8_STAGE(PG8_SB(1, 1), b3 + hstepB, voffB); PG8_STAGE(PG8_SA(1, 0), a3, voffA);
;             PG8_WAIT_V(8); PG8_WAIT_L(0); PG8_BAR; PG8_MMA(1, 0, At, B0); PG8_MMA(1, 1, At, B1); PG8_BAR; PG8_SCHED;
	s_add_i32 s44, s63, s94
	v_lshl_add_u64 v[212:213], v[212:213], 0, s[30:31]
	s_mov_b32 m0, s44
	ds_read_b128 v[180:183], v147 offset:49152
	ds_read_b128 v[184:187], v147 offset:50176
	ds_read_b128 v[188:191], v147 offset:51200
	ds_read_b128 v[192:195], v147 offset:52224
	ds_read_b128 v[196:199], v147 offset:53248
	ds_read_b128 v[200:203], v147 offset:54272
	ds_read_b128 v[204:207], v147 offset:55296
	ds_read_b128 v[208:211], v147 offset:56320
	global_load_lds_dwordx4 v[212:213], off
	s_add_i32 m0, s44, 0x2000
	s_add_u32 s44, s46, 0x20080
	v_lshl_add_u64 v[212:213], v[214:215], 0, s[30:31]
	s_addc_u32 s45, s47, 0
	s_add_i32 s46, s64, s94
	global_load_lds_dwordx4 v[212:213], off
	v_lshl_add_u64 v[212:213], s[44:45], 0, v[132:133]
	s_mov_b32 m0, s46
	s_nop 0
	global_load_lds_dwordx4 v[212:213], off
	v_lshl_add_u64 v[212:213], s[44:45], 0, v[128:129]
	s_add_i32 m0, s46, 0x2000
	s_nop 0
	global_load_lds_dwordx4 v[212:213], off
	v_lshl_add_u64 v[212:213], v[216:217], 0, s[30:31]
	s_mov_b32 m0, s52
	s_nop 0
	global_load_lds_dwordx4 v[212:213], off
	v_lshl_add_u64 v[212:213], v[218:219], 0, s[30:31]
	s_mov_b32 m0, s53
	s_nop 0
	global_load_lds_dwordx4 v[212:213], off
	s_waitcnt vmcnt(8)
	s_waitcnt lgkmcnt(0)
	s_barrier
	s_setprio 1
	v_mfma_f32_16x16x32_bf16 v[60:63], v[148:151], v[180:183], v[60:63]
	v_mfma_f32_16x16x32_bf16 v[56:59], v[156:159], v[180:183], v[56:59]
	v_mfma_f32_16x16x32_bf16 v[52:55], v[148:151], v[188:191], v[52:55]
	v_mfma_f32_16x16x32_bf16 v[48:51], v[156:159], v[188:191], v[48:51]
	v_mfma_f32_16x16x32_bf16 v[36:39], v[148:151], v[196:199], v[36:39]
	v_mfma_f32_16x16x32_bf16 v[32:35], v[156:159], v[196:199], v[32:35]
	v_mfma_f32_16x16x32_bf16 v[20:23], v[148:151], v[204:207], v[20:23]
	v_mfma_f32_16x16x32_bf16 v[16:19], v[156:159], v[204:207], v[16:19]
	v_mfma_f32_16x16x32_bf16 v[60:63], v[152:155], v[184:187], v[60:63]
	v_mfma_f32_16x16x32_bf16 v[56:59], v[160:163], v[184:187], v[56:59]
	v_mfma_f32_16x16x32_bf16 v[52:55], v[152:155], v[192:195], v[52:55]
	v_mfma_f32_16x16x32_bf16 v[48:51], v[160:163], v[192:195], v[48:51]
	v_mfma_f32_16x16x32_bf16 v[36:39], v[152:155], v[200:203], v[36:39]
	v_mfma_f32_16x16x32_bf16 v[32:35], v[160:163], v[200:203], v[32:35]
	v_mfma_f32_16x16x32_bf16 v[20:23], v[152:155], v[208:211], v[20:23]
	v_mfma_f32_16x16x32_bf16 v[16:19], v[160:163], v[208:211], v[16:19]
	v_mfma_f32_16x16x32_bf16 v[44:47], v[164:167], v[180:183], v[44:47]
	v_mfma_f32_16x16x32_bf16 v[40:43], v[172:175], v[180:183], v[40:43]
	v_mfma_f32_16x16x32_bf16 v[28:31], v[164:167], v[188:191], v[28:31]
	v_mfma_f32_16x16x32_bf16 v[24:27], v[172:175], v[188:191], v[24:27]
	v_mfma_f32_16x16x32_bf16 v[12:15], v[164:167], v[196:199], v[12:15]
	v_mfma_f32_16x16x32_bf16 v[8:11], v[172:175], v[196:199], v[8:11]
	v_mfma_f32_16x16x32_bf16 v[4:7], v[164:167], v[204:207], v[4:7]
	v_mfma_f32_16x16x32_bf16 v[0:3], v[172:175], v[204:207], v[0:3]
	v_mfma_f32_16x16x32_bf16 v[44:47], v[168:171], v[184:187], v[44:47]
	v_mfma_f32_16x16x32_bf16 v[40:43], v[176:179], v[184:187], v[40:43]
	v_mfma_f32_16x16x32_bf16 v[28:31], v[168:171], v[192:195], v[28:31]
	v_mfma_f32_16x16x32_bf16 v[24:27], v[176:179], v[192:195], v[24:27]
	v_mfma_f32_16x16x32_bf16 v[12:15], v[168:171], v[200:203], v[12:15]
	v_mfma_f32_16x16x32_bf16 v[8:11], v[176:179], v[200:203], v[8:11]
	v_mfma_f32_16x16x32_bf16 v[4:7], v[168:171], v[208:211], v[4:7]
	v_mfma_f32_16x16x32_bf16 v[0:3], v[176:179], v[208:211], v[0:3]
	s_setprio 0
	s_barrier
	s_add_i32 s62, s62, 2
	s_add_u32 s39, s39, 0x100
	s_addc_u32 s61, s61, 0
	s_cmp_gt_u32 s62, 5
	s_mov_b64 s[44:45], s[12:13]
	s_cbranch_scc0 .LBB0_790
	s_branch .Lpeel_exit_3
.LBB0_790:
	ds_read_b128 v[148:151], v145
	ds_read_b128 v[152:155], v145 offset:1024
	ds_read_b128 v[156:159], v145 offset:2048
	ds_read_b128 v[160:163], v145 offset:3072
	ds_read_b128 v[164:167], v146
	ds_read_b128 v[168:171], v146 offset:1024
	ds_read_b128 v[172:175], v146 offset:2048
	ds_read_b128 v[176:179], v146 offset:3072
	s_add_u32 s12, s44, 0x100
	s_addc_u32 s13, s45, 0
	s_cmp_eq_u32 s62, 4
	s_cselect_b32 s49, s41, s13
	s_cselect_b32 s48, s40, s12
	s_cselect_b32 s47, s29, s61
	s_cselect_b32 s46, s37, s39
	v_lshl_add_u64 v[212:213], s[44:45], 0, v[136:137]
	s_add_i32 m0, s21, 0xc000
	ds_read_b128 v[180:183], v147
	ds_read_b128 v[184:187], v147 offset:1024
	ds_read_b128 v[188:191], v147 offset:2048
	ds_read_b128 v[192:195], v147 offset:3072
	ds_read_b128 v[196:199], v147 offset:4096
	ds_read_b128 v[200:203], v147 offset:5120
	ds_read_b128 v[204:207], v147 offset:6144
	ds_read_b128 v[208:211], v147 offset:7168
	global_load_lds_dwordx4 v[212:213], off
	v_lshl_add_u64 v[212:213], s[44:45], 0, v[138:139]
	s_add_i32 m0, s21, 0xe000
	s_nop 0
	global_load_lds_dwordx4 v[212:213], off
	s_waitcnt vmcnt(8)
	s_waitcnt lgkmcnt(0)
	s_barrier
; #define PG8_STAGE(bufoff, gbase, voff) do { _Pragma("unroll") for (int _i = 0; _i < 2; ++_i) \
;         __builtin_amdgcn_global_load_lds((const unsigned*)((const char*)(gbase) + (voff)[_i]), (LAS unsigned*)(lds + (bufoff) + ldsw + _i * 8192), 16, 0, 0); } while (0)
; #define PG8_LDA(dst, b, h) do { _Pragma("unroll") for (int m = 0; m < 4; ++m) _Pragma("unroll") for (int k = 0; k < 2; ++k) dst[m][k] = *(const LAS bf16x8*)(lds + PG8_SA(b, h) + aoff + m * 2048 + k * 1024); } while (0)
; #define PG8_MMA(ai, bj, At, Bt) do { __builtin_amdgcn_s_setprio(1); _Pragma("unroll") for (int m = 0; m < 4; ++m) _Pragma("unroll") for (int n = 0; n < 2; ++n) _Pragma("unroll") for (int k = 0; k < 2; ++k) \
;         acc[ai][bj][m][n] = __builtin_amdgcn_mfma_f32_16x16x32_bf16(Bt[n][k], At[m][k], acc[ai][bj][m][n], 0, 0, 0); __builtin_amdgcn_s_setprio(0); } while (0)
; #define PG8_WAIT_V(n) asm volatile("s_waitcnt vmcnt(" #n ")" ::: "memory")
; #define PG8_WAIT_L(n) asm volatile("s_waitcnt lgkmcnt(" #n ")" ::: "memory")
; #define PG8_BAR __builtin_amdgcn_s_barrier()
; #define PG8_SCHED __builtin_amdgcn_sched_barrier(0)
; template <class Epi>
; DI void gemm_phase(LAS unsigned char* lds, const int wid, const Gemm g, const Order& S, const Epi& E) {
;     ...
;             PG8_WAIT_V(8); PG8_WAIT_L(0); PG8_BAR; PG8_MMA(0, 0, At, B0); PG8_MMA(0, 1, At, B1); PG8_BAR; PG8_SCHED;
;             PG8_LDA(At, 0, 1); PG8_STAGE(PG8_SB(0, 0), b2, voffB); PG8_STAGE(PG8_SB(0, 1), b2 + hstepB, voffB); PG8_STAGE(PG8_SA(0, 0), a2, voffA);
;             PG8_WAIT_V(8); PG8_WAIT_L(0); PG8_BAR; PG8_MMA(1, 0, At, B0); PG8_MMA(1, 1, At, B1); PG8_BAR; PG8_SCHED;
	s_setprio 1
	v_mfma_f32_16x16x32_bf16 v[124:127], v[148:151], v[180:183], v[124:127]
	v_mfma_f32_16x16x32_bf16 v[120:123], v[156:159], v[180:183], v[120:123]
	v_mfma_f32_16x16x32_bf16 v[116:119], v[148:151], v[188:191], v[116:119]
	v_mfma_f32_16x16x32_bf16 v[112:115], v[156:159], v[188:191], v[112:115]
	v_mfma_f32_16x16x32_bf16 v[100:103], v[148:151], v[196:199], v[100:103]
	v_mfma_f32_16x16x32_bf16 v[96:99], v[156:159], v[196:199], v[96:99]
	v_mfma_f32_16x16x32_bf16 v[84:87], v[148:151], v[204:207], v[84:87]
	v_mfma_f32_16x16x32_bf16 v[80:83], v[156:159], v[204:207], v[80:83]
	v_mfma_f32_16x16x32_bf16 v[124:127], v[152:155], v[184:187], v[124:127]
	v_mfma_f32_16x16x32_bf16 v[120:123], v[160:163], v[184:187], v[120:123]
	v_mfma_f32_16x16x32_bf16 v[116:119], v[152:155], v[192:195], v[116:119]
	v_mfma_f32_16x16x32_bf16 v[112:115], v[160:163], v[192:195], v[112:115]
	v_mfma_f32_16x16x32_bf16 v[100:103], v[152:155], v[200:203], v[100:103]
	v_mfma_f32_16x16x32_bf16 v[96:99], v[160:163], v[200:203], v[96:99]
	v_mfma_f32_16x16x32_bf16 v[84:87], v[152:155], v[208:211], v[84:87]
	v_mfma_f32_16x16x32_bf16 v[80:83], v[160:163], v[208:211], v[80:83]
	v_mfma_f32_16x16x32_bf16 v[108:111], v[164:167], v[180:183], v[108:111]
	v_mfma_f32_16x16x32_bf16 v[104:107], v[172:175], v[180:183], v[104:107]
	v_mfma_f32_16x16x32_bf16 v[92:95], v[164:167], v[188:191], v[92:95]
	v_mfma_f32_16x16x32_bf16 v[88:91], v[172:175], v[188:191], v[88:91]
	v_mfma_f32_16x16x32_bf16 v[76:79], v[164:167], v[196:199], v[76:79]
	v_mfma_f32_16x16x32_bf16 v[72:75], v[172:175], v[196:199], v[72:75]
	v_mfma_f32_16x16x32_bf16 v[68:71], v[164:167], v[204:207], v[68:71]
	v_mfma_f32_16x16x32_bf16 v[64:67], v[172:175], v[204:207], v[64:67]
	v_mfma_f32_16x16x32_bf16 v[108:111], v[168:171], v[184:187], v[108:111]
	v_mfma_f32_16x16x32_bf16 v[104:107], v[176:179], v[184:187], v[104:107]
	v_mfma_f32_16x16x32_bf16 v[92:95], v[168:171], v[192:195], v[92:95]
	v_mfma_f32_16x16x32_bf16 v[88:91], v[176:179], v[192:195], v[88:91]
	v_mfma_f32_16x16x32_bf16 v[76:79], v[168:171], v[200:203], v[76:79]
	v_mfma_f32_16x16x32_bf16 v[72:75], v[176:179], v[200:203], v[72:75]
	v_mfma_f32_16x16x32_bf16 v[68:71], v[168:171], v[208:211], v[68:71]
	v_mfma_f32_16x16x32_bf16 v[64:67], v[176:179], v[208:211], v[64:67]
	s_setprio 0
	s_barrier
	s_add_i32 s44, s57, s94
	v_lshl_add_u64 v[212:213], s[46:47], 0, v[132:133]
	s_mov_b32 m0, s44
	ds_read_b128 v[180:183], v147 offset:16384
	ds_read_b128 v[184:187], v147 offset:17408
	ds_read_b128 v[188:191], v147 offset:18432
	ds_read_b128 v[192:195], v147 offset:19456
	ds_read_b128 v[196:199], v147 offset:20480
	ds_read_b128 v[200:203], v147 offset:21504
	ds_read_b128 v[204:207], v147 offset:22528
	ds_read_b128 v[208:211], v147 offset:23552
	global_load_lds_dwordx4 v[212:213], off
	s_add_i32 m0, s44, 0x2000
	s_add_u32 s44, s46, 0x20000
	v_lshl_add_u64 v[214:215], s[46:47], 0, v[128:129]
	s_addc_u32 s45, s47, 0
	s_add_i32 s63, s58, s94
	global_load_lds_dwordx4 v[214:215], off
	v_lshl_add_u64 v[216:217], s[44:45], 0, v[132:133]
	s_mov_b32 m0, s63
	v_lshl_add_u64 v[218:219], s[48:49], 0, v[130:131]
	global_load_lds_dwordx4 v[216:217], off
	v_lshl_add_u64 v[216:217], s[44:45], 0, v[128:129]
	s_add_i32 m0, s63, 0x2000
	s_nop 0
	global_load_lds_dwordx4 v[216:217], off
	v_lshl_add_u64 v[216:217], s[48:49], 0, v[134:135]
	s_mov_b32 m0, s21
	s_nop 0
	global_load_lds_dwordx4 v[216:217], off
	s_mov_b32 m0, s25
	s_nop 0
	global_load_lds_dwordx4 v[218:219], off
	s_waitcnt vmcnt(8)
	s_waitcnt lgkmcnt(0)
	s_barrier
	s_setprio 1
	v_mfma_f32_16x16x32_bf16 v[60:63], v[148:151], v[180:183], v[60:63]
	v_mfma_f32_16x16x32_bf16 v[56:59], v[156:159], v[180:183], v[56:59]
	v_mfma_f32_16x16x32_bf16 v[52:55], v[148:151], v[188:191], v[52:55]
	v_mfma_f32_16x16x32_bf16 v[48:51], v[156:159], v[188:191], v[48:51]
	v_mfma_f32_16x16x32_bf16 v[36:39], v[148:151], v[196:199], v[36:39]
	v_mfma_f32_16x16x32_bf16 v[32:35], v[156:159], v[196:199], v[32:35]
	v_mfma_f32_16x16x32_bf16 v[20:23], v[148:151], v[204:207], v[20:23]
	v_mfma_f32_16x16x32_bf16 v[16:19], v[156:159], v[204:207], v[16:19]
	v_mfma_f32_16x16x32_bf16 v[60:63], v[152:155], v[184:187], v[60:63]
	v_mfma_f32_16x16x32_bf16 v[56:59], v[160:163], v[184:187], v[56:59]
	v_mfma_f32_16x16x32_bf16 v[52:55], v[152:155], v[192:195], v[52:55]
	v_mfma_f32_16x16x32_bf16 v[48:51], v[160:163], v[192:195], v[48:51]
	v_mfma_f32_16x16x32_bf16 v[36:39], v[152:155], v[200:203], v[36:39]
	v_mfma_f32_16x16x32_bf16 v[32:35], v[160:163], v[200:203], v[32:35]
	v_mfma_f32_16x16x32_bf16 v[20:23], v[152:155], v[208:211], v[20:23]
	v_mfma_f32_16x16x32_bf16 v[16:19], v[160:163], v[208:211], v[16:19]
	v_mfma_f32_16x16x32_bf16 v[44:47], v[164:167], v[180:183], v[44:47]
	v_mfma_f32_16x16x32_bf16 v[40:43], v[172:175], v[180:183], v[40:43]
	v_mfma_f32_16x16x32_bf16 v[28:31], v[164:167], v[188:191], v[28:31]
	v_mfma_f32_16x16x32_bf16 v[24:27], v[172:175], v[188:191], v[24:27]
	v_mfma_f32_16x16x32_bf16 v[12:15], v[164:167], v[196:199], v[12:15]
	v_mfma_f32_16x16x32_bf16 v[8:11], v[172:175], v[196:199], v[8:11]
	v_mfma_f32_16x16x32_bf16 v[4:7], v[164:167], v[204:207], v[4:7]
	v_mfma_f32_16x16x32_bf16 v[0:3], v[172:175], v[204:207], v[0:3]
	v_mfma_f32_16x16x32_bf16 v[44:47], v[168:171], v[184:187], v[44:47]
	v_mfma_f32_16x16x32_bf16 v[40:43], v[176:179], v[184:187], v[40:43]
	v_mfma_f32_16x16x32_bf16 v[28:31], v[168:171], v[192:195], v[28:31]
	v_mfma_f32_16x16x32_bf16 v[24:27], v[176:179], v[192:195], v[24:27]
	v_mfma_f32_16x16x32_bf16 v[12:15], v[168:171], v[200:203], v[12:15]
	v_mfma_f32_16x16x32_bf16 v[8:11], v[176:179], v[200:203], v[8:11]
	v_mfma_f32_16x16x32_bf16 v[4:7], v[168:171], v[208:211], v[4:7]
	v_mfma_f32_16x16x32_bf16 v[0:3], v[176:179], v[208:211], v[0:3]
	s_setprio 0
	s_barrier
; #define PG8_STAGE(bufoff, gbase, voff) do { _Pragma("unroll") for (int _i = 0; _i < 2; ++_i) \
;         __builtin_amdgcn_global_load_lds((const unsigned*)((const char*)(gbase) + (voff)[_i]), (LAS unsigned*)(lds + (bufoff) + ldsw + _i * 8192), 16, 0, 0); } while (0)
; #define PG8_LDA(dst, b, h) do { _Pragma("unroll") for (int m = 0; m < 4; ++m) _Pragma("unroll") for (int k = 0; k < 2; ++k) dst[m][k] = *(const LAS bf16x8*)(lds + PG8_SA(b, h) + aoff + m * 2048 + k * 1024); } while (0)
; #define PG8_LDB(dst, b, h) do { _Pragma("unroll") for (int n = 0; n < 2; ++n) _Pragma("unroll") for (int k = 0; k < 2; ++k) dst[n][k] = *(const LAS bf16x8*)(lds + PG8_SB(b, h) + boff + n * 2048 + k * 1024); } while (0)
; #define PG8_MMA(ai, bj, At, Bt) do { __builtin_amdgcn_s_setprio(1); _Pragma("unroll") for (int m = 0; m < 4; ++m) _Pragma("unroll") for (int n = 0; n < 2; ++n) _Pragma("unroll") for (int k = 0; k < 2; ++k) \
;         acc[ai][bj][m][n] = __builtin_amdgcn_mfma_f32_16x16x32_bf16(Bt[n][k], At[m][k], acc[ai][bj][m][n], 0, 0, 0); __builtin_amdgcn_s_setprio(0); } while (0)
; #define PG8_WAIT_V(n) asm volatile("s_waitcnt vmcnt(" #n ")" ::: "memory")
; #define PG8_WAIT_L(n) asm volatile("s_waitcnt lgkmcnt(" #n ")" ::: "memory")
; #define PG8_BAR __builtin_amdgcn_s_barrier()
; #define PG8_SCHED __builtin_amdgcn_sched_barrier(0)
; template <class Epi>
; DI void gemm_phase(LAS unsigned char* lds, const int wid, const Gemm g, const Order& S, const Epi& E) {
;     ...
;         for (int t = 0; t < nt; t += 2) {
;     ...
;             PG8_LDB(B0, 1, 0); PG8_LDB(B1, 1, 1); PG8_SCHED; PG8_LDA(At, 1, 0); PG8_STAGE(PG8_SA(0, 1), a2 + hstepA, voffA);
;             PG8_WAIT_V(8); PG8_WAIT_L(0); PG8_BAR; PG8_MMA(0, 0, At, B0); PG8_MMA(0, 1, At, B1); PG8_BAR; PG8_SCHED;
;             PG8_LDA(At, 1, 1); PG8_STAGE(PG8_SB(1, 0), b3, voffB); PG8_STAGE(PG8_SB(1, 1), b3 + hstepB, voffB); PG8_STAGE(PG8_SA(1, 0), a3, voffA);
;             PG8_WAIT_V(8); PG8_WAIT_L(0); PG8_BAR; PG8_MMA(1, 0, At, B0); PG8_MMA(1, 1, At, B1); PG8_BAR; PG8_SCHED;
	s_add_i32 s63, 0, 0x18000
	s_add_i32 s64, 0, 0x1c000
	v_add_u32_e32 v160, s63, v144
	v_add_u32_e32 v176, s64, v144
	ds_read_b128 v[148:151], v160
	ds_read_b128 v[152:155], v160 offset:1024
	ds_read_b128 v[156:159], v160 offset:2048
	ds_read_b128 v[160:163], v160 offset:3072
	ds_read_b128 v[164:167], v176
	ds_read_b128 v[168:171], v176 offset:1024
	ds_read_b128 v[172:175], v176 offset:2048
	ds_read_b128 v[176:179], v176 offset:3072
	s_add_u32 s44, s48, 0x30000
	s_addc_u32 s45, s49, 0
	s_mov_b32 m0, s26
	v_lshl_add_u64 v[220:221], s[44:45], 0, v[134:135]
	ds_read_b128 v[180:183], v147 offset:32768
	ds_read_b128 v[184:187], v147 offset:33792
	ds_read_b128 v[188:191], v147 offset:34816
	ds_read_b128 v[192:195], v147 offset:35840
	ds_read_b128 v[196:199], v147 offset:36864
	ds_read_b128 v[200:203], v147 offset:37888
	ds_read_b128 v[204:207], v147 offset:38912
	ds_read_b128 v[208:211], v147 offset:39936
	global_load_lds_dwordx4 v[220:221], off
	v_lshl_add_u64 v[220:221], s[44:45], 0, v[130:131]
	s_mov_b32 m0, s27
	s_nop 0
	global_load_lds_dwordx4 v[220:221], off
	s_waitcnt vmcnt(8)
	s_waitcnt lgkmcnt(0)
	s_barrier
	s_setprio 1
	v_mfma_f32_16x16x32_bf16 v[124:127], v[148:151], v[180:183], v[124:127]
	v_mfma_f32_16x16x32_bf16 v[120:123], v[156:159], v[180:183], v[120:123]
	v_mfma_f32_16x16x32_bf16 v[116:119], v[148:151], v[188:191], v[116:119]
	v_mfma_f32_16x16x32_bf16 v[112:115], v[156:159], v[188:191], v[112:115]
	v_mfma_f32_16x16x32_bf16 v[100:103], v[148:151], v[196:199], v[100:103]
	v_mfma_f32_16x16x32_bf16 v[96:99], v[156:159], v[196:199], v[96:99]
	v_mfma_f32_16x16x32_bf16 v[84:87], v[148:151], v[204:207], v[84:87]
	v_mfma_f32_16x16x32_bf16 v[80:83], v[156:159], v[204:207], v[80:83]
	v_mfma_f32_16x16x32_bf16 v[124:127], v[152:155], v[184:187], v[124:127]
	v_mfma_f32_16x16x32_bf16 v[120:123], v[160:163], v[184:187], v[120:123]
	v_mfma_f32_16x16x32_bf16 v[116:119], v[152:155], v[192:195], v[116:119]
	v_mfma_f32_16x16x32_bf16 v[112:115], v[160:163], v[192:195], v[112:115]
	v_mfma_f32_16x16x32_bf16 v[100:103], v[152:155], v[200:203], v[100:103]
	v_mfma_f32_16x16x32_bf16 v[96:99], v[160:163], v[200:203], v[96:99]
	v_mfma_f32_16x16x32_bf16 v[84:87], v[152:155], v[208:211], v[84:87]
	v_mfma_f32_16x16x32_bf16 v[80:83], v[160:163], v[208:211], v[80:83]
	v_mfma_f32_16x16x32_bf16 v[108:111], v[164:167], v[180:183], v[108:111]
	v_mfma_f32_16x16x32_bf16 v[104:107], v[172:175], v[180:183], v[104:107]
	v_mfma_f32_16x16x32_bf16 v[92:95], v[164:167], v[188:191], v[92:95]
	v_mfma_f32_16x16x32_bf16 v[88:91], v[172:175], v[188:191], v[88:91]
	v_mfma_f32_16x16x32_bf16 v[76:79], v[164:167], v[196:199], v[76:79]
	v_mfma_f32_16x16x32_bf16 v[72:75], v[172:175], v[196:199], v[72:75]
	v_mfma_f32_16x16x32_bf16 v[68:71], v[164:167], v[204:207], v[68:71]
	v_mfma_f32_16x16x32_bf16 v[64:67], v[172:175], v[204:207], v[64:67]
	v_mfma_f32_16x16x32_bf16 v[108:111], v[168:171], v[184:187], v[108:111]
	v_mfma_f32_16x16x32_bf16 v[104:107], v[176:179], v[184:187], v[104:107]
	v_mfma_f32_16x16x32_bf16 v[92:95], v[168:171], v[192:195], v[92:95]
	v_mfma_f32_16x16x32_bf16 v[88:91], v[176:179], v[192:195], v[88:91]
	v_mfma_f32_16x16x32_bf16 v[76:79], v[168:171], v[200:203], v[76:79]
	v_mfma_f32_16x16x32_bf16 v[72:75], v[176:179], v[200:203], v[72:75]
	v_mfma_f32_16x16x32_bf16 v[68:71], v[168:171], v[208:211], v[68:71]
	v_mfma_f32_16x16x32_bf16 v[64:67], v[176:179], v[208:211], v[64:67]
	s_setprio 0
	s_barrier
	s_add_i32 s44, s63, s94
	v_lshl_add_u64 v[212:213], v[212:213], 0, s[30:31]
	s_mov_b32 m0, s44
	ds_read_b128 v[180:183], v147 offset:49152
	ds_read_b128 v[184:187], v147 offset:50176
	ds_read_b128 v[188:191], v147 offset:51200
	ds_read_b128 v[192:195], v147 offset:52224
	ds_read_b128 v[196:199], v147 offset:53248
	ds_read_b128 v[200:203], v147 offset:54272
	ds_read_b128 v[204:207], v147 offset:55296
	ds_read_b128 v[208:211], v147 offset:56320
	global_load_lds_dwordx4 v[212:213], off
	s_add_i32 m0, s44, 0x2000
	s_add_u32 s44, s46, 0x20080
	v_lshl_add_u64 v[212:213], v[214:215], 0, s[30:31]
	s_addc_u32 s45, s47, 0
	s_add_i32 s46, s64, s94
	global_load_lds_dwordx4 v[212:213], off
	v_lshl_add_u64 v[212:213], s[44:45], 0, v[132:133]
	s_mov_b32 m0, s46
	s_nop 0
	global_load_lds_dwordx4 v[212:213], off
	v_lshl_add_u64 v[212:213], s[44:45], 0, v[128:129]
	s_add_i32 m0, s46, 0x2000
	s_nop 0
	global_load_lds_dwordx4 v[212:213], off
	v_lshl_add_u64 v[212:213], v[216:217], 0, s[30:31]
	s_mov_b32 m0, s52
	s_nop 0
	global_load_lds_dwordx4 v[212:213], off
	v_lshl_add_u64 v[212:213], v[218:219], 0, s[30:31]
	s_mov_b32 m0, s53
	s_nop 0
	global_load_lds_dwordx4 v[212:213], off
	s_waitcnt vmcnt(8)
	s_waitcnt lgkmcnt(0)
	s_barrier
	s_setprio 1
	v_mfma_f32_16x16x32_bf16 v[60:63], v[148:151], v[180:183], v[60:63]
	v_mfma_f32_16x16x32_bf16 v[56:59], v[156:159], v[180:183], v[56:59]
	v_mfma_f32_16x16x32_bf16 v[52:55], v[148:151], v[188:191], v[52:55]
	v_mfma_f32_16x16x32_bf16 v[48:51], v[156:159], v[188:191], v[48:51]
	v_mfma_f32_16x16x32_bf16 v[36:39], v[148:151], v[196:199], v[36:39]
	v_mfma_f32_16x16x32_bf16 v[32:35], v[156:159], v[196:199], v[32:35]
	v_mfma_f32_16x16x32_bf16 v[20:23], v[148:151], v[204:207], v[20:23]
	v_mfma_f32_16x16x32_bf16 v[16:19], v[156:159], v[204:207], v[16:19]
	v_mfma_f32_16x16x32_bf16 v[60:63], v[152:155], v[184:187], v[60:63]
	v_mfma_f32_16x16x32_bf16 v[56:59], v[160:163], v[184:187], v[56:59]
	v_mfma_f32_16x16x32_bf16 v[52:55], v[152:155], v[192:195], v[52:55]
	v_mfma_f32_16x16x32_bf16 v[48:51], v[160:163], v[192:195], v[48:51]
	v_mfma_f32_16x16x32_bf16 v[36:39], v[152:155], v[200:203], v[36:39]
	v_mfma_f32_16x16x32_bf16 v[32:35], v[160:163], v[200:203], v[32:35]
	v_mfma_f32_16x16x32_bf16 v[20:23], v[152:155], v[208:211], v[20:23]
	v_mfma_f32_16x16x32_bf16 v[16:19], v[160:163], v[208:211], v[16:19]
	v_mfma_f32_16x16x32_bf16 v[44:47], v[164:167], v[180:183], v[44:47]
	v_mfma_f32_16x16x32_bf16 v[40:43], v[172:175], v[180:183], v[40:43]
	v_mfma_f32_16x16x32_bf16 v[28:31], v[164:167], v[188:191], v[28:31]
	v_mfma_f32_16x16x32_bf16 v[24:27], v[172:175], v[188:191], v[24:27]
	v_mfma_f32_16x16x32_bf16 v[12:15], v[164:167], v[196:199], v[12:15]
	v_mfma_f32_16x16x32_bf16 v[8:11], v[172:175], v[196:199], v[8:11]
	v_mfma_f32_16x16x32_bf16 v[4:7], v[164:167], v[204:207], v[4:7]
	v_mfma_f32_16x16x32_bf16 v[0:3], v[172:175], v[204:207], v[0:3]
	v_mfma_f32_16x16x32_bf16 v[44:47], v[168:171], v[184:187], v[44:47]
	v_mfma_f32_16x16x32_bf16 v[40:43], v[176:179], v[184:187], v[40:43]
	v_mfma_f32_16x16x32_bf16 v[28:31], v[168:171], v[192:195], v[28:31]
	v_mfma_f32_16x16x32_bf16 v[24:27], v[176:179], v[192:195], v[24:27]
	v_mfma_f32_16x16x32_bf16 v[12:15], v[168:171], v[200:203], v[12:15]
	v_mfma_f32_16x16x32_bf16 v[8:11], v[176:179], v[200:203], v[8:11]
	v_mfma_f32_16x16x32_bf16 v[4:7], v[168:171], v[208:211], v[4:7]
	v_mfma_f32_16x16x32_bf16 v[0:3], v[176:179], v[208:211], v[0:3]
	s_setprio 0
	s_barrier
	s_add_i32 s62, s62, 2
	s_add_u32 s39, s39, 0x100
	s_addc_u32 s61, s61, 0
	s_cmp_gt_u32 s62, 5
	s_mov_b64 s[44:45], s[12:13]
	s_cbranch_scc0 .LBB0_790

; #define PG8_STAGE(bufoff, gbase, voff) do { _Pragma("unroll") for (int _i = 0; _i < 2; ++_i) \
;         __builtin_amdgcn_global_load_lds((const unsigned*)((const char*)(gbase) + (voff)[_i]), (LAS unsigned*)(lds + (bufoff) + ldsw + _i * 8192), 16, 0, 0); } while (0)
; #define PG8_LDA(dst, b, h) do { _Pragma("unroll") for (int m = 0; m < 4; ++m) _Pragma("unroll") for (int k = 0; k < 2; ++k) dst[m][k] = *(const LAS bf16x8*)(lds + PG8_SA(b, h) + aoff + m * 2048 + k * 1024); } while (0)
; #define PG8_LDB(dst, b, h) do { _Pragma("unroll") for (int n = 0; n < 2; ++n) _Pragma("unroll") for (int k = 0; k < 2; ++k) dst[n][k] = *(const LAS bf16x8*)(lds + PG8_SB(b, h) + boff + n * 2048 + k * 1024); } while (0)
; #define PG8_MMA(ai, bj, At, Bt) do { __builtin_amdgcn_s_setprio(1); _Pragma("unroll") for (int m = 0; m < 4; ++m) _Pragma("unroll") for (int n = 0; n < 2; ++n) _Pragma("unroll") for (int k = 0; k < 2; ++k) \
;         acc[ai][bj][m][n] = __builtin_amdgcn_mfma_f32_16x16x32_bf16(Bt[n][k], At[m][k], acc[ai][bj][m][n], 0, 0, 0); __builtin_amdgcn_s_setprio(0); } while (0)
; template <class Epi>
; DI void gemm_phase(LAS unsigned char* lds, const int wid, const Gemm g, const Order& S, const Epi& E) {
;     ...
;         const bool has_next = S.next(ui + 1, nxt);
;         const char* nA = has_next ? (const char*)(g.A + (size_t)nxt.g * g.gsA + (size_t)nxt.pm * BM * g.lda) : cA;
;         const char* nB = has_next ? (const char*)(g.Bt + (size_t)nxt.g * g.gsB + (size_t)nxt.pn * BM * g.ldb) : cB;
;         for (int t = 0; t < nt; t += 2) {
;             const bool last = (t == nt - 2);
;             const char* a1 = cA + (size_t)(t + 1) * kstep;
;             const char* a2 = last ? nA : cA + (size_t)(t + 2) * kstep; const char* b2 = last ? nB : cB + (size_t)(t + 2) * kstep;
;             const char* a3 = a2 + kstep; const char* b3 = b2 + kstep;
;             PG8_LDB(B0, 0, 0); PG8_LDB(B1, 0, 1); PG8_SCHED; PG8_LDA(At, 0, 0); PG8_STAGE(PG8_SA(1, 1), a1 + hstepA, voffA);
;             PG8_WAIT_V(8); PG8_WAIT_L(0); PG8_BAR; PG8_MMA(0, 0, At, B0); PG8_MMA(0, 1, At, B1); PG8_BAR; PG8_SCHED;
;             PG8_LDA(At, 0, 1); PG8_STAGE(PG8_SB(0, 0), b2, voffB); PG8_STAGE(PG8_SB(0, 1), b2 + hstepB, voffB); PG8_STAGE(PG8_SA(0, 0), a2, voffA);
;             PG8_WAIT_V(8); PG8_WAIT_L(0); PG8_BAR; PG8_MMA(1, 0, At, B0); PG8_MMA(1, 1, At, B1); PG8_BAR; PG8_SCHED;
.LBB0_988:
	s_add_u32 s54, s36, 0x100
	v_mov_b32_e32 v0, 0
	s_addc_u32 s55, s37, 0
	s_mov_b32 s56, -2
	ds_read_b128 v[152:155], v149
	ds_read_b128 v[156:159], v149 offset:1024
	ds_read_b128 v[160:163], v149 offset:2048
	ds_read_b128 v[164:167], v149 offset:3072
	ds_read_b128 v[168:171], v150
	ds_read_b128 v[172:175], v150 offset:1024
	ds_read_b128 v[176:179], v150 offset:2048
	ds_read_b128 v[180:183], v150 offset:3072
	s_add_u32 s36, s34, 0x100
	s_addc_u32 s37, s35, 0
	s_cmp_eq_u32 s56, 8
	s_cselect_b32 s41, s11, s37
	s_cselect_b32 s40, s10, s36
	s_cselect_b32 s39, s31, s55
	s_cselect_b32 s38, s30, s54
	v_lshl_add_u64 v[146:147], s[34:35], 0, v[138:139]
	s_add_i32 m0, s25, 0xc000
	ds_read_b128 v[184:187], v151
	ds_read_b128 v[188:191], v151 offset:1024
	ds_read_b128 v[192:195], v151 offset:2048
	ds_read_b128 v[196:199], v151 offset:3072
	ds_read_b128 v[200:203], v151 offset:4096
	ds_read_b128 v[204:207], v151 offset:5120
	ds_read_b128 v[208:211], v151 offset:6144
	ds_read_b128 v[212:215], v151 offset:7168
	global_load_lds_dwordx4 v[146:147], off
	v_lshl_add_u64 v[146:147], s[34:35], 0, v[140:141]
	s_add_i32 m0, s25, 0xe000
	s_nop 0
	global_load_lds_dwordx4 v[146:147], off
	s_waitcnt vmcnt(8)
	s_waitcnt lgkmcnt(0)
	s_barrier
	s_setprio 1
	v_mfma_f32_16x16x32_bf16 v[124:127], v[152:155], v[184:187], 0
	v_mfma_f32_16x16x32_bf16 v[120:123], v[160:163], v[184:187], 0
	v_mfma_f32_16x16x32_bf16 v[108:111], v[152:155], v[192:195], 0
	v_mfma_f32_16x16x32_bf16 v[104:107], v[160:163], v[192:195], 0
	v_mfma_f32_16x16x32_bf16 v[92:95], v[152:155], v[200:203], 0
	v_mfma_f32_16x16x32_bf16 v[88:91], v[160:163], v[200:203], 0
	v_mfma_f32_16x16x32_bf16 v[76:79], v[152:155], v[208:211], 0
	v_mfma_f32_16x16x32_bf16 v[72:75], v[160:163], v[208:211], 0
	v_mfma_f32_16x16x32_bf16 v[124:127], v[156:159], v[188:191], v[124:127]
	v_mfma_f32_16x16x32_bf16 v[120:123], v[164:167], v[188:191], v[120:123]
	v_mfma_f32_16x16x32_bf16 v[108:111], v[156:159], v[196:199], v[108:111]
	v_mfma_f32_16x16x32_bf16 v[104:107], v[164:167], v[196:199], v[104:107]
	v_mfma_f32_16x16x32_bf16 v[92:95], v[156:159], v[204:207], v[92:95]
	v_mfma_f32_16x16x32_bf16 v[88:91], v[164:167], v[204:207], v[88:91]
	v_mfma_f32_16x16x32_bf16 v[76:79], v[156:159], v[212:215], v[76:79]
	v_mfma_f32_16x16x32_bf16 v[72:75], v[164:167], v[212:215], v[72:75]
	v_mfma_f32_16x16x32_bf16 v[116:119], v[168:171], v[184:187], 0
	v_mfma_f32_16x16x32_bf16 v[112:115], v[176:179], v[184:187], 0
	v_mfma_f32_16x16x32_bf16 v[100:103], v[168:171], v[192:195], 0
	v_mfma_f32_16x16x32_bf16 v[96:99], v[176:179], v[192:195], 0
	v_mfma_f32_16x16x32_bf16 v[84:87], v[168:171], v[200:203], 0
	v_mfma_f32_16x16x32_bf16 v[80:83], v[176:179], v[200:203], 0
	v_mfma_f32_16x16x32_bf16 v[68:71], v[168:171], v[208:211], 0
	v_mfma_f32_16x16x32_bf16 v[64:67], v[176:179], v[208:211], 0
	v_mfma_f32_16x16x32_bf16 v[116:119], v[172:175], v[188:191], v[116:119]
	v_mfma_f32_16x16x32_bf16 v[112:115], v[180:183], v[188:191], v[112:115]
	v_mfma_f32_16x16x32_bf16 v[100:103], v[172:175], v[196:199], v[100:103]
	v_mfma_f32_16x16x32_bf16 v[96:99], v[180:183], v[196:199], v[96:99]
	v_mfma_f32_16x16x32_bf16 v[84:87], v[172:175], v[204:207], v[84:87]
	v_mfma_f32_16x16x32_bf16 v[80:83], v[180:183], v[204:207], v[80:83]
	v_mfma_f32_16x16x32_bf16 v[68:71], v[172:175], v[212:215], v[68:71]
	v_mfma_f32_16x16x32_bf16 v[64:67], v[180:183], v[212:215], v[64:67]
	s_setprio 0
	s_barrier
	s_add_i32 s34, s48, s94
	v_lshl_add_u64 v[146:147], s[38:39], 0, v[130:131]
	s_mov_b32 m0, s34
	ds_read_b128 v[184:187], v151 offset:16384
	ds_read_b128 v[188:191], v151 offset:17408
	ds_read_b128 v[192:195], v151 offset:18432
	ds_read_b128 v[196:199], v151 offset:19456
	ds_read_b128 v[200:203], v151 offset:20480
	ds_read_b128 v[204:207], v151 offset:21504
	ds_read_b128 v[208:211], v151 offset:22528
	ds_read_b128 v[212:215], v151 offset:23552
	global_load_lds_dwordx4 v[146:147], off
	s_add_i32 m0, s34, 0x2000
	s_add_u32 s34, s38, 0x30000
	v_lshl_add_u64 v[216:217], s[38:39], 0, v[134:135]
	s_addc_u32 s35, s39, 0
	s_add_i32 s57, s49, s94
	global_load_lds_dwordx4 v[216:217], off
	v_lshl_add_u64 v[218:219], s[34:35], 0, v[130:131]
	s_mov_b32 m0, s57
	v_lshl_add_u64 v[220:221], s[40:41], 0, v[132:133]
	global_load_lds_dwordx4 v[218:219], off
	v_lshl_add_u64 v[218:219], s[34:35], 0, v[134:135]
	s_add_i32 m0, s57, 0x2000
	s_nop 0
	global_load_lds_dwordx4 v[218:219], off
	v_lshl_add_u64 v[218:219], s[40:41], 0, v[128:129]
	s_mov_b32 m0, s25
	s_nop 0
	global_load_lds_dwordx4 v[218:219], off
	s_mov_b32 m0, s42
	s_nop 0
	global_load_lds_dwordx4 v[220:221], off
	s_waitcnt vmcnt(8)
	s_waitcnt lgkmcnt(0)
	s_barrier
; #define PG8_STAGE(bufoff, gbase, voff) do { _Pragma("unroll") for (int _i = 0; _i < 2; ++_i) \
;         __builtin_amdgcn_global_load_lds((const unsigned*)((const char*)(gbase) + (voff)[_i]), (LAS unsigned*)(lds + (bufoff) + ldsw + _i * 8192), 16, 0, 0); } while (0)
; #define PG8_LDA(dst, b, h) do { _Pragma("unroll") for (int m = 0; m < 4; ++m) _Pragma("unroll") for (int k = 0; k < 2; ++k) dst[m][k] = *(const LAS bf16x8*)(lds + PG8_SA(b, h) + aoff + m * 2048 + k * 1024); } while (0)
; #define PG8_LDB(dst, b, h) do { _Pragma("unroll") for (int n = 0; n < 2; ++n) _Pragma("unroll") for (int k = 0; k < 2; ++k) dst[n][k] = *(const LAS bf16x8*)(lds + PG8_SB(b, h) + boff + n * 2048 + k * 1024); } while (0)
; #define PG8_MMA(ai, bj, At, Bt) do { __builtin_amdgcn_s_setprio(1); _Pragma("unroll") for (int m = 0; m < 4; ++m) _Pragma("unroll") for (int n = 0; n < 2; ++n) _Pragma("unroll") for (int k = 0; k < 2; ++k) \
;         acc[ai][bj][m][n] = __builtin_amdgcn_mfma_f32_16x16x32_bf16(Bt[n][k], At[m][k], acc[ai][bj][m][n], 0, 0, 0); __builtin_amdgcn_s_setprio(0); } while (0)
; #define PG8_WAIT_V(n) asm volatile("s_waitcnt vmcnt(" #n ")" ::: "memory")
; #define PG8_WAIT_L(n) asm volatile("s_waitcnt lgkmcnt(" #n ")" ::: "memory")
; #define PG8_BAR __builtin_amdgcn_s_barrier()
; #define PG8_SCHED __builtin_amdgcn_sched_barrier(0)
; template <class Epi>
; DI void gemm_phase(LAS unsigned char* lds, const int wid, const Gemm g, const Order& S, const Epi& E) {
;     ...
;             PG8_WAIT_V(8); PG8_WAIT_L(0); PG8_BAR; PG8_MMA(1, 0, At, B0); PG8_MMA(1, 1, At, B1); PG8_BAR; PG8_SCHED;
;             PG8_LDB(B0, 1, 0); PG8_LDB(B1, 1, 1); PG8_SCHED; PG8_LDA(At, 1, 0); PG8_STAGE(PG8_SA(0, 1), a2 + hstepA, voffA);
;             PG8_WAIT_V(8); PG8_WAIT_L(0); PG8_BAR; PG8_MMA(0, 0, At, B0); PG8_MMA(0, 1, At, B1); PG8_BAR; PG8_SCHED;
	s_setprio 1
	v_mfma_f32_16x16x32_bf16 v[60:63], v[152:155], v[184:187], 0
	v_mfma_f32_16x16x32_bf16 v[56:59], v[160:163], v[184:187], 0
	v_mfma_f32_16x16x32_bf16 v[44:47], v[152:155], v[192:195], 0
	v_mfma_f32_16x16x32_bf16 v[40:43], v[160:163], v[192:195], 0
	v_mfma_f32_16x16x32_bf16 v[28:31], v[152:155], v[200:203], 0
	v_mfma_f32_16x16x32_bf16 v[24:27], v[160:163], v[200:203], 0
	v_mfma_f32_16x16x32_bf16 v[12:15], v[152:155], v[208:211], 0
	v_mfma_f32_16x16x32_bf16 v[8:11], v[160:163], v[208:211], 0
	v_mfma_f32_16x16x32_bf16 v[60:63], v[156:159], v[188:191], v[60:63]
	v_mfma_f32_16x16x32_bf16 v[56:59], v[164:167], v[188:191], v[56:59]
	v_mfma_f32_16x16x32_bf16 v[44:47], v[156:159], v[196:199], v[44:47]
	v_mfma_f32_16x16x32_bf16 v[40:43], v[164:167], v[196:199], v[40:43]
	v_mfma_f32_16x16x32_bf16 v[28:31], v[156:159], v[204:207], v[28:31]
	v_mfma_f32_16x16x32_bf16 v[24:27], v[164:167], v[204:207], v[24:27]
	v_mfma_f32_16x16x32_bf16 v[12:15], v[156:159], v[212:215], v[12:15]
	v_mfma_f32_16x16x32_bf16 v[8:11], v[164:167], v[212:215], v[8:11]
	v_mfma_f32_16x16x32_bf16 v[52:55], v[168:171], v[184:187], 0
	v_mfma_f32_16x16x32_bf16 v[48:51], v[176:179], v[184:187], 0
	v_mfma_f32_16x16x32_bf16 v[36:39], v[168:171], v[192:195], 0
	v_mfma_f32_16x16x32_bf16 v[32:35], v[176:179], v[192:195], 0
	v_mfma_f32_16x16x32_bf16 v[20:23], v[168:171], v[200:203], 0
	v_mfma_f32_16x16x32_bf16 v[16:19], v[176:179], v[200:203], 0
	v_mfma_f32_16x16x32_bf16 v[4:7], v[168:171], v[208:211], 0
	v_mfma_f32_16x16x32_bf16 v[0:3], v[176:179], v[208:211], 0
	v_mfma_f32_16x16x32_bf16 v[52:55], v[172:175], v[188:191], v[52:55]
	v_mfma_f32_16x16x32_bf16 v[48:51], v[180:183], v[188:191], v[48:51]
	v_mfma_f32_16x16x32_bf16 v[36:39], v[172:175], v[196:199], v[36:39]
	v_mfma_f32_16x16x32_bf16 v[32:35], v[180:183], v[196:199], v[32:35]
	v_mfma_f32_16x16x32_bf16 v[20:23], v[172:175], v[204:207], v[20:23]
	v_mfma_f32_16x16x32_bf16 v[16:19], v[180:183], v[204:207], v[16:19]
	v_mfma_f32_16x16x32_bf16 v[4:7], v[172:175], v[212:215], v[4:7]
	v_mfma_f32_16x16x32_bf16 v[0:3], v[180:183], v[212:215], v[0:3]
	s_setprio 0
	s_barrier
	s_add_i32 s57, 0, 0x18000
	v_add_u32_e32 v136, s57, v148
	s_add_i32 s58, 0, 0x1c000
	ds_read_b128 v[152:155], v136
	ds_read_b128 v[156:159], v136 offset:1024
	ds_read_b128 v[160:163], v136 offset:2048
	ds_read_b128 v[164:167], v136 offset:3072
	v_add_u32_e32 v136, s58, v148
	ds_read_b128 v[168:171], v136
	ds_read_b128 v[172:175], v136 offset:1024
	ds_read_b128 v[176:179], v136 offset:2048
	ds_read_b128 v[180:183], v136 offset:3072
	s_add_u32 s34, s40, 0x30000
	s_addc_u32 s35, s41, 0
	s_mov_b32 m0, s43
	v_lshl_add_u64 v[222:223], s[34:35], 0, v[128:129]
	ds_read_b128 v[184:187], v151 offset:32768
	ds_read_b128 v[188:191], v151 offset:33792
	ds_read_b128 v[192:195], v151 offset:34816
	ds_read_b128 v[196:199], v151 offset:35840
	ds_read_b128 v[200:203], v151 offset:36864
	ds_read_b128 v[204:207], v151 offset:37888
	ds_read_b128 v[208:211], v151 offset:38912
	ds_read_b128 v[212:215], v151 offset:39936
	global_load_lds_dwordx4 v[222:223], off
	v_lshl_add_u64 v[222:223], s[34:35], 0, v[132:133]
	s_mov_b32 m0, s44
	s_nop 0
	global_load_lds_dwordx4 v[222:223], off
	s_waitcnt vmcnt(8)
	s_waitcnt lgkmcnt(0)
	s_barrier
	s_setprio 1
	v_mfma_f32_16x16x32_bf16 v[124:127], v[152:155], v[184:187], v[124:127]
	v_mfma_f32_16x16x32_bf16 v[120:123], v[160:163], v[184:187], v[120:123]
	v_mfma_f32_16x16x32_bf16 v[108:111], v[152:155], v[192:195], v[108:111]
	v_mfma_f32_16x16x32_bf16 v[104:107], v[160:163], v[192:195], v[104:107]
	v_mfma_f32_16x16x32_bf16 v[92:95], v[152:155], v[200:203], v[92:95]
	v_mfma_f32_16x16x32_bf16 v[88:91], v[160:163], v[200:203], v[88:91]
	v_mfma_f32_16x16x32_bf16 v[76:79], v[152:155], v[208:211], v[76:79]
	v_mfma_f32_16x16x32_bf16 v[72:75], v[160:163], v[208:211], v[72:75]
	v_mfma_f32_16x16x32_bf16 v[124:127], v[156:159], v[188:191], v[124:127]
	v_mfma_f32_16x16x32_bf16 v[120:123], v[164:167], v[188:191], v[120:123]
	v_mfma_f32_16x16x32_bf16 v[108:111], v[156:159], v[196:199], v[108:111]
	v_mfma_f32_16x16x32_bf16 v[104:107], v[164:167], v[196:199], v[104:107]
	v_mfma_f32_16x16x32_bf16 v[92:95], v[156:159], v[204:207], v[92:95]
	v_mfma_f32_16x16x32_bf16 v[88:91], v[164:167], v[204:207], v[88:91]
	v_mfma_f32_16x16x32_bf16 v[76:79], v[156:159], v[212:215], v[76:79]
	v_mfma_f32_16x16x32_bf16 v[72:75], v[164:167], v[212:215], v[72:75]
	v_mfma_f32_16x16x32_bf16 v[116:119], v[168:171], v[184:187], v[116:119]
	v_mfma_f32_16x16x32_bf16 v[112:115], v[176:179], v[184:187], v[112:115]
	v_mfma_f32_16x16x32_bf16 v[100:103], v[168:171], v[192:195], v[100:103]
	v_mfma_f32_16x16x32_bf16 v[96:99], v[176:179], v[192:195], v[96:99]
	v_mfma_f32_16x16x32_bf16 v[84:87], v[168:171], v[200:203], v[84:87]
	v_mfma_f32_16x16x32_bf16 v[80:83], v[176:179], v[200:203], v[80:83]
	v_mfma_f32_16x16x32_bf16 v[68:71], v[168:171], v[208:211], v[68:71]
	v_mfma_f32_16x16x32_bf16 v[64:67], v[176:179], v[208:211], v[64:67]
	v_mfma_f32_16x16x32_bf16 v[116:119], v[172:175], v[188:191], v[116:119]
	v_mfma_f32_16x16x32_bf16 v[112:115], v[180:183], v[188:191], v[112:115]
	v_mfma_f32_16x16x32_bf16 v[100:103], v[172:175], v[196:199], v[100:103]
	v_mfma_f32_16x16x32_bf16 v[96:99], v[180:183], v[196:199], v[96:99]
	v_mfma_f32_16x16x32_bf16 v[84:87], v[172:175], v[204:207], v[84:87]
	v_mfma_f32_16x16x32_bf16 v[80:83], v[180:183], v[204:207], v[80:83]
	v_mfma_f32_16x16x32_bf16 v[68:71], v[172:175], v[212:215], v[68:71]
	v_mfma_f32_16x16x32_bf16 v[64:67], v[180:183], v[212:215], v[64:67]
	s_setprio 0
	s_barrier
; #define PG8_STAGE(bufoff, gbase, voff) do { _Pragma("unroll") for (int _i = 0; _i < 2; ++_i) \
;         __builtin_amdgcn_global_load_lds((const unsigned*)((const char*)(gbase) + (voff)[_i]), (LAS unsigned*)(lds + (bufoff) + ldsw + _i * 8192), 16, 0, 0); } while (0)
; #define PG8_LDA(dst, b, h) do { _Pragma("unroll") for (int m = 0; m < 4; ++m) _Pragma("unroll") for (int k = 0; k < 2; ++k) dst[m][k] = *(const LAS bf16x8*)(lds + PG8_SA(b, h) + aoff + m * 2048 + k * 1024); } while (0)
; #define PG8_LDB(dst, b, h) do { _Pragma("unroll") for (int n = 0; n < 2; ++n) _Pragma("unroll") for (int k = 0; k < 2; ++k) dst[n][k] = *(const LAS bf16x8*)(lds + PG8_SB(b, h) + boff + n * 2048 + k * 1024); } while (0)
; #define PG8_WAIT_V(n) asm volatile("s_waitcnt vmcnt(" #n ")" ::: "memory")
; #define PG8_WAIT_L(n) asm volatile("s_waitcnt lgkmcnt(" #n ")" ::: "memory")
; template <class Epi>
; DI void gemm_phase(LAS unsigned char* lds, const int wid, const Gemm g, const Order& S, const Epi& E) {
;     ...
;         for (int t = 0; t < nt; t += 2) {
;             const bool last = (t == nt - 2);
;             const char* a1 = cA + (size_t)(t + 1) * kstep;
;             const char* a2 = last ? nA : cA + (size_t)(t + 2) * kstep; const char* b2 = last ? nB : cB + (size_t)(t + 2) * kstep;
;             const char* a3 = a2 + kstep; const char* b3 = b2 + kstep;
;             PG8_LDB(B0, 0, 0); PG8_LDB(B1, 0, 1); PG8_SCHED; PG8_LDA(At, 0, 0); PG8_STAGE(PG8_SA(1, 1), a1 + hstepA, voffA);
;             PG8_WAIT_V(8); PG8_WAIT_L(0); PG8_BAR; PG8_MMA(0, 0, At, B0); PG8_MMA(0, 1, At, B1); PG8_BAR; PG8_SCHED;
;             PG8_LDA(At, 0, 1); PG8_STAGE(PG8_SB(0, 0), b2, voffB); PG8_STAGE(PG8_SB(0, 1), b2 + hstepB, voffB); PG8_STAGE(PG8_SA(0, 0), a2, voffA);
;             PG8_WAIT_V(8); PG8_WAIT_L(0); PG8_BAR; PG8_MMA(1, 0, At, B0); PG8_MMA(1, 1, At, B1); PG8_BAR; PG8_SCHED;
;             PG8_LDB(B0, 1, 0); PG8_LDB(B1, 1, 1); PG8_SCHED; PG8_LDA(At, 1, 0); PG8_STAGE(PG8_SA(0, 1), a2 + hstepA, voffA);
;             PG8_WAIT_V(8); PG8_WAIT_L(0); PG8_BAR; PG8_MMA(0, 0, At, B0); PG8_MMA(0, 1, At, B1); PG8_BAR; PG8_SCHED;
;             PG8_LDA(At, 1, 1); PG8_STAGE(PG8_SB(1, 0), b3, voffB); PG8_STAGE(PG8_SB(1, 1), b3 + hstepB, voffB); PG8_STAGE(PG8_SA(1, 0), a3, voffA);
;             PG8_WAIT_V(8); PG8_WAIT_L(0); PG8_BAR; PG8_MMA(1, 0, At, B0); PG8_MMA(1, 1, At, B1); PG8_BAR; PG8_SCHED;
	s_add_i32 s34, s57, s94
	v_lshl_add_u64 v[146:147], v[146:147], 0, s[16:17]
	s_mov_b32 m0, s34
	ds_read_b128 v[184:187], v151 offset:49152
	ds_read_b128 v[188:191], v151 offset:50176
	ds_read_b128 v[192:195], v151 offset:51200
	ds_read_b128 v[196:199], v151 offset:52224
	ds_read_b128 v[200:203], v151 offset:53248
	ds_read_b128 v[204:207], v151 offset:54272
	ds_read_b128 v[208:211], v151 offset:55296
	ds_read_b128 v[212:215], v151 offset:56320
	global_load_lds_dwordx4 v[146:147], off
	s_add_i32 m0, s34, 0x2000
	s_add_u32 s34, s38, 0x30080
	v_lshl_add_u64 v[146:147], v[216:217], 0, s[16:17]
	s_addc_u32 s35, s39, 0
	s_add_i32 s38, s58, s94
	global_load_lds_dwordx4 v[146:147], off
	v_lshl_add_u64 v[146:147], s[34:35], 0, v[130:131]
	s_mov_b32 m0, s38
	s_nop 0
	global_load_lds_dwordx4 v[146:147], off
	v_lshl_add_u64 v[146:147], s[34:35], 0, v[134:135]
	s_add_i32 m0, s38, 0x2000
	s_nop 0
	global_load_lds_dwordx4 v[146:147], off
	v_lshl_add_u64 v[146:147], v[218:219], 0, s[16:17]
	s_mov_b32 m0, s46
	s_nop 0
	global_load_lds_dwordx4 v[146:147], off
	v_lshl_add_u64 v[146:147], v[220:221], 0, s[16:17]
	s_mov_b32 m0, s47
	s_nop 0
	global_load_lds_dwordx4 v[146:147], off
	s_waitcnt vmcnt(8)
	s_waitcnt lgkmcnt(0)
	s_barrier
	s_setprio 1
	v_mfma_f32_16x16x32_bf16 v[60:63], v[152:155], v[184:187], v[60:63]
	v_mfma_f32_16x16x32_bf16 v[56:59], v[160:163], v[184:187], v[56:59]
	v_mfma_f32_16x16x32_bf16 v[44:47], v[152:155], v[192:195], v[44:47]
	v_mfma_f32_16x16x32_bf16 v[40:43], v[160:163], v[192:195], v[40:43]
	v_mfma_f32_16x16x32_bf16 v[28:31], v[152:155], v[200:203], v[28:31]
	v_mfma_f32_16x16x32_bf16 v[24:27], v[160:163], v[200:203], v[24:27]
	v_mfma_f32_16x16x32_bf16 v[12:15], v[152:155], v[208:211], v[12:15]
	v_mfma_f32_16x16x32_bf16 v[8:11], v[160:163], v[208:211], v[8:11]
	v_mfma_f32_16x16x32_bf16 v[60:63], v[156:159], v[188:191], v[60:63]
	v_mfma_f32_16x16x32_bf16 v[56:59], v[164:167], v[188:191], v[56:59]
	v_mfma_f32_16x16x32_bf16 v[44:47], v[156:159], v[196:199], v[44:47]
	v_mfma_f32_16x16x32_bf16 v[40:43], v[164:167], v[196:199], v[40:43]
	v_mfma_f32_16x16x32_bf16 v[28:31], v[156:159], v[204:207], v[28:31]
	v_mfma_f32_16x16x32_bf16 v[24:27], v[164:167], v[204:207], v[24:27]
	v_mfma_f32_16x16x32_bf16 v[12:15], v[156:159], v[212:215], v[12:15]
	v_mfma_f32_16x16x32_bf16 v[8:11], v[164:167], v[212:215], v[8:11]
	v_mfma_f32_16x16x32_bf16 v[52:55], v[168:171], v[184:187], v[52:55]
	v_mfma_f32_16x16x32_bf16 v[48:51], v[176:179], v[184:187], v[48:51]
	v_mfma_f32_16x16x32_bf16 v[36:39], v[168:171], v[192:195], v[36:39]
	v_mfma_f32_16x16x32_bf16 v[32:35], v[176:179], v[192:195], v[32:35]
	v_mfma_f32_16x16x32_bf16 v[20:23], v[168:171], v[200:203], v[20:23]
	v_mfma_f32_16x16x32_bf16 v[16:19], v[176:179], v[200:203], v[16:19]
	v_mfma_f32_16x16x32_bf16 v[4:7], v[168:171], v[208:211], v[4:7]
	v_mfma_f32_16x16x32_bf16 v[0:3], v[176:179], v[208:211], v[0:3]
	v_mfma_f32_16x16x32_bf16 v[52:55], v[172:175], v[188:191], v[52:55]
	v_mfma_f32_16x16x32_bf16 v[48:51], v[180:183], v[188:191], v[48:51]
	v_mfma_f32_16x16x32_bf16 v[36:39], v[172:175], v[196:199], v[36:39]
	v_mfma_f32_16x16x32_bf16 v[32:35], v[180:183], v[196:199], v[32:35]
	v_mfma_f32_16x16x32_bf16 v[20:23], v[172:175], v[204:207], v[20:23]
	v_mfma_f32_16x16x32_bf16 v[16:19], v[180:183], v[204:207], v[16:19]
	v_mfma_f32_16x16x32_bf16 v[4:7], v[172:175], v[212:215], v[4:7]
	v_mfma_f32_16x16x32_bf16 v[0:3], v[180:183], v[212:215], v[0:3]
	s_setprio 0
	s_barrier
	s_add_i32 s56, s56, 2
	s_add_u32 s54, s54, 0x100
	s_addc_u32 s55, s55, 0
	s_cmp_gt_u32 s56, 9
	s_mov_b64 s[34:35], s[36:37]
	s_cbranch_scc0 .LBB0_989
	s_branch .Lpeel_exit_4
.LBB0_989:
	ds_read_b128 v[152:155], v149
	ds_read_b128 v[156:159], v149 offset:1024
	ds_read_b128 v[160:163], v149 offset:2048
	ds_read_b128 v[164:167], v149 offset:3072
	ds_read_b128 v[168:171], v150
	ds_read_b128 v[172:175], v150 offset:1024
	ds_read_b128 v[176:179], v150 offset:2048
	ds_read_b128 v[180:183], v150 offset:3072
	s_add_u32 s36, s34, 0x100
	s_addc_u32 s37, s35, 0
	s_cmp_eq_u32 s56, 8
	s_cselect_b32 s41, s11, s37
	s_cselect_b32 s40, s10, s36
	s_cselect_b32 s39, s31, s55
	s_cselect_b32 s38, s30, s54
	v_lshl_add_u64 v[146:147], s[34:35], 0, v[138:139]
	s_add_i32 m0, s25, 0xc000
	ds_read_b128 v[184:187], v151
	ds_read_b128 v[188:191], v151 offset:1024
	ds_read_b128 v[192:195], v151 offset:2048
	ds_read_b128 v[196:199], v151 offset:3072
	ds_read_b128 v[200:203], v151 offset:4096
	ds_read_b128 v[204:207], v151 offset:5120
	ds_read_b128 v[208:211], v151 offset:6144
	ds_read_b128 v[212:215], v151 offset:7168
	global_load_lds_dwordx4 v[146:147], off
	v_lshl_add_u64 v[146:147], s[34:35], 0, v[140:141]
	s_add_i32 m0, s25, 0xe000
	s_nop 0
	global_load_lds_dwordx4 v[146:147], off
	s_waitcnt vmcnt(8)
	s_waitcnt lgkmcnt(0)
	s_barrier
; #define PG8_STAGE(bufoff, gbase, voff) do { _Pragma("unroll") for (int _i = 0; _i < 2; ++_i) \
;         __builtin_amdgcn_global_load_lds((const unsigned*)((const char*)(gbase) + (voff)[_i]), (LAS unsigned*)(lds + (bufoff) + ldsw + _i * 8192), 16, 0, 0); } while (0)
; #define PG8_LDA(dst, b, h) do { _Pragma("unroll") for (int m = 0; m < 4; ++m) _Pragma("unroll") for (int k = 0; k < 2; ++k) dst[m][k] = *(const LAS bf16x8*)(lds + PG8_SA(b, h) + aoff + m * 2048 + k * 1024); } while (0)
; #define PG8_MMA(ai, bj, At, Bt) do { __builtin_amdgcn_s_setprio(1); _Pragma("unroll") for (int m = 0; m < 4; ++m) _Pragma("unroll") for (int n = 0; n < 2; ++n) _Pragma("unroll") for (int k = 0; k < 2; ++k) \
;         acc[ai][bj][m][n] = __builtin_amdgcn_mfma_f32_16x16x32_bf16(Bt[n][k], At[m][k], acc[ai][bj][m][n], 0, 0, 0); __builtin_amdgcn_s_setprio(0); } while (0)
; #define PG8_WAIT_V(n) asm volatile("s_waitcnt vmcnt(" #n ")" ::: "memory")
; #define PG8_WAIT_L(n) asm volatile("s_waitcnt lgkmcnt(" #n ")" ::: "memory")
; #define PG8_BAR __builtin_amdgcn_s_barrier()
; #define PG8_SCHED __builtin_amdgcn_sched_barrier(0)
; template <class Epi>
; DI void gemm_phase(LAS unsigned char* lds, const int wid, const Gemm g, const Order& S, const Epi& E) {
;     ...
;             PG8_WAIT_V(8); PG8_WAIT_L(0); PG8_BAR; PG8_MMA(0, 0, At, B0); PG8_MMA(0, 1, At, B1); PG8_BAR; PG8_SCHED;
;             PG8_LDA(At, 0, 1); PG8_STAGE(PG8_SB(0, 0), b2, voffB); PG8_STAGE(PG8_SB(0, 1), b2 + hstepB, voffB); PG8_STAGE(PG8_SA(0, 0), a2, voffA);
;             PG8_WAIT_V(8); PG8_WAIT_L(0); PG8_BAR; PG8_MMA(1, 0, At, B0); PG8_MMA(1, 1, At, B1); PG8_BAR; PG8_SCHED;
	s_setprio 1
	v_mfma_f32_16x16x32_bf16 v[124:127], v[152:155], v[184:187], v[124:127]
	v_mfma_f32_16x16x32_bf16 v[120:123], v[160:163], v[184:187], v[120:123]
	v_mfma_f32_16x16x32_bf16 v[108:111], v[152:155], v[192:195], v[108:111]
	v_mfma_f32_16x16x32_bf16 v[104:107], v[160:163], v[192:195], v[104:107]
	v_mfma_f32_16x16x32_bf16 v[92:95], v[152:155], v[200:203], v[92:95]
	v_mfma_f32_16x16x32_bf16 v[88:91], v[160:163], v[200:203], v[88:91]
	v_mfma_f32_16x16x32_bf16 v[76:79], v[152:155], v[208:211], v[76:79]
	v_mfma_f32_16x16x32_bf16 v[72:75], v[160:163], v[208:211], v[72:75]
	v_mfma_f32_16x16x32_bf16 v[124:127], v[156:159], v[188:191], v[124:127]
	v_mfma_f32_16x16x32_bf16 v[120:123], v[164:167], v[188:191], v[120:123]
	v_mfma_f32_16x16x32_bf16 v[108:111], v[156:159], v[196:199], v[108:111]
	v_mfma_f32_16x16x32_bf16 v[104:107], v[164:167], v[196:199], v[104:107]
	v_mfma_f32_16x16x32_bf16 v[92:95], v[156:159], v[204:207], v[92:95]
	v_mfma_f32_16x16x32_bf16 v[88:91], v[164:167], v[204:207], v[88:91]
	v_mfma_f32_16x16x32_bf16 v[76:79], v[156:159], v[212:215], v[76:79]
	v_mfma_f32_16x16x32_bf16 v[72:75], v[164:167], v[212:215], v[72:75]
	v_mfma_f32_16x16x32_bf16 v[116:119], v[168:171], v[184:187], v[116:119]
	v_mfma_f32_16x16x32_bf16 v[112:115], v[176:179], v[184:187], v[112:115]
	v_mfma_f32_16x16x32_bf16 v[100:103], v[168:171], v[192:195], v[100:103]
	v_mfma_f32_16x16x32_bf16 v[96:99], v[176:179], v[192:195], v[96:99]
	v_mfma_f32_16x16x32_bf16 v[84:87], v[168:171], v[200:203], v[84:87]
	v_mfma_f32_16x16x32_bf16 v[80:83], v[176:179], v[200:203], v[80:83]
	v_mfma_f32_16x16x32_bf16 v[68:71], v[168:171], v[208:211], v[68:71]
	v_mfma_f32_16x16x32_bf16 v[64:67], v[176:179], v[208:211], v[64:67]
	v_mfma_f32_16x16x32_bf16 v[116:119], v[172:175], v[188:191], v[116:119]
	v_mfma_f32_16x16x32_bf16 v[112:115], v[180:183], v[188:191], v[112:115]
	v_mfma_f32_16x16x32_bf16 v[100:103], v[172:175], v[196:199], v[100:103]
	v_mfma_f32_16x16x32_bf16 v[96:99], v[180:183], v[196:199], v[96:99]
	v_mfma_f32_16x16x32_bf16 v[84:87], v[172:175], v[204:207], v[84:87]
	v_mfma_f32_16x16x32_bf16 v[80:83], v[180:183], v[204:207], v[80:83]
	v_mfma_f32_16x16x32_bf16 v[68:71], v[172:175], v[212:215], v[68:71]
	v_mfma_f32_16x16x32_bf16 v[64:67], v[180:183], v[212:215], v[64:67]
	s_setprio 0
	s_barrier
	s_add_i32 s34, s48, s94
	v_lshl_add_u64 v[146:147], s[38:39], 0, v[130:131]
	s_mov_b32 m0, s34
	ds_read_b128 v[184:187], v151 offset:16384
	ds_read_b128 v[188:191], v151 offset:17408
	ds_read_b128 v[192:195], v151 offset:18432
	ds_read_b128 v[196:199], v151 offset:19456
	ds_read_b128 v[200:203], v151 offset:20480
	ds_read_b128 v[204:207], v151 offset:21504
	ds_read_b128 v[208:211], v151 offset:22528
	ds_read_b128 v[212:215], v151 offset:23552
	global_load_lds_dwordx4 v[146:147], off
	s_add_i32 m0, s34, 0x2000
	s_add_u32 s34, s38, 0x30000
	v_lshl_add_u64 v[216:217], s[38:39], 0, v[134:135]
	s_addc_u32 s35, s39, 0
	s_add_i32 s57, s49, s94
	global_load_lds_dwordx4 v[216:217], off
	v_lshl_add_u64 v[218:219], s[34:35], 0, v[130:131]
	s_mov_b32 m0, s57
	v_lshl_add_u64 v[220:221], s[40:41], 0, v[132:133]
	global_load_lds_dwordx4 v[218:219], off
	v_lshl_add_u64 v[218:219], s[34:35], 0, v[134:135]
	s_add_i32 m0, s57, 0x2000
	s_nop 0
	global_load_lds_dwordx4 v[218:219], off
	v_lshl_add_u64 v[218:219], s[40:41], 0, v[128:129]
	s_mov_b32 m0, s25
	s_nop 0
	global_load_lds_dwordx4 v[218:219], off
	s_mov_b32 m0, s42
	s_nop 0
	global_load_lds_dwordx4 v[220:221], off
	s_waitcnt vmcnt(8)
	s_waitcnt lgkmcnt(0)
	s_barrier
	s_setprio 1
	v_mfma_f32_16x16x32_bf16 v[60:63], v[152:155], v[184:187], v[60:63]
	v_mfma_f32_16x16x32_bf16 v[56:59], v[160:163], v[184:187], v[56:59]
	v_mfma_f32_16x16x32_bf16 v[44:47], v[152:155], v[192:195], v[44:47]
	v_mfma_f32_16x16x32_bf16 v[40:43], v[160:163], v[192:195], v[40:43]
	v_mfma_f32_16x16x32_bf16 v[28:31], v[152:155], v[200:203], v[28:31]
	v_mfma_f32_16x16x32_bf16 v[24:27], v[160:163], v[200:203], v[24:27]
	v_mfma_f32_16x16x32_bf16 v[12:15], v[152:155], v[208:211], v[12:15]
	v_mfma_f32_16x16x32_bf16 v[8:11], v[160:163], v[208:211], v[8:11]
	v_mfma_f32_16x16x32_bf16 v[60:63], v[156:159], v[188:191], v[60:63]
	v_mfma_f32_16x16x32_bf16 v[56:59], v[164:167], v[188:191], v[56:59]
	v_mfma_f32_16x16x32_bf16 v[44:47], v[156:159], v[196:199], v[44:47]
	v_mfma_f32_16x16x32_bf16 v[40:43], v[164:167], v[196:199], v[40:43]
	v_mfma_f32_16x16x32_bf16 v[28:31], v[156:159], v[204:207], v[28:31]
	v_mfma_f32_16x16x32_bf16 v[24:27], v[164:167], v[204:207], v[24:27]
	v_mfma_f32_16x16x32_bf16 v[12:15], v[156:159], v[212:215], v[12:15]
	v_mfma_f32_16x16x32_bf16 v[8:11], v[164:167], v[212:215], v[8:11]
	v_mfma_f32_16x16x32_bf16 v[52:55], v[168:171], v[184:187], v[52:55]
	v_mfma_f32_16x16x32_bf16 v[48:51], v[176:179], v[184:187], v[48:51]
	v_mfma_f32_16x16x32_bf16 v[36:39], v[168:171], v[192:195], v[36:39]
	v_mfma_f32_16x16x32_bf16 v[32:35], v[176:179], v[192:195], v[32:35]
	v_mfma_f32_16x16x32_bf16 v[20:23], v[168:171], v[200:203], v[20:23]
	v_mfma_f32_16x16x32_bf16 v[16:19], v[176:179], v[200:203], v[16:19]
	v_mfma_f32_16x16x32_bf16 v[4:7], v[168:171], v[208:211], v[4:7]
	v_mfma_f32_16x16x32_bf16 v[0:3], v[176:179], v[208:211], v[0:3]
	v_mfma_f32_16x16x32_bf16 v[52:55], v[172:175], v[188:191], v[52:55]
	v_mfma_f32_16x16x32_bf16 v[48:51], v[180:183], v[188:191], v[48:51]
	v_mfma_f32_16x16x32_bf16 v[36:39], v[172:175], v[196:199], v[36:39]
	v_mfma_f32_16x16x32_bf16 v[32:35], v[180:183], v[196:199], v[32:35]
	v_mfma_f32_16x16x32_bf16 v[20:23], v[172:175], v[204:207], v[20:23]
	v_mfma_f32_16x16x32_bf16 v[16:19], v[180:183], v[204:207], v[16:19]
	v_mfma_f32_16x16x32_bf16 v[4:7], v[172:175], v[212:215], v[4:7]
	v_mfma_f32_16x16x32_bf16 v[0:3], v[180:183], v[212:215], v[0:3]
	s_setprio 0
	s_barrier
; #define PG8_STAGE(bufoff, gbase, voff) do { _Pragma("unroll") for (int _i = 0; _i < 2; ++_i) \
;         __builtin_amdgcn_global_load_lds((const unsigned*)((const char*)(gbase) + (voff)[_i]), (LAS unsigned*)(lds + (bufoff) + ldsw + _i * 8192), 16, 0, 0); } while (0)
; #define PG8_LDA(dst, b, h) do { _Pragma("unroll") for (int m = 0; m < 4; ++m) _Pragma("unroll") for (int k = 0; k < 2; ++k) dst[m][k] = *(const LAS bf16x8*)(lds + PG8_SA(b, h) + aoff + m * 2048 + k * 1024); } while (0)
; #define PG8_LDB(dst, b, h) do { _Pragma("unroll") for (int n = 0; n < 2; ++n) _Pragma("unroll") for (int k = 0; k < 2; ++k) dst[n][k] = *(const LAS bf16x8*)(lds + PG8_SB(b, h) + boff + n * 2048 + k * 1024); } while (0)
; #define PG8_MMA(ai, bj, At, Bt) do { __builtin_amdgcn_s_setprio(1); _Pragma("unroll") for (int m = 0; m < 4; ++m) _Pragma("unroll") for (int n = 0; n < 2; ++n) _Pragma("unroll") for (int k = 0; k < 2; ++k) \
;         acc[ai][bj][m][n] = __builtin_amdgcn_mfma_f32_16x16x32_bf16(Bt[n][k], At[m][k], acc[ai][bj][m][n], 0, 0, 0); __builtin_amdgcn_s_setprio(0); } while (0)
; #define PG8_WAIT_V(n) asm volatile("s_waitcnt vmcnt(" #n ")" ::: "memory")
; #define PG8_WAIT_L(n) asm volatile("s_waitcnt lgkmcnt(" #n ")" ::: "memory")
; #define PG8_BAR __builtin_amdgcn_s_barrier()
; #define PG8_SCHED __builtin_amdgcn_sched_barrier(0)
; template <class Epi>
; DI void gemm_phase(LAS unsigned char* lds, const int wid, const Gemm g, const Order& S, const Epi& E) {
;     ...
;         for (int t = 0; t < nt; t += 2) {
;     ...
;             PG8_LDB(B0, 1, 0); PG8_LDB(B1, 1, 1); PG8_SCHED; PG8_LDA(At, 1, 0); PG8_STAGE(PG8_SA(0, 1), a2 + hstepA, voffA);
;             PG8_WAIT_V(8); PG8_WAIT_L(0); PG8_BAR; PG8_MMA(0, 0, At, B0); PG8_MMA(0, 1, At, B1); PG8_BAR; PG8_SCHED;
;             PG8_LDA(At, 1, 1); PG8_STAGE(PG8_SB(1, 0), b3, voffB); PG8_STAGE(PG8_SB(1, 1), b3 + hstepB, voffB); PG8_STAGE(PG8_SA(1, 0), a3, voffA);
;             PG8_WAIT_V(8); PG8_WAIT_L(0); PG8_BAR; PG8_MMA(1, 0, At, B0); PG8_MMA(1, 1, At, B1); PG8_BAR; PG8_SCHED;
	s_add_i32 s57, 0, 0x18000
	v_add_u32_e32 v136, s57, v148
	s_add_i32 s58, 0, 0x1c000
	ds_read_b128 v[152:155], v136
	ds_read_b128 v[156:159], v136 offset:1024
	ds_read_b128 v[160:163], v136 offset:2048
	ds_read_b128 v[164:167], v136 offset:3072
	v_add_u32_e32 v136, s58, v148
	ds_read_b128 v[168:171], v136
	ds_read_b128 v[172:175], v136 offset:1024
	ds_read_b128 v[176:179], v136 offset:2048
	ds_read_b128 v[180:183], v136 offset:3072
	s_add_u32 s34, s40, 0x30000
	s_addc_u32 s35, s41, 0
	s_mov_b32 m0, s43
	v_lshl_add_u64 v[222:223], s[34:35], 0, v[128:129]
	ds_read_b128 v[184:187], v151 offset:32768
	ds_read_b128 v[188:191], v151 offset:33792
	ds_read_b128 v[192:195], v151 offset:34816
	ds_read_b128 v[196:199], v151 offset:35840
	ds_read_b128 v[200:203], v151 offset:36864
	ds_read_b128 v[204:207], v151 offset:37888
	ds_read_b128 v[208:211], v151 offset:38912
	ds_read_b128 v[212:215], v151 offset:39936
	global_load_lds_dwordx4 v[222:223], off
	v_lshl_add_u64 v[222:223], s[34:35], 0, v[132:133]
	s_mov_b32 m0, s44
	s_nop 0
	global_load_lds_dwordx4 v[222:223], off
	s_waitcnt vmcnt(8)
	s_waitcnt lgkmcnt(0)
	s_barrier
	s_setprio 1
	v_mfma_f32_16x16x32_bf16 v[124:127], v[152:155], v[184:187], v[124:127]
	v_mfma_f32_16x16x32_bf16 v[120:123], v[160:163], v[184:187], v[120:123]
	v_mfma_f32_16x16x32_bf16 v[108:111], v[152:155], v[192:195], v[108:111]
	v_mfma_f32_16x16x32_bf16 v[104:107], v[160:163], v[192:195], v[104:107]
	v_mfma_f32_16x16x32_bf16 v[92:95], v[152:155], v[200:203], v[92:95]
	v_mfma_f32_16x16x32_bf16 v[88:91], v[160:163], v[200:203], v[88:91]
	v_mfma_f32_16x16x32_bf16 v[76:79], v[152:155], v[208:211], v[76:79]
	v_mfma_f32_16x16x32_bf16 v[72:75], v[160:163], v[208:211], v[72:75]
	v_mfma_f32_16x16x32_bf16 v[124:127], v[156:159], v[188:191], v[124:127]
	v_mfma_f32_16x16x32_bf16 v[120:123], v[164:167], v[188:191], v[120:123]
	v_mfma_f32_16x16x32_bf16 v[108:111], v[156:159], v[196:199], v[108:111]
	v_mfma_f32_16x16x32_bf16 v[104:107], v[164:167], v[196:199], v[104:107]
	v_mfma_f32_16x16x32_bf16 v[92:95], v[156:159], v[204:207], v[92:95]
	v_mfma_f32_16x16x32_bf16 v[88:91], v[164:167], v[204:207], v[88:91]
	v_mfma_f32_16x16x32_bf16 v[76:79], v[156:159], v[212:215], v[76:79]
	v_mfma_f32_16x16x32_bf16 v[72:75], v[164:167], v[212:215], v[72:75]
	v_mfma_f32_16x16x32_bf16 v[116:119], v[168:171], v[184:187], v[116:119]
	v_mfma_f32_16x16x32_bf16 v[112:115], v[176:179], v[184:187], v[112:115]
	v_mfma_f32_16x16x32_bf16 v[100:103], v[168:171], v[192:195], v[100:103]
	v_mfma_f32_16x16x32_bf16 v[96:99], v[176:179], v[192:195], v[96:99]
	v_mfma_f32_16x16x32_bf16 v[84:87], v[168:171], v[200:203], v[84:87]
	v_mfma_f32_16x16x32_bf16 v[80:83], v[176:179], v[200:203], v[80:83]
	v_mfma_f32_16x16x32_bf16 v[68:71], v[168:171], v[208:211], v[68:71]
	v_mfma_f32_16x16x32_bf16 v[64:67], v[176:179], v[208:211], v[64:67]
	v_mfma_f32_16x16x32_bf16 v[116:119], v[172:175], v[188:191], v[116:119]
	v_mfma_f32_16x16x32_bf16 v[112:115], v[180:183], v[188:191], v[112:115]
	v_mfma_f32_16x16x32_bf16 v[100:103], v[172:175], v[196:199], v[100:103]
	v_mfma_f32_16x16x32_bf16 v[96:99], v[180:183], v[196:199], v[96:99]
	v_mfma_f32_16x16x32_bf16 v[84:87], v[172:175], v[204:207], v[84:87]
	v_mfma_f32_16x16x32_bf16 v[80:83], v[180:183], v[204:207], v[80:83]
	v_mfma_f32_16x16x32_bf16 v[68:71], v[172:175], v[212:215], v[68:71]
	v_mfma_f32_16x16x32_bf16 v[64:67], v[180:183], v[212:215], v[64:67]
	s_setprio 0
	s_barrier
	s_add_i32 s34, s57, s94
	v_lshl_add_u64 v[146:147], v[146:147], 0, s[16:17]
	s_mov_b32 m0, s34
	ds_read_b128 v[184:187], v151 offset:49152
	ds_read_b128 v[188:191], v151 offset:50176
	ds_read_b128 v[192:195], v151 offset:51200
	ds_read_b128 v[196:199], v151 offset:52224
	ds_read_b128 v[200:203], v151 offset:53248
	ds_read_b128 v[204:207], v151 offset:54272
	ds_read_b128 v[208:211], v151 offset:55296
	ds_read_b128 v[212:215], v151 offset:56320
	global_load_lds_dwordx4 v[146:147], off
	s_add_i32 m0, s34, 0x2000
	s_add_u32 s34, s38, 0x30080
	v_lshl_add_u64 v[146:147], v[216:217], 0, s[16:17]
	s_addc_u32 s35, s39, 0
	s_add_i32 s38, s58, s94
	global_load_lds_dwordx4 v[146:147], off
	v_lshl_add_u64 v[146:147], s[34:35], 0, v[130:131]
	s_mov_b32 m0, s38
	s_nop 0
	global_load_lds_dwordx4 v[146:147], off
	v_lshl_add_u64 v[146:147], s[34:35], 0, v[134:135]
	s_add_i32 m0, s38, 0x2000
	s_nop 0
	global_load_lds_dwordx4 v[146:147], off
	v_lshl_add_u64 v[146:147], v[218:219], 0, s[16:17]
	s_mov_b32 m0, s46
	s_nop 0
	global_load_lds_dwordx4 v[146:147], off
	v_lshl_add_u64 v[146:147], v[220:221], 0, s[16:17]
	s_mov_b32 m0, s47
	s_nop 0
	global_load_lds_dwordx4 v[146:147], off
	s_waitcnt vmcnt(8)
	s_waitcnt lgkmcnt(0)
	s_barrier
	s_setprio 1
	v_mfma_f32_16x16x32_bf16 v[60:63], v[152:155], v[184:187], v[60:63]
	v_mfma_f32_16x16x32_bf16 v[56:59], v[160:163], v[184:187], v[56:59]
	v_mfma_f32_16x16x32_bf16 v[44:47], v[152:155], v[192:195], v[44:47]
	v_mfma_f32_16x16x32_bf16 v[40:43], v[160:163], v[192:195], v[40:43]
	v_mfma_f32_16x16x32_bf16 v[28:31], v[152:155], v[200:203], v[28:31]
	v_mfma_f32_16x16x32_bf16 v[24:27], v[160:163], v[200:203], v[24:27]
	v_mfma_f32_16x16x32_bf16 v[12:15], v[152:155], v[208:211], v[12:15]
	v_mfma_f32_16x16x32_bf16 v[8:11], v[160:163], v[208:211], v[8:11]
	v_mfma_f32_16x16x32_bf16 v[60:63], v[156:159], v[188:191], v[60:63]
	v_mfma_f32_16x16x32_bf16 v[56:59], v[164:167], v[188:191], v[56:59]
	v_mfma_f32_16x16x32_bf16 v[44:47], v[156:159], v[196:199], v[44:47]
	v_mfma_f32_16x16x32_bf16 v[40:43], v[164:167], v[196:199], v[40:43]
	v_mfma_f32_16x16x32_bf16 v[28:31], v[156:159], v[204:207], v[28:31]
	v_mfma_f32_16x16x32_bf16 v[24:27], v[164:167], v[204:207], v[24:27]
	v_mfma_f32_16x16x32_bf16 v[12:15], v[156:159], v[212:215], v[12:15]
	v_mfma_f32_16x16x32_bf16 v[8:11], v[164:167], v[212:215], v[8:11]
	v_mfma_f32_16x16x32_bf16 v[52:55], v[168:171], v[184:187], v[52:55]
	v_mfma_f32_16x16x32_bf16 v[48:51], v[176:179], v[184:187], v[48:51]
	v_mfma_f32_16x16x32_bf16 v[36:39], v[168:171], v[192:195], v[36:39]
	v_mfma_f32_16x16x32_bf16 v[32:35], v[176:179], v[192:195], v[32:35]
	v_mfma_f32_16x16x32_bf16 v[20:23], v[168:171], v[200:203], v[20:23]
	v_mfma_f32_16x16x32_bf16 v[16:19], v[176:179], v[200:203], v[16:19]
	v_mfma_f32_16x16x32_bf16 v[4:7], v[168:171], v[208:211], v[4:7]
	v_mfma_f32_16x16x32_bf16 v[0:3], v[176:179], v[208:211], v[0:3]
	v_mfma_f32_16x16x32_bf16 v[52:55], v[172:175], v[188:191], v[52:55]
	v_mfma_f32_16x16x32_bf16 v[48:51], v[180:183], v[188:191], v[48:51]
	v_mfma_f32_16x16x32_bf16 v[36:39], v[172:175], v[196:199], v[36:39]
	v_mfma_f32_16x16x32_bf16 v[32:35], v[180:183], v[196:199], v[32:35]
	v_mfma_f32_16x16x32_bf16 v[20:23], v[172:175], v[204:207], v[20:23]
	v_mfma_f32_16x16x32_bf16 v[16:19], v[180:183], v[204:207], v[16:19]
	v_mfma_f32_16x16x32_bf16 v[4:7], v[172:175], v[212:215], v[4:7]
	v_mfma_f32_16x16x32_bf16 v[0:3], v[180:183], v[212:215], v[0:3]
	s_setprio 0
	s_barrier
	s_add_i32 s56, s56, 2
	s_add_u32 s54, s54, 0x100
	s_addc_u32 s55, s55, 0
	s_cmp_gt_u32 s56, 9
	s_mov_b64 s[34:35], s[36:37]
	s_cbranch_scc0 .LBB0_989

; #define PG8_STAGE(bufoff, gbase, voff) do { _Pragma("unroll") for (int _i = 0; _i < 2; ++_i) \
;         __builtin_amdgcn_global_load_lds((const unsigned*)((const char*)(gbase) + (voff)[_i]), (LAS unsigned*)(lds + (bufoff) + ldsw + _i * 8192), 16, 0, 0); } while (0)
; #define PG8_LDA(dst, b, h) do { _Pragma("unroll") for (int m = 0; m < 4; ++m) _Pragma("unroll") for (int k = 0; k < 2; ++k) dst[m][k] = *(const LAS bf16x8*)(lds + PG8_SA(b, h) + aoff + m * 2048 + k * 1024); } while (0)
; #define PG8_LDB(dst, b, h) do { _Pragma("unroll") for (int n = 0; n < 2; ++n) _Pragma("unroll") for (int k = 0; k < 2; ++k) dst[n][k] = *(const LAS bf16x8*)(lds + PG8_SB(b, h) + boff + n * 2048 + k * 1024); } while (0)
; #define PG8_MMA(ai, bj, At, Bt) do { __builtin_amdgcn_s_setprio(1); _Pragma("unroll") for (int m = 0; m < 4; ++m) _Pragma("unroll") for (int n = 0; n < 2; ++n) _Pragma("unroll") for (int k = 0; k < 2; ++k) \
;         acc[ai][bj][m][n] = __builtin_amdgcn_mfma_f32_16x16x32_bf16(Bt[n][k], At[m][k], acc[ai][bj][m][n], 0, 0, 0); __builtin_amdgcn_s_setprio(0); } while (0)
; template <class Epi>
; DI void gemm_phase(LAS unsigned char* lds, const int wid, const Gemm g, const Order& S, const Epi& E) {
;     ...
;         const bool has_next = S.next(ui + 1, nxt);
;         const char* nA = has_next ? (const char*)(g.A + (size_t)nxt.g * g.gsA + (size_t)nxt.pm * BM * g.lda) : cA;
;         const char* nB = has_next ? (const char*)(g.Bt + (size_t)nxt.g * g.gsB + (size_t)nxt.pn * BM * g.ldb) : cB;
;         for (int t = 0; t < nt; t += 2) {
;             const bool last = (t == nt - 2);
;             const char* a1 = cA + (size_t)(t + 1) * kstep;
;             const char* a2 = last ? nA : cA + (size_t)(t + 2) * kstep; const char* b2 = last ? nB : cB + (size_t)(t + 2) * kstep;
;             const char* a3 = a2 + kstep; const char* b3 = b2 + kstep;
;             PG8_LDB(B0, 0, 0); PG8_LDB(B1, 0, 1); PG8_SCHED; PG8_LDA(At, 0, 0); PG8_STAGE(PG8_SA(1, 1), a1 + hstepA, voffA);
;             PG8_WAIT_V(8); PG8_WAIT_L(0); PG8_BAR; PG8_MMA(0, 0, At, B0); PG8_MMA(0, 1, At, B1); PG8_BAR; PG8_SCHED;
;             PG8_LDA(At, 0, 1); PG8_STAGE(PG8_SB(0, 0), b2, voffB); PG8_STAGE(PG8_SB(0, 1), b2 + hstepB, voffB); PG8_STAGE(PG8_SA(0, 0), a2, voffA);
;             PG8_WAIT_V(8); PG8_WAIT_L(0); PG8_BAR; PG8_MMA(1, 0, At, B0); PG8_MMA(1, 1, At, B1); PG8_BAR; PG8_SCHED;
.LBB0_1012:
	s_ashr_i32 s29, s28, 31
	s_lshl_b64 s[34:35], s[28:29], 18
	s_add_u32 s34, s6, s34
	s_addc_u32 s35, s7, s35
	s_and_b64 s[36:37], s[8:9], exec
	s_cselect_b32 s29, s35, s41
	s_cselect_b32 s54, s34, s40
	s_ashr_i32 s31, s30, 31
	s_lshl_b64 s[36:37], s[30:31], 18
	s_add_u32 s36, s21, s36
	s_addc_u32 s37, s24, s37
	s_and_b64 s[44:45], s[8:9], exec
	s_cselect_b32 s31, s37, s43
	s_cselect_b32 s55, s36, s42
	s_add_u32 s40, s40, 0x20080
	s_addc_u32 s41, s41, 0
	s_add_u32 s56, s42, 0x100
	v_mov_b32_e32 v0, 0
	s_addc_u32 s57, s43, 0
	s_mov_b32 s58, -2
	s_waitcnt vmcnt(0)
	ds_read_b128 v[144:147], v153
	ds_read_b128 v[148:151], v153 offset:1024
	ds_read_b128 v[156:159], v153 offset:2048
	ds_read_b128 v[160:163], v153 offset:3072
	ds_read_b128 v[164:167], v154
	ds_read_b128 v[168:171], v154 offset:1024
	ds_read_b128 v[172:175], v154 offset:2048
	ds_read_b128 v[176:179], v154 offset:3072
	s_add_u32 s42, s40, 0xfffe0080
	s_addc_u32 s43, s41, -1
	s_cmp_eq_u32 s58, 4
	s_cselect_b32 s45, s29, s43
	s_cselect_b32 s44, s54, s42
	s_cselect_b32 s43, s31, s57
	s_cselect_b32 s42, s55, s56
	v_lshl_add_u64 v[212:213], s[40:41], 0, v[136:137]
	s_add_i32 m0, s25, 0xc000
	ds_read_b128 v[180:183], v155
	ds_read_b128 v[184:187], v155 offset:1024
	ds_read_b128 v[188:191], v155 offset:2048
	ds_read_b128 v[192:195], v155 offset:3072
	ds_read_b128 v[196:199], v155 offset:4096
	ds_read_b128 v[200:203], v155 offset:5120
	ds_read_b128 v[204:207], v155 offset:6144
	ds_read_b128 v[208:211], v155 offset:7168
	global_load_lds_dwordx4 v[212:213], off
	v_lshl_add_u64 v[212:213], s[40:41], 0, v[138:139]
	s_add_i32 m0, s25, 0xe000
	s_nop 0
	global_load_lds_dwordx4 v[212:213], off
	s_waitcnt vmcnt(8)
	s_waitcnt lgkmcnt(0)
	s_barrier
	s_setprio 1
	v_mfma_f32_16x16x32_bf16 v[124:127], v[144:147], v[180:183], 0
	v_mfma_f32_16x16x32_bf16 v[120:123], v[156:159], v[180:183], 0
	v_mfma_f32_16x16x32_bf16 v[116:119], v[144:147], v[188:191], 0
	v_mfma_f32_16x16x32_bf16 v[112:115], v[156:159], v[188:191], 0
	v_mfma_f32_16x16x32_bf16 v[96:99], v[144:147], v[196:199], 0
	v_mfma_f32_16x16x32_bf16 v[88:91], v[156:159], v[196:199], 0
	v_mfma_f32_16x16x32_bf16 v[80:83], v[144:147], v[204:207], 0
	v_mfma_f32_16x16x32_bf16 v[72:75], v[156:159], v[204:207], 0
	v_mfma_f32_16x16x32_bf16 v[124:127], v[148:151], v[184:187], v[124:127]
	v_mfma_f32_16x16x32_bf16 v[120:123], v[160:163], v[184:187], v[120:123]
	v_mfma_f32_16x16x32_bf16 v[116:119], v[148:151], v[192:195], v[116:119]
	v_mfma_f32_16x16x32_bf16 v[112:115], v[160:163], v[192:195], v[112:115]
	v_mfma_f32_16x16x32_bf16 v[96:99], v[148:151], v[200:203], v[96:99]
	v_mfma_f32_16x16x32_bf16 v[88:91], v[160:163], v[200:203], v[88:91]
	v_mfma_f32_16x16x32_bf16 v[80:83], v[148:151], v[208:211], v[80:83]
	v_mfma_f32_16x16x32_bf16 v[72:75], v[160:163], v[208:211], v[72:75]
	v_mfma_f32_16x16x32_bf16 v[108:111], v[164:167], v[180:183], 0
	v_mfma_f32_16x16x32_bf16 v[104:107], v[172:175], v[180:183], 0
	v_mfma_f32_16x16x32_bf16 v[100:103], v[164:167], v[188:191], 0
	v_mfma_f32_16x16x32_bf16 v[92:95], v[172:175], v[188:191], 0
	v_mfma_f32_16x16x32_bf16 v[84:87], v[164:167], v[196:199], 0
	v_mfma_f32_16x16x32_bf16 v[76:79], v[172:175], v[196:199], 0
	v_mfma_f32_16x16x32_bf16 v[68:71], v[164:167], v[204:207], 0
	v_mfma_f32_16x16x32_bf16 v[64:67], v[172:175], v[204:207], 0
	v_mfma_f32_16x16x32_bf16 v[108:111], v[168:171], v[184:187], v[108:111]
	v_mfma_f32_16x16x32_bf16 v[104:107], v[176:179], v[184:187], v[104:107]
	v_mfma_f32_16x16x32_bf16 v[100:103], v[168:171], v[192:195], v[100:103]
	v_mfma_f32_16x16x32_bf16 v[92:95], v[176:179], v[192:195], v[92:95]
	v_mfma_f32_16x16x32_bf16 v[84:87], v[168:171], v[200:203], v[84:87]
	v_mfma_f32_16x16x32_bf16 v[76:79], v[176:179], v[200:203], v[76:79]
	v_mfma_f32_16x16x32_bf16 v[68:71], v[168:171], v[208:211], v[68:71]
	v_mfma_f32_16x16x32_bf16 v[64:67], v[176:179], v[208:211], v[64:67]
	s_setprio 0
	s_barrier
	s_add_i32 s59, s51, s94
	v_lshl_add_u64 v[212:213], s[42:43], 0, v[130:131]
	s_mov_b32 m0, s59
	ds_read_b128 v[180:183], v155 offset:16384
	ds_read_b128 v[184:187], v155 offset:17408
	ds_read_b128 v[188:191], v155 offset:18432
	ds_read_b128 v[192:195], v155 offset:19456
	ds_read_b128 v[196:199], v155 offset:20480
	ds_read_b128 v[200:203], v155 offset:21504
	ds_read_b128 v[204:207], v155 offset:22528
	ds_read_b128 v[208:211], v155 offset:23552
	global_load_lds_dwordx4 v[212:213], off
	s_add_i32 m0, s59, 0x2000
	s_add_u32 s60, s42, 0x20000
	v_lshl_add_u64 v[214:215], s[42:43], 0, v[134:135]
	s_addc_u32 s61, s43, 0
	s_add_i32 s59, s52, s94
	global_load_lds_dwordx4 v[214:215], off
	v_lshl_add_u64 v[216:217], s[60:61], 0, v[130:131]
	s_mov_b32 m0, s59
	v_lshl_add_u64 v[218:219], s[44:45], 0, v[132:133]
	global_load_lds_dwordx4 v[216:217], off
	v_lshl_add_u64 v[216:217], s[60:61], 0, v[134:135]
	s_add_i32 m0, s59, 0x2000
	s_nop 0
	global_load_lds_dwordx4 v[216:217], off
	v_lshl_add_u64 v[216:217], s[44:45], 0, v[128:129]
	s_mov_b32 m0, s25
	s_nop 0
	global_load_lds_dwordx4 v[216:217], off
	s_mov_b32 m0, s39
	s_nop 0
	global_load_lds_dwordx4 v[218:219], off
	s_waitcnt vmcnt(8)
	s_waitcnt lgkmcnt(0)
	s_barrier
; #define PG8_STAGE(bufoff, gbase, voff) do { _Pragma("unroll") for (int _i = 0; _i < 2; ++_i) \
;         __builtin_amdgcn_global_load_lds((const unsigned*)((const char*)(gbase) + (voff)[_i]), (LAS unsigned*)(lds + (bufoff) + ldsw + _i * 8192), 16, 0, 0); } while (0)
; #define PG8_LDA(dst, b, h) do { _Pragma("unroll") for (int m = 0; m < 4; ++m) _Pragma("unroll") for (int k = 0; k < 2; ++k) dst[m][k] = *(const LAS bf16x8*)(lds + PG8_SA(b, h) + aoff + m * 2048 + k * 1024); } while (0)
; #define PG8_LDB(dst, b, h) do { _Pragma("unroll") for (int n = 0; n < 2; ++n) _Pragma("unroll") for (int k = 0; k < 2; ++k) dst[n][k] = *(const LAS bf16x8*)(lds + PG8_SB(b, h) + boff + n * 2048 + k * 1024); } while (0)
; #define PG8_MMA(ai, bj, At, Bt) do { __builtin_amdgcn_s_setprio(1); _Pragma("unroll") for (int m = 0; m < 4; ++m) _Pragma("unroll") for (int n = 0; n < 2; ++n) _Pragma("unroll") for (int k = 0; k < 2; ++k) \
;         acc[ai][bj][m][n] = __builtin_amdgcn_mfma_f32_16x16x32_bf16(Bt[n][k], At[m][k], acc[ai][bj][m][n], 0, 0, 0); __builtin_amdgcn_s_setprio(0); } while (0)
; #define PG8_WAIT_V(n) asm volatile("s_waitcnt vmcnt(" #n ")" ::: "memory")
; #define PG8_WAIT_L(n) asm volatile("s_waitcnt lgkmcnt(" #n ")" ::: "memory")
; #define PG8_BAR __builtin_amdgcn_s_barrier()
; #define PG8_SCHED __builtin_amdgcn_sched_barrier(0)
; template <class Epi>
; DI void gemm_phase(LAS unsigned char* lds, const int wid, const Gemm g, const Order& S, const Epi& E) {
;     ...
;             PG8_WAIT_V(8); PG8_WAIT_L(0); PG8_BAR; PG8_MMA(1, 0, At, B0); PG8_MMA(1, 1, At, B1); PG8_BAR; PG8_SCHED;
;             PG8_LDB(B0, 1, 0); PG8_LDB(B1, 1, 1); PG8_SCHED; PG8_LDA(At, 1, 0); PG8_STAGE(PG8_SA(0, 1), a2 + hstepA, voffA);
;             PG8_WAIT_V(8); PG8_WAIT_L(0); PG8_BAR; PG8_MMA(0, 0, At, B0); PG8_MMA(0, 1, At, B1); PG8_BAR; PG8_SCHED;
	s_setprio 1
	v_mfma_f32_16x16x32_bf16 v[60:63], v[144:147], v[180:183], 0
	v_mfma_f32_16x16x32_bf16 v[56:59], v[156:159], v[180:183], 0
	v_mfma_f32_16x16x32_bf16 v[48:51], v[144:147], v[188:191], 0
	v_mfma_f32_16x16x32_bf16 v[40:43], v[156:159], v[188:191], 0
	v_mfma_f32_16x16x32_bf16 v[32:35], v[144:147], v[196:199], 0
	v_mfma_f32_16x16x32_bf16 v[24:27], v[156:159], v[196:199], 0
	v_mfma_f32_16x16x32_bf16 v[16:19], v[144:147], v[204:207], 0
	v_mfma_f32_16x16x32_bf16 v[8:11], v[156:159], v[204:207], 0
	v_mfma_f32_16x16x32_bf16 v[60:63], v[148:151], v[184:187], v[60:63]
	v_mfma_f32_16x16x32_bf16 v[56:59], v[160:163], v[184:187], v[56:59]
	v_mfma_f32_16x16x32_bf16 v[48:51], v[148:151], v[192:195], v[48:51]
	v_mfma_f32_16x16x32_bf16 v[40:43], v[160:163], v[192:195], v[40:43]
	v_mfma_f32_16x16x32_bf16 v[32:35], v[148:151], v[200:203], v[32:35]
	v_mfma_f32_16x16x32_bf16 v[24:27], v[160:163], v[200:203], v[24:27]
	v_mfma_f32_16x16x32_bf16 v[16:19], v[148:151], v[208:211], v[16:19]
	v_mfma_f32_16x16x32_bf16 v[8:11], v[160:163], v[208:211], v[8:11]
	v_mfma_f32_16x16x32_bf16 v[52:55], v[164:167], v[180:183], 0
	v_mfma_f32_16x16x32_bf16 v[44:47], v[172:175], v[180:183], 0
	v_mfma_f32_16x16x32_bf16 v[36:39], v[164:167], v[188:191], 0
	v_mfma_f32_16x16x32_bf16 v[28:31], v[172:175], v[188:191], 0
	v_mfma_f32_16x16x32_bf16 v[20:23], v[164:167], v[196:199], 0
	v_mfma_f32_16x16x32_bf16 v[12:15], v[172:175], v[196:199], 0
	v_mfma_f32_16x16x32_bf16 v[4:7], v[164:167], v[204:207], 0
	v_mfma_f32_16x16x32_bf16 v[0:3], v[172:175], v[204:207], 0
	v_mfma_f32_16x16x32_bf16 v[52:55], v[168:171], v[184:187], v[52:55]
	v_mfma_f32_16x16x32_bf16 v[44:47], v[176:179], v[184:187], v[44:47]
	v_mfma_f32_16x16x32_bf16 v[36:39], v[168:171], v[192:195], v[36:39]
	v_mfma_f32_16x16x32_bf16 v[28:31], v[176:179], v[192:195], v[28:31]
	v_mfma_f32_16x16x32_bf16 v[20:23], v[168:171], v[200:203], v[20:23]
	v_mfma_f32_16x16x32_bf16 v[12:15], v[176:179], v[200:203], v[12:15]
	v_mfma_f32_16x16x32_bf16 v[4:7], v[168:171], v[208:211], v[4:7]
	v_mfma_f32_16x16x32_bf16 v[0:3], v[176:179], v[208:211], v[0:3]
	s_setprio 0
	s_barrier
	s_add_i32 s59, 0, 0x18000
	s_add_i32 s60, 0, 0x1c000
	v_add_u32_e32 v160, s59, v152
	v_add_u32_e32 v176, s60, v152
	ds_read_b128 v[144:147], v160
	ds_read_b128 v[148:151], v160 offset:1024
	ds_read_b128 v[156:159], v160 offset:2048
	ds_read_b128 v[160:163], v160 offset:3072
	ds_read_b128 v[164:167], v176
	ds_read_b128 v[168:171], v176 offset:1024
	ds_read_b128 v[172:175], v176 offset:2048
	ds_read_b128 v[176:179], v176 offset:3072
	s_add_u32 s44, s44, 0x20000
	s_addc_u32 s45, s45, 0
	s_mov_b32 m0, s46
	v_lshl_add_u64 v[220:221], s[44:45], 0, v[128:129]
	ds_read_b128 v[180:183], v155 offset:32768
	ds_read_b128 v[184:187], v155 offset:33792
	ds_read_b128 v[188:191], v155 offset:34816
	ds_read_b128 v[192:195], v155 offset:35840
	ds_read_b128 v[196:199], v155 offset:36864
	ds_read_b128 v[200:203], v155 offset:37888
	ds_read_b128 v[204:207], v155 offset:38912
	ds_read_b128 v[208:211], v155 offset:39936
	global_load_lds_dwordx4 v[220:221], off
	v_lshl_add_u64 v[220:221], s[44:45], 0, v[132:133]
	s_mov_b32 m0, s47
	s_nop 0
	global_load_lds_dwordx4 v[220:221], off
	s_waitcnt vmcnt(8)
	s_waitcnt lgkmcnt(0)
	s_barrier
	s_setprio 1
	v_mfma_f32_16x16x32_bf16 v[124:127], v[144:147], v[180:183], v[124:127]
	v_mfma_f32_16x16x32_bf16 v[120:123], v[156:159], v[180:183], v[120:123]
	v_mfma_f32_16x16x32_bf16 v[116:119], v[144:147], v[188:191], v[116:119]
	v_mfma_f32_16x16x32_bf16 v[112:115], v[156:159], v[188:191], v[112:115]
	v_mfma_f32_16x16x32_bf16 v[96:99], v[144:147], v[196:199], v[96:99]
	v_mfma_f32_16x16x32_bf16 v[88:91], v[156:159], v[196:199], v[88:91]
	v_mfma_f32_16x16x32_bf16 v[80:83], v[144:147], v[204:207], v[80:83]
	v_mfma_f32_16x16x32_bf16 v[72:75], v[156:159], v[204:207], v[72:75]
	v_mfma_f32_16x16x32_bf16 v[124:127], v[148:151], v[184:187], v[124:127]
	v_mfma_f32_16x16x32_bf16 v[120:123], v[160:163], v[184:187], v[120:123]
	v_mfma_f32_16x16x32_bf16 v[116:119], v[148:151], v[192:195], v[116:119]
	v_mfma_f32_16x16x32_bf16 v[112:115], v[160:163], v[192:195], v[112:115]
	v_mfma_f32_16x16x32_bf16 v[96:99], v[148:151], v[200:203], v[96:99]
	v_mfma_f32_16x16x32_bf16 v[88:91], v[160:163], v[200:203], v[88:91]
	v_mfma_f32_16x16x32_bf16 v[80:83], v[148:151], v[208:211], v[80:83]
	v_mfma_f32_16x16x32_bf16 v[72:75], v[160:163], v[208:211], v[72:75]
	v_mfma_f32_16x16x32_bf16 v[108:111], v[164:167], v[180:183], v[108:111]
	v_mfma_f32_16x16x32_bf16 v[104:107], v[172:175], v[180:183], v[104:107]
	v_mfma_f32_16x16x32_bf16 v[100:103], v[164:167], v[188:191], v[100:103]
	v_mfma_f32_16x16x32_bf16 v[92:95], v[172:175], v[188:191], v[92:95]
	v_mfma_f32_16x16x32_bf16 v[84:87], v[164:167], v[196:199], v[84:87]
	v_mfma_f32_16x16x32_bf16 v[76:79], v[172:175], v[196:199], v[76:79]
	v_mfma_f32_16x16x32_bf16 v[68:71], v[164:167], v[204:207], v[68:71]
	v_mfma_f32_16x16x32_bf16 v[64:67], v[172:175], v[204:207], v[64:67]
	v_mfma_f32_16x16x32_bf16 v[108:111], v[168:171], v[184:187], v[108:111]
	v_mfma_f32_16x16x32_bf16 v[104:107], v[176:179], v[184:187], v[104:107]
	v_mfma_f32_16x16x32_bf16 v[100:103], v[168:171], v[192:195], v[100:103]
	v_mfma_f32_16x16x32_bf16 v[92:95], v[176:179], v[192:195], v[92:95]
	v_mfma_f32_16x16x32_bf16 v[84:87], v[168:171], v[200:203], v[84:87]
	v_mfma_f32_16x16x32_bf16 v[76:79], v[176:179], v[200:203], v[76:79]
	v_mfma_f32_16x16x32_bf16 v[68:71], v[168:171], v[208:211], v[68:71]
	v_mfma_f32_16x16x32_bf16 v[64:67], v[176:179], v[208:211], v[64:67]
	s_setprio 0
	s_barrier
; #define PG8_STAGE(bufoff, gbase, voff) do { _Pragma("unroll") for (int _i = 0; _i < 2; ++_i) \
;         __builtin_amdgcn_global_load_lds((const unsigned*)((const char*)(gbase) + (voff)[_i]), (LAS unsigned*)(lds + (bufoff) + ldsw + _i * 8192), 16, 0, 0); } while (0)
; #define PG8_LDA(dst, b, h) do { _Pragma("unroll") for (int m = 0; m < 4; ++m) _Pragma("unroll") for (int k = 0; k < 2; ++k) dst[m][k] = *(const LAS bf16x8*)(lds + PG8_SA(b, h) + aoff + m * 2048 + k * 1024); } while (0)
; #define PG8_LDB(dst, b, h) do { _Pragma("unroll") for (int n = 0; n < 2; ++n) _Pragma("unroll") for (int k = 0; k < 2; ++k) dst[n][k] = *(const LAS bf16x8*)(lds + PG8_SB(b, h) + boff + n * 2048 + k * 1024); } while (0)
; #define PG8_WAIT_V(n) asm volatile("s_waitcnt vmcnt(" #n ")" ::: "memory")
; #define PG8_WAIT_L(n) asm volatile("s_waitcnt lgkmcnt(" #n ")" ::: "memory")
; template <class Epi>
; DI void gemm_phase(LAS unsigned char* lds, const int wid, const Gemm g, const Order& S, const Epi& E) {
;     ...
;         for (int t = 0; t < nt; t += 2) {
;             const bool last = (t == nt - 2);
;             const char* a1 = cA + (size_t)(t + 1) * kstep;
;             const char* a2 = last ? nA : cA + (size_t)(t + 2) * kstep; const char* b2 = last ? nB : cB + (size_t)(t + 2) * kstep;
;             const char* a3 = a2 + kstep; const char* b3 = b2 + kstep;
;             PG8_LDB(B0, 0, 0); PG8_LDB(B1, 0, 1); PG8_SCHED; PG8_LDA(At, 0, 0); PG8_STAGE(PG8_SA(1, 1), a1 + hstepA, voffA);
;             PG8_WAIT_V(8); PG8_WAIT_L(0); PG8_BAR; PG8_MMA(0, 0, At, B0); PG8_MMA(0, 1, At, B1); PG8_BAR; PG8_SCHED;
;             PG8_LDA(At, 0, 1); PG8_STAGE(PG8_SB(0, 0), b2, voffB); PG8_STAGE(PG8_SB(0, 1), b2 + hstepB, voffB); PG8_STAGE(PG8_SA(0, 0), a2, voffA);
;             PG8_WAIT_V(8); PG8_WAIT_L(0); PG8_BAR; PG8_MMA(1, 0, At, B0); PG8_MMA(1, 1, At, B1); PG8_BAR; PG8_SCHED;
;             PG8_LDB(B0, 1, 0); PG8_LDB(B1, 1, 1); PG8_SCHED; PG8_LDA(At, 1, 0); PG8_STAGE(PG8_SA(0, 1), a2 + hstepA, voffA);
;             PG8_WAIT_V(8); PG8_WAIT_L(0); PG8_BAR; PG8_MMA(0, 0, At, B0); PG8_MMA(0, 1, At, B1); PG8_BAR; PG8_SCHED;
;             PG8_LDA(At, 1, 1); PG8_STAGE(PG8_SB(1, 0), b3, voffB); PG8_STAGE(PG8_SB(1, 1), b3 + hstepB, voffB); PG8_STAGE(PG8_SA(1, 0), a3, voffA);
;             PG8_WAIT_V(8); PG8_WAIT_L(0); PG8_BAR; PG8_MMA(1, 0, At, B0); PG8_MMA(1, 1, At, B1); PG8_BAR; PG8_SCHED;
	s_add_i32 s44, s59, s94
	v_lshl_add_u64 v[212:213], v[212:213], 0, s[16:17]
	s_mov_b32 m0, s44
	ds_read_b128 v[180:183], v155 offset:49152
	ds_read_b128 v[184:187], v155 offset:50176
	ds_read_b128 v[188:191], v155 offset:51200
	ds_read_b128 v[192:195], v155 offset:52224
	ds_read_b128 v[196:199], v155 offset:53248
	ds_read_b128 v[200:203], v155 offset:54272
	ds_read_b128 v[204:207], v155 offset:55296
	ds_read_b128 v[208:211], v155 offset:56320
	global_load_lds_dwordx4 v[212:213], off
	s_add_i32 m0, s44, 0x2000
	s_add_u32 s42, s42, 0x20080
	v_lshl_add_u64 v[212:213], v[214:215], 0, s[16:17]
	s_addc_u32 s43, s43, 0
	s_add_i32 s44, s60, s94
	global_load_lds_dwordx4 v[212:213], off
	v_lshl_add_u64 v[212:213], s[42:43], 0, v[130:131]
	s_mov_b32 m0, s44
	s_nop 0
	global_load_lds_dwordx4 v[212:213], off
	v_lshl_add_u64 v[212:213], s[42:43], 0, v[134:135]
	s_add_i32 m0, s44, 0x2000
	s_nop 0
	global_load_lds_dwordx4 v[212:213], off
	v_lshl_add_u64 v[212:213], v[216:217], 0, s[16:17]
	s_mov_b32 m0, s49
	s_nop 0
	global_load_lds_dwordx4 v[212:213], off
	v_lshl_add_u64 v[212:213], v[218:219], 0, s[16:17]
	s_mov_b32 m0, s50
	s_nop 0
	global_load_lds_dwordx4 v[212:213], off
	s_waitcnt vmcnt(8)
	s_waitcnt lgkmcnt(0)
	s_barrier
	s_setprio 1
	v_mfma_f32_16x16x32_bf16 v[60:63], v[144:147], v[180:183], v[60:63]
	v_mfma_f32_16x16x32_bf16 v[56:59], v[156:159], v[180:183], v[56:59]
	v_mfma_f32_16x16x32_bf16 v[48:51], v[144:147], v[188:191], v[48:51]
	v_mfma_f32_16x16x32_bf16 v[40:43], v[156:159], v[188:191], v[40:43]
	v_mfma_f32_16x16x32_bf16 v[32:35], v[144:147], v[196:199], v[32:35]
	v_mfma_f32_16x16x32_bf16 v[24:27], v[156:159], v[196:199], v[24:27]
	v_mfma_f32_16x16x32_bf16 v[16:19], v[144:147], v[204:207], v[16:19]
	v_mfma_f32_16x16x32_bf16 v[8:11], v[156:159], v[204:207], v[8:11]
	v_mfma_f32_16x16x32_bf16 v[60:63], v[148:151], v[184:187], v[60:63]
	v_mfma_f32_16x16x32_bf16 v[56:59], v[160:163], v[184:187], v[56:59]
	v_mfma_f32_16x16x32_bf16 v[48:51], v[148:151], v[192:195], v[48:51]
	v_mfma_f32_16x16x32_bf16 v[40:43], v[160:163], v[192:195], v[40:43]
	v_mfma_f32_16x16x32_bf16 v[32:35], v[148:151], v[200:203], v[32:35]
	v_mfma_f32_16x16x32_bf16 v[24:27], v[160:163], v[200:203], v[24:27]
	v_mfma_f32_16x16x32_bf16 v[16:19], v[148:151], v[208:211], v[16:19]
	v_mfma_f32_16x16x32_bf16 v[8:11], v[160:163], v[208:211], v[8:11]
	v_mfma_f32_16x16x32_bf16 v[52:55], v[164:167], v[180:183], v[52:55]
	v_mfma_f32_16x16x32_bf16 v[44:47], v[172:175], v[180:183], v[44:47]
	v_mfma_f32_16x16x32_bf16 v[36:39], v[164:167], v[188:191], v[36:39]
	v_mfma_f32_16x16x32_bf16 v[28:31], v[172:175], v[188:191], v[28:31]
	v_mfma_f32_16x16x32_bf16 v[20:23], v[164:167], v[196:199], v[20:23]
	v_mfma_f32_16x16x32_bf16 v[12:15], v[172:175], v[196:199], v[12:15]
	v_mfma_f32_16x16x32_bf16 v[4:7], v[164:167], v[204:207], v[4:7]
	v_mfma_f32_16x16x32_bf16 v[0:3], v[172:175], v[204:207], v[0:3]
	v_mfma_f32_16x16x32_bf16 v[52:55], v[168:171], v[184:187], v[52:55]
	v_mfma_f32_16x16x32_bf16 v[44:47], v[176:179], v[184:187], v[44:47]
	v_mfma_f32_16x16x32_bf16 v[36:39], v[168:171], v[192:195], v[36:39]
	v_mfma_f32_16x16x32_bf16 v[28:31], v[176:179], v[192:195], v[28:31]
	v_mfma_f32_16x16x32_bf16 v[20:23], v[168:171], v[200:203], v[20:23]
	v_mfma_f32_16x16x32_bf16 v[12:15], v[176:179], v[200:203], v[12:15]
	v_mfma_f32_16x16x32_bf16 v[4:7], v[168:171], v[208:211], v[4:7]
	v_mfma_f32_16x16x32_bf16 v[0:3], v[176:179], v[208:211], v[0:3]
	s_setprio 0
	s_barrier
	s_add_i32 s58, s58, 2
	s_add_u32 s40, s40, 0x100
	s_addc_u32 s41, s41, 0
	s_add_u32 s56, s56, 0x100
	s_addc_u32 s57, s57, 0
	s_cmp_gt_u32 s58, 5
	s_cbranch_scc0 .LBB0_1013
	s_branch .Lpeel_exit_5
.LBB0_1013:
	ds_read_b128 v[144:147], v153
	ds_read_b128 v[148:151], v153 offset:1024
	ds_read_b128 v[156:159], v153 offset:2048
	ds_read_b128 v[160:163], v153 offset:3072
	ds_read_b128 v[164:167], v154
	ds_read_b128 v[168:171], v154 offset:1024
	ds_read_b128 v[172:175], v154 offset:2048
	ds_read_b128 v[176:179], v154 offset:3072
	s_add_u32 s42, s40, 0xfffe0080
	s_addc_u32 s43, s41, -1
	s_cmp_eq_u32 s58, 4
	s_cselect_b32 s45, s29, s43
	s_cselect_b32 s44, s54, s42
	s_cselect_b32 s43, s31, s57
	s_cselect_b32 s42, s55, s56
	v_lshl_add_u64 v[212:213], s[40:41], 0, v[136:137]
	s_add_i32 m0, s25, 0xc000
	ds_read_b128 v[180:183], v155
	ds_read_b128 v[184:187], v155 offset:1024
	ds_read_b128 v[188:191], v155 offset:2048
	ds_read_b128 v[192:195], v155 offset:3072
	ds_read_b128 v[196:199], v155 offset:4096
	ds_read_b128 v[200:203], v155 offset:5120
	ds_read_b128 v[204:207], v155 offset:6144
	ds_read_b128 v[208:211], v155 offset:7168
	global_load_lds_dwordx4 v[212:213], off
	v_lshl_add_u64 v[212:213], s[40:41], 0, v[138:139]
	s_add_i32 m0, s25, 0xe000
	s_nop 0
	global_load_lds_dwordx4 v[212:213], off
	s_waitcnt vmcnt(8)
	s_waitcnt lgkmcnt(0)
	s_barrier
; #define PG8_STAGE(bufoff, gbase, voff) do { _Pragma("unroll") for (int _i = 0; _i < 2; ++_i) \
;         __builtin_amdgcn_global_load_lds((const unsigned*)((const char*)(gbase) + (voff)[_i]), (LAS unsigned*)(lds + (bufoff) + ldsw + _i * 8192), 16, 0, 0); } while (0)
; #define PG8_LDA(dst, b, h) do { _Pragma("unroll") for (int m = 0; m < 4; ++m) _Pragma("unroll") for (int k = 0; k < 2; ++k) dst[m][k] = *(const LAS bf16x8*)(lds + PG8_SA(b, h) + aoff + m * 2048 + k * 1024); } while (0)
; #define PG8_MMA(ai, bj, At, Bt) do { __builtin_amdgcn_s_setprio(1); _Pragma("unroll") for (int m = 0; m < 4; ++m) _Pragma("unroll") for (int n = 0; n < 2; ++n) _Pragma("unroll") for (int k = 0; k < 2; ++k) \
;         acc[ai][bj][m][n] = __builtin_amdgcn_mfma_f32_16x16x32_bf16(Bt[n][k], At[m][k], acc[ai][bj][m][n], 0, 0, 0); __builtin_amdgcn_s_setprio(0); } while (0)
; #define PG8_WAIT_V(n) asm volatile("s_waitcnt vmcnt(" #n ")" ::: "memory")
; #define PG8_WAIT_L(n) asm volatile("s_waitcnt lgkmcnt(" #n ")" ::: "memory")
; #define PG8_BAR __builtin_amdgcn_s_barrier()
; #define PG8_SCHED __builtin_amdgcn_sched_barrier(0)
; template <class Epi>
; DI void gemm_phase(LAS unsigned char* lds, const int wid, const Gemm g, const Order& S, const Epi& E) {
;     ...
;             PG8_WAIT_V(8); PG8_WAIT_L(0); PG8_BAR; PG8_MMA(0, 0, At, B0); PG8_MMA(0, 1, At, B1); PG8_BAR; PG8_SCHED;
;             PG8_LDA(At, 0, 1); PG8_STAGE(PG8_SB(0, 0), b2, voffB); PG8_STAGE(PG8_SB(0, 1), b2 + hstepB, voffB); PG8_STAGE(PG8_SA(0, 0), a2, voffA);
;             PG8_WAIT_V(8); PG8_WAIT_L(0); PG8_BAR; PG8_MMA(1, 0, At, B0); PG8_MMA(1, 1, At, B1); PG8_BAR; PG8_SCHED;
	s_setprio 1
	v_mfma_f32_16x16x32_bf16 v[124:127], v[144:147], v[180:183], v[124:127]
	v_mfma_f32_16x16x32_bf16 v[120:123], v[156:159], v[180:183], v[120:123]
	v_mfma_f32_16x16x32_bf16 v[116:119], v[144:147], v[188:191], v[116:119]
	v_mfma_f32_16x16x32_bf16 v[112:115], v[156:159], v[188:191], v[112:115]
	v_mfma_f32_16x16x32_bf16 v[96:99], v[144:147], v[196:199], v[96:99]
	v_mfma_f32_16x16x32_bf16 v[88:91], v[156:159], v[196:199], v[88:91]
	v_mfma_f32_16x16x32_bf16 v[80:83], v[144:147], v[204:207], v[80:83]
	v_mfma_f32_16x16x32_bf16 v[72:75], v[156:159], v[204:207], v[72:75]
	v_mfma_f32_16x16x32_bf16 v[124:127], v[148:151], v[184:187], v[124:127]
	v_mfma_f32_16x16x32_bf16 v[120:123], v[160:163], v[184:187], v[120:123]
	v_mfma_f32_16x16x32_bf16 v[116:119], v[148:151], v[192:195], v[116:119]
	v_mfma_f32_16x16x32_bf16 v[112:115], v[160:163], v[192:195], v[112:115]
	v_mfma_f32_16x16x32_bf16 v[96:99], v[148:151], v[200:203], v[96:99]
	v_mfma_f32_16x16x32_bf16 v[88:91], v[160:163], v[200:203], v[88:91]
	v_mfma_f32_16x16x32_bf16 v[80:83], v[148:151], v[208:211], v[80:83]
	v_mfma_f32_16x16x32_bf16 v[72:75], v[160:163], v[208:211], v[72:75]
	v_mfma_f32_16x16x32_bf16 v[108:111], v[164:167], v[180:183], v[108:111]
	v_mfma_f32_16x16x32_bf16 v[104:107], v[172:175], v[180:183], v[104:107]
	v_mfma_f32_16x16x32_bf16 v[100:103], v[164:167], v[188:191], v[100:103]
	v_mfma_f32_16x16x32_bf16 v[92:95], v[172:175], v[188:191], v[92:95]
	v_mfma_f32_16x16x32_bf16 v[84:87], v[164:167], v[196:199], v[84:87]
	v_mfma_f32_16x16x32_bf16 v[76:79], v[172:175], v[196:199], v[76:79]
	v_mfma_f32_16x16x32_bf16 v[68:71], v[164:167], v[204:207], v[68:71]
	v_mfma_f32_16x16x32_bf16 v[64:67], v[172:175], v[204:207], v[64:67]
	v_mfma_f32_16x16x32_bf16 v[108:111], v[168:171], v[184:187], v[108:111]
	v_mfma_f32_16x16x32_bf16 v[104:107], v[176:179], v[184:187], v[104:107]
	v_mfma_f32_16x16x32_bf16 v[100:103], v[168:171], v[192:195], v[100:103]
	v_mfma_f32_16x16x32_bf16 v[92:95], v[176:179], v[192:195], v[92:95]
	v_mfma_f32_16x16x32_bf16 v[84:87], v[168:171], v[200:203], v[84:87]
	v_mfma_f32_16x16x32_bf16 v[76:79], v[176:179], v[200:203], v[76:79]
	v_mfma_f32_16x16x32_bf16 v[68:71], v[168:171], v[208:211], v[68:71]
	v_mfma_f32_16x16x32_bf16 v[64:67], v[176:179], v[208:211], v[64:67]
	s_setprio 0
	s_barrier
	s_add_i32 s59, s51, s94
	v_lshl_add_u64 v[212:213], s[42:43], 0, v[130:131]
	s_mov_b32 m0, s59
	ds_read_b128 v[180:183], v155 offset:16384
	ds_read_b128 v[184:187], v155 offset:17408
	ds_read_b128 v[188:191], v155 offset:18432
	ds_read_b128 v[192:195], v155 offset:19456
	ds_read_b128 v[196:199], v155 offset:20480
	ds_read_b128 v[200:203], v155 offset:21504
	ds_read_b128 v[204:207], v155 offset:22528
	ds_read_b128 v[208:211], v155 offset:23552
	global_load_lds_dwordx4 v[212:213], off
	s_add_i32 m0, s59, 0x2000
	s_add_u32 s60, s42, 0x20000
	v_lshl_add_u64 v[214:215], s[42:43], 0, v[134:135]
	s_addc_u32 s61, s43, 0
	s_add_i32 s59, s52, s94
	global_load_lds_dwordx4 v[214:215], off
	v_lshl_add_u64 v[216:217], s[60:61], 0, v[130:131]
	s_mov_b32 m0, s59
	v_lshl_add_u64 v[218:219], s[44:45], 0, v[132:133]
	global_load_lds_dwordx4 v[216:217], off
	v_lshl_add_u64 v[216:217], s[60:61], 0, v[134:135]
	s_add_i32 m0, s59, 0x2000
	s_nop 0
	global_load_lds_dwordx4 v[216:217], off
	v_lshl_add_u64 v[216:217], s[44:45], 0, v[128:129]
	s_mov_b32 m0, s25
	s_nop 0
	global_load_lds_dwordx4 v[216:217], off
	s_mov_b32 m0, s39
	s_nop 0
	global_load_lds_dwordx4 v[218:219], off
	s_waitcnt vmcnt(8)
	s_waitcnt lgkmcnt(0)
	s_barrier
	s_setprio 1
	v_mfma_f32_16x16x32_bf16 v[60:63], v[144:147], v[180:183], v[60:63]
	v_mfma_f32_16x16x32_bf16 v[56:59], v[156:159], v[180:183], v[56:59]
	v_mfma_f32_16x16x32_bf16 v[48:51], v[144:147], v[188:191], v[48:51]
	v_mfma_f32_16x16x32_bf16 v[40:43], v[156:159], v[188:191], v[40:43]
	v_mfma_f32_16x16x32_bf16 v[32:35], v[144:147], v[196:199], v[32:35]
	v_mfma_f32_16x16x32_bf16 v[24:27], v[156:159], v[196:199], v[24:27]
	v_mfma_f32_16x16x32_bf16 v[16:19], v[144:147], v[204:207], v[16:19]
	v_mfma_f32_16x16x32_bf16 v[8:11], v[156:159], v[204:207], v[8:11]
	v_mfma_f32_16x16x32_bf16 v[60:63], v[148:151], v[184:187], v[60:63]
	v_mfma_f32_16x16x32_bf16 v[56:59], v[160:163], v[184:187], v[56:59]
	v_mfma_f32_16x16x32_bf16 v[48:51], v[148:151], v[192:195], v[48:51]
	v_mfma_f32_16x16x32_bf16 v[40:43], v[160:163], v[192:195], v[40:43]
	v_mfma_f32_16x16x32_bf16 v[32:35], v[148:151], v[200:203], v[32:35]
	v_mfma_f32_16x16x32_bf16 v[24:27], v[160:163], v[200:203], v[24:27]
	v_mfma_f32_16x16x32_bf16 v[16:19], v[148:151], v[208:211], v[16:19]
	v_mfma_f32_16x16x32_bf16 v[8:11], v[160:163], v[208:211], v[8:11]
	v_mfma_f32_16x16x32_bf16 v[52:55], v[164:167], v[180:183], v[52:55]
	v_mfma_f32_16x16x32_bf16 v[44:47], v[172:175], v[180:183], v[44:47]
	v_mfma_f32_16x16x32_bf16 v[36:39], v[164:167], v[188:191], v[36:39]
	v_mfma_f32_16x16x32_bf16 v[28:31], v[172:175], v[188:191], v[28:31]
	v_mfma_f32_16x16x32_bf16 v[20:23], v[164:167], v[196:199], v[20:23]
	v_mfma_f32_16x16x32_bf16 v[12:15], v[172:175], v[196:199], v[12:15]
	v_mfma_f32_16x16x32_bf16 v[4:7], v[164:167], v[204:207], v[4:7]
	v_mfma_f32_16x16x32_bf16 v[0:3], v[172:175], v[204:207], v[0:3]
	v_mfma_f32_16x16x32_bf16 v[52:55], v[168:171], v[184:187], v[52:55]
	v_mfma_f32_16x16x32_bf16 v[44:47], v[176:179], v[184:187], v[44:47]
	v_mfma_f32_16x16x32_bf16 v[36:39], v[168:171], v[192:195], v[36:39]
	v_mfma_f32_16x16x32_bf16 v[28:31], v[176:179], v[192:195], v[28:31]
	v_mfma_f32_16x16x32_bf16 v[20:23], v[168:171], v[200:203], v[20:23]
	v_mfma_f32_16x16x32_bf16 v[12:15], v[176:179], v[200:203], v[12:15]
	v_mfma_f32_16x16x32_bf16 v[4:7], v[168:171], v[208:211], v[4:7]
	v_mfma_f32_16x16x32_bf16 v[0:3], v[176:179], v[208:211], v[0:3]
	s_setprio 0
	s_barrier
; #define PG8_STAGE(bufoff, gbase, voff) do { _Pragma("unroll") for (int _i = 0; _i < 2; ++_i) \
;         __builtin_amdgcn_global_load_lds((const unsigned*)((const char*)(gbase) + (voff)[_i]), (LAS unsigned*)(lds + (bufoff) + ldsw + _i * 8192), 16, 0, 0); } while (0)
; #define PG8_LDA(dst, b, h) do { _Pragma("unroll") for (int m = 0; m < 4; ++m) _Pragma("unroll") for (int k = 0; k < 2; ++k) dst[m][k] = *(const LAS bf16x8*)(lds + PG8_SA(b, h) + aoff + m * 2048 + k * 1024); } while (0)
; #define PG8_LDB(dst, b, h) do { _Pragma("unroll") for (int n = 0; n < 2; ++n) _Pragma("unroll") for (int k = 0; k < 2; ++k) dst[n][k] = *(const LAS bf16x8*)(lds + PG8_SB(b, h) + boff + n * 2048 + k * 1024); } while (0)
; #define PG8_MMA(ai, bj, At, Bt) do { __builtin_amdgcn_s_setprio(1); _Pragma("unroll") for (int m = 0; m < 4; ++m) _Pragma("unroll") for (int n = 0; n < 2; ++n) _Pragma("unroll") for (int k = 0; k < 2; ++k) \
;         acc[ai][bj][m][n] = __builtin_amdgcn_mfma_f32_16x16x32_bf16(Bt[n][k], At[m][k], acc[ai][bj][m][n], 0, 0, 0); __builtin_amdgcn_s_setprio(0); } while (0)
; #define PG8_WAIT_V(n) asm volatile("s_waitcnt vmcnt(" #n ")" ::: "memory")
; #define PG8_WAIT_L(n) asm volatile("s_waitcnt lgkmcnt(" #n ")" ::: "memory")
; #define PG8_BAR __builtin_amdgcn_s_barrier()
; #define PG8_SCHED __builtin_amdgcn_sched_barrier(0)
; template <class Epi>
; DI void gemm_phase(LAS unsigned char* lds, const int wid, const Gemm g, const Order& S, const Epi& E) {
;     ...
;             PG8_LDB(B0, 1, 0); PG8_LDB(B1, 1, 1); PG8_SCHED; PG8_LDA(At, 1, 0); PG8_STAGE(PG8_SA(0, 1), a2 + hstepA, voffA);
;             PG8_WAIT_V(8); PG8_WAIT_L(0); PG8_BAR; PG8_MMA(0, 0, At, B0); PG8_MMA(0, 1, At, B1); PG8_BAR; PG8_SCHED;
	s_add_i32 s59, 0, 0x18000
	s_add_i32 s60, 0, 0x1c000
	v_add_u32_e32 v160, s59, v152
	v_add_u32_e32 v176, s60, v152
	ds_read_b128 v[144:147], v160
	ds_read_b128 v[148:151], v160 offset:1024
	ds_read_b128 v[156:159], v160 offset:2048
	ds_read_b128 v[160:163], v160 offset:3072
	ds_read_b128 v[164:167], v176
	ds_read_b128 v[168:171], v176 offset:1024
	ds_read_b128 v[172:175], v176 offset:2048
	ds_read_b128 v[176:179], v176 offset:3072
	s_add_u32 s44, s44, 0x20000
	s_addc_u32 s45, s45, 0
	s_mov_b32 m0, s46
	v_lshl_add_u64 v[220:221], s[44:45], 0, v[128:129]
	ds_read_b128 v[180:183], v155 offset:32768
	ds_read_b128 v[184:187], v155 offset:33792
	ds_read_b128 v[188:191], v155 offset:34816
	ds_read_b128 v[192:195], v155 offset:35840
	ds_read_b128 v[196:199], v155 offset:36864
	ds_read_b128 v[200:203], v155 offset:37888
	ds_read_b128 v[204:207], v155 offset:38912
	ds_read_b128 v[208:211], v155 offset:39936
	global_load_lds_dwordx4 v[220:221], off
	v_lshl_add_u64 v[220:221], s[44:45], 0, v[132:133]
	s_mov_b32 m0, s47
	s_nop 0
	global_load_lds_dwordx4 v[220:221], off
	s_waitcnt vmcnt(8)
	s_waitcnt lgkmcnt(0)
	s_barrier
	s_setprio 1
	v_mfma_f32_16x16x32_bf16 v[124:127], v[144:147], v[180:183], v[124:127]
	v_mfma_f32_16x16x32_bf16 v[120:123], v[156:159], v[180:183], v[120:123]
	v_mfma_f32_16x16x32_bf16 v[116:119], v[144:147], v[188:191], v[116:119]
	v_mfma_f32_16x16x32_bf16 v[112:115], v[156:159], v[188:191], v[112:115]
	v_mfma_f32_16x16x32_bf16 v[96:99], v[144:147], v[196:199], v[96:99]
	v_mfma_f32_16x16x32_bf16 v[88:91], v[156:159], v[196:199], v[88:91]
	v_mfma_f32_16x16x32_bf16 v[80:83], v[144:147], v[204:207], v[80:83]
	v_mfma_f32_16x16x32_bf16 v[72:75], v[156:159], v[204:207], v[72:75]
	v_mfma_f32_16x16x32_bf16 v[124:127], v[148:151], v[184:187], v[124:127]
	v_mfma_f32_16x16x32_bf16 v[120:123], v[160:163], v[184:187], v[120:123]
	v_mfma_f32_16x16x32_bf16 v[116:119], v[148:151], v[192:195], v[116:119]
	v_mfma_f32_16x16x32_bf16 v[112:115], v[160:163], v[192:195], v[112:115]
	v_mfma_f32_16x16x32_bf16 v[96:99], v[148:151], v[200:203], v[96:99]
	v_mfma_f32_16x16x32_bf16 v[88:91], v[160:163], v[200:203], v[88:91]
	v_mfma_f32_16x16x32_bf16 v[80:83], v[148:151], v[208:211], v[80:83]
	v_mfma_f32_16x16x32_bf16 v[72:75], v[160:163], v[208:211], v[72:75]
	v_mfma_f32_16x16x32_bf16 v[108:111], v[164:167], v[180:183], v[108:111]
	v_mfma_f32_16x16x32_bf16 v[104:107], v[172:175], v[180:183], v[104:107]
	v_mfma_f32_16x16x32_bf16 v[100:103], v[164:167], v[188:191], v[100:103]
	v_mfma_f32_16x16x32_bf16 v[92:95], v[172:175], v[188:191], v[92:95]
	v_mfma_f32_16x16x32_bf16 v[84:87], v[164:167], v[196:199], v[84:87]
	v_mfma_f32_16x16x32_bf16 v[76:79], v[172:175], v[196:199], v[76:79]
	v_mfma_f32_16x16x32_bf16 v[68:71], v[164:167], v[204:207], v[68:71]
	v_mfma_f32_16x16x32_bf16 v[64:67], v[172:175], v[204:207], v[64:67]
	v_mfma_f32_16x16x32_bf16 v[108:111], v[168:171], v[184:187], v[108:111]
	v_mfma_f32_16x16x32_bf16 v[104:107], v[176:179], v[184:187], v[104:107]
	v_mfma_f32_16x16x32_bf16 v[100:103], v[168:171], v[192:195], v[100:103]
	v_mfma_f32_16x16x32_bf16 v[92:95], v[176:179], v[192:195], v[92:95]
	v_mfma_f32_16x16x32_bf16 v[84:87], v[168:171], v[200:203], v[84:87]
	v_mfma_f32_16x16x32_bf16 v[76:79], v[176:179], v[200:203], v[76:79]
	v_mfma_f32_16x16x32_bf16 v[68:71], v[168:171], v[208:211], v[68:71]
	v_mfma_f32_16x16x32_bf16 v[64:67], v[176:179], v[208:211], v[64:67]
	s_setprio 0
	s_barrier
; #define PG8_STAGE(bufoff, gbase, voff) do { _Pragma("unroll") for (int _i = 0; _i < 2; ++_i) \
;         __builtin_amdgcn_global_load_lds((const unsigned*)((const char*)(gbase) + (voff)[_i]), (LAS unsigned*)(lds + (bufoff) + ldsw + _i * 8192), 16, 0, 0); } while (0)
; #define PG8_LDA(dst, b, h) do { _Pragma("unroll") for (int m = 0; m < 4; ++m) _Pragma("unroll") for (int k = 0; k < 2; ++k) dst[m][k] = *(const LAS bf16x8*)(lds + PG8_SA(b, h) + aoff + m * 2048 + k * 1024); } while (0)
; #define PG8_MMA(ai, bj, At, Bt) do { __builtin_amdgcn_s_setprio(1); _Pragma("unroll") for (int m = 0; m < 4; ++m) _Pragma("unroll") for (int n = 0; n < 2; ++n) _Pragma("unroll") for (int k = 0; k < 2; ++k) \
;         acc[ai][bj][m][n] = __builtin_amdgcn_mfma_f32_16x16x32_bf16(Bt[n][k], At[m][k], acc[ai][bj][m][n], 0, 0, 0); __builtin_amdgcn_s_setprio(0); } while (0)
; #define PG8_WAIT_V(n) asm volatile("s_waitcnt vmcnt(" #n ")" ::: "memory")
; #define PG8_WAIT_L(n) asm volatile("s_waitcnt lgkmcnt(" #n ")" ::: "memory")
; #define PG8_BAR __builtin_amdgcn_s_barrier()
; #define PG8_SCHED __builtin_amdgcn_sched_barrier(0)
; template <class Epi>
; DI void gemm_phase(LAS unsigned char* lds, const int wid, const Gemm g, const Order& S, const Epi& E) {
;     ...
;         for (int t = 0; t < nt; t += 2) {
;     ...
;             PG8_LDA(At, 1, 1); PG8_STAGE(PG8_SB(1, 0), b3, voffB); PG8_STAGE(PG8_SB(1, 1), b3 + hstepB, voffB); PG8_STAGE(PG8_SA(1, 0), a3, voffA);
;             PG8_WAIT_V(8); PG8_WAIT_L(0); PG8_BAR; PG8_MMA(1, 0, At, B0); PG8_MMA(1, 1, At, B1); PG8_BAR; PG8_SCHED;
	s_add_i32 s44, s59, s94
	v_lshl_add_u64 v[212:213], v[212:213], 0, s[16:17]
	s_mov_b32 m0, s44
	ds_read_b128 v[180:183], v155 offset:49152
	ds_read_b128 v[184:187], v155 offset:50176
	ds_read_b128 v[188:191], v155 offset:51200
	ds_read_b128 v[192:195], v155 offset:52224
	ds_read_b128 v[196:199], v155 offset:53248
	ds_read_b128 v[200:203], v155 offset:54272
	ds_read_b128 v[204:207], v155 offset:55296
	ds_read_b128 v[208:211], v155 offset:56320
	global_load_lds_dwordx4 v[212:213], off
	s_add_i32 m0, s44, 0x2000
	s_add_u32 s42, s42, 0x20080
	v_lshl_add_u64 v[212:213], v[214:215], 0, s[16:17]
	s_addc_u32 s43, s43, 0
	s_add_i32 s44, s60, s94
	global_load_lds_dwordx4 v[212:213], off
	v_lshl_add_u64 v[212:213], s[42:43], 0, v[130:131]
	s_mov_b32 m0, s44
	s_nop 0
	global_load_lds_dwordx4 v[212:213], off
	v_lshl_add_u64 v[212:213], s[42:43], 0, v[134:135]
	s_add_i32 m0, s44, 0x2000
	s_nop 0
	global_load_lds_dwordx4 v[212:213], off
	v_lshl_add_u64 v[212:213], v[216:217], 0, s[16:17]
	s_mov_b32 m0, s49
	s_nop 0
	global_load_lds_dwordx4 v[212:213], off
	v_lshl_add_u64 v[212:213], v[218:219], 0, s[16:17]
	s_mov_b32 m0, s50
	s_nop 0
	global_load_lds_dwordx4 v[212:213], off
	s_waitcnt vmcnt(8)
	s_waitcnt lgkmcnt(0)
	s_barrier
	s_setprio 1
	v_mfma_f32_16x16x32_bf16 v[60:63], v[144:147], v[180:183], v[60:63]
	v_mfma_f32_16x16x32_bf16 v[56:59], v[156:159], v[180:183], v[56:59]
	v_mfma_f32_16x16x32_bf16 v[48:51], v[144:147], v[188:191], v[48:51]
	v_mfma_f32_16x16x32_bf16 v[40:43], v[156:159], v[188:191], v[40:43]
	v_mfma_f32_16x16x32_bf16 v[32:35], v[144:147], v[196:199], v[32:35]
	v_mfma_f32_16x16x32_bf16 v[24:27], v[156:159], v[196:199], v[24:27]
	v_mfma_f32_16x16x32_bf16 v[16:19], v[144:147], v[204:207], v[16:19]
	v_mfma_f32_16x16x32_bf16 v[8:11], v[156:159], v[204:207], v[8:11]
	v_mfma_f32_16x16x32_bf16 v[60:63], v[148:151], v[184:187], v[60:63]
	v_mfma_f32_16x16x32_bf16 v[56:59], v[160:163], v[184:187], v[56:59]
	v_mfma_f32_16x16x32_bf16 v[48:51], v[148:151], v[192:195], v[48:51]
	v_mfma_f32_16x16x32_bf16 v[40:43], v[160:163], v[192:195], v[40:43]
	v_mfma_f32_16x16x32_bf16 v[32:35], v[148:151], v[200:203], v[32:35]
	v_mfma_f32_16x16x32_bf16 v[24:27], v[160:163], v[200:203], v[24:27]
	v_mfma_f32_16x16x32_bf16 v[16:19], v[148:151], v[208:211], v[16:19]
	v_mfma_f32_16x16x32_bf16 v[8:11], v[160:163], v[208:211], v[8:11]
	v_mfma_f32_16x16x32_bf16 v[52:55], v[164:167], v[180:183], v[52:55]
	v_mfma_f32_16x16x32_bf16 v[44:47], v[172:175], v[180:183], v[44:47]
	v_mfma_f32_16x16x32_bf16 v[36:39], v[164:167], v[188:191], v[36:39]
	v_mfma_f32_16x16x32_bf16 v[28:31], v[172:175], v[188:191], v[28:31]
	v_mfma_f32_16x16x32_bf16 v[20:23], v[164:167], v[196:199], v[20:23]
	v_mfma_f32_16x16x32_bf16 v[12:15], v[172:175], v[196:199], v[12:15]
	v_mfma_f32_16x16x32_bf16 v[4:7], v[164:167], v[204:207], v[4:7]
	v_mfma_f32_16x16x32_bf16 v[0:3], v[172:175], v[204:207], v[0:3]
	v_mfma_f32_16x16x32_bf16 v[52:55], v[168:171], v[184:187], v[52:55]
	v_mfma_f32_16x16x32_bf16 v[44:47], v[176:179], v[184:187], v[44:47]
	v_mfma_f32_16x16x32_bf16 v[36:39], v[168:171], v[192:195], v[36:39]
	v_mfma_f32_16x16x32_bf16 v[28:31], v[176:179], v[192:195], v[28:31]
	v_mfma_f32_16x16x32_bf16 v[20:23], v[168:171], v[200:203], v[20:23]
	v_mfma_f32_16x16x32_bf16 v[12:15], v[176:179], v[200:203], v[12:15]
	v_mfma_f32_16x16x32_bf16 v[4:7], v[168:171], v[208:211], v[4:7]
	v_mfma_f32_16x16x32_bf16 v[0:3], v[176:179], v[208:211], v[0:3]
	s_setprio 0
	s_barrier
	s_add_i32 s58, s58, 2
	s_add_u32 s40, s40, 0x100
	s_addc_u32 s41, s41, 0
	s_add_u32 s56, s56, 0x100
	s_addc_u32 s57, s57, 0
	s_cmp_gt_u32 s58, 5
	s_cbranch_scc0 .LBB0_1013

; #define PG8_STAGE(bufoff, gbase, voff) do { _Pragma("unroll") for (int _i = 0; _i < 2; ++_i) \
;         __builtin_amdgcn_global_load_lds((const unsigned*)((const char*)(gbase) + (voff)[_i]), (LAS unsigned*)(lds + (bufoff) + ldsw + _i * 8192), 16, 0, 0); } while (0)
; #define PG8_LDA(dst, b, h) do { _Pragma("unroll") for (int m = 0; m < 4; ++m) _Pragma("unroll") for (int k = 0; k < 2; ++k) dst[m][k] = *(const LAS bf16x8*)(lds + PG8_SA(b, h) + aoff + m * 2048 + k * 1024); } while (0)
; #define PG8_LDB(dst, b, h) do { _Pragma("unroll") for (int n = 0; n < 2; ++n) _Pragma("unroll") for (int k = 0; k < 2; ++k) dst[n][k] = *(const LAS bf16x8*)(lds + PG8_SB(b, h) + boff + n * 2048 + k * 1024); } while (0)
; #define PG8_MMA(ai, bj, At, Bt) do { __builtin_amdgcn_s_setprio(1); _Pragma("unroll") for (int m = 0; m < 4; ++m) _Pragma("unroll") for (int n = 0; n < 2; ++n) _Pragma("unroll") for (int k = 0; k < 2; ++k) \
;         acc[ai][bj][m][n] = __builtin_amdgcn_mfma_f32_16x16x32_bf16(Bt[n][k], At[m][k], acc[ai][bj][m][n], 0, 0, 0); __builtin_amdgcn_s_setprio(0); } while (0)
; template <class Epi>
; DI void gemm_phase(LAS unsigned char* lds, const int wid, const Gemm g, const Order& S, const Epi& E) {
;     ...
;         const bool has_next = S.next(ui + 1, nxt);
;         const char* nA = has_next ? (const char*)(g.A + (size_t)nxt.g * g.gsA + (size_t)nxt.pm * BM * g.lda) : cA;
;         const char* nB = has_next ? (const char*)(g.Bt + (size_t)nxt.g * g.gsB + (size_t)nxt.pn * BM * g.ldb) : cB;
;         for (int t = 0; t < nt; t += 2) {
;             const bool last = (t == nt - 2);
;             const char* a1 = cA + (size_t)(t + 1) * kstep;
;             const char* a2 = last ? nA : cA + (size_t)(t + 2) * kstep; const char* b2 = last ? nB : cB + (size_t)(t + 2) * kstep;
;             const char* a3 = a2 + kstep; const char* b3 = b2 + kstep;
;             PG8_LDB(B0, 0, 0); PG8_LDB(B1, 0, 1); PG8_SCHED; PG8_LDA(At, 0, 0); PG8_STAGE(PG8_SA(1, 1), a1 + hstepA, voffA);
;             PG8_WAIT_V(8); PG8_WAIT_L(0); PG8_BAR; PG8_MMA(0, 0, At, B0); PG8_MMA(0, 1, At, B1); PG8_BAR; PG8_SCHED;
;             PG8_LDA(At, 0, 1); PG8_STAGE(PG8_SB(0, 0), b2, voffB); PG8_STAGE(PG8_SB(0, 1), b2 + hstepB, voffB); PG8_STAGE(PG8_SA(0, 0), a2, voffA);
;             PG8_WAIT_V(8); PG8_WAIT_L(0); PG8_BAR; PG8_MMA(1, 0, At, B0); PG8_MMA(1, 1, At, B1); PG8_BAR; PG8_SCHED;
.LBB0_1090:
	s_ashr_i32 s29, s28, 31
	s_lshl_b64 s[34:35], s[28:29], 18
	s_add_u32 s34, s6, s34
	s_addc_u32 s35, s7, s35
	s_and_b64 s[36:37], s[8:9], exec
	s_cselect_b32 s29, s35, s41
	s_cselect_b32 s54, s34, s40
	s_ashr_i32 s31, s30, 31
	s_lshl_b64 s[36:37], s[30:31], 18
	s_add_u32 s36, s21, s36
	s_addc_u32 s37, s24, s37
	s_and_b64 s[44:45], s[8:9], exec
	s_cselect_b32 s31, s37, s43
	s_cselect_b32 s55, s36, s42
	s_add_u32 s40, s40, 0x20080
	s_addc_u32 s41, s41, 0
	s_add_u32 s56, s42, 0x100
	v_mov_b32_e32 v0, 0
	s_addc_u32 s57, s43, 0
	s_mov_b32 s58, -2
	ds_read_b128 v[128:131], v165
	ds_read_b128 v[132:135], v165 offset:1024
	ds_read_b128 v[136:139], v165 offset:2048
	ds_read_b128 v[140:143], v165 offset:3072
	ds_read_b128 v[160:163], v166
	ds_read_b128 v[168:171], v166 offset:1024
	ds_read_b128 v[172:175], v166 offset:2048
	ds_read_b128 v[176:179], v166 offset:3072
	s_add_u32 s42, s40, 0xfffe0080
	s_addc_u32 s43, s41, -1
	s_cmp_eq_u32 s58, 4
	s_cselect_b32 s45, s29, s43
	s_cselect_b32 s44, s54, s42
	s_cselect_b32 s43, s31, s57
	s_cselect_b32 s42, s55, s56
	v_lshl_add_u64 v[212:213], s[40:41], 0, v[152:153]
	s_add_i32 m0, s25, 0xc000
	ds_read_b128 v[180:183], v167
	ds_read_b128 v[184:187], v167 offset:1024
	ds_read_b128 v[188:191], v167 offset:2048
	ds_read_b128 v[192:195], v167 offset:3072
	ds_read_b128 v[196:199], v167 offset:4096
	ds_read_b128 v[200:203], v167 offset:5120
	ds_read_b128 v[204:207], v167 offset:6144
	ds_read_b128 v[208:211], v167 offset:7168
	global_load_lds_dwordx4 v[212:213], off
	v_lshl_add_u64 v[212:213], s[40:41], 0, v[154:155]
	s_add_i32 m0, s25, 0xe000
	s_nop 0
	global_load_lds_dwordx4 v[212:213], off
	s_waitcnt vmcnt(8)
	s_waitcnt lgkmcnt(0)
	s_barrier
	s_setprio 1
	v_mfma_f32_16x16x32_bf16 v[124:127], v[128:131], v[180:183], 0
	v_mfma_f32_16x16x32_bf16 v[120:123], v[136:139], v[180:183], 0
	v_mfma_f32_16x16x32_bf16 v[116:119], v[128:131], v[188:191], 0
	v_mfma_f32_16x16x32_bf16 v[104:107], v[136:139], v[188:191], 0
	v_mfma_f32_16x16x32_bf16 v[92:95], v[128:131], v[196:199], 0
	v_mfma_f32_16x16x32_bf16 v[88:91], v[136:139], v[196:199], 0
	v_mfma_f32_16x16x32_bf16 v[76:79], v[128:131], v[204:207], 0
	v_mfma_f32_16x16x32_bf16 v[72:75], v[136:139], v[204:207], 0
	v_mfma_f32_16x16x32_bf16 v[124:127], v[132:135], v[184:187], v[124:127]
	v_mfma_f32_16x16x32_bf16 v[120:123], v[140:143], v[184:187], v[120:123]
	v_mfma_f32_16x16x32_bf16 v[116:119], v[132:135], v[192:195], v[116:119]
	v_mfma_f32_16x16x32_bf16 v[104:107], v[140:143], v[192:195], v[104:107]
	v_mfma_f32_16x16x32_bf16 v[92:95], v[132:135], v[200:203], v[92:95]
	v_mfma_f32_16x16x32_bf16 v[88:91], v[140:143], v[200:203], v[88:91]
	v_mfma_f32_16x16x32_bf16 v[76:79], v[132:135], v[208:211], v[76:79]
	v_mfma_f32_16x16x32_bf16 v[72:75], v[140:143], v[208:211], v[72:75]
	v_mfma_f32_16x16x32_bf16 v[112:115], v[160:163], v[180:183], 0
	v_mfma_f32_16x16x32_bf16 v[108:111], v[172:175], v[180:183], 0
	v_mfma_f32_16x16x32_bf16 v[100:103], v[160:163], v[188:191], 0
	v_mfma_f32_16x16x32_bf16 v[96:99], v[172:175], v[188:191], 0
	v_mfma_f32_16x16x32_bf16 v[84:87], v[160:163], v[196:199], 0
	v_mfma_f32_16x16x32_bf16 v[80:83], v[172:175], v[196:199], 0
	v_mfma_f32_16x16x32_bf16 v[68:71], v[160:163], v[204:207], 0
	v_mfma_f32_16x16x32_bf16 v[64:67], v[172:175], v[204:207], 0
	v_mfma_f32_16x16x32_bf16 v[112:115], v[168:171], v[184:187], v[112:115]
	v_mfma_f32_16x16x32_bf16 v[108:111], v[176:179], v[184:187], v[108:111]
	v_mfma_f32_16x16x32_bf16 v[100:103], v[168:171], v[192:195], v[100:103]
	v_mfma_f32_16x16x32_bf16 v[96:99], v[176:179], v[192:195], v[96:99]
	v_mfma_f32_16x16x32_bf16 v[84:87], v[168:171], v[200:203], v[84:87]
	v_mfma_f32_16x16x32_bf16 v[80:83], v[176:179], v[200:203], v[80:83]
	v_mfma_f32_16x16x32_bf16 v[68:71], v[168:171], v[208:211], v[68:71]
	v_mfma_f32_16x16x32_bf16 v[64:67], v[176:179], v[208:211], v[64:67]
	s_setprio 0
	s_barrier
	s_add_i32 s59, s51, s94
	v_lshl_add_u64 v[212:213], s[42:43], 0, v[146:147]
	s_mov_b32 m0, s59
	ds_read_b128 v[180:183], v167 offset:16384
	ds_read_b128 v[184:187], v167 offset:17408
	ds_read_b128 v[188:191], v167 offset:18432
	ds_read_b128 v[192:195], v167 offset:19456
	ds_read_b128 v[196:199], v167 offset:20480
	ds_read_b128 v[200:203], v167 offset:21504
	ds_read_b128 v[204:207], v167 offset:22528
	ds_read_b128 v[208:211], v167 offset:23552
	global_load_lds_dwordx4 v[212:213], off
	s_add_i32 m0, s59, 0x2000
	s_add_u32 s60, s42, 0x20000
	v_lshl_add_u64 v[214:215], s[42:43], 0, v[150:151]
	s_addc_u32 s61, s43, 0
	s_add_i32 s59, s52, s94
	global_load_lds_dwordx4 v[214:215], off
	v_lshl_add_u64 v[216:217], s[60:61], 0, v[146:147]
	s_mov_b32 m0, s59
	v_lshl_add_u64 v[218:219], s[44:45], 0, v[148:149]
	global_load_lds_dwordx4 v[216:217], off
	v_lshl_add_u64 v[216:217], s[60:61], 0, v[150:151]
	s_add_i32 m0, s59, 0x2000
	s_nop 0
	global_load_lds_dwordx4 v[216:217], off
	v_lshl_add_u64 v[216:217], s[44:45], 0, v[144:145]
	s_mov_b32 m0, s25
	s_nop 0
	global_load_lds_dwordx4 v[216:217], off
	s_mov_b32 m0, s39
	s_nop 0
	global_load_lds_dwordx4 v[218:219], off
	s_waitcnt vmcnt(8)
	s_waitcnt lgkmcnt(0)
	s_barrier
; #define PG8_STAGE(bufoff, gbase, voff) do { _Pragma("unroll") for (int _i = 0; _i < 2; ++_i) \
;         __builtin_amdgcn_global_load_lds((const unsigned*)((const char*)(gbase) + (voff)[_i]), (LAS unsigned*)(lds + (bufoff) + ldsw + _i * 8192), 16, 0, 0); } while (0)
; #define PG8_LDA(dst, b, h) do { _Pragma("unroll") for (int m = 0; m < 4; ++m) _Pragma("unroll") for (int k = 0; k < 2; ++k) dst[m][k] = *(const LAS bf16x8*)(lds + PG8_SA(b, h) + aoff + m * 2048 + k * 1024); } while (0)
; #define PG8_LDB(dst, b, h) do { _Pragma("unroll") for (int n = 0; n < 2; ++n) _Pragma("unroll") for (int k = 0; k < 2; ++k) dst[n][k] = *(const LAS bf16x8*)(lds + PG8_SB(b, h) + boff + n * 2048 + k * 1024); } while (0)
; #define PG8_MMA(ai, bj, At, Bt) do { __builtin_amdgcn_s_setprio(1); _Pragma("unroll") for (int m = 0; m < 4; ++m) _Pragma("unroll") for (int n = 0; n < 2; ++n) _Pragma("unroll") for (int k = 0; k < 2; ++k) \
;         acc[ai][bj][m][n] = __builtin_amdgcn_mfma_f32_16x16x32_bf16(Bt[n][k], At[m][k], acc[ai][bj][m][n], 0, 0, 0); __builtin_amdgcn_s_setprio(0); } while (0)
; #define PG8_WAIT_V(n) asm volatile("s_waitcnt vmcnt(" #n ")" ::: "memory")
; #define PG8_WAIT_L(n) asm volatile("s_waitcnt lgkmcnt(" #n ")" ::: "memory")
; #define PG8_BAR __builtin_amdgcn_s_barrier()
; #define PG8_SCHED __builtin_amdgcn_sched_barrier(0)
; template <class Epi>
; DI void gemm_phase(LAS unsigned char* lds, const int wid, const Gemm g, const Order& S, const Epi& E) {
;     ...
;             PG8_WAIT_V(8); PG8_WAIT_L(0); PG8_BAR; PG8_MMA(1, 0, At, B0); PG8_MMA(1, 1, At, B1); PG8_BAR; PG8_SCHED;
;             PG8_LDB(B0, 1, 0); PG8_LDB(B1, 1, 1); PG8_SCHED; PG8_LDA(At, 1, 0); PG8_STAGE(PG8_SA(0, 1), a2 + hstepA, voffA);
;             PG8_WAIT_V(8); PG8_WAIT_L(0); PG8_BAR; PG8_MMA(0, 0, At, B0); PG8_MMA(0, 1, At, B1); PG8_BAR; PG8_SCHED;
	s_setprio 1
	v_mfma_f32_16x16x32_bf16 v[60:63], v[128:131], v[180:183], 0
	v_mfma_f32_16x16x32_bf16 v[56:59], v[136:139], v[180:183], 0
	v_mfma_f32_16x16x32_bf16 v[44:47], v[128:131], v[188:191], 0
	v_mfma_f32_16x16x32_bf16 v[40:43], v[136:139], v[188:191], 0
	v_mfma_f32_16x16x32_bf16 v[28:31], v[128:131], v[196:199], 0
	v_mfma_f32_16x16x32_bf16 v[24:27], v[136:139], v[196:199], 0
	v_mfma_f32_16x16x32_bf16 v[12:15], v[128:131], v[204:207], 0
	v_mfma_f32_16x16x32_bf16 v[8:11], v[136:139], v[204:207], 0
	v_mfma_f32_16x16x32_bf16 v[60:63], v[132:135], v[184:187], v[60:63]
	v_mfma_f32_16x16x32_bf16 v[56:59], v[140:143], v[184:187], v[56:59]
	v_mfma_f32_16x16x32_bf16 v[44:47], v[132:135], v[192:195], v[44:47]
	v_mfma_f32_16x16x32_bf16 v[40:43], v[140:143], v[192:195], v[40:43]
	v_mfma_f32_16x16x32_bf16 v[28:31], v[132:135], v[200:203], v[28:31]
	v_mfma_f32_16x16x32_bf16 v[24:27], v[140:143], v[200:203], v[24:27]
	v_mfma_f32_16x16x32_bf16 v[12:15], v[132:135], v[208:211], v[12:15]
	v_mfma_f32_16x16x32_bf16 v[8:11], v[140:143], v[208:211], v[8:11]
	v_mfma_f32_16x16x32_bf16 v[52:55], v[160:163], v[180:183], 0
	v_mfma_f32_16x16x32_bf16 v[48:51], v[172:175], v[180:183], 0
	v_mfma_f32_16x16x32_bf16 v[36:39], v[160:163], v[188:191], 0
	v_mfma_f32_16x16x32_bf16 v[32:35], v[172:175], v[188:191], 0
	v_mfma_f32_16x16x32_bf16 v[20:23], v[160:163], v[196:199], 0
	v_mfma_f32_16x16x32_bf16 v[16:19], v[172:175], v[196:199], 0
	v_mfma_f32_16x16x32_bf16 v[4:7], v[160:163], v[204:207], 0
	v_mfma_f32_16x16x32_bf16 v[0:3], v[172:175], v[204:207], 0
	v_mfma_f32_16x16x32_bf16 v[52:55], v[168:171], v[184:187], v[52:55]
	v_mfma_f32_16x16x32_bf16 v[48:51], v[176:179], v[184:187], v[48:51]
	v_mfma_f32_16x16x32_bf16 v[36:39], v[168:171], v[192:195], v[36:39]
	v_mfma_f32_16x16x32_bf16 v[32:35], v[176:179], v[192:195], v[32:35]
	v_mfma_f32_16x16x32_bf16 v[20:23], v[168:171], v[200:203], v[20:23]
	v_mfma_f32_16x16x32_bf16 v[16:19], v[176:179], v[200:203], v[16:19]
	v_mfma_f32_16x16x32_bf16 v[4:7], v[168:171], v[208:211], v[4:7]
	v_mfma_f32_16x16x32_bf16 v[0:3], v[176:179], v[208:211], v[0:3]
	s_setprio 0
	s_barrier
	s_add_i32 s59, 0, 0x18000
	s_add_i32 s60, 0, 0x1c000
	v_add_u32_e32 v140, s59, v164
	v_add_u32_e32 v176, s60, v164
	ds_read_b128 v[128:131], v140
	ds_read_b128 v[132:135], v140 offset:1024
	ds_read_b128 v[136:139], v140 offset:2048
	ds_read_b128 v[140:143], v140 offset:3072
	ds_read_b128 v[160:163], v176
	ds_read_b128 v[168:171], v176 offset:1024
	ds_read_b128 v[172:175], v176 offset:2048
	ds_read_b128 v[176:179], v176 offset:3072
	s_add_u32 s44, s44, 0x20000
	s_addc_u32 s45, s45, 0
	s_mov_b32 m0, s46
	v_lshl_add_u64 v[220:221], s[44:45], 0, v[144:145]
	ds_read_b128 v[180:183], v167 offset:32768
	ds_read_b128 v[184:187], v167 offset:33792
	ds_read_b128 v[188:191], v167 offset:34816
	ds_read_b128 v[192:195], v167 offset:35840
	ds_read_b128 v[196:199], v167 offset:36864
	ds_read_b128 v[200:203], v167 offset:37888
	ds_read_b128 v[204:207], v167 offset:38912
	ds_read_b128 v[208:211], v167 offset:39936
	global_load_lds_dwordx4 v[220:221], off
	v_lshl_add_u64 v[220:221], s[44:45], 0, v[148:149]
	s_mov_b32 m0, s47
	s_nop 0
	global_load_lds_dwordx4 v[220:221], off
	s_waitcnt vmcnt(8)
	s_waitcnt lgkmcnt(0)
	s_barrier
	s_setprio 1
	v_mfma_f32_16x16x32_bf16 v[124:127], v[128:131], v[180:183], v[124:127]
	v_mfma_f32_16x16x32_bf16 v[120:123], v[136:139], v[180:183], v[120:123]
	v_mfma_f32_16x16x32_bf16 v[116:119], v[128:131], v[188:191], v[116:119]
	v_mfma_f32_16x16x32_bf16 v[104:107], v[136:139], v[188:191], v[104:107]
	v_mfma_f32_16x16x32_bf16 v[92:95], v[128:131], v[196:199], v[92:95]
	v_mfma_f32_16x16x32_bf16 v[88:91], v[136:139], v[196:199], v[88:91]
	v_mfma_f32_16x16x32_bf16 v[76:79], v[128:131], v[204:207], v[76:79]
	v_mfma_f32_16x16x32_bf16 v[72:75], v[136:139], v[204:207], v[72:75]
	v_mfma_f32_16x16x32_bf16 v[124:127], v[132:135], v[184:187], v[124:127]
	v_mfma_f32_16x16x32_bf16 v[120:123], v[140:143], v[184:187], v[120:123]
	v_mfma_f32_16x16x32_bf16 v[116:119], v[132:135], v[192:195], v[116:119]
	v_mfma_f32_16x16x32_bf16 v[104:107], v[140:143], v[192:195], v[104:107]
	v_mfma_f32_16x16x32_bf16 v[92:95], v[132:135], v[200:203], v[92:95]
	v_mfma_f32_16x16x32_bf16 v[88:91], v[140:143], v[200:203], v[88:91]
	v_mfma_f32_16x16x32_bf16 v[76:79], v[132:135], v[208:211], v[76:79]
	v_mfma_f32_16x16x32_bf16 v[72:75], v[140:143], v[208:211], v[72:75]
	v_mfma_f32_16x16x32_bf16 v[112:115], v[160:163], v[180:183], v[112:115]
	v_mfma_f32_16x16x32_bf16 v[108:111], v[172:175], v[180:183], v[108:111]
	v_mfma_f32_16x16x32_bf16 v[100:103], v[160:163], v[188:191], v[100:103]
	v_mfma_f32_16x16x32_bf16 v[96:99], v[172:175], v[188:191], v[96:99]
	v_mfma_f32_16x16x32_bf16 v[84:87], v[160:163], v[196:199], v[84:87]
	v_mfma_f32_16x16x32_bf16 v[80:83], v[172:175], v[196:199], v[80:83]
	v_mfma_f32_16x16x32_bf16 v[68:71], v[160:163], v[204:207], v[68:71]
	v_mfma_f32_16x16x32_bf16 v[64:67], v[172:175], v[204:207], v[64:67]
	v_mfma_f32_16x16x32_bf16 v[112:115], v[168:171], v[184:187], v[112:115]
	v_mfma_f32_16x16x32_bf16 v[108:111], v[176:179], v[184:187], v[108:111]
	v_mfma_f32_16x16x32_bf16 v[100:103], v[168:171], v[192:195], v[100:103]
	v_mfma_f32_16x16x32_bf16 v[96:99], v[176:179], v[192:195], v[96:99]
	v_mfma_f32_16x16x32_bf16 v[84:87], v[168:171], v[200:203], v[84:87]
	v_mfma_f32_16x16x32_bf16 v[80:83], v[176:179], v[200:203], v[80:83]
	v_mfma_f32_16x16x32_bf16 v[68:71], v[168:171], v[208:211], v[68:71]
	v_mfma_f32_16x16x32_bf16 v[64:67], v[176:179], v[208:211], v[64:67]
	s_setprio 0
	s_barrier
; #define PG8_STAGE(bufoff, gbase, voff) do { _Pragma("unroll") for (int _i = 0; _i < 2; ++_i) \
;         __builtin_amdgcn_global_load_lds((const unsigned*)((const char*)(gbase) + (voff)[_i]), (LAS unsigned*)(lds + (bufoff) + ldsw + _i * 8192), 16, 0, 0); } while (0)
; #define PG8_LDA(dst, b, h) do { _Pragma("unroll") for (int m = 0; m < 4; ++m) _Pragma("unroll") for (int k = 0; k < 2; ++k) dst[m][k] = *(const LAS bf16x8*)(lds + PG8_SA(b, h) + aoff + m * 2048 + k * 1024); } while (0)
; #define PG8_LDB(dst, b, h) do { _Pragma("unroll") for (int n = 0; n < 2; ++n) _Pragma("unroll") for (int k = 0; k < 2; ++k) dst[n][k] = *(const LAS bf16x8*)(lds + PG8_SB(b, h) + boff + n * 2048 + k * 1024); } while (0)
; #define PG8_WAIT_V(n) asm volatile("s_waitcnt vmcnt(" #n ")" ::: "memory")
; #define PG8_WAIT_L(n) asm volatile("s_waitcnt lgkmcnt(" #n ")" ::: "memory")
; template <class Epi>
; DI void gemm_phase(LAS unsigned char* lds, const int wid, const Gemm g, const Order& S, const Epi& E) {
;     ...
;         for (int t = 0; t < nt; t += 2) {
;             const bool last = (t == nt - 2);
;             const char* a1 = cA + (size_t)(t + 1) * kstep;
;             const char* a2 = last ? nA : cA + (size_t)(t + 2) * kstep; const char* b2 = last ? nB : cB + (size_t)(t + 2) * kstep;
;             const char* a3 = a2 + kstep; const char* b3 = b2 + kstep;
;             PG8_LDB(B0, 0, 0); PG8_LDB(B1, 0, 1); PG8_SCHED; PG8_LDA(At, 0, 0); PG8_STAGE(PG8_SA(1, 1), a1 + hstepA, voffA);
;             PG8_WAIT_V(8); PG8_WAIT_L(0); PG8_BAR; PG8_MMA(0, 0, At, B0); PG8_MMA(0, 1, At, B1); PG8_BAR; PG8_SCHED;
;             PG8_LDA(At, 0, 1); PG8_STAGE(PG8_SB(0, 0), b2, voffB); PG8_STAGE(PG8_SB(0, 1), b2 + hstepB, voffB); PG8_STAGE(PG8_SA(0, 0), a2, voffA);
;             PG8_WAIT_V(8); PG8_WAIT_L(0); PG8_BAR; PG8_MMA(1, 0, At, B0); PG8_MMA(1, 1, At, B1); PG8_BAR; PG8_SCHED;
;             PG8_LDB(B0, 1, 0); PG8_LDB(B1, 1, 1); PG8_SCHED; PG8_LDA(At, 1, 0); PG8_STAGE(PG8_SA(0, 1), a2 + hstepA, voffA);
;             PG8_WAIT_V(8); PG8_WAIT_L(0); PG8_BAR; PG8_MMA(0, 0, At, B0); PG8_MMA(0, 1, At, B1); PG8_BAR; PG8_SCHED;
;             PG8_LDA(At, 1, 1); PG8_STAGE(PG8_SB(1, 0), b3, voffB); PG8_STAGE(PG8_SB(1, 1), b3 + hstepB, voffB); PG8_STAGE(PG8_SA(1, 0), a3, voffA);
;             PG8_WAIT_V(8); PG8_WAIT_L(0); PG8_BAR; PG8_MMA(1, 0, At, B0); PG8_MMA(1, 1, At, B1); PG8_BAR; PG8_SCHED;
	s_add_i32 s44, s59, s94
	v_lshl_add_u64 v[212:213], v[212:213], 0, s[16:17]
	s_mov_b32 m0, s44
	ds_read_b128 v[180:183], v167 offset:49152
	ds_read_b128 v[184:187], v167 offset:50176
	ds_read_b128 v[188:191], v167 offset:51200
	ds_read_b128 v[192:195], v167 offset:52224
	ds_read_b128 v[196:199], v167 offset:53248
	ds_read_b128 v[200:203], v167 offset:54272
	ds_read_b128 v[204:207], v167 offset:55296
	ds_read_b128 v[208:211], v167 offset:56320
	global_load_lds_dwordx4 v[212:213], off
	s_add_i32 m0, s44, 0x2000
	s_add_u32 s42, s42, 0x20080
	v_lshl_add_u64 v[212:213], v[214:215], 0, s[16:17]
	s_addc_u32 s43, s43, 0
	s_add_i32 s44, s60, s94
	global_load_lds_dwordx4 v[212:213], off
	v_lshl_add_u64 v[212:213], s[42:43], 0, v[146:147]
	s_mov_b32 m0, s44
	s_nop 0
	global_load_lds_dwordx4 v[212:213], off
	v_lshl_add_u64 v[212:213], s[42:43], 0, v[150:151]
	s_add_i32 m0, s44, 0x2000
	s_nop 0
	global_load_lds_dwordx4 v[212:213], off
	v_lshl_add_u64 v[212:213], v[216:217], 0, s[16:17]
	s_mov_b32 m0, s49
	s_nop 0
	global_load_lds_dwordx4 v[212:213], off
	v_lshl_add_u64 v[212:213], v[218:219], 0, s[16:17]
	s_mov_b32 m0, s50
	s_nop 0
	global_load_lds_dwordx4 v[212:213], off
	s_waitcnt vmcnt(8)
	s_waitcnt lgkmcnt(0)
	s_barrier
	s_setprio 1
	v_mfma_f32_16x16x32_bf16 v[60:63], v[128:131], v[180:183], v[60:63]
	v_mfma_f32_16x16x32_bf16 v[56:59], v[136:139], v[180:183], v[56:59]
	v_mfma_f32_16x16x32_bf16 v[44:47], v[128:131], v[188:191], v[44:47]
	v_mfma_f32_16x16x32_bf16 v[40:43], v[136:139], v[188:191], v[40:43]
	v_mfma_f32_16x16x32_bf16 v[28:31], v[128:131], v[196:199], v[28:31]
	v_mfma_f32_16x16x32_bf16 v[24:27], v[136:139], v[196:199], v[24:27]
	v_mfma_f32_16x16x32_bf16 v[12:15], v[128:131], v[204:207], v[12:15]
	v_mfma_f32_16x16x32_bf16 v[8:11], v[136:139], v[204:207], v[8:11]
	v_mfma_f32_16x16x32_bf16 v[60:63], v[132:135], v[184:187], v[60:63]
	v_mfma_f32_16x16x32_bf16 v[56:59], v[140:143], v[184:187], v[56:59]
	v_mfma_f32_16x16x32_bf16 v[44:47], v[132:135], v[192:195], v[44:47]
	v_mfma_f32_16x16x32_bf16 v[40:43], v[140:143], v[192:195], v[40:43]
	v_mfma_f32_16x16x32_bf16 v[28:31], v[132:135], v[200:203], v[28:31]
	v_mfma_f32_16x16x32_bf16 v[24:27], v[140:143], v[200:203], v[24:27]
	v_mfma_f32_16x16x32_bf16 v[12:15], v[132:135], v[208:211], v[12:15]
	v_mfma_f32_16x16x32_bf16 v[8:11], v[140:143], v[208:211], v[8:11]
	v_mfma_f32_16x16x32_bf16 v[52:55], v[160:163], v[180:183], v[52:55]
	v_mfma_f32_16x16x32_bf16 v[48:51], v[172:175], v[180:183], v[48:51]
	v_mfma_f32_16x16x32_bf16 v[36:39], v[160:163], v[188:191], v[36:39]
	v_mfma_f32_16x16x32_bf16 v[32:35], v[172:175], v[188:191], v[32:35]
	v_mfma_f32_16x16x32_bf16 v[20:23], v[160:163], v[196:199], v[20:23]
	v_mfma_f32_16x16x32_bf16 v[16:19], v[172:175], v[196:199], v[16:19]
	v_mfma_f32_16x16x32_bf16 v[4:7], v[160:163], v[204:207], v[4:7]
	v_mfma_f32_16x16x32_bf16 v[0:3], v[172:175], v[204:207], v[0:3]
	v_mfma_f32_16x16x32_bf16 v[52:55], v[168:171], v[184:187], v[52:55]
	v_mfma_f32_16x16x32_bf16 v[48:51], v[176:179], v[184:187], v[48:51]
	v_mfma_f32_16x16x32_bf16 v[36:39], v[168:171], v[192:195], v[36:39]
	v_mfma_f32_16x16x32_bf16 v[32:35], v[176:179], v[192:195], v[32:35]
	v_mfma_f32_16x16x32_bf16 v[20:23], v[168:171], v[200:203], v[20:23]
	v_mfma_f32_16x16x32_bf16 v[16:19], v[176:179], v[200:203], v[16:19]
	v_mfma_f32_16x16x32_bf16 v[4:7], v[168:171], v[208:211], v[4:7]
	v_mfma_f32_16x16x32_bf16 v[0:3], v[176:179], v[208:211], v[0:3]
	s_setprio 0
	s_barrier
	s_add_i32 s58, s58, 2
	s_add_u32 s40, s40, 0x100
	s_addc_u32 s41, s41, 0
	s_add_u32 s56, s56, 0x100
	s_addc_u32 s57, s57, 0
	s_cmp_gt_u32 s58, 5
	s_cbranch_scc0 .LBB0_1091
	s_branch .Lpeel_exit_6
.LBB0_1091:
	ds_read_b128 v[128:131], v165
	ds_read_b128 v[132:135], v165 offset:1024
	ds_read_b128 v[136:139], v165 offset:2048
	ds_read_b128 v[140:143], v165 offset:3072
	ds_read_b128 v[160:163], v166
	ds_read_b128 v[168:171], v166 offset:1024
	ds_read_b128 v[172:175], v166 offset:2048
	ds_read_b128 v[176:179], v166 offset:3072
	s_add_u32 s42, s40, 0xfffe0080
	s_addc_u32 s43, s41, -1
	s_cmp_eq_u32 s58, 4
	s_cselect_b32 s45, s29, s43
	s_cselect_b32 s44, s54, s42
	s_cselect_b32 s43, s31, s57
	s_cselect_b32 s42, s55, s56
	v_lshl_add_u64 v[212:213], s[40:41], 0, v[152:153]
	s_add_i32 m0, s25, 0xc000
	ds_read_b128 v[180:183], v167
	ds_read_b128 v[184:187], v167 offset:1024
	ds_read_b128 v[188:191], v167 offset:2048
	ds_read_b128 v[192:195], v167 offset:3072
	ds_read_b128 v[196:199], v167 offset:4096
	ds_read_b128 v[200:203], v167 offset:5120
	ds_read_b128 v[204:207], v167 offset:6144
	ds_read_b128 v[208:211], v167 offset:7168
	global_load_lds_dwordx4 v[212:213], off
	v_lshl_add_u64 v[212:213], s[40:41], 0, v[154:155]
	s_add_i32 m0, s25, 0xe000
	s_nop 0
	global_load_lds_dwordx4 v[212:213], off
	s_waitcnt vmcnt(8)
	s_waitcnt lgkmcnt(0)
	s_barrier
; #define PG8_STAGE(bufoff, gbase, voff) do { _Pragma("unroll") for (int _i = 0; _i < 2; ++_i) \
;         __builtin_amdgcn_global_load_lds((const unsigned*)((const char*)(gbase) + (voff)[_i]), (LAS unsigned*)(lds + (bufoff) + ldsw + _i * 8192), 16, 0, 0); } while (0)
; #define PG8_LDA(dst, b, h) do { _Pragma("unroll") for (int m = 0; m < 4; ++m) _Pragma("unroll") for (int k = 0; k < 2; ++k) dst[m][k] = *(const LAS bf16x8*)(lds + PG8_SA(b, h) + aoff + m * 2048 + k * 1024); } while (0)
; #define PG8_MMA(ai, bj, At, Bt) do { __builtin_amdgcn_s_setprio(1); _Pragma("unroll") for (int m = 0; m < 4; ++m) _Pragma("unroll") for (int n = 0; n < 2; ++n) _Pragma("unroll") for (int k = 0; k < 2; ++k) \
;         acc[ai][bj][m][n] = __builtin_amdgcn_mfma_f32_16x16x32_bf16(Bt[n][k], At[m][k], acc[ai][bj][m][n], 0, 0, 0); __builtin_amdgcn_s_setprio(0); } while (0)
; #define PG8_WAIT_V(n) asm volatile("s_waitcnt vmcnt(" #n ")" ::: "memory")
; #define PG8_WAIT_L(n) asm volatile("s_waitcnt lgkmcnt(" #n ")" ::: "memory")
; #define PG8_BAR __builtin_amdgcn_s_barrier()
; #define PG8_SCHED __builtin_amdgcn_sched_barrier(0)
; template <class Epi>
; DI void gemm_phase(LAS unsigned char* lds, const int wid, const Gemm g, const Order& S, const Epi& E) {
;     ...
;             PG8_WAIT_V(8); PG8_WAIT_L(0); PG8_BAR; PG8_MMA(0, 0, At, B0); PG8_MMA(0, 1, At, B1); PG8_BAR; PG8_SCHED;
;             PG8_LDA(At, 0, 1); PG8_STAGE(PG8_SB(0, 0), b2, voffB); PG8_STAGE(PG8_SB(0, 1), b2 + hstepB, voffB); PG8_STAGE(PG8_SA(0, 0), a2, voffA);
;             PG8_WAIT_V(8); PG8_WAIT_L(0); PG8_BAR; PG8_MMA(1, 0, At, B0); PG8_MMA(1, 1, At, B1); PG8_BAR; PG8_SCHED;
	s_setprio 1
	v_mfma_f32_16x16x32_bf16 v[124:127], v[128:131], v[180:183], v[124:127]
	v_mfma_f32_16x16x32_bf16 v[120:123], v[136:139], v[180:183], v[120:123]
	v_mfma_f32_16x16x32_bf16 v[116:119], v[128:131], v[188:191], v[116:119]
	v_mfma_f32_16x16x32_bf16 v[104:107], v[136:139], v[188:191], v[104:107]
	v_mfma_f32_16x16x32_bf16 v[92:95], v[128:131], v[196:199], v[92:95]
	v_mfma_f32_16x16x32_bf16 v[88:91], v[136:139], v[196:199], v[88:91]
	v_mfma_f32_16x16x32_bf16 v[76:79], v[128:131], v[204:207], v[76:79]
	v_mfma_f32_16x16x32_bf16 v[72:75], v[136:139], v[204:207], v[72:75]
	v_mfma_f32_16x16x32_bf16 v[124:127], v[132:135], v[184:187], v[124:127]
	v_mfma_f32_16x16x32_bf16 v[120:123], v[140:143], v[184:187], v[120:123]
	v_mfma_f32_16x16x32_bf16 v[116:119], v[132:135], v[192:195], v[116:119]
	v_mfma_f32_16x16x32_bf16 v[104:107], v[140:143], v[192:195], v[104:107]
	v_mfma_f32_16x16x32_bf16 v[92:95], v[132:135], v[200:203], v[92:95]
	v_mfma_f32_16x16x32_bf16 v[88:91], v[140:143], v[200:203], v[88:91]
	v_mfma_f32_16x16x32_bf16 v[76:79], v[132:135], v[208:211], v[76:79]
	v_mfma_f32_16x16x32_bf16 v[72:75], v[140:143], v[208:211], v[72:75]
	v_mfma_f32_16x16x32_bf16 v[112:115], v[160:163], v[180:183], v[112:115]
	v_mfma_f32_16x16x32_bf16 v[108:111], v[172:175], v[180:183], v[108:111]
	v_mfma_f32_16x16x32_bf16 v[100:103], v[160:163], v[188:191], v[100:103]
	v_mfma_f32_16x16x32_bf16 v[96:99], v[172:175], v[188:191], v[96:99]
	v_mfma_f32_16x16x32_bf16 v[84:87], v[160:163], v[196:199], v[84:87]
	v_mfma_f32_16x16x32_bf16 v[80:83], v[172:175], v[196:199], v[80:83]
	v_mfma_f32_16x16x32_bf16 v[68:71], v[160:163], v[204:207], v[68:71]
	v_mfma_f32_16x16x32_bf16 v[64:67], v[172:175], v[204:207], v[64:67]
	v_mfma_f32_16x16x32_bf16 v[112:115], v[168:171], v[184:187], v[112:115]
	v_mfma_f32_16x16x32_bf16 v[108:111], v[176:179], v[184:187], v[108:111]
	v_mfma_f32_16x16x32_bf16 v[100:103], v[168:171], v[192:195], v[100:103]
	v_mfma_f32_16x16x32_bf16 v[96:99], v[176:179], v[192:195], v[96:99]
	v_mfma_f32_16x16x32_bf16 v[84:87], v[168:171], v[200:203], v[84:87]
	v_mfma_f32_16x16x32_bf16 v[80:83], v[176:179], v[200:203], v[80:83]
	v_mfma_f32_16x16x32_bf16 v[68:71], v[168:171], v[208:211], v[68:71]
	v_mfma_f32_16x16x32_bf16 v[64:67], v[176:179], v[208:211], v[64:67]
	s_setprio 0
	s_barrier
	s_add_i32 s59, s51, s94
	v_lshl_add_u64 v[212:213], s[42:43], 0, v[146:147]
	s_mov_b32 m0, s59
	ds_read_b128 v[180:183], v167 offset:16384
	ds_read_b128 v[184:187], v167 offset:17408
	ds_read_b128 v[188:191], v167 offset:18432
	ds_read_b128 v[192:195], v167 offset:19456
	ds_read_b128 v[196:199], v167 offset:20480
	ds_read_b128 v[200:203], v167 offset:21504
	ds_read_b128 v[204:207], v167 offset:22528
	ds_read_b128 v[208:211], v167 offset:23552
	global_load_lds_dwordx4 v[212:213], off
	s_add_i32 m0, s59, 0x2000
	s_add_u32 s60, s42, 0x20000
	v_lshl_add_u64 v[214:215], s[42:43], 0, v[150:151]
	s_addc_u32 s61, s43, 0
	s_add_i32 s59, s52, s94
	global_load_lds_dwordx4 v[214:215], off
	v_lshl_add_u64 v[216:217], s[60:61], 0, v[146:147]
	s_mov_b32 m0, s59
	v_lshl_add_u64 v[218:219], s[44:45], 0, v[148:149]
	global_load_lds_dwordx4 v[216:217], off
	v_lshl_add_u64 v[216:217], s[60:61], 0, v[150:151]
	s_add_i32 m0, s59, 0x2000
	s_nop 0
	global_load_lds_dwordx4 v[216:217], off
	v_lshl_add_u64 v[216:217], s[44:45], 0, v[144:145]
	s_mov_b32 m0, s25
	s_nop 0
	global_load_lds_dwordx4 v[216:217], off
	s_mov_b32 m0, s39
	s_nop 0
	global_load_lds_dwordx4 v[218:219], off
	s_waitcnt vmcnt(8)
	s_waitcnt lgkmcnt(0)
	s_barrier
	s_setprio 1
	v_mfma_f32_16x16x32_bf16 v[60:63], v[128:131], v[180:183], v[60:63]
	v_mfma_f32_16x16x32_bf16 v[56:59], v[136:139], v[180:183], v[56:59]
	v_mfma_f32_16x16x32_bf16 v[44:47], v[128:131], v[188:191], v[44:47]
	v_mfma_f32_16x16x32_bf16 v[40:43], v[136:139], v[188:191], v[40:43]
	v_mfma_f32_16x16x32_bf16 v[28:31], v[128:131], v[196:199], v[28:31]
	v_mfma_f32_16x16x32_bf16 v[24:27], v[136:139], v[196:199], v[24:27]
	v_mfma_f32_16x16x32_bf16 v[12:15], v[128:131], v[204:207], v[12:15]
	v_mfma_f32_16x16x32_bf16 v[8:11], v[136:139], v[204:207], v[8:11]
	v_mfma_f32_16x16x32_bf16 v[60:63], v[132:135], v[184:187], v[60:63]
	v_mfma_f32_16x16x32_bf16 v[56:59], v[140:143], v[184:187], v[56:59]
	v_mfma_f32_16x16x32_bf16 v[44:47], v[132:135], v[192:195], v[44:47]
	v_mfma_f32_16x16x32_bf16 v[40:43], v[140:143], v[192:195], v[40:43]
	v_mfma_f32_16x16x32_bf16 v[28:31], v[132:135], v[200:203], v[28:31]
	v_mfma_f32_16x16x32_bf16 v[24:27], v[140:143], v[200:203], v[24:27]
	v_mfma_f32_16x16x32_bf16 v[12:15], v[132:135], v[208:211], v[12:15]
	v_mfma_f32_16x16x32_bf16 v[8:11], v[140:143], v[208:211], v[8:11]
	v_mfma_f32_16x16x32_bf16 v[52:55], v[160:163], v[180:183], v[52:55]
	v_mfma_f32_16x16x32_bf16 v[48:51], v[172:175], v[180:183], v[48:51]
	v_mfma_f32_16x16x32_bf16 v[36:39], v[160:163], v[188:191], v[36:39]
	v_mfma_f32_16x16x32_bf16 v[32:35], v[172:175], v[188:191], v[32:35]
	v_mfma_f32_16x16x32_bf16 v[20:23], v[160:163], v[196:199], v[20:23]
	v_mfma_f32_16x16x32_bf16 v[16:19], v[172:175], v[196:199], v[16:19]
	v_mfma_f32_16x16x32_bf16 v[4:7], v[160:163], v[204:207], v[4:7]
	v_mfma_f32_16x16x32_bf16 v[0:3], v[172:175], v[204:207], v[0:3]
	v_mfma_f32_16x16x32_bf16 v[52:55], v[168:171], v[184:187], v[52:55]
	v_mfma_f32_16x16x32_bf16 v[48:51], v[176:179], v[184:187], v[48:51]
	v_mfma_f32_16x16x32_bf16 v[36:39], v[168:171], v[192:195], v[36:39]
	v_mfma_f32_16x16x32_bf16 v[32:35], v[176:179], v[192:195], v[32:35]
	v_mfma_f32_16x16x32_bf16 v[20:23], v[168:171], v[200:203], v[20:23]
	v_mfma_f32_16x16x32_bf16 v[16:19], v[176:179], v[200:203], v[16:19]
	v_mfma_f32_16x16x32_bf16 v[4:7], v[168:171], v[208:211], v[4:7]
	v_mfma_f32_16x16x32_bf16 v[0:3], v[176:179], v[208:211], v[0:3]
	s_setprio 0
	s_barrier
; #define PG8_STAGE(bufoff, gbase, voff) do { _Pragma("unroll") for (int _i = 0; _i < 2; ++_i) \
;         __builtin_amdgcn_global_load_lds((const unsigned*)((const char*)(gbase) + (voff)[_i]), (LAS unsigned*)(lds + (bufoff) + ldsw + _i * 8192), 16, 0, 0); } while (0)
; #define PG8_LDA(dst, b, h) do { _Pragma("unroll") for (int m = 0; m < 4; ++m) _Pragma("unroll") for (int k = 0; k < 2; ++k) dst[m][k] = *(const LAS bf16x8*)(lds + PG8_SA(b, h) + aoff + m * 2048 + k * 1024); } while (0)
; #define PG8_LDB(dst, b, h) do { _Pragma("unroll") for (int n = 0; n < 2; ++n) _Pragma("unroll") for (int k = 0; k < 2; ++k) dst[n][k] = *(const LAS bf16x8*)(lds + PG8_SB(b, h) + boff + n * 2048 + k * 1024); } while (0)
; #define PG8_MMA(ai, bj, At, Bt) do { __builtin_amdgcn_s_setprio(1); _Pragma("unroll") for (int m = 0; m < 4; ++m) _Pragma("unroll") for (int n = 0; n < 2; ++n) _Pragma("unroll") for (int k = 0; k < 2; ++k) \
;         acc[ai][bj][m][n] = __builtin_amdgcn_mfma_f32_16x16x32_bf16(Bt[n][k], At[m][k], acc[ai][bj][m][n], 0, 0, 0); __builtin_amdgcn_s_setprio(0); } while (0)
; #define PG8_WAIT_V(n) asm volatile("s_waitcnt vmcnt(" #n ")" ::: "memory")
; #define PG8_WAIT_L(n) asm volatile("s_waitcnt lgkmcnt(" #n ")" ::: "memory")
; #define PG8_BAR __builtin_amdgcn_s_barrier()
; #define PG8_SCHED __builtin_amdgcn_sched_barrier(0)
; template <class Epi>
; DI void gemm_phase(LAS unsigned char* lds, const int wid, const Gemm g, const Order& S, const Epi& E) {
;     ...
;             PG8_LDB(B0, 1, 0); PG8_LDB(B1, 1, 1); PG8_SCHED; PG8_LDA(At, 1, 0); PG8_STAGE(PG8_SA(0, 1), a2 + hstepA, voffA);
;             PG8_WAIT_V(8); PG8_WAIT_L(0); PG8_BAR; PG8_MMA(0, 0, At, B0); PG8_MMA(0, 1, At, B1); PG8_BAR; PG8_SCHED;
	s_add_i32 s59, 0, 0x18000
	s_add_i32 s60, 0, 0x1c000
	v_add_u32_e32 v140, s59, v164
	v_add_u32_e32 v176, s60, v164
	ds_read_b128 v[128:131], v140
	ds_read_b128 v[132:135], v140 offset:1024
	ds_read_b128 v[136:139], v140 offset:2048
	ds_read_b128 v[140:143], v140 offset:3072
	ds_read_b128 v[160:163], v176
	ds_read_b128 v[168:171], v176 offset:1024
	ds_read_b128 v[172:175], v176 offset:2048
	ds_read_b128 v[176:179], v176 offset:3072
	s_add_u32 s44, s44, 0x20000
	s_addc_u32 s45, s45, 0
	s_mov_b32 m0, s46
	v_lshl_add_u64 v[220:221], s[44:45], 0, v[144:145]
	ds_read_b128 v[180:183], v167 offset:32768
	ds_read_b128 v[184:187], v167 offset:33792
	ds_read_b128 v[188:191], v167 offset:34816
	ds_read_b128 v[192:195], v167 offset:35840
	ds_read_b128 v[196:199], v167 offset:36864
	ds_read_b128 v[200:203], v167 offset:37888
	ds_read_b128 v[204:207], v167 offset:38912
	ds_read_b128 v[208:211], v167 offset:39936
	global_load_lds_dwordx4 v[220:221], off
	v_lshl_add_u64 v[220:221], s[44:45], 0, v[148:149]
	s_mov_b32 m0, s47
	s_nop 0
	global_load_lds_dwordx4 v[220:221], off
	s_waitcnt vmcnt(8)
	s_waitcnt lgkmcnt(0)
	s_barrier
	s_setprio 1
	v_mfma_f32_16x16x32_bf16 v[124:127], v[128:131], v[180:183], v[124:127]
	v_mfma_f32_16x16x32_bf16 v[120:123], v[136:139], v[180:183], v[120:123]
	v_mfma_f32_16x16x32_bf16 v[116:119], v[128:131], v[188:191], v[116:119]
	v_mfma_f32_16x16x32_bf16 v[104:107], v[136:139], v[188:191], v[104:107]
	v_mfma_f32_16x16x32_bf16 v[92:95], v[128:131], v[196:199], v[92:95]
	v_mfma_f32_16x16x32_bf16 v[88:91], v[136:139], v[196:199], v[88:91]
	v_mfma_f32_16x16x32_bf16 v[76:79], v[128:131], v[204:207], v[76:79]
	v_mfma_f32_16x16x32_bf16 v[72:75], v[136:139], v[204:207], v[72:75]
	v_mfma_f32_16x16x32_bf16 v[124:127], v[132:135], v[184:187], v[124:127]
	v_mfma_f32_16x16x32_bf16 v[120:123], v[140:143], v[184:187], v[120:123]
	v_mfma_f32_16x16x32_bf16 v[116:119], v[132:135], v[192:195], v[116:119]
	v_mfma_f32_16x16x32_bf16 v[104:107], v[140:143], v[192:195], v[104:107]
	v_mfma_f32_16x16x32_bf16 v[92:95], v[132:135], v[200:203], v[92:95]
	v_mfma_f32_16x16x32_bf16 v[88:91], v[140:143], v[200:203], v[88:91]
	v_mfma_f32_16x16x32_bf16 v[76:79], v[132:135], v[208:211], v[76:79]
	v_mfma_f32_16x16x32_bf16 v[72:75], v[140:143], v[208:211], v[72:75]
	v_mfma_f32_16x16x32_bf16 v[112:115], v[160:163], v[180:183], v[112:115]
	v_mfma_f32_16x16x32_bf16 v[108:111], v[172:175], v[180:183], v[108:111]
	v_mfma_f32_16x16x32_bf16 v[100:103], v[160:163], v[188:191], v[100:103]
	v_mfma_f32_16x16x32_bf16 v[96:99], v[172:175], v[188:191], v[96:99]
	v_mfma_f32_16x16x32_bf16 v[84:87], v[160:163], v[196:199], v[84:87]
	v_mfma_f32_16x16x32_bf16 v[80:83], v[172:175], v[196:199], v[80:83]
	v_mfma_f32_16x16x32_bf16 v[68:71], v[160:163], v[204:207], v[68:71]
	v_mfma_f32_16x16x32_bf16 v[64:67], v[172:175], v[204:207], v[64:67]
	v_mfma_f32_16x16x32_bf16 v[112:115], v[168:171], v[184:187], v[112:115]
	v_mfma_f32_16x16x32_bf16 v[108:111], v[176:179], v[184:187], v[108:111]
	v_mfma_f32_16x16x32_bf16 v[100:103], v[168:171], v[192:195], v[100:103]
	v_mfma_f32_16x16x32_bf16 v[96:99], v[176:179], v[192:195], v[96:99]
	v_mfma_f32_16x16x32_bf16 v[84:87], v[168:171], v[200:203], v[84:87]
	v_mfma_f32_16x16x32_bf16 v[80:83], v[176:179], v[200:203], v[80:83]
	v_mfma_f32_16x16x32_bf16 v[68:71], v[168:171], v[208:211], v[68:71]
	v_mfma_f32_16x16x32_bf16 v[64:67], v[176:179], v[208:211], v[64:67]
	s_setprio 0
	s_barrier
; #define PG8_STAGE(bufoff, gbase, voff) do { _Pragma("unroll") for (int _i = 0; _i < 2; ++_i) \
;         __builtin_amdgcn_global_load_lds((const unsigned*)((const char*)(gbase) + (voff)[_i]), (LAS unsigned*)(lds + (bufoff) + ldsw + _i * 8192), 16, 0, 0); } while (0)
; #define PG8_LDA(dst, b, h) do { _Pragma("unroll") for (int m = 0; m < 4; ++m) _Pragma("unroll") for (int k = 0; k < 2; ++k) dst[m][k] = *(const LAS bf16x8*)(lds + PG8_SA(b, h) + aoff + m * 2048 + k * 1024); } while (0)
; #define PG8_MMA(ai, bj, At, Bt) do { __builtin_amdgcn_s_setprio(1); _Pragma("unroll") for (int m = 0; m < 4; ++m) _Pragma("unroll") for (int n = 0; n < 2; ++n) _Pragma("unroll") for (int k = 0; k < 2; ++k) \
;         acc[ai][bj][m][n] = __builtin_amdgcn_mfma_f32_16x16x32_bf16(Bt[n][k], At[m][k], acc[ai][bj][m][n], 0, 0, 0); __builtin_amdgcn_s_setprio(0); } while (0)
; #define PG8_WAIT_V(n) asm volatile("s_waitcnt vmcnt(" #n ")" ::: "memory")
; #define PG8_WAIT_L(n) asm volatile("s_waitcnt lgkmcnt(" #n ")" ::: "memory")
; #define PG8_BAR __builtin_amdgcn_s_barrier()
; #define PG8_SCHED __builtin_amdgcn_sched_barrier(0)
; template <class Epi>
; DI void gemm_phase(LAS unsigned char* lds, const int wid, const Gemm g, const Order& S, const Epi& E) {
;     ...
;         for (int t = 0; t < nt; t += 2) {
;     ...
;             PG8_LDA(At, 1, 1); PG8_STAGE(PG8_SB(1, 0), b3, voffB); PG8_STAGE(PG8_SB(1, 1), b3 + hstepB, voffB); PG8_STAGE(PG8_SA(1, 0), a3, voffA);
;             PG8_WAIT_V(8); PG8_WAIT_L(0); PG8_BAR; PG8_MMA(1, 0, At, B0); PG8_MMA(1, 1, At, B1); PG8_BAR; PG8_SCHED;
	s_add_i32 s44, s59, s94
	v_lshl_add_u64 v[212:213], v[212:213], 0, s[16:17]
	s_mov_b32 m0, s44
	ds_read_b128 v[180:183], v167 offset:49152
	ds_read_b128 v[184:187], v167 offset:50176
	ds_read_b128 v[188:191], v167 offset:51200
	ds_read_b128 v[192:195], v167 offset:52224
	ds_read_b128 v[196:199], v167 offset:53248
	ds_read_b128 v[200:203], v167 offset:54272
	ds_read_b128 v[204:207], v167 offset:55296
	ds_read_b128 v[208:211], v167 offset:56320
	global_load_lds_dwordx4 v[212:213], off
	s_add_i32 m0, s44, 0x2000
	s_add_u32 s42, s42, 0x20080
	v_lshl_add_u64 v[212:213], v[214:215], 0, s[16:17]
	s_addc_u32 s43, s43, 0
	s_add_i32 s44, s60, s94
	global_load_lds_dwordx4 v[212:213], off
	v_lshl_add_u64 v[212:213], s[42:43], 0, v[146:147]
	s_mov_b32 m0, s44
	s_nop 0
	global_load_lds_dwordx4 v[212:213], off
	v_lshl_add_u64 v[212:213], s[42:43], 0, v[150:151]
	s_add_i32 m0, s44, 0x2000
	s_nop 0
	global_load_lds_dwordx4 v[212:213], off
	v_lshl_add_u64 v[212:213], v[216:217], 0, s[16:17]
	s_mov_b32 m0, s49
	s_nop 0
	global_load_lds_dwordx4 v[212:213], off
	v_lshl_add_u64 v[212:213], v[218:219], 0, s[16:17]
	s_mov_b32 m0, s50
	s_nop 0
	global_load_lds_dwordx4 v[212:213], off
	s_waitcnt vmcnt(8)
	s_waitcnt lgkmcnt(0)
	s_barrier
	s_setprio 1
	v_mfma_f32_16x16x32_bf16 v[60:63], v[128:131], v[180:183], v[60:63]
	v_mfma_f32_16x16x32_bf16 v[56:59], v[136:139], v[180:183], v[56:59]
	v_mfma_f32_16x16x32_bf16 v[44:47], v[128:131], v[188:191], v[44:47]
	v_mfma_f32_16x16x32_bf16 v[40:43], v[136:139], v[188:191], v[40:43]
	v_mfma_f32_16x16x32_bf16 v[28:31], v[128:131], v[196:199], v[28:31]
	v_mfma_f32_16x16x32_bf16 v[24:27], v[136:139], v[196:199], v[24:27]
	v_mfma_f32_16x16x32_bf16 v[12:15], v[128:131], v[204:207], v[12:15]
	v_mfma_f32_16x16x32_bf16 v[8:11], v[136:139], v[204:207], v[8:11]
	v_mfma_f32_16x16x32_bf16 v[60:63], v[132:135], v[184:187], v[60:63]
	v_mfma_f32_16x16x32_bf16 v[56:59], v[140:143], v[184:187], v[56:59]
	v_mfma_f32_16x16x32_bf16 v[44:47], v[132:135], v[192:195], v[44:47]
	v_mfma_f32_16x16x32_bf16 v[40:43], v[140:143], v[192:195], v[40:43]
	v_mfma_f32_16x16x32_bf16 v[28:31], v[132:135], v[200:203], v[28:31]
	v_mfma_f32_16x16x32_bf16 v[24:27], v[140:143], v[200:203], v[24:27]
	v_mfma_f32_16x16x32_bf16 v[12:15], v[132:135], v[208:211], v[12:15]
	v_mfma_f32_16x16x32_bf16 v[8:11], v[140:143], v[208:211], v[8:11]
	v_mfma_f32_16x16x32_bf16 v[52:55], v[160:163], v[180:183], v[52:55]
	v_mfma_f32_16x16x32_bf16 v[48:51], v[172:175], v[180:183], v[48:51]
	v_mfma_f32_16x16x32_bf16 v[36:39], v[160:163], v[188:191], v[36:39]
	v_mfma_f32_16x16x32_bf16 v[32:35], v[172:175], v[188:191], v[32:35]
	v_mfma_f32_16x16x32_bf16 v[20:23], v[160:163], v[196:199], v[20:23]
	v_mfma_f32_16x16x32_bf16 v[16:19], v[172:175], v[196:199], v[16:19]
	v_mfma_f32_16x16x32_bf16 v[4:7], v[160:163], v[204:207], v[4:7]
	v_mfma_f32_16x16x32_bf16 v[0:3], v[172:175], v[204:207], v[0:3]
	v_mfma_f32_16x16x32_bf16 v[52:55], v[168:171], v[184:187], v[52:55]
	v_mfma_f32_16x16x32_bf16 v[48:51], v[176:179], v[184:187], v[48:51]
	v_mfma_f32_16x16x32_bf16 v[36:39], v[168:171], v[192:195], v[36:39]
	v_mfma_f32_16x16x32_bf16 v[32:35], v[176:179], v[192:195], v[32:35]
	v_mfma_f32_16x16x32_bf16 v[20:23], v[168:171], v[200:203], v[20:23]
	v_mfma_f32_16x16x32_bf16 v[16:19], v[176:179], v[200:203], v[16:19]
	v_mfma_f32_16x16x32_bf16 v[4:7], v[168:171], v[208:211], v[4:7]
	v_mfma_f32_16x16x32_bf16 v[0:3], v[176:179], v[208:211], v[0:3]
	s_setprio 0
	s_barrier
	s_add_i32 s58, s58, 2
	s_add_u32 s40, s40, 0x100
	s_addc_u32 s41, s41, 0
	s_add_u32 s56, s56, 0x100
	s_addc_u32 s57, s57, 0
	s_cmp_gt_u32 s58, 5
	s_cbranch_scc0 .LBB0_1091

; #define PG8_STAGE(bufoff, gbase, voff) do { _Pragma("unroll") for (int _i = 0; _i < 2; ++_i) \
;         __builtin_amdgcn_global_load_lds((const unsigned*)((const char*)(gbase) + (voff)[_i]), (LAS unsigned*)(lds + (bufoff) + ldsw + _i * 8192), 16, 0, 0); } while (0)
; #define PG8_LDA(dst, b, h) do { _Pragma("unroll") for (int m = 0; m < 4; ++m) _Pragma("unroll") for (int k = 0; k < 2; ++k) dst[m][k] = *(const LAS bf16x8*)(lds + PG8_SA(b, h) + aoff + m * 2048 + k * 1024); } while (0)
; #define PG8_LDB(dst, b, h) do { _Pragma("unroll") for (int n = 0; n < 2; ++n) _Pragma("unroll") for (int k = 0; k < 2; ++k) dst[n][k] = *(const LAS bf16x8*)(lds + PG8_SB(b, h) + boff + n * 2048 + k * 1024); } while (0)
; #define PG8_MMA(ai, bj, At, Bt) do { __builtin_amdgcn_s_setprio(1); _Pragma("unroll") for (int m = 0; m < 4; ++m) _Pragma("unroll") for (int n = 0; n < 2; ++n) _Pragma("unroll") for (int k = 0; k < 2; ++k) \
;         acc[ai][bj][m][n] = __builtin_amdgcn_mfma_f32_16x16x32_bf16(Bt[n][k], At[m][k], acc[ai][bj][m][n], 0, 0, 0); __builtin_amdgcn_s_setprio(0); } while (0)
; template <class Epi>
; DI void gemm_phase(LAS unsigned char* lds, const int wid, const Gemm g, const Order& S, const Epi& E) {
;     ...
;         const bool has_next = S.next(ui + 1, nxt);
;         const char* nA = has_next ? (const char*)(g.A + (size_t)nxt.g * g.gsA + (size_t)nxt.pm * BM * g.lda) : cA;
;         const char* nB = has_next ? (const char*)(g.Bt + (size_t)nxt.g * g.gsB + (size_t)nxt.pn * BM * g.ldb) : cB;
;         for (int t = 0; t < nt; t += 2) {
;             const bool last = (t == nt - 2);
;             const char* a1 = cA + (size_t)(t + 1) * kstep;
;             const char* a2 = last ? nA : cA + (size_t)(t + 2) * kstep; const char* b2 = last ? nB : cB + (size_t)(t + 2) * kstep;
;             const char* a3 = a2 + kstep; const char* b3 = b2 + kstep;
;             PG8_LDB(B0, 0, 0); PG8_LDB(B1, 0, 1); PG8_SCHED; PG8_LDA(At, 0, 0); PG8_STAGE(PG8_SA(1, 1), a1 + hstepA, voffA);
;             PG8_WAIT_V(8); PG8_WAIT_L(0); PG8_BAR; PG8_MMA(0, 0, At, B0); PG8_MMA(0, 1, At, B1); PG8_BAR; PG8_SCHED;
;             PG8_LDA(At, 0, 1); PG8_STAGE(PG8_SB(0, 0), b2, voffB); PG8_STAGE(PG8_SB(0, 1), b2 + hstepB, voffB); PG8_STAGE(PG8_SA(0, 0), a2, voffA);
;             PG8_WAIT_V(8); PG8_WAIT_L(0); PG8_BAR; PG8_MMA(1, 0, At, B0); PG8_MMA(1, 1, At, B1); PG8_BAR; PG8_SCHED;
.LBB0_1169:
	s_ashr_i32 s31, s30, 31
	s_lshl_b64 s[36:37], s[30:31], 18
	s_add_u32 s36, s6, s36
	s_addc_u32 s37, s7, s37
	s_and_b64 s[38:39], s[8:9], exec
	s_cselect_b32 s31, s37, s43
	s_cselect_b32 s56, s36, s42
	s_ashr_i32 s35, s34, 31
	s_lshl_b64 s[38:39], s[34:35], 18
	s_add_u32 s38, s21, s38
	s_addc_u32 s39, s24, s39
	s_and_b64 s[46:47], s[8:9], exec
	s_cselect_b32 s35, s39, s45
	s_cselect_b32 s57, s38, s44
	s_add_u32 s42, s42, 0x20080
	s_addc_u32 s43, s43, 0
	s_add_u32 s58, s44, 0x100
	v_mov_b32_e32 v0, 0
	s_addc_u32 s59, s45, 0
	s_mov_b32 s60, -2
	ds_read_b128 v[128:131], v183
	ds_read_b128 v[132:135], v183 offset:1024
	ds_read_b128 v[136:139], v183 offset:2048
	ds_read_b128 v[140:143], v183 offset:3072
	ds_read_b128 v[144:147], v184
	ds_read_b128 v[148:151], v184 offset:1024
	ds_read_b128 v[152:155], v184 offset:2048
	ds_read_b128 v[172:175], v184 offset:3072
	s_add_u32 s44, s42, 0xfffe0080
	s_addc_u32 s45, s43, -1
	s_cmp_eq_u32 s60, 4
	s_cselect_b32 s47, s31, s45
	s_cselect_b32 s46, s56, s44
	s_cselect_b32 s45, s35, s59
	s_cselect_b32 s44, s57, s58
	v_lshl_add_u64 v[180:181], s[42:43], 0, v[164:165]
	s_add_i32 m0, s25, 0xc000
	ds_read_b128 v[176:179], v185
	ds_read_b128 v[186:189], v185 offset:1024
	ds_read_b128 v[190:193], v185 offset:2048
	ds_read_b128 v[194:197], v185 offset:3072
	ds_read_b128 v[198:201], v185 offset:4096
	ds_read_b128 v[202:205], v185 offset:5120
	ds_read_b128 v[206:209], v185 offset:6144
	ds_read_b128 v[210:213], v185 offset:7168
	global_load_lds_dwordx4 v[180:181], off
	v_lshl_add_u64 v[180:181], s[42:43], 0, v[166:167]
	s_add_i32 m0, s25, 0xe000
	s_nop 0
	global_load_lds_dwordx4 v[180:181], off
	s_waitcnt vmcnt(8)
	s_waitcnt lgkmcnt(0)
	s_barrier
	s_setprio 1
	v_mfma_f32_16x16x32_bf16 v[124:127], v[128:131], v[176:179], 0
	v_mfma_f32_16x16x32_bf16 v[120:123], v[136:139], v[176:179], 0
	v_mfma_f32_16x16x32_bf16 v[108:111], v[128:131], v[190:193], 0
	v_mfma_f32_16x16x32_bf16 v[104:107], v[136:139], v[190:193], 0
	v_mfma_f32_16x16x32_bf16 v[92:95], v[128:131], v[198:201], 0
	v_mfma_f32_16x16x32_bf16 v[88:91], v[136:139], v[198:201], 0
	v_mfma_f32_16x16x32_bf16 v[76:79], v[128:131], v[206:209], 0
	v_mfma_f32_16x16x32_bf16 v[72:75], v[136:139], v[206:209], 0
	v_mfma_f32_16x16x32_bf16 v[124:127], v[132:135], v[186:189], v[124:127]
	v_mfma_f32_16x16x32_bf16 v[120:123], v[140:143], v[186:189], v[120:123]
	v_mfma_f32_16x16x32_bf16 v[108:111], v[132:135], v[194:197], v[108:111]
	v_mfma_f32_16x16x32_bf16 v[104:107], v[140:143], v[194:197], v[104:107]
	v_mfma_f32_16x16x32_bf16 v[92:95], v[132:135], v[202:205], v[92:95]
	v_mfma_f32_16x16x32_bf16 v[88:91], v[140:143], v[202:205], v[88:91]
	v_mfma_f32_16x16x32_bf16 v[76:79], v[132:135], v[210:213], v[76:79]
	v_mfma_f32_16x16x32_bf16 v[72:75], v[140:143], v[210:213], v[72:75]
	v_mfma_f32_16x16x32_bf16 v[116:119], v[144:147], v[176:179], 0
	v_mfma_f32_16x16x32_bf16 v[112:115], v[152:155], v[176:179], 0
	v_mfma_f32_16x16x32_bf16 v[100:103], v[144:147], v[190:193], 0
	v_mfma_f32_16x16x32_bf16 v[96:99], v[152:155], v[190:193], 0
	v_mfma_f32_16x16x32_bf16 v[84:87], v[144:147], v[198:201], 0
	v_mfma_f32_16x16x32_bf16 v[80:83], v[152:155], v[198:201], 0
	v_mfma_f32_16x16x32_bf16 v[68:71], v[144:147], v[206:209], 0
	v_mfma_f32_16x16x32_bf16 v[64:67], v[152:155], v[206:209], 0
	v_mfma_f32_16x16x32_bf16 v[116:119], v[148:151], v[186:189], v[116:119]
	v_mfma_f32_16x16x32_bf16 v[112:115], v[172:175], v[186:189], v[112:115]
	v_mfma_f32_16x16x32_bf16 v[100:103], v[148:151], v[194:197], v[100:103]
	v_mfma_f32_16x16x32_bf16 v[96:99], v[172:175], v[194:197], v[96:99]
	v_mfma_f32_16x16x32_bf16 v[84:87], v[148:151], v[202:205], v[84:87]
	v_mfma_f32_16x16x32_bf16 v[80:83], v[172:175], v[202:205], v[80:83]
	v_mfma_f32_16x16x32_bf16 v[68:71], v[148:151], v[210:213], v[68:71]
	v_mfma_f32_16x16x32_bf16 v[64:67], v[172:175], v[210:213], v[64:67]
	s_setprio 0
	s_barrier
	s_add_i32 s61, s53, s94
	v_lshl_add_u64 v[180:181], s[44:45], 0, v[158:159]
	s_mov_b32 m0, s61
	ds_read_b128 v[176:179], v185 offset:16384
	ds_read_b128 v[186:189], v185 offset:17408
	ds_read_b128 v[190:193], v185 offset:18432
	ds_read_b128 v[194:197], v185 offset:19456
	ds_read_b128 v[198:201], v185 offset:20480
	ds_read_b128 v[202:205], v185 offset:21504
	ds_read_b128 v[206:209], v185 offset:22528
	ds_read_b128 v[210:213], v185 offset:23552
	global_load_lds_dwordx4 v[180:181], off
	s_add_i32 m0, s61, 0x2000
	s_add_u32 s62, s44, 0x20000
	v_lshl_add_u64 v[214:215], s[44:45], 0, v[162:163]
	s_addc_u32 s63, s45, 0
	s_add_i32 s61, s54, s94
	global_load_lds_dwordx4 v[214:215], off
	v_lshl_add_u64 v[216:217], s[62:63], 0, v[158:159]
	s_mov_b32 m0, s61
	v_lshl_add_u64 v[218:219], s[46:47], 0, v[160:161]
	global_load_lds_dwordx4 v[216:217], off
	v_lshl_add_u64 v[216:217], s[62:63], 0, v[162:163]
	s_add_i32 m0, s61, 0x2000
	s_nop 0
	global_load_lds_dwordx4 v[216:217], off
	v_lshl_add_u64 v[216:217], s[46:47], 0, v[156:157]
	s_mov_b32 m0, s25
	s_nop 0
	global_load_lds_dwordx4 v[216:217], off
	s_mov_b32 m0, s41
	s_nop 0
	global_load_lds_dwordx4 v[218:219], off
	s_waitcnt vmcnt(8)
	s_waitcnt lgkmcnt(0)
	s_barrier
; #define PG8_STAGE(bufoff, gbase, voff) do { _Pragma("unroll") for (int _i = 0; _i < 2; ++_i) \
;         __builtin_amdgcn_global_load_lds((const unsigned*)((const char*)(gbase) + (voff)[_i]), (LAS unsigned*)(lds + (bufoff) + ldsw + _i * 8192), 16, 0, 0); } while (0)
; #define PG8_LDA(dst, b, h) do { _Pragma("unroll") for (int m = 0; m < 4; ++m) _Pragma("unroll") for (int k = 0; k < 2; ++k) dst[m][k] = *(const LAS bf16x8*)(lds + PG8_SA(b, h) + aoff + m * 2048 + k * 1024); } while (0)
; #define PG8_LDB(dst, b, h) do { _Pragma("unroll") for (int n = 0; n < 2; ++n) _Pragma("unroll") for (int k = 0; k < 2; ++k) dst[n][k] = *(const LAS bf16x8*)(lds + PG8_SB(b, h) + boff + n * 2048 + k * 1024); } while (0)
; #define PG8_MMA(ai, bj, At, Bt) do { __builtin_amdgcn_s_setprio(1); _Pragma("unroll") for (int m = 0; m < 4; ++m) _Pragma("unroll") for (int n = 0; n < 2; ++n) _Pragma("unroll") for (int k = 0; k < 2; ++k) \
;         acc[ai][bj][m][n] = __builtin_amdgcn_mfma_f32_16x16x32_bf16(Bt[n][k], At[m][k], acc[ai][bj][m][n], 0, 0, 0); __builtin_amdgcn_s_setprio(0); } while (0)
; #define PG8_WAIT_V(n) asm volatile("s_waitcnt vmcnt(" #n ")" ::: "memory")
; #define PG8_WAIT_L(n) asm volatile("s_waitcnt lgkmcnt(" #n ")" ::: "memory")
; #define PG8_BAR __builtin_amdgcn_s_barrier()
; #define PG8_SCHED __builtin_amdgcn_sched_barrier(0)
; template <class Epi>
; DI void gemm_phase(LAS unsigned char* lds, const int wid, const Gemm g, const Order& S, const Epi& E) {
;     ...
;             PG8_WAIT_V(8); PG8_WAIT_L(0); PG8_BAR; PG8_MMA(1, 0, At, B0); PG8_MMA(1, 1, At, B1); PG8_BAR; PG8_SCHED;
;             PG8_LDB(B0, 1, 0); PG8_LDB(B1, 1, 1); PG8_SCHED; PG8_LDA(At, 1, 0); PG8_STAGE(PG8_SA(0, 1), a2 + hstepA, voffA);
;             PG8_WAIT_V(8); PG8_WAIT_L(0); PG8_BAR; PG8_MMA(0, 0, At, B0); PG8_MMA(0, 1, At, B1); PG8_BAR; PG8_SCHED;
	s_setprio 1
	v_mfma_f32_16x16x32_bf16 v[60:63], v[128:131], v[176:179], 0
	v_mfma_f32_16x16x32_bf16 v[56:59], v[136:139], v[176:179], 0
	v_mfma_f32_16x16x32_bf16 v[44:47], v[128:131], v[190:193], 0
	v_mfma_f32_16x16x32_bf16 v[40:43], v[136:139], v[190:193], 0
	v_mfma_f32_16x16x32_bf16 v[28:31], v[128:131], v[198:201], 0
	v_mfma_f32_16x16x32_bf16 v[24:27], v[136:139], v[198:201], 0
	v_mfma_f32_16x16x32_bf16 v[12:15], v[128:131], v[206:209], 0
	v_mfma_f32_16x16x32_bf16 v[8:11], v[136:139], v[206:209], 0
	v_mfma_f32_16x16x32_bf16 v[60:63], v[132:135], v[186:189], v[60:63]
	v_mfma_f32_16x16x32_bf16 v[56:59], v[140:143], v[186:189], v[56:59]
	v_mfma_f32_16x16x32_bf16 v[44:47], v[132:135], v[194:197], v[44:47]
	v_mfma_f32_16x16x32_bf16 v[40:43], v[140:143], v[194:197], v[40:43]
	v_mfma_f32_16x16x32_bf16 v[28:31], v[132:135], v[202:205], v[28:31]
	v_mfma_f32_16x16x32_bf16 v[24:27], v[140:143], v[202:205], v[24:27]
	v_mfma_f32_16x16x32_bf16 v[12:15], v[132:135], v[210:213], v[12:15]
	v_mfma_f32_16x16x32_bf16 v[8:11], v[140:143], v[210:213], v[8:11]
	v_mfma_f32_16x16x32_bf16 v[52:55], v[144:147], v[176:179], 0
	v_mfma_f32_16x16x32_bf16 v[48:51], v[152:155], v[176:179], 0
	v_mfma_f32_16x16x32_bf16 v[36:39], v[144:147], v[190:193], 0
	v_mfma_f32_16x16x32_bf16 v[32:35], v[152:155], v[190:193], 0
	v_mfma_f32_16x16x32_bf16 v[20:23], v[144:147], v[198:201], 0
	v_mfma_f32_16x16x32_bf16 v[16:19], v[152:155], v[198:201], 0
	v_mfma_f32_16x16x32_bf16 v[4:7], v[144:147], v[206:209], 0
	v_mfma_f32_16x16x32_bf16 v[0:3], v[152:155], v[206:209], 0
	v_mfma_f32_16x16x32_bf16 v[52:55], v[148:151], v[186:189], v[52:55]
	v_mfma_f32_16x16x32_bf16 v[48:51], v[172:175], v[186:189], v[48:51]
	v_mfma_f32_16x16x32_bf16 v[36:39], v[148:151], v[194:197], v[36:39]
	v_mfma_f32_16x16x32_bf16 v[32:35], v[172:175], v[194:197], v[32:35]
	v_mfma_f32_16x16x32_bf16 v[20:23], v[148:151], v[202:205], v[20:23]
	v_mfma_f32_16x16x32_bf16 v[16:19], v[172:175], v[202:205], v[16:19]
	v_mfma_f32_16x16x32_bf16 v[4:7], v[148:151], v[210:213], v[4:7]
	v_mfma_f32_16x16x32_bf16 v[0:3], v[172:175], v[210:213], v[0:3]
	s_setprio 0
	s_barrier
	s_add_i32 s61, 0, 0x18000
	s_add_i32 s62, 0, 0x1c000
	v_add_u32_e32 v140, s61, v182
	v_add_u32_e32 v172, s62, v182
	ds_read_b128 v[128:131], v140
	ds_read_b128 v[132:135], v140 offset:1024
	ds_read_b128 v[136:139], v140 offset:2048
	ds_read_b128 v[140:143], v140 offset:3072
	ds_read_b128 v[144:147], v172
	ds_read_b128 v[148:151], v172 offset:1024
	ds_read_b128 v[152:155], v172 offset:2048
	ds_read_b128 v[172:175], v172 offset:3072
	s_add_u32 s46, s46, 0x20000
	s_addc_u32 s47, s47, 0
	s_mov_b32 m0, s48
	v_lshl_add_u64 v[220:221], s[46:47], 0, v[156:157]
	ds_read_b128 v[176:179], v185 offset:32768
	ds_read_b128 v[186:189], v185 offset:33792
	ds_read_b128 v[190:193], v185 offset:34816
	ds_read_b128 v[194:197], v185 offset:35840
	ds_read_b128 v[198:201], v185 offset:36864
	ds_read_b128 v[202:205], v185 offset:37888
	ds_read_b128 v[206:209], v185 offset:38912
	ds_read_b128 v[210:213], v185 offset:39936
	global_load_lds_dwordx4 v[220:221], off
	v_lshl_add_u64 v[220:221], s[46:47], 0, v[160:161]
	s_mov_b32 m0, s49
	s_nop 0
	global_load_lds_dwordx4 v[220:221], off
	s_waitcnt vmcnt(8)
	s_waitcnt lgkmcnt(0)
	s_barrier
	s_setprio 1
	v_mfma_f32_16x16x32_bf16 v[124:127], v[128:131], v[176:179], v[124:127]
	v_mfma_f32_16x16x32_bf16 v[120:123], v[136:139], v[176:179], v[120:123]
	v_mfma_f32_16x16x32_bf16 v[108:111], v[128:131], v[190:193], v[108:111]
	v_mfma_f32_16x16x32_bf16 v[104:107], v[136:139], v[190:193], v[104:107]
	v_mfma_f32_16x16x32_bf16 v[92:95], v[128:131], v[198:201], v[92:95]
	v_mfma_f32_16x16x32_bf16 v[88:91], v[136:139], v[198:201], v[88:91]
	v_mfma_f32_16x16x32_bf16 v[76:79], v[128:131], v[206:209], v[76:79]
	v_mfma_f32_16x16x32_bf16 v[72:75], v[136:139], v[206:209], v[72:75]
	v_mfma_f32_16x16x32_bf16 v[124:127], v[132:135], v[186:189], v[124:127]
	v_mfma_f32_16x16x32_bf16 v[120:123], v[140:143], v[186:189], v[120:123]
	v_mfma_f32_16x16x32_bf16 v[108:111], v[132:135], v[194:197], v[108:111]
	v_mfma_f32_16x16x32_bf16 v[104:107], v[140:143], v[194:197], v[104:107]
	v_mfma_f32_16x16x32_bf16 v[92:95], v[132:135], v[202:205], v[92:95]
	v_mfma_f32_16x16x32_bf16 v[88:91], v[140:143], v[202:205], v[88:91]
	v_mfma_f32_16x16x32_bf16 v[76:79], v[132:135], v[210:213], v[76:79]
	v_mfma_f32_16x16x32_bf16 v[72:75], v[140:143], v[210:213], v[72:75]
	v_mfma_f32_16x16x32_bf16 v[116:119], v[144:147], v[176:179], v[116:119]
	v_mfma_f32_16x16x32_bf16 v[112:115], v[152:155], v[176:179], v[112:115]
	v_mfma_f32_16x16x32_bf16 v[100:103], v[144:147], v[190:193], v[100:103]
	v_mfma_f32_16x16x32_bf16 v[96:99], v[152:155], v[190:193], v[96:99]
	v_mfma_f32_16x16x32_bf16 v[84:87], v[144:147], v[198:201], v[84:87]
	v_mfma_f32_16x16x32_bf16 v[80:83], v[152:155], v[198:201], v[80:83]
	v_mfma_f32_16x16x32_bf16 v[68:71], v[144:147], v[206:209], v[68:71]
	v_mfma_f32_16x16x32_bf16 v[64:67], v[152:155], v[206:209], v[64:67]
	v_mfma_f32_16x16x32_bf16 v[116:119], v[148:151], v[186:189], v[116:119]
	v_mfma_f32_16x16x32_bf16 v[112:115], v[172:175], v[186:189], v[112:115]
	v_mfma_f32_16x16x32_bf16 v[100:103], v[148:151], v[194:197], v[100:103]
	v_mfma_f32_16x16x32_bf16 v[96:99], v[172:175], v[194:197], v[96:99]
	v_mfma_f32_16x16x32_bf16 v[84:87], v[148:151], v[202:205], v[84:87]
	v_mfma_f32_16x16x32_bf16 v[80:83], v[172:175], v[202:205], v[80:83]
	v_mfma_f32_16x16x32_bf16 v[68:71], v[148:151], v[210:213], v[68:71]
	v_mfma_f32_16x16x32_bf16 v[64:67], v[172:175], v[210:213], v[64:67]
	s_setprio 0
	s_barrier
; #define PG8_STAGE(bufoff, gbase, voff) do { _Pragma("unroll") for (int _i = 0; _i < 2; ++_i) \
;         __builtin_amdgcn_global_load_lds((const unsigned*)((const char*)(gbase) + (voff)[_i]), (LAS unsigned*)(lds + (bufoff) + ldsw + _i * 8192), 16, 0, 0); } while (0)
; #define PG8_LDA(dst, b, h) do { _Pragma("unroll") for (int m = 0; m < 4; ++m) _Pragma("unroll") for (int k = 0; k < 2; ++k) dst[m][k] = *(const LAS bf16x8*)(lds + PG8_SA(b, h) + aoff + m * 2048 + k * 1024); } while (0)
; #define PG8_LDB(dst, b, h) do { _Pragma("unroll") for (int n = 0; n < 2; ++n) _Pragma("unroll") for (int k = 0; k < 2; ++k) dst[n][k] = *(const LAS bf16x8*)(lds + PG8_SB(b, h) + boff + n * 2048 + k * 1024); } while (0)
; #define PG8_WAIT_V(n) asm volatile("s_waitcnt vmcnt(" #n ")" ::: "memory")
; #define PG8_WAIT_L(n) asm volatile("s_waitcnt lgkmcnt(" #n ")" ::: "memory")
; template <class Epi>
; DI void gemm_phase(LAS unsigned char* lds, const int wid, const Gemm g, const Order& S, const Epi& E) {
;     ...
;         for (int t = 0; t < nt; t += 2) {
;             const bool last = (t == nt - 2);
;             const char* a1 = cA + (size_t)(t + 1) * kstep;
;             const char* a2 = last ? nA : cA + (size_t)(t + 2) * kstep; const char* b2 = last ? nB : cB + (size_t)(t + 2) * kstep;
;             const char* a3 = a2 + kstep; const char* b3 = b2 + kstep;
;             PG8_LDB(B0, 0, 0); PG8_LDB(B1, 0, 1); PG8_SCHED; PG8_LDA(At, 0, 0); PG8_STAGE(PG8_SA(1, 1), a1 + hstepA, voffA);
;             PG8_WAIT_V(8); PG8_WAIT_L(0); PG8_BAR; PG8_MMA(0, 0, At, B0); PG8_MMA(0, 1, At, B1); PG8_BAR; PG8_SCHED;
;             PG8_LDA(At, 0, 1); PG8_STAGE(PG8_SB(0, 0), b2, voffB); PG8_STAGE(PG8_SB(0, 1), b2 + hstepB, voffB); PG8_STAGE(PG8_SA(0, 0), a2, voffA);
;             PG8_WAIT_V(8); PG8_WAIT_L(0); PG8_BAR; PG8_MMA(1, 0, At, B0); PG8_MMA(1, 1, At, B1); PG8_BAR; PG8_SCHED;
;             PG8_LDB(B0, 1, 0); PG8_LDB(B1, 1, 1); PG8_SCHED; PG8_LDA(At, 1, 0); PG8_STAGE(PG8_SA(0, 1), a2 + hstepA, voffA);
;             PG8_WAIT_V(8); PG8_WAIT_L(0); PG8_BAR; PG8_MMA(0, 0, At, B0); PG8_MMA(0, 1, At, B1); PG8_BAR; PG8_SCHED;
;             PG8_LDA(At, 1, 1); PG8_STAGE(PG8_SB(1, 0), b3, voffB); PG8_STAGE(PG8_SB(1, 1), b3 + hstepB, voffB); PG8_STAGE(PG8_SA(1, 0), a3, voffA);
;             PG8_WAIT_V(8); PG8_WAIT_L(0); PG8_BAR; PG8_MMA(1, 0, At, B0); PG8_MMA(1, 1, At, B1); PG8_BAR; PG8_SCHED;
	s_add_i32 s46, s61, s94
	v_lshl_add_u64 v[180:181], v[180:181], 0, s[26:27]
	s_mov_b32 m0, s46
	ds_read_b128 v[176:179], v185 offset:49152
	ds_read_b128 v[186:189], v185 offset:50176
	ds_read_b128 v[190:193], v185 offset:51200
	ds_read_b128 v[194:197], v185 offset:52224
	ds_read_b128 v[198:201], v185 offset:53248
	ds_read_b128 v[202:205], v185 offset:54272
	ds_read_b128 v[206:209], v185 offset:55296
	ds_read_b128 v[210:213], v185 offset:56320
	global_load_lds_dwordx4 v[180:181], off
	s_add_i32 m0, s46, 0x2000
	s_add_u32 s44, s44, 0x20080
	v_lshl_add_u64 v[180:181], v[214:215], 0, s[26:27]
	s_addc_u32 s45, s45, 0
	s_add_i32 s46, s62, s94
	global_load_lds_dwordx4 v[180:181], off
	v_lshl_add_u64 v[180:181], s[44:45], 0, v[158:159]
	s_mov_b32 m0, s46
	s_nop 0
	global_load_lds_dwordx4 v[180:181], off
	v_lshl_add_u64 v[180:181], s[44:45], 0, v[162:163]
	s_add_i32 m0, s46, 0x2000
	s_nop 0
	global_load_lds_dwordx4 v[180:181], off
	v_lshl_add_u64 v[180:181], v[216:217], 0, s[26:27]
	s_mov_b32 m0, s51
	s_nop 0
	global_load_lds_dwordx4 v[180:181], off
	v_lshl_add_u64 v[180:181], v[218:219], 0, s[26:27]
	s_mov_b32 m0, s52
	s_nop 0
	global_load_lds_dwordx4 v[180:181], off
	s_waitcnt vmcnt(8)
	s_waitcnt lgkmcnt(0)
	s_barrier
	s_setprio 1
	v_mfma_f32_16x16x32_bf16 v[60:63], v[128:131], v[176:179], v[60:63]
	v_mfma_f32_16x16x32_bf16 v[56:59], v[136:139], v[176:179], v[56:59]
	v_mfma_f32_16x16x32_bf16 v[44:47], v[128:131], v[190:193], v[44:47]
	v_mfma_f32_16x16x32_bf16 v[40:43], v[136:139], v[190:193], v[40:43]
	v_mfma_f32_16x16x32_bf16 v[28:31], v[128:131], v[198:201], v[28:31]
	v_mfma_f32_16x16x32_bf16 v[24:27], v[136:139], v[198:201], v[24:27]
	v_mfma_f32_16x16x32_bf16 v[12:15], v[128:131], v[206:209], v[12:15]
	v_mfma_f32_16x16x32_bf16 v[8:11], v[136:139], v[206:209], v[8:11]
	v_mfma_f32_16x16x32_bf16 v[60:63], v[132:135], v[186:189], v[60:63]
	v_mfma_f32_16x16x32_bf16 v[56:59], v[140:143], v[186:189], v[56:59]
	v_mfma_f32_16x16x32_bf16 v[44:47], v[132:135], v[194:197], v[44:47]
	v_mfma_f32_16x16x32_bf16 v[40:43], v[140:143], v[194:197], v[40:43]
	v_mfma_f32_16x16x32_bf16 v[28:31], v[132:135], v[202:205], v[28:31]
	v_mfma_f32_16x16x32_bf16 v[24:27], v[140:143], v[202:205], v[24:27]
	v_mfma_f32_16x16x32_bf16 v[12:15], v[132:135], v[210:213], v[12:15]
	v_mfma_f32_16x16x32_bf16 v[8:11], v[140:143], v[210:213], v[8:11]
	v_mfma_f32_16x16x32_bf16 v[52:55], v[144:147], v[176:179], v[52:55]
	v_mfma_f32_16x16x32_bf16 v[48:51], v[152:155], v[176:179], v[48:51]
	v_mfma_f32_16x16x32_bf16 v[36:39], v[144:147], v[190:193], v[36:39]
	v_mfma_f32_16x16x32_bf16 v[32:35], v[152:155], v[190:193], v[32:35]
	v_mfma_f32_16x16x32_bf16 v[20:23], v[144:147], v[198:201], v[20:23]
	v_mfma_f32_16x16x32_bf16 v[16:19], v[152:155], v[198:201], v[16:19]
	v_mfma_f32_16x16x32_bf16 v[4:7], v[144:147], v[206:209], v[4:7]
	v_mfma_f32_16x16x32_bf16 v[0:3], v[152:155], v[206:209], v[0:3]
	v_mfma_f32_16x16x32_bf16 v[52:55], v[148:151], v[186:189], v[52:55]
	v_mfma_f32_16x16x32_bf16 v[48:51], v[172:175], v[186:189], v[48:51]
	v_mfma_f32_16x16x32_bf16 v[36:39], v[148:151], v[194:197], v[36:39]
	v_mfma_f32_16x16x32_bf16 v[32:35], v[172:175], v[194:197], v[32:35]
	v_mfma_f32_16x16x32_bf16 v[20:23], v[148:151], v[202:205], v[20:23]
	v_mfma_f32_16x16x32_bf16 v[16:19], v[172:175], v[202:205], v[16:19]
	v_mfma_f32_16x16x32_bf16 v[4:7], v[148:151], v[210:213], v[4:7]
	v_mfma_f32_16x16x32_bf16 v[0:3], v[172:175], v[210:213], v[0:3]
	s_setprio 0
	s_barrier
	s_add_i32 s60, s60, 2
	s_add_u32 s42, s42, 0x100
	s_addc_u32 s43, s43, 0
	s_add_u32 s58, s58, 0x100
	s_addc_u32 s59, s59, 0
	s_cmp_gt_u32 s60, 5
	s_cbranch_scc0 .LBB0_1170
	s_branch .Lpeel_exit_7
.LBB0_1170:
	ds_read_b128 v[128:131], v183
	ds_read_b128 v[132:135], v183 offset:1024
	ds_read_b128 v[136:139], v183 offset:2048
	ds_read_b128 v[140:143], v183 offset:3072
	ds_read_b128 v[144:147], v184
	ds_read_b128 v[148:151], v184 offset:1024
	ds_read_b128 v[152:155], v184 offset:2048
	ds_read_b128 v[172:175], v184 offset:3072
	s_add_u32 s44, s42, 0xfffe0080
	s_addc_u32 s45, s43, -1
	s_cmp_eq_u32 s60, 4
	s_cselect_b32 s47, s31, s45
	s_cselect_b32 s46, s56, s44
	s_cselect_b32 s45, s35, s59
	s_cselect_b32 s44, s57, s58
	v_lshl_add_u64 v[180:181], s[42:43], 0, v[164:165]
	s_add_i32 m0, s25, 0xc000
	ds_read_b128 v[176:179], v185
	ds_read_b128 v[186:189], v185 offset:1024
	ds_read_b128 v[190:193], v185 offset:2048
	ds_read_b128 v[194:197], v185 offset:3072
	ds_read_b128 v[198:201], v185 offset:4096
	ds_read_b128 v[202:205], v185 offset:5120
	ds_read_b128 v[206:209], v185 offset:6144
	ds_read_b128 v[210:213], v185 offset:7168
	global_load_lds_dwordx4 v[180:181], off
	v_lshl_add_u64 v[180:181], s[42:43], 0, v[166:167]
	s_add_i32 m0, s25, 0xe000
	s_nop 0
	global_load_lds_dwordx4 v[180:181], off
	s_waitcnt vmcnt(8)
	s_waitcnt lgkmcnt(0)
	s_barrier
; #define PG8_STAGE(bufoff, gbase, voff) do { _Pragma("unroll") for (int _i = 0; _i < 2; ++_i) \
;         __builtin_amdgcn_global_load_lds((const unsigned*)((const char*)(gbase) + (voff)[_i]), (LAS unsigned*)(lds + (bufoff) + ldsw + _i * 8192), 16, 0, 0); } while (0)
; #define PG8_LDA(dst, b, h) do { _Pragma("unroll") for (int m = 0; m < 4; ++m) _Pragma("unroll") for (int k = 0; k < 2; ++k) dst[m][k] = *(const LAS bf16x8*)(lds + PG8_SA(b, h) + aoff + m * 2048 + k * 1024); } while (0)
; #define PG8_MMA(ai, bj, At, Bt) do { __builtin_amdgcn_s_setprio(1); _Pragma("unroll") for (int m = 0; m < 4; ++m) _Pragma("unroll") for (int n = 0; n < 2; ++n) _Pragma("unroll") for (int k = 0; k < 2; ++k) \
;         acc[ai][bj][m][n] = __builtin_amdgcn_mfma_f32_16x16x32_bf16(Bt[n][k], At[m][k], acc[ai][bj][m][n], 0, 0, 0); __builtin_amdgcn_s_setprio(0); } while (0)
; #define PG8_WAIT_V(n) asm volatile("s_waitcnt vmcnt(" #n ")" ::: "memory")
; #define PG8_WAIT_L(n) asm volatile("s_waitcnt lgkmcnt(" #n ")" ::: "memory")
; #define PG8_BAR __builtin_amdgcn_s_barrier()
; #define PG8_SCHED __builtin_amdgcn_sched_barrier(0)
; template <class Epi>
; DI void gemm_phase(LAS unsigned char* lds, const int wid, const Gemm g, const Order& S, const Epi& E) {
;     ...
;             PG8_WAIT_V(8); PG8_WAIT_L(0); PG8_BAR; PG8_MMA(0, 0, At, B0); PG8_MMA(0, 1, At, B1); PG8_BAR; PG8_SCHED;
;             PG8_LDA(At, 0, 1); PG8_STAGE(PG8_SB(0, 0), b2, voffB); PG8_STAGE(PG8_SB(0, 1), b2 + hstepB, voffB); PG8_STAGE(PG8_SA(0, 0), a2, voffA);
;             PG8_WAIT_V(8); PG8_WAIT_L(0); PG8_BAR; PG8_MMA(1, 0, At, B0); PG8_MMA(1, 1, At, B1); PG8_BAR; PG8_SCHED;
	s_setprio 1
	v_mfma_f32_16x16x32_bf16 v[124:127], v[128:131], v[176:179], v[124:127]
	v_mfma_f32_16x16x32_bf16 v[120:123], v[136:139], v[176:179], v[120:123]
	v_mfma_f32_16x16x32_bf16 v[108:111], v[128:131], v[190:193], v[108:111]
	v_mfma_f32_16x16x32_bf16 v[104:107], v[136:139], v[190:193], v[104:107]
	v_mfma_f32_16x16x32_bf16 v[92:95], v[128:131], v[198:201], v[92:95]
	v_mfma_f32_16x16x32_bf16 v[88:91], v[136:139], v[198:201], v[88:91]
	v_mfma_f32_16x16x32_bf16 v[76:79], v[128:131], v[206:209], v[76:79]
	v_mfma_f32_16x16x32_bf16 v[72:75], v[136:139], v[206:209], v[72:75]
	v_mfma_f32_16x16x32_bf16 v[124:127], v[132:135], v[186:189], v[124:127]
	v_mfma_f32_16x16x32_bf16 v[120:123], v[140:143], v[186:189], v[120:123]
	v_mfma_f32_16x16x32_bf16 v[108:111], v[132:135], v[194:197], v[108:111]
	v_mfma_f32_16x16x32_bf16 v[104:107], v[140:143], v[194:197], v[104:107]
	v_mfma_f32_16x16x32_bf16 v[92:95], v[132:135], v[202:205], v[92:95]
	v_mfma_f32_16x16x32_bf16 v[88:91], v[140:143], v[202:205], v[88:91]
	v_mfma_f32_16x16x32_bf16 v[76:79], v[132:135], v[210:213], v[76:79]
	v_mfma_f32_16x16x32_bf16 v[72:75], v[140:143], v[210:213], v[72:75]
	v_mfma_f32_16x16x32_bf16 v[116:119], v[144:147], v[176:179], v[116:119]
	v_mfma_f32_16x16x32_bf16 v[112:115], v[152:155], v[176:179], v[112:115]
	v_mfma_f32_16x16x32_bf16 v[100:103], v[144:147], v[190:193], v[100:103]
	v_mfma_f32_16x16x32_bf16 v[96:99], v[152:155], v[190:193], v[96:99]
	v_mfma_f32_16x16x32_bf16 v[84:87], v[144:147], v[198:201], v[84:87]
	v_mfma_f32_16x16x32_bf16 v[80:83], v[152:155], v[198:201], v[80:83]
	v_mfma_f32_16x16x32_bf16 v[68:71], v[144:147], v[206:209], v[68:71]
	v_mfma_f32_16x16x32_bf16 v[64:67], v[152:155], v[206:209], v[64:67]
	v_mfma_f32_16x16x32_bf16 v[116:119], v[148:151], v[186:189], v[116:119]
	v_mfma_f32_16x16x32_bf16 v[112:115], v[172:175], v[186:189], v[112:115]
	v_mfma_f32_16x16x32_bf16 v[100:103], v[148:151], v[194:197], v[100:103]
	v_mfma_f32_16x16x32_bf16 v[96:99], v[172:175], v[194:197], v[96:99]
	v_mfma_f32_16x16x32_bf16 v[84:87], v[148:151], v[202:205], v[84:87]
	v_mfma_f32_16x16x32_bf16 v[80:83], v[172:175], v[202:205], v[80:83]
	v_mfma_f32_16x16x32_bf16 v[68:71], v[148:151], v[210:213], v[68:71]
	v_mfma_f32_16x16x32_bf16 v[64:67], v[172:175], v[210:213], v[64:67]
	s_setprio 0
	s_barrier
	s_add_i32 s61, s53, s94
	v_lshl_add_u64 v[180:181], s[44:45], 0, v[158:159]
	s_mov_b32 m0, s61
	ds_read_b128 v[176:179], v185 offset:16384
	ds_read_b128 v[186:189], v185 offset:17408
	ds_read_b128 v[190:193], v185 offset:18432
	ds_read_b128 v[194:197], v185 offset:19456
	ds_read_b128 v[198:201], v185 offset:20480
	ds_read_b128 v[202:205], v185 offset:21504
	ds_read_b128 v[206:209], v185 offset:22528
	ds_read_b128 v[210:213], v185 offset:23552
	global_load_lds_dwordx4 v[180:181], off
	s_add_i32 m0, s61, 0x2000
	s_add_u32 s62, s44, 0x20000
	v_lshl_add_u64 v[214:215], s[44:45], 0, v[162:163]
	s_addc_u32 s63, s45, 0
	s_add_i32 s61, s54, s94
	global_load_lds_dwordx4 v[214:215], off
	v_lshl_add_u64 v[216:217], s[62:63], 0, v[158:159]
	s_mov_b32 m0, s61
	v_lshl_add_u64 v[218:219], s[46:47], 0, v[160:161]
	global_load_lds_dwordx4 v[216:217], off
	v_lshl_add_u64 v[216:217], s[62:63], 0, v[162:163]
	s_add_i32 m0, s61, 0x2000
	s_nop 0
	global_load_lds_dwordx4 v[216:217], off
	v_lshl_add_u64 v[216:217], s[46:47], 0, v[156:157]
	s_mov_b32 m0, s25
	s_nop 0
	global_load_lds_dwordx4 v[216:217], off
	s_mov_b32 m0, s41
	s_nop 0
	global_load_lds_dwordx4 v[218:219], off
	s_waitcnt vmcnt(8)
	s_waitcnt lgkmcnt(0)
	s_barrier
	s_setprio 1
	v_mfma_f32_16x16x32_bf16 v[60:63], v[128:131], v[176:179], v[60:63]
	v_mfma_f32_16x16x32_bf16 v[56:59], v[136:139], v[176:179], v[56:59]
	v_mfma_f32_16x16x32_bf16 v[44:47], v[128:131], v[190:193], v[44:47]
	v_mfma_f32_16x16x32_bf16 v[40:43], v[136:139], v[190:193], v[40:43]
	v_mfma_f32_16x16x32_bf16 v[28:31], v[128:131], v[198:201], v[28:31]
	v_mfma_f32_16x16x32_bf16 v[24:27], v[136:139], v[198:201], v[24:27]
	v_mfma_f32_16x16x32_bf16 v[12:15], v[128:131], v[206:209], v[12:15]
	v_mfma_f32_16x16x32_bf16 v[8:11], v[136:139], v[206:209], v[8:11]
	v_mfma_f32_16x16x32_bf16 v[60:63], v[132:135], v[186:189], v[60:63]
	v_mfma_f32_16x16x32_bf16 v[56:59], v[140:143], v[186:189], v[56:59]
	v_mfma_f32_16x16x32_bf16 v[44:47], v[132:135], v[194:197], v[44:47]
	v_mfma_f32_16x16x32_bf16 v[40:43], v[140:143], v[194:197], v[40:43]
	v_mfma_f32_16x16x32_bf16 v[28:31], v[132:135], v[202:205], v[28:31]
	v_mfma_f32_16x16x32_bf16 v[24:27], v[140:143], v[202:205], v[24:27]
	v_mfma_f32_16x16x32_bf16 v[12:15], v[132:135], v[210:213], v[12:15]
	v_mfma_f32_16x16x32_bf16 v[8:11], v[140:143], v[210:213], v[8:11]
	v_mfma_f32_16x16x32_bf16 v[52:55], v[144:147], v[176:179], v[52:55]
	v_mfma_f32_16x16x32_bf16 v[48:51], v[152:155], v[176:179], v[48:51]
	v_mfma_f32_16x16x32_bf16 v[36:39], v[144:147], v[190:193], v[36:39]
	v_mfma_f32_16x16x32_bf16 v[32:35], v[152:155], v[190:193], v[32:35]
	v_mfma_f32_16x16x32_bf16 v[20:23], v[144:147], v[198:201], v[20:23]
	v_mfma_f32_16x16x32_bf16 v[16:19], v[152:155], v[198:201], v[16:19]
	v_mfma_f32_16x16x32_bf16 v[4:7], v[144:147], v[206:209], v[4:7]
	v_mfma_f32_16x16x32_bf16 v[0:3], v[152:155], v[206:209], v[0:3]
	v_mfma_f32_16x16x32_bf16 v[52:55], v[148:151], v[186:189], v[52:55]
	v_mfma_f32_16x16x32_bf16 v[48:51], v[172:175], v[186:189], v[48:51]
	v_mfma_f32_16x16x32_bf16 v[36:39], v[148:151], v[194:197], v[36:39]
	v_mfma_f32_16x16x32_bf16 v[32:35], v[172:175], v[194:197], v[32:35]
	v_mfma_f32_16x16x32_bf16 v[20:23], v[148:151], v[202:205], v[20:23]
	v_mfma_f32_16x16x32_bf16 v[16:19], v[172:175], v[202:205], v[16:19]
	v_mfma_f32_16x16x32_bf16 v[4:7], v[148:151], v[210:213], v[4:7]
	v_mfma_f32_16x16x32_bf16 v[0:3], v[172:175], v[210:213], v[0:3]
	s_setprio 0
	s_barrier
; #define PG8_STAGE(bufoff, gbase, voff) do { _Pragma("unroll") for (int _i = 0; _i < 2; ++_i) \
;         __builtin_amdgcn_global_load_lds((const unsigned*)((const char*)(gbase) + (voff)[_i]), (LAS unsigned*)(lds + (bufoff) + ldsw + _i * 8192), 16, 0, 0); } while (0)
; #define PG8_LDA(dst, b, h) do { _Pragma("unroll") for (int m = 0; m < 4; ++m) _Pragma("unroll") for (int k = 0; k < 2; ++k) dst[m][k] = *(const LAS bf16x8*)(lds + PG8_SA(b, h) + aoff + m * 2048 + k * 1024); } while (0)
; #define PG8_LDB(dst, b, h) do { _Pragma("unroll") for (int n = 0; n < 2; ++n) _Pragma("unroll") for (int k = 0; k < 2; ++k) dst[n][k] = *(const LAS bf16x8*)(lds + PG8_SB(b, h) + boff + n * 2048 + k * 1024); } while (0)
; #define PG8_MMA(ai, bj, At, Bt) do { __builtin_amdgcn_s_setprio(1); _Pragma("unroll") for (int m = 0; m < 4; ++m) _Pragma("unroll") for (int n = 0; n < 2; ++n) _Pragma("unroll") for (int k = 0; k < 2; ++k) \
;         acc[ai][bj][m][n] = __builtin_amdgcn_mfma_f32_16x16x32_bf16(Bt[n][k], At[m][k], acc[ai][bj][m][n], 0, 0, 0); __builtin_amdgcn_s_setprio(0); } while (0)
; #define PG8_WAIT_V(n) asm volatile("s_waitcnt vmcnt(" #n ")" ::: "memory")
; #define PG8_WAIT_L(n) asm volatile("s_waitcnt lgkmcnt(" #n ")" ::: "memory")
; #define PG8_BAR __builtin_amdgcn_s_barrier()
; #define PG8_SCHED __builtin_amdgcn_sched_barrier(0)
; template <class Epi>
; DI void gemm_phase(LAS unsigned char* lds, const int wid, const Gemm g, const Order& S, const Epi& E) {
;     ...
;             PG8_LDB(B0, 1, 0); PG8_LDB(B1, 1, 1); PG8_SCHED; PG8_LDA(At, 1, 0); PG8_STAGE(PG8_SA(0, 1), a2 + hstepA, voffA);
;             PG8_WAIT_V(8); PG8_WAIT_L(0); PG8_BAR; PG8_MMA(0, 0, At, B0); PG8_MMA(0, 1, At, B1); PG8_BAR; PG8_SCHED;
	s_add_i32 s61, 0, 0x18000
	s_add_i32 s62, 0, 0x1c000
	v_add_u32_e32 v140, s61, v182
	v_add_u32_e32 v172, s62, v182
	ds_read_b128 v[128:131], v140
	ds_read_b128 v[132:135], v140 offset:1024
	ds_read_b128 v[136:139], v140 offset:2048
	ds_read_b128 v[140:143], v140 offset:3072
	ds_read_b128 v[144:147], v172
	ds_read_b128 v[148:151], v172 offset:1024
	ds_read_b128 v[152:155], v172 offset:2048
	ds_read_b128 v[172:175], v172 offset:3072
	s_add_u32 s46, s46, 0x20000
	s_addc_u32 s47, s47, 0
	s_mov_b32 m0, s48
	v_lshl_add_u64 v[220:221], s[46:47], 0, v[156:157]
	ds_read_b128 v[176:179], v185 offset:32768
	ds_read_b128 v[186:189], v185 offset:33792
	ds_read_b128 v[190:193], v185 offset:34816
	ds_read_b128 v[194:197], v185 offset:35840
	ds_read_b128 v[198:201], v185 offset:36864
	ds_read_b128 v[202:205], v185 offset:37888
	ds_read_b128 v[206:209], v185 offset:38912
	ds_read_b128 v[210:213], v185 offset:39936
	global_load_lds_dwordx4 v[220:221], off
	v_lshl_add_u64 v[220:221], s[46:47], 0, v[160:161]
	s_mov_b32 m0, s49
	s_nop 0
	global_load_lds_dwordx4 v[220:221], off
	s_waitcnt vmcnt(8)
	s_waitcnt lgkmcnt(0)
	s_barrier
	s_setprio 1
	v_mfma_f32_16x16x32_bf16 v[124:127], v[128:131], v[176:179], v[124:127]
	v_mfma_f32_16x16x32_bf16 v[120:123], v[136:139], v[176:179], v[120:123]
	v_mfma_f32_16x16x32_bf16 v[108:111], v[128:131], v[190:193], v[108:111]
	v_mfma_f32_16x16x32_bf16 v[104:107], v[136:139], v[190:193], v[104:107]
	v_mfma_f32_16x16x32_bf16 v[92:95], v[128:131], v[198:201], v[92:95]
	v_mfma_f32_16x16x32_bf16 v[88:91], v[136:139], v[198:201], v[88:91]
	v_mfma_f32_16x16x32_bf16 v[76:79], v[128:131], v[206:209], v[76:79]
	v_mfma_f32_16x16x32_bf16 v[72:75], v[136:139], v[206:209], v[72:75]
	v_mfma_f32_16x16x32_bf16 v[124:127], v[132:135], v[186:189], v[124:127]
	v_mfma_f32_16x16x32_bf16 v[120:123], v[140:143], v[186:189], v[120:123]
	v_mfma_f32_16x16x32_bf16 v[108:111], v[132:135], v[194:197], v[108:111]
	v_mfma_f32_16x16x32_bf16 v[104:107], v[140:143], v[194:197], v[104:107]
	v_mfma_f32_16x16x32_bf16 v[92:95], v[132:135], v[202:205], v[92:95]
	v_mfma_f32_16x16x32_bf16 v[88:91], v[140:143], v[202:205], v[88:91]
	v_mfma_f32_16x16x32_bf16 v[76:79], v[132:135], v[210:213], v[76:79]
	v_mfma_f32_16x16x32_bf16 v[72:75], v[140:143], v[210:213], v[72:75]
	v_mfma_f32_16x16x32_bf16 v[116:119], v[144:147], v[176:179], v[116:119]
	v_mfma_f32_16x16x32_bf16 v[112:115], v[152:155], v[176:179], v[112:115]
	v_mfma_f32_16x16x32_bf16 v[100:103], v[144:147], v[190:193], v[100:103]
	v_mfma_f32_16x16x32_bf16 v[96:99], v[152:155], v[190:193], v[96:99]
	v_mfma_f32_16x16x32_bf16 v[84:87], v[144:147], v[198:201], v[84:87]
	v_mfma_f32_16x16x32_bf16 v[80:83], v[152:155], v[198:201], v[80:83]
	v_mfma_f32_16x16x32_bf16 v[68:71], v[144:147], v[206:209], v[68:71]
	v_mfma_f32_16x16x32_bf16 v[64:67], v[152:155], v[206:209], v[64:67]
	v_mfma_f32_16x16x32_bf16 v[116:119], v[148:151], v[186:189], v[116:119]
	v_mfma_f32_16x16x32_bf16 v[112:115], v[172:175], v[186:189], v[112:115]
	v_mfma_f32_16x16x32_bf16 v[100:103], v[148:151], v[194:197], v[100:103]
	v_mfma_f32_16x16x32_bf16 v[96:99], v[172:175], v[194:197], v[96:99]
	v_mfma_f32_16x16x32_bf16 v[84:87], v[148:151], v[202:205], v[84:87]
	v_mfma_f32_16x16x32_bf16 v[80:83], v[172:175], v[202:205], v[80:83]
	v_mfma_f32_16x16x32_bf16 v[68:71], v[148:151], v[210:213], v[68:71]
	v_mfma_f32_16x16x32_bf16 v[64:67], v[172:175], v[210:213], v[64:67]
	s_setprio 0
	s_barrier
; #define PG8_STAGE(bufoff, gbase, voff) do { _Pragma("unroll") for (int _i = 0; _i < 2; ++_i) \
;         __builtin_amdgcn_global_load_lds((const unsigned*)((const char*)(gbase) + (voff)[_i]), (LAS unsigned*)(lds + (bufoff) + ldsw + _i * 8192), 16, 0, 0); } while (0)
; #define PG8_LDA(dst, b, h) do { _Pragma("unroll") for (int m = 0; m < 4; ++m) _Pragma("unroll") for (int k = 0; k < 2; ++k) dst[m][k] = *(const LAS bf16x8*)(lds + PG8_SA(b, h) + aoff + m * 2048 + k * 1024); } while (0)
; #define PG8_MMA(ai, bj, At, Bt) do { __builtin_amdgcn_s_setprio(1); _Pragma("unroll") for (int m = 0; m < 4; ++m) _Pragma("unroll") for (int n = 0; n < 2; ++n) _Pragma("unroll") for (int k = 0; k < 2; ++k) \
;         acc[ai][bj][m][n] = __builtin_amdgcn_mfma_f32_16x16x32_bf16(Bt[n][k], At[m][k], acc[ai][bj][m][n], 0, 0, 0); __builtin_amdgcn_s_setprio(0); } while (0)
; #define PG8_WAIT_V(n) asm volatile("s_waitcnt vmcnt(" #n ")" ::: "memory")
; #define PG8_WAIT_L(n) asm volatile("s_waitcnt lgkmcnt(" #n ")" ::: "memory")
; #define PG8_BAR __builtin_amdgcn_s_barrier()
; #define PG8_SCHED __builtin_amdgcn_sched_barrier(0)
; template <class Epi>
; DI void gemm_phase(LAS unsigned char* lds, const int wid, const Gemm g, const Order& S, const Epi& E) {
;     ...
;         for (int t = 0; t < nt; t += 2) {
;     ...
;             PG8_LDA(At, 1, 1); PG8_STAGE(PG8_SB(1, 0), b3, voffB); PG8_STAGE(PG8_SB(1, 1), b3 + hstepB, voffB); PG8_STAGE(PG8_SA(1, 0), a3, voffA);
;             PG8_WAIT_V(8); PG8_WAIT_L(0); PG8_BAR; PG8_MMA(1, 0, At, B0); PG8_MMA(1, 1, At, B1); PG8_BAR; PG8_SCHED;
	s_add_i32 s46, s61, s94
	v_lshl_add_u64 v[180:181], v[180:181], 0, s[26:27]
	s_mov_b32 m0, s46
	ds_read_b128 v[176:179], v185 offset:49152
	ds_read_b128 v[186:189], v185 offset:50176
	ds_read_b128 v[190:193], v185 offset:51200
	ds_read_b128 v[194:197], v185 offset:52224
	ds_read_b128 v[198:201], v185 offset:53248
	ds_read_b128 v[202:205], v185 offset:54272
	ds_read_b128 v[206:209], v185 offset:55296
	ds_read_b128 v[210:213], v185 offset:56320
	global_load_lds_dwordx4 v[180:181], off
	s_add_i32 m0, s46, 0x2000
	s_add_u32 s44, s44, 0x20080
	v_lshl_add_u64 v[180:181], v[214:215], 0, s[26:27]
	s_addc_u32 s45, s45, 0
	s_add_i32 s46, s62, s94
	global_load_lds_dwordx4 v[180:181], off
	v_lshl_add_u64 v[180:181], s[44:45], 0, v[158:159]
	s_mov_b32 m0, s46
	s_nop 0
	global_load_lds_dwordx4 v[180:181], off
	v_lshl_add_u64 v[180:181], s[44:45], 0, v[162:163]
	s_add_i32 m0, s46, 0x2000
	s_nop 0
	global_load_lds_dwordx4 v[180:181], off
	v_lshl_add_u64 v[180:181], v[216:217], 0, s[26:27]
	s_mov_b32 m0, s51
	s_nop 0
	global_load_lds_dwordx4 v[180:181], off
	v_lshl_add_u64 v[180:181], v[218:219], 0, s[26:27]
	s_mov_b32 m0, s52
	s_nop 0
	global_load_lds_dwordx4 v[180:181], off
	s_waitcnt vmcnt(8)
	s_waitcnt lgkmcnt(0)
	s_barrier
	s_setprio 1
	v_mfma_f32_16x16x32_bf16 v[60:63], v[128:131], v[176:179], v[60:63]
	v_mfma_f32_16x16x32_bf16 v[56:59], v[136:139], v[176:179], v[56:59]
	v_mfma_f32_16x16x32_bf16 v[44:47], v[128:131], v[190:193], v[44:47]
	v_mfma_f32_16x16x32_bf16 v[40:43], v[136:139], v[190:193], v[40:43]
	v_mfma_f32_16x16x32_bf16 v[28:31], v[128:131], v[198:201], v[28:31]
	v_mfma_f32_16x16x32_bf16 v[24:27], v[136:139], v[198:201], v[24:27]
	v_mfma_f32_16x16x32_bf16 v[12:15], v[128:131], v[206:209], v[12:15]
	v_mfma_f32_16x16x32_bf16 v[8:11], v[136:139], v[206:209], v[8:11]
	v_mfma_f32_16x16x32_bf16 v[60:63], v[132:135], v[186:189], v[60:63]
	v_mfma_f32_16x16x32_bf16 v[56:59], v[140:143], v[186:189], v[56:59]
	v_mfma_f32_16x16x32_bf16 v[44:47], v[132:135], v[194:197], v[44:47]
	v_mfma_f32_16x16x32_bf16 v[40:43], v[140:143], v[194:197], v[40:43]
	v_mfma_f32_16x16x32_bf16 v[28:31], v[132:135], v[202:205], v[28:31]
	v_mfma_f32_16x16x32_bf16 v[24:27], v[140:143], v[202:205], v[24:27]
	v_mfma_f32_16x16x32_bf16 v[12:15], v[132:135], v[210:213], v[12:15]
	v_mfma_f32_16x16x32_bf16 v[8:11], v[140:143], v[210:213], v[8:11]
	v_mfma_f32_16x16x32_bf16 v[52:55], v[144:147], v[176:179], v[52:55]
	v_mfma_f32_16x16x32_bf16 v[48:51], v[152:155], v[176:179], v[48:51]
	v_mfma_f32_16x16x32_bf16 v[36:39], v[144:147], v[190:193], v[36:39]
	v_mfma_f32_16x16x32_bf16 v[32:35], v[152:155], v[190:193], v[32:35]
	v_mfma_f32_16x16x32_bf16 v[20:23], v[144:147], v[198:201], v[20:23]
	v_mfma_f32_16x16x32_bf16 v[16:19], v[152:155], v[198:201], v[16:19]
	v_mfma_f32_16x16x32_bf16 v[4:7], v[144:147], v[206:209], v[4:7]
	v_mfma_f32_16x16x32_bf16 v[0:3], v[152:155], v[206:209], v[0:3]
	v_mfma_f32_16x16x32_bf16 v[52:55], v[148:151], v[186:189], v[52:55]
	v_mfma_f32_16x16x32_bf16 v[48:51], v[172:175], v[186:189], v[48:51]
	v_mfma_f32_16x16x32_bf16 v[36:39], v[148:151], v[194:197], v[36:39]
	v_mfma_f32_16x16x32_bf16 v[32:35], v[172:175], v[194:197], v[32:35]
	v_mfma_f32_16x16x32_bf16 v[20:23], v[148:151], v[202:205], v[20:23]
	v_mfma_f32_16x16x32_bf16 v[16:19], v[172:175], v[202:205], v[16:19]
	v_mfma_f32_16x16x32_bf16 v[4:7], v[148:151], v[210:213], v[4:7]
	v_mfma_f32_16x16x32_bf16 v[0:3], v[172:175], v[210:213], v[0:3]
	s_setprio 0
	s_barrier
	s_add_i32 s60, s60, 2
	s_add_u32 s42, s42, 0x100
	s_addc_u32 s43, s43, 0
	s_add_u32 s58, s58, 0x100
	s_addc_u32 s59, s59, 0
	s_cmp_gt_u32 s60, 5
	s_cbranch_scc0 .LBB0_1170

; #define PG8_STAGE(bufoff, gbase, voff) do { _Pragma("unroll") for (int _i = 0; _i < 2; ++_i) \
;         __builtin_amdgcn_global_load_lds((const unsigned*)((const char*)(gbase) + (voff)[_i]), (LAS unsigned*)(lds + (bufoff) + ldsw + _i * 8192), 16, 0, 0); } while (0)
; #define PG8_LDA(dst, b, h) do { _Pragma("unroll") for (int m = 0; m < 4; ++m) _Pragma("unroll") for (int k = 0; k < 2; ++k) dst[m][k] = *(const LAS bf16x8*)(lds + PG8_SA(b, h) + aoff + m * 2048 + k * 1024); } while (0)
; #define PG8_LDB(dst, b, h) do { _Pragma("unroll") for (int n = 0; n < 2; ++n) _Pragma("unroll") for (int k = 0; k < 2; ++k) dst[n][k] = *(const LAS bf16x8*)(lds + PG8_SB(b, h) + boff + n * 2048 + k * 1024); } while (0)
; #define PG8_MMA(ai, bj, At, Bt) do { __builtin_amdgcn_s_setprio(1); _Pragma("unroll") for (int m = 0; m < 4; ++m) _Pragma("unroll") for (int n = 0; n < 2; ++n) _Pragma("unroll") for (int k = 0; k < 2; ++k) \
;         acc[ai][bj][m][n] = __builtin_amdgcn_mfma_f32_16x16x32_bf16(Bt[n][k], At[m][k], acc[ai][bj][m][n], 0, 0, 0); __builtin_amdgcn_s_setprio(0); } while (0)
; #define PG8_WAIT_V(n) asm volatile("s_waitcnt vmcnt(" #n ")" ::: "memory")
; template <class Epi>
; DI void gemm_phase(LAS unsigned char* lds, const int wid, const Gemm g, const Order& S, const Epi& E) {
;     ...
;         const char* nA = has_next ? (const char*)(g.A + (size_t)nxt.g * g.gsA + (size_t)nxt.pm * BM * g.lda) : cA;
;         const char* nB = has_next ? (const char*)(g.Bt + (size_t)nxt.g * g.gsB + (size_t)nxt.pn * BM * g.ldb) : cB;
;         for (int t = 0; t < nt; t += 2) {
;             const bool last = (t == nt - 2);
;             const char* a1 = cA + (size_t)(t + 1) * kstep;
;             const char* a2 = last ? nA : cA + (size_t)(t + 2) * kstep; const char* b2 = last ? nB : cB + (size_t)(t + 2) * kstep;
;             const char* a3 = a2 + kstep; const char* b3 = b2 + kstep;
;             PG8_LDB(B0, 0, 0); PG8_LDB(B1, 0, 1); PG8_SCHED; PG8_LDA(At, 0, 0); PG8_STAGE(PG8_SA(1, 1), a1 + hstepA, voffA);
;             PG8_WAIT_V(8); PG8_WAIT_L(0); PG8_BAR; PG8_MMA(0, 0, At, B0); PG8_MMA(0, 1, At, B1); PG8_BAR; PG8_SCHED;
;             PG8_LDA(At, 0, 1); PG8_STAGE(PG8_SB(0, 0), b2, voffB); PG8_STAGE(PG8_SB(0, 1), b2 + hstepB, voffB); PG8_STAGE(PG8_SA(0, 0), a2, voffA);
;             PG8_WAIT_V(8); PG8_WAIT_L(0); PG8_BAR; PG8_MMA(1, 0, At, B0); PG8_MMA(1, 1, At, B1); PG8_BAR; PG8_SCHED;
.LBB0_1249:
	s_ashr_i32 s37, s36, 31
	s_lshl_b64 s[40:41], s[36:37], 19
	s_add_u32 s40, s6, s40
	s_addc_u32 s41, s7, s41
	s_and_b64 s[42:43], s[8:9], exec
	s_cselect_b32 s11, s41, s47
	s_cselect_b32 s37, s40, s46
	s_ashr_i32 s39, s38, 31
	s_lshl_b64 s[42:43], s[38:39], 19
	s_add_u32 s42, s21, s42
	s_addc_u32 s43, s24, s43
	s_and_b64 s[50:51], s[8:9], exec
	s_cselect_b32 s39, s43, s49
	s_cselect_b32 s59, s42, s48
	s_add_u32 s46, s46, 0x40080
	s_addc_u32 s47, s47, 0
	s_add_u32 s60, s48, 0x100
	v_mov_b32_e32 v0, 0
	s_addc_u32 s61, s49, 0
	s_mov_b32 s62, -2
	s_waitcnt lgkmcnt(0)
	ds_read_b128 v[128:131], v209
	ds_read_b128 v[132:135], v209 offset:1024
	ds_read_b128 v[136:139], v209 offset:2048
	ds_read_b128 v[140:143], v209 offset:3072
	ds_read_b128 v[144:147], v210
	ds_read_b128 v[148:151], v210 offset:1024
	ds_read_b128 v[152:155], v210 offset:2048
	ds_read_b128 v[156:159], v210 offset:3072
	s_add_u32 s48, s46, 0xfffc0080
	s_addc_u32 s49, s47, -1
	s_cmp_eq_u32 s62, 12
	s_cselect_b32 s51, s11, s49
	s_cselect_b32 s50, s37, s48
	s_cselect_b32 s49, s39, s61
	s_cselect_b32 s48, s59, s60
	v_lshl_add_u64 v[214:215], s[46:47], 0, v[184:185]
	s_add_i32 m0, s25, 0xc000
	ds_read_b128 v[160:163], v211
	ds_read_b128 v[164:167], v211 offset:1024
	ds_read_b128 v[168:171], v211 offset:2048
	ds_read_b128 v[172:175], v211 offset:3072
	ds_read_b128 v[192:195], v211 offset:4096
	ds_read_b128 v[196:199], v211 offset:5120
	ds_read_b128 v[200:203], v211 offset:6144
	ds_read_b128 v[204:207], v211 offset:7168
	global_load_lds_dwordx4 v[214:215], off
	v_lshl_add_u64 v[214:215], s[46:47], 0, v[186:187]
	s_add_i32 m0, s25, 0xe000
	s_nop 0
	global_load_lds_dwordx4 v[214:215], off
	s_waitcnt vmcnt(8)
	s_waitcnt lgkmcnt(0)
	s_barrier
	s_setprio 1
	v_mfma_f32_16x16x32_bf16 v[124:127], v[128:131], v[160:163], 0
	v_mfma_f32_16x16x32_bf16 v[120:123], v[136:139], v[160:163], 0
	v_mfma_f32_16x16x32_bf16 v[108:111], v[128:131], v[168:171], 0
	v_mfma_f32_16x16x32_bf16 v[104:107], v[136:139], v[168:171], 0
	v_mfma_f32_16x16x32_bf16 v[92:95], v[128:131], v[192:195], 0
	v_mfma_f32_16x16x32_bf16 v[88:91], v[136:139], v[192:195], 0
	v_mfma_f32_16x16x32_bf16 v[76:79], v[128:131], v[200:203], 0
	v_mfma_f32_16x16x32_bf16 v[72:75], v[136:139], v[200:203], 0
	v_mfma_f32_16x16x32_bf16 v[124:127], v[132:135], v[164:167], v[124:127]
	v_mfma_f32_16x16x32_bf16 v[120:123], v[140:143], v[164:167], v[120:123]
	v_mfma_f32_16x16x32_bf16 v[108:111], v[132:135], v[172:175], v[108:111]
	v_mfma_f32_16x16x32_bf16 v[104:107], v[140:143], v[172:175], v[104:107]
	v_mfma_f32_16x16x32_bf16 v[92:95], v[132:135], v[196:199], v[92:95]
	v_mfma_f32_16x16x32_bf16 v[88:91], v[140:143], v[196:199], v[88:91]
	v_mfma_f32_16x16x32_bf16 v[76:79], v[132:135], v[204:207], v[76:79]
	v_mfma_f32_16x16x32_bf16 v[72:75], v[140:143], v[204:207], v[72:75]
	v_mfma_f32_16x16x32_bf16 v[116:119], v[144:147], v[160:163], 0
	v_mfma_f32_16x16x32_bf16 v[112:115], v[152:155], v[160:163], 0
	v_mfma_f32_16x16x32_bf16 v[100:103], v[144:147], v[168:171], 0
	v_mfma_f32_16x16x32_bf16 v[96:99], v[152:155], v[168:171], 0
	v_mfma_f32_16x16x32_bf16 v[84:87], v[144:147], v[192:195], 0
	v_mfma_f32_16x16x32_bf16 v[80:83], v[152:155], v[192:195], 0
	v_mfma_f32_16x16x32_bf16 v[68:71], v[144:147], v[200:203], 0
	v_mfma_f32_16x16x32_bf16 v[64:67], v[152:155], v[200:203], 0
	v_mfma_f32_16x16x32_bf16 v[116:119], v[148:151], v[164:167], v[116:119]
	v_mfma_f32_16x16x32_bf16 v[112:115], v[156:159], v[164:167], v[112:115]
	v_mfma_f32_16x16x32_bf16 v[100:103], v[148:151], v[172:175], v[100:103]
	v_mfma_f32_16x16x32_bf16 v[96:99], v[156:159], v[172:175], v[96:99]
	v_mfma_f32_16x16x32_bf16 v[84:87], v[148:151], v[196:199], v[84:87]
	v_mfma_f32_16x16x32_bf16 v[80:83], v[156:159], v[196:199], v[80:83]
	v_mfma_f32_16x16x32_bf16 v[68:71], v[148:151], v[204:207], v[68:71]
	v_mfma_f32_16x16x32_bf16 v[64:67], v[156:159], v[204:207], v[64:67]
	s_setprio 0
	s_barrier
	s_add_i32 s63, s57, s94
	v_lshl_add_u64 v[214:215], s[48:49], 0, v[178:179]
	s_mov_b32 m0, s63
	ds_read_b128 v[160:163], v211 offset:16384
	ds_read_b128 v[164:167], v211 offset:17408
	ds_read_b128 v[168:171], v211 offset:18432
	ds_read_b128 v[172:175], v211 offset:19456
	ds_read_b128 v[192:195], v211 offset:20480
	ds_read_b128 v[196:199], v211 offset:21504
	ds_read_b128 v[200:203], v211 offset:22528
	ds_read_b128 v[204:207], v211 offset:23552
	global_load_lds_dwordx4 v[214:215], off
	s_add_i32 m0, s63, 0x2000
	s_add_u32 s66, s48, 0x40000
	v_lshl_add_u64 v[216:217], s[48:49], 0, v[182:183]
	s_addc_u32 s67, s49, 0
	s_add_i32 s63, s58, s94
	global_load_lds_dwordx4 v[216:217], off
	v_lshl_add_u64 v[218:219], s[66:67], 0, v[178:179]
	s_mov_b32 m0, s63
	v_lshl_add_u64 v[220:221], s[50:51], 0, v[180:181]
	global_load_lds_dwordx4 v[218:219], off
	v_lshl_add_u64 v[218:219], s[66:67], 0, v[182:183]
	s_add_i32 m0, s63, 0x2000
	s_nop 0
	global_load_lds_dwordx4 v[218:219], off
	v_lshl_add_u64 v[218:219], s[50:51], 0, v[176:177]
	s_mov_b32 m0, s25
	s_nop 0
	global_load_lds_dwordx4 v[218:219], off
	s_mov_b32 m0, s45
	s_nop 0
	global_load_lds_dwordx4 v[220:221], off
	s_waitcnt vmcnt(8)
	s_waitcnt lgkmcnt(0)
	s_barrier
; #define PG8_STAGE(bufoff, gbase, voff) do { _Pragma("unroll") for (int _i = 0; _i < 2; ++_i) \
;         __builtin_amdgcn_global_load_lds((const unsigned*)((const char*)(gbase) + (voff)[_i]), (LAS unsigned*)(lds + (bufoff) + ldsw + _i * 8192), 16, 0, 0); } while (0)
; #define PG8_LDA(dst, b, h) do { _Pragma("unroll") for (int m = 0; m < 4; ++m) _Pragma("unroll") for (int k = 0; k < 2; ++k) dst[m][k] = *(const LAS bf16x8*)(lds + PG8_SA(b, h) + aoff + m * 2048 + k * 1024); } while (0)
; #define PG8_LDB(dst, b, h) do { _Pragma("unroll") for (int n = 0; n < 2; ++n) _Pragma("unroll") for (int k = 0; k < 2; ++k) dst[n][k] = *(const LAS bf16x8*)(lds + PG8_SB(b, h) + boff + n * 2048 + k * 1024); } while (0)
; #define PG8_MMA(ai, bj, At, Bt) do { __builtin_amdgcn_s_setprio(1); _Pragma("unroll") for (int m = 0; m < 4; ++m) _Pragma("unroll") for (int n = 0; n < 2; ++n) _Pragma("unroll") for (int k = 0; k < 2; ++k) \
;         acc[ai][bj][m][n] = __builtin_amdgcn_mfma_f32_16x16x32_bf16(Bt[n][k], At[m][k], acc[ai][bj][m][n], 0, 0, 0); __builtin_amdgcn_s_setprio(0); } while (0)
; #define PG8_WAIT_V(n) asm volatile("s_waitcnt vmcnt(" #n ")" ::: "memory")
; #define PG8_WAIT_L(n) asm volatile("s_waitcnt lgkmcnt(" #n ")" ::: "memory")
; #define PG8_BAR __builtin_amdgcn_s_barrier()
; #define PG8_SCHED __builtin_amdgcn_sched_barrier(0)
; template <class Epi>
; DI void gemm_phase(LAS unsigned char* lds, const int wid, const Gemm g, const Order& S, const Epi& E) {
;     ...
;             PG8_WAIT_V(8); PG8_WAIT_L(0); PG8_BAR; PG8_MMA(1, 0, At, B0); PG8_MMA(1, 1, At, B1); PG8_BAR; PG8_SCHED;
;             PG8_LDB(B0, 1, 0); PG8_LDB(B1, 1, 1); PG8_SCHED; PG8_LDA(At, 1, 0); PG8_STAGE(PG8_SA(0, 1), a2 + hstepA, voffA);
;             PG8_WAIT_V(8); PG8_WAIT_L(0); PG8_BAR; PG8_MMA(0, 0, At, B0); PG8_MMA(0, 1, At, B1); PG8_BAR; PG8_SCHED;
;             PG8_LDA(At, 1, 1); PG8_STAGE(PG8_SB(1, 0), b3, voffB); PG8_STAGE(PG8_SB(1, 1), b3 + hstepB, voffB); PG8_STAGE(PG8_SA(1, 0), a3, voffA);
;             PG8_WAIT_V(8); PG8_WAIT_L(0); PG8_BAR; PG8_MMA(1, 0, At, B0); PG8_MMA(1, 1, At, B1); PG8_BAR; PG8_SCHED;
	s_setprio 1
	v_mfma_f32_16x16x32_bf16 v[60:63], v[128:131], v[160:163], 0
	v_mfma_f32_16x16x32_bf16 v[56:59], v[136:139], v[160:163], 0
	v_mfma_f32_16x16x32_bf16 v[44:47], v[128:131], v[168:171], 0
	v_mfma_f32_16x16x32_bf16 v[40:43], v[136:139], v[168:171], 0
	v_mfma_f32_16x16x32_bf16 v[28:31], v[128:131], v[192:195], 0
	v_mfma_f32_16x16x32_bf16 v[24:27], v[136:139], v[192:195], 0
	v_mfma_f32_16x16x32_bf16 v[12:15], v[128:131], v[200:203], 0
	v_mfma_f32_16x16x32_bf16 v[8:11], v[136:139], v[200:203], 0
	v_mfma_f32_16x16x32_bf16 v[60:63], v[132:135], v[164:167], v[60:63]
	v_mfma_f32_16x16x32_bf16 v[56:59], v[140:143], v[164:167], v[56:59]
	v_mfma_f32_16x16x32_bf16 v[44:47], v[132:135], v[172:175], v[44:47]
	v_mfma_f32_16x16x32_bf16 v[40:43], v[140:143], v[172:175], v[40:43]
	v_mfma_f32_16x16x32_bf16 v[28:31], v[132:135], v[196:199], v[28:31]
	v_mfma_f32_16x16x32_bf16 v[24:27], v[140:143], v[196:199], v[24:27]
	v_mfma_f32_16x16x32_bf16 v[12:15], v[132:135], v[204:207], v[12:15]
	v_mfma_f32_16x16x32_bf16 v[8:11], v[140:143], v[204:207], v[8:11]
	v_mfma_f32_16x16x32_bf16 v[52:55], v[144:147], v[160:163], 0
	v_mfma_f32_16x16x32_bf16 v[48:51], v[152:155], v[160:163], 0
	v_mfma_f32_16x16x32_bf16 v[36:39], v[144:147], v[168:171], 0
	v_mfma_f32_16x16x32_bf16 v[32:35], v[152:155], v[168:171], 0
	v_mfma_f32_16x16x32_bf16 v[20:23], v[144:147], v[192:195], 0
	v_mfma_f32_16x16x32_bf16 v[16:19], v[152:155], v[192:195], 0
	v_mfma_f32_16x16x32_bf16 v[4:7], v[144:147], v[200:203], 0
	v_mfma_f32_16x16x32_bf16 v[0:3], v[152:155], v[200:203], 0
	v_mfma_f32_16x16x32_bf16 v[52:55], v[148:151], v[164:167], v[52:55]
	v_mfma_f32_16x16x32_bf16 v[48:51], v[156:159], v[164:167], v[48:51]
	v_mfma_f32_16x16x32_bf16 v[36:39], v[148:151], v[172:175], v[36:39]
	v_mfma_f32_16x16x32_bf16 v[32:35], v[156:159], v[172:175], v[32:35]
	v_mfma_f32_16x16x32_bf16 v[20:23], v[148:151], v[196:199], v[20:23]
	v_mfma_f32_16x16x32_bf16 v[16:19], v[156:159], v[196:199], v[16:19]
	v_mfma_f32_16x16x32_bf16 v[4:7], v[148:151], v[204:207], v[4:7]
	v_mfma_f32_16x16x32_bf16 v[0:3], v[156:159], v[204:207], v[0:3]
	s_setprio 0
	s_barrier
	s_add_i32 s63, 0, 0x18000
	s_add_i32 s65, 0, 0x1c000
	v_add_u32_e32 v140, s63, v208
	v_add_u32_e32 v156, s65, v208
	ds_read_b128 v[128:131], v140
	ds_read_b128 v[132:135], v140 offset:1024
	ds_read_b128 v[136:139], v140 offset:2048
	ds_read_b128 v[140:143], v140 offset:3072
	ds_read_b128 v[144:147], v156
	ds_read_b128 v[148:151], v156 offset:1024
	ds_read_b128 v[152:155], v156 offset:2048
	ds_read_b128 v[156:159], v156 offset:3072
	s_add_u32 s50, s50, 0x40000
	s_addc_u32 s51, s51, 0
	s_mov_b32 m0, s52
	v_lshl_add_u64 v[222:223], s[50:51], 0, v[176:177]
	ds_read_b128 v[160:163], v211 offset:32768
	ds_read_b128 v[164:167], v211 offset:33792
	ds_read_b128 v[168:171], v211 offset:34816
	ds_read_b128 v[172:175], v211 offset:35840
	ds_read_b128 v[192:195], v211 offset:36864
	ds_read_b128 v[196:199], v211 offset:37888
	ds_read_b128 v[200:203], v211 offset:38912
	ds_read_b128 v[204:207], v211 offset:39936
	global_load_lds_dwordx4 v[222:223], off
	v_lshl_add_u64 v[222:223], s[50:51], 0, v[180:181]
	s_mov_b32 m0, s53
	s_nop 0
	global_load_lds_dwordx4 v[222:223], off
	s_waitcnt vmcnt(8)
	s_waitcnt lgkmcnt(0)
	s_barrier
	s_setprio 1
	v_mfma_f32_16x16x32_bf16 v[124:127], v[128:131], v[160:163], v[124:127]
	v_mfma_f32_16x16x32_bf16 v[120:123], v[136:139], v[160:163], v[120:123]
	v_mfma_f32_16x16x32_bf16 v[108:111], v[128:131], v[168:171], v[108:111]
	v_mfma_f32_16x16x32_bf16 v[104:107], v[136:139], v[168:171], v[104:107]
	v_mfma_f32_16x16x32_bf16 v[92:95], v[128:131], v[192:195], v[92:95]
	v_mfma_f32_16x16x32_bf16 v[88:91], v[136:139], v[192:195], v[88:91]
	v_mfma_f32_16x16x32_bf16 v[76:79], v[128:131], v[200:203], v[76:79]
	v_mfma_f32_16x16x32_bf16 v[72:75], v[136:139], v[200:203], v[72:75]
	v_mfma_f32_16x16x32_bf16 v[124:127], v[132:135], v[164:167], v[124:127]
	v_mfma_f32_16x16x32_bf16 v[120:123], v[140:143], v[164:167], v[120:123]
	v_mfma_f32_16x16x32_bf16 v[108:111], v[132:135], v[172:175], v[108:111]
	v_mfma_f32_16x16x32_bf16 v[104:107], v[140:143], v[172:175], v[104:107]
	v_mfma_f32_16x16x32_bf16 v[92:95], v[132:135], v[196:199], v[92:95]
	v_mfma_f32_16x16x32_bf16 v[88:91], v[140:143], v[196:199], v[88:91]
	v_mfma_f32_16x16x32_bf16 v[76:79], v[132:135], v[204:207], v[76:79]
	v_mfma_f32_16x16x32_bf16 v[72:75], v[140:143], v[204:207], v[72:75]
	v_mfma_f32_16x16x32_bf16 v[116:119], v[144:147], v[160:163], v[116:119]
	v_mfma_f32_16x16x32_bf16 v[112:115], v[152:155], v[160:163], v[112:115]
	v_mfma_f32_16x16x32_bf16 v[100:103], v[144:147], v[168:171], v[100:103]
	v_mfma_f32_16x16x32_bf16 v[96:99], v[152:155], v[168:171], v[96:99]
	v_mfma_f32_16x16x32_bf16 v[84:87], v[144:147], v[192:195], v[84:87]
	v_mfma_f32_16x16x32_bf16 v[80:83], v[152:155], v[192:195], v[80:83]
	v_mfma_f32_16x16x32_bf16 v[68:71], v[144:147], v[200:203], v[68:71]
	v_mfma_f32_16x16x32_bf16 v[64:67], v[152:155], v[200:203], v[64:67]
	v_mfma_f32_16x16x32_bf16 v[116:119], v[148:151], v[164:167], v[116:119]
	v_mfma_f32_16x16x32_bf16 v[112:115], v[156:159], v[164:167], v[112:115]
	v_mfma_f32_16x16x32_bf16 v[100:103], v[148:151], v[172:175], v[100:103]
	v_mfma_f32_16x16x32_bf16 v[96:99], v[156:159], v[172:175], v[96:99]
	v_mfma_f32_16x16x32_bf16 v[84:87], v[148:151], v[196:199], v[84:87]
	v_mfma_f32_16x16x32_bf16 v[80:83], v[156:159], v[196:199], v[80:83]
	v_mfma_f32_16x16x32_bf16 v[68:71], v[148:151], v[204:207], v[68:71]
	v_mfma_f32_16x16x32_bf16 v[64:67], v[156:159], v[204:207], v[64:67]
	s_setprio 0
	s_barrier
; #define PG8_STAGE(bufoff, gbase, voff) do { _Pragma("unroll") for (int _i = 0; _i < 2; ++_i) \
;         __builtin_amdgcn_global_load_lds((const unsigned*)((const char*)(gbase) + (voff)[_i]), (LAS unsigned*)(lds + (bufoff) + ldsw + _i * 8192), 16, 0, 0); } while (0)
; #define PG8_LDA(dst, b, h) do { _Pragma("unroll") for (int m = 0; m < 4; ++m) _Pragma("unroll") for (int k = 0; k < 2; ++k) dst[m][k] = *(const LAS bf16x8*)(lds + PG8_SA(b, h) + aoff + m * 2048 + k * 1024); } while (0)
; #define PG8_LDB(dst, b, h) do { _Pragma("unroll") for (int n = 0; n < 2; ++n) _Pragma("unroll") for (int k = 0; k < 2; ++k) dst[n][k] = *(const LAS bf16x8*)(lds + PG8_SB(b, h) + boff + n * 2048 + k * 1024); } while (0)
; #define PG8_MMA(ai, bj, At, Bt) do { __builtin_amdgcn_s_setprio(1); _Pragma("unroll") for (int m = 0; m < 4; ++m) _Pragma("unroll") for (int n = 0; n < 2; ++n) _Pragma("unroll") for (int k = 0; k < 2; ++k) \
;         acc[ai][bj][m][n] = __builtin_amdgcn_mfma_f32_16x16x32_bf16(Bt[n][k], At[m][k], acc[ai][bj][m][n], 0, 0, 0); __builtin_amdgcn_s_setprio(0); } while (0)
; #define PG8_WAIT_V(n) asm volatile("s_waitcnt vmcnt(" #n ")" ::: "memory")
; #define PG8_WAIT_L(n) asm volatile("s_waitcnt lgkmcnt(" #n ")" ::: "memory")
; template <class Epi>
; DI void gemm_phase(LAS unsigned char* lds, const int wid, const Gemm g, const Order& S, const Epi& E) {
;     ...
;             PG8_LDB(B0, 0, 0); PG8_LDB(B1, 0, 1); PG8_SCHED; PG8_LDA(At, 0, 0); PG8_STAGE(PG8_SA(1, 1), a1 + hstepA, voffA);
;             PG8_WAIT_V(8); PG8_WAIT_L(0); PG8_BAR; PG8_MMA(0, 0, At, B0); PG8_MMA(0, 1, At, B1); PG8_BAR; PG8_SCHED;
;             PG8_LDA(At, 0, 1); PG8_STAGE(PG8_SB(0, 0), b2, voffB); PG8_STAGE(PG8_SB(0, 1), b2 + hstepB, voffB); PG8_STAGE(PG8_SA(0, 0), a2, voffA);
;             PG8_WAIT_V(8); PG8_WAIT_L(0); PG8_BAR; PG8_MMA(1, 0, At, B0); PG8_MMA(1, 1, At, B1); PG8_BAR; PG8_SCHED;
;             PG8_LDB(B0, 1, 0); PG8_LDB(B1, 1, 1); PG8_SCHED; PG8_LDA(At, 1, 0); PG8_STAGE(PG8_SA(0, 1), a2 + hstepA, voffA);
;             PG8_WAIT_V(8); PG8_WAIT_L(0); PG8_BAR; PG8_MMA(0, 0, At, B0); PG8_MMA(0, 1, At, B1); PG8_BAR; PG8_SCHED;
;             PG8_LDA(At, 1, 1); PG8_STAGE(PG8_SB(1, 0), b3, voffB); PG8_STAGE(PG8_SB(1, 1), b3 + hstepB, voffB); PG8_STAGE(PG8_SA(1, 0), a3, voffA);
;             PG8_WAIT_V(8); PG8_WAIT_L(0); PG8_BAR; PG8_MMA(1, 0, At, B0); PG8_MMA(1, 1, At, B1); PG8_BAR; PG8_SCHED;
	s_add_i32 s50, s63, s94
	v_lshl_add_u64 v[214:215], v[214:215], 0, s[30:31]
	s_mov_b32 m0, s50
	ds_read_b128 v[160:163], v211 offset:49152
	ds_read_b128 v[164:167], v211 offset:50176
	ds_read_b128 v[168:171], v211 offset:51200
	ds_read_b128 v[172:175], v211 offset:52224
	ds_read_b128 v[192:195], v211 offset:53248
	ds_read_b128 v[196:199], v211 offset:54272
	ds_read_b128 v[200:203], v211 offset:55296
	ds_read_b128 v[204:207], v211 offset:56320
	global_load_lds_dwordx4 v[214:215], off
	s_add_i32 m0, s50, 0x2000
	s_add_u32 s48, s48, 0x40080
	v_lshl_add_u64 v[214:215], v[216:217], 0, s[30:31]
	s_addc_u32 s49, s49, 0
	s_add_i32 s50, s65, s94
	global_load_lds_dwordx4 v[214:215], off
	v_lshl_add_u64 v[214:215], s[48:49], 0, v[178:179]
	s_mov_b32 m0, s50
	s_nop 0
	global_load_lds_dwordx4 v[214:215], off
	v_lshl_add_u64 v[214:215], s[48:49], 0, v[182:183]
	s_add_i32 m0, s50, 0x2000
	s_nop 0
	global_load_lds_dwordx4 v[214:215], off
	v_lshl_add_u64 v[214:215], v[218:219], 0, s[30:31]
	s_mov_b32 m0, s55
	s_nop 0
	global_load_lds_dwordx4 v[214:215], off
	v_lshl_add_u64 v[214:215], v[220:221], 0, s[30:31]
	s_mov_b32 m0, s56
	s_nop 0
	global_load_lds_dwordx4 v[214:215], off
	s_waitcnt vmcnt(8)
	s_waitcnt lgkmcnt(0)
	s_barrier
	s_setprio 1
	v_mfma_f32_16x16x32_bf16 v[60:63], v[128:131], v[160:163], v[60:63]
	v_mfma_f32_16x16x32_bf16 v[56:59], v[136:139], v[160:163], v[56:59]
	v_mfma_f32_16x16x32_bf16 v[44:47], v[128:131], v[168:171], v[44:47]
	v_mfma_f32_16x16x32_bf16 v[40:43], v[136:139], v[168:171], v[40:43]
	v_mfma_f32_16x16x32_bf16 v[28:31], v[128:131], v[192:195], v[28:31]
	v_mfma_f32_16x16x32_bf16 v[24:27], v[136:139], v[192:195], v[24:27]
	v_mfma_f32_16x16x32_bf16 v[12:15], v[128:131], v[200:203], v[12:15]
	v_mfma_f32_16x16x32_bf16 v[8:11], v[136:139], v[200:203], v[8:11]
	v_mfma_f32_16x16x32_bf16 v[60:63], v[132:135], v[164:167], v[60:63]
	v_mfma_f32_16x16x32_bf16 v[56:59], v[140:143], v[164:167], v[56:59]
	v_mfma_f32_16x16x32_bf16 v[44:47], v[132:135], v[172:175], v[44:47]
	v_mfma_f32_16x16x32_bf16 v[40:43], v[140:143], v[172:175], v[40:43]
	v_mfma_f32_16x16x32_bf16 v[28:31], v[132:135], v[196:199], v[28:31]
	v_mfma_f32_16x16x32_bf16 v[24:27], v[140:143], v[196:199], v[24:27]
	v_mfma_f32_16x16x32_bf16 v[12:15], v[132:135], v[204:207], v[12:15]
	v_mfma_f32_16x16x32_bf16 v[8:11], v[140:143], v[204:207], v[8:11]
	v_mfma_f32_16x16x32_bf16 v[52:55], v[144:147], v[160:163], v[52:55]
	v_mfma_f32_16x16x32_bf16 v[48:51], v[152:155], v[160:163], v[48:51]
	v_mfma_f32_16x16x32_bf16 v[36:39], v[144:147], v[168:171], v[36:39]
	v_mfma_f32_16x16x32_bf16 v[32:35], v[152:155], v[168:171], v[32:35]
	v_mfma_f32_16x16x32_bf16 v[20:23], v[144:147], v[192:195], v[20:23]
	v_mfma_f32_16x16x32_bf16 v[16:19], v[152:155], v[192:195], v[16:19]
	v_mfma_f32_16x16x32_bf16 v[4:7], v[144:147], v[200:203], v[4:7]
	v_mfma_f32_16x16x32_bf16 v[0:3], v[152:155], v[200:203], v[0:3]
	v_mfma_f32_16x16x32_bf16 v[52:55], v[148:151], v[164:167], v[52:55]
	v_mfma_f32_16x16x32_bf16 v[48:51], v[156:159], v[164:167], v[48:51]
	v_mfma_f32_16x16x32_bf16 v[36:39], v[148:151], v[172:175], v[36:39]
	v_mfma_f32_16x16x32_bf16 v[32:35], v[156:159], v[172:175], v[32:35]
	v_mfma_f32_16x16x32_bf16 v[20:23], v[148:151], v[196:199], v[20:23]
	v_mfma_f32_16x16x32_bf16 v[16:19], v[156:159], v[196:199], v[16:19]
	v_mfma_f32_16x16x32_bf16 v[4:7], v[148:151], v[204:207], v[4:7]
	v_mfma_f32_16x16x32_bf16 v[0:3], v[156:159], v[204:207], v[0:3]
	s_setprio 0
	s_barrier
	s_add_i32 s62, s62, 2
	s_add_u32 s46, s46, 0x100
	s_addc_u32 s47, s47, 0
	s_add_u32 s60, s60, 0x100
	s_addc_u32 s61, s61, 0
	s_cmp_gt_u32 s62, 13
	s_cbranch_scc0 .LBB0_1250
	s_branch .Lpeel_exit_8
.LBB0_1250:
	ds_read_b128 v[128:131], v209
	ds_read_b128 v[132:135], v209 offset:1024
	ds_read_b128 v[136:139], v209 offset:2048
	ds_read_b128 v[140:143], v209 offset:3072
	ds_read_b128 v[144:147], v210
	ds_read_b128 v[148:151], v210 offset:1024
	ds_read_b128 v[152:155], v210 offset:2048
	ds_read_b128 v[156:159], v210 offset:3072
	s_add_u32 s48, s46, 0xfffc0080
	s_addc_u32 s49, s47, -1
	s_cmp_eq_u32 s62, 12
	s_cselect_b32 s51, s11, s49
	s_cselect_b32 s50, s37, s48
	s_cselect_b32 s49, s39, s61
	s_cselect_b32 s48, s59, s60
	v_lshl_add_u64 v[214:215], s[46:47], 0, v[184:185]
	s_add_i32 m0, s25, 0xc000
	ds_read_b128 v[160:163], v211
	ds_read_b128 v[164:167], v211 offset:1024
	ds_read_b128 v[168:171], v211 offset:2048
	ds_read_b128 v[172:175], v211 offset:3072
	ds_read_b128 v[192:195], v211 offset:4096
	ds_read_b128 v[196:199], v211 offset:5120
	ds_read_b128 v[200:203], v211 offset:6144
	ds_read_b128 v[204:207], v211 offset:7168
	global_load_lds_dwordx4 v[214:215], off
	v_lshl_add_u64 v[214:215], s[46:47], 0, v[186:187]
	s_add_i32 m0, s25, 0xe000
	s_nop 0
	global_load_lds_dwordx4 v[214:215], off
	s_waitcnt vmcnt(8)
	s_waitcnt lgkmcnt(0)
	s_barrier
; #define PG8_STAGE(bufoff, gbase, voff) do { _Pragma("unroll") for (int _i = 0; _i < 2; ++_i) \
;         __builtin_amdgcn_global_load_lds((const unsigned*)((const char*)(gbase) + (voff)[_i]), (LAS unsigned*)(lds + (bufoff) + ldsw + _i * 8192), 16, 0, 0); } while (0)
; #define PG8_LDA(dst, b, h) do { _Pragma("unroll") for (int m = 0; m < 4; ++m) _Pragma("unroll") for (int k = 0; k < 2; ++k) dst[m][k] = *(const LAS bf16x8*)(lds + PG8_SA(b, h) + aoff + m * 2048 + k * 1024); } while (0)
; #define PG8_LDB(dst, b, h) do { _Pragma("unroll") for (int n = 0; n < 2; ++n) _Pragma("unroll") for (int k = 0; k < 2; ++k) dst[n][k] = *(const LAS bf16x8*)(lds + PG8_SB(b, h) + boff + n * 2048 + k * 1024); } while (0)
; #define PG8_MMA(ai, bj, At, Bt) do { __builtin_amdgcn_s_setprio(1); _Pragma("unroll") for (int m = 0; m < 4; ++m) _Pragma("unroll") for (int n = 0; n < 2; ++n) _Pragma("unroll") for (int k = 0; k < 2; ++k) \
;         acc[ai][bj][m][n] = __builtin_amdgcn_mfma_f32_16x16x32_bf16(Bt[n][k], At[m][k], acc[ai][bj][m][n], 0, 0, 0); __builtin_amdgcn_s_setprio(0); } while (0)
; #define PG8_WAIT_V(n) asm volatile("s_waitcnt vmcnt(" #n ")" ::: "memory")
; #define PG8_WAIT_L(n) asm volatile("s_waitcnt lgkmcnt(" #n ")" ::: "memory")
; #define PG8_BAR __builtin_amdgcn_s_barrier()
; #define PG8_SCHED __builtin_amdgcn_sched_barrier(0)
; template <class Epi>
; DI void gemm_phase(LAS unsigned char* lds, const int wid, const Gemm g, const Order& S, const Epi& E) {
;     ...
;             PG8_WAIT_V(8); PG8_WAIT_L(0); PG8_BAR; PG8_MMA(0, 0, At, B0); PG8_MMA(0, 1, At, B1); PG8_BAR; PG8_SCHED;
;             PG8_LDA(At, 0, 1); PG8_STAGE(PG8_SB(0, 0), b2, voffB); PG8_STAGE(PG8_SB(0, 1), b2 + hstepB, voffB); PG8_STAGE(PG8_SA(0, 0), a2, voffA);
;             PG8_WAIT_V(8); PG8_WAIT_L(0); PG8_BAR; PG8_MMA(1, 0, At, B0); PG8_MMA(1, 1, At, B1); PG8_BAR; PG8_SCHED;
;             PG8_LDB(B0, 1, 0); PG8_LDB(B1, 1, 1); PG8_SCHED; PG8_LDA(At, 1, 0); PG8_STAGE(PG8_SA(0, 1), a2 + hstepA, voffA);
;             PG8_WAIT_V(8); PG8_WAIT_L(0); PG8_BAR; PG8_MMA(0, 0, At, B0); PG8_MMA(0, 1, At, B1); PG8_BAR; PG8_SCHED;
	s_setprio 1
	v_mfma_f32_16x16x32_bf16 v[124:127], v[128:131], v[160:163], v[124:127]
	v_mfma_f32_16x16x32_bf16 v[120:123], v[136:139], v[160:163], v[120:123]
	v_mfma_f32_16x16x32_bf16 v[108:111], v[128:131], v[168:171], v[108:111]
	v_mfma_f32_16x16x32_bf16 v[104:107], v[136:139], v[168:171], v[104:107]
	v_mfma_f32_16x16x32_bf16 v[92:95], v[128:131], v[192:195], v[92:95]
	v_mfma_f32_16x16x32_bf16 v[88:91], v[136:139], v[192:195], v[88:91]
	v_mfma_f32_16x16x32_bf16 v[76:79], v[128:131], v[200:203], v[76:79]
	v_mfma_f32_16x16x32_bf16 v[72:75], v[136:139], v[200:203], v[72:75]
	v_mfma_f32_16x16x32_bf16 v[124:127], v[132:135], v[164:167], v[124:127]
	v_mfma_f32_16x16x32_bf16 v[120:123], v[140:143], v[164:167], v[120:123]
	v_mfma_f32_16x16x32_bf16 v[108:111], v[132:135], v[172:175], v[108:111]
	v_mfma_f32_16x16x32_bf16 v[104:107], v[140:143], v[172:175], v[104:107]
	v_mfma_f32_16x16x32_bf16 v[92:95], v[132:135], v[196:199], v[92:95]
	v_mfma_f32_16x16x32_bf16 v[88:91], v[140:143], v[196:199], v[88:91]
	v_mfma_f32_16x16x32_bf16 v[76:79], v[132:135], v[204:207], v[76:79]
	v_mfma_f32_16x16x32_bf16 v[72:75], v[140:143], v[204:207], v[72:75]
	v_mfma_f32_16x16x32_bf16 v[116:119], v[144:147], v[160:163], v[116:119]
	v_mfma_f32_16x16x32_bf16 v[112:115], v[152:155], v[160:163], v[112:115]
	v_mfma_f32_16x16x32_bf16 v[100:103], v[144:147], v[168:171], v[100:103]
	v_mfma_f32_16x16x32_bf16 v[96:99], v[152:155], v[168:171], v[96:99]
	v_mfma_f32_16x16x32_bf16 v[84:87], v[144:147], v[192:195], v[84:87]
	v_mfma_f32_16x16x32_bf16 v[80:83], v[152:155], v[192:195], v[80:83]
	v_mfma_f32_16x16x32_bf16 v[68:71], v[144:147], v[200:203], v[68:71]
	v_mfma_f32_16x16x32_bf16 v[64:67], v[152:155], v[200:203], v[64:67]
	v_mfma_f32_16x16x32_bf16 v[116:119], v[148:151], v[164:167], v[116:119]
	v_mfma_f32_16x16x32_bf16 v[112:115], v[156:159], v[164:167], v[112:115]
	v_mfma_f32_16x16x32_bf16 v[100:103], v[148:151], v[172:175], v[100:103]
	v_mfma_f32_16x16x32_bf16 v[96:99], v[156:159], v[172:175], v[96:99]
	v_mfma_f32_16x16x32_bf16 v[84:87], v[148:151], v[196:199], v[84:87]
	v_mfma_f32_16x16x32_bf16 v[80:83], v[156:159], v[196:199], v[80:83]
	v_mfma_f32_16x16x32_bf16 v[68:71], v[148:151], v[204:207], v[68:71]
	v_mfma_f32_16x16x32_bf16 v[64:67], v[156:159], v[204:207], v[64:67]
	s_setprio 0
	s_barrier
	s_add_i32 s63, s57, s94
	v_lshl_add_u64 v[214:215], s[48:49], 0, v[178:179]
	s_mov_b32 m0, s63
	ds_read_b128 v[160:163], v211 offset:16384
	ds_read_b128 v[164:167], v211 offset:17408
	ds_read_b128 v[168:171], v211 offset:18432
	ds_read_b128 v[172:175], v211 offset:19456
	ds_read_b128 v[192:195], v211 offset:20480
	ds_read_b128 v[196:199], v211 offset:21504
	ds_read_b128 v[200:203], v211 offset:22528
	ds_read_b128 v[204:207], v211 offset:23552
	global_load_lds_dwordx4 v[214:215], off
	s_add_i32 m0, s63, 0x2000
	s_add_u32 s66, s48, 0x40000
	v_lshl_add_u64 v[216:217], s[48:49], 0, v[182:183]
	s_addc_u32 s67, s49, 0
	s_add_i32 s63, s58, s94
	global_load_lds_dwordx4 v[216:217], off
	v_lshl_add_u64 v[218:219], s[66:67], 0, v[178:179]
	s_mov_b32 m0, s63
	v_lshl_add_u64 v[220:221], s[50:51], 0, v[180:181]
	global_load_lds_dwordx4 v[218:219], off
	v_lshl_add_u64 v[218:219], s[66:67], 0, v[182:183]
	s_add_i32 m0, s63, 0x2000
	s_nop 0
	global_load_lds_dwordx4 v[218:219], off
	v_lshl_add_u64 v[218:219], s[50:51], 0, v[176:177]
	s_mov_b32 m0, s25
	s_nop 0
	global_load_lds_dwordx4 v[218:219], off
	s_mov_b32 m0, s45
	s_nop 0
	global_load_lds_dwordx4 v[220:221], off
	s_waitcnt vmcnt(8)
	s_waitcnt lgkmcnt(0)
	s_barrier
	s_setprio 1
	v_mfma_f32_16x16x32_bf16 v[60:63], v[128:131], v[160:163], v[60:63]
	v_mfma_f32_16x16x32_bf16 v[56:59], v[136:139], v[160:163], v[56:59]
	v_mfma_f32_16x16x32_bf16 v[44:47], v[128:131], v[168:171], v[44:47]
	v_mfma_f32_16x16x32_bf16 v[40:43], v[136:139], v[168:171], v[40:43]
	v_mfma_f32_16x16x32_bf16 v[28:31], v[128:131], v[192:195], v[28:31]
	v_mfma_f32_16x16x32_bf16 v[24:27], v[136:139], v[192:195], v[24:27]
	v_mfma_f32_16x16x32_bf16 v[12:15], v[128:131], v[200:203], v[12:15]
	v_mfma_f32_16x16x32_bf16 v[8:11], v[136:139], v[200:203], v[8:11]
	v_mfma_f32_16x16x32_bf16 v[60:63], v[132:135], v[164:167], v[60:63]
	v_mfma_f32_16x16x32_bf16 v[56:59], v[140:143], v[164:167], v[56:59]
	v_mfma_f32_16x16x32_bf16 v[44:47], v[132:135], v[172:175], v[44:47]
	v_mfma_f32_16x16x32_bf16 v[40:43], v[140:143], v[172:175], v[40:43]
	v_mfma_f32_16x16x32_bf16 v[28:31], v[132:135], v[196:199], v[28:31]
	v_mfma_f32_16x16x32_bf16 v[24:27], v[140:143], v[196:199], v[24:27]
	v_mfma_f32_16x16x32_bf16 v[12:15], v[132:135], v[204:207], v[12:15]
	v_mfma_f32_16x16x32_bf16 v[8:11], v[140:143], v[204:207], v[8:11]
	v_mfma_f32_16x16x32_bf16 v[52:55], v[144:147], v[160:163], v[52:55]
	v_mfma_f32_16x16x32_bf16 v[48:51], v[152:155], v[160:163], v[48:51]
	v_mfma_f32_16x16x32_bf16 v[36:39], v[144:147], v[168:171], v[36:39]
	v_mfma_f32_16x16x32_bf16 v[32:35], v[152:155], v[168:171], v[32:35]
	v_mfma_f32_16x16x32_bf16 v[20:23], v[144:147], v[192:195], v[20:23]
	v_mfma_f32_16x16x32_bf16 v[16:19], v[152:155], v[192:195], v[16:19]
	v_mfma_f32_16x16x32_bf16 v[4:7], v[144:147], v[200:203], v[4:7]
	v_mfma_f32_16x16x32_bf16 v[0:3], v[152:155], v[200:203], v[0:3]
	v_mfma_f32_16x16x32_bf16 v[52:55], v[148:151], v[164:167], v[52:55]
	v_mfma_f32_16x16x32_bf16 v[48:51], v[156:159], v[164:167], v[48:51]
	v_mfma_f32_16x16x32_bf16 v[36:39], v[148:151], v[172:175], v[36:39]
	v_mfma_f32_16x16x32_bf16 v[32:35], v[156:159], v[172:175], v[32:35]
	v_mfma_f32_16x16x32_bf16 v[20:23], v[148:151], v[196:199], v[20:23]
	v_mfma_f32_16x16x32_bf16 v[16:19], v[156:159], v[196:199], v[16:19]
	v_mfma_f32_16x16x32_bf16 v[4:7], v[148:151], v[204:207], v[4:7]
	v_mfma_f32_16x16x32_bf16 v[0:3], v[156:159], v[204:207], v[0:3]
	s_setprio 0
	s_barrier
; #define PG8_STAGE(bufoff, gbase, voff) do { _Pragma("unroll") for (int _i = 0; _i < 2; ++_i) \
;         __builtin_amdgcn_global_load_lds((const unsigned*)((const char*)(gbase) + (voff)[_i]), (LAS unsigned*)(lds + (bufoff) + ldsw + _i * 8192), 16, 0, 0); } while (0)
; #define PG8_LDA(dst, b, h) do { _Pragma("unroll") for (int m = 0; m < 4; ++m) _Pragma("unroll") for (int k = 0; k < 2; ++k) dst[m][k] = *(const LAS bf16x8*)(lds + PG8_SA(b, h) + aoff + m * 2048 + k * 1024); } while (0)
; #define PG8_LDB(dst, b, h) do { _Pragma("unroll") for (int n = 0; n < 2; ++n) _Pragma("unroll") for (int k = 0; k < 2; ++k) dst[n][k] = *(const LAS bf16x8*)(lds + PG8_SB(b, h) + boff + n * 2048 + k * 1024); } while (0)
; #define PG8_MMA(ai, bj, At, Bt) do { __builtin_amdgcn_s_setprio(1); _Pragma("unroll") for (int m = 0; m < 4; ++m) _Pragma("unroll") for (int n = 0; n < 2; ++n) _Pragma("unroll") for (int k = 0; k < 2; ++k) \
;         acc[ai][bj][m][n] = __builtin_amdgcn_mfma_f32_16x16x32_bf16(Bt[n][k], At[m][k], acc[ai][bj][m][n], 0, 0, 0); __builtin_amdgcn_s_setprio(0); } while (0)
; #define PG8_WAIT_V(n) asm volatile("s_waitcnt vmcnt(" #n ")" ::: "memory")
; #define PG8_WAIT_L(n) asm volatile("s_waitcnt lgkmcnt(" #n ")" ::: "memory")
; #define PG8_BAR __builtin_amdgcn_s_barrier()
; #define PG8_SCHED __builtin_amdgcn_sched_barrier(0)
; template <class Epi>
; DI void gemm_phase(LAS unsigned char* lds, const int wid, const Gemm g, const Order& S, const Epi& E) {
;     ...
;             PG8_LDB(B0, 1, 0); PG8_LDB(B1, 1, 1); PG8_SCHED; PG8_LDA(At, 1, 0); PG8_STAGE(PG8_SA(0, 1), a2 + hstepA, voffA);
;             PG8_WAIT_V(8); PG8_WAIT_L(0); PG8_BAR; PG8_MMA(0, 0, At, B0); PG8_MMA(0, 1, At, B1); PG8_BAR; PG8_SCHED;
	s_add_i32 s63, 0, 0x18000
	s_add_i32 s65, 0, 0x1c000
	v_add_u32_e32 v140, s63, v208
	v_add_u32_e32 v156, s65, v208
	ds_read_b128 v[128:131], v140
	ds_read_b128 v[132:135], v140 offset:1024
	ds_read_b128 v[136:139], v140 offset:2048
	ds_read_b128 v[140:143], v140 offset:3072
	ds_read_b128 v[144:147], v156
	ds_read_b128 v[148:151], v156 offset:1024
	ds_read_b128 v[152:155], v156 offset:2048
	ds_read_b128 v[156:159], v156 offset:3072
	s_add_u32 s50, s50, 0x40000
	s_addc_u32 s51, s51, 0
	s_mov_b32 m0, s52
	v_lshl_add_u64 v[222:223], s[50:51], 0, v[176:177]
	ds_read_b128 v[160:163], v211 offset:32768
	ds_read_b128 v[164:167], v211 offset:33792
	ds_read_b128 v[168:171], v211 offset:34816
	ds_read_b128 v[172:175], v211 offset:35840
	ds_read_b128 v[192:195], v211 offset:36864
	ds_read_b128 v[196:199], v211 offset:37888
	ds_read_b128 v[200:203], v211 offset:38912
	ds_read_b128 v[204:207], v211 offset:39936
	global_load_lds_dwordx4 v[222:223], off
	v_lshl_add_u64 v[222:223], s[50:51], 0, v[180:181]
	s_mov_b32 m0, s53
	s_nop 0
	global_load_lds_dwordx4 v[222:223], off
	s_waitcnt vmcnt(8)
	s_waitcnt lgkmcnt(0)
	s_barrier
	s_setprio 1
	v_mfma_f32_16x16x32_bf16 v[124:127], v[128:131], v[160:163], v[124:127]
	v_mfma_f32_16x16x32_bf16 v[120:123], v[136:139], v[160:163], v[120:123]
	v_mfma_f32_16x16x32_bf16 v[108:111], v[128:131], v[168:171], v[108:111]
	v_mfma_f32_16x16x32_bf16 v[104:107], v[136:139], v[168:171], v[104:107]
	v_mfma_f32_16x16x32_bf16 v[92:95], v[128:131], v[192:195], v[92:95]
	v_mfma_f32_16x16x32_bf16 v[88:91], v[136:139], v[192:195], v[88:91]
	v_mfma_f32_16x16x32_bf16 v[76:79], v[128:131], v[200:203], v[76:79]
	v_mfma_f32_16x16x32_bf16 v[72:75], v[136:139], v[200:203], v[72:75]
	v_mfma_f32_16x16x32_bf16 v[124:127], v[132:135], v[164:167], v[124:127]
	v_mfma_f32_16x16x32_bf16 v[120:123], v[140:143], v[164:167], v[120:123]
	v_mfma_f32_16x16x32_bf16 v[108:111], v[132:135], v[172:175], v[108:111]
	v_mfma_f32_16x16x32_bf16 v[104:107], v[140:143], v[172:175], v[104:107]
	v_mfma_f32_16x16x32_bf16 v[92:95], v[132:135], v[196:199], v[92:95]
	v_mfma_f32_16x16x32_bf16 v[88:91], v[140:143], v[196:199], v[88:91]
	v_mfma_f32_16x16x32_bf16 v[76:79], v[132:135], v[204:207], v[76:79]
	v_mfma_f32_16x16x32_bf16 v[72:75], v[140:143], v[204:207], v[72:75]
	v_mfma_f32_16x16x32_bf16 v[116:119], v[144:147], v[160:163], v[116:119]
	v_mfma_f32_16x16x32_bf16 v[112:115], v[152:155], v[160:163], v[112:115]
	v_mfma_f32_16x16x32_bf16 v[100:103], v[144:147], v[168:171], v[100:103]
	v_mfma_f32_16x16x32_bf16 v[96:99], v[152:155], v[168:171], v[96:99]
	v_mfma_f32_16x16x32_bf16 v[84:87], v[144:147], v[192:195], v[84:87]
	v_mfma_f32_16x16x32_bf16 v[80:83], v[152:155], v[192:195], v[80:83]
	v_mfma_f32_16x16x32_bf16 v[68:71], v[144:147], v[200:203], v[68:71]
	v_mfma_f32_16x16x32_bf16 v[64:67], v[152:155], v[200:203], v[64:67]
	v_mfma_f32_16x16x32_bf16 v[116:119], v[148:151], v[164:167], v[116:119]
	v_mfma_f32_16x16x32_bf16 v[112:115], v[156:159], v[164:167], v[112:115]
	v_mfma_f32_16x16x32_bf16 v[100:103], v[148:151], v[172:175], v[100:103]
	v_mfma_f32_16x16x32_bf16 v[96:99], v[156:159], v[172:175], v[96:99]
	v_mfma_f32_16x16x32_bf16 v[84:87], v[148:151], v[196:199], v[84:87]
	v_mfma_f32_16x16x32_bf16 v[80:83], v[156:159], v[196:199], v[80:83]
	v_mfma_f32_16x16x32_bf16 v[68:71], v[148:151], v[204:207], v[68:71]
	v_mfma_f32_16x16x32_bf16 v[64:67], v[156:159], v[204:207], v[64:67]
	s_setprio 0
	s_barrier
; #define PG8_STAGE(bufoff, gbase, voff) do { _Pragma("unroll") for (int _i = 0; _i < 2; ++_i) \
;         __builtin_amdgcn_global_load_lds((const unsigned*)((const char*)(gbase) + (voff)[_i]), (LAS unsigned*)(lds + (bufoff) + ldsw + _i * 8192), 16, 0, 0); } while (0)
; #define PG8_LDA(dst, b, h) do { _Pragma("unroll") for (int m = 0; m < 4; ++m) _Pragma("unroll") for (int k = 0; k < 2; ++k) dst[m][k] = *(const LAS bf16x8*)(lds + PG8_SA(b, h) + aoff + m * 2048 + k * 1024); } while (0)
; #define PG8_MMA(ai, bj, At, Bt) do { __builtin_amdgcn_s_setprio(1); _Pragma("unroll") for (int m = 0; m < 4; ++m) _Pragma("unroll") for (int n = 0; n < 2; ++n) _Pragma("unroll") for (int k = 0; k < 2; ++k) \
;         acc[ai][bj][m][n] = __builtin_amdgcn_mfma_f32_16x16x32_bf16(Bt[n][k], At[m][k], acc[ai][bj][m][n], 0, 0, 0); __builtin_amdgcn_s_setprio(0); } while (0)
; #define PG8_WAIT_V(n) asm volatile("s_waitcnt vmcnt(" #n ")" ::: "memory")
; #define PG8_WAIT_L(n) asm volatile("s_waitcnt lgkmcnt(" #n ")" ::: "memory")
; #define PG8_BAR __builtin_amdgcn_s_barrier()
; #define PG8_SCHED __builtin_amdgcn_sched_barrier(0)
; template <class Epi>
; DI void gemm_phase(LAS unsigned char* lds, const int wid, const Gemm g, const Order& S, const Epi& E) {
;     ...
;         for (int t = 0; t < nt; t += 2) {
;     ...
;             PG8_LDA(At, 1, 1); PG8_STAGE(PG8_SB(1, 0), b3, voffB); PG8_STAGE(PG8_SB(1, 1), b3 + hstepB, voffB); PG8_STAGE(PG8_SA(1, 0), a3, voffA);
;             PG8_WAIT_V(8); PG8_WAIT_L(0); PG8_BAR; PG8_MMA(1, 0, At, B0); PG8_MMA(1, 1, At, B1); PG8_BAR; PG8_SCHED;
	s_add_i32 s50, s63, s94
	v_lshl_add_u64 v[214:215], v[214:215], 0, s[30:31]
	s_mov_b32 m0, s50
	ds_read_b128 v[160:163], v211 offset:49152
	ds_read_b128 v[164:167], v211 offset:50176
	ds_read_b128 v[168:171], v211 offset:51200
	ds_read_b128 v[172:175], v211 offset:52224
	ds_read_b128 v[192:195], v211 offset:53248
	ds_read_b128 v[196:199], v211 offset:54272
	ds_read_b128 v[200:203], v211 offset:55296
	ds_read_b128 v[204:207], v211 offset:56320
	global_load_lds_dwordx4 v[214:215], off
	s_add_i32 m0, s50, 0x2000
	s_add_u32 s48, s48, 0x40080
	v_lshl_add_u64 v[214:215], v[216:217], 0, s[30:31]
	s_addc_u32 s49, s49, 0
	s_add_i32 s50, s65, s94
	global_load_lds_dwordx4 v[214:215], off
	v_lshl_add_u64 v[214:215], s[48:49], 0, v[178:179]
	s_mov_b32 m0, s50
	s_nop 0
	global_load_lds_dwordx4 v[214:215], off
	v_lshl_add_u64 v[214:215], s[48:49], 0, v[182:183]
	s_add_i32 m0, s50, 0x2000
	s_nop 0
	global_load_lds_dwordx4 v[214:215], off
	v_lshl_add_u64 v[214:215], v[218:219], 0, s[30:31]
	s_mov_b32 m0, s55
	s_nop 0
	global_load_lds_dwordx4 v[214:215], off
	v_lshl_add_u64 v[214:215], v[220:221], 0, s[30:31]
	s_mov_b32 m0, s56
	s_nop 0
	global_load_lds_dwordx4 v[214:215], off
	s_waitcnt vmcnt(8)
	s_waitcnt lgkmcnt(0)
	s_barrier
	s_setprio 1
	v_mfma_f32_16x16x32_bf16 v[60:63], v[128:131], v[160:163], v[60:63]
	v_mfma_f32_16x16x32_bf16 v[56:59], v[136:139], v[160:163], v[56:59]
	v_mfma_f32_16x16x32_bf16 v[44:47], v[128:131], v[168:171], v[44:47]
	v_mfma_f32_16x16x32_bf16 v[40:43], v[136:139], v[168:171], v[40:43]
	v_mfma_f32_16x16x32_bf16 v[28:31], v[128:131], v[192:195], v[28:31]
	v_mfma_f32_16x16x32_bf16 v[24:27], v[136:139], v[192:195], v[24:27]
	v_mfma_f32_16x16x32_bf16 v[12:15], v[128:131], v[200:203], v[12:15]
	v_mfma_f32_16x16x32_bf16 v[8:11], v[136:139], v[200:203], v[8:11]
	v_mfma_f32_16x16x32_bf16 v[60:63], v[132:135], v[164:167], v[60:63]
	v_mfma_f32_16x16x32_bf16 v[56:59], v[140:143], v[164:167], v[56:59]
	v_mfma_f32_16x16x32_bf16 v[44:47], v[132:135], v[172:175], v[44:47]
	v_mfma_f32_16x16x32_bf16 v[40:43], v[140:143], v[172:175], v[40:43]
	v_mfma_f32_16x16x32_bf16 v[28:31], v[132:135], v[196:199], v[28:31]
	v_mfma_f32_16x16x32_bf16 v[24:27], v[140:143], v[196:199], v[24:27]
	v_mfma_f32_16x16x32_bf16 v[12:15], v[132:135], v[204:207], v[12:15]
	v_mfma_f32_16x16x32_bf16 v[8:11], v[140:143], v[204:207], v[8:11]
	v_mfma_f32_16x16x32_bf16 v[52:55], v[144:147], v[160:163], v[52:55]
	v_mfma_f32_16x16x32_bf16 v[48:51], v[152:155], v[160:163], v[48:51]
	v_mfma_f32_16x16x32_bf16 v[36:39], v[144:147], v[168:171], v[36:39]
	v_mfma_f32_16x16x32_bf16 v[32:35], v[152:155], v[168:171], v[32:35]
	v_mfma_f32_16x16x32_bf16 v[20:23], v[144:147], v[192:195], v[20:23]
	v_mfma_f32_16x16x32_bf16 v[16:19], v[152:155], v[192:195], v[16:19]
	v_mfma_f32_16x16x32_bf16 v[4:7], v[144:147], v[200:203], v[4:7]
	v_mfma_f32_16x16x32_bf16 v[0:3], v[152:155], v[200:203], v[0:3]
	v_mfma_f32_16x16x32_bf16 v[52:55], v[148:151], v[164:167], v[52:55]
	v_mfma_f32_16x16x32_bf16 v[48:51], v[156:159], v[164:167], v[48:51]
	v_mfma_f32_16x16x32_bf16 v[36:39], v[148:151], v[172:175], v[36:39]
	v_mfma_f32_16x16x32_bf16 v[32:35], v[156:159], v[172:175], v[32:35]
	v_mfma_f32_16x16x32_bf16 v[20:23], v[148:151], v[196:199], v[20:23]
	v_mfma_f32_16x16x32_bf16 v[16:19], v[156:159], v[196:199], v[16:19]
	v_mfma_f32_16x16x32_bf16 v[4:7], v[148:151], v[204:207], v[4:7]
	v_mfma_f32_16x16x32_bf16 v[0:3], v[156:159], v[204:207], v[0:3]
	s_setprio 0
	s_barrier
	s_add_i32 s62, s62, 2
	s_add_u32 s46, s46, 0x100
	s_addc_u32 s47, s47, 0
	s_add_u32 s60, s60, 0x100
	s_addc_u32 s61, s61, 0
	s_cmp_gt_u32 s62, 13
	s_cbranch_scc0 .LBB0_1250

; #define PG8_STAGE(bufoff, gbase, voff) do { _Pragma("unroll") for (int _i = 0; _i < 2; ++_i) \
;         __builtin_amdgcn_global_load_lds((const unsigned*)((const char*)(gbase) + (voff)[_i]), (LAS unsigned*)(lds + (bufoff) + ldsw + _i * 8192), 16, 0, 0); } while (0)
; #define PG8_LDA(dst, b, h) do { _Pragma("unroll") for (int m = 0; m < 4; ++m) _Pragma("unroll") for (int k = 0; k < 2; ++k) dst[m][k] = *(const LAS bf16x8*)(lds + PG8_SA(b, h) + aoff + m * 2048 + k * 1024); } while (0)
; #define PG8_LDB(dst, b, h) do { _Pragma("unroll") for (int n = 0; n < 2; ++n) _Pragma("unroll") for (int k = 0; k < 2; ++k) dst[n][k] = *(const LAS bf16x8*)(lds + PG8_SB(b, h) + boff + n * 2048 + k * 1024); } while (0)
; #define PG8_MMA(ai, bj, At, Bt) do { __builtin_amdgcn_s_setprio(1); _Pragma("unroll") for (int m = 0; m < 4; ++m) _Pragma("unroll") for (int n = 0; n < 2; ++n) _Pragma("unroll") for (int k = 0; k < 2; ++k) \
;         acc[ai][bj][m][n] = __builtin_amdgcn_mfma_f32_16x16x32_bf16(Bt[n][k], At[m][k], acc[ai][bj][m][n], 0, 0, 0); __builtin_amdgcn_s_setprio(0); } while (0)
; #define PG8_WAIT_V(n) asm volatile("s_waitcnt vmcnt(" #n ")" ::: "memory")
; template <class Epi>
; DI void gemm_phase(LAS unsigned char* lds, const int wid, const Gemm g, const Order& S, const Epi& E) {
;     ...
;         const char* nA = has_next ? (const char*)(g.A + (size_t)nxt.g * g.gsA + (size_t)nxt.pm * BM * g.lda) : cA;
;         const char* nB = has_next ? (const char*)(g.Bt + (size_t)nxt.g * g.gsB + (size_t)nxt.pn * BM * g.ldb) : cB;
;         for (int t = 0; t < nt; t += 2) {
;             const bool last = (t == nt - 2);
;             const char* a1 = cA + (size_t)(t + 1) * kstep;
;             const char* a2 = last ? nA : cA + (size_t)(t + 2) * kstep; const char* b2 = last ? nB : cB + (size_t)(t + 2) * kstep;
;             const char* a3 = a2 + kstep; const char* b3 = b2 + kstep;
;             PG8_LDB(B0, 0, 0); PG8_LDB(B1, 0, 1); PG8_SCHED; PG8_LDA(At, 0, 0); PG8_STAGE(PG8_SA(1, 1), a1 + hstepA, voffA);
;             PG8_WAIT_V(8); PG8_WAIT_L(0); PG8_BAR; PG8_MMA(0, 0, At, B0); PG8_MMA(0, 1, At, B1); PG8_BAR; PG8_SCHED;
;             PG8_LDA(At, 0, 1); PG8_STAGE(PG8_SB(0, 0), b2, voffB); PG8_STAGE(PG8_SB(0, 1), b2 + hstepB, voffB); PG8_STAGE(PG8_SA(0, 0), a2, voffA);
;             PG8_WAIT_V(8); PG8_WAIT_L(0); PG8_BAR; PG8_MMA(1, 0, At, B0); PG8_MMA(1, 1, At, B1); PG8_BAR; PG8_SCHED;
.LBB0_1335:
	s_ashr_i32 s27, s26, 31
	s_lshl_b64 s[30:31], s[26:27], 19
	s_add_u32 s30, s6, s30
	s_addc_u32 s31, s7, s31
	s_and_b64 s[34:35], s[8:9], exec
	s_cselect_b32 s27, s31, s39
	s_cselect_b32 s56, s30, s38
	s_ashr_i32 s29, s28, 31
	s_lshl_b64 s[34:35], s[28:29], 19
	s_add_u32 s34, s21, s34
	s_addc_u32 s35, s44, s35
	s_and_b64 s[42:43], s[8:9], exec
	s_cselect_b32 s29, s35, s41
	s_cselect_b32 s57, s34, s40
	s_add_u32 s38, s38, 0x40080
	s_addc_u32 s39, s39, 0
	s_add_u32 s58, s40, 0x100
	v_mov_b32_e32 v0, 0
	s_addc_u32 s59, s41, 0
	s_mov_b32 s60, -2
	ds_read_b128 v[164:167], v151
	ds_read_b128 v[168:171], v151 offset:1024
	ds_read_b128 v[172:175], v151 offset:2048
	ds_read_b128 v[176:179], v151 offset:3072
	ds_read_b128 v[180:183], v155
	ds_read_b128 v[184:187], v155 offset:1024
	ds_read_b128 v[188:191], v155 offset:2048
	ds_read_b128 v[192:195], v155 offset:3072
	s_add_u32 s40, s38, 0xfffc0080
	s_addc_u32 s41, s39, -1
	s_cmp_eq_u32 s60, 12
	s_cselect_b32 s43, s27, s41
	s_cselect_b32 s42, s56, s40
	s_cselect_b32 s41, s29, s59
	s_cselect_b32 s40, s57, s58
	v_lshl_add_u64 v[144:145], s[38:39], 0, v[136:137]
	s_add_i32 m0, s37, 0xc000
	ds_read_b128 v[196:199], v159
	ds_read_b128 v[200:203], v159 offset:1024
	ds_read_b128 v[204:207], v159 offset:2048
	ds_read_b128 v[208:211], v159 offset:3072
	ds_read_b128 v[212:215], v159 offset:4096
	ds_read_b128 v[216:219], v159 offset:5120
	ds_read_b128 v[220:223], v159 offset:6144
	ds_read_b128 v[224:227], v159 offset:7168
	global_load_lds_dwordx4 v[144:145], off
	v_lshl_add_u64 v[144:145], s[38:39], 0, v[138:139]
	s_add_i32 m0, s37, 0xe000
	s_nop 0
	global_load_lds_dwordx4 v[144:145], off
	s_waitcnt vmcnt(8)
	s_waitcnt lgkmcnt(0)
	s_barrier
	s_setprio 1
	v_mfma_f32_16x16x32_bf16 v[124:127], v[164:167], v[196:199], 0
	v_mfma_f32_16x16x32_bf16 v[120:123], v[172:175], v[196:199], 0
	v_mfma_f32_16x16x32_bf16 v[108:111], v[164:167], v[204:207], 0
	v_mfma_f32_16x16x32_bf16 v[104:107], v[172:175], v[204:207], 0
	v_mfma_f32_16x16x32_bf16 v[92:95], v[164:167], v[212:215], 0
	v_mfma_f32_16x16x32_bf16 v[88:91], v[172:175], v[212:215], 0
	v_mfma_f32_16x16x32_bf16 v[76:79], v[164:167], v[220:223], 0
	v_mfma_f32_16x16x32_bf16 v[72:75], v[172:175], v[220:223], 0
	v_mfma_f32_16x16x32_bf16 v[124:127], v[168:171], v[200:203], v[124:127]
	v_mfma_f32_16x16x32_bf16 v[120:123], v[176:179], v[200:203], v[120:123]
	v_mfma_f32_16x16x32_bf16 v[108:111], v[168:171], v[208:211], v[108:111]
	v_mfma_f32_16x16x32_bf16 v[104:107], v[176:179], v[208:211], v[104:107]
	v_mfma_f32_16x16x32_bf16 v[92:95], v[168:171], v[216:219], v[92:95]
	v_mfma_f32_16x16x32_bf16 v[88:91], v[176:179], v[216:219], v[88:91]
	v_mfma_f32_16x16x32_bf16 v[76:79], v[168:171], v[224:227], v[76:79]
	v_mfma_f32_16x16x32_bf16 v[72:75], v[176:179], v[224:227], v[72:75]
	v_mfma_f32_16x16x32_bf16 v[116:119], v[180:183], v[196:199], 0
	v_mfma_f32_16x16x32_bf16 v[112:115], v[188:191], v[196:199], 0
	v_mfma_f32_16x16x32_bf16 v[100:103], v[180:183], v[204:207], 0
	v_mfma_f32_16x16x32_bf16 v[96:99], v[188:191], v[204:207], 0
	v_mfma_f32_16x16x32_bf16 v[84:87], v[180:183], v[212:215], 0
	v_mfma_f32_16x16x32_bf16 v[80:83], v[188:191], v[212:215], 0
	v_mfma_f32_16x16x32_bf16 v[68:71], v[180:183], v[220:223], 0
	v_mfma_f32_16x16x32_bf16 v[64:67], v[188:191], v[220:223], 0
	v_mfma_f32_16x16x32_bf16 v[116:119], v[184:187], v[200:203], v[116:119]
	v_mfma_f32_16x16x32_bf16 v[112:115], v[192:195], v[200:203], v[112:115]
	v_mfma_f32_16x16x32_bf16 v[100:103], v[184:187], v[208:211], v[100:103]
	v_mfma_f32_16x16x32_bf16 v[96:99], v[192:195], v[208:211], v[96:99]
	v_mfma_f32_16x16x32_bf16 v[84:87], v[184:187], v[216:219], v[84:87]
	v_mfma_f32_16x16x32_bf16 v[80:83], v[192:195], v[216:219], v[80:83]
	v_mfma_f32_16x16x32_bf16 v[68:71], v[184:187], v[224:227], v[68:71]
	v_mfma_f32_16x16x32_bf16 v[64:67], v[192:195], v[224:227], v[64:67]
	s_setprio 0
	s_barrier
	s_add_i32 s61, s53, s94
	v_lshl_add_u64 v[144:145], s[40:41], 0, v[132:133]
	s_mov_b32 m0, s61
	ds_read_b128 v[196:199], v159 offset:16384
	ds_read_b128 v[200:203], v159 offset:17408
	ds_read_b128 v[204:207], v159 offset:18432
	ds_read_b128 v[208:211], v159 offset:19456
	ds_read_b128 v[212:215], v159 offset:20480
	ds_read_b128 v[216:219], v159 offset:21504
	ds_read_b128 v[220:223], v159 offset:22528
	ds_read_b128 v[224:227], v159 offset:23552
	global_load_lds_dwordx4 v[144:145], off
	s_add_i32 m0, s61, 0x2000
	s_add_u32 s62, s40, 0x40000
	v_lshl_add_u64 v[148:149], s[40:41], 0, v[128:129]
	s_addc_u32 s63, s41, 0
	s_add_i32 s61, s54, s94
	global_load_lds_dwordx4 v[148:149], off
	v_lshl_add_u64 v[152:153], s[62:63], 0, v[132:133]
	s_mov_b32 m0, s61
	v_lshl_add_u64 v[156:157], s[42:43], 0, v[130:131]
	global_load_lds_dwordx4 v[152:153], off
	v_lshl_add_u64 v[152:153], s[62:63], 0, v[128:129]
	s_add_i32 m0, s61, 0x2000
	s_nop 0
	global_load_lds_dwordx4 v[152:153], off
	v_lshl_add_u64 v[152:153], s[42:43], 0, v[134:135]
	s_mov_b32 m0, s37
	s_nop 0
	global_load_lds_dwordx4 v[152:153], off
	s_mov_b32 m0, s46
	s_nop 0
	global_load_lds_dwordx4 v[156:157], off
	s_waitcnt vmcnt(8)
	s_waitcnt lgkmcnt(0)
	s_barrier
; #define PG8_STAGE(bufoff, gbase, voff) do { _Pragma("unroll") for (int _i = 0; _i < 2; ++_i) \
;         __builtin_amdgcn_global_load_lds((const unsigned*)((const char*)(gbase) + (voff)[_i]), (LAS unsigned*)(lds + (bufoff) + ldsw + _i * 8192), 16, 0, 0); } while (0)
; #define PG8_LDA(dst, b, h) do { _Pragma("unroll") for (int m = 0; m < 4; ++m) _Pragma("unroll") for (int k = 0; k < 2; ++k) dst[m][k] = *(const LAS bf16x8*)(lds + PG8_SA(b, h) + aoff + m * 2048 + k * 1024); } while (0)
; #define PG8_LDB(dst, b, h) do { _Pragma("unroll") for (int n = 0; n < 2; ++n) _Pragma("unroll") for (int k = 0; k < 2; ++k) dst[n][k] = *(const LAS bf16x8*)(lds + PG8_SB(b, h) + boff + n * 2048 + k * 1024); } while (0)
; #define PG8_MMA(ai, bj, At, Bt) do { __builtin_amdgcn_s_setprio(1); _Pragma("unroll") for (int m = 0; m < 4; ++m) _Pragma("unroll") for (int n = 0; n < 2; ++n) _Pragma("unroll") for (int k = 0; k < 2; ++k) \
;         acc[ai][bj][m][n] = __builtin_amdgcn_mfma_f32_16x16x32_bf16(Bt[n][k], At[m][k], acc[ai][bj][m][n], 0, 0, 0); __builtin_amdgcn_s_setprio(0); } while (0)
; #define PG8_WAIT_V(n) asm volatile("s_waitcnt vmcnt(" #n ")" ::: "memory")
; #define PG8_WAIT_L(n) asm volatile("s_waitcnt lgkmcnt(" #n ")" ::: "memory")
; #define PG8_BAR __builtin_amdgcn_s_barrier()
; #define PG8_SCHED __builtin_amdgcn_sched_barrier(0)
; template <class Epi>
; DI void gemm_phase(LAS unsigned char* lds, const int wid, const Gemm g, const Order& S, const Epi& E) {
;     ...
;             PG8_WAIT_V(8); PG8_WAIT_L(0); PG8_BAR; PG8_MMA(1, 0, At, B0); PG8_MMA(1, 1, At, B1); PG8_BAR; PG8_SCHED;
;             PG8_LDB(B0, 1, 0); PG8_LDB(B1, 1, 1); PG8_SCHED; PG8_LDA(At, 1, 0); PG8_STAGE(PG8_SA(0, 1), a2 + hstepA, voffA);
;             PG8_WAIT_V(8); PG8_WAIT_L(0); PG8_BAR; PG8_MMA(0, 0, At, B0); PG8_MMA(0, 1, At, B1); PG8_BAR; PG8_SCHED;
;             PG8_LDA(At, 1, 1); PG8_STAGE(PG8_SB(1, 0), b3, voffB); PG8_STAGE(PG8_SB(1, 1), b3 + hstepB, voffB); PG8_STAGE(PG8_SA(1, 0), a3, voffA);
;             PG8_WAIT_V(8); PG8_WAIT_L(0); PG8_BAR; PG8_MMA(1, 0, At, B0); PG8_MMA(1, 1, At, B1); PG8_BAR; PG8_SCHED;
	s_setprio 1
	v_mfma_f32_16x16x32_bf16 v[60:63], v[164:167], v[196:199], 0
	v_mfma_f32_16x16x32_bf16 v[56:59], v[172:175], v[196:199], 0
	v_mfma_f32_16x16x32_bf16 v[44:47], v[164:167], v[204:207], 0
	v_mfma_f32_16x16x32_bf16 v[40:43], v[172:175], v[204:207], 0
	v_mfma_f32_16x16x32_bf16 v[28:31], v[164:167], v[212:215], 0
	v_mfma_f32_16x16x32_bf16 v[24:27], v[172:175], v[212:215], 0
	v_mfma_f32_16x16x32_bf16 v[12:15], v[164:167], v[220:223], 0
	v_mfma_f32_16x16x32_bf16 v[8:11], v[172:175], v[220:223], 0
	v_mfma_f32_16x16x32_bf16 v[60:63], v[168:171], v[200:203], v[60:63]
	v_mfma_f32_16x16x32_bf16 v[56:59], v[176:179], v[200:203], v[56:59]
	v_mfma_f32_16x16x32_bf16 v[44:47], v[168:171], v[208:211], v[44:47]
	v_mfma_f32_16x16x32_bf16 v[40:43], v[176:179], v[208:211], v[40:43]
	v_mfma_f32_16x16x32_bf16 v[28:31], v[168:171], v[216:219], v[28:31]
	v_mfma_f32_16x16x32_bf16 v[24:27], v[176:179], v[216:219], v[24:27]
	v_mfma_f32_16x16x32_bf16 v[12:15], v[168:171], v[224:227], v[12:15]
	v_mfma_f32_16x16x32_bf16 v[8:11], v[176:179], v[224:227], v[8:11]
	v_mfma_f32_16x16x32_bf16 v[52:55], v[180:183], v[196:199], 0
	v_mfma_f32_16x16x32_bf16 v[48:51], v[188:191], v[196:199], 0
	v_mfma_f32_16x16x32_bf16 v[36:39], v[180:183], v[204:207], 0
	v_mfma_f32_16x16x32_bf16 v[32:35], v[188:191], v[204:207], 0
	v_mfma_f32_16x16x32_bf16 v[20:23], v[180:183], v[212:215], 0
	v_mfma_f32_16x16x32_bf16 v[16:19], v[188:191], v[212:215], 0
	v_mfma_f32_16x16x32_bf16 v[4:7], v[180:183], v[220:223], 0
	v_mfma_f32_16x16x32_bf16 v[0:3], v[188:191], v[220:223], 0
	v_mfma_f32_16x16x32_bf16 v[52:55], v[184:187], v[200:203], v[52:55]
	v_mfma_f32_16x16x32_bf16 v[48:51], v[192:195], v[200:203], v[48:51]
	v_mfma_f32_16x16x32_bf16 v[36:39], v[184:187], v[208:211], v[36:39]
	v_mfma_f32_16x16x32_bf16 v[32:35], v[192:195], v[208:211], v[32:35]
	v_mfma_f32_16x16x32_bf16 v[20:23], v[184:187], v[216:219], v[20:23]
	v_mfma_f32_16x16x32_bf16 v[16:19], v[192:195], v[216:219], v[16:19]
	v_mfma_f32_16x16x32_bf16 v[4:7], v[184:187], v[224:227], v[4:7]
	v_mfma_f32_16x16x32_bf16 v[0:3], v[192:195], v[224:227], v[0:3]
	s_setprio 0
	s_barrier
	s_add_i32 s61, 0, 0x18000
	v_add_u32_e32 v146, s61, v147
	s_add_i32 s62, 0, 0x1c000
	ds_read_b128 v[164:167], v146
	ds_read_b128 v[168:171], v146 offset:1024
	ds_read_b128 v[172:175], v146 offset:2048
	ds_read_b128 v[176:179], v146 offset:3072
	v_add_u32_e32 v146, s62, v147
	ds_read_b128 v[180:183], v146
	ds_read_b128 v[184:187], v146 offset:1024
	ds_read_b128 v[188:191], v146 offset:2048
	ds_read_b128 v[192:195], v146 offset:3072
	s_add_u32 s42, s42, 0x40000
	s_addc_u32 s43, s43, 0
	s_mov_b32 m0, s47
	v_lshl_add_u64 v[160:161], s[42:43], 0, v[134:135]
	ds_read_b128 v[196:199], v159 offset:32768
	ds_read_b128 v[200:203], v159 offset:33792
	ds_read_b128 v[204:207], v159 offset:34816
	ds_read_b128 v[208:211], v159 offset:35840
	ds_read_b128 v[212:215], v159 offset:36864
	ds_read_b128 v[216:219], v159 offset:37888
	ds_read_b128 v[220:223], v159 offset:38912
	ds_read_b128 v[224:227], v159 offset:39936
	global_load_lds_dwordx4 v[160:161], off
	v_lshl_add_u64 v[160:161], s[42:43], 0, v[130:131]
	s_mov_b32 m0, s48
	s_nop 0
	global_load_lds_dwordx4 v[160:161], off
	s_waitcnt vmcnt(8)
	s_waitcnt lgkmcnt(0)
	s_barrier
	s_setprio 1
	v_mfma_f32_16x16x32_bf16 v[124:127], v[164:167], v[196:199], v[124:127]
	v_mfma_f32_16x16x32_bf16 v[120:123], v[172:175], v[196:199], v[120:123]
	v_mfma_f32_16x16x32_bf16 v[108:111], v[164:167], v[204:207], v[108:111]
	v_mfma_f32_16x16x32_bf16 v[104:107], v[172:175], v[204:207], v[104:107]
	v_mfma_f32_16x16x32_bf16 v[92:95], v[164:167], v[212:215], v[92:95]
	v_mfma_f32_16x16x32_bf16 v[88:91], v[172:175], v[212:215], v[88:91]
	v_mfma_f32_16x16x32_bf16 v[76:79], v[164:167], v[220:223], v[76:79]
	v_mfma_f32_16x16x32_bf16 v[72:75], v[172:175], v[220:223], v[72:75]
	v_mfma_f32_16x16x32_bf16 v[124:127], v[168:171], v[200:203], v[124:127]
	v_mfma_f32_16x16x32_bf16 v[120:123], v[176:179], v[200:203], v[120:123]
	v_mfma_f32_16x16x32_bf16 v[108:111], v[168:171], v[208:211], v[108:111]
	v_mfma_f32_16x16x32_bf16 v[104:107], v[176:179], v[208:211], v[104:107]
	v_mfma_f32_16x16x32_bf16 v[92:95], v[168:171], v[216:219], v[92:95]
	v_mfma_f32_16x16x32_bf16 v[88:91], v[176:179], v[216:219], v[88:91]
	v_mfma_f32_16x16x32_bf16 v[76:79], v[168:171], v[224:227], v[76:79]
	v_mfma_f32_16x16x32_bf16 v[72:75], v[176:179], v[224:227], v[72:75]
	v_mfma_f32_16x16x32_bf16 v[116:119], v[180:183], v[196:199], v[116:119]
	v_mfma_f32_16x16x32_bf16 v[112:115], v[188:191], v[196:199], v[112:115]
	v_mfma_f32_16x16x32_bf16 v[100:103], v[180:183], v[204:207], v[100:103]
	v_mfma_f32_16x16x32_bf16 v[96:99], v[188:191], v[204:207], v[96:99]
	v_mfma_f32_16x16x32_bf16 v[84:87], v[180:183], v[212:215], v[84:87]
	v_mfma_f32_16x16x32_bf16 v[80:83], v[188:191], v[212:215], v[80:83]
	v_mfma_f32_16x16x32_bf16 v[68:71], v[180:183], v[220:223], v[68:71]
	v_mfma_f32_16x16x32_bf16 v[64:67], v[188:191], v[220:223], v[64:67]
	v_mfma_f32_16x16x32_bf16 v[116:119], v[184:187], v[200:203], v[116:119]
	v_mfma_f32_16x16x32_bf16 v[112:115], v[192:195], v[200:203], v[112:115]
	v_mfma_f32_16x16x32_bf16 v[100:103], v[184:187], v[208:211], v[100:103]
	v_mfma_f32_16x16x32_bf16 v[96:99], v[192:195], v[208:211], v[96:99]
	v_mfma_f32_16x16x32_bf16 v[84:87], v[184:187], v[216:219], v[84:87]
	v_mfma_f32_16x16x32_bf16 v[80:83], v[192:195], v[216:219], v[80:83]
	v_mfma_f32_16x16x32_bf16 v[68:71], v[184:187], v[224:227], v[68:71]
	v_mfma_f32_16x16x32_bf16 v[64:67], v[192:195], v[224:227], v[64:67]
	s_setprio 0
	s_barrier
; #define PG8_STAGE(bufoff, gbase, voff) do { _Pragma("unroll") for (int _i = 0; _i < 2; ++_i) \
;         __builtin_amdgcn_global_load_lds((const unsigned*)((const char*)(gbase) + (voff)[_i]), (LAS unsigned*)(lds + (bufoff) + ldsw + _i * 8192), 16, 0, 0); } while (0)
; #define PG8_LDA(dst, b, h) do { _Pragma("unroll") for (int m = 0; m < 4; ++m) _Pragma("unroll") for (int k = 0; k < 2; ++k) dst[m][k] = *(const LAS bf16x8*)(lds + PG8_SA(b, h) + aoff + m * 2048 + k * 1024); } while (0)
; #define PG8_LDB(dst, b, h) do { _Pragma("unroll") for (int n = 0; n < 2; ++n) _Pragma("unroll") for (int k = 0; k < 2; ++k) dst[n][k] = *(const LAS bf16x8*)(lds + PG8_SB(b, h) + boff + n * 2048 + k * 1024); } while (0)
; #define PG8_MMA(ai, bj, At, Bt) do { __builtin_amdgcn_s_setprio(1); _Pragma("unroll") for (int m = 0; m < 4; ++m) _Pragma("unroll") for (int n = 0; n < 2; ++n) _Pragma("unroll") for (int k = 0; k < 2; ++k) \
;         acc[ai][bj][m][n] = __builtin_amdgcn_mfma_f32_16x16x32_bf16(Bt[n][k], At[m][k], acc[ai][bj][m][n], 0, 0, 0); __builtin_amdgcn_s_setprio(0); } while (0)
; #define PG8_WAIT_V(n) asm volatile("s_waitcnt vmcnt(" #n ")" ::: "memory")
; #define PG8_WAIT_L(n) asm volatile("s_waitcnt lgkmcnt(" #n ")" ::: "memory")
; template <class Epi>
; DI void gemm_phase(LAS unsigned char* lds, const int wid, const Gemm g, const Order& S, const Epi& E) {
;     ...
;             PG8_LDB(B0, 0, 0); PG8_LDB(B1, 0, 1); PG8_SCHED; PG8_LDA(At, 0, 0); PG8_STAGE(PG8_SA(1, 1), a1 + hstepA, voffA);
;             PG8_WAIT_V(8); PG8_WAIT_L(0); PG8_BAR; PG8_MMA(0, 0, At, B0); PG8_MMA(0, 1, At, B1); PG8_BAR; PG8_SCHED;
;             PG8_LDA(At, 0, 1); PG8_STAGE(PG8_SB(0, 0), b2, voffB); PG8_STAGE(PG8_SB(0, 1), b2 + hstepB, voffB); PG8_STAGE(PG8_SA(0, 0), a2, voffA);
;             PG8_WAIT_V(8); PG8_WAIT_L(0); PG8_BAR; PG8_MMA(1, 0, At, B0); PG8_MMA(1, 1, At, B1); PG8_BAR; PG8_SCHED;
;             PG8_LDB(B0, 1, 0); PG8_LDB(B1, 1, 1); PG8_SCHED; PG8_LDA(At, 1, 0); PG8_STAGE(PG8_SA(0, 1), a2 + hstepA, voffA);
;             PG8_WAIT_V(8); PG8_WAIT_L(0); PG8_BAR; PG8_MMA(0, 0, At, B0); PG8_MMA(0, 1, At, B1); PG8_BAR; PG8_SCHED;
;             PG8_LDA(At, 1, 1); PG8_STAGE(PG8_SB(1, 0), b3, voffB); PG8_STAGE(PG8_SB(1, 1), b3 + hstepB, voffB); PG8_STAGE(PG8_SA(1, 0), a3, voffA);
;             PG8_WAIT_V(8); PG8_WAIT_L(0); PG8_BAR; PG8_MMA(1, 0, At, B0); PG8_MMA(1, 1, At, B1); PG8_BAR; PG8_SCHED;
	s_add_i32 s42, s61, s94
	v_lshl_add_u64 v[144:145], v[144:145], 0, s[16:17]
	s_mov_b32 m0, s42
	ds_read_b128 v[196:199], v159 offset:49152
	ds_read_b128 v[200:203], v159 offset:50176
	ds_read_b128 v[204:207], v159 offset:51200
	ds_read_b128 v[208:211], v159 offset:52224
	ds_read_b128 v[212:215], v159 offset:53248
	ds_read_b128 v[216:219], v159 offset:54272
	ds_read_b128 v[220:223], v159 offset:55296
	ds_read_b128 v[224:227], v159 offset:56320
	global_load_lds_dwordx4 v[144:145], off
	s_add_i32 m0, s42, 0x2000
	s_add_u32 s40, s40, 0x40080
	v_lshl_add_u64 v[144:145], v[148:149], 0, s[16:17]
	s_addc_u32 s41, s41, 0
	s_add_i32 s42, s62, s94
	global_load_lds_dwordx4 v[144:145], off
	v_lshl_add_u64 v[144:145], s[40:41], 0, v[132:133]
	s_mov_b32 m0, s42
	s_nop 0
	global_load_lds_dwordx4 v[144:145], off
	v_lshl_add_u64 v[144:145], s[40:41], 0, v[128:129]
	s_add_i32 m0, s42, 0x2000
	s_nop 0
	global_load_lds_dwordx4 v[144:145], off
	v_lshl_add_u64 v[144:145], v[152:153], 0, s[16:17]
	s_mov_b32 m0, s51
	s_nop 0
	global_load_lds_dwordx4 v[144:145], off
	v_lshl_add_u64 v[144:145], v[156:157], 0, s[16:17]
	s_mov_b32 m0, s52
	s_nop 0
	global_load_lds_dwordx4 v[144:145], off
	s_waitcnt vmcnt(8)
	s_waitcnt lgkmcnt(0)
	s_barrier
	s_setprio 1
	v_mfma_f32_16x16x32_bf16 v[60:63], v[164:167], v[196:199], v[60:63]
	v_mfma_f32_16x16x32_bf16 v[56:59], v[172:175], v[196:199], v[56:59]
	v_mfma_f32_16x16x32_bf16 v[44:47], v[164:167], v[204:207], v[44:47]
	v_mfma_f32_16x16x32_bf16 v[40:43], v[172:175], v[204:207], v[40:43]
	v_mfma_f32_16x16x32_bf16 v[28:31], v[164:167], v[212:215], v[28:31]
	v_mfma_f32_16x16x32_bf16 v[24:27], v[172:175], v[212:215], v[24:27]
	v_mfma_f32_16x16x32_bf16 v[12:15], v[164:167], v[220:223], v[12:15]
	v_mfma_f32_16x16x32_bf16 v[8:11], v[172:175], v[220:223], v[8:11]
	v_mfma_f32_16x16x32_bf16 v[60:63], v[168:171], v[200:203], v[60:63]
	v_mfma_f32_16x16x32_bf16 v[56:59], v[176:179], v[200:203], v[56:59]
	v_mfma_f32_16x16x32_bf16 v[44:47], v[168:171], v[208:211], v[44:47]
	v_mfma_f32_16x16x32_bf16 v[40:43], v[176:179], v[208:211], v[40:43]
	v_mfma_f32_16x16x32_bf16 v[28:31], v[168:171], v[216:219], v[28:31]
	v_mfma_f32_16x16x32_bf16 v[24:27], v[176:179], v[216:219], v[24:27]
	v_mfma_f32_16x16x32_bf16 v[12:15], v[168:171], v[224:227], v[12:15]
	v_mfma_f32_16x16x32_bf16 v[8:11], v[176:179], v[224:227], v[8:11]
	v_mfma_f32_16x16x32_bf16 v[52:55], v[180:183], v[196:199], v[52:55]
	v_mfma_f32_16x16x32_bf16 v[48:51], v[188:191], v[196:199], v[48:51]
	v_mfma_f32_16x16x32_bf16 v[36:39], v[180:183], v[204:207], v[36:39]
	v_mfma_f32_16x16x32_bf16 v[32:35], v[188:191], v[204:207], v[32:35]
	v_mfma_f32_16x16x32_bf16 v[20:23], v[180:183], v[212:215], v[20:23]
	v_mfma_f32_16x16x32_bf16 v[16:19], v[188:191], v[212:215], v[16:19]
	v_mfma_f32_16x16x32_bf16 v[4:7], v[180:183], v[220:223], v[4:7]
	v_mfma_f32_16x16x32_bf16 v[0:3], v[188:191], v[220:223], v[0:3]
	v_mfma_f32_16x16x32_bf16 v[52:55], v[184:187], v[200:203], v[52:55]
	v_mfma_f32_16x16x32_bf16 v[48:51], v[192:195], v[200:203], v[48:51]
	v_mfma_f32_16x16x32_bf16 v[36:39], v[184:187], v[208:211], v[36:39]
	v_mfma_f32_16x16x32_bf16 v[32:35], v[192:195], v[208:211], v[32:35]
	v_mfma_f32_16x16x32_bf16 v[20:23], v[184:187], v[216:219], v[20:23]
	v_mfma_f32_16x16x32_bf16 v[16:19], v[192:195], v[216:219], v[16:19]
	v_mfma_f32_16x16x32_bf16 v[4:7], v[184:187], v[224:227], v[4:7]
	v_mfma_f32_16x16x32_bf16 v[0:3], v[192:195], v[224:227], v[0:3]
	s_setprio 0
	s_barrier
	s_add_i32 s60, s60, 2
	s_add_u32 s38, s38, 0x100
	s_addc_u32 s39, s39, 0
	s_add_u32 s58, s58, 0x100
	s_addc_u32 s59, s59, 0
	s_cmp_gt_u32 s60, 13
	s_cbranch_scc0 .LBB0_1336
	s_branch .Lpeel_exit_9
.LBB0_1336:
	ds_read_b128 v[164:167], v151
	ds_read_b128 v[168:171], v151 offset:1024
	ds_read_b128 v[172:175], v151 offset:2048
	ds_read_b128 v[176:179], v151 offset:3072
	ds_read_b128 v[180:183], v155
	ds_read_b128 v[184:187], v155 offset:1024
	ds_read_b128 v[188:191], v155 offset:2048
	ds_read_b128 v[192:195], v155 offset:3072
	s_add_u32 s40, s38, 0xfffc0080
	s_addc_u32 s41, s39, -1
	s_cmp_eq_u32 s60, 12
	s_cselect_b32 s43, s27, s41
	s_cselect_b32 s42, s56, s40
	s_cselect_b32 s41, s29, s59
	s_cselect_b32 s40, s57, s58
	v_lshl_add_u64 v[144:145], s[38:39], 0, v[136:137]
	s_add_i32 m0, s37, 0xc000
	ds_read_b128 v[196:199], v159
	ds_read_b128 v[200:203], v159 offset:1024
	ds_read_b128 v[204:207], v159 offset:2048
	ds_read_b128 v[208:211], v159 offset:3072
	ds_read_b128 v[212:215], v159 offset:4096
	ds_read_b128 v[216:219], v159 offset:5120
	ds_read_b128 v[220:223], v159 offset:6144
	ds_read_b128 v[224:227], v159 offset:7168
	global_load_lds_dwordx4 v[144:145], off
	v_lshl_add_u64 v[144:145], s[38:39], 0, v[138:139]
	s_add_i32 m0, s37, 0xe000
	s_nop 0
	global_load_lds_dwordx4 v[144:145], off
	s_waitcnt vmcnt(8)
	s_waitcnt lgkmcnt(0)
	s_barrier
; #define PG8_STAGE(bufoff, gbase, voff) do { _Pragma("unroll") for (int _i = 0; _i < 2; ++_i) \
;         __builtin_amdgcn_global_load_lds((const unsigned*)((const char*)(gbase) + (voff)[_i]), (LAS unsigned*)(lds + (bufoff) + ldsw + _i * 8192), 16, 0, 0); } while (0)
; #define PG8_LDA(dst, b, h) do { _Pragma("unroll") for (int m = 0; m < 4; ++m) _Pragma("unroll") for (int k = 0; k < 2; ++k) dst[m][k] = *(const LAS bf16x8*)(lds + PG8_SA(b, h) + aoff + m * 2048 + k * 1024); } while (0)
; #define PG8_LDB(dst, b, h) do { _Pragma("unroll") for (int n = 0; n < 2; ++n) _Pragma("unroll") for (int k = 0; k < 2; ++k) dst[n][k] = *(const LAS bf16x8*)(lds + PG8_SB(b, h) + boff + n * 2048 + k * 1024); } while (0)
; #define PG8_MMA(ai, bj, At, Bt) do { __builtin_amdgcn_s_setprio(1); _Pragma("unroll") for (int m = 0; m < 4; ++m) _Pragma("unroll") for (int n = 0; n < 2; ++n) _Pragma("unroll") for (int k = 0; k < 2; ++k) \
;         acc[ai][bj][m][n] = __builtin_amdgcn_mfma_f32_16x16x32_bf16(Bt[n][k], At[m][k], acc[ai][bj][m][n], 0, 0, 0); __builtin_amdgcn_s_setprio(0); } while (0)
; #define PG8_WAIT_V(n) asm volatile("s_waitcnt vmcnt(" #n ")" ::: "memory")
; #define PG8_WAIT_L(n) asm volatile("s_waitcnt lgkmcnt(" #n ")" ::: "memory")
; #define PG8_BAR __builtin_amdgcn_s_barrier()
; #define PG8_SCHED __builtin_amdgcn_sched_barrier(0)
; template <class Epi>
; DI void gemm_phase(LAS unsigned char* lds, const int wid, const Gemm g, const Order& S, const Epi& E) {
;     ...
;             PG8_WAIT_V(8); PG8_WAIT_L(0); PG8_BAR; PG8_MMA(0, 0, At, B0); PG8_MMA(0, 1, At, B1); PG8_BAR; PG8_SCHED;
;             PG8_LDA(At, 0, 1); PG8_STAGE(PG8_SB(0, 0), b2, voffB); PG8_STAGE(PG8_SB(0, 1), b2 + hstepB, voffB); PG8_STAGE(PG8_SA(0, 0), a2, voffA);
;             PG8_WAIT_V(8); PG8_WAIT_L(0); PG8_BAR; PG8_MMA(1, 0, At, B0); PG8_MMA(1, 1, At, B1); PG8_BAR; PG8_SCHED;
;             PG8_LDB(B0, 1, 0); PG8_LDB(B1, 1, 1); PG8_SCHED; PG8_LDA(At, 1, 0); PG8_STAGE(PG8_SA(0, 1), a2 + hstepA, voffA);
;             PG8_WAIT_V(8); PG8_WAIT_L(0); PG8_BAR; PG8_MMA(0, 0, At, B0); PG8_MMA(0, 1, At, B1); PG8_BAR; PG8_SCHED;
	s_setprio 1
	v_mfma_f32_16x16x32_bf16 v[124:127], v[164:167], v[196:199], v[124:127]
	v_mfma_f32_16x16x32_bf16 v[120:123], v[172:175], v[196:199], v[120:123]
	v_mfma_f32_16x16x32_bf16 v[108:111], v[164:167], v[204:207], v[108:111]
	v_mfma_f32_16x16x32_bf16 v[104:107], v[172:175], v[204:207], v[104:107]
	v_mfma_f32_16x16x32_bf16 v[92:95], v[164:167], v[212:215], v[92:95]
	v_mfma_f32_16x16x32_bf16 v[88:91], v[172:175], v[212:215], v[88:91]
	v_mfma_f32_16x16x32_bf16 v[76:79], v[164:167], v[220:223], v[76:79]
	v_mfma_f32_16x16x32_bf16 v[72:75], v[172:175], v[220:223], v[72:75]
	v_mfma_f32_16x16x32_bf16 v[124:127], v[168:171], v[200:203], v[124:127]
	v_mfma_f32_16x16x32_bf16 v[120:123], v[176:179], v[200:203], v[120:123]
	v_mfma_f32_16x16x32_bf16 v[108:111], v[168:171], v[208:211], v[108:111]
	v_mfma_f32_16x16x32_bf16 v[104:107], v[176:179], v[208:211], v[104:107]
	v_mfma_f32_16x16x32_bf16 v[92:95], v[168:171], v[216:219], v[92:95]
	v_mfma_f32_16x16x32_bf16 v[88:91], v[176:179], v[216:219], v[88:91]
	v_mfma_f32_16x16x32_bf16 v[76:79], v[168:171], v[224:227], v[76:79]
	v_mfma_f32_16x16x32_bf16 v[72:75], v[176:179], v[224:227], v[72:75]
	v_mfma_f32_16x16x32_bf16 v[116:119], v[180:183], v[196:199], v[116:119]
	v_mfma_f32_16x16x32_bf16 v[112:115], v[188:191], v[196:199], v[112:115]
	v_mfma_f32_16x16x32_bf16 v[100:103], v[180:183], v[204:207], v[100:103]
	v_mfma_f32_16x16x32_bf16 v[96:99], v[188:191], v[204:207], v[96:99]
	v_mfma_f32_16x16x32_bf16 v[84:87], v[180:183], v[212:215], v[84:87]
	v_mfma_f32_16x16x32_bf16 v[80:83], v[188:191], v[212:215], v[80:83]
	v_mfma_f32_16x16x32_bf16 v[68:71], v[180:183], v[220:223], v[68:71]
	v_mfma_f32_16x16x32_bf16 v[64:67], v[188:191], v[220:223], v[64:67]
	v_mfma_f32_16x16x32_bf16 v[116:119], v[184:187], v[200:203], v[116:119]
	v_mfma_f32_16x16x32_bf16 v[112:115], v[192:195], v[200:203], v[112:115]
	v_mfma_f32_16x16x32_bf16 v[100:103], v[184:187], v[208:211], v[100:103]
	v_mfma_f32_16x16x32_bf16 v[96:99], v[192:195], v[208:211], v[96:99]
	v_mfma_f32_16x16x32_bf16 v[84:87], v[184:187], v[216:219], v[84:87]
	v_mfma_f32_16x16x32_bf16 v[80:83], v[192:195], v[216:219], v[80:83]
	v_mfma_f32_16x16x32_bf16 v[68:71], v[184:187], v[224:227], v[68:71]
	v_mfma_f32_16x16x32_bf16 v[64:67], v[192:195], v[224:227], v[64:67]
	s_setprio 0
	s_barrier
	s_add_i32 s61, s53, s94
	v_lshl_add_u64 v[144:145], s[40:41], 0, v[132:133]
	s_mov_b32 m0, s61
	ds_read_b128 v[196:199], v159 offset:16384
	ds_read_b128 v[200:203], v159 offset:17408
	ds_read_b128 v[204:207], v159 offset:18432
	ds_read_b128 v[208:211], v159 offset:19456
	ds_read_b128 v[212:215], v159 offset:20480
	ds_read_b128 v[216:219], v159 offset:21504
	ds_read_b128 v[220:223], v159 offset:22528
	ds_read_b128 v[224:227], v159 offset:23552
	global_load_lds_dwordx4 v[144:145], off
	s_add_i32 m0, s61, 0x2000
	s_add_u32 s62, s40, 0x40000
	v_lshl_add_u64 v[148:149], s[40:41], 0, v[128:129]
	s_addc_u32 s63, s41, 0
	s_add_i32 s61, s54, s94
	global_load_lds_dwordx4 v[148:149], off
	v_lshl_add_u64 v[152:153], s[62:63], 0, v[132:133]
	s_mov_b32 m0, s61
	v_lshl_add_u64 v[156:157], s[42:43], 0, v[130:131]
	global_load_lds_dwordx4 v[152:153], off
	v_lshl_add_u64 v[152:153], s[62:63], 0, v[128:129]
	s_add_i32 m0, s61, 0x2000
	s_nop 0
	global_load_lds_dwordx4 v[152:153], off
	v_lshl_add_u64 v[152:153], s[42:43], 0, v[134:135]
	s_mov_b32 m0, s37
	s_nop 0
	global_load_lds_dwordx4 v[152:153], off
	s_mov_b32 m0, s46
	s_nop 0
	global_load_lds_dwordx4 v[156:157], off
	s_waitcnt vmcnt(8)
	s_waitcnt lgkmcnt(0)
	s_barrier
	s_setprio 1
	v_mfma_f32_16x16x32_bf16 v[60:63], v[164:167], v[196:199], v[60:63]
	v_mfma_f32_16x16x32_bf16 v[56:59], v[172:175], v[196:199], v[56:59]
	v_mfma_f32_16x16x32_bf16 v[44:47], v[164:167], v[204:207], v[44:47]
	v_mfma_f32_16x16x32_bf16 v[40:43], v[172:175], v[204:207], v[40:43]
	v_mfma_f32_16x16x32_bf16 v[28:31], v[164:167], v[212:215], v[28:31]
	v_mfma_f32_16x16x32_bf16 v[24:27], v[172:175], v[212:215], v[24:27]
	v_mfma_f32_16x16x32_bf16 v[12:15], v[164:167], v[220:223], v[12:15]
	v_mfma_f32_16x16x32_bf16 v[8:11], v[172:175], v[220:223], v[8:11]
	v_mfma_f32_16x16x32_bf16 v[60:63], v[168:171], v[200:203], v[60:63]
	v_mfma_f32_16x16x32_bf16 v[56:59], v[176:179], v[200:203], v[56:59]
	v_mfma_f32_16x16x32_bf16 v[44:47], v[168:171], v[208:211], v[44:47]
	v_mfma_f32_16x16x32_bf16 v[40:43], v[176:179], v[208:211], v[40:43]
	v_mfma_f32_16x16x32_bf16 v[28:31], v[168:171], v[216:219], v[28:31]
	v_mfma_f32_16x16x32_bf16 v[24:27], v[176:179], v[216:219], v[24:27]
	v_mfma_f32_16x16x32_bf16 v[12:15], v[168:171], v[224:227], v[12:15]
	v_mfma_f32_16x16x32_bf16 v[8:11], v[176:179], v[224:227], v[8:11]
	v_mfma_f32_16x16x32_bf16 v[52:55], v[180:183], v[196:199], v[52:55]
	v_mfma_f32_16x16x32_bf16 v[48:51], v[188:191], v[196:199], v[48:51]
	v_mfma_f32_16x16x32_bf16 v[36:39], v[180:183], v[204:207], v[36:39]
	v_mfma_f32_16x16x32_bf16 v[32:35], v[188:191], v[204:207], v[32:35]
	v_mfma_f32_16x16x32_bf16 v[20:23], v[180:183], v[212:215], v[20:23]
	v_mfma_f32_16x16x32_bf16 v[16:19], v[188:191], v[212:215], v[16:19]
	v_mfma_f32_16x16x32_bf16 v[4:7], v[180:183], v[220:223], v[4:7]
	v_mfma_f32_16x16x32_bf16 v[0:3], v[188:191], v[220:223], v[0:3]
	v_mfma_f32_16x16x32_bf16 v[52:55], v[184:187], v[200:203], v[52:55]
	v_mfma_f32_16x16x32_bf16 v[48:51], v[192:195], v[200:203], v[48:51]
	v_mfma_f32_16x16x32_bf16 v[36:39], v[184:187], v[208:211], v[36:39]
	v_mfma_f32_16x16x32_bf16 v[32:35], v[192:195], v[208:211], v[32:35]
	v_mfma_f32_16x16x32_bf16 v[20:23], v[184:187], v[216:219], v[20:23]
	v_mfma_f32_16x16x32_bf16 v[16:19], v[192:195], v[216:219], v[16:19]
	v_mfma_f32_16x16x32_bf16 v[4:7], v[184:187], v[224:227], v[4:7]
	v_mfma_f32_16x16x32_bf16 v[0:3], v[192:195], v[224:227], v[0:3]
	s_setprio 0
	s_barrier
; #define PG8_STAGE(bufoff, gbase, voff) do { _Pragma("unroll") for (int _i = 0; _i < 2; ++_i) \
;         __builtin_amdgcn_global_load_lds((const unsigned*)((const char*)(gbase) + (voff)[_i]), (LAS unsigned*)(lds + (bufoff) + ldsw + _i * 8192), 16, 0, 0); } while (0)
; #define PG8_LDA(dst, b, h) do { _Pragma("unroll") for (int m = 0; m < 4; ++m) _Pragma("unroll") for (int k = 0; k < 2; ++k) dst[m][k] = *(const LAS bf16x8*)(lds + PG8_SA(b, h) + aoff + m * 2048 + k * 1024); } while (0)
; #define PG8_LDB(dst, b, h) do { _Pragma("unroll") for (int n = 0; n < 2; ++n) _Pragma("unroll") for (int k = 0; k < 2; ++k) dst[n][k] = *(const LAS bf16x8*)(lds + PG8_SB(b, h) + boff + n * 2048 + k * 1024); } while (0)
; #define PG8_MMA(ai, bj, At, Bt) do { __builtin_amdgcn_s_setprio(1); _Pragma("unroll") for (int m = 0; m < 4; ++m) _Pragma("unroll") for (int n = 0; n < 2; ++n) _Pragma("unroll") for (int k = 0; k < 2; ++k) \
;         acc[ai][bj][m][n] = __builtin_amdgcn_mfma_f32_16x16x32_bf16(Bt[n][k], At[m][k], acc[ai][bj][m][n], 0, 0, 0); __builtin_amdgcn_s_setprio(0); } while (0)
; #define PG8_WAIT_V(n) asm volatile("s_waitcnt vmcnt(" #n ")" ::: "memory")
; #define PG8_WAIT_L(n) asm volatile("s_waitcnt lgkmcnt(" #n ")" ::: "memory")
; #define PG8_BAR __builtin_amdgcn_s_barrier()
; #define PG8_SCHED __builtin_amdgcn_sched_barrier(0)
; template <class Epi>
; DI void gemm_phase(LAS unsigned char* lds, const int wid, const Gemm g, const Order& S, const Epi& E) {
;     ...
;             PG8_LDB(B0, 1, 0); PG8_LDB(B1, 1, 1); PG8_SCHED; PG8_LDA(At, 1, 0); PG8_STAGE(PG8_SA(0, 1), a2 + hstepA, voffA);
;             PG8_WAIT_V(8); PG8_WAIT_L(0); PG8_BAR; PG8_MMA(0, 0, At, B0); PG8_MMA(0, 1, At, B1); PG8_BAR; PG8_SCHED;
	s_add_i32 s61, 0, 0x18000
	v_add_u32_e32 v146, s61, v147
	s_add_i32 s62, 0, 0x1c000
	ds_read_b128 v[164:167], v146
	ds_read_b128 v[168:171], v146 offset:1024
	ds_read_b128 v[172:175], v146 offset:2048
	ds_read_b128 v[176:179], v146 offset:3072
	v_add_u32_e32 v146, s62, v147
	ds_read_b128 v[180:183], v146
	ds_read_b128 v[184:187], v146 offset:1024
	ds_read_b128 v[188:191], v146 offset:2048
	ds_read_b128 v[192:195], v146 offset:3072
	s_add_u32 s42, s42, 0x40000
	s_addc_u32 s43, s43, 0
	s_mov_b32 m0, s47
	v_lshl_add_u64 v[160:161], s[42:43], 0, v[134:135]
	ds_read_b128 v[196:199], v159 offset:32768
	ds_read_b128 v[200:203], v159 offset:33792
	ds_read_b128 v[204:207], v159 offset:34816
	ds_read_b128 v[208:211], v159 offset:35840
	ds_read_b128 v[212:215], v159 offset:36864
	ds_read_b128 v[216:219], v159 offset:37888
	ds_read_b128 v[220:223], v159 offset:38912
	ds_read_b128 v[224:227], v159 offset:39936
	global_load_lds_dwordx4 v[160:161], off
	v_lshl_add_u64 v[160:161], s[42:43], 0, v[130:131]
	s_mov_b32 m0, s48
	s_nop 0
	global_load_lds_dwordx4 v[160:161], off
	s_waitcnt vmcnt(8)
	s_waitcnt lgkmcnt(0)
	s_barrier
	s_setprio 1
	v_mfma_f32_16x16x32_bf16 v[124:127], v[164:167], v[196:199], v[124:127]
	v_mfma_f32_16x16x32_bf16 v[120:123], v[172:175], v[196:199], v[120:123]
	v_mfma_f32_16x16x32_bf16 v[108:111], v[164:167], v[204:207], v[108:111]
	v_mfma_f32_16x16x32_bf16 v[104:107], v[172:175], v[204:207], v[104:107]
	v_mfma_f32_16x16x32_bf16 v[92:95], v[164:167], v[212:215], v[92:95]
	v_mfma_f32_16x16x32_bf16 v[88:91], v[172:175], v[212:215], v[88:91]
	v_mfma_f32_16x16x32_bf16 v[76:79], v[164:167], v[220:223], v[76:79]
	v_mfma_f32_16x16x32_bf16 v[72:75], v[172:175], v[220:223], v[72:75]
	v_mfma_f32_16x16x32_bf16 v[124:127], v[168:171], v[200:203], v[124:127]
	v_mfma_f32_16x16x32_bf16 v[120:123], v[176:179], v[200:203], v[120:123]
	v_mfma_f32_16x16x32_bf16 v[108:111], v[168:171], v[208:211], v[108:111]
	v_mfma_f32_16x16x32_bf16 v[104:107], v[176:179], v[208:211], v[104:107]
	v_mfma_f32_16x16x32_bf16 v[92:95], v[168:171], v[216:219], v[92:95]
	v_mfma_f32_16x16x32_bf16 v[88:91], v[176:179], v[216:219], v[88:91]
	v_mfma_f32_16x16x32_bf16 v[76:79], v[168:171], v[224:227], v[76:79]
	v_mfma_f32_16x16x32_bf16 v[72:75], v[176:179], v[224:227], v[72:75]
	v_mfma_f32_16x16x32_bf16 v[116:119], v[180:183], v[196:199], v[116:119]
	v_mfma_f32_16x16x32_bf16 v[112:115], v[188:191], v[196:199], v[112:115]
	v_mfma_f32_16x16x32_bf16 v[100:103], v[180:183], v[204:207], v[100:103]
	v_mfma_f32_16x16x32_bf16 v[96:99], v[188:191], v[204:207], v[96:99]
	v_mfma_f32_16x16x32_bf16 v[84:87], v[180:183], v[212:215], v[84:87]
	v_mfma_f32_16x16x32_bf16 v[80:83], v[188:191], v[212:215], v[80:83]
	v_mfma_f32_16x16x32_bf16 v[68:71], v[180:183], v[220:223], v[68:71]
	v_mfma_f32_16x16x32_bf16 v[64:67], v[188:191], v[220:223], v[64:67]
	v_mfma_f32_16x16x32_bf16 v[116:119], v[184:187], v[200:203], v[116:119]
	v_mfma_f32_16x16x32_bf16 v[112:115], v[192:195], v[200:203], v[112:115]
	v_mfma_f32_16x16x32_bf16 v[100:103], v[184:187], v[208:211], v[100:103]
	v_mfma_f32_16x16x32_bf16 v[96:99], v[192:195], v[208:211], v[96:99]
	v_mfma_f32_16x16x32_bf16 v[84:87], v[184:187], v[216:219], v[84:87]
	v_mfma_f32_16x16x32_bf16 v[80:83], v[192:195], v[216:219], v[80:83]
	v_mfma_f32_16x16x32_bf16 v[68:71], v[184:187], v[224:227], v[68:71]
	v_mfma_f32_16x16x32_bf16 v[64:67], v[192:195], v[224:227], v[64:67]
	s_setprio 0
	s_barrier
; #define PG8_STAGE(bufoff, gbase, voff) do { _Pragma("unroll") for (int _i = 0; _i < 2; ++_i) \
;         __builtin_amdgcn_global_load_lds((const unsigned*)((const char*)(gbase) + (voff)[_i]), (LAS unsigned*)(lds + (bufoff) + ldsw + _i * 8192), 16, 0, 0); } while (0)
; #define PG8_LDA(dst, b, h) do { _Pragma("unroll") for (int m = 0; m < 4; ++m) _Pragma("unroll") for (int k = 0; k < 2; ++k) dst[m][k] = *(const LAS bf16x8*)(lds + PG8_SA(b, h) + aoff + m * 2048 + k * 1024); } while (0)
; #define PG8_MMA(ai, bj, At, Bt) do { __builtin_amdgcn_s_setprio(1); _Pragma("unroll") for (int m = 0; m < 4; ++m) _Pragma("unroll") for (int n = 0; n < 2; ++n) _Pragma("unroll") for (int k = 0; k < 2; ++k) \
;         acc[ai][bj][m][n] = __builtin_amdgcn_mfma_f32_16x16x32_bf16(Bt[n][k], At[m][k], acc[ai][bj][m][n], 0, 0, 0); __builtin_amdgcn_s_setprio(0); } while (0)
; #define PG8_WAIT_V(n) asm volatile("s_waitcnt vmcnt(" #n ")" ::: "memory")
; #define PG8_WAIT_L(n) asm volatile("s_waitcnt lgkmcnt(" #n ")" ::: "memory")
; #define PG8_BAR __builtin_amdgcn_s_barrier()
; #define PG8_SCHED __builtin_amdgcn_sched_barrier(0)
; template <class Epi>
; DI void gemm_phase(LAS unsigned char* lds, const int wid, const Gemm g, const Order& S, const Epi& E) {
;     ...
;         for (int t = 0; t < nt; t += 2) {
;     ...
;             PG8_LDA(At, 1, 1); PG8_STAGE(PG8_SB(1, 0), b3, voffB); PG8_STAGE(PG8_SB(1, 1), b3 + hstepB, voffB); PG8_STAGE(PG8_SA(1, 0), a3, voffA);
;             PG8_WAIT_V(8); PG8_WAIT_L(0); PG8_BAR; PG8_MMA(1, 0, At, B0); PG8_MMA(1, 1, At, B1); PG8_BAR; PG8_SCHED;
	s_add_i32 s42, s61, s94
	v_lshl_add_u64 v[144:145], v[144:145], 0, s[16:17]
	s_mov_b32 m0, s42
	ds_read_b128 v[196:199], v159 offset:49152
	ds_read_b128 v[200:203], v159 offset:50176
	ds_read_b128 v[204:207], v159 offset:51200
	ds_read_b128 v[208:211], v159 offset:52224
	ds_read_b128 v[212:215], v159 offset:53248
	ds_read_b128 v[216:219], v159 offset:54272
	ds_read_b128 v[220:223], v159 offset:55296
	ds_read_b128 v[224:227], v159 offset:56320
	global_load_lds_dwordx4 v[144:145], off
	s_add_i32 m0, s42, 0x2000
	s_add_u32 s40, s40, 0x40080
	v_lshl_add_u64 v[144:145], v[148:149], 0, s[16:17]
	s_addc_u32 s41, s41, 0
	s_add_i32 s42, s62, s94
	global_load_lds_dwordx4 v[144:145], off
	v_lshl_add_u64 v[144:145], s[40:41], 0, v[132:133]
	s_mov_b32 m0, s42
	s_nop 0
	global_load_lds_dwordx4 v[144:145], off
	v_lshl_add_u64 v[144:145], s[40:41], 0, v[128:129]
	s_add_i32 m0, s42, 0x2000
	s_nop 0
	global_load_lds_dwordx4 v[144:145], off
	v_lshl_add_u64 v[144:145], v[152:153], 0, s[16:17]
	s_mov_b32 m0, s51
	s_nop 0
	global_load_lds_dwordx4 v[144:145], off
	v_lshl_add_u64 v[144:145], v[156:157], 0, s[16:17]
	s_mov_b32 m0, s52
	s_nop 0
	global_load_lds_dwordx4 v[144:145], off
	s_waitcnt vmcnt(8)
	s_waitcnt lgkmcnt(0)
	s_barrier
	s_setprio 1
	v_mfma_f32_16x16x32_bf16 v[60:63], v[164:167], v[196:199], v[60:63]
	v_mfma_f32_16x16x32_bf16 v[56:59], v[172:175], v[196:199], v[56:59]
	v_mfma_f32_16x16x32_bf16 v[44:47], v[164:167], v[204:207], v[44:47]
	v_mfma_f32_16x16x32_bf16 v[40:43], v[172:175], v[204:207], v[40:43]
	v_mfma_f32_16x16x32_bf16 v[28:31], v[164:167], v[212:215], v[28:31]
	v_mfma_f32_16x16x32_bf16 v[24:27], v[172:175], v[212:215], v[24:27]
	v_mfma_f32_16x16x32_bf16 v[12:15], v[164:167], v[220:223], v[12:15]
	v_mfma_f32_16x16x32_bf16 v[8:11], v[172:175], v[220:223], v[8:11]
	v_mfma_f32_16x16x32_bf16 v[60:63], v[168:171], v[200:203], v[60:63]
	v_mfma_f32_16x16x32_bf16 v[56:59], v[176:179], v[200:203], v[56:59]
	v_mfma_f32_16x16x32_bf16 v[44:47], v[168:171], v[208:211], v[44:47]
	v_mfma_f32_16x16x32_bf16 v[40:43], v[176:179], v[208:211], v[40:43]
	v_mfma_f32_16x16x32_bf16 v[28:31], v[168:171], v[216:219], v[28:31]
	v_mfma_f32_16x16x32_bf16 v[24:27], v[176:179], v[216:219], v[24:27]
	v_mfma_f32_16x16x32_bf16 v[12:15], v[168:171], v[224:227], v[12:15]
	v_mfma_f32_16x16x32_bf16 v[8:11], v[176:179], v[224:227], v[8:11]
	v_mfma_f32_16x16x32_bf16 v[52:55], v[180:183], v[196:199], v[52:55]
	v_mfma_f32_16x16x32_bf16 v[48:51], v[188:191], v[196:199], v[48:51]
	v_mfma_f32_16x16x32_bf16 v[36:39], v[180:183], v[204:207], v[36:39]
	v_mfma_f32_16x16x32_bf16 v[32:35], v[188:191], v[204:207], v[32:35]
	v_mfma_f32_16x16x32_bf16 v[20:23], v[180:183], v[212:215], v[20:23]
	v_mfma_f32_16x16x32_bf16 v[16:19], v[188:191], v[212:215], v[16:19]
	v_mfma_f32_16x16x32_bf16 v[4:7], v[180:183], v[220:223], v[4:7]
	v_mfma_f32_16x16x32_bf16 v[0:3], v[188:191], v[220:223], v[0:3]
	v_mfma_f32_16x16x32_bf16 v[52:55], v[184:187], v[200:203], v[52:55]
	v_mfma_f32_16x16x32_bf16 v[48:51], v[192:195], v[200:203], v[48:51]
	v_mfma_f32_16x16x32_bf16 v[36:39], v[184:187], v[208:211], v[36:39]
	v_mfma_f32_16x16x32_bf16 v[32:35], v[192:195], v[208:211], v[32:35]
	v_mfma_f32_16x16x32_bf16 v[20:23], v[184:187], v[216:219], v[20:23]
	v_mfma_f32_16x16x32_bf16 v[16:19], v[192:195], v[216:219], v[16:19]
	v_mfma_f32_16x16x32_bf16 v[4:7], v[184:187], v[224:227], v[4:7]
	v_mfma_f32_16x16x32_bf16 v[0:3], v[192:195], v[224:227], v[0:3]
	s_setprio 0
	s_barrier
	s_add_i32 s60, s60, 2
	s_add_u32 s38, s38, 0x100
	s_addc_u32 s39, s39, 0
	s_add_u32 s58, s58, 0x100
	s_addc_u32 s59, s59, 0
	s_cmp_gt_u32 s60, 13
	s_cbranch_scc0 .LBB0_1336

; #define PG8_STAGE(bufoff, gbase, voff) do { _Pragma("unroll") for (int _i = 0; _i < 2; ++_i) \
;         __builtin_amdgcn_global_load_lds((const unsigned*)((const char*)(gbase) + (voff)[_i]), (LAS unsigned*)(lds + (bufoff) + ldsw + _i * 8192), 16, 0, 0); } while (0)
; #define PG8_LDA(dst, b, h) do { _Pragma("unroll") for (int m = 0; m < 4; ++m) _Pragma("unroll") for (int k = 0; k < 2; ++k) dst[m][k] = *(const LAS bf16x8*)(lds + PG8_SA(b, h) + aoff + m * 2048 + k * 1024); } while (0)
; #define PG8_LDB(dst, b, h) do { _Pragma("unroll") for (int n = 0; n < 2; ++n) _Pragma("unroll") for (int k = 0; k < 2; ++k) dst[n][k] = *(const LAS bf16x8*)(lds + PG8_SB(b, h) + boff + n * 2048 + k * 1024); } while (0)
; #define PG8_MMA(ai, bj, At, Bt) do { __builtin_amdgcn_s_setprio(1); _Pragma("unroll") for (int m = 0; m < 4; ++m) _Pragma("unroll") for (int n = 0; n < 2; ++n) _Pragma("unroll") for (int k = 0; k < 2; ++k) \
;         acc[ai][bj][m][n] = __builtin_amdgcn_mfma_f32_16x16x32_bf16(Bt[n][k], At[m][k], acc[ai][bj][m][n], 0, 0, 0); __builtin_amdgcn_s_setprio(0); } while (0)
; #define PG8_WAIT_V(n) asm volatile("s_waitcnt vmcnt(" #n ")" ::: "memory")
; template <class Epi>
; DI void gemm_phase(LAS unsigned char* lds, const int wid, const Gemm g, const Order& S, const Epi& E) {
;     ...
;         const char* nA = has_next ? (const char*)(g.A + (size_t)nxt.g * g.gsA + (size_t)nxt.pm * BM * g.lda) : cA;
;         const char* nB = has_next ? (const char*)(g.Bt + (size_t)nxt.g * g.gsB + (size_t)nxt.pn * BM * g.ldb) : cB;
;         for (int t = 0; t < nt; t += 2) {
;             const bool last = (t == nt - 2);
;             const char* a1 = cA + (size_t)(t + 1) * kstep;
;             const char* a2 = last ? nA : cA + (size_t)(t + 2) * kstep; const char* b2 = last ? nB : cB + (size_t)(t + 2) * kstep;
;             const char* a3 = a2 + kstep; const char* b3 = b2 + kstep;
;             PG8_LDB(B0, 0, 0); PG8_LDB(B1, 0, 1); PG8_SCHED; PG8_LDA(At, 0, 0); PG8_STAGE(PG8_SA(1, 1), a1 + hstepA, voffA);
;             PG8_WAIT_V(8); PG8_WAIT_L(0); PG8_BAR; PG8_MMA(0, 0, At, B0); PG8_MMA(0, 1, At, B1); PG8_BAR; PG8_SCHED;
;             PG8_LDA(At, 0, 1); PG8_STAGE(PG8_SB(0, 0), b2, voffB); PG8_STAGE(PG8_SB(0, 1), b2 + hstepB, voffB); PG8_STAGE(PG8_SA(0, 0), a2, voffA);
;             PG8_WAIT_V(8); PG8_WAIT_L(0); PG8_BAR; PG8_MMA(1, 0, At, B0); PG8_MMA(1, 1, At, B1); PG8_BAR; PG8_SCHED;
.LBB0_1420:
	s_add_u32 s56, s38, 0x100
	v_mov_b32_e32 v0, 0
	s_addc_u32 s57, s39, 0
	s_mov_b32 s58, -2
	s_waitcnt lgkmcnt(0)
	ds_read_b128 v[128:131], v216
	ds_read_b128 v[132:135], v216 offset:1024
	ds_read_b128 v[136:139], v216 offset:2048
	ds_read_b128 v[140:143], v216 offset:3072
	ds_read_b128 v[144:147], v217
	ds_read_b128 v[148:151], v217 offset:1024
	ds_read_b128 v[152:155], v217 offset:2048
	ds_read_b128 v[156:159], v217 offset:3072
	s_add_u32 s10, s36, 0x100
	s_addc_u32 s11, s37, 0
	s_cmp_eq_u32 s58, 40
	s_cselect_b32 s41, s31, s11
	s_cselect_b32 s40, s30, s10
	s_cselect_b32 s39, s35, s57
	s_cselect_b32 s38, s34, s56
	v_lshl_add_u64 v[208:209], s[36:37], 0, v[184:185]
	s_add_i32 m0, s43, 0xc000
	ds_read_b128 v[160:163], v218
	ds_read_b128 v[164:167], v218 offset:1024
	ds_read_b128 v[168:171], v218 offset:2048
	ds_read_b128 v[172:175], v218 offset:3072
	ds_read_b128 v[192:195], v218 offset:4096
	ds_read_b128 v[196:199], v218 offset:5120
	ds_read_b128 v[200:203], v218 offset:6144
	ds_read_b128 v[204:207], v218 offset:7168
	global_load_lds_dwordx4 v[208:209], off
	v_lshl_add_u64 v[208:209], s[36:37], 0, v[186:187]
	s_add_i32 m0, s43, 0xe000
	s_nop 0
	global_load_lds_dwordx4 v[208:209], off
	s_waitcnt vmcnt(8)
	s_waitcnt lgkmcnt(0)
	s_barrier
	s_setprio 1
	v_mfma_f32_16x16x32_bf16 v[124:127], v[128:131], v[160:163], 0
	v_mfma_f32_16x16x32_bf16 v[120:123], v[136:139], v[160:163], 0
	v_mfma_f32_16x16x32_bf16 v[108:111], v[128:131], v[168:171], 0
	v_mfma_f32_16x16x32_bf16 v[104:107], v[136:139], v[168:171], 0
	v_mfma_f32_16x16x32_bf16 v[92:95], v[128:131], v[192:195], 0
	v_mfma_f32_16x16x32_bf16 v[88:91], v[136:139], v[192:195], 0
	v_mfma_f32_16x16x32_bf16 v[76:79], v[128:131], v[200:203], 0
	v_mfma_f32_16x16x32_bf16 v[72:75], v[136:139], v[200:203], 0
	v_mfma_f32_16x16x32_bf16 v[124:127], v[132:135], v[164:167], v[124:127]
	v_mfma_f32_16x16x32_bf16 v[120:123], v[140:143], v[164:167], v[120:123]
	v_mfma_f32_16x16x32_bf16 v[108:111], v[132:135], v[172:175], v[108:111]
	v_mfma_f32_16x16x32_bf16 v[104:107], v[140:143], v[172:175], v[104:107]
	v_mfma_f32_16x16x32_bf16 v[92:95], v[132:135], v[196:199], v[92:95]
	v_mfma_f32_16x16x32_bf16 v[88:91], v[140:143], v[196:199], v[88:91]
	v_mfma_f32_16x16x32_bf16 v[76:79], v[132:135], v[204:207], v[76:79]
	v_mfma_f32_16x16x32_bf16 v[72:75], v[140:143], v[204:207], v[72:75]
	v_mfma_f32_16x16x32_bf16 v[116:119], v[144:147], v[160:163], 0
	v_mfma_f32_16x16x32_bf16 v[112:115], v[152:155], v[160:163], 0
	v_mfma_f32_16x16x32_bf16 v[100:103], v[144:147], v[168:171], 0
	v_mfma_f32_16x16x32_bf16 v[96:99], v[152:155], v[168:171], 0
	v_mfma_f32_16x16x32_bf16 v[84:87], v[144:147], v[192:195], 0
	v_mfma_f32_16x16x32_bf16 v[80:83], v[152:155], v[192:195], 0
	v_mfma_f32_16x16x32_bf16 v[68:71], v[144:147], v[200:203], 0
	v_mfma_f32_16x16x32_bf16 v[64:67], v[152:155], v[200:203], 0
	v_mfma_f32_16x16x32_bf16 v[116:119], v[148:151], v[164:167], v[116:119]
	v_mfma_f32_16x16x32_bf16 v[112:115], v[156:159], v[164:167], v[112:115]
	v_mfma_f32_16x16x32_bf16 v[100:103], v[148:151], v[172:175], v[100:103]
	v_mfma_f32_16x16x32_bf16 v[96:99], v[156:159], v[172:175], v[96:99]
	v_mfma_f32_16x16x32_bf16 v[84:87], v[148:151], v[196:199], v[84:87]
	v_mfma_f32_16x16x32_bf16 v[80:83], v[156:159], v[196:199], v[80:83]
	v_mfma_f32_16x16x32_bf16 v[68:71], v[148:151], v[204:207], v[68:71]
	v_mfma_f32_16x16x32_bf16 v[64:67], v[156:159], v[204:207], v[64:67]
	s_setprio 0
	s_barrier
	s_add_i32 s36, s50, s94
	v_lshl_add_u64 v[208:209], s[38:39], 0, v[178:179]
	s_mov_b32 m0, s36
	ds_read_b128 v[160:163], v218 offset:16384
	ds_read_b128 v[164:167], v218 offset:17408
	ds_read_b128 v[168:171], v218 offset:18432
	ds_read_b128 v[172:175], v218 offset:19456
	ds_read_b128 v[192:195], v218 offset:20480
	ds_read_b128 v[196:199], v218 offset:21504
	ds_read_b128 v[200:203], v218 offset:22528
	ds_read_b128 v[204:207], v218 offset:23552
	global_load_lds_dwordx4 v[208:209], off
	s_add_i32 m0, s36, 0x2000
	s_add_u32 s36, s38, 0xb0000
	v_lshl_add_u64 v[210:211], s[38:39], 0, v[182:183]
	s_addc_u32 s37, s39, 0
	s_add_i32 s59, s51, s94
	global_load_lds_dwordx4 v[210:211], off
	v_lshl_add_u64 v[212:213], s[36:37], 0, v[178:179]
	s_mov_b32 m0, s59
	v_lshl_add_u64 v[220:221], s[40:41], 0, v[180:181]
	global_load_lds_dwordx4 v[212:213], off
	v_lshl_add_u64 v[212:213], s[36:37], 0, v[182:183]
	s_add_i32 m0, s59, 0x2000
	s_nop 0
	global_load_lds_dwordx4 v[212:213], off
	v_lshl_add_u64 v[212:213], s[40:41], 0, v[176:177]
	s_mov_b32 m0, s43
	s_nop 0
	global_load_lds_dwordx4 v[212:213], off
	s_mov_b32 m0, s44
	s_nop 0
	global_load_lds_dwordx4 v[220:221], off
	s_waitcnt vmcnt(8)
	s_waitcnt lgkmcnt(0)
	s_barrier
; #define PG8_STAGE(bufoff, gbase, voff) do { _Pragma("unroll") for (int _i = 0; _i < 2; ++_i) \
;         __builtin_amdgcn_global_load_lds((const unsigned*)((const char*)(gbase) + (voff)[_i]), (LAS unsigned*)(lds + (bufoff) + ldsw + _i * 8192), 16, 0, 0); } while (0)
; #define PG8_LDA(dst, b, h) do { _Pragma("unroll") for (int m = 0; m < 4; ++m) _Pragma("unroll") for (int k = 0; k < 2; ++k) dst[m][k] = *(const LAS bf16x8*)(lds + PG8_SA(b, h) + aoff + m * 2048 + k * 1024); } while (0)
; #define PG8_LDB(dst, b, h) do { _Pragma("unroll") for (int n = 0; n < 2; ++n) _Pragma("unroll") for (int k = 0; k < 2; ++k) dst[n][k] = *(const LAS bf16x8*)(lds + PG8_SB(b, h) + boff + n * 2048 + k * 1024); } while (0)
; #define PG8_MMA(ai, bj, At, Bt) do { __builtin_amdgcn_s_setprio(1); _Pragma("unroll") for (int m = 0; m < 4; ++m) _Pragma("unroll") for (int n = 0; n < 2; ++n) _Pragma("unroll") for (int k = 0; k < 2; ++k) \
;         acc[ai][bj][m][n] = __builtin_amdgcn_mfma_f32_16x16x32_bf16(Bt[n][k], At[m][k], acc[ai][bj][m][n], 0, 0, 0); __builtin_amdgcn_s_setprio(0); } while (0)
; #define PG8_WAIT_V(n) asm volatile("s_waitcnt vmcnt(" #n ")" ::: "memory")
; #define PG8_WAIT_L(n) asm volatile("s_waitcnt lgkmcnt(" #n ")" ::: "memory")
; #define PG8_BAR __builtin_amdgcn_s_barrier()
; #define PG8_SCHED __builtin_amdgcn_sched_barrier(0)
; template <class Epi>
; DI void gemm_phase(LAS unsigned char* lds, const int wid, const Gemm g, const Order& S, const Epi& E) {
;     ...
;             PG8_WAIT_V(8); PG8_WAIT_L(0); PG8_BAR; PG8_MMA(1, 0, At, B0); PG8_MMA(1, 1, At, B1); PG8_BAR; PG8_SCHED;
;             PG8_LDB(B0, 1, 0); PG8_LDB(B1, 1, 1); PG8_SCHED; PG8_LDA(At, 1, 0); PG8_STAGE(PG8_SA(0, 1), a2 + hstepA, voffA);
;             PG8_WAIT_V(8); PG8_WAIT_L(0); PG8_BAR; PG8_MMA(0, 0, At, B0); PG8_MMA(0, 1, At, B1); PG8_BAR; PG8_SCHED;
;             PG8_LDA(At, 1, 1); PG8_STAGE(PG8_SB(1, 0), b3, voffB); PG8_STAGE(PG8_SB(1, 1), b3 + hstepB, voffB); PG8_STAGE(PG8_SA(1, 0), a3, voffA);
;             PG8_WAIT_V(8); PG8_WAIT_L(0); PG8_BAR; PG8_MMA(1, 0, At, B0); PG8_MMA(1, 1, At, B1); PG8_BAR; PG8_SCHED;
	s_setprio 1
	v_mfma_f32_16x16x32_bf16 v[60:63], v[128:131], v[160:163], 0
	v_mfma_f32_16x16x32_bf16 v[56:59], v[136:139], v[160:163], 0
	v_mfma_f32_16x16x32_bf16 v[44:47], v[128:131], v[168:171], 0
	v_mfma_f32_16x16x32_bf16 v[40:43], v[136:139], v[168:171], 0
	v_mfma_f32_16x16x32_bf16 v[28:31], v[128:131], v[192:195], 0
	v_mfma_f32_16x16x32_bf16 v[24:27], v[136:139], v[192:195], 0
	v_mfma_f32_16x16x32_bf16 v[12:15], v[128:131], v[200:203], 0
	v_mfma_f32_16x16x32_bf16 v[8:11], v[136:139], v[200:203], 0
	v_mfma_f32_16x16x32_bf16 v[60:63], v[132:135], v[164:167], v[60:63]
	v_mfma_f32_16x16x32_bf16 v[56:59], v[140:143], v[164:167], v[56:59]
	v_mfma_f32_16x16x32_bf16 v[44:47], v[132:135], v[172:175], v[44:47]
	v_mfma_f32_16x16x32_bf16 v[40:43], v[140:143], v[172:175], v[40:43]
	v_mfma_f32_16x16x32_bf16 v[28:31], v[132:135], v[196:199], v[28:31]
	v_mfma_f32_16x16x32_bf16 v[24:27], v[140:143], v[196:199], v[24:27]
	v_mfma_f32_16x16x32_bf16 v[12:15], v[132:135], v[204:207], v[12:15]
	v_mfma_f32_16x16x32_bf16 v[8:11], v[140:143], v[204:207], v[8:11]
	v_mfma_f32_16x16x32_bf16 v[52:55], v[144:147], v[160:163], 0
	v_mfma_f32_16x16x32_bf16 v[48:51], v[152:155], v[160:163], 0
	v_mfma_f32_16x16x32_bf16 v[36:39], v[144:147], v[168:171], 0
	v_mfma_f32_16x16x32_bf16 v[32:35], v[152:155], v[168:171], 0
	v_mfma_f32_16x16x32_bf16 v[20:23], v[144:147], v[192:195], 0
	v_mfma_f32_16x16x32_bf16 v[16:19], v[152:155], v[192:195], 0
	v_mfma_f32_16x16x32_bf16 v[4:7], v[144:147], v[200:203], 0
	v_mfma_f32_16x16x32_bf16 v[0:3], v[152:155], v[200:203], 0
	v_mfma_f32_16x16x32_bf16 v[52:55], v[148:151], v[164:167], v[52:55]
	v_mfma_f32_16x16x32_bf16 v[48:51], v[156:159], v[164:167], v[48:51]
	v_mfma_f32_16x16x32_bf16 v[36:39], v[148:151], v[172:175], v[36:39]
	v_mfma_f32_16x16x32_bf16 v[32:35], v[156:159], v[172:175], v[32:35]
	v_mfma_f32_16x16x32_bf16 v[20:23], v[148:151], v[196:199], v[20:23]
	v_mfma_f32_16x16x32_bf16 v[16:19], v[156:159], v[196:199], v[16:19]
	v_mfma_f32_16x16x32_bf16 v[4:7], v[148:151], v[204:207], v[4:7]
	v_mfma_f32_16x16x32_bf16 v[0:3], v[156:159], v[204:207], v[0:3]
	s_setprio 0
	s_barrier
	s_add_i32 s59, 0, 0x18000
	s_add_i32 s60, 0, 0x1c000
	v_add_u32_e32 v140, s59, v215
	v_add_u32_e32 v156, s60, v215
	ds_read_b128 v[128:131], v140
	ds_read_b128 v[132:135], v140 offset:1024
	ds_read_b128 v[136:139], v140 offset:2048
	ds_read_b128 v[140:143], v140 offset:3072
	ds_read_b128 v[144:147], v156
	ds_read_b128 v[148:151], v156 offset:1024
	ds_read_b128 v[152:155], v156 offset:2048
	ds_read_b128 v[156:159], v156 offset:3072
	s_add_u32 s36, s40, 0xb0000
	s_addc_u32 s37, s41, 0
	s_mov_b32 m0, s45
	v_lshl_add_u64 v[222:223], s[36:37], 0, v[176:177]
	ds_read_b128 v[160:163], v218 offset:32768
	ds_read_b128 v[164:167], v218 offset:33792
	ds_read_b128 v[168:171], v218 offset:34816
	ds_read_b128 v[172:175], v218 offset:35840
	ds_read_b128 v[192:195], v218 offset:36864
	ds_read_b128 v[196:199], v218 offset:37888
	ds_read_b128 v[200:203], v218 offset:38912
	ds_read_b128 v[204:207], v218 offset:39936
	global_load_lds_dwordx4 v[222:223], off
	v_lshl_add_u64 v[222:223], s[36:37], 0, v[180:181]
	s_mov_b32 m0, s46
	s_nop 0
	global_load_lds_dwordx4 v[222:223], off
	s_waitcnt vmcnt(8)
	s_waitcnt lgkmcnt(0)
	s_barrier
	s_setprio 1
	v_mfma_f32_16x16x32_bf16 v[124:127], v[128:131], v[160:163], v[124:127]
	v_mfma_f32_16x16x32_bf16 v[120:123], v[136:139], v[160:163], v[120:123]
	v_mfma_f32_16x16x32_bf16 v[108:111], v[128:131], v[168:171], v[108:111]
	v_mfma_f32_16x16x32_bf16 v[104:107], v[136:139], v[168:171], v[104:107]
	v_mfma_f32_16x16x32_bf16 v[92:95], v[128:131], v[192:195], v[92:95]
	v_mfma_f32_16x16x32_bf16 v[88:91], v[136:139], v[192:195], v[88:91]
	v_mfma_f32_16x16x32_bf16 v[76:79], v[128:131], v[200:203], v[76:79]
	v_mfma_f32_16x16x32_bf16 v[72:75], v[136:139], v[200:203], v[72:75]
	v_mfma_f32_16x16x32_bf16 v[124:127], v[132:135], v[164:167], v[124:127]
	v_mfma_f32_16x16x32_bf16 v[120:123], v[140:143], v[164:167], v[120:123]
	v_mfma_f32_16x16x32_bf16 v[108:111], v[132:135], v[172:175], v[108:111]
	v_mfma_f32_16x16x32_bf16 v[104:107], v[140:143], v[172:175], v[104:107]
	v_mfma_f32_16x16x32_bf16 v[92:95], v[132:135], v[196:199], v[92:95]
	v_mfma_f32_16x16x32_bf16 v[88:91], v[140:143], v[196:199], v[88:91]
	v_mfma_f32_16x16x32_bf16 v[76:79], v[132:135], v[204:207], v[76:79]
	v_mfma_f32_16x16x32_bf16 v[72:75], v[140:143], v[204:207], v[72:75]
	v_mfma_f32_16x16x32_bf16 v[116:119], v[144:147], v[160:163], v[116:119]
	v_mfma_f32_16x16x32_bf16 v[112:115], v[152:155], v[160:163], v[112:115]
	v_mfma_f32_16x16x32_bf16 v[100:103], v[144:147], v[168:171], v[100:103]
	v_mfma_f32_16x16x32_bf16 v[96:99], v[152:155], v[168:171], v[96:99]
	v_mfma_f32_16x16x32_bf16 v[84:87], v[144:147], v[192:195], v[84:87]
	v_mfma_f32_16x16x32_bf16 v[80:83], v[152:155], v[192:195], v[80:83]
	v_mfma_f32_16x16x32_bf16 v[68:71], v[144:147], v[200:203], v[68:71]
	v_mfma_f32_16x16x32_bf16 v[64:67], v[152:155], v[200:203], v[64:67]
	v_mfma_f32_16x16x32_bf16 v[116:119], v[148:151], v[164:167], v[116:119]
	v_mfma_f32_16x16x32_bf16 v[112:115], v[156:159], v[164:167], v[112:115]
	v_mfma_f32_16x16x32_bf16 v[100:103], v[148:151], v[172:175], v[100:103]
	v_mfma_f32_16x16x32_bf16 v[96:99], v[156:159], v[172:175], v[96:99]
	v_mfma_f32_16x16x32_bf16 v[84:87], v[148:151], v[196:199], v[84:87]
	v_mfma_f32_16x16x32_bf16 v[80:83], v[156:159], v[196:199], v[80:83]
	v_mfma_f32_16x16x32_bf16 v[68:71], v[148:151], v[204:207], v[68:71]
	v_mfma_f32_16x16x32_bf16 v[64:67], v[156:159], v[204:207], v[64:67]
	s_setprio 0
	s_barrier
; #define PG8_STAGE(bufoff, gbase, voff) do { _Pragma("unroll") for (int _i = 0; _i < 2; ++_i) \
;         __builtin_amdgcn_global_load_lds((const unsigned*)((const char*)(gbase) + (voff)[_i]), (LAS unsigned*)(lds + (bufoff) + ldsw + _i * 8192), 16, 0, 0); } while (0)
; #define PG8_LDA(dst, b, h) do { _Pragma("unroll") for (int m = 0; m < 4; ++m) _Pragma("unroll") for (int k = 0; k < 2; ++k) dst[m][k] = *(const LAS bf16x8*)(lds + PG8_SA(b, h) + aoff + m * 2048 + k * 1024); } while (0)
; #define PG8_LDB(dst, b, h) do { _Pragma("unroll") for (int n = 0; n < 2; ++n) _Pragma("unroll") for (int k = 0; k < 2; ++k) dst[n][k] = *(const LAS bf16x8*)(lds + PG8_SB(b, h) + boff + n * 2048 + k * 1024); } while (0)
; #define PG8_MMA(ai, bj, At, Bt) do { __builtin_amdgcn_s_setprio(1); _Pragma("unroll") for (int m = 0; m < 4; ++m) _Pragma("unroll") for (int n = 0; n < 2; ++n) _Pragma("unroll") for (int k = 0; k < 2; ++k) \
;         acc[ai][bj][m][n] = __builtin_amdgcn_mfma_f32_16x16x32_bf16(Bt[n][k], At[m][k], acc[ai][bj][m][n], 0, 0, 0); __builtin_amdgcn_s_setprio(0); } while (0)
; #define PG8_WAIT_V(n) asm volatile("s_waitcnt vmcnt(" #n ")" ::: "memory")
; #define PG8_WAIT_L(n) asm volatile("s_waitcnt lgkmcnt(" #n ")" ::: "memory")
; template <class Epi>
; DI void gemm_phase(LAS unsigned char* lds, const int wid, const Gemm g, const Order& S, const Epi& E) {
;     ...
;             PG8_LDB(B0, 0, 0); PG8_LDB(B1, 0, 1); PG8_SCHED; PG8_LDA(At, 0, 0); PG8_STAGE(PG8_SA(1, 1), a1 + hstepA, voffA);
;             PG8_WAIT_V(8); PG8_WAIT_L(0); PG8_BAR; PG8_MMA(0, 0, At, B0); PG8_MMA(0, 1, At, B1); PG8_BAR; PG8_SCHED;
;             PG8_LDA(At, 0, 1); PG8_STAGE(PG8_SB(0, 0), b2, voffB); PG8_STAGE(PG8_SB(0, 1), b2 + hstepB, voffB); PG8_STAGE(PG8_SA(0, 0), a2, voffA);
;             PG8_WAIT_V(8); PG8_WAIT_L(0); PG8_BAR; PG8_MMA(1, 0, At, B0); PG8_MMA(1, 1, At, B1); PG8_BAR; PG8_SCHED;
;             PG8_LDB(B0, 1, 0); PG8_LDB(B1, 1, 1); PG8_SCHED; PG8_LDA(At, 1, 0); PG8_STAGE(PG8_SA(0, 1), a2 + hstepA, voffA);
;             PG8_WAIT_V(8); PG8_WAIT_L(0); PG8_BAR; PG8_MMA(0, 0, At, B0); PG8_MMA(0, 1, At, B1); PG8_BAR; PG8_SCHED;
;             PG8_LDA(At, 1, 1); PG8_STAGE(PG8_SB(1, 0), b3, voffB); PG8_STAGE(PG8_SB(1, 1), b3 + hstepB, voffB); PG8_STAGE(PG8_SA(1, 0), a3, voffA);
;             PG8_WAIT_V(8); PG8_WAIT_L(0); PG8_BAR; PG8_MMA(1, 0, At, B0); PG8_MMA(1, 1, At, B1); PG8_BAR; PG8_SCHED;
	s_add_i32 s36, s59, s94
	v_lshl_add_u64 v[208:209], v[208:209], 0, s[26:27]
	s_mov_b32 m0, s36
	ds_read_b128 v[160:163], v218 offset:49152
	ds_read_b128 v[164:167], v218 offset:50176
	ds_read_b128 v[168:171], v218 offset:51200
	ds_read_b128 v[172:175], v218 offset:52224
	ds_read_b128 v[192:195], v218 offset:53248
	ds_read_b128 v[196:199], v218 offset:54272
	ds_read_b128 v[200:203], v218 offset:55296
	ds_read_b128 v[204:207], v218 offset:56320
	global_load_lds_dwordx4 v[208:209], off
	s_add_i32 m0, s36, 0x2000
	s_add_u32 s36, s38, 0xb0080
	v_lshl_add_u64 v[208:209], v[210:211], 0, s[26:27]
	s_addc_u32 s37, s39, 0
	s_add_i32 s38, s60, s94
	global_load_lds_dwordx4 v[208:209], off
	v_lshl_add_u64 v[208:209], s[36:37], 0, v[178:179]
	s_mov_b32 m0, s38
	s_nop 0
	global_load_lds_dwordx4 v[208:209], off
	v_lshl_add_u64 v[208:209], s[36:37], 0, v[182:183]
	s_add_i32 m0, s38, 0x2000
	s_nop 0
	global_load_lds_dwordx4 v[208:209], off
	v_lshl_add_u64 v[208:209], v[212:213], 0, s[26:27]
	s_mov_b32 m0, s48
	s_nop 0
	global_load_lds_dwordx4 v[208:209], off
	v_lshl_add_u64 v[208:209], v[220:221], 0, s[26:27]
	s_mov_b32 m0, s49
	s_nop 0
	global_load_lds_dwordx4 v[208:209], off
	s_waitcnt vmcnt(8)
	s_waitcnt lgkmcnt(0)
	s_barrier
	s_setprio 1
	v_mfma_f32_16x16x32_bf16 v[60:63], v[128:131], v[160:163], v[60:63]
	v_mfma_f32_16x16x32_bf16 v[56:59], v[136:139], v[160:163], v[56:59]
	v_mfma_f32_16x16x32_bf16 v[44:47], v[128:131], v[168:171], v[44:47]
	v_mfma_f32_16x16x32_bf16 v[40:43], v[136:139], v[168:171], v[40:43]
	v_mfma_f32_16x16x32_bf16 v[28:31], v[128:131], v[192:195], v[28:31]
	v_mfma_f32_16x16x32_bf16 v[24:27], v[136:139], v[192:195], v[24:27]
	v_mfma_f32_16x16x32_bf16 v[12:15], v[128:131], v[200:203], v[12:15]
	v_mfma_f32_16x16x32_bf16 v[8:11], v[136:139], v[200:203], v[8:11]
	v_mfma_f32_16x16x32_bf16 v[60:63], v[132:135], v[164:167], v[60:63]
	v_mfma_f32_16x16x32_bf16 v[56:59], v[140:143], v[164:167], v[56:59]
	v_mfma_f32_16x16x32_bf16 v[44:47], v[132:135], v[172:175], v[44:47]
	v_mfma_f32_16x16x32_bf16 v[40:43], v[140:143], v[172:175], v[40:43]
	v_mfma_f32_16x16x32_bf16 v[28:31], v[132:135], v[196:199], v[28:31]
	v_mfma_f32_16x16x32_bf16 v[24:27], v[140:143], v[196:199], v[24:27]
	v_mfma_f32_16x16x32_bf16 v[12:15], v[132:135], v[204:207], v[12:15]
	v_mfma_f32_16x16x32_bf16 v[8:11], v[140:143], v[204:207], v[8:11]
	v_mfma_f32_16x16x32_bf16 v[52:55], v[144:147], v[160:163], v[52:55]
	v_mfma_f32_16x16x32_bf16 v[48:51], v[152:155], v[160:163], v[48:51]
	v_mfma_f32_16x16x32_bf16 v[36:39], v[144:147], v[168:171], v[36:39]
	v_mfma_f32_16x16x32_bf16 v[32:35], v[152:155], v[168:171], v[32:35]
	v_mfma_f32_16x16x32_bf16 v[20:23], v[144:147], v[192:195], v[20:23]
	v_mfma_f32_16x16x32_bf16 v[16:19], v[152:155], v[192:195], v[16:19]
	v_mfma_f32_16x16x32_bf16 v[4:7], v[144:147], v[200:203], v[4:7]
	v_mfma_f32_16x16x32_bf16 v[0:3], v[152:155], v[200:203], v[0:3]
	v_mfma_f32_16x16x32_bf16 v[52:55], v[148:151], v[164:167], v[52:55]
	v_mfma_f32_16x16x32_bf16 v[48:51], v[156:159], v[164:167], v[48:51]
	v_mfma_f32_16x16x32_bf16 v[36:39], v[148:151], v[172:175], v[36:39]
	v_mfma_f32_16x16x32_bf16 v[32:35], v[156:159], v[172:175], v[32:35]
	v_mfma_f32_16x16x32_bf16 v[20:23], v[148:151], v[196:199], v[20:23]
	v_mfma_f32_16x16x32_bf16 v[16:19], v[156:159], v[196:199], v[16:19]
	v_mfma_f32_16x16x32_bf16 v[4:7], v[148:151], v[204:207], v[4:7]
	v_mfma_f32_16x16x32_bf16 v[0:3], v[156:159], v[204:207], v[0:3]
	s_setprio 0
	s_barrier
	s_add_i32 s58, s58, 2
	s_add_u32 s56, s56, 0x100
	s_addc_u32 s57, s57, 0
	s_cmp_gt_u32 s58, 41
	s_mov_b64 s[36:37], s[10:11]
	s_cbranch_scc0 .LBB0_1421
	s_branch .Lpeel_exit_10
.LBB0_1421:
	ds_read_b128 v[128:131], v216
	ds_read_b128 v[132:135], v216 offset:1024
	ds_read_b128 v[136:139], v216 offset:2048
	ds_read_b128 v[140:143], v216 offset:3072
	ds_read_b128 v[144:147], v217
	ds_read_b128 v[148:151], v217 offset:1024
	ds_read_b128 v[152:155], v217 offset:2048
	ds_read_b128 v[156:159], v217 offset:3072
	s_add_u32 s10, s36, 0x100
	s_addc_u32 s11, s37, 0
	s_cmp_eq_u32 s58, 40
	s_cselect_b32 s41, s31, s11
	s_cselect_b32 s40, s30, s10
	s_cselect_b32 s39, s35, s57
	s_cselect_b32 s38, s34, s56
	v_lshl_add_u64 v[208:209], s[36:37], 0, v[184:185]
	s_add_i32 m0, s43, 0xc000
	ds_read_b128 v[160:163], v218
	ds_read_b128 v[164:167], v218 offset:1024
	ds_read_b128 v[168:171], v218 offset:2048
	ds_read_b128 v[172:175], v218 offset:3072
	ds_read_b128 v[192:195], v218 offset:4096
	ds_read_b128 v[196:199], v218 offset:5120
	ds_read_b128 v[200:203], v218 offset:6144
	ds_read_b128 v[204:207], v218 offset:7168
	global_load_lds_dwordx4 v[208:209], off
	v_lshl_add_u64 v[208:209], s[36:37], 0, v[186:187]
	s_add_i32 m0, s43, 0xe000
	s_nop 0
	global_load_lds_dwordx4 v[208:209], off
	s_waitcnt vmcnt(8)
	s_waitcnt lgkmcnt(0)
	s_barrier
; #define PG8_STAGE(bufoff, gbase, voff) do { _Pragma("unroll") for (int _i = 0; _i < 2; ++_i) \
;         __builtin_amdgcn_global_load_lds((const unsigned*)((const char*)(gbase) + (voff)[_i]), (LAS unsigned*)(lds + (bufoff) + ldsw + _i * 8192), 16, 0, 0); } while (0)
; #define PG8_LDA(dst, b, h) do { _Pragma("unroll") for (int m = 0; m < 4; ++m) _Pragma("unroll") for (int k = 0; k < 2; ++k) dst[m][k] = *(const LAS bf16x8*)(lds + PG8_SA(b, h) + aoff + m * 2048 + k * 1024); } while (0)
; #define PG8_LDB(dst, b, h) do { _Pragma("unroll") for (int n = 0; n < 2; ++n) _Pragma("unroll") for (int k = 0; k < 2; ++k) dst[n][k] = *(const LAS bf16x8*)(lds + PG8_SB(b, h) + boff + n * 2048 + k * 1024); } while (0)
; #define PG8_MMA(ai, bj, At, Bt) do { __builtin_amdgcn_s_setprio(1); _Pragma("unroll") for (int m = 0; m < 4; ++m) _Pragma("unroll") for (int n = 0; n < 2; ++n) _Pragma("unroll") for (int k = 0; k < 2; ++k) \
;         acc[ai][bj][m][n] = __builtin_amdgcn_mfma_f32_16x16x32_bf16(Bt[n][k], At[m][k], acc[ai][bj][m][n], 0, 0, 0); __builtin_amdgcn_s_setprio(0); } while (0)
; #define PG8_WAIT_V(n) asm volatile("s_waitcnt vmcnt(" #n ")" ::: "memory")
; #define PG8_WAIT_L(n) asm volatile("s_waitcnt lgkmcnt(" #n ")" ::: "memory")
; #define PG8_BAR __builtin_amdgcn_s_barrier()
; #define PG8_SCHED __builtin_amdgcn_sched_barrier(0)
; template <class Epi>
; DI void gemm_phase(LAS unsigned char* lds, const int wid, const Gemm g, const Order& S, const Epi& E) {
;     ...
;             PG8_WAIT_V(8); PG8_WAIT_L(0); PG8_BAR; PG8_MMA(0, 0, At, B0); PG8_MMA(0, 1, At, B1); PG8_BAR; PG8_SCHED;
;             PG8_LDA(At, 0, 1); PG8_STAGE(PG8_SB(0, 0), b2, voffB); PG8_STAGE(PG8_SB(0, 1), b2 + hstepB, voffB); PG8_STAGE(PG8_SA(0, 0), a2, voffA);
;             PG8_WAIT_V(8); PG8_WAIT_L(0); PG8_BAR; PG8_MMA(1, 0, At, B0); PG8_MMA(1, 1, At, B1); PG8_BAR; PG8_SCHED;
;             PG8_LDB(B0, 1, 0); PG8_LDB(B1, 1, 1); PG8_SCHED; PG8_LDA(At, 1, 0); PG8_STAGE(PG8_SA(0, 1), a2 + hstepA, voffA);
;             PG8_WAIT_V(8); PG8_WAIT_L(0); PG8_BAR; PG8_MMA(0, 0, At, B0); PG8_MMA(0, 1, At, B1); PG8_BAR; PG8_SCHED;
	s_setprio 1
	v_mfma_f32_16x16x32_bf16 v[124:127], v[128:131], v[160:163], v[124:127]
	v_mfma_f32_16x16x32_bf16 v[120:123], v[136:139], v[160:163], v[120:123]
	v_mfma_f32_16x16x32_bf16 v[108:111], v[128:131], v[168:171], v[108:111]
	v_mfma_f32_16x16x32_bf16 v[104:107], v[136:139], v[168:171], v[104:107]
	v_mfma_f32_16x16x32_bf16 v[92:95], v[128:131], v[192:195], v[92:95]
	v_mfma_f32_16x16x32_bf16 v[88:91], v[136:139], v[192:195], v[88:91]
	v_mfma_f32_16x16x32_bf16 v[76:79], v[128:131], v[200:203], v[76:79]
	v_mfma_f32_16x16x32_bf16 v[72:75], v[136:139], v[200:203], v[72:75]
	v_mfma_f32_16x16x32_bf16 v[124:127], v[132:135], v[164:167], v[124:127]
	v_mfma_f32_16x16x32_bf16 v[120:123], v[140:143], v[164:167], v[120:123]
	v_mfma_f32_16x16x32_bf16 v[108:111], v[132:135], v[172:175], v[108:111]
	v_mfma_f32_16x16x32_bf16 v[104:107], v[140:143], v[172:175], v[104:107]
	v_mfma_f32_16x16x32_bf16 v[92:95], v[132:135], v[196:199], v[92:95]
	v_mfma_f32_16x16x32_bf16 v[88:91], v[140:143], v[196:199], v[88:91]
	v_mfma_f32_16x16x32_bf16 v[76:79], v[132:135], v[204:207], v[76:79]
	v_mfma_f32_16x16x32_bf16 v[72:75], v[140:143], v[204:207], v[72:75]
	v_mfma_f32_16x16x32_bf16 v[116:119], v[144:147], v[160:163], v[116:119]
	v_mfma_f32_16x16x32_bf16 v[112:115], v[152:155], v[160:163], v[112:115]
	v_mfma_f32_16x16x32_bf16 v[100:103], v[144:147], v[168:171], v[100:103]
	v_mfma_f32_16x16x32_bf16 v[96:99], v[152:155], v[168:171], v[96:99]
	v_mfma_f32_16x16x32_bf16 v[84:87], v[144:147], v[192:195], v[84:87]
	v_mfma_f32_16x16x32_bf16 v[80:83], v[152:155], v[192:195], v[80:83]
	v_mfma_f32_16x16x32_bf16 v[68:71], v[144:147], v[200:203], v[68:71]
	v_mfma_f32_16x16x32_bf16 v[64:67], v[152:155], v[200:203], v[64:67]
	v_mfma_f32_16x16x32_bf16 v[116:119], v[148:151], v[164:167], v[116:119]
	v_mfma_f32_16x16x32_bf16 v[112:115], v[156:159], v[164:167], v[112:115]
	v_mfma_f32_16x16x32_bf16 v[100:103], v[148:151], v[172:175], v[100:103]
	v_mfma_f32_16x16x32_bf16 v[96:99], v[156:159], v[172:175], v[96:99]
	v_mfma_f32_16x16x32_bf16 v[84:87], v[148:151], v[196:199], v[84:87]
	v_mfma_f32_16x16x32_bf16 v[80:83], v[156:159], v[196:199], v[80:83]
	v_mfma_f32_16x16x32_bf16 v[68:71], v[148:151], v[204:207], v[68:71]
	v_mfma_f32_16x16x32_bf16 v[64:67], v[156:159], v[204:207], v[64:67]
	s_setprio 0
	s_barrier
	s_add_i32 s36, s50, s94
	v_lshl_add_u64 v[208:209], s[38:39], 0, v[178:179]
	s_mov_b32 m0, s36
	ds_read_b128 v[160:163], v218 offset:16384
	ds_read_b128 v[164:167], v218 offset:17408
	ds_read_b128 v[168:171], v218 offset:18432
	ds_read_b128 v[172:175], v218 offset:19456
	ds_read_b128 v[192:195], v218 offset:20480
	ds_read_b128 v[196:199], v218 offset:21504
	ds_read_b128 v[200:203], v218 offset:22528
	ds_read_b128 v[204:207], v218 offset:23552
	global_load_lds_dwordx4 v[208:209], off
	s_add_i32 m0, s36, 0x2000
	s_add_u32 s36, s38, 0xb0000
	v_lshl_add_u64 v[210:211], s[38:39], 0, v[182:183]
	s_addc_u32 s37, s39, 0
	s_add_i32 s59, s51, s94
	global_load_lds_dwordx4 v[210:211], off
	v_lshl_add_u64 v[212:213], s[36:37], 0, v[178:179]
	s_mov_b32 m0, s59
	v_lshl_add_u64 v[220:221], s[40:41], 0, v[180:181]
	global_load_lds_dwordx4 v[212:213], off
	v_lshl_add_u64 v[212:213], s[36:37], 0, v[182:183]
	s_add_i32 m0, s59, 0x2000
	s_nop 0
	global_load_lds_dwordx4 v[212:213], off
	v_lshl_add_u64 v[212:213], s[40:41], 0, v[176:177]
	s_mov_b32 m0, s43
	s_nop 0
	global_load_lds_dwordx4 v[212:213], off
	s_mov_b32 m0, s44
	s_nop 0
	global_load_lds_dwordx4 v[220:221], off
	s_waitcnt vmcnt(8)
	s_waitcnt lgkmcnt(0)
	s_barrier
	s_setprio 1
	v_mfma_f32_16x16x32_bf16 v[60:63], v[128:131], v[160:163], v[60:63]
	v_mfma_f32_16x16x32_bf16 v[56:59], v[136:139], v[160:163], v[56:59]
	v_mfma_f32_16x16x32_bf16 v[44:47], v[128:131], v[168:171], v[44:47]
	v_mfma_f32_16x16x32_bf16 v[40:43], v[136:139], v[168:171], v[40:43]
	v_mfma_f32_16x16x32_bf16 v[28:31], v[128:131], v[192:195], v[28:31]
	v_mfma_f32_16x16x32_bf16 v[24:27], v[136:139], v[192:195], v[24:27]
	v_mfma_f32_16x16x32_bf16 v[12:15], v[128:131], v[200:203], v[12:15]
	v_mfma_f32_16x16x32_bf16 v[8:11], v[136:139], v[200:203], v[8:11]
	v_mfma_f32_16x16x32_bf16 v[60:63], v[132:135], v[164:167], v[60:63]
	v_mfma_f32_16x16x32_bf16 v[56:59], v[140:143], v[164:167], v[56:59]
	v_mfma_f32_16x16x32_bf16 v[44:47], v[132:135], v[172:175], v[44:47]
	v_mfma_f32_16x16x32_bf16 v[40:43], v[140:143], v[172:175], v[40:43]
	v_mfma_f32_16x16x32_bf16 v[28:31], v[132:135], v[196:199], v[28:31]
	v_mfma_f32_16x16x32_bf16 v[24:27], v[140:143], v[196:199], v[24:27]
	v_mfma_f32_16x16x32_bf16 v[12:15], v[132:135], v[204:207], v[12:15]
	v_mfma_f32_16x16x32_bf16 v[8:11], v[140:143], v[204:207], v[8:11]
	v_mfma_f32_16x16x32_bf16 v[52:55], v[144:147], v[160:163], v[52:55]
	v_mfma_f32_16x16x32_bf16 v[48:51], v[152:155], v[160:163], v[48:51]
	v_mfma_f32_16x16x32_bf16 v[36:39], v[144:147], v[168:171], v[36:39]
	v_mfma_f32_16x16x32_bf16 v[32:35], v[152:155], v[168:171], v[32:35]
	v_mfma_f32_16x16x32_bf16 v[20:23], v[144:147], v[192:195], v[20:23]
	v_mfma_f32_16x16x32_bf16 v[16:19], v[152:155], v[192:195], v[16:19]
	v_mfma_f32_16x16x32_bf16 v[4:7], v[144:147], v[200:203], v[4:7]
	v_mfma_f32_16x16x32_bf16 v[0:3], v[152:155], v[200:203], v[0:3]
	v_mfma_f32_16x16x32_bf16 v[52:55], v[148:151], v[164:167], v[52:55]
	v_mfma_f32_16x16x32_bf16 v[48:51], v[156:159], v[164:167], v[48:51]
	v_mfma_f32_16x16x32_bf16 v[36:39], v[148:151], v[172:175], v[36:39]
	v_mfma_f32_16x16x32_bf16 v[32:35], v[156:159], v[172:175], v[32:35]
	v_mfma_f32_16x16x32_bf16 v[20:23], v[148:151], v[196:199], v[20:23]
	v_mfma_f32_16x16x32_bf16 v[16:19], v[156:159], v[196:199], v[16:19]
	v_mfma_f32_16x16x32_bf16 v[4:7], v[148:151], v[204:207], v[4:7]
	v_mfma_f32_16x16x32_bf16 v[0:3], v[156:159], v[204:207], v[0:3]
	s_setprio 0
	s_barrier
; #define PG8_STAGE(bufoff, gbase, voff) do { _Pragma("unroll") for (int _i = 0; _i < 2; ++_i) \
;         __builtin_amdgcn_global_load_lds((const unsigned*)((const char*)(gbase) + (voff)[_i]), (LAS unsigned*)(lds + (bufoff) + ldsw + _i * 8192), 16, 0, 0); } while (0)
; #define PG8_LDA(dst, b, h) do { _Pragma("unroll") for (int m = 0; m < 4; ++m) _Pragma("unroll") for (int k = 0; k < 2; ++k) dst[m][k] = *(const LAS bf16x8*)(lds + PG8_SA(b, h) + aoff + m * 2048 + k * 1024); } while (0)
; #define PG8_LDB(dst, b, h) do { _Pragma("unroll") for (int n = 0; n < 2; ++n) _Pragma("unroll") for (int k = 0; k < 2; ++k) dst[n][k] = *(const LAS bf16x8*)(lds + PG8_SB(b, h) + boff + n * 2048 + k * 1024); } while (0)
; #define PG8_MMA(ai, bj, At, Bt) do { __builtin_amdgcn_s_setprio(1); _Pragma("unroll") for (int m = 0; m < 4; ++m) _Pragma("unroll") for (int n = 0; n < 2; ++n) _Pragma("unroll") for (int k = 0; k < 2; ++k) \
;         acc[ai][bj][m][n] = __builtin_amdgcn_mfma_f32_16x16x32_bf16(Bt[n][k], At[m][k], acc[ai][bj][m][n], 0, 0, 0); __builtin_amdgcn_s_setprio(0); } while (0)
; #define PG8_WAIT_V(n) asm volatile("s_waitcnt vmcnt(" #n ")" ::: "memory")
; #define PG8_WAIT_L(n) asm volatile("s_waitcnt lgkmcnt(" #n ")" ::: "memory")
; #define PG8_BAR __builtin_amdgcn_s_barrier()
; #define PG8_SCHED __builtin_amdgcn_sched_barrier(0)
; template <class Epi>
; DI void gemm_phase(LAS unsigned char* lds, const int wid, const Gemm g, const Order& S, const Epi& E) {
;     ...
;         for (int t = 0; t < nt; t += 2) {
;     ...
;             PG8_LDB(B0, 1, 0); PG8_LDB(B1, 1, 1); PG8_SCHED; PG8_LDA(At, 1, 0); PG8_STAGE(PG8_SA(0, 1), a2 + hstepA, voffA);
;             PG8_WAIT_V(8); PG8_WAIT_L(0); PG8_BAR; PG8_MMA(0, 0, At, B0); PG8_MMA(0, 1, At, B1); PG8_BAR; PG8_SCHED;
;             PG8_LDA(At, 1, 1); PG8_STAGE(PG8_SB(1, 0), b3, voffB); PG8_STAGE(PG8_SB(1, 1), b3 + hstepB, voffB); PG8_STAGE(PG8_SA(1, 0), a3, voffA);
;             PG8_WAIT_V(8); PG8_WAIT_L(0); PG8_BAR; PG8_MMA(1, 0, At, B0); PG8_MMA(1, 1, At, B1); PG8_BAR; PG8_SCHED;
	s_add_i32 s59, 0, 0x18000
	s_add_i32 s60, 0, 0x1c000
	v_add_u32_e32 v140, s59, v215
	v_add_u32_e32 v156, s60, v215
	ds_read_b128 v[128:131], v140
	ds_read_b128 v[132:135], v140 offset:1024
	ds_read_b128 v[136:139], v140 offset:2048
	ds_read_b128 v[140:143], v140 offset:3072
	ds_read_b128 v[144:147], v156
	ds_read_b128 v[148:151], v156 offset:1024
	ds_read_b128 v[152:155], v156 offset:2048
	ds_read_b128 v[156:159], v156 offset:3072
	s_add_u32 s36, s40, 0xb0000
	s_addc_u32 s37, s41, 0
	s_mov_b32 m0, s45
	v_lshl_add_u64 v[222:223], s[36:37], 0, v[176:177]
	ds_read_b128 v[160:163], v218 offset:32768
	ds_read_b128 v[164:167], v218 offset:33792
	ds_read_b128 v[168:171], v218 offset:34816
	ds_read_b128 v[172:175], v218 offset:35840
	ds_read_b128 v[192:195], v218 offset:36864
	ds_read_b128 v[196:199], v218 offset:37888
	ds_read_b128 v[200:203], v218 offset:38912
	ds_read_b128 v[204:207], v218 offset:39936
	global_load_lds_dwordx4 v[222:223], off
	v_lshl_add_u64 v[222:223], s[36:37], 0, v[180:181]
	s_mov_b32 m0, s46
	s_nop 0
	global_load_lds_dwordx4 v[222:223], off
	s_waitcnt vmcnt(8)
	s_waitcnt lgkmcnt(0)
	s_barrier
	s_setprio 1
	v_mfma_f32_16x16x32_bf16 v[124:127], v[128:131], v[160:163], v[124:127]
	v_mfma_f32_16x16x32_bf16 v[120:123], v[136:139], v[160:163], v[120:123]
	v_mfma_f32_16x16x32_bf16 v[108:111], v[128:131], v[168:171], v[108:111]
	v_mfma_f32_16x16x32_bf16 v[104:107], v[136:139], v[168:171], v[104:107]
	v_mfma_f32_16x16x32_bf16 v[92:95], v[128:131], v[192:195], v[92:95]
	v_mfma_f32_16x16x32_bf16 v[88:91], v[136:139], v[192:195], v[88:91]
	v_mfma_f32_16x16x32_bf16 v[76:79], v[128:131], v[200:203], v[76:79]
	v_mfma_f32_16x16x32_bf16 v[72:75], v[136:139], v[200:203], v[72:75]
	v_mfma_f32_16x16x32_bf16 v[124:127], v[132:135], v[164:167], v[124:127]
	v_mfma_f32_16x16x32_bf16 v[120:123], v[140:143], v[164:167], v[120:123]
	v_mfma_f32_16x16x32_bf16 v[108:111], v[132:135], v[172:175], v[108:111]
	v_mfma_f32_16x16x32_bf16 v[104:107], v[140:143], v[172:175], v[104:107]
	v_mfma_f32_16x16x32_bf16 v[92:95], v[132:135], v[196:199], v[92:95]
	v_mfma_f32_16x16x32_bf16 v[88:91], v[140:143], v[196:199], v[88:91]
	v_mfma_f32_16x16x32_bf16 v[76:79], v[132:135], v[204:207], v[76:79]
	v_mfma_f32_16x16x32_bf16 v[72:75], v[140:143], v[204:207], v[72:75]
	v_mfma_f32_16x16x32_bf16 v[116:119], v[144:147], v[160:163], v[116:119]
	v_mfma_f32_16x16x32_bf16 v[112:115], v[152:155], v[160:163], v[112:115]
	v_mfma_f32_16x16x32_bf16 v[100:103], v[144:147], v[168:171], v[100:103]
	v_mfma_f32_16x16x32_bf16 v[96:99], v[152:155], v[168:171], v[96:99]
	v_mfma_f32_16x16x32_bf16 v[84:87], v[144:147], v[192:195], v[84:87]
	v_mfma_f32_16x16x32_bf16 v[80:83], v[152:155], v[192:195], v[80:83]
	v_mfma_f32_16x16x32_bf16 v[68:71], v[144:147], v[200:203], v[68:71]
	v_mfma_f32_16x16x32_bf16 v[64:67], v[152:155], v[200:203], v[64:67]
	v_mfma_f32_16x16x32_bf16 v[116:119], v[148:151], v[164:167], v[116:119]
	v_mfma_f32_16x16x32_bf16 v[112:115], v[156:159], v[164:167], v[112:115]
	v_mfma_f32_16x16x32_bf16 v[100:103], v[148:151], v[172:175], v[100:103]
	v_mfma_f32_16x16x32_bf16 v[96:99], v[156:159], v[172:175], v[96:99]
	v_mfma_f32_16x16x32_bf16 v[84:87], v[148:151], v[196:199], v[84:87]
	v_mfma_f32_16x16x32_bf16 v[80:83], v[156:159], v[196:199], v[80:83]
	v_mfma_f32_16x16x32_bf16 v[68:71], v[148:151], v[204:207], v[68:71]
	v_mfma_f32_16x16x32_bf16 v[64:67], v[156:159], v[204:207], v[64:67]
	s_setprio 0
	s_barrier
	s_add_i32 s36, s59, s94
	v_lshl_add_u64 v[208:209], v[208:209], 0, s[26:27]
	s_mov_b32 m0, s36
	ds_read_b128 v[160:163], v218 offset:49152
	ds_read_b128 v[164:167], v218 offset:50176
	ds_read_b128 v[168:171], v218 offset:51200
	ds_read_b128 v[172:175], v218 offset:52224
	ds_read_b128 v[192:195], v218 offset:53248
	ds_read_b128 v[196:199], v218 offset:54272
	ds_read_b128 v[200:203], v218 offset:55296
	ds_read_b128 v[204:207], v218 offset:56320
	global_load_lds_dwordx4 v[208:209], off
	s_add_i32 m0, s36, 0x2000
	s_add_u32 s36, s38, 0xb0080
	v_lshl_add_u64 v[208:209], v[210:211], 0, s[26:27]
	s_addc_u32 s37, s39, 0
	s_add_i32 s38, s60, s94
	global_load_lds_dwordx4 v[208:209], off
	v_lshl_add_u64 v[208:209], s[36:37], 0, v[178:179]
	s_mov_b32 m0, s38
	s_nop 0
	global_load_lds_dwordx4 v[208:209], off
	v_lshl_add_u64 v[208:209], s[36:37], 0, v[182:183]
	s_add_i32 m0, s38, 0x2000
	s_nop 0
	global_load_lds_dwordx4 v[208:209], off
	v_lshl_add_u64 v[208:209], v[212:213], 0, s[26:27]
	s_mov_b32 m0, s48
	s_nop 0
	global_load_lds_dwordx4 v[208:209], off
	v_lshl_add_u64 v[208:209], v[220:221], 0, s[26:27]
	s_mov_b32 m0, s49
	s_nop 0
	global_load_lds_dwordx4 v[208:209], off
	s_waitcnt vmcnt(8)
	s_waitcnt lgkmcnt(0)
	s_barrier
	s_setprio 1
	v_mfma_f32_16x16x32_bf16 v[60:63], v[128:131], v[160:163], v[60:63]
	v_mfma_f32_16x16x32_bf16 v[56:59], v[136:139], v[160:163], v[56:59]
	v_mfma_f32_16x16x32_bf16 v[44:47], v[128:131], v[168:171], v[44:47]
	v_mfma_f32_16x16x32_bf16 v[40:43], v[136:139], v[168:171], v[40:43]
	v_mfma_f32_16x16x32_bf16 v[28:31], v[128:131], v[192:195], v[28:31]
	v_mfma_f32_16x16x32_bf16 v[24:27], v[136:139], v[192:195], v[24:27]
	v_mfma_f32_16x16x32_bf16 v[12:15], v[128:131], v[200:203], v[12:15]
	v_mfma_f32_16x16x32_bf16 v[8:11], v[136:139], v[200:203], v[8:11]
	v_mfma_f32_16x16x32_bf16 v[60:63], v[132:135], v[164:167], v[60:63]
	v_mfma_f32_16x16x32_bf16 v[56:59], v[140:143], v[164:167], v[56:59]
	v_mfma_f32_16x16x32_bf16 v[44:47], v[132:135], v[172:175], v[44:47]
	v_mfma_f32_16x16x32_bf16 v[40:43], v[140:143], v[172:175], v[40:43]
	v_mfma_f32_16x16x32_bf16 v[28:31], v[132:135], v[196:199], v[28:31]
	v_mfma_f32_16x16x32_bf16 v[24:27], v[140:143], v[196:199], v[24:27]
	v_mfma_f32_16x16x32_bf16 v[12:15], v[132:135], v[204:207], v[12:15]
	v_mfma_f32_16x16x32_bf16 v[8:11], v[140:143], v[204:207], v[8:11]
	v_mfma_f32_16x16x32_bf16 v[52:55], v[144:147], v[160:163], v[52:55]
	v_mfma_f32_16x16x32_bf16 v[48:51], v[152:155], v[160:163], v[48:51]
	v_mfma_f32_16x16x32_bf16 v[36:39], v[144:147], v[168:171], v[36:39]
	v_mfma_f32_16x16x32_bf16 v[32:35], v[152:155], v[168:171], v[32:35]
	v_mfma_f32_16x16x32_bf16 v[20:23], v[144:147], v[192:195], v[20:23]
	v_mfma_f32_16x16x32_bf16 v[16:19], v[152:155], v[192:195], v[16:19]
	v_mfma_f32_16x16x32_bf16 v[4:7], v[144:147], v[200:203], v[4:7]
	v_mfma_f32_16x16x32_bf16 v[0:3], v[152:155], v[200:203], v[0:3]
	v_mfma_f32_16x16x32_bf16 v[52:55], v[148:151], v[164:167], v[52:55]
	v_mfma_f32_16x16x32_bf16 v[48:51], v[156:159], v[164:167], v[48:51]
	v_mfma_f32_16x16x32_bf16 v[36:39], v[148:151], v[172:175], v[36:39]
	v_mfma_f32_16x16x32_bf16 v[32:35], v[156:159], v[172:175], v[32:35]
	v_mfma_f32_16x16x32_bf16 v[20:23], v[148:151], v[196:199], v[20:23]
	v_mfma_f32_16x16x32_bf16 v[16:19], v[156:159], v[196:199], v[16:19]
	v_mfma_f32_16x16x32_bf16 v[4:7], v[148:151], v[204:207], v[4:7]
	v_mfma_f32_16x16x32_bf16 v[0:3], v[156:159], v[204:207], v[0:3]
	s_setprio 0
	s_barrier
	s_add_i32 s58, s58, 2
	s_add_u32 s56, s56, 0x100
	s_addc_u32 s57, s57, 0
	s_cmp_gt_u32 s58, 41
	s_mov_b64 s[36:37], s[10:11]
	s_cbranch_scc0 .LBB0_1421

; #define PG8_STAGE(bufoff, gbase, voff) do { _Pragma("unroll") for (int _i = 0; _i < 2; ++_i) \
;         __builtin_amdgcn_global_load_lds((const unsigned*)((const char*)(gbase) + (voff)[_i]), (LAS unsigned*)(lds + (bufoff) + ldsw + _i * 8192), 16, 0, 0); } while (0)
; #define PG8_LDA(dst, b, h) do { _Pragma("unroll") for (int m = 0; m < 4; ++m) _Pragma("unroll") for (int k = 0; k < 2; ++k) dst[m][k] = *(const LAS bf16x8*)(lds + PG8_SA(b, h) + aoff + m * 2048 + k * 1024); } while (0)
; #define PG8_LDB(dst, b, h) do { _Pragma("unroll") for (int n = 0; n < 2; ++n) _Pragma("unroll") for (int k = 0; k < 2; ++k) dst[n][k] = *(const LAS bf16x8*)(lds + PG8_SB(b, h) + boff + n * 2048 + k * 1024); } while (0)
; #define PG8_MMA(ai, bj, At, Bt) do { __builtin_amdgcn_s_setprio(1); _Pragma("unroll") for (int m = 0; m < 4; ++m) _Pragma("unroll") for (int n = 0; n < 2; ++n) _Pragma("unroll") for (int k = 0; k < 2; ++k) \
;         acc[ai][bj][m][n] = __builtin_amdgcn_mfma_f32_16x16x32_bf16(Bt[n][k], At[m][k], acc[ai][bj][m][n], 0, 0, 0); __builtin_amdgcn_s_setprio(0); } while (0)
; #define PG8_WAIT_V(n) asm volatile("s_waitcnt vmcnt(" #n ")" ::: "memory")
; template <class Epi>
; DI void gemm_phase(LAS unsigned char* lds, const int wid, const Gemm g, const Order& S, const Epi& E) {
;     ...
;         const char* nA = has_next ? (const char*)(g.A + (size_t)nxt.g * g.gsA + (size_t)nxt.pm * BM * g.lda) : cA;
;         const char* nB = has_next ? (const char*)(g.Bt + (size_t)nxt.g * g.gsB + (size_t)nxt.pn * BM * g.ldb) : cB;
;         for (int t = 0; t < nt; t += 2) {
;             const bool last = (t == nt - 2);
;             const char* a1 = cA + (size_t)(t + 1) * kstep;
;             const char* a2 = last ? nA : cA + (size_t)(t + 2) * kstep; const char* b2 = last ? nB : cB + (size_t)(t + 2) * kstep;
;             const char* a3 = a2 + kstep; const char* b3 = b2 + kstep;
;             PG8_LDB(B0, 0, 0); PG8_LDB(B1, 0, 1); PG8_SCHED; PG8_LDA(At, 0, 0); PG8_STAGE(PG8_SA(1, 1), a1 + hstepA, voffA);
;             PG8_WAIT_V(8); PG8_WAIT_L(0); PG8_BAR; PG8_MMA(0, 0, At, B0); PG8_MMA(0, 1, At, B1); PG8_BAR; PG8_SCHED;
;             PG8_LDA(At, 0, 1); PG8_STAGE(PG8_SB(0, 0), b2, voffB); PG8_STAGE(PG8_SB(0, 1), b2 + hstepB, voffB); PG8_STAGE(PG8_SA(0, 0), a2, voffA);
;             PG8_WAIT_V(8); PG8_WAIT_L(0); PG8_BAR; PG8_MMA(1, 0, At, B0); PG8_MMA(1, 1, At, B1); PG8_BAR; PG8_SCHED;
.LBB0_1525:
	s_add_u32 s52, s26, 0x100
	v_mov_b32_e32 v0, 0
	s_addc_u32 s53, s27, 0
	s_mov_b32 s54, -2
	ds_read_b128 v[128:131], v229
	ds_read_b128 v[132:135], v229 offset:1024
	ds_read_b128 v[136:139], v229 offset:2048
	ds_read_b128 v[140:143], v229 offset:3072
	ds_read_b128 v[144:147], v230
	ds_read_b128 v[148:151], v230 offset:1024
	ds_read_b128 v[152:155], v230 offset:2048
	ds_read_b128 v[156:159], v230 offset:3072
	s_add_u32 s4, s24, 0x100
	s_addc_u32 s5, s25, 0
	s_cmp_eq_u32 s54, 40
	s_cselect_b32 s29, s21, s5
	s_cselect_b32 s28, s20, s4
	s_cselect_b32 s27, s23, s53
	s_cselect_b32 s26, s22, s52
	v_lshl_add_u64 v[208:209], s[24:25], 0, v[184:185]
	s_add_i32 m0, s36, 0xc000
	ds_read_b128 v[160:163], v231
	ds_read_b128 v[164:167], v231 offset:1024
	ds_read_b128 v[168:171], v231 offset:2048
	ds_read_b128 v[172:175], v231 offset:3072
	ds_read_b128 v[192:195], v231 offset:4096
	ds_read_b128 v[196:199], v231 offset:5120
	ds_read_b128 v[200:203], v231 offset:6144
	ds_read_b128 v[204:207], v231 offset:7168
	global_load_lds_dwordx4 v[208:209], off
	v_lshl_add_u64 v[208:209], s[24:25], 0, v[186:187]
	s_add_i32 m0, s36, 0xe000
	s_nop 0
	global_load_lds_dwordx4 v[208:209], off
	s_waitcnt vmcnt(8)
	s_waitcnt lgkmcnt(0)
	s_barrier
	s_setprio 1
	v_mfma_f32_16x16x32_bf16 v[124:127], v[128:131], v[160:163], 0
	v_mfma_f32_16x16x32_bf16 v[120:123], v[136:139], v[160:163], 0
	v_mfma_f32_16x16x32_bf16 v[108:111], v[128:131], v[168:171], 0
	v_mfma_f32_16x16x32_bf16 v[104:107], v[136:139], v[168:171], 0
	v_mfma_f32_16x16x32_bf16 v[92:95], v[128:131], v[192:195], 0
	v_mfma_f32_16x16x32_bf16 v[88:91], v[136:139], v[192:195], 0
	v_mfma_f32_16x16x32_bf16 v[76:79], v[128:131], v[200:203], 0
	v_mfma_f32_16x16x32_bf16 v[72:75], v[136:139], v[200:203], 0
	v_mfma_f32_16x16x32_bf16 v[124:127], v[132:135], v[164:167], v[124:127]
	v_mfma_f32_16x16x32_bf16 v[120:123], v[140:143], v[164:167], v[120:123]
	v_mfma_f32_16x16x32_bf16 v[108:111], v[132:135], v[172:175], v[108:111]
	v_mfma_f32_16x16x32_bf16 v[104:107], v[140:143], v[172:175], v[104:107]
	v_mfma_f32_16x16x32_bf16 v[92:95], v[132:135], v[196:199], v[92:95]
	v_mfma_f32_16x16x32_bf16 v[88:91], v[140:143], v[196:199], v[88:91]
	v_mfma_f32_16x16x32_bf16 v[76:79], v[132:135], v[204:207], v[76:79]
	v_mfma_f32_16x16x32_bf16 v[72:75], v[140:143], v[204:207], v[72:75]
	v_mfma_f32_16x16x32_bf16 v[116:119], v[144:147], v[160:163], 0
	v_mfma_f32_16x16x32_bf16 v[112:115], v[152:155], v[160:163], 0
	v_mfma_f32_16x16x32_bf16 v[100:103], v[144:147], v[168:171], 0
	v_mfma_f32_16x16x32_bf16 v[96:99], v[152:155], v[168:171], 0
	v_mfma_f32_16x16x32_bf16 v[84:87], v[144:147], v[192:195], 0
	v_mfma_f32_16x16x32_bf16 v[80:83], v[152:155], v[192:195], 0
	v_mfma_f32_16x16x32_bf16 v[68:71], v[144:147], v[200:203], 0
	v_mfma_f32_16x16x32_bf16 v[64:67], v[152:155], v[200:203], 0
	v_mfma_f32_16x16x32_bf16 v[116:119], v[148:151], v[164:167], v[116:119]
	v_mfma_f32_16x16x32_bf16 v[112:115], v[156:159], v[164:167], v[112:115]
	v_mfma_f32_16x16x32_bf16 v[100:103], v[148:151], v[172:175], v[100:103]
	v_mfma_f32_16x16x32_bf16 v[96:99], v[156:159], v[172:175], v[96:99]
	v_mfma_f32_16x16x32_bf16 v[84:87], v[148:151], v[196:199], v[84:87]
	v_mfma_f32_16x16x32_bf16 v[80:83], v[156:159], v[196:199], v[80:83]
	v_mfma_f32_16x16x32_bf16 v[68:71], v[148:151], v[204:207], v[68:71]
	v_mfma_f32_16x16x32_bf16 v[64:67], v[156:159], v[204:207], v[64:67]
	s_setprio 0
	s_barrier
	s_add_i32 s24, s46, s94
	v_lshl_add_u64 v[208:209], s[26:27], 0, v[178:179]
	s_mov_b32 m0, s24
	ds_read_b128 v[160:163], v231 offset:16384
	ds_read_b128 v[164:167], v231 offset:17408
	ds_read_b128 v[168:171], v231 offset:18432
	ds_read_b128 v[172:175], v231 offset:19456
	ds_read_b128 v[192:195], v231 offset:20480
	ds_read_b128 v[196:199], v231 offset:21504
	ds_read_b128 v[200:203], v231 offset:22528
	ds_read_b128 v[204:207], v231 offset:23552
	global_load_lds_dwordx4 v[208:209], off
	s_add_i32 m0, s24, 0x2000
	s_add_u32 s24, s26, 0xb0000
	v_lshl_add_u64 v[210:211], s[26:27], 0, v[182:183]
	s_addc_u32 s25, s27, 0
	s_add_i32 s55, s47, s94
	global_load_lds_dwordx4 v[210:211], off
	v_lshl_add_u64 v[212:213], s[24:25], 0, v[178:179]
	s_mov_b32 m0, s55
	v_lshl_add_u64 v[214:215], s[28:29], 0, v[180:181]
	global_load_lds_dwordx4 v[212:213], off
	v_lshl_add_u64 v[212:213], s[24:25], 0, v[182:183]
	s_add_i32 m0, s55, 0x2000
	s_nop 0
	global_load_lds_dwordx4 v[212:213], off
	v_lshl_add_u64 v[212:213], s[28:29], 0, v[176:177]
	s_mov_b32 m0, s36
	s_nop 0
	global_load_lds_dwordx4 v[212:213], off
	s_mov_b32 m0, s37
	s_nop 0
	global_load_lds_dwordx4 v[214:215], off
	s_waitcnt vmcnt(8)
	s_waitcnt lgkmcnt(0)
	s_barrier
; #define PG8_STAGE(bufoff, gbase, voff) do { _Pragma("unroll") for (int _i = 0; _i < 2; ++_i) \
;         __builtin_amdgcn_global_load_lds((const unsigned*)((const char*)(gbase) + (voff)[_i]), (LAS unsigned*)(lds + (bufoff) + ldsw + _i * 8192), 16, 0, 0); } while (0)
; #define PG8_LDA(dst, b, h) do { _Pragma("unroll") for (int m = 0; m < 4; ++m) _Pragma("unroll") for (int k = 0; k < 2; ++k) dst[m][k] = *(const LAS bf16x8*)(lds + PG8_SA(b, h) + aoff + m * 2048 + k * 1024); } while (0)
; #define PG8_LDB(dst, b, h) do { _Pragma("unroll") for (int n = 0; n < 2; ++n) _Pragma("unroll") for (int k = 0; k < 2; ++k) dst[n][k] = *(const LAS bf16x8*)(lds + PG8_SB(b, h) + boff + n * 2048 + k * 1024); } while (0)
; #define PG8_MMA(ai, bj, At, Bt) do { __builtin_amdgcn_s_setprio(1); _Pragma("unroll") for (int m = 0; m < 4; ++m) _Pragma("unroll") for (int n = 0; n < 2; ++n) _Pragma("unroll") for (int k = 0; k < 2; ++k) \
;         acc[ai][bj][m][n] = __builtin_amdgcn_mfma_f32_16x16x32_bf16(Bt[n][k], At[m][k], acc[ai][bj][m][n], 0, 0, 0); __builtin_amdgcn_s_setprio(0); } while (0)
; #define PG8_WAIT_V(n) asm volatile("s_waitcnt vmcnt(" #n ")" ::: "memory")
; #define PG8_WAIT_L(n) asm volatile("s_waitcnt lgkmcnt(" #n ")" ::: "memory")
; #define PG8_BAR __builtin_amdgcn_s_barrier()
; #define PG8_SCHED __builtin_amdgcn_sched_barrier(0)
; template <class Epi>
; DI void gemm_phase(LAS unsigned char* lds, const int wid, const Gemm g, const Order& S, const Epi& E) {
;     ...
;             PG8_WAIT_V(8); PG8_WAIT_L(0); PG8_BAR; PG8_MMA(1, 0, At, B0); PG8_MMA(1, 1, At, B1); PG8_BAR; PG8_SCHED;
;             PG8_LDB(B0, 1, 0); PG8_LDB(B1, 1, 1); PG8_SCHED; PG8_LDA(At, 1, 0); PG8_STAGE(PG8_SA(0, 1), a2 + hstepA, voffA);
;             PG8_WAIT_V(8); PG8_WAIT_L(0); PG8_BAR; PG8_MMA(0, 0, At, B0); PG8_MMA(0, 1, At, B1); PG8_BAR; PG8_SCHED;
;             PG8_LDA(At, 1, 1); PG8_STAGE(PG8_SB(1, 0), b3, voffB); PG8_STAGE(PG8_SB(1, 1), b3 + hstepB, voffB); PG8_STAGE(PG8_SA(1, 0), a3, voffA);
;             PG8_WAIT_V(8); PG8_WAIT_L(0); PG8_BAR; PG8_MMA(1, 0, At, B0); PG8_MMA(1, 1, At, B1); PG8_BAR; PG8_SCHED;
	s_setprio 1
	v_mfma_f32_16x16x32_bf16 v[60:63], v[128:131], v[160:163], 0
	v_mfma_f32_16x16x32_bf16 v[56:59], v[136:139], v[160:163], 0
	v_mfma_f32_16x16x32_bf16 v[44:47], v[128:131], v[168:171], 0
	v_mfma_f32_16x16x32_bf16 v[40:43], v[136:139], v[168:171], 0
	v_mfma_f32_16x16x32_bf16 v[28:31], v[128:131], v[192:195], 0
	v_mfma_f32_16x16x32_bf16 v[24:27], v[136:139], v[192:195], 0
	v_mfma_f32_16x16x32_bf16 v[12:15], v[128:131], v[200:203], 0
	v_mfma_f32_16x16x32_bf16 v[8:11], v[136:139], v[200:203], 0
	v_mfma_f32_16x16x32_bf16 v[60:63], v[132:135], v[164:167], v[60:63]
	v_mfma_f32_16x16x32_bf16 v[56:59], v[140:143], v[164:167], v[56:59]
	v_mfma_f32_16x16x32_bf16 v[44:47], v[132:135], v[172:175], v[44:47]
	v_mfma_f32_16x16x32_bf16 v[40:43], v[140:143], v[172:175], v[40:43]
	v_mfma_f32_16x16x32_bf16 v[28:31], v[132:135], v[196:199], v[28:31]
	v_mfma_f32_16x16x32_bf16 v[24:27], v[140:143], v[196:199], v[24:27]
	v_mfma_f32_16x16x32_bf16 v[12:15], v[132:135], v[204:207], v[12:15]
	v_mfma_f32_16x16x32_bf16 v[8:11], v[140:143], v[204:207], v[8:11]
	v_mfma_f32_16x16x32_bf16 v[52:55], v[144:147], v[160:163], 0
	v_mfma_f32_16x16x32_bf16 v[48:51], v[152:155], v[160:163], 0
	v_mfma_f32_16x16x32_bf16 v[36:39], v[144:147], v[168:171], 0
	v_mfma_f32_16x16x32_bf16 v[32:35], v[152:155], v[168:171], 0
	v_mfma_f32_16x16x32_bf16 v[20:23], v[144:147], v[192:195], 0
	v_mfma_f32_16x16x32_bf16 v[16:19], v[152:155], v[192:195], 0
	v_mfma_f32_16x16x32_bf16 v[4:7], v[144:147], v[200:203], 0
	v_mfma_f32_16x16x32_bf16 v[0:3], v[152:155], v[200:203], 0
	v_mfma_f32_16x16x32_bf16 v[52:55], v[148:151], v[164:167], v[52:55]
	v_mfma_f32_16x16x32_bf16 v[48:51], v[156:159], v[164:167], v[48:51]
	v_mfma_f32_16x16x32_bf16 v[36:39], v[148:151], v[172:175], v[36:39]
	v_mfma_f32_16x16x32_bf16 v[32:35], v[156:159], v[172:175], v[32:35]
	v_mfma_f32_16x16x32_bf16 v[20:23], v[148:151], v[196:199], v[20:23]
	v_mfma_f32_16x16x32_bf16 v[16:19], v[156:159], v[196:199], v[16:19]
	v_mfma_f32_16x16x32_bf16 v[4:7], v[148:151], v[204:207], v[4:7]
	v_mfma_f32_16x16x32_bf16 v[0:3], v[156:159], v[204:207], v[0:3]
	s_setprio 0
	s_barrier
	s_add_i32 s55, 0, 0x18000
	s_add_i32 s56, 0, 0x1c000
	v_add_u32_e32 v140, s55, v228
	v_add_u32_e32 v156, s56, v228
	ds_read_b128 v[128:131], v140
	ds_read_b128 v[132:135], v140 offset:1024
	ds_read_b128 v[136:139], v140 offset:2048
	ds_read_b128 v[140:143], v140 offset:3072
	ds_read_b128 v[144:147], v156
	ds_read_b128 v[148:151], v156 offset:1024
	ds_read_b128 v[152:155], v156 offset:2048
	ds_read_b128 v[156:159], v156 offset:3072
	s_add_u32 s24, s28, 0xb0000
	s_addc_u32 s25, s29, 0
	s_mov_b32 m0, s38
	v_lshl_add_u64 v[216:217], s[24:25], 0, v[176:177]
	ds_read_b128 v[160:163], v231 offset:32768
	ds_read_b128 v[164:167], v231 offset:33792
	ds_read_b128 v[168:171], v231 offset:34816
	ds_read_b128 v[172:175], v231 offset:35840
	ds_read_b128 v[192:195], v231 offset:36864
	ds_read_b128 v[196:199], v231 offset:37888
	ds_read_b128 v[200:203], v231 offset:38912
	ds_read_b128 v[204:207], v231 offset:39936
	global_load_lds_dwordx4 v[216:217], off
	v_lshl_add_u64 v[216:217], s[24:25], 0, v[180:181]
	s_mov_b32 m0, s39
	s_nop 0
	global_load_lds_dwordx4 v[216:217], off
	s_waitcnt vmcnt(8)
	s_waitcnt lgkmcnt(0)
	s_barrier
	s_setprio 1
	v_mfma_f32_16x16x32_bf16 v[124:127], v[128:131], v[160:163], v[124:127]
	v_mfma_f32_16x16x32_bf16 v[120:123], v[136:139], v[160:163], v[120:123]
	v_mfma_f32_16x16x32_bf16 v[108:111], v[128:131], v[168:171], v[108:111]
	v_mfma_f32_16x16x32_bf16 v[104:107], v[136:139], v[168:171], v[104:107]
	v_mfma_f32_16x16x32_bf16 v[92:95], v[128:131], v[192:195], v[92:95]
	v_mfma_f32_16x16x32_bf16 v[88:91], v[136:139], v[192:195], v[88:91]
	v_mfma_f32_16x16x32_bf16 v[76:79], v[128:131], v[200:203], v[76:79]
	v_mfma_f32_16x16x32_bf16 v[72:75], v[136:139], v[200:203], v[72:75]
	v_mfma_f32_16x16x32_bf16 v[124:127], v[132:135], v[164:167], v[124:127]
	v_mfma_f32_16x16x32_bf16 v[120:123], v[140:143], v[164:167], v[120:123]
	v_mfma_f32_16x16x32_bf16 v[108:111], v[132:135], v[172:175], v[108:111]
	v_mfma_f32_16x16x32_bf16 v[104:107], v[140:143], v[172:175], v[104:107]
	v_mfma_f32_16x16x32_bf16 v[92:95], v[132:135], v[196:199], v[92:95]
	v_mfma_f32_16x16x32_bf16 v[88:91], v[140:143], v[196:199], v[88:91]
	v_mfma_f32_16x16x32_bf16 v[76:79], v[132:135], v[204:207], v[76:79]
	v_mfma_f32_16x16x32_bf16 v[72:75], v[140:143], v[204:207], v[72:75]
	v_mfma_f32_16x16x32_bf16 v[116:119], v[144:147], v[160:163], v[116:119]
	v_mfma_f32_16x16x32_bf16 v[112:115], v[152:155], v[160:163], v[112:115]
	v_mfma_f32_16x16x32_bf16 v[100:103], v[144:147], v[168:171], v[100:103]
	v_mfma_f32_16x16x32_bf16 v[96:99], v[152:155], v[168:171], v[96:99]
	v_mfma_f32_16x16x32_bf16 v[84:87], v[144:147], v[192:195], v[84:87]
	v_mfma_f32_16x16x32_bf16 v[80:83], v[152:155], v[192:195], v[80:83]
	v_mfma_f32_16x16x32_bf16 v[68:71], v[144:147], v[200:203], v[68:71]
	v_mfma_f32_16x16x32_bf16 v[64:67], v[152:155], v[200:203], v[64:67]
	v_mfma_f32_16x16x32_bf16 v[116:119], v[148:151], v[164:167], v[116:119]
	v_mfma_f32_16x16x32_bf16 v[112:115], v[156:159], v[164:167], v[112:115]
	v_mfma_f32_16x16x32_bf16 v[100:103], v[148:151], v[172:175], v[100:103]
	v_mfma_f32_16x16x32_bf16 v[96:99], v[156:159], v[172:175], v[96:99]
	v_mfma_f32_16x16x32_bf16 v[84:87], v[148:151], v[196:199], v[84:87]
	v_mfma_f32_16x16x32_bf16 v[80:83], v[156:159], v[196:199], v[80:83]
	v_mfma_f32_16x16x32_bf16 v[68:71], v[148:151], v[204:207], v[68:71]
	v_mfma_f32_16x16x32_bf16 v[64:67], v[156:159], v[204:207], v[64:67]
	s_setprio 0
	s_barrier
; #define PG8_STAGE(bufoff, gbase, voff) do { _Pragma("unroll") for (int _i = 0; _i < 2; ++_i) \
;         __builtin_amdgcn_global_load_lds((const unsigned*)((const char*)(gbase) + (voff)[_i]), (LAS unsigned*)(lds + (bufoff) + ldsw + _i * 8192), 16, 0, 0); } while (0)
; #define PG8_LDA(dst, b, h) do { _Pragma("unroll") for (int m = 0; m < 4; ++m) _Pragma("unroll") for (int k = 0; k < 2; ++k) dst[m][k] = *(const LAS bf16x8*)(lds + PG8_SA(b, h) + aoff + m * 2048 + k * 1024); } while (0)
; #define PG8_LDB(dst, b, h) do { _Pragma("unroll") for (int n = 0; n < 2; ++n) _Pragma("unroll") for (int k = 0; k < 2; ++k) dst[n][k] = *(const LAS bf16x8*)(lds + PG8_SB(b, h) + boff + n * 2048 + k * 1024); } while (0)
; #define PG8_MMA(ai, bj, At, Bt) do { __builtin_amdgcn_s_setprio(1); _Pragma("unroll") for (int m = 0; m < 4; ++m) _Pragma("unroll") for (int n = 0; n < 2; ++n) _Pragma("unroll") for (int k = 0; k < 2; ++k) \
;         acc[ai][bj][m][n] = __builtin_amdgcn_mfma_f32_16x16x32_bf16(Bt[n][k], At[m][k], acc[ai][bj][m][n], 0, 0, 0); __builtin_amdgcn_s_setprio(0); } while (0)
; #define PG8_WAIT_V(n) asm volatile("s_waitcnt vmcnt(" #n ")" ::: "memory")
; #define PG8_WAIT_L(n) asm volatile("s_waitcnt lgkmcnt(" #n ")" ::: "memory")
; template <class Epi>
; DI void gemm_phase(LAS unsigned char* lds, const int wid, const Gemm g, const Order& S, const Epi& E) {
;     ...
;             PG8_LDB(B0, 0, 0); PG8_LDB(B1, 0, 1); PG8_SCHED; PG8_LDA(At, 0, 0); PG8_STAGE(PG8_SA(1, 1), a1 + hstepA, voffA);
;             PG8_WAIT_V(8); PG8_WAIT_L(0); PG8_BAR; PG8_MMA(0, 0, At, B0); PG8_MMA(0, 1, At, B1); PG8_BAR; PG8_SCHED;
;             PG8_LDA(At, 0, 1); PG8_STAGE(PG8_SB(0, 0), b2, voffB); PG8_STAGE(PG8_SB(0, 1), b2 + hstepB, voffB); PG8_STAGE(PG8_SA(0, 0), a2, voffA);
;             PG8_WAIT_V(8); PG8_WAIT_L(0); PG8_BAR; PG8_MMA(1, 0, At, B0); PG8_MMA(1, 1, At, B1); PG8_BAR; PG8_SCHED;
;             PG8_LDB(B0, 1, 0); PG8_LDB(B1, 1, 1); PG8_SCHED; PG8_LDA(At, 1, 0); PG8_STAGE(PG8_SA(0, 1), a2 + hstepA, voffA);
;             PG8_WAIT_V(8); PG8_WAIT_L(0); PG8_BAR; PG8_MMA(0, 0, At, B0); PG8_MMA(0, 1, At, B1); PG8_BAR; PG8_SCHED;
;             PG8_LDA(At, 1, 1); PG8_STAGE(PG8_SB(1, 0), b3, voffB); PG8_STAGE(PG8_SB(1, 1), b3 + hstepB, voffB); PG8_STAGE(PG8_SA(1, 0), a3, voffA);
;             PG8_WAIT_V(8); PG8_WAIT_L(0); PG8_BAR; PG8_MMA(1, 0, At, B0); PG8_MMA(1, 1, At, B1); PG8_BAR; PG8_SCHED;
	s_add_i32 s24, s55, s94
	v_lshl_add_u64 v[208:209], v[208:209], 0, s[16:17]
	s_mov_b32 m0, s24
	ds_read_b128 v[160:163], v231 offset:49152
	ds_read_b128 v[164:167], v231 offset:50176
	ds_read_b128 v[168:171], v231 offset:51200
	ds_read_b128 v[172:175], v231 offset:52224
	ds_read_b128 v[192:195], v231 offset:53248
	ds_read_b128 v[196:199], v231 offset:54272
	ds_read_b128 v[200:203], v231 offset:55296
	ds_read_b128 v[204:207], v231 offset:56320
	global_load_lds_dwordx4 v[208:209], off
	s_add_i32 m0, s24, 0x2000
	s_add_u32 s24, s26, 0xb0080
	v_lshl_add_u64 v[208:209], v[210:211], 0, s[16:17]
	s_addc_u32 s25, s27, 0
	s_add_i32 s26, s56, s94
	global_load_lds_dwordx4 v[208:209], off
	v_lshl_add_u64 v[208:209], s[24:25], 0, v[178:179]
	s_mov_b32 m0, s26
	s_nop 0
	global_load_lds_dwordx4 v[208:209], off
	v_lshl_add_u64 v[208:209], s[24:25], 0, v[182:183]
	s_add_i32 m0, s26, 0x2000
	s_nop 0
	global_load_lds_dwordx4 v[208:209], off
	v_lshl_add_u64 v[208:209], v[212:213], 0, s[16:17]
	s_mov_b32 m0, s43
	s_nop 0
	global_load_lds_dwordx4 v[208:209], off
	v_lshl_add_u64 v[208:209], v[214:215], 0, s[16:17]
	s_mov_b32 m0, s44
	s_nop 0
	global_load_lds_dwordx4 v[208:209], off
	s_waitcnt vmcnt(8)
	s_waitcnt lgkmcnt(0)
	s_barrier
	s_setprio 1
	v_mfma_f32_16x16x32_bf16 v[60:63], v[128:131], v[160:163], v[60:63]
	v_mfma_f32_16x16x32_bf16 v[56:59], v[136:139], v[160:163], v[56:59]
	v_mfma_f32_16x16x32_bf16 v[44:47], v[128:131], v[168:171], v[44:47]
	v_mfma_f32_16x16x32_bf16 v[40:43], v[136:139], v[168:171], v[40:43]
	v_mfma_f32_16x16x32_bf16 v[28:31], v[128:131], v[192:195], v[28:31]
	v_mfma_f32_16x16x32_bf16 v[24:27], v[136:139], v[192:195], v[24:27]
	v_mfma_f32_16x16x32_bf16 v[12:15], v[128:131], v[200:203], v[12:15]
	v_mfma_f32_16x16x32_bf16 v[8:11], v[136:139], v[200:203], v[8:11]
	v_mfma_f32_16x16x32_bf16 v[60:63], v[132:135], v[164:167], v[60:63]
	v_mfma_f32_16x16x32_bf16 v[56:59], v[140:143], v[164:167], v[56:59]
	v_mfma_f32_16x16x32_bf16 v[44:47], v[132:135], v[172:175], v[44:47]
	v_mfma_f32_16x16x32_bf16 v[40:43], v[140:143], v[172:175], v[40:43]
	v_mfma_f32_16x16x32_bf16 v[28:31], v[132:135], v[196:199], v[28:31]
	v_mfma_f32_16x16x32_bf16 v[24:27], v[140:143], v[196:199], v[24:27]
	v_mfma_f32_16x16x32_bf16 v[12:15], v[132:135], v[204:207], v[12:15]
	v_mfma_f32_16x16x32_bf16 v[8:11], v[140:143], v[204:207], v[8:11]
	v_mfma_f32_16x16x32_bf16 v[52:55], v[144:147], v[160:163], v[52:55]
	v_mfma_f32_16x16x32_bf16 v[48:51], v[152:155], v[160:163], v[48:51]
	v_mfma_f32_16x16x32_bf16 v[36:39], v[144:147], v[168:171], v[36:39]
	v_mfma_f32_16x16x32_bf16 v[32:35], v[152:155], v[168:171], v[32:35]
	v_mfma_f32_16x16x32_bf16 v[20:23], v[144:147], v[192:195], v[20:23]
	v_mfma_f32_16x16x32_bf16 v[16:19], v[152:155], v[192:195], v[16:19]
	v_mfma_f32_16x16x32_bf16 v[4:7], v[144:147], v[200:203], v[4:7]
	v_mfma_f32_16x16x32_bf16 v[0:3], v[152:155], v[200:203], v[0:3]
	v_mfma_f32_16x16x32_bf16 v[52:55], v[148:151], v[164:167], v[52:55]
	v_mfma_f32_16x16x32_bf16 v[48:51], v[156:159], v[164:167], v[48:51]
	v_mfma_f32_16x16x32_bf16 v[36:39], v[148:151], v[172:175], v[36:39]
	v_mfma_f32_16x16x32_bf16 v[32:35], v[156:159], v[172:175], v[32:35]
	v_mfma_f32_16x16x32_bf16 v[20:23], v[148:151], v[196:199], v[20:23]
	v_mfma_f32_16x16x32_bf16 v[16:19], v[156:159], v[196:199], v[16:19]
	v_mfma_f32_16x16x32_bf16 v[4:7], v[148:151], v[204:207], v[4:7]
	v_mfma_f32_16x16x32_bf16 v[0:3], v[156:159], v[204:207], v[0:3]
	s_setprio 0
	s_barrier
	s_add_i32 s54, s54, 2
	s_add_u32 s52, s52, 0x100
	s_addc_u32 s53, s53, 0
	s_cmp_gt_u32 s54, 41
	s_mov_b64 s[24:25], s[4:5]
	s_cbranch_scc0 .LBB0_1526
	s_branch .Lpeel_exit_11
.LBB0_1526:
	ds_read_b128 v[128:131], v229
	ds_read_b128 v[132:135], v229 offset:1024
	ds_read_b128 v[136:139], v229 offset:2048
	ds_read_b128 v[140:143], v229 offset:3072
	ds_read_b128 v[144:147], v230
	ds_read_b128 v[148:151], v230 offset:1024
	ds_read_b128 v[152:155], v230 offset:2048
	ds_read_b128 v[156:159], v230 offset:3072
	s_add_u32 s4, s24, 0x100
	s_addc_u32 s5, s25, 0
	s_cmp_eq_u32 s54, 40
	s_cselect_b32 s29, s21, s5
	s_cselect_b32 s28, s20, s4
	s_cselect_b32 s27, s23, s53
	s_cselect_b32 s26, s22, s52
	v_lshl_add_u64 v[208:209], s[24:25], 0, v[184:185]
	s_add_i32 m0, s36, 0xc000
	ds_read_b128 v[160:163], v231
	ds_read_b128 v[164:167], v231 offset:1024
	ds_read_b128 v[168:171], v231 offset:2048
	ds_read_b128 v[172:175], v231 offset:3072
	ds_read_b128 v[192:195], v231 offset:4096
	ds_read_b128 v[196:199], v231 offset:5120
	ds_read_b128 v[200:203], v231 offset:6144
	ds_read_b128 v[204:207], v231 offset:7168
	global_load_lds_dwordx4 v[208:209], off
	v_lshl_add_u64 v[208:209], s[24:25], 0, v[186:187]
	s_add_i32 m0, s36, 0xe000
	s_nop 0
	global_load_lds_dwordx4 v[208:209], off
	s_waitcnt vmcnt(8)
	s_waitcnt lgkmcnt(0)
	s_barrier
; #define PG8_STAGE(bufoff, gbase, voff) do { _Pragma("unroll") for (int _i = 0; _i < 2; ++_i) \
;         __builtin_amdgcn_global_load_lds((const unsigned*)((const char*)(gbase) + (voff)[_i]), (LAS unsigned*)(lds + (bufoff) + ldsw + _i * 8192), 16, 0, 0); } while (0)
; #define PG8_LDA(dst, b, h) do { _Pragma("unroll") for (int m = 0; m < 4; ++m) _Pragma("unroll") for (int k = 0; k < 2; ++k) dst[m][k] = *(const LAS bf16x8*)(lds + PG8_SA(b, h) + aoff + m * 2048 + k * 1024); } while (0)
; #define PG8_LDB(dst, b, h) do { _Pragma("unroll") for (int n = 0; n < 2; ++n) _Pragma("unroll") for (int k = 0; k < 2; ++k) dst[n][k] = *(const LAS bf16x8*)(lds + PG8_SB(b, h) + boff + n * 2048 + k * 1024); } while (0)
; #define PG8_MMA(ai, bj, At, Bt) do { __builtin_amdgcn_s_setprio(1); _Pragma("unroll") for (int m = 0; m < 4; ++m) _Pragma("unroll") for (int n = 0; n < 2; ++n) _Pragma("unroll") for (int k = 0; k < 2; ++k) \
;         acc[ai][bj][m][n] = __builtin_amdgcn_mfma_f32_16x16x32_bf16(Bt[n][k], At[m][k], acc[ai][bj][m][n], 0, 0, 0); __builtin_amdgcn_s_setprio(0); } while (0)
; #define PG8_WAIT_V(n) asm volatile("s_waitcnt vmcnt(" #n ")" ::: "memory")
; #define PG8_WAIT_L(n) asm volatile("s_waitcnt lgkmcnt(" #n ")" ::: "memory")
; #define PG8_BAR __builtin_amdgcn_s_barrier()
; #define PG8_SCHED __builtin_amdgcn_sched_barrier(0)
; template <class Epi>
; DI void gemm_phase(LAS unsigned char* lds, const int wid, const Gemm g, const Order& S, const Epi& E) {
;     ...
;             PG8_WAIT_V(8); PG8_WAIT_L(0); PG8_BAR; PG8_MMA(0, 0, At, B0); PG8_MMA(0, 1, At, B1); PG8_BAR; PG8_SCHED;
;             PG8_LDA(At, 0, 1); PG8_STAGE(PG8_SB(0, 0), b2, voffB); PG8_STAGE(PG8_SB(0, 1), b2 + hstepB, voffB); PG8_STAGE(PG8_SA(0, 0), a2, voffA);
;             PG8_WAIT_V(8); PG8_WAIT_L(0); PG8_BAR; PG8_MMA(1, 0, At, B0); PG8_MMA(1, 1, At, B1); PG8_BAR; PG8_SCHED;
;             PG8_LDB(B0, 1, 0); PG8_LDB(B1, 1, 1); PG8_SCHED; PG8_LDA(At, 1, 0); PG8_STAGE(PG8_SA(0, 1), a2 + hstepA, voffA);
;             PG8_WAIT_V(8); PG8_WAIT_L(0); PG8_BAR; PG8_MMA(0, 0, At, B0); PG8_MMA(0, 1, At, B1); PG8_BAR; PG8_SCHED;
	s_setprio 1
	v_mfma_f32_16x16x32_bf16 v[124:127], v[128:131], v[160:163], v[124:127]
	v_mfma_f32_16x16x32_bf16 v[120:123], v[136:139], v[160:163], v[120:123]
	v_mfma_f32_16x16x32_bf16 v[108:111], v[128:131], v[168:171], v[108:111]
	v_mfma_f32_16x16x32_bf16 v[104:107], v[136:139], v[168:171], v[104:107]
	v_mfma_f32_16x16x32_bf16 v[92:95], v[128:131], v[192:195], v[92:95]
	v_mfma_f32_16x16x32_bf16 v[88:91], v[136:139], v[192:195], v[88:91]
	v_mfma_f32_16x16x32_bf16 v[76:79], v[128:131], v[200:203], v[76:79]
	v_mfma_f32_16x16x32_bf16 v[72:75], v[136:139], v[200:203], v[72:75]
	v_mfma_f32_16x16x32_bf16 v[124:127], v[132:135], v[164:167], v[124:127]
	v_mfma_f32_16x16x32_bf16 v[120:123], v[140:143], v[164:167], v[120:123]
	v_mfma_f32_16x16x32_bf16 v[108:111], v[132:135], v[172:175], v[108:111]
	v_mfma_f32_16x16x32_bf16 v[104:107], v[140:143], v[172:175], v[104:107]
	v_mfma_f32_16x16x32_bf16 v[92:95], v[132:135], v[196:199], v[92:95]
	v_mfma_f32_16x16x32_bf16 v[88:91], v[140:143], v[196:199], v[88:91]
	v_mfma_f32_16x16x32_bf16 v[76:79], v[132:135], v[204:207], v[76:79]
	v_mfma_f32_16x16x32_bf16 v[72:75], v[140:143], v[204:207], v[72:75]
	v_mfma_f32_16x16x32_bf16 v[116:119], v[144:147], v[160:163], v[116:119]
	v_mfma_f32_16x16x32_bf16 v[112:115], v[152:155], v[160:163], v[112:115]
	v_mfma_f32_16x16x32_bf16 v[100:103], v[144:147], v[168:171], v[100:103]
	v_mfma_f32_16x16x32_bf16 v[96:99], v[152:155], v[168:171], v[96:99]
	v_mfma_f32_16x16x32_bf16 v[84:87], v[144:147], v[192:195], v[84:87]
	v_mfma_f32_16x16x32_bf16 v[80:83], v[152:155], v[192:195], v[80:83]
	v_mfma_f32_16x16x32_bf16 v[68:71], v[144:147], v[200:203], v[68:71]
	v_mfma_f32_16x16x32_bf16 v[64:67], v[152:155], v[200:203], v[64:67]
	v_mfma_f32_16x16x32_bf16 v[116:119], v[148:151], v[164:167], v[116:119]
	v_mfma_f32_16x16x32_bf16 v[112:115], v[156:159], v[164:167], v[112:115]
	v_mfma_f32_16x16x32_bf16 v[100:103], v[148:151], v[172:175], v[100:103]
	v_mfma_f32_16x16x32_bf16 v[96:99], v[156:159], v[172:175], v[96:99]
	v_mfma_f32_16x16x32_bf16 v[84:87], v[148:151], v[196:199], v[84:87]
	v_mfma_f32_16x16x32_bf16 v[80:83], v[156:159], v[196:199], v[80:83]
	v_mfma_f32_16x16x32_bf16 v[68:71], v[148:151], v[204:207], v[68:71]
	v_mfma_f32_16x16x32_bf16 v[64:67], v[156:159], v[204:207], v[64:67]
	s_setprio 0
	s_barrier
	s_add_i32 s24, s46, s94
	v_lshl_add_u64 v[208:209], s[26:27], 0, v[178:179]
	s_mov_b32 m0, s24
	ds_read_b128 v[160:163], v231 offset:16384
	ds_read_b128 v[164:167], v231 offset:17408
	ds_read_b128 v[168:171], v231 offset:18432
	ds_read_b128 v[172:175], v231 offset:19456
	ds_read_b128 v[192:195], v231 offset:20480
	ds_read_b128 v[196:199], v231 offset:21504
	ds_read_b128 v[200:203], v231 offset:22528
	ds_read_b128 v[204:207], v231 offset:23552
	global_load_lds_dwordx4 v[208:209], off
	s_add_i32 m0, s24, 0x2000
	s_add_u32 s24, s26, 0xb0000
	v_lshl_add_u64 v[210:211], s[26:27], 0, v[182:183]
	s_addc_u32 s25, s27, 0
	s_add_i32 s55, s47, s94
	global_load_lds_dwordx4 v[210:211], off
	v_lshl_add_u64 v[212:213], s[24:25], 0, v[178:179]
	s_mov_b32 m0, s55
	v_lshl_add_u64 v[214:215], s[28:29], 0, v[180:181]
	global_load_lds_dwordx4 v[212:213], off
	v_lshl_add_u64 v[212:213], s[24:25], 0, v[182:183]
	s_add_i32 m0, s55, 0x2000
	s_nop 0
	global_load_lds_dwordx4 v[212:213], off
	v_lshl_add_u64 v[212:213], s[28:29], 0, v[176:177]
	s_mov_b32 m0, s36
	s_nop 0
	global_load_lds_dwordx4 v[212:213], off
	s_mov_b32 m0, s37
	s_nop 0
	global_load_lds_dwordx4 v[214:215], off
	s_waitcnt vmcnt(8)
	s_waitcnt lgkmcnt(0)
	s_barrier
	s_setprio 1
	v_mfma_f32_16x16x32_bf16 v[60:63], v[128:131], v[160:163], v[60:63]
	v_mfma_f32_16x16x32_bf16 v[56:59], v[136:139], v[160:163], v[56:59]
	v_mfma_f32_16x16x32_bf16 v[44:47], v[128:131], v[168:171], v[44:47]
	v_mfma_f32_16x16x32_bf16 v[40:43], v[136:139], v[168:171], v[40:43]
	v_mfma_f32_16x16x32_bf16 v[28:31], v[128:131], v[192:195], v[28:31]
	v_mfma_f32_16x16x32_bf16 v[24:27], v[136:139], v[192:195], v[24:27]
	v_mfma_f32_16x16x32_bf16 v[12:15], v[128:131], v[200:203], v[12:15]
	v_mfma_f32_16x16x32_bf16 v[8:11], v[136:139], v[200:203], v[8:11]
	v_mfma_f32_16x16x32_bf16 v[60:63], v[132:135], v[164:167], v[60:63]
	v_mfma_f32_16x16x32_bf16 v[56:59], v[140:143], v[164:167], v[56:59]
	v_mfma_f32_16x16x32_bf16 v[44:47], v[132:135], v[172:175], v[44:47]
	v_mfma_f32_16x16x32_bf16 v[40:43], v[140:143], v[172:175], v[40:43]
	v_mfma_f32_16x16x32_bf16 v[28:31], v[132:135], v[196:199], v[28:31]
	v_mfma_f32_16x16x32_bf16 v[24:27], v[140:143], v[196:199], v[24:27]
	v_mfma_f32_16x16x32_bf16 v[12:15], v[132:135], v[204:207], v[12:15]
	v_mfma_f32_16x16x32_bf16 v[8:11], v[140:143], v[204:207], v[8:11]
	v_mfma_f32_16x16x32_bf16 v[52:55], v[144:147], v[160:163], v[52:55]
	v_mfma_f32_16x16x32_bf16 v[48:51], v[152:155], v[160:163], v[48:51]
	v_mfma_f32_16x16x32_bf16 v[36:39], v[144:147], v[168:171], v[36:39]
	v_mfma_f32_16x16x32_bf16 v[32:35], v[152:155], v[168:171], v[32:35]
	v_mfma_f32_16x16x32_bf16 v[20:23], v[144:147], v[192:195], v[20:23]
	v_mfma_f32_16x16x32_bf16 v[16:19], v[152:155], v[192:195], v[16:19]
	v_mfma_f32_16x16x32_bf16 v[4:7], v[144:147], v[200:203], v[4:7]
	v_mfma_f32_16x16x32_bf16 v[0:3], v[152:155], v[200:203], v[0:3]
	v_mfma_f32_16x16x32_bf16 v[52:55], v[148:151], v[164:167], v[52:55]
	v_mfma_f32_16x16x32_bf16 v[48:51], v[156:159], v[164:167], v[48:51]
	v_mfma_f32_16x16x32_bf16 v[36:39], v[148:151], v[172:175], v[36:39]
	v_mfma_f32_16x16x32_bf16 v[32:35], v[156:159], v[172:175], v[32:35]
	v_mfma_f32_16x16x32_bf16 v[20:23], v[148:151], v[196:199], v[20:23]
	v_mfma_f32_16x16x32_bf16 v[16:19], v[156:159], v[196:199], v[16:19]
	v_mfma_f32_16x16x32_bf16 v[4:7], v[148:151], v[204:207], v[4:7]
	v_mfma_f32_16x16x32_bf16 v[0:3], v[156:159], v[204:207], v[0:3]
	s_setprio 0
	s_barrier
; #define PG8_STAGE(bufoff, gbase, voff) do { _Pragma("unroll") for (int _i = 0; _i < 2; ++_i) \
;         __builtin_amdgcn_global_load_lds((const unsigned*)((const char*)(gbase) + (voff)[_i]), (LAS unsigned*)(lds + (bufoff) + ldsw + _i * 8192), 16, 0, 0); } while (0)
; #define PG8_LDA(dst, b, h) do { _Pragma("unroll") for (int m = 0; m < 4; ++m) _Pragma("unroll") for (int k = 0; k < 2; ++k) dst[m][k] = *(const LAS bf16x8*)(lds + PG8_SA(b, h) + aoff + m * 2048 + k * 1024); } while (0)
; #define PG8_LDB(dst, b, h) do { _Pragma("unroll") for (int n = 0; n < 2; ++n) _Pragma("unroll") for (int k = 0; k < 2; ++k) dst[n][k] = *(const LAS bf16x8*)(lds + PG8_SB(b, h) + boff + n * 2048 + k * 1024); } while (0)
; #define PG8_MMA(ai, bj, At, Bt) do { __builtin_amdgcn_s_setprio(1); _Pragma("unroll") for (int m = 0; m < 4; ++m) _Pragma("unroll") for (int n = 0; n < 2; ++n) _Pragma("unroll") for (int k = 0; k < 2; ++k) \
;         acc[ai][bj][m][n] = __builtin_amdgcn_mfma_f32_16x16x32_bf16(Bt[n][k], At[m][k], acc[ai][bj][m][n], 0, 0, 0); __builtin_amdgcn_s_setprio(0); } while (0)
; #define PG8_WAIT_V(n) asm volatile("s_waitcnt vmcnt(" #n ")" ::: "memory")
; #define PG8_WAIT_L(n) asm volatile("s_waitcnt lgkmcnt(" #n ")" ::: "memory")
; #define PG8_BAR __builtin_amdgcn_s_barrier()
; #define PG8_SCHED __builtin_amdgcn_sched_barrier(0)
; template <class Epi>
; DI void gemm_phase(LAS unsigned char* lds, const int wid, const Gemm g, const Order& S, const Epi& E) {
;     ...
;         for (int t = 0; t < nt; t += 2) {
;     ...
;             PG8_LDB(B0, 1, 0); PG8_LDB(B1, 1, 1); PG8_SCHED; PG8_LDA(At, 1, 0); PG8_STAGE(PG8_SA(0, 1), a2 + hstepA, voffA);
;             PG8_WAIT_V(8); PG8_WAIT_L(0); PG8_BAR; PG8_MMA(0, 0, At, B0); PG8_MMA(0, 1, At, B1); PG8_BAR; PG8_SCHED;
;             PG8_LDA(At, 1, 1); PG8_STAGE(PG8_SB(1, 0), b3, voffB); PG8_STAGE(PG8_SB(1, 1), b3 + hstepB, voffB); PG8_STAGE(PG8_SA(1, 0), a3, voffA);
;             PG8_WAIT_V(8); PG8_WAIT_L(0); PG8_BAR; PG8_MMA(1, 0, At, B0); PG8_MMA(1, 1, At, B1); PG8_BAR; PG8_SCHED;
	s_add_i32 s55, 0, 0x18000
	s_add_i32 s56, 0, 0x1c000
	v_add_u32_e32 v140, s55, v228
	v_add_u32_e32 v156, s56, v228
	ds_read_b128 v[128:131], v140
	ds_read_b128 v[132:135], v140 offset:1024
	ds_read_b128 v[136:139], v140 offset:2048
	ds_read_b128 v[140:143], v140 offset:3072
	ds_read_b128 v[144:147], v156
	ds_read_b128 v[148:151], v156 offset:1024
	ds_read_b128 v[152:155], v156 offset:2048
	ds_read_b128 v[156:159], v156 offset:3072
	s_add_u32 s24, s28, 0xb0000
	s_addc_u32 s25, s29, 0
	s_mov_b32 m0, s38
	v_lshl_add_u64 v[216:217], s[24:25], 0, v[176:177]
	ds_read_b128 v[160:163], v231 offset:32768
	ds_read_b128 v[164:167], v231 offset:33792
	ds_read_b128 v[168:171], v231 offset:34816
	ds_read_b128 v[172:175], v231 offset:35840
	ds_read_b128 v[192:195], v231 offset:36864
	ds_read_b128 v[196:199], v231 offset:37888
	ds_read_b128 v[200:203], v231 offset:38912
	ds_read_b128 v[204:207], v231 offset:39936
	global_load_lds_dwordx4 v[216:217], off
	v_lshl_add_u64 v[216:217], s[24:25], 0, v[180:181]
	s_mov_b32 m0, s39
	s_nop 0
	global_load_lds_dwordx4 v[216:217], off
	s_waitcnt vmcnt(8)
	s_waitcnt lgkmcnt(0)
	s_barrier
	s_setprio 1
	v_mfma_f32_16x16x32_bf16 v[124:127], v[128:131], v[160:163], v[124:127]
	v_mfma_f32_16x16x32_bf16 v[120:123], v[136:139], v[160:163], v[120:123]
	v_mfma_f32_16x16x32_bf16 v[108:111], v[128:131], v[168:171], v[108:111]
	v_mfma_f32_16x16x32_bf16 v[104:107], v[136:139], v[168:171], v[104:107]
	v_mfma_f32_16x16x32_bf16 v[92:95], v[128:131], v[192:195], v[92:95]
	v_mfma_f32_16x16x32_bf16 v[88:91], v[136:139], v[192:195], v[88:91]
	v_mfma_f32_16x16x32_bf16 v[76:79], v[128:131], v[200:203], v[76:79]
	v_mfma_f32_16x16x32_bf16 v[72:75], v[136:139], v[200:203], v[72:75]
	v_mfma_f32_16x16x32_bf16 v[124:127], v[132:135], v[164:167], v[124:127]
	v_mfma_f32_16x16x32_bf16 v[120:123], v[140:143], v[164:167], v[120:123]
	v_mfma_f32_16x16x32_bf16 v[108:111], v[132:135], v[172:175], v[108:111]
	v_mfma_f32_16x16x32_bf16 v[104:107], v[140:143], v[172:175], v[104:107]
	v_mfma_f32_16x16x32_bf16 v[92:95], v[132:135], v[196:199], v[92:95]
	v_mfma_f32_16x16x32_bf16 v[88:91], v[140:143], v[196:199], v[88:91]
	v_mfma_f32_16x16x32_bf16 v[76:79], v[132:135], v[204:207], v[76:79]
	v_mfma_f32_16x16x32_bf16 v[72:75], v[140:143], v[204:207], v[72:75]
	v_mfma_f32_16x16x32_bf16 v[116:119], v[144:147], v[160:163], v[116:119]
	v_mfma_f32_16x16x32_bf16 v[112:115], v[152:155], v[160:163], v[112:115]
	v_mfma_f32_16x16x32_bf16 v[100:103], v[144:147], v[168:171], v[100:103]
	v_mfma_f32_16x16x32_bf16 v[96:99], v[152:155], v[168:171], v[96:99]
	v_mfma_f32_16x16x32_bf16 v[84:87], v[144:147], v[192:195], v[84:87]
	v_mfma_f32_16x16x32_bf16 v[80:83], v[152:155], v[192:195], v[80:83]
	v_mfma_f32_16x16x32_bf16 v[68:71], v[144:147], v[200:203], v[68:71]
	v_mfma_f32_16x16x32_bf16 v[64:67], v[152:155], v[200:203], v[64:67]
	v_mfma_f32_16x16x32_bf16 v[116:119], v[148:151], v[164:167], v[116:119]
	v_mfma_f32_16x16x32_bf16 v[112:115], v[156:159], v[164:167], v[112:115]
	v_mfma_f32_16x16x32_bf16 v[100:103], v[148:151], v[172:175], v[100:103]
	v_mfma_f32_16x16x32_bf16 v[96:99], v[156:159], v[172:175], v[96:99]
	v_mfma_f32_16x16x32_bf16 v[84:87], v[148:151], v[196:199], v[84:87]
	v_mfma_f32_16x16x32_bf16 v[80:83], v[156:159], v[196:199], v[80:83]
	v_mfma_f32_16x16x32_bf16 v[68:71], v[148:151], v[204:207], v[68:71]
	v_mfma_f32_16x16x32_bf16 v[64:67], v[156:159], v[204:207], v[64:67]
	s_setprio 0
	s_barrier
	s_add_i32 s24, s55, s94
	v_lshl_add_u64 v[208:209], v[208:209], 0, s[16:17]
	s_mov_b32 m0, s24
	ds_read_b128 v[160:163], v231 offset:49152
	ds_read_b128 v[164:167], v231 offset:50176
	ds_read_b128 v[168:171], v231 offset:51200
	ds_read_b128 v[172:175], v231 offset:52224
	ds_read_b128 v[192:195], v231 offset:53248
	ds_read_b128 v[196:199], v231 offset:54272
	ds_read_b128 v[200:203], v231 offset:55296
	ds_read_b128 v[204:207], v231 offset:56320
	global_load_lds_dwordx4 v[208:209], off
	s_add_i32 m0, s24, 0x2000
	s_add_u32 s24, s26, 0xb0080
	v_lshl_add_u64 v[208:209], v[210:211], 0, s[16:17]
	s_addc_u32 s25, s27, 0
	s_add_i32 s26, s56, s94
	global_load_lds_dwordx4 v[208:209], off
	v_lshl_add_u64 v[208:209], s[24:25], 0, v[178:179]
	s_mov_b32 m0, s26
	s_nop 0
	global_load_lds_dwordx4 v[208:209], off
	v_lshl_add_u64 v[208:209], s[24:25], 0, v[182:183]
	s_add_i32 m0, s26, 0x2000
	s_nop 0
	global_load_lds_dwordx4 v[208:209], off
	v_lshl_add_u64 v[208:209], v[212:213], 0, s[16:17]
	s_mov_b32 m0, s43
	s_nop 0
	global_load_lds_dwordx4 v[208:209], off
	v_lshl_add_u64 v[208:209], v[214:215], 0, s[16:17]
	s_mov_b32 m0, s44
	s_nop 0
	global_load_lds_dwordx4 v[208:209], off
	s_waitcnt vmcnt(8)
	s_waitcnt lgkmcnt(0)
	s_barrier
	s_setprio 1
	v_mfma_f32_16x16x32_bf16 v[60:63], v[128:131], v[160:163], v[60:63]
	v_mfma_f32_16x16x32_bf16 v[56:59], v[136:139], v[160:163], v[56:59]
	v_mfma_f32_16x16x32_bf16 v[44:47], v[128:131], v[168:171], v[44:47]
	v_mfma_f32_16x16x32_bf16 v[40:43], v[136:139], v[168:171], v[40:43]
	v_mfma_f32_16x16x32_bf16 v[28:31], v[128:131], v[192:195], v[28:31]
	v_mfma_f32_16x16x32_bf16 v[24:27], v[136:139], v[192:195], v[24:27]
	v_mfma_f32_16x16x32_bf16 v[12:15], v[128:131], v[200:203], v[12:15]
	v_mfma_f32_16x16x32_bf16 v[8:11], v[136:139], v[200:203], v[8:11]
	v_mfma_f32_16x16x32_bf16 v[60:63], v[132:135], v[164:167], v[60:63]
	v_mfma_f32_16x16x32_bf16 v[56:59], v[140:143], v[164:167], v[56:59]
	v_mfma_f32_16x16x32_bf16 v[44:47], v[132:135], v[172:175], v[44:47]
	v_mfma_f32_16x16x32_bf16 v[40:43], v[140:143], v[172:175], v[40:43]
	v_mfma_f32_16x16x32_bf16 v[28:31], v[132:135], v[196:199], v[28:31]
	v_mfma_f32_16x16x32_bf16 v[24:27], v[140:143], v[196:199], v[24:27]
	v_mfma_f32_16x16x32_bf16 v[12:15], v[132:135], v[204:207], v[12:15]
	v_mfma_f32_16x16x32_bf16 v[8:11], v[140:143], v[204:207], v[8:11]
	v_mfma_f32_16x16x32_bf16 v[52:55], v[144:147], v[160:163], v[52:55]
	v_mfma_f32_16x16x32_bf16 v[48:51], v[152:155], v[160:163], v[48:51]
	v_mfma_f32_16x16x32_bf16 v[36:39], v[144:147], v[168:171], v[36:39]
	v_mfma_f32_16x16x32_bf16 v[32:35], v[152:155], v[168:171], v[32:35]
	v_mfma_f32_16x16x32_bf16 v[20:23], v[144:147], v[192:195], v[20:23]
	v_mfma_f32_16x16x32_bf16 v[16:19], v[152:155], v[192:195], v[16:19]
	v_mfma_f32_16x16x32_bf16 v[4:7], v[144:147], v[200:203], v[4:7]
	v_mfma_f32_16x16x32_bf16 v[0:3], v[152:155], v[200:203], v[0:3]
	v_mfma_f32_16x16x32_bf16 v[52:55], v[148:151], v[164:167], v[52:55]
	v_mfma_f32_16x16x32_bf16 v[48:51], v[156:159], v[164:167], v[48:51]
	v_mfma_f32_16x16x32_bf16 v[36:39], v[148:151], v[172:175], v[36:39]
	v_mfma_f32_16x16x32_bf16 v[32:35], v[156:159], v[172:175], v[32:35]
	v_mfma_f32_16x16x32_bf16 v[20:23], v[148:151], v[196:199], v[20:23]
	v_mfma_f32_16x16x32_bf16 v[16:19], v[156:159], v[196:199], v[16:19]
	v_mfma_f32_16x16x32_bf16 v[4:7], v[148:151], v[204:207], v[4:7]
	v_mfma_f32_16x16x32_bf16 v[0:3], v[156:159], v[204:207], v[0:3]
	s_setprio 0
	s_barrier
	s_add_i32 s54, s54, 2
	s_add_u32 s52, s52, 0x100
	s_addc_u32 s53, s53, 0
	s_cmp_gt_u32 s54, 41
	s_mov_b64 s[24:25], s[4:5]
	s_cbranch_scc0 .LBB0_1526
